# nt hint on the once-read streaming row loads of the hand-written prep (P1 x rows, P11 h rows); otherwise identical to v46
# baseline (speedup 1.0000x reference)
; __device__ __forceinline__ float bf_lo(unsigned w) { return __uint_as_float(w << 16); }
; __device__ __forceinline__ float bf_hi(unsigned w) { return __uint_as_float(w & 0xffff0000u); }
; #define PH_IDS() const int tid = lnd((int)threadIdx.x), lane = tid & 63, wave = __builtin_amdgcn_readfirstlane(tid >> 6), gw = bid * 8 + wave; (void)lane; (void)gw
; #define REPS(k) for (int rep_ = 0; rep_ < (((REP_MASK >> (k)) & 1) ? 2 : 1); ++rep_)
; template <bool BF> __device__ __forceinline__ void prep_rows(const float* xp, const float* xs, const bf16* hb, const float* g, const float* MOD, int shoff, int scoff, bf16* U, int gw, int NGW, int lane) {
;     constexpr int R = 4;
;     for (int mb = gw; mb < MT; mb += R * NGW) {
;         f32x4 v[R][4]; float s[R];
; #pragma unroll
;         for (int r = 0; r < R; ++r) { const int m = mb + r * NGW; const int mc = m < MT ? m : mb;
; #pragma unroll
;             for (int j = 0; j < 4; ++j) {
;                 if (BF) { const v2u a0 = *(const v2u*)(hb + (size_t)mc * DM + 4 * lane + 256 * j);
;                     v[r][j].x = pg8::bf_lo(a0.x); v[r][j].y = pg8::bf_hi(a0.x); v[r][j].z = pg8::bf_lo(a0.y); v[r][j].w = pg8::bf_hi(a0.y); }
;                 else { const float* xr = mc < MP ? xp + (size_t)mc * DM : xs + (size_t)(mc - MP) * DM; v[r][j] = *(const f32x4*)(xr + 4 * lane + 256 * j); } } }
; template <int PHM> __global__ void __launch_bounds__(512, 2) mk_fwd(Args karg) {
;     ...
;     if (IN(1)) REPS(1) { PH_ARGS(); PH_IDS(); prep_rows<false>(a.in[I_XP], a.in[I_XS], nullptr, a.in[I_N1G], MOD, 0, 1024, (bf16*)(ws + WS_U1), gw, NGW, lane); kraw_items(a, gw, NGW, lane); }
.LBB0_106:
	s_cmp_lt_i32 s78, 2
	s_cselect_b64 s[2:3], -1, 0
	s_and_b64 s[12:13], s[2:3], s[0:1]
	s_andn2_b64 vcc, exec, s[12:13]
	s_cbranch_vccnz .LBB0_122
	s_mov_b64 s[2:3], s[72:73]
	s_load_dwordx2 s[0:1], s[2:3], 0x90
	s_load_dwordx2 s[4:5], s[2:3], 0xe8
	v_mov_b32_e32 v0, v254
	s_lshl_b32 s33, s96, 3
	v_readfirstlane_b32 s44, v0
	s_ashr_i32 s43, s44, 6
	s_add_i32 s42, s43, s33
	s_cmp_gt_i32 s42, 0x17fff
	v_and_b32_e32 v94, 63, v0
	s_cbranch_scc1 .LBB0_116
	s_cmp_eq_u32 s70, 0x100
	s_cbranch_scc0 .Lorig_prep1
	s_load_dwordx2 s[6:7], s[72:73], 0x38
	s_load_dwordx2 s[10:11], s[72:73], 0x0
	s_load_dwordx2 s[14:15], s[72:73], 0x8
	s_load_dwordx2 s[8:9], s[72:73], 0xe8
	v_and_b32_e32 v82, 63, v254
	v_lshlrev_b32_e32 v80, 5, v82
	v_add_u32_e32 v81, 0x1000, v80
	v_xor_b32_e32 v83, 1, v82
	v_xor_b32_e32 v84, 2, v82
	v_xor_b32_e32 v85, 4, v82
	v_xor_b32_e32 v86, 8, v82
	v_xor_b32_e32 v87, 16, v82
	v_xor_b32_e32 v88, 32, v82
	v_lshlrev_b32_e32 v83, 2, v83
	v_lshlrev_b32_e32 v84, 2, v84
	v_lshlrev_b32_e32 v85, 2, v85
	v_lshlrev_b32_e32 v86, 2, v86
	v_lshlrev_b32_e32 v87, 2, v87
	v_lshlrev_b32_e32 v88, 2, v88
	v_lshlrev_b32_e32 v82, 4, v82
	v_mov_b32_e32 v89, 0x358637bd
	v_mov_b32_e32 v90, 0x260
	s_mov_b32 s54, 0xf800000
	v_readfirstlane_b32 s45, v254
	s_nop 3
	s_lshl_b32 s50, s96, 3
	s_lshr_b32 s45, s45, 6
	s_add_i32 s45, s45, s50
	s_waitcnt lgkmcnt(0)
	s_lshl_b32 s50, s45, 12
	s_add_u32 s16, s10, s50
	s_addc_u32 s17, s11, 0
	s_add_u32 s18, s14, s50
	s_addc_u32 s19, s15, 0
	s_lshl_b32 s50, s45, 11
	s_add_u32 s20, s8, s50
	s_addc_u32 s21, s9, 0
	s_add_u32 s20, s20, 0x3000000
	s_addc_u32 s21, s21, 0
	global_load_dwordx4 v[64:67], v80, s[6:7] offset:0
	global_load_dwordx4 v[68:71], v80, s[6:7] offset:16
	global_load_dwordx4 v[72:75], v80, s[6:7] offset:2048
	global_load_dwordx4 v[76:79], v80, s[6:7] offset:2064
	s_mov_b64 s[24:25], s[16:17]
	s_add_u32 s26, s16, 0x800000
	s_addc_u32 s27, s17, 0
	s_add_u32 s28, s16, 0x1000000
	s_addc_u32 s29, s17, 0
	s_add_u32 s30, s16, 0x1800000
	s_addc_u32 s31, s17, 0
	global_load_dwordx4 v[0:3], v80, s[24:25] offset:0 nt
	global_load_dwordx4 v[4:7], v80, s[24:25] offset:16 nt
	global_load_dwordx4 v[8:11], v80, s[24:25] offset:2048 nt
	global_load_dwordx4 v[12:15], v80, s[24:25] offset:2064 nt
	global_load_dwordx4 v[16:19], v80, s[26:27] offset:0 nt
	global_load_dwordx4 v[20:23], v80, s[26:27] offset:16 nt
	global_load_dwordx4 v[24:27], v80, s[26:27] offset:2048 nt
	global_load_dwordx4 v[28:31], v80, s[26:27] offset:2064 nt
	global_load_dwordx4 v[32:35], v80, s[28:29] offset:0 nt
	global_load_dwordx4 v[36:39], v80, s[28:29] offset:16 nt
	global_load_dwordx4 v[40:43], v80, s[28:29] offset:2048 nt
	global_load_dwordx4 v[44:47], v80, s[28:29] offset:2064 nt
	global_load_dwordx4 v[48:51], v80, s[30:31] offset:0 nt
	global_load_dwordx4 v[52:55], v80, s[30:31] offset:16 nt
	global_load_dwordx4 v[56:59], v80, s[30:31] offset:2048 nt
	global_load_dwordx4 v[60:63], v80, s[30:31] offset:2064 nt
	s_mov_b64 s[34:35], s[8:9]
	s_mov_b64 s[36:37], s[8:9]
	global_load_dwordx4 v[176:179], v80, s[34:35] offset:0
	global_load_dwordx4 v[180:183], v80, s[34:35] offset:16
	global_load_dwordx4 v[184:187], v80, s[34:35] offset:2048
	global_load_dwordx4 v[188:191], v80, s[34:35] offset:2064
	global_load_dwordx4 v[160:163], v81, s[34:35] offset:0
	global_load_dwordx4 v[164:167], v81, s[34:35] offset:16
	global_load_dwordx4 v[168:171], v81, s[34:35] offset:2048
	global_load_dwordx4 v[172:175], v81, s[34:35] offset:2064
	global_load_dwordx4 v[208:211], v80, s[36:37] offset:0
	global_load_dwordx4 v[212:215], v80, s[36:37] offset:16
	global_load_dwordx4 v[216:219], v80, s[36:37] offset:2048
	global_load_dwordx4 v[220:223], v80, s[36:37] offset:2064
	global_load_dwordx4 v[192:195], v81, s[36:37] offset:0
	global_load_dwordx4 v[196:199], v81, s[36:37] offset:16
	global_load_dwordx4 v[200:203], v81, s[36:37] offset:2048
	global_load_dwordx4 v[204:207], v81, s[36:37] offset:2064
	s_add_u32 s24, s16, 0x2000000
	s_addc_u32 s25, s17, 0
	s_add_u32 s26, s16, 0x2800000
	s_addc_u32 s27, s17, 0
	s_add_u32 s28, s16, 0x3000000
	s_addc_u32 s29, s17, 0
	s_add_u32 s30, s16, 0x3800000
	s_addc_u32 s31, s17, 0
	global_load_dwordx4 v[96:99], v80, s[24:25] offset:0 nt
	global_load_dwordx4 v[100:103], v80, s[24:25] offset:16 nt
	global_load_dwordx4 v[104:107], v80, s[24:25] offset:2048 nt
	global_load_dwordx4 v[108:111], v80, s[24:25] offset:2064 nt
	global_load_dwordx4 v[112:115], v80, s[26:27] offset:0 nt
	global_load_dwordx4 v[116:119], v80, s[26:27] offset:16 nt
	global_load_dwordx4 v[120:123], v80, s[26:27] offset:2048 nt
	global_load_dwordx4 v[124:127], v80, s[26:27] offset:2064 nt
	global_load_dwordx4 v[128:131], v80, s[28:29] offset:0 nt
	global_load_dwordx4 v[132:135], v80, s[28:29] offset:16 nt
	global_load_dwordx4 v[136:139], v80, s[28:29] offset:2048 nt
	global_load_dwordx4 v[140:143], v80, s[28:29] offset:2064 nt
	global_load_dwordx4 v[144:147], v80, s[30:31] offset:0 nt
	global_load_dwordx4 v[148:151], v80, s[30:31] offset:16 nt
	global_load_dwordx4 v[152:155], v80, s[30:31] offset:2048 nt
	global_load_dwordx4 v[156:159], v80, s[30:31] offset:2064 nt
	s_waitcnt vmcnt(32)
; template <bool BF> __device__ __forceinline__ void prep_rows(const float* xp, const float* xs, const bf16* hb, const float* g, const float* MOD, int shoff, int scoff, bf16* U, int gw, int NGW, int lane) {
;     ...
; #pragma unroll
;         for (int r = 0; r < R; ++r) { float t = 0.f;
; #pragma unroll
;             for (int j = 0; j < 4; ++j) t += (v[r][j].x * v[r][j].x + v[r][j].y * v[r][j].y) + (v[r][j].z * v[r][j].z + v[r][j].w * v[r][j].w);
;             s[r] = t; }
; #pragma unroll
;         for (int o = 1; o < 64; o <<= 1) {
; #pragma unroll
;             for (int r = 0; r < R; ++r) s[r] += __shfl_xor(s[r], o); }
; #pragma unroll
;         for (int r = 0; r < R; ++r) { const int m = mb + r * NGW; if (m < MT) {
;             const float rstd = 1.0f / sqrtf(s[r] * (1.0f / DM) + RMS_EPS);
	v_pk_mul_f32 v[240:241], v[0:1], v[0:1]
	v_pk_mul_f32 v[242:243], v[16:17], v[16:17]
	v_pk_mul_f32 v[244:245], v[32:33], v[32:33]
	v_pk_mul_f32 v[246:247], v[48:49], v[48:49]
	v_pk_fma_f32 v[240:241], v[2:3], v[2:3], v[240:241]
	v_pk_fma_f32 v[242:243], v[18:19], v[18:19], v[242:243]
	v_pk_fma_f32 v[244:245], v[34:35], v[34:35], v[244:245]
	v_pk_fma_f32 v[246:247], v[50:51], v[50:51], v[246:247]
	v_pk_fma_f32 v[240:241], v[4:5], v[4:5], v[240:241]
	v_pk_fma_f32 v[242:243], v[20:21], v[20:21], v[242:243]
	v_pk_fma_f32 v[244:245], v[36:37], v[36:37], v[244:245]
	v_pk_fma_f32 v[246:247], v[52:53], v[52:53], v[246:247]
	v_pk_fma_f32 v[240:241], v[6:7], v[6:7], v[240:241]
	v_pk_fma_f32 v[242:243], v[22:23], v[22:23], v[242:243]
	v_pk_fma_f32 v[244:245], v[38:39], v[38:39], v[244:245]
	v_pk_fma_f32 v[246:247], v[54:55], v[54:55], v[246:247]
	v_pk_fma_f32 v[240:241], v[8:9], v[8:9], v[240:241]
	v_pk_fma_f32 v[242:243], v[24:25], v[24:25], v[242:243]
	v_pk_fma_f32 v[244:245], v[40:41], v[40:41], v[244:245]
	v_pk_fma_f32 v[246:247], v[56:57], v[56:57], v[246:247]
	v_pk_fma_f32 v[240:241], v[10:11], v[10:11], v[240:241]
	v_pk_fma_f32 v[242:243], v[26:27], v[26:27], v[242:243]
	v_pk_fma_f32 v[244:245], v[42:43], v[42:43], v[244:245]
	v_pk_fma_f32 v[246:247], v[58:59], v[58:59], v[246:247]
	v_pk_fma_f32 v[240:241], v[12:13], v[12:13], v[240:241]
	v_pk_fma_f32 v[242:243], v[28:29], v[28:29], v[242:243]
	v_pk_fma_f32 v[244:245], v[44:45], v[44:45], v[244:245]
	v_pk_fma_f32 v[246:247], v[60:61], v[60:61], v[246:247]
	v_pk_fma_f32 v[240:241], v[14:15], v[14:15], v[240:241]
	v_pk_fma_f32 v[242:243], v[30:31], v[30:31], v[242:243]
	v_pk_fma_f32 v[244:245], v[46:47], v[46:47], v[244:245]
	v_pk_fma_f32 v[246:247], v[62:63], v[62:63], v[246:247]
	v_add_f32_e32 v224, v240, v241
	v_add_f32_e32 v225, v242, v243
	v_add_f32_e32 v226, v244, v245
	v_add_f32_e32 v227, v246, v247
	ds_bpermute_b32 v228, v83, v224
	ds_bpermute_b32 v229, v83, v225
	ds_bpermute_b32 v230, v83, v226
	ds_bpermute_b32 v231, v83, v227
	s_waitcnt lgkmcnt(0)
	v_add_f32_e32 v224, v224, v228
	v_add_f32_e32 v225, v225, v229
	v_add_f32_e32 v226, v226, v230
	v_add_f32_e32 v227, v227, v231
	ds_bpermute_b32 v228, v84, v224
	ds_bpermute_b32 v229, v84, v225
	ds_bpermute_b32 v230, v84, v226
	ds_bpermute_b32 v231, v84, v227
	s_waitcnt lgkmcnt(0)
	v_add_f32_e32 v224, v224, v228
	v_add_f32_e32 v225, v225, v229
	v_add_f32_e32 v226, v226, v230
	v_add_f32_e32 v227, v227, v231
	ds_bpermute_b32 v228, v85, v224
	ds_bpermute_b32 v229, v85, v225
	ds_bpermute_b32 v230, v85, v226
	ds_bpermute_b32 v231, v85, v227
	s_waitcnt lgkmcnt(0)
	v_add_f32_e32 v224, v224, v228
	v_add_f32_e32 v225, v225, v229
	v_add_f32_e32 v226, v226, v230
	v_add_f32_e32 v227, v227, v231
	ds_bpermute_b32 v228, v86, v224
	ds_bpermute_b32 v229, v86, v225
	ds_bpermute_b32 v230, v86, v226
	ds_bpermute_b32 v231, v86, v227
	s_waitcnt lgkmcnt(0)
	v_add_f32_e32 v224, v224, v228
	v_add_f32_e32 v225, v225, v229
	v_add_f32_e32 v226, v226, v230
	v_add_f32_e32 v227, v227, v231
	ds_bpermute_b32 v228, v87, v224
	ds_bpermute_b32 v229, v87, v225
	ds_bpermute_b32 v230, v87, v226
	ds_bpermute_b32 v231, v87, v227
	s_waitcnt lgkmcnt(0)
	v_add_f32_e32 v224, v224, v228
	v_add_f32_e32 v225, v225, v229
	v_add_f32_e32 v226, v226, v230
	v_add_f32_e32 v227, v227, v231
	ds_bpermute_b32 v228, v88, v224
	ds_bpermute_b32 v229, v88, v225
	ds_bpermute_b32 v230, v88, v226
	ds_bpermute_b32 v231, v88, v227
	s_waitcnt lgkmcnt(0)
	v_add_f32_e32 v224, v224, v228
	v_add_f32_e32 v225, v225, v229
	v_add_f32_e32 v226, v226, v230
	v_add_f32_e32 v227, v227, v231
	v_fmamk_f32 v240, v224, 0x3a800000, v89
	v_mul_f32_e32 v241, 0x4f800000, v240
	v_cmp_gt_f32_e32 vcc, s54, v240
	s_nop 1
	v_cndmask_b32_e32 v247, v240, v241, vcc
	v_sqrt_f32_e32 v242, v247
	s_nop 1
	v_add_u32_e32 v243, -1, v242
	v_add_u32_e32 v244, 1, v242
	v_fma_f32 v245, -v243, v242, v247
	v_fma_f32 v246, -v244, v242, v247
	v_cmp_ge_f32_e64 s[52:53], 0, v245
	s_nop 1
	v_cndmask_b32_e64 v242, v242, v243, s[52:53]
	v_cmp_lt_f32_e64 s[52:53], 0, v246
	s_nop 1
	v_cndmask_b32_e64 v242, v242, v244, s[52:53]
	v_mul_f32_e32 v243, 0x37800000, v242
	v_cndmask_b32_e32 v242, v242, v243, vcc
	v_cmp_class_f32_e32 vcc, v247, v90
	s_nop 1
	v_cndmask_b32_e32 v247, v242, v247, vcc
	v_div_scale_f32 v248, s[52:53], v247, v247, 1.0
	v_rcp_f32_e32 v249, v248
	v_div_scale_f32 v228, vcc, 1.0, v247, 1.0
	s_nop 0
	v_fma_f32 v229, -v248, v249, 1.0
	v_fmac_f32_e32 v249, v229, v249
	v_mul_f32_e32 v230, v228, v249
	v_fma_f32 v229, -v248, v230, v228
	v_fmac_f32_e32 v230, v229, v249
	v_fma_f32 v248, -v248, v230, v228
	v_div_fmas_f32 v248, v248, v249, v230
	v_div_fixup_f32 v232, v248, v247, 1.0
	v_fmamk_f32 v240, v225, 0x3a800000, v89
	v_mul_f32_e32 v241, 0x4f800000, v240
	v_cmp_gt_f32_e32 vcc, s54, v240
	s_nop 1
	v_cndmask_b32_e32 v247, v240, v241, vcc
	v_sqrt_f32_e32 v242, v247
	s_nop 1
	v_add_u32_e32 v243, -1, v242
	v_add_u32_e32 v244, 1, v242
	v_fma_f32 v245, -v243, v242, v247
	v_fma_f32 v246, -v244, v242, v247
	v_cmp_ge_f32_e64 s[52:53], 0, v245
	s_nop 1
	v_cndmask_b32_e64 v242, v242, v243, s[52:53]
	v_cmp_lt_f32_e64 s[52:53], 0, v246
	s_nop 1
	v_cndmask_b32_e64 v242, v242, v244, s[52:53]
	v_mul_f32_e32 v243, 0x37800000, v242
	v_cndmask_b32_e32 v242, v242, v243, vcc
	v_cmp_class_f32_e32 vcc, v247, v90
	s_nop 1
	v_cndmask_b32_e32 v247, v242, v247, vcc
	v_div_scale_f32 v248, s[52:53], v247, v247, 1.0
	v_rcp_f32_e32 v249, v248
	v_div_scale_f32 v228, vcc, 1.0, v247, 1.0
	s_nop 0
	v_fma_f32 v229, -v248, v249, 1.0
	v_fmac_f32_e32 v249, v229, v249
	v_mul_f32_e32 v230, v228, v249
	v_fma_f32 v229, -v248, v230, v228
	v_fmac_f32_e32 v230, v229, v249
; __device__ __forceinline__ unsigned pk2(float lo, float hi) { return pg8::cvt_pk_bf16(lo, hi); }
; template <bool BF> __device__ __forceinline__ void prep_rows(const float* xp, const float* xs, const bf16* hb, const float* g, const float* MOD, int shoff, int scoff, bf16* U, int gw, int NGW, int lane) {
;     ...
;         for (int r = 0; r < R; ++r) { const int m = mb + r * NGW; if (m < MT) {
;             const float rstd = 1.0f / sqrtf(s[r] * (1.0f / DM) + RMS_EPS);
;             const float* mr = MOD + (size_t)(m < MP ? (m >> 13) : 8 + ((m - MP) >> 12)) * 6144;
; #pragma unroll
;             for (int j = 0; j < 4; ++j) { const int c = 4 * lane + 256 * j;
;                 const f32x4 gg = *(const f32x4*)(g + c), sc = *(const f32x4*)(mr + scoff + c), sh = *(const f32x4*)(mr + shoff + c);
;                 const f32x4 o = v[r][j] * rstd * gg * (sc + 1.0f) + sh; v2u w; w.x = pk2(o.x, o.y); w.y = pk2(o.z, o.w); *(v2u*)(U + (size_t)m * DM + c) = w; } } }
	v_fma_f32 v248, -v248, v230, v228
	v_div_fmas_f32 v248, v248, v249, v230
	v_div_fixup_f32 v234, v248, v247, 1.0
	v_fmamk_f32 v240, v226, 0x3a800000, v89
	v_mul_f32_e32 v241, 0x4f800000, v240
	v_cmp_gt_f32_e32 vcc, s54, v240
	s_nop 1
	v_cndmask_b32_e32 v247, v240, v241, vcc
	v_sqrt_f32_e32 v242, v247
	s_nop 1
	v_add_u32_e32 v243, -1, v242
	v_add_u32_e32 v244, 1, v242
	v_fma_f32 v245, -v243, v242, v247
	v_fma_f32 v246, -v244, v242, v247
	v_cmp_ge_f32_e64 s[52:53], 0, v245
	s_nop 1
	v_cndmask_b32_e64 v242, v242, v243, s[52:53]
	v_cmp_lt_f32_e64 s[52:53], 0, v246
	s_nop 1
	v_cndmask_b32_e64 v242, v242, v244, s[52:53]
	v_mul_f32_e32 v243, 0x37800000, v242
	v_cndmask_b32_e32 v242, v242, v243, vcc
	v_cmp_class_f32_e32 vcc, v247, v90
	s_nop 1
	v_cndmask_b32_e32 v247, v242, v247, vcc
	v_div_scale_f32 v248, s[52:53], v247, v247, 1.0
	v_rcp_f32_e32 v249, v248
	v_div_scale_f32 v228, vcc, 1.0, v247, 1.0
	s_nop 0
	v_fma_f32 v229, -v248, v249, 1.0
	v_fmac_f32_e32 v249, v229, v249
	v_mul_f32_e32 v230, v228, v249
	v_fma_f32 v229, -v248, v230, v228
	v_fmac_f32_e32 v230, v229, v249
	v_fma_f32 v248, -v248, v230, v228
	v_div_fmas_f32 v248, v248, v249, v230
	v_div_fixup_f32 v236, v248, v247, 1.0
	v_fmamk_f32 v240, v227, 0x3a800000, v89
	v_mul_f32_e32 v241, 0x4f800000, v240
	v_cmp_gt_f32_e32 vcc, s54, v240
	s_nop 1
	v_cndmask_b32_e32 v247, v240, v241, vcc
	v_sqrt_f32_e32 v242, v247
	s_nop 1
	v_add_u32_e32 v243, -1, v242
	v_add_u32_e32 v244, 1, v242
	v_fma_f32 v245, -v243, v242, v247
	v_fma_f32 v246, -v244, v242, v247
	v_cmp_ge_f32_e64 s[52:53], 0, v245
	s_nop 1
	v_cndmask_b32_e64 v242, v242, v243, s[52:53]
	v_cmp_lt_f32_e64 s[52:53], 0, v246
	s_nop 1
	v_cndmask_b32_e64 v242, v242, v244, s[52:53]
	v_mul_f32_e32 v243, 0x37800000, v242
	v_cndmask_b32_e32 v242, v242, v243, vcc
	v_cmp_class_f32_e32 vcc, v247, v90
	s_nop 1
	v_cndmask_b32_e32 v247, v242, v247, vcc
	v_div_scale_f32 v248, s[52:53], v247, v247, 1.0
	v_rcp_f32_e32 v249, v248
	v_div_scale_f32 v228, vcc, 1.0, v247, 1.0
	s_nop 0
	v_fma_f32 v229, -v248, v249, 1.0
	v_fmac_f32_e32 v249, v229, v249
	v_mul_f32_e32 v230, v228, v249
	v_fma_f32 v229, -v248, v230, v228
	v_fmac_f32_e32 v230, v229, v249
	v_fma_f32 v248, -v248, v230, v228
	v_div_fmas_f32 v248, v248, v249, v230
	v_div_fixup_f32 v238, v248, v247, 1.0
	s_waitcnt vmcnt(16)
	v_pk_add_f32 v[160:161], v[160:161], 1.0 op_sel_hi:[1,0]
	v_pk_add_f32 v[162:163], v[162:163], 1.0 op_sel_hi:[1,0]
	v_pk_add_f32 v[164:165], v[164:165], 1.0 op_sel_hi:[1,0]
	v_pk_add_f32 v[166:167], v[166:167], 1.0 op_sel_hi:[1,0]
	v_pk_add_f32 v[168:169], v[168:169], 1.0 op_sel_hi:[1,0]
	v_pk_add_f32 v[170:171], v[170:171], 1.0 op_sel_hi:[1,0]
	v_pk_add_f32 v[172:173], v[172:173], 1.0 op_sel_hi:[1,0]
	v_pk_add_f32 v[174:175], v[174:175], 1.0 op_sel_hi:[1,0]
	v_pk_add_f32 v[192:193], v[192:193], 1.0 op_sel_hi:[1,0]
	v_pk_add_f32 v[194:195], v[194:195], 1.0 op_sel_hi:[1,0]
	v_pk_add_f32 v[196:197], v[196:197], 1.0 op_sel_hi:[1,0]
	v_pk_add_f32 v[198:199], v[198:199], 1.0 op_sel_hi:[1,0]
	v_pk_add_f32 v[200:201], v[200:201], 1.0 op_sel_hi:[1,0]
	v_pk_add_f32 v[202:203], v[202:203], 1.0 op_sel_hi:[1,0]
	v_pk_add_f32 v[204:205], v[204:205], 1.0 op_sel_hi:[1,0]
	v_pk_add_f32 v[206:207], v[206:207], 1.0 op_sel_hi:[1,0]
	s_mov_b64 s[38:39], s[20:21]
	s_add_u32 s40, s20, 0x400000
	s_addc_u32 s41, s21, 0
	s_add_u32 s46, s20, 0x800000
	s_addc_u32 s47, s21, 0
	s_add_u32 s48, s20, 0xc00000
	s_addc_u32 s49, s21, 0
	v_pk_mul_f32 v[0:1], v[0:1], v[232:233] op_sel_hi:[1,0]
	v_pk_mul_f32 v[2:3], v[2:3], v[232:233] op_sel_hi:[1,0]
	v_pk_mul_f32 v[0:1], v[64:65], v[0:1]
	v_pk_mul_f32 v[2:3], v[66:67], v[2:3]
	v_pk_fma_f32 v[0:1], v[160:161], v[0:1], v[176:177]
	v_pk_fma_f32 v[2:3], v[162:163], v[2:3], v[178:179]
	v_cvt_pk_bf16_f32 v244, v0, v1
	v_cvt_pk_bf16_f32 v245, v2, v3
	v_pk_mul_f32 v[4:5], v[4:5], v[232:233] op_sel_hi:[1,0]
	v_pk_mul_f32 v[6:7], v[6:7], v[232:233] op_sel_hi:[1,0]
	v_pk_mul_f32 v[4:5], v[68:69], v[4:5]
	v_pk_mul_f32 v[6:7], v[70:71], v[6:7]
	v_pk_fma_f32 v[4:5], v[164:165], v[4:5], v[180:181]
	v_pk_fma_f32 v[6:7], v[166:167], v[6:7], v[182:183]
	v_cvt_pk_bf16_f32 v246, v4, v5
	v_cvt_pk_bf16_f32 v247, v6, v7
	global_store_dwordx4 v82, v[244:247], s[38:39] offset:0
	v_pk_mul_f32 v[8:9], v[8:9], v[232:233] op_sel_hi:[1,0]
	v_pk_mul_f32 v[10:11], v[10:11], v[232:233] op_sel_hi:[1,0]
	v_pk_mul_f32 v[8:9], v[72:73], v[8:9]
	v_pk_mul_f32 v[10:11], v[74:75], v[10:11]
	v_pk_fma_f32 v[8:9], v[168:169], v[8:9], v[184:185]
	v_pk_fma_f32 v[10:11], v[170:171], v[10:11], v[186:187]
	v_cvt_pk_bf16_f32 v240, v8, v9
	v_cvt_pk_bf16_f32 v241, v10, v11
	v_pk_mul_f32 v[12:13], v[12:13], v[232:233] op_sel_hi:[1,0]
	v_pk_mul_f32 v[14:15], v[14:15], v[232:233] op_sel_hi:[1,0]
	v_pk_mul_f32 v[12:13], v[76:77], v[12:13]
	v_pk_mul_f32 v[14:15], v[78:79], v[14:15]
	v_pk_fma_f32 v[12:13], v[172:173], v[12:13], v[188:189]
	v_pk_fma_f32 v[14:15], v[174:175], v[14:15], v[190:191]
	v_cvt_pk_bf16_f32 v242, v12, v13
	v_cvt_pk_bf16_f32 v243, v14, v15
	global_store_dwordx4 v82, v[240:243], s[38:39] offset:1024
	v_pk_mul_f32 v[16:17], v[16:17], v[234:235] op_sel_hi:[1,0]
	v_pk_mul_f32 v[18:19], v[18:19], v[234:235] op_sel_hi:[1,0]
	v_pk_mul_f32 v[16:17], v[64:65], v[16:17]
	v_pk_mul_f32 v[18:19], v[66:67], v[18:19]
	v_pk_fma_f32 v[16:17], v[160:161], v[16:17], v[176:177]
	v_pk_fma_f32 v[18:19], v[162:163], v[18:19], v[178:179]
	v_cvt_pk_bf16_f32 v244, v16, v17
	v_cvt_pk_bf16_f32 v245, v18, v19
	v_pk_mul_f32 v[20:21], v[20:21], v[234:235] op_sel_hi:[1,0]
	v_pk_mul_f32 v[22:23], v[22:23], v[234:235] op_sel_hi:[1,0]
	v_pk_mul_f32 v[20:21], v[68:69], v[20:21]
	v_pk_mul_f32 v[22:23], v[70:71], v[22:23]
; __device__ __forceinline__ float bf_lo(unsigned w) { return __uint_as_float(w << 16); }
; __device__ __forceinline__ float bf_hi(unsigned w) { return __uint_as_float(w & 0xffff0000u); }
; __device__ __forceinline__ unsigned pk2(float lo, float hi) { return pg8::cvt_pk_bf16(lo, hi); }
; template <bool BF> __device__ __forceinline__ void prep_rows(const float* xp, const float* xs, const bf16* hb, const float* g, const float* MOD, int shoff, int scoff, bf16* U, int gw, int NGW, int lane) {
;     ...
;     for (int mb = gw; mb < MT; mb += R * NGW) {
;         f32x4 v[R][4]; float s[R];
; #pragma unroll
;         for (int r = 0; r < R; ++r) { const int m = mb + r * NGW; const int mc = m < MT ? m : mb;
; #pragma unroll
;             for (int j = 0; j < 4; ++j) {
;                 if (BF) { const v2u a0 = *(const v2u*)(hb + (size_t)mc * DM + 4 * lane + 256 * j);
;                     v[r][j].x = pg8::bf_lo(a0.x); v[r][j].y = pg8::bf_hi(a0.x); v[r][j].z = pg8::bf_lo(a0.y); v[r][j].w = pg8::bf_hi(a0.y); }
;                 else { const float* xr = mc < MP ? xp + (size_t)mc * DM : xs + (size_t)(mc - MP) * DM; v[r][j] = *(const f32x4*)(xr + 4 * lane + 256 * j); } } }
;     ...
;         for (int r = 0; r < R; ++r) { const int m = mb + r * NGW; if (m < MT) {
;             const float rstd = 1.0f / sqrtf(s[r] * (1.0f / DM) + RMS_EPS);
;             const float* mr = MOD + (size_t)(m < MP ? (m >> 13) : 8 + ((m - MP) >> 12)) * 6144;
; #pragma unroll
;             for (int j = 0; j < 4; ++j) { const int c = 4 * lane + 256 * j;
;                 const f32x4 gg = *(const f32x4*)(g + c), sc = *(const f32x4*)(mr + scoff + c), sh = *(const f32x4*)(mr + shoff + c);
;                 const f32x4 o = v[r][j] * rstd * gg * (sc + 1.0f) + sh; v2u w; w.x = pk2(o.x, o.y); w.y = pk2(o.z, o.w); *(v2u*)(U + (size_t)m * DM + c) = w; } } }
	v_pk_fma_f32 v[20:21], v[164:165], v[20:21], v[180:181]
	v_pk_fma_f32 v[22:23], v[166:167], v[22:23], v[182:183]
	v_cvt_pk_bf16_f32 v246, v20, v21
	v_cvt_pk_bf16_f32 v247, v22, v23
	global_store_dwordx4 v82, v[244:247], s[40:41] offset:0
	v_pk_mul_f32 v[24:25], v[24:25], v[234:235] op_sel_hi:[1,0]
	v_pk_mul_f32 v[26:27], v[26:27], v[234:235] op_sel_hi:[1,0]
	v_pk_mul_f32 v[24:25], v[72:73], v[24:25]
	v_pk_mul_f32 v[26:27], v[74:75], v[26:27]
	v_pk_fma_f32 v[24:25], v[168:169], v[24:25], v[184:185]
	v_pk_fma_f32 v[26:27], v[170:171], v[26:27], v[186:187]
	v_cvt_pk_bf16_f32 v240, v24, v25
	v_cvt_pk_bf16_f32 v241, v26, v27
	v_pk_mul_f32 v[28:29], v[28:29], v[234:235] op_sel_hi:[1,0]
	v_pk_mul_f32 v[30:31], v[30:31], v[234:235] op_sel_hi:[1,0]
	v_pk_mul_f32 v[28:29], v[76:77], v[28:29]
	v_pk_mul_f32 v[30:31], v[78:79], v[30:31]
	v_pk_fma_f32 v[28:29], v[172:173], v[28:29], v[188:189]
	v_pk_fma_f32 v[30:31], v[174:175], v[30:31], v[190:191]
	v_cvt_pk_bf16_f32 v242, v28, v29
	v_cvt_pk_bf16_f32 v243, v30, v31
	global_store_dwordx4 v82, v[240:243], s[40:41] offset:1024
	v_pk_mul_f32 v[32:33], v[32:33], v[236:237] op_sel_hi:[1,0]
	v_pk_mul_f32 v[34:35], v[34:35], v[236:237] op_sel_hi:[1,0]
	v_pk_mul_f32 v[32:33], v[64:65], v[32:33]
	v_pk_mul_f32 v[34:35], v[66:67], v[34:35]
	v_pk_fma_f32 v[32:33], v[192:193], v[32:33], v[208:209]
	v_pk_fma_f32 v[34:35], v[194:195], v[34:35], v[210:211]
	v_cvt_pk_bf16_f32 v244, v32, v33
	v_cvt_pk_bf16_f32 v245, v34, v35
	v_pk_mul_f32 v[36:37], v[36:37], v[236:237] op_sel_hi:[1,0]
	v_pk_mul_f32 v[38:39], v[38:39], v[236:237] op_sel_hi:[1,0]
	v_pk_mul_f32 v[36:37], v[68:69], v[36:37]
	v_pk_mul_f32 v[38:39], v[70:71], v[38:39]
	v_pk_fma_f32 v[36:37], v[196:197], v[36:37], v[212:213]
	v_pk_fma_f32 v[38:39], v[198:199], v[38:39], v[214:215]
	v_cvt_pk_bf16_f32 v246, v36, v37
	v_cvt_pk_bf16_f32 v247, v38, v39
	global_store_dwordx4 v82, v[244:247], s[46:47] offset:0
	v_pk_mul_f32 v[40:41], v[40:41], v[236:237] op_sel_hi:[1,0]
	v_pk_mul_f32 v[42:43], v[42:43], v[236:237] op_sel_hi:[1,0]
	v_pk_mul_f32 v[40:41], v[72:73], v[40:41]
	v_pk_mul_f32 v[42:43], v[74:75], v[42:43]
	v_pk_fma_f32 v[40:41], v[200:201], v[40:41], v[216:217]
	v_pk_fma_f32 v[42:43], v[202:203], v[42:43], v[218:219]
	v_cvt_pk_bf16_f32 v240, v40, v41
	v_cvt_pk_bf16_f32 v241, v42, v43
	v_pk_mul_f32 v[44:45], v[44:45], v[236:237] op_sel_hi:[1,0]
	v_pk_mul_f32 v[46:47], v[46:47], v[236:237] op_sel_hi:[1,0]
	v_pk_mul_f32 v[44:45], v[76:77], v[44:45]
	v_pk_mul_f32 v[46:47], v[78:79], v[46:47]
	v_pk_fma_f32 v[44:45], v[204:205], v[44:45], v[220:221]
	v_pk_fma_f32 v[46:47], v[206:207], v[46:47], v[222:223]
	v_cvt_pk_bf16_f32 v242, v44, v45
	v_cvt_pk_bf16_f32 v243, v46, v47
	global_store_dwordx4 v82, v[240:243], s[46:47] offset:1024
	v_pk_mul_f32 v[48:49], v[48:49], v[238:239] op_sel_hi:[1,0]
	v_pk_mul_f32 v[50:51], v[50:51], v[238:239] op_sel_hi:[1,0]
	v_pk_mul_f32 v[48:49], v[64:65], v[48:49]
	v_pk_mul_f32 v[50:51], v[66:67], v[50:51]
	v_pk_fma_f32 v[48:49], v[192:193], v[48:49], v[208:209]
	v_pk_fma_f32 v[50:51], v[194:195], v[50:51], v[210:211]
	v_cvt_pk_bf16_f32 v244, v48, v49
	v_cvt_pk_bf16_f32 v245, v50, v51
	v_pk_mul_f32 v[52:53], v[52:53], v[238:239] op_sel_hi:[1,0]
	v_pk_mul_f32 v[54:55], v[54:55], v[238:239] op_sel_hi:[1,0]
	v_pk_mul_f32 v[52:53], v[68:69], v[52:53]
	v_pk_mul_f32 v[54:55], v[70:71], v[54:55]
	v_pk_fma_f32 v[52:53], v[196:197], v[52:53], v[212:213]
	v_pk_fma_f32 v[54:55], v[198:199], v[54:55], v[214:215]
	v_cvt_pk_bf16_f32 v246, v52, v53
	v_cvt_pk_bf16_f32 v247, v54, v55
	global_store_dwordx4 v82, v[244:247], s[48:49] offset:0
	v_pk_mul_f32 v[56:57], v[56:57], v[238:239] op_sel_hi:[1,0]
	v_pk_mul_f32 v[58:59], v[58:59], v[238:239] op_sel_hi:[1,0]
	v_pk_mul_f32 v[56:57], v[72:73], v[56:57]
	v_pk_mul_f32 v[58:59], v[74:75], v[58:59]
	v_pk_fma_f32 v[56:57], v[200:201], v[56:57], v[216:217]
	v_pk_fma_f32 v[58:59], v[202:203], v[58:59], v[218:219]
	v_cvt_pk_bf16_f32 v240, v56, v57
	v_cvt_pk_bf16_f32 v241, v58, v59
	v_pk_mul_f32 v[60:61], v[60:61], v[238:239] op_sel_hi:[1,0]
	v_pk_mul_f32 v[62:63], v[62:63], v[238:239] op_sel_hi:[1,0]
	v_pk_mul_f32 v[60:61], v[76:77], v[60:61]
	v_pk_mul_f32 v[62:63], v[78:79], v[62:63]
	v_pk_fma_f32 v[60:61], v[204:205], v[60:61], v[220:221]
	v_pk_fma_f32 v[62:63], v[206:207], v[62:63], v[222:223]
	v_cvt_pk_bf16_f32 v242, v60, v61
	v_cvt_pk_bf16_f32 v243, v62, v63
	global_store_dwordx4 v82, v[240:243], s[48:49] offset:1024
	s_add_u32 s34, s8, 0x6000
	s_addc_u32 s35, s9, 0
	s_add_u32 s36, s8, 0x6000
	s_addc_u32 s37, s9, 0
	global_load_dwordx4 v[176:179], v80, s[34:35] offset:0
	global_load_dwordx4 v[180:183], v80, s[34:35] offset:16
	global_load_dwordx4 v[184:187], v80, s[34:35] offset:2048
	global_load_dwordx4 v[188:191], v80, s[34:35] offset:2064
	global_load_dwordx4 v[160:163], v81, s[34:35] offset:0
	global_load_dwordx4 v[164:167], v81, s[34:35] offset:16
	global_load_dwordx4 v[168:171], v81, s[34:35] offset:2048
	global_load_dwordx4 v[172:175], v81, s[34:35] offset:2064
	global_load_dwordx4 v[208:211], v80, s[36:37] offset:0
	global_load_dwordx4 v[212:215], v80, s[36:37] offset:16
	global_load_dwordx4 v[216:219], v80, s[36:37] offset:2048
	global_load_dwordx4 v[220:223], v80, s[36:37] offset:2064
	global_load_dwordx4 v[192:195], v81, s[36:37] offset:0
	global_load_dwordx4 v[196:199], v81, s[36:37] offset:16
	global_load_dwordx4 v[200:203], v81, s[36:37] offset:2048
	global_load_dwordx4 v[204:207], v81, s[36:37] offset:2064
	s_add_u32 s24, s16, 0x4000000
	s_addc_u32 s25, s17, 0
	s_add_u32 s26, s16, 0x4800000
	s_addc_u32 s27, s17, 0
	s_add_u32 s28, s16, 0x5000000
	s_addc_u32 s29, s17, 0
	s_add_u32 s30, s16, 0x5800000
	s_addc_u32 s31, s17, 0
	global_load_dwordx4 v[0:3], v80, s[24:25] offset:0 nt
	global_load_dwordx4 v[4:7], v80, s[24:25] offset:16 nt
	global_load_dwordx4 v[8:11], v80, s[24:25] offset:2048 nt
	global_load_dwordx4 v[12:15], v80, s[24:25] offset:2064 nt
	global_load_dwordx4 v[16:19], v80, s[26:27] offset:0 nt
	global_load_dwordx4 v[20:23], v80, s[26:27] offset:16 nt
	global_load_dwordx4 v[24:27], v80, s[26:27] offset:2048 nt
	global_load_dwordx4 v[28:31], v80, s[26:27] offset:2064 nt
	global_load_dwordx4 v[32:35], v80, s[28:29] offset:0 nt
	global_load_dwordx4 v[36:39], v80, s[28:29] offset:16 nt
	global_load_dwordx4 v[40:43], v80, s[28:29] offset:2048 nt
	global_load_dwordx4 v[44:47], v80, s[28:29] offset:2064 nt
	global_load_dwordx4 v[48:51], v80, s[30:31] offset:0 nt
	global_load_dwordx4 v[52:55], v80, s[30:31] offset:16 nt
	global_load_dwordx4 v[56:59], v80, s[30:31] offset:2048 nt
	global_load_dwordx4 v[60:63], v80, s[30:31] offset:2064 nt
	s_waitcnt vmcnt(40)
; template <bool BF> __device__ __forceinline__ void prep_rows(const float* xp, const float* xs, const bf16* hb, const float* g, const float* MOD, int shoff, int scoff, bf16* U, int gw, int NGW, int lane) {
;     ...
; #pragma unroll
;         for (int r = 0; r < R; ++r) { float t = 0.f;
; #pragma unroll
;             for (int j = 0; j < 4; ++j) t += (v[r][j].x * v[r][j].x + v[r][j].y * v[r][j].y) + (v[r][j].z * v[r][j].z + v[r][j].w * v[r][j].w);
;             s[r] = t; }
; #pragma unroll
;         for (int o = 1; o < 64; o <<= 1) {
; #pragma unroll
;             for (int r = 0; r < R; ++r) s[r] += __shfl_xor(s[r], o); }
; #pragma unroll
;         for (int r = 0; r < R; ++r) { const int m = mb + r * NGW; if (m < MT) {
;             const float rstd = 1.0f / sqrtf(s[r] * (1.0f / DM) + RMS_EPS);
	v_pk_mul_f32 v[240:241], v[96:97], v[96:97]
	v_pk_mul_f32 v[242:243], v[112:113], v[112:113]
	v_pk_mul_f32 v[244:245], v[128:129], v[128:129]
	v_pk_mul_f32 v[246:247], v[144:145], v[144:145]
	v_pk_fma_f32 v[240:241], v[98:99], v[98:99], v[240:241]
	v_pk_fma_f32 v[242:243], v[114:115], v[114:115], v[242:243]
	v_pk_fma_f32 v[244:245], v[130:131], v[130:131], v[244:245]
	v_pk_fma_f32 v[246:247], v[146:147], v[146:147], v[246:247]
	v_pk_fma_f32 v[240:241], v[100:101], v[100:101], v[240:241]
	v_pk_fma_f32 v[242:243], v[116:117], v[116:117], v[242:243]
	v_pk_fma_f32 v[244:245], v[132:133], v[132:133], v[244:245]
	v_pk_fma_f32 v[246:247], v[148:149], v[148:149], v[246:247]
	v_pk_fma_f32 v[240:241], v[102:103], v[102:103], v[240:241]
	v_pk_fma_f32 v[242:243], v[118:119], v[118:119], v[242:243]
	v_pk_fma_f32 v[244:245], v[134:135], v[134:135], v[244:245]
	v_pk_fma_f32 v[246:247], v[150:151], v[150:151], v[246:247]
	v_pk_fma_f32 v[240:241], v[104:105], v[104:105], v[240:241]
	v_pk_fma_f32 v[242:243], v[120:121], v[120:121], v[242:243]
	v_pk_fma_f32 v[244:245], v[136:137], v[136:137], v[244:245]
	v_pk_fma_f32 v[246:247], v[152:153], v[152:153], v[246:247]
	v_pk_fma_f32 v[240:241], v[106:107], v[106:107], v[240:241]
	v_pk_fma_f32 v[242:243], v[122:123], v[122:123], v[242:243]
	v_pk_fma_f32 v[244:245], v[138:139], v[138:139], v[244:245]
	v_pk_fma_f32 v[246:247], v[154:155], v[154:155], v[246:247]
	v_pk_fma_f32 v[240:241], v[108:109], v[108:109], v[240:241]
	v_pk_fma_f32 v[242:243], v[124:125], v[124:125], v[242:243]
	v_pk_fma_f32 v[244:245], v[140:141], v[140:141], v[244:245]
	v_pk_fma_f32 v[246:247], v[156:157], v[156:157], v[246:247]
	v_pk_fma_f32 v[240:241], v[110:111], v[110:111], v[240:241]
	v_pk_fma_f32 v[242:243], v[126:127], v[126:127], v[242:243]
	v_pk_fma_f32 v[244:245], v[142:143], v[142:143], v[244:245]
	v_pk_fma_f32 v[246:247], v[158:159], v[158:159], v[246:247]
	v_add_f32_e32 v224, v240, v241
	v_add_f32_e32 v225, v242, v243
	v_add_f32_e32 v226, v244, v245
	v_add_f32_e32 v227, v246, v247
	ds_bpermute_b32 v228, v83, v224
	ds_bpermute_b32 v229, v83, v225
	ds_bpermute_b32 v230, v83, v226
	ds_bpermute_b32 v231, v83, v227
	s_waitcnt lgkmcnt(0)
	v_add_f32_e32 v224, v224, v228
	v_add_f32_e32 v225, v225, v229
	v_add_f32_e32 v226, v226, v230
	v_add_f32_e32 v227, v227, v231
	ds_bpermute_b32 v228, v84, v224
	ds_bpermute_b32 v229, v84, v225
	ds_bpermute_b32 v230, v84, v226
	ds_bpermute_b32 v231, v84, v227
	s_waitcnt lgkmcnt(0)
	v_add_f32_e32 v224, v224, v228
	v_add_f32_e32 v225, v225, v229
	v_add_f32_e32 v226, v226, v230
	v_add_f32_e32 v227, v227, v231
	ds_bpermute_b32 v228, v85, v224
	ds_bpermute_b32 v229, v85, v225
	ds_bpermute_b32 v230, v85, v226
	ds_bpermute_b32 v231, v85, v227
	s_waitcnt lgkmcnt(0)
	v_add_f32_e32 v224, v224, v228
	v_add_f32_e32 v225, v225, v229
	v_add_f32_e32 v226, v226, v230
	v_add_f32_e32 v227, v227, v231
	ds_bpermute_b32 v228, v86, v224
	ds_bpermute_b32 v229, v86, v225
	ds_bpermute_b32 v230, v86, v226
	ds_bpermute_b32 v231, v86, v227
	s_waitcnt lgkmcnt(0)
	v_add_f32_e32 v224, v224, v228
	v_add_f32_e32 v225, v225, v229
	v_add_f32_e32 v226, v226, v230
	v_add_f32_e32 v227, v227, v231
	ds_bpermute_b32 v228, v87, v224
	ds_bpermute_b32 v229, v87, v225
	ds_bpermute_b32 v230, v87, v226
	ds_bpermute_b32 v231, v87, v227
	s_waitcnt lgkmcnt(0)
	v_add_f32_e32 v224, v224, v228
	v_add_f32_e32 v225, v225, v229
	v_add_f32_e32 v226, v226, v230
	v_add_f32_e32 v227, v227, v231
	ds_bpermute_b32 v228, v88, v224
	ds_bpermute_b32 v229, v88, v225
	ds_bpermute_b32 v230, v88, v226
	ds_bpermute_b32 v231, v88, v227
	s_waitcnt lgkmcnt(0)
	v_add_f32_e32 v224, v224, v228
	v_add_f32_e32 v225, v225, v229
	v_add_f32_e32 v226, v226, v230
	v_add_f32_e32 v227, v227, v231
	v_fmamk_f32 v240, v224, 0x3a800000, v89
	v_mul_f32_e32 v241, 0x4f800000, v240
	v_cmp_gt_f32_e32 vcc, s54, v240
	s_nop 1
	v_cndmask_b32_e32 v247, v240, v241, vcc
	v_sqrt_f32_e32 v242, v247
	s_nop 1
	v_add_u32_e32 v243, -1, v242
	v_add_u32_e32 v244, 1, v242
	v_fma_f32 v245, -v243, v242, v247
	v_fma_f32 v246, -v244, v242, v247
	v_cmp_ge_f32_e64 s[52:53], 0, v245
	s_nop 1
	v_cndmask_b32_e64 v242, v242, v243, s[52:53]
	v_cmp_lt_f32_e64 s[52:53], 0, v246
	s_nop 1
	v_cndmask_b32_e64 v242, v242, v244, s[52:53]
	v_mul_f32_e32 v243, 0x37800000, v242
	v_cndmask_b32_e32 v242, v242, v243, vcc
	v_cmp_class_f32_e32 vcc, v247, v90
	s_nop 1
	v_cndmask_b32_e32 v247, v242, v247, vcc
	v_div_scale_f32 v248, s[52:53], v247, v247, 1.0
	v_rcp_f32_e32 v249, v248
	v_div_scale_f32 v228, vcc, 1.0, v247, 1.0
	s_nop 0
	v_fma_f32 v229, -v248, v249, 1.0
	v_fmac_f32_e32 v249, v229, v249
	v_mul_f32_e32 v230, v228, v249
	v_fma_f32 v229, -v248, v230, v228
	v_fmac_f32_e32 v230, v229, v249
	v_fma_f32 v248, -v248, v230, v228
	v_div_fmas_f32 v248, v248, v249, v230
	v_div_fixup_f32 v232, v248, v247, 1.0
	v_fmamk_f32 v240, v225, 0x3a800000, v89
	v_mul_f32_e32 v241, 0x4f800000, v240
	v_cmp_gt_f32_e32 vcc, s54, v240
	s_nop 1
	v_cndmask_b32_e32 v247, v240, v241, vcc
	v_sqrt_f32_e32 v242, v247
	s_nop 1
	v_add_u32_e32 v243, -1, v242
	v_add_u32_e32 v244, 1, v242
	v_fma_f32 v245, -v243, v242, v247
	v_fma_f32 v246, -v244, v242, v247
	v_cmp_ge_f32_e64 s[52:53], 0, v245
	s_nop 1
	v_cndmask_b32_e64 v242, v242, v243, s[52:53]
	v_cmp_lt_f32_e64 s[52:53], 0, v246
	s_nop 1
	v_cndmask_b32_e64 v242, v242, v244, s[52:53]
	v_mul_f32_e32 v243, 0x37800000, v242
	v_cndmask_b32_e32 v242, v242, v243, vcc
	v_cmp_class_f32_e32 vcc, v247, v90
	s_nop 1
	v_cndmask_b32_e32 v247, v242, v247, vcc
	v_div_scale_f32 v248, s[52:53], v247, v247, 1.0
	v_rcp_f32_e32 v249, v248
	v_div_scale_f32 v228, vcc, 1.0, v247, 1.0
	s_nop 0
	v_fma_f32 v229, -v248, v249, 1.0
; __device__ __forceinline__ unsigned pk2(float lo, float hi) { return pg8::cvt_pk_bf16(lo, hi); }
; template <bool BF> __device__ __forceinline__ void prep_rows(const float* xp, const float* xs, const bf16* hb, const float* g, const float* MOD, int shoff, int scoff, bf16* U, int gw, int NGW, int lane) {
;     ...
;         for (int r = 0; r < R; ++r) { const int m = mb + r * NGW; if (m < MT) {
;             const float rstd = 1.0f / sqrtf(s[r] * (1.0f / DM) + RMS_EPS);
;             const float* mr = MOD + (size_t)(m < MP ? (m >> 13) : 8 + ((m - MP) >> 12)) * 6144;
; #pragma unroll
;             for (int j = 0; j < 4; ++j) { const int c = 4 * lane + 256 * j;
;                 const f32x4 gg = *(const f32x4*)(g + c), sc = *(const f32x4*)(mr + scoff + c), sh = *(const f32x4*)(mr + shoff + c);
;                 const f32x4 o = v[r][j] * rstd * gg * (sc + 1.0f) + sh; v2u w; w.x = pk2(o.x, o.y); w.y = pk2(o.z, o.w); *(v2u*)(U + (size_t)m * DM + c) = w; } } }
	v_fmac_f32_e32 v249, v229, v249
	v_mul_f32_e32 v230, v228, v249
	v_fma_f32 v229, -v248, v230, v228
	v_fmac_f32_e32 v230, v229, v249
	v_fma_f32 v248, -v248, v230, v228
	v_div_fmas_f32 v248, v248, v249, v230
	v_div_fixup_f32 v234, v248, v247, 1.0
	v_fmamk_f32 v240, v226, 0x3a800000, v89
	v_mul_f32_e32 v241, 0x4f800000, v240
	v_cmp_gt_f32_e32 vcc, s54, v240
	s_nop 1
	v_cndmask_b32_e32 v247, v240, v241, vcc
	v_sqrt_f32_e32 v242, v247
	s_nop 1
	v_add_u32_e32 v243, -1, v242
	v_add_u32_e32 v244, 1, v242
	v_fma_f32 v245, -v243, v242, v247
	v_fma_f32 v246, -v244, v242, v247
	v_cmp_ge_f32_e64 s[52:53], 0, v245
	s_nop 1
	v_cndmask_b32_e64 v242, v242, v243, s[52:53]
	v_cmp_lt_f32_e64 s[52:53], 0, v246
	s_nop 1
	v_cndmask_b32_e64 v242, v242, v244, s[52:53]
	v_mul_f32_e32 v243, 0x37800000, v242
	v_cndmask_b32_e32 v242, v242, v243, vcc
	v_cmp_class_f32_e32 vcc, v247, v90
	s_nop 1
	v_cndmask_b32_e32 v247, v242, v247, vcc
	v_div_scale_f32 v248, s[52:53], v247, v247, 1.0
	v_rcp_f32_e32 v249, v248
	v_div_scale_f32 v228, vcc, 1.0, v247, 1.0
	s_nop 0
	v_fma_f32 v229, -v248, v249, 1.0
	v_fmac_f32_e32 v249, v229, v249
	v_mul_f32_e32 v230, v228, v249
	v_fma_f32 v229, -v248, v230, v228
	v_fmac_f32_e32 v230, v229, v249
	v_fma_f32 v248, -v248, v230, v228
	v_div_fmas_f32 v248, v248, v249, v230
	v_div_fixup_f32 v236, v248, v247, 1.0
	v_fmamk_f32 v240, v227, 0x3a800000, v89
	v_mul_f32_e32 v241, 0x4f800000, v240
	v_cmp_gt_f32_e32 vcc, s54, v240
	s_nop 1
	v_cndmask_b32_e32 v247, v240, v241, vcc
	v_sqrt_f32_e32 v242, v247
	s_nop 1
	v_add_u32_e32 v243, -1, v242
	v_add_u32_e32 v244, 1, v242
	v_fma_f32 v245, -v243, v242, v247
	v_fma_f32 v246, -v244, v242, v247
	v_cmp_ge_f32_e64 s[52:53], 0, v245
	s_nop 1
	v_cndmask_b32_e64 v242, v242, v243, s[52:53]
	v_cmp_lt_f32_e64 s[52:53], 0, v246
	s_nop 1
	v_cndmask_b32_e64 v242, v242, v244, s[52:53]
	v_mul_f32_e32 v243, 0x37800000, v242
	v_cndmask_b32_e32 v242, v242, v243, vcc
	v_cmp_class_f32_e32 vcc, v247, v90
	s_nop 1
	v_cndmask_b32_e32 v247, v242, v247, vcc
	v_div_scale_f32 v248, s[52:53], v247, v247, 1.0
	v_rcp_f32_e32 v249, v248
	v_div_scale_f32 v228, vcc, 1.0, v247, 1.0
	s_nop 0
	v_fma_f32 v229, -v248, v249, 1.0
	v_fmac_f32_e32 v249, v229, v249
	v_mul_f32_e32 v230, v228, v249
	v_fma_f32 v229, -v248, v230, v228
	v_fmac_f32_e32 v230, v229, v249
	v_fma_f32 v248, -v248, v230, v228
	v_div_fmas_f32 v248, v248, v249, v230
	v_div_fixup_f32 v238, v248, v247, 1.0
	s_waitcnt vmcnt(16)
	v_pk_add_f32 v[160:161], v[160:161], 1.0 op_sel_hi:[1,0]
	v_pk_add_f32 v[162:163], v[162:163], 1.0 op_sel_hi:[1,0]
	v_pk_add_f32 v[164:165], v[164:165], 1.0 op_sel_hi:[1,0]
	v_pk_add_f32 v[166:167], v[166:167], 1.0 op_sel_hi:[1,0]
	v_pk_add_f32 v[168:169], v[168:169], 1.0 op_sel_hi:[1,0]
	v_pk_add_f32 v[170:171], v[170:171], 1.0 op_sel_hi:[1,0]
	v_pk_add_f32 v[172:173], v[172:173], 1.0 op_sel_hi:[1,0]
	v_pk_add_f32 v[174:175], v[174:175], 1.0 op_sel_hi:[1,0]
	v_pk_add_f32 v[192:193], v[192:193], 1.0 op_sel_hi:[1,0]
	v_pk_add_f32 v[194:195], v[194:195], 1.0 op_sel_hi:[1,0]
	v_pk_add_f32 v[196:197], v[196:197], 1.0 op_sel_hi:[1,0]
	v_pk_add_f32 v[198:199], v[198:199], 1.0 op_sel_hi:[1,0]
	v_pk_add_f32 v[200:201], v[200:201], 1.0 op_sel_hi:[1,0]
	v_pk_add_f32 v[202:203], v[202:203], 1.0 op_sel_hi:[1,0]
	v_pk_add_f32 v[204:205], v[204:205], 1.0 op_sel_hi:[1,0]
	v_pk_add_f32 v[206:207], v[206:207], 1.0 op_sel_hi:[1,0]
	s_add_u32 s38, s20, 0x1000000
	s_addc_u32 s39, s21, 0
	s_add_u32 s40, s20, 0x1400000
	s_addc_u32 s41, s21, 0
	s_add_u32 s46, s20, 0x1800000
	s_addc_u32 s47, s21, 0
	s_add_u32 s48, s20, 0x1c00000
	s_addc_u32 s49, s21, 0
	v_pk_mul_f32 v[96:97], v[96:97], v[232:233] op_sel_hi:[1,0]
	v_pk_mul_f32 v[98:99], v[98:99], v[232:233] op_sel_hi:[1,0]
	v_pk_mul_f32 v[96:97], v[64:65], v[96:97]
	v_pk_mul_f32 v[98:99], v[66:67], v[98:99]
	v_pk_fma_f32 v[96:97], v[160:161], v[96:97], v[176:177]
	v_pk_fma_f32 v[98:99], v[162:163], v[98:99], v[178:179]
	v_cvt_pk_bf16_f32 v244, v96, v97
	v_cvt_pk_bf16_f32 v245, v98, v99
	v_pk_mul_f32 v[100:101], v[100:101], v[232:233] op_sel_hi:[1,0]
	v_pk_mul_f32 v[102:103], v[102:103], v[232:233] op_sel_hi:[1,0]
	v_pk_mul_f32 v[100:101], v[68:69], v[100:101]
	v_pk_mul_f32 v[102:103], v[70:71], v[102:103]
	v_pk_fma_f32 v[100:101], v[164:165], v[100:101], v[180:181]
	v_pk_fma_f32 v[102:103], v[166:167], v[102:103], v[182:183]
	v_cvt_pk_bf16_f32 v246, v100, v101
	v_cvt_pk_bf16_f32 v247, v102, v103
	global_store_dwordx4 v82, v[244:247], s[38:39] offset:0
	v_pk_mul_f32 v[104:105], v[104:105], v[232:233] op_sel_hi:[1,0]
	v_pk_mul_f32 v[106:107], v[106:107], v[232:233] op_sel_hi:[1,0]
	v_pk_mul_f32 v[104:105], v[72:73], v[104:105]
	v_pk_mul_f32 v[106:107], v[74:75], v[106:107]
	v_pk_fma_f32 v[104:105], v[168:169], v[104:105], v[184:185]
	v_pk_fma_f32 v[106:107], v[170:171], v[106:107], v[186:187]
	v_cvt_pk_bf16_f32 v240, v104, v105
	v_cvt_pk_bf16_f32 v241, v106, v107
	v_pk_mul_f32 v[108:109], v[108:109], v[232:233] op_sel_hi:[1,0]
	v_pk_mul_f32 v[110:111], v[110:111], v[232:233] op_sel_hi:[1,0]
	v_pk_mul_f32 v[108:109], v[76:77], v[108:109]
	v_pk_mul_f32 v[110:111], v[78:79], v[110:111]
	v_pk_fma_f32 v[108:109], v[172:173], v[108:109], v[188:189]
	v_pk_fma_f32 v[110:111], v[174:175], v[110:111], v[190:191]
	v_cvt_pk_bf16_f32 v242, v108, v109
	v_cvt_pk_bf16_f32 v243, v110, v111
	global_store_dwordx4 v82, v[240:243], s[38:39] offset:1024
	v_pk_mul_f32 v[112:113], v[112:113], v[234:235] op_sel_hi:[1,0]
	v_pk_mul_f32 v[114:115], v[114:115], v[234:235] op_sel_hi:[1,0]
	v_pk_mul_f32 v[112:113], v[64:65], v[112:113]
	v_pk_mul_f32 v[114:115], v[66:67], v[114:115]
	v_pk_fma_f32 v[112:113], v[160:161], v[112:113], v[176:177]
; __device__ __forceinline__ float bf_lo(unsigned w) { return __uint_as_float(w << 16); }
; __device__ __forceinline__ float bf_hi(unsigned w) { return __uint_as_float(w & 0xffff0000u); }
; __device__ __forceinline__ unsigned pk2(float lo, float hi) { return pg8::cvt_pk_bf16(lo, hi); }
; template <bool BF> __device__ __forceinline__ void prep_rows(const float* xp, const float* xs, const bf16* hb, const float* g, const float* MOD, int shoff, int scoff, bf16* U, int gw, int NGW, int lane) {
;     ...
;     for (int mb = gw; mb < MT; mb += R * NGW) {
;         f32x4 v[R][4]; float s[R];
; #pragma unroll
;         for (int r = 0; r < R; ++r) { const int m = mb + r * NGW; const int mc = m < MT ? m : mb;
; #pragma unroll
;             for (int j = 0; j < 4; ++j) {
;                 if (BF) { const v2u a0 = *(const v2u*)(hb + (size_t)mc * DM + 4 * lane + 256 * j);
;                     v[r][j].x = pg8::bf_lo(a0.x); v[r][j].y = pg8::bf_hi(a0.x); v[r][j].z = pg8::bf_lo(a0.y); v[r][j].w = pg8::bf_hi(a0.y); }
;                 else { const float* xr = mc < MP ? xp + (size_t)mc * DM : xs + (size_t)(mc - MP) * DM; v[r][j] = *(const f32x4*)(xr + 4 * lane + 256 * j); } } }
;     ...
;         for (int r = 0; r < R; ++r) { const int m = mb + r * NGW; if (m < MT) {
;             const float rstd = 1.0f / sqrtf(s[r] * (1.0f / DM) + RMS_EPS);
;             const float* mr = MOD + (size_t)(m < MP ? (m >> 13) : 8 + ((m - MP) >> 12)) * 6144;
; #pragma unroll
;             for (int j = 0; j < 4; ++j) { const int c = 4 * lane + 256 * j;
;                 const f32x4 gg = *(const f32x4*)(g + c), sc = *(const f32x4*)(mr + scoff + c), sh = *(const f32x4*)(mr + shoff + c);
;                 const f32x4 o = v[r][j] * rstd * gg * (sc + 1.0f) + sh; v2u w; w.x = pk2(o.x, o.y); w.y = pk2(o.z, o.w); *(v2u*)(U + (size_t)m * DM + c) = w; } } }
	v_pk_fma_f32 v[114:115], v[162:163], v[114:115], v[178:179]
	v_cvt_pk_bf16_f32 v244, v112, v113
	v_cvt_pk_bf16_f32 v245, v114, v115
	v_pk_mul_f32 v[116:117], v[116:117], v[234:235] op_sel_hi:[1,0]
	v_pk_mul_f32 v[118:119], v[118:119], v[234:235] op_sel_hi:[1,0]
	v_pk_mul_f32 v[116:117], v[68:69], v[116:117]
	v_pk_mul_f32 v[118:119], v[70:71], v[118:119]
	v_pk_fma_f32 v[116:117], v[164:165], v[116:117], v[180:181]
	v_pk_fma_f32 v[118:119], v[166:167], v[118:119], v[182:183]
	v_cvt_pk_bf16_f32 v246, v116, v117
	v_cvt_pk_bf16_f32 v247, v118, v119
	global_store_dwordx4 v82, v[244:247], s[40:41] offset:0
	v_pk_mul_f32 v[120:121], v[120:121], v[234:235] op_sel_hi:[1,0]
	v_pk_mul_f32 v[122:123], v[122:123], v[234:235] op_sel_hi:[1,0]
	v_pk_mul_f32 v[120:121], v[72:73], v[120:121]
	v_pk_mul_f32 v[122:123], v[74:75], v[122:123]
	v_pk_fma_f32 v[120:121], v[168:169], v[120:121], v[184:185]
	v_pk_fma_f32 v[122:123], v[170:171], v[122:123], v[186:187]
	v_cvt_pk_bf16_f32 v240, v120, v121
	v_cvt_pk_bf16_f32 v241, v122, v123
	v_pk_mul_f32 v[124:125], v[124:125], v[234:235] op_sel_hi:[1,0]
	v_pk_mul_f32 v[126:127], v[126:127], v[234:235] op_sel_hi:[1,0]
	v_pk_mul_f32 v[124:125], v[76:77], v[124:125]
	v_pk_mul_f32 v[126:127], v[78:79], v[126:127]
	v_pk_fma_f32 v[124:125], v[172:173], v[124:125], v[188:189]
	v_pk_fma_f32 v[126:127], v[174:175], v[126:127], v[190:191]
	v_cvt_pk_bf16_f32 v242, v124, v125
	v_cvt_pk_bf16_f32 v243, v126, v127
	global_store_dwordx4 v82, v[240:243], s[40:41] offset:1024
	v_pk_mul_f32 v[128:129], v[128:129], v[236:237] op_sel_hi:[1,0]
	v_pk_mul_f32 v[130:131], v[130:131], v[236:237] op_sel_hi:[1,0]
	v_pk_mul_f32 v[128:129], v[64:65], v[128:129]
	v_pk_mul_f32 v[130:131], v[66:67], v[130:131]
	v_pk_fma_f32 v[128:129], v[192:193], v[128:129], v[208:209]
	v_pk_fma_f32 v[130:131], v[194:195], v[130:131], v[210:211]
	v_cvt_pk_bf16_f32 v244, v128, v129
	v_cvt_pk_bf16_f32 v245, v130, v131
	v_pk_mul_f32 v[132:133], v[132:133], v[236:237] op_sel_hi:[1,0]
	v_pk_mul_f32 v[134:135], v[134:135], v[236:237] op_sel_hi:[1,0]
	v_pk_mul_f32 v[132:133], v[68:69], v[132:133]
	v_pk_mul_f32 v[134:135], v[70:71], v[134:135]
	v_pk_fma_f32 v[132:133], v[196:197], v[132:133], v[212:213]
	v_pk_fma_f32 v[134:135], v[198:199], v[134:135], v[214:215]
	v_cvt_pk_bf16_f32 v246, v132, v133
	v_cvt_pk_bf16_f32 v247, v134, v135
	global_store_dwordx4 v82, v[244:247], s[46:47] offset:0
	v_pk_mul_f32 v[136:137], v[136:137], v[236:237] op_sel_hi:[1,0]
	v_pk_mul_f32 v[138:139], v[138:139], v[236:237] op_sel_hi:[1,0]
	v_pk_mul_f32 v[136:137], v[72:73], v[136:137]
	v_pk_mul_f32 v[138:139], v[74:75], v[138:139]
	v_pk_fma_f32 v[136:137], v[200:201], v[136:137], v[216:217]
	v_pk_fma_f32 v[138:139], v[202:203], v[138:139], v[218:219]
	v_cvt_pk_bf16_f32 v240, v136, v137
	v_cvt_pk_bf16_f32 v241, v138, v139
	v_pk_mul_f32 v[140:141], v[140:141], v[236:237] op_sel_hi:[1,0]
	v_pk_mul_f32 v[142:143], v[142:143], v[236:237] op_sel_hi:[1,0]
	v_pk_mul_f32 v[140:141], v[76:77], v[140:141]
	v_pk_mul_f32 v[142:143], v[78:79], v[142:143]
	v_pk_fma_f32 v[140:141], v[204:205], v[140:141], v[220:221]
	v_pk_fma_f32 v[142:143], v[206:207], v[142:143], v[222:223]
	v_cvt_pk_bf16_f32 v242, v140, v141
	v_cvt_pk_bf16_f32 v243, v142, v143
	global_store_dwordx4 v82, v[240:243], s[46:47] offset:1024
	v_pk_mul_f32 v[144:145], v[144:145], v[238:239] op_sel_hi:[1,0]
	v_pk_mul_f32 v[146:147], v[146:147], v[238:239] op_sel_hi:[1,0]
	v_pk_mul_f32 v[144:145], v[64:65], v[144:145]
	v_pk_mul_f32 v[146:147], v[66:67], v[146:147]
	v_pk_fma_f32 v[144:145], v[192:193], v[144:145], v[208:209]
	v_pk_fma_f32 v[146:147], v[194:195], v[146:147], v[210:211]
	v_cvt_pk_bf16_f32 v244, v144, v145
	v_cvt_pk_bf16_f32 v245, v146, v147
	v_pk_mul_f32 v[148:149], v[148:149], v[238:239] op_sel_hi:[1,0]
	v_pk_mul_f32 v[150:151], v[150:151], v[238:239] op_sel_hi:[1,0]
	v_pk_mul_f32 v[148:149], v[68:69], v[148:149]
	v_pk_mul_f32 v[150:151], v[70:71], v[150:151]
	v_pk_fma_f32 v[148:149], v[196:197], v[148:149], v[212:213]
	v_pk_fma_f32 v[150:151], v[198:199], v[150:151], v[214:215]
	v_cvt_pk_bf16_f32 v246, v148, v149
	v_cvt_pk_bf16_f32 v247, v150, v151
	global_store_dwordx4 v82, v[244:247], s[48:49] offset:0
	v_pk_mul_f32 v[152:153], v[152:153], v[238:239] op_sel_hi:[1,0]
	v_pk_mul_f32 v[154:155], v[154:155], v[238:239] op_sel_hi:[1,0]
	v_pk_mul_f32 v[152:153], v[72:73], v[152:153]
	v_pk_mul_f32 v[154:155], v[74:75], v[154:155]
	v_pk_fma_f32 v[152:153], v[200:201], v[152:153], v[216:217]
	v_pk_fma_f32 v[154:155], v[202:203], v[154:155], v[218:219]
	v_cvt_pk_bf16_f32 v240, v152, v153
	v_cvt_pk_bf16_f32 v241, v154, v155
	v_pk_mul_f32 v[156:157], v[156:157], v[238:239] op_sel_hi:[1,0]
	v_pk_mul_f32 v[158:159], v[158:159], v[238:239] op_sel_hi:[1,0]
	v_pk_mul_f32 v[156:157], v[76:77], v[156:157]
	v_pk_mul_f32 v[158:159], v[78:79], v[158:159]
	v_pk_fma_f32 v[156:157], v[204:205], v[156:157], v[220:221]
	v_pk_fma_f32 v[158:159], v[206:207], v[158:159], v[222:223]
	v_cvt_pk_bf16_f32 v242, v156, v157
	v_cvt_pk_bf16_f32 v243, v158, v159
	global_store_dwordx4 v82, v[240:243], s[48:49] offset:1024
	s_add_u32 s34, s8, 0xc000
	s_addc_u32 s35, s9, 0
	s_add_u32 s36, s8, 0xc000
	s_addc_u32 s37, s9, 0
	global_load_dwordx4 v[176:179], v80, s[34:35] offset:0
	global_load_dwordx4 v[180:183], v80, s[34:35] offset:16
	global_load_dwordx4 v[184:187], v80, s[34:35] offset:2048
	global_load_dwordx4 v[188:191], v80, s[34:35] offset:2064
	global_load_dwordx4 v[160:163], v81, s[34:35] offset:0
	global_load_dwordx4 v[164:167], v81, s[34:35] offset:16
	global_load_dwordx4 v[168:171], v81, s[34:35] offset:2048
	global_load_dwordx4 v[172:175], v81, s[34:35] offset:2064
; __device__ __forceinline__ float bf_lo(unsigned w) { return __uint_as_float(w << 16); }
; __device__ __forceinline__ float bf_hi(unsigned w) { return __uint_as_float(w & 0xffff0000u); }
; template <bool BF> __device__ __forceinline__ void prep_rows(const float* xp, const float* xs, const bf16* hb, const float* g, const float* MOD, int shoff, int scoff, bf16* U, int gw, int NGW, int lane) {
;     ...
;     for (int mb = gw; mb < MT; mb += R * NGW) {
;         f32x4 v[R][4]; float s[R];
; #pragma unroll
;         for (int r = 0; r < R; ++r) { const int m = mb + r * NGW; const int mc = m < MT ? m : mb;
; #pragma unroll
;             for (int j = 0; j < 4; ++j) {
;                 if (BF) { const v2u a0 = *(const v2u*)(hb + (size_t)mc * DM + 4 * lane + 256 * j);
;                     v[r][j].x = pg8::bf_lo(a0.x); v[r][j].y = pg8::bf_hi(a0.x); v[r][j].z = pg8::bf_lo(a0.y); v[r][j].w = pg8::bf_hi(a0.y); }
;                 else { const float* xr = mc < MP ? xp + (size_t)mc * DM : xs + (size_t)(mc - MP) * DM; v[r][j] = *(const f32x4*)(xr + 4 * lane + 256 * j); } } }
; #pragma unroll
;         for (int r = 0; r < R; ++r) { float t = 0.f;
; #pragma unroll
;             for (int j = 0; j < 4; ++j) t += (v[r][j].x * v[r][j].x + v[r][j].y * v[r][j].y) + (v[r][j].z * v[r][j].z + v[r][j].w * v[r][j].w);
;             s[r] = t; }
; #pragma unroll
;         for (int o = 1; o < 64; o <<= 1) {
; #pragma unroll
;             for (int r = 0; r < R; ++r) s[r] += __shfl_xor(s[r], o); }
	global_load_dwordx4 v[208:211], v80, s[36:37] offset:0
	global_load_dwordx4 v[212:215], v80, s[36:37] offset:16
	global_load_dwordx4 v[216:219], v80, s[36:37] offset:2048
	global_load_dwordx4 v[220:223], v80, s[36:37] offset:2064
	global_load_dwordx4 v[192:195], v81, s[36:37] offset:0
	global_load_dwordx4 v[196:199], v81, s[36:37] offset:16
	global_load_dwordx4 v[200:203], v81, s[36:37] offset:2048
	global_load_dwordx4 v[204:207], v81, s[36:37] offset:2064
	s_add_u32 s24, s16, 0x6000000
	s_addc_u32 s25, s17, 0
	s_add_u32 s26, s16, 0x6800000
	s_addc_u32 s27, s17, 0
	s_add_u32 s28, s16, 0x7000000
	s_addc_u32 s29, s17, 0
	s_add_u32 s30, s16, 0x7800000
	s_addc_u32 s31, s17, 0
	global_load_dwordx4 v[96:99], v80, s[24:25] offset:0 nt
	global_load_dwordx4 v[100:103], v80, s[24:25] offset:16 nt
	global_load_dwordx4 v[104:107], v80, s[24:25] offset:2048 nt
	global_load_dwordx4 v[108:111], v80, s[24:25] offset:2064 nt
	global_load_dwordx4 v[112:115], v80, s[26:27] offset:0 nt
	global_load_dwordx4 v[116:119], v80, s[26:27] offset:16 nt
	global_load_dwordx4 v[120:123], v80, s[26:27] offset:2048 nt
	global_load_dwordx4 v[124:127], v80, s[26:27] offset:2064 nt
	global_load_dwordx4 v[128:131], v80, s[28:29] offset:0 nt
	global_load_dwordx4 v[132:135], v80, s[28:29] offset:16 nt
	global_load_dwordx4 v[136:139], v80, s[28:29] offset:2048 nt
	global_load_dwordx4 v[140:143], v80, s[28:29] offset:2064 nt
	global_load_dwordx4 v[144:147], v80, s[30:31] offset:0 nt
	global_load_dwordx4 v[148:151], v80, s[30:31] offset:16 nt
	global_load_dwordx4 v[152:155], v80, s[30:31] offset:2048 nt
	global_load_dwordx4 v[156:159], v80, s[30:31] offset:2064 nt
	s_waitcnt vmcnt(40)
	v_pk_mul_f32 v[240:241], v[0:1], v[0:1]
	v_pk_mul_f32 v[242:243], v[16:17], v[16:17]
	v_pk_mul_f32 v[244:245], v[32:33], v[32:33]
	v_pk_mul_f32 v[246:247], v[48:49], v[48:49]
	v_pk_fma_f32 v[240:241], v[2:3], v[2:3], v[240:241]
	v_pk_fma_f32 v[242:243], v[18:19], v[18:19], v[242:243]
	v_pk_fma_f32 v[244:245], v[34:35], v[34:35], v[244:245]
	v_pk_fma_f32 v[246:247], v[50:51], v[50:51], v[246:247]
	v_pk_fma_f32 v[240:241], v[4:5], v[4:5], v[240:241]
	v_pk_fma_f32 v[242:243], v[20:21], v[20:21], v[242:243]
	v_pk_fma_f32 v[244:245], v[36:37], v[36:37], v[244:245]
	v_pk_fma_f32 v[246:247], v[52:53], v[52:53], v[246:247]
	v_pk_fma_f32 v[240:241], v[6:7], v[6:7], v[240:241]
	v_pk_fma_f32 v[242:243], v[22:23], v[22:23], v[242:243]
	v_pk_fma_f32 v[244:245], v[38:39], v[38:39], v[244:245]
	v_pk_fma_f32 v[246:247], v[54:55], v[54:55], v[246:247]
	v_pk_fma_f32 v[240:241], v[8:9], v[8:9], v[240:241]
	v_pk_fma_f32 v[242:243], v[24:25], v[24:25], v[242:243]
	v_pk_fma_f32 v[244:245], v[40:41], v[40:41], v[244:245]
	v_pk_fma_f32 v[246:247], v[56:57], v[56:57], v[246:247]
	v_pk_fma_f32 v[240:241], v[10:11], v[10:11], v[240:241]
	v_pk_fma_f32 v[242:243], v[26:27], v[26:27], v[242:243]
	v_pk_fma_f32 v[244:245], v[42:43], v[42:43], v[244:245]
	v_pk_fma_f32 v[246:247], v[58:59], v[58:59], v[246:247]
	v_pk_fma_f32 v[240:241], v[12:13], v[12:13], v[240:241]
	v_pk_fma_f32 v[242:243], v[28:29], v[28:29], v[242:243]
	v_pk_fma_f32 v[244:245], v[44:45], v[44:45], v[244:245]
	v_pk_fma_f32 v[246:247], v[60:61], v[60:61], v[246:247]
	v_pk_fma_f32 v[240:241], v[14:15], v[14:15], v[240:241]
	v_pk_fma_f32 v[242:243], v[30:31], v[30:31], v[242:243]
	v_pk_fma_f32 v[244:245], v[46:47], v[46:47], v[244:245]
	v_pk_fma_f32 v[246:247], v[62:63], v[62:63], v[246:247]
	v_add_f32_e32 v224, v240, v241
	v_add_f32_e32 v225, v242, v243
	v_add_f32_e32 v226, v244, v245
	v_add_f32_e32 v227, v246, v247
	ds_bpermute_b32 v228, v83, v224
	ds_bpermute_b32 v229, v83, v225
	ds_bpermute_b32 v230, v83, v226
	ds_bpermute_b32 v231, v83, v227
	s_waitcnt lgkmcnt(0)
	v_add_f32_e32 v224, v224, v228
	v_add_f32_e32 v225, v225, v229
	v_add_f32_e32 v226, v226, v230
	v_add_f32_e32 v227, v227, v231
	ds_bpermute_b32 v228, v84, v224
	ds_bpermute_b32 v229, v84, v225
	ds_bpermute_b32 v230, v84, v226
	ds_bpermute_b32 v231, v84, v227
	s_waitcnt lgkmcnt(0)
	v_add_f32_e32 v224, v224, v228
	v_add_f32_e32 v225, v225, v229
	v_add_f32_e32 v226, v226, v230
	v_add_f32_e32 v227, v227, v231
	ds_bpermute_b32 v228, v85, v224
	ds_bpermute_b32 v229, v85, v225
	ds_bpermute_b32 v230, v85, v226
	ds_bpermute_b32 v231, v85, v227
	s_waitcnt lgkmcnt(0)
	v_add_f32_e32 v224, v224, v228
	v_add_f32_e32 v225, v225, v229
	v_add_f32_e32 v226, v226, v230
	v_add_f32_e32 v227, v227, v231
	ds_bpermute_b32 v228, v86, v224
	ds_bpermute_b32 v229, v86, v225
	ds_bpermute_b32 v230, v86, v226
	ds_bpermute_b32 v231, v86, v227
	s_waitcnt lgkmcnt(0)
	v_add_f32_e32 v224, v224, v228
	v_add_f32_e32 v225, v225, v229
	v_add_f32_e32 v226, v226, v230
	v_add_f32_e32 v227, v227, v231
	ds_bpermute_b32 v228, v87, v224
	ds_bpermute_b32 v229, v87, v225
	ds_bpermute_b32 v230, v87, v226
	ds_bpermute_b32 v231, v87, v227
	s_waitcnt lgkmcnt(0)
	v_add_f32_e32 v224, v224, v228
	v_add_f32_e32 v225, v225, v229
	v_add_f32_e32 v226, v226, v230
	v_add_f32_e32 v227, v227, v231
	ds_bpermute_b32 v228, v88, v224
	ds_bpermute_b32 v229, v88, v225
	ds_bpermute_b32 v230, v88, v226
	ds_bpermute_b32 v231, v88, v227
	s_waitcnt lgkmcnt(0)
; template <bool BF> __device__ __forceinline__ void prep_rows(const float* xp, const float* xs, const bf16* hb, const float* g, const float* MOD, int shoff, int scoff, bf16* U, int gw, int NGW, int lane) {
;     ...
;             for (int r = 0; r < R; ++r) s[r] += __shfl_xor(s[r], o); }
; #pragma unroll
;         for (int r = 0; r < R; ++r) { const int m = mb + r * NGW; if (m < MT) {
;             const float rstd = 1.0f / sqrtf(s[r] * (1.0f / DM) + RMS_EPS);
	v_add_f32_e32 v224, v224, v228
	v_add_f32_e32 v225, v225, v229
	v_add_f32_e32 v226, v226, v230
	v_add_f32_e32 v227, v227, v231
	v_fmamk_f32 v240, v224, 0x3a800000, v89
	v_mul_f32_e32 v241, 0x4f800000, v240
	v_cmp_gt_f32_e32 vcc, s54, v240
	s_nop 1
	v_cndmask_b32_e32 v247, v240, v241, vcc
	v_sqrt_f32_e32 v242, v247
	s_nop 1
	v_add_u32_e32 v243, -1, v242
	v_add_u32_e32 v244, 1, v242
	v_fma_f32 v245, -v243, v242, v247
	v_fma_f32 v246, -v244, v242, v247
	v_cmp_ge_f32_e64 s[52:53], 0, v245
	s_nop 1
	v_cndmask_b32_e64 v242, v242, v243, s[52:53]
	v_cmp_lt_f32_e64 s[52:53], 0, v246
	s_nop 1
	v_cndmask_b32_e64 v242, v242, v244, s[52:53]
	v_mul_f32_e32 v243, 0x37800000, v242
	v_cndmask_b32_e32 v242, v242, v243, vcc
	v_cmp_class_f32_e32 vcc, v247, v90
	s_nop 1
	v_cndmask_b32_e32 v247, v242, v247, vcc
	v_div_scale_f32 v248, s[52:53], v247, v247, 1.0
	v_rcp_f32_e32 v249, v248
	v_div_scale_f32 v228, vcc, 1.0, v247, 1.0
	s_nop 0
	v_fma_f32 v229, -v248, v249, 1.0
	v_fmac_f32_e32 v249, v229, v249
	v_mul_f32_e32 v230, v228, v249
	v_fma_f32 v229, -v248, v230, v228
	v_fmac_f32_e32 v230, v229, v249
	v_fma_f32 v248, -v248, v230, v228
	v_div_fmas_f32 v248, v248, v249, v230
	v_div_fixup_f32 v232, v248, v247, 1.0
	v_fmamk_f32 v240, v225, 0x3a800000, v89
	v_mul_f32_e32 v241, 0x4f800000, v240
	v_cmp_gt_f32_e32 vcc, s54, v240
	s_nop 1
	v_cndmask_b32_e32 v247, v240, v241, vcc
	v_sqrt_f32_e32 v242, v247
	s_nop 1
	v_add_u32_e32 v243, -1, v242
	v_add_u32_e32 v244, 1, v242
	v_fma_f32 v245, -v243, v242, v247
	v_fma_f32 v246, -v244, v242, v247
	v_cmp_ge_f32_e64 s[52:53], 0, v245
	s_nop 1
	v_cndmask_b32_e64 v242, v242, v243, s[52:53]
	v_cmp_lt_f32_e64 s[52:53], 0, v246
	s_nop 1
	v_cndmask_b32_e64 v242, v242, v244, s[52:53]
	v_mul_f32_e32 v243, 0x37800000, v242
	v_cndmask_b32_e32 v242, v242, v243, vcc
	v_cmp_class_f32_e32 vcc, v247, v90
	s_nop 1
	v_cndmask_b32_e32 v247, v242, v247, vcc
	v_div_scale_f32 v248, s[52:53], v247, v247, 1.0
	v_rcp_f32_e32 v249, v248
	v_div_scale_f32 v228, vcc, 1.0, v247, 1.0
	s_nop 0
	v_fma_f32 v229, -v248, v249, 1.0
	v_fmac_f32_e32 v249, v229, v249
	v_mul_f32_e32 v230, v228, v249
	v_fma_f32 v229, -v248, v230, v228
	v_fmac_f32_e32 v230, v229, v249
	v_fma_f32 v248, -v248, v230, v228
	v_div_fmas_f32 v248, v248, v249, v230
	v_div_fixup_f32 v234, v248, v247, 1.0
	v_fmamk_f32 v240, v226, 0x3a800000, v89
	v_mul_f32_e32 v241, 0x4f800000, v240
	v_cmp_gt_f32_e32 vcc, s54, v240
	s_nop 1
	v_cndmask_b32_e32 v247, v240, v241, vcc
	v_sqrt_f32_e32 v242, v247
	s_nop 1
	v_add_u32_e32 v243, -1, v242
	v_add_u32_e32 v244, 1, v242
	v_fma_f32 v245, -v243, v242, v247
	v_fma_f32 v246, -v244, v242, v247
	v_cmp_ge_f32_e64 s[52:53], 0, v245
	s_nop 1
	v_cndmask_b32_e64 v242, v242, v243, s[52:53]
	v_cmp_lt_f32_e64 s[52:53], 0, v246
	s_nop 1
	v_cndmask_b32_e64 v242, v242, v244, s[52:53]
	v_mul_f32_e32 v243, 0x37800000, v242
	v_cndmask_b32_e32 v242, v242, v243, vcc
	v_cmp_class_f32_e32 vcc, v247, v90
	s_nop 1
	v_cndmask_b32_e32 v247, v242, v247, vcc
	v_div_scale_f32 v248, s[52:53], v247, v247, 1.0
	v_rcp_f32_e32 v249, v248
	v_div_scale_f32 v228, vcc, 1.0, v247, 1.0
	s_nop 0
	v_fma_f32 v229, -v248, v249, 1.0
	v_fmac_f32_e32 v249, v229, v249
	v_mul_f32_e32 v230, v228, v249
	v_fma_f32 v229, -v248, v230, v228
	v_fmac_f32_e32 v230, v229, v249
	v_fma_f32 v248, -v248, v230, v228
	v_div_fmas_f32 v248, v248, v249, v230
	v_div_fixup_f32 v236, v248, v247, 1.0
	v_fmamk_f32 v240, v227, 0x3a800000, v89
	v_mul_f32_e32 v241, 0x4f800000, v240
	v_cmp_gt_f32_e32 vcc, s54, v240
	s_nop 1
	v_cndmask_b32_e32 v247, v240, v241, vcc
	v_sqrt_f32_e32 v242, v247
	s_nop 1
	v_add_u32_e32 v243, -1, v242
	v_add_u32_e32 v244, 1, v242
	v_fma_f32 v245, -v243, v242, v247
	v_fma_f32 v246, -v244, v242, v247
	v_cmp_ge_f32_e64 s[52:53], 0, v245
	s_nop 1
	v_cndmask_b32_e64 v242, v242, v243, s[52:53]
	v_cmp_lt_f32_e64 s[52:53], 0, v246
	s_nop 1
	v_cndmask_b32_e64 v242, v242, v244, s[52:53]
	v_mul_f32_e32 v243, 0x37800000, v242
	v_cndmask_b32_e32 v242, v242, v243, vcc
	v_cmp_class_f32_e32 vcc, v247, v90
	s_nop 1
	v_cndmask_b32_e32 v247, v242, v247, vcc
	v_div_scale_f32 v248, s[52:53], v247, v247, 1.0
	v_rcp_f32_e32 v249, v248
	v_div_scale_f32 v228, vcc, 1.0, v247, 1.0
	s_nop 0
	v_fma_f32 v229, -v248, v249, 1.0
	v_fmac_f32_e32 v249, v229, v249
	v_mul_f32_e32 v230, v228, v249
	v_fma_f32 v229, -v248, v230, v228
	v_fmac_f32_e32 v230, v229, v249
	v_fma_f32 v248, -v248, v230, v228
	v_div_fmas_f32 v248, v248, v249, v230
	v_div_fixup_f32 v238, v248, v247, 1.0
	s_waitcnt vmcnt(16)
; __device__ __forceinline__ unsigned pk2(float lo, float hi) { return pg8::cvt_pk_bf16(lo, hi); }
; template <bool BF> __device__ __forceinline__ void prep_rows(const float* xp, const float* xs, const bf16* hb, const float* g, const float* MOD, int shoff, int scoff, bf16* U, int gw, int NGW, int lane) {
;     ...
;         for (int r = 0; r < R; ++r) { const int m = mb + r * NGW; if (m < MT) {
;             const float rstd = 1.0f / sqrtf(s[r] * (1.0f / DM) + RMS_EPS);
;             const float* mr = MOD + (size_t)(m < MP ? (m >> 13) : 8 + ((m - MP) >> 12)) * 6144;
; #pragma unroll
;             for (int j = 0; j < 4; ++j) { const int c = 4 * lane + 256 * j;
;                 const f32x4 gg = *(const f32x4*)(g + c), sc = *(const f32x4*)(mr + scoff + c), sh = *(const f32x4*)(mr + shoff + c);
;                 const f32x4 o = v[r][j] * rstd * gg * (sc + 1.0f) + sh; v2u w; w.x = pk2(o.x, o.y); w.y = pk2(o.z, o.w); *(v2u*)(U + (size_t)m * DM + c) = w; } } }
	v_pk_add_f32 v[160:161], v[160:161], 1.0 op_sel_hi:[1,0]
	v_pk_add_f32 v[162:163], v[162:163], 1.0 op_sel_hi:[1,0]
	v_pk_add_f32 v[164:165], v[164:165], 1.0 op_sel_hi:[1,0]
	v_pk_add_f32 v[166:167], v[166:167], 1.0 op_sel_hi:[1,0]
	v_pk_add_f32 v[168:169], v[168:169], 1.0 op_sel_hi:[1,0]
	v_pk_add_f32 v[170:171], v[170:171], 1.0 op_sel_hi:[1,0]
	v_pk_add_f32 v[172:173], v[172:173], 1.0 op_sel_hi:[1,0]
	v_pk_add_f32 v[174:175], v[174:175], 1.0 op_sel_hi:[1,0]
	v_pk_add_f32 v[192:193], v[192:193], 1.0 op_sel_hi:[1,0]
	v_pk_add_f32 v[194:195], v[194:195], 1.0 op_sel_hi:[1,0]
	v_pk_add_f32 v[196:197], v[196:197], 1.0 op_sel_hi:[1,0]
	v_pk_add_f32 v[198:199], v[198:199], 1.0 op_sel_hi:[1,0]
	v_pk_add_f32 v[200:201], v[200:201], 1.0 op_sel_hi:[1,0]
	v_pk_add_f32 v[202:203], v[202:203], 1.0 op_sel_hi:[1,0]
	v_pk_add_f32 v[204:205], v[204:205], 1.0 op_sel_hi:[1,0]
	v_pk_add_f32 v[206:207], v[206:207], 1.0 op_sel_hi:[1,0]
	s_add_u32 s38, s20, 0x2000000
	s_addc_u32 s39, s21, 0
	s_add_u32 s40, s20, 0x2400000
	s_addc_u32 s41, s21, 0
	s_add_u32 s46, s20, 0x2800000
	s_addc_u32 s47, s21, 0
	s_add_u32 s48, s20, 0x2c00000
	s_addc_u32 s49, s21, 0
	v_pk_mul_f32 v[0:1], v[0:1], v[232:233] op_sel_hi:[1,0]
	v_pk_mul_f32 v[2:3], v[2:3], v[232:233] op_sel_hi:[1,0]
	v_pk_mul_f32 v[0:1], v[64:65], v[0:1]
	v_pk_mul_f32 v[2:3], v[66:67], v[2:3]
	v_pk_fma_f32 v[0:1], v[160:161], v[0:1], v[176:177]
	v_pk_fma_f32 v[2:3], v[162:163], v[2:3], v[178:179]
	v_cvt_pk_bf16_f32 v244, v0, v1
	v_cvt_pk_bf16_f32 v245, v2, v3
	v_pk_mul_f32 v[4:5], v[4:5], v[232:233] op_sel_hi:[1,0]
	v_pk_mul_f32 v[6:7], v[6:7], v[232:233] op_sel_hi:[1,0]
	v_pk_mul_f32 v[4:5], v[68:69], v[4:5]
	v_pk_mul_f32 v[6:7], v[70:71], v[6:7]
	v_pk_fma_f32 v[4:5], v[164:165], v[4:5], v[180:181]
	v_pk_fma_f32 v[6:7], v[166:167], v[6:7], v[182:183]
	v_cvt_pk_bf16_f32 v246, v4, v5
	v_cvt_pk_bf16_f32 v247, v6, v7
	global_store_dwordx4 v82, v[244:247], s[38:39] offset:0
	v_pk_mul_f32 v[8:9], v[8:9], v[232:233] op_sel_hi:[1,0]
	v_pk_mul_f32 v[10:11], v[10:11], v[232:233] op_sel_hi:[1,0]
	v_pk_mul_f32 v[8:9], v[72:73], v[8:9]
	v_pk_mul_f32 v[10:11], v[74:75], v[10:11]
	v_pk_fma_f32 v[8:9], v[168:169], v[8:9], v[184:185]
	v_pk_fma_f32 v[10:11], v[170:171], v[10:11], v[186:187]
	v_cvt_pk_bf16_f32 v240, v8, v9
	v_cvt_pk_bf16_f32 v241, v10, v11
	v_pk_mul_f32 v[12:13], v[12:13], v[232:233] op_sel_hi:[1,0]
	v_pk_mul_f32 v[14:15], v[14:15], v[232:233] op_sel_hi:[1,0]
	v_pk_mul_f32 v[12:13], v[76:77], v[12:13]
	v_pk_mul_f32 v[14:15], v[78:79], v[14:15]
	v_pk_fma_f32 v[12:13], v[172:173], v[12:13], v[188:189]
	v_pk_fma_f32 v[14:15], v[174:175], v[14:15], v[190:191]
	v_cvt_pk_bf16_f32 v242, v12, v13
	v_cvt_pk_bf16_f32 v243, v14, v15
	global_store_dwordx4 v82, v[240:243], s[38:39] offset:1024
	v_pk_mul_f32 v[16:17], v[16:17], v[234:235] op_sel_hi:[1,0]
	v_pk_mul_f32 v[18:19], v[18:19], v[234:235] op_sel_hi:[1,0]
	v_pk_mul_f32 v[16:17], v[64:65], v[16:17]
	v_pk_mul_f32 v[18:19], v[66:67], v[18:19]
	v_pk_fma_f32 v[16:17], v[160:161], v[16:17], v[176:177]
	v_pk_fma_f32 v[18:19], v[162:163], v[18:19], v[178:179]
	v_cvt_pk_bf16_f32 v244, v16, v17
	v_cvt_pk_bf16_f32 v245, v18, v19
	v_pk_mul_f32 v[20:21], v[20:21], v[234:235] op_sel_hi:[1,0]
	v_pk_mul_f32 v[22:23], v[22:23], v[234:235] op_sel_hi:[1,0]
	v_pk_mul_f32 v[20:21], v[68:69], v[20:21]
	v_pk_mul_f32 v[22:23], v[70:71], v[22:23]
	v_pk_fma_f32 v[20:21], v[164:165], v[20:21], v[180:181]
	v_pk_fma_f32 v[22:23], v[166:167], v[22:23], v[182:183]
	v_cvt_pk_bf16_f32 v246, v20, v21
	v_cvt_pk_bf16_f32 v247, v22, v23
	global_store_dwordx4 v82, v[244:247], s[40:41] offset:0
	v_pk_mul_f32 v[24:25], v[24:25], v[234:235] op_sel_hi:[1,0]
	v_pk_mul_f32 v[26:27], v[26:27], v[234:235] op_sel_hi:[1,0]
	v_pk_mul_f32 v[24:25], v[72:73], v[24:25]
	v_pk_mul_f32 v[26:27], v[74:75], v[26:27]
	v_pk_fma_f32 v[24:25], v[168:169], v[24:25], v[184:185]
	v_pk_fma_f32 v[26:27], v[170:171], v[26:27], v[186:187]
	v_cvt_pk_bf16_f32 v240, v24, v25
	v_cvt_pk_bf16_f32 v241, v26, v27
	v_pk_mul_f32 v[28:29], v[28:29], v[234:235] op_sel_hi:[1,0]
	v_pk_mul_f32 v[30:31], v[30:31], v[234:235] op_sel_hi:[1,0]
	v_pk_mul_f32 v[28:29], v[76:77], v[28:29]
	v_pk_mul_f32 v[30:31], v[78:79], v[30:31]
	v_pk_fma_f32 v[28:29], v[172:173], v[28:29], v[188:189]
	v_pk_fma_f32 v[30:31], v[174:175], v[30:31], v[190:191]
	v_cvt_pk_bf16_f32 v242, v28, v29
	v_cvt_pk_bf16_f32 v243, v30, v31
	global_store_dwordx4 v82, v[240:243], s[40:41] offset:1024
	v_pk_mul_f32 v[32:33], v[32:33], v[236:237] op_sel_hi:[1,0]
	v_pk_mul_f32 v[34:35], v[34:35], v[236:237] op_sel_hi:[1,0]
	v_pk_mul_f32 v[32:33], v[64:65], v[32:33]
	v_pk_mul_f32 v[34:35], v[66:67], v[34:35]
	v_pk_fma_f32 v[32:33], v[192:193], v[32:33], v[208:209]
	v_pk_fma_f32 v[34:35], v[194:195], v[34:35], v[210:211]
	v_cvt_pk_bf16_f32 v244, v32, v33
	v_cvt_pk_bf16_f32 v245, v34, v35
	v_pk_mul_f32 v[36:37], v[36:37], v[236:237] op_sel_hi:[1,0]
	v_pk_mul_f32 v[38:39], v[38:39], v[236:237] op_sel_hi:[1,0]
	v_pk_mul_f32 v[36:37], v[68:69], v[36:37]
	v_pk_mul_f32 v[38:39], v[70:71], v[38:39]
	v_pk_fma_f32 v[36:37], v[196:197], v[36:37], v[212:213]
	v_pk_fma_f32 v[38:39], v[198:199], v[38:39], v[214:215]
	v_cvt_pk_bf16_f32 v246, v36, v37
	v_cvt_pk_bf16_f32 v247, v38, v39
	global_store_dwordx4 v82, v[244:247], s[46:47] offset:0
	v_pk_mul_f32 v[40:41], v[40:41], v[236:237] op_sel_hi:[1,0]
	v_pk_mul_f32 v[42:43], v[42:43], v[236:237] op_sel_hi:[1,0]
	v_pk_mul_f32 v[40:41], v[72:73], v[40:41]
	v_pk_mul_f32 v[42:43], v[74:75], v[42:43]
	v_pk_fma_f32 v[40:41], v[200:201], v[40:41], v[216:217]
	v_pk_fma_f32 v[42:43], v[202:203], v[42:43], v[218:219]
	v_cvt_pk_bf16_f32 v240, v40, v41
; __device__ __forceinline__ float bf_lo(unsigned w) { return __uint_as_float(w << 16); }
; __device__ __forceinline__ float bf_hi(unsigned w) { return __uint_as_float(w & 0xffff0000u); }
; template <bool BF> __device__ __forceinline__ void prep_rows(const float* xp, const float* xs, const bf16* hb, const float* g, const float* MOD, int shoff, int scoff, bf16* U, int gw, int NGW, int lane) {
;     ...
;         for (int r = 0; r < R; ++r) { const int m = mb + r * NGW; const int mc = m < MT ? m : mb;
; #pragma unroll
;             for (int j = 0; j < 4; ++j) {
;                 if (BF) { const v2u a0 = *(const v2u*)(hb + (size_t)mc * DM + 4 * lane + 256 * j);
;                     v[r][j].x = pg8::bf_lo(a0.x); v[r][j].y = pg8::bf_hi(a0.x); v[r][j].z = pg8::bf_lo(a0.y); v[r][j].w = pg8::bf_hi(a0.y); }
;                 else { const float* xr = mc < MP ? xp + (size_t)mc * DM : xs + (size_t)(mc - MP) * DM; v[r][j] = *(const f32x4*)(xr + 4 * lane + 256 * j); } } }
; #pragma unroll
;         for (int r = 0; r < R; ++r) { float t = 0.f;
; #pragma unroll
;             for (int j = 0; j < 4; ++j) t += (v[r][j].x * v[r][j].x + v[r][j].y * v[r][j].y) + (v[r][j].z * v[r][j].z + v[r][j].w * v[r][j].w);
;             s[r] = t; }
; #pragma unroll
;         for (int o = 1; o < 64; o <<= 1) {
; #pragma unroll
;             for (int r = 0; r < R; ++r) s[r] += __shfl_xor(s[r], o); }
;     ...
;                 const f32x4 gg = *(const f32x4*)(g + c), sc = *(const f32x4*)(mr + scoff + c), sh = *(const f32x4*)(mr + shoff + c);
	v_cvt_pk_bf16_f32 v241, v42, v43
	v_pk_mul_f32 v[44:45], v[44:45], v[236:237] op_sel_hi:[1,0]
	v_pk_mul_f32 v[46:47], v[46:47], v[236:237] op_sel_hi:[1,0]
	v_pk_mul_f32 v[44:45], v[76:77], v[44:45]
	v_pk_mul_f32 v[46:47], v[78:79], v[46:47]
	v_pk_fma_f32 v[44:45], v[204:205], v[44:45], v[220:221]
	v_pk_fma_f32 v[46:47], v[206:207], v[46:47], v[222:223]
	v_cvt_pk_bf16_f32 v242, v44, v45
	v_cvt_pk_bf16_f32 v243, v46, v47
	global_store_dwordx4 v82, v[240:243], s[46:47] offset:1024
	v_pk_mul_f32 v[48:49], v[48:49], v[238:239] op_sel_hi:[1,0]
	v_pk_mul_f32 v[50:51], v[50:51], v[238:239] op_sel_hi:[1,0]
	v_pk_mul_f32 v[48:49], v[64:65], v[48:49]
	v_pk_mul_f32 v[50:51], v[66:67], v[50:51]
	v_pk_fma_f32 v[48:49], v[192:193], v[48:49], v[208:209]
	v_pk_fma_f32 v[50:51], v[194:195], v[50:51], v[210:211]
	v_cvt_pk_bf16_f32 v244, v48, v49
	v_cvt_pk_bf16_f32 v245, v50, v51
	v_pk_mul_f32 v[52:53], v[52:53], v[238:239] op_sel_hi:[1,0]
	v_pk_mul_f32 v[54:55], v[54:55], v[238:239] op_sel_hi:[1,0]
	v_pk_mul_f32 v[52:53], v[68:69], v[52:53]
	v_pk_mul_f32 v[54:55], v[70:71], v[54:55]
	v_pk_fma_f32 v[52:53], v[196:197], v[52:53], v[212:213]
	v_pk_fma_f32 v[54:55], v[198:199], v[54:55], v[214:215]
	v_cvt_pk_bf16_f32 v246, v52, v53
	v_cvt_pk_bf16_f32 v247, v54, v55
	global_store_dwordx4 v82, v[244:247], s[48:49] offset:0
	v_pk_mul_f32 v[56:57], v[56:57], v[238:239] op_sel_hi:[1,0]
	v_pk_mul_f32 v[58:59], v[58:59], v[238:239] op_sel_hi:[1,0]
	v_pk_mul_f32 v[56:57], v[72:73], v[56:57]
	v_pk_mul_f32 v[58:59], v[74:75], v[58:59]
	v_pk_fma_f32 v[56:57], v[200:201], v[56:57], v[216:217]
	v_pk_fma_f32 v[58:59], v[202:203], v[58:59], v[218:219]
	v_cvt_pk_bf16_f32 v240, v56, v57
	v_cvt_pk_bf16_f32 v241, v58, v59
	v_pk_mul_f32 v[60:61], v[60:61], v[238:239] op_sel_hi:[1,0]
	v_pk_mul_f32 v[62:63], v[62:63], v[238:239] op_sel_hi:[1,0]
	v_pk_mul_f32 v[60:61], v[76:77], v[60:61]
	v_pk_mul_f32 v[62:63], v[78:79], v[62:63]
	v_pk_fma_f32 v[60:61], v[204:205], v[60:61], v[220:221]
	v_pk_fma_f32 v[62:63], v[206:207], v[62:63], v[222:223]
	v_cvt_pk_bf16_f32 v242, v60, v61
	v_cvt_pk_bf16_f32 v243, v62, v63
	global_store_dwordx4 v82, v[240:243], s[48:49] offset:1024
	s_add_u32 s34, s8, 0x12000
	s_addc_u32 s35, s9, 0
	s_add_u32 s36, s8, 0x12000
	s_addc_u32 s37, s9, 0
	global_load_dwordx4 v[176:179], v80, s[34:35] offset:0
	global_load_dwordx4 v[180:183], v80, s[34:35] offset:16
	global_load_dwordx4 v[184:187], v80, s[34:35] offset:2048
	global_load_dwordx4 v[188:191], v80, s[34:35] offset:2064
	global_load_dwordx4 v[160:163], v81, s[34:35] offset:0
	global_load_dwordx4 v[164:167], v81, s[34:35] offset:16
	global_load_dwordx4 v[168:171], v81, s[34:35] offset:2048
	global_load_dwordx4 v[172:175], v81, s[34:35] offset:2064
	global_load_dwordx4 v[208:211], v80, s[36:37] offset:0
	global_load_dwordx4 v[212:215], v80, s[36:37] offset:16
	global_load_dwordx4 v[216:219], v80, s[36:37] offset:2048
	global_load_dwordx4 v[220:223], v80, s[36:37] offset:2064
	global_load_dwordx4 v[192:195], v81, s[36:37] offset:0
	global_load_dwordx4 v[196:199], v81, s[36:37] offset:16
	global_load_dwordx4 v[200:203], v81, s[36:37] offset:2048
	global_load_dwordx4 v[204:207], v81, s[36:37] offset:2064
	s_add_u32 s24, s16, 0x8000000
	s_addc_u32 s25, s17, 0
	s_add_u32 s26, s16, 0x8800000
	s_addc_u32 s27, s17, 0
	s_add_u32 s28, s16, 0x9000000
	s_addc_u32 s29, s17, 0
	s_add_u32 s30, s16, 0x9800000
	s_addc_u32 s31, s17, 0
	global_load_dwordx4 v[0:3], v80, s[24:25] offset:0 nt
	global_load_dwordx4 v[4:7], v80, s[24:25] offset:16 nt
	global_load_dwordx4 v[8:11], v80, s[24:25] offset:2048 nt
	global_load_dwordx4 v[12:15], v80, s[24:25] offset:2064 nt
	global_load_dwordx4 v[16:19], v80, s[26:27] offset:0 nt
	global_load_dwordx4 v[20:23], v80, s[26:27] offset:16 nt
	global_load_dwordx4 v[24:27], v80, s[26:27] offset:2048 nt
	global_load_dwordx4 v[28:31], v80, s[26:27] offset:2064 nt
	global_load_dwordx4 v[32:35], v80, s[28:29] offset:0 nt
	global_load_dwordx4 v[36:39], v80, s[28:29] offset:16 nt
	global_load_dwordx4 v[40:43], v80, s[28:29] offset:2048 nt
	global_load_dwordx4 v[44:47], v80, s[28:29] offset:2064 nt
	global_load_dwordx4 v[48:51], v80, s[30:31] offset:0 nt
	global_load_dwordx4 v[52:55], v80, s[30:31] offset:16 nt
	global_load_dwordx4 v[56:59], v80, s[30:31] offset:2048 nt
	global_load_dwordx4 v[60:63], v80, s[30:31] offset:2064 nt
	s_waitcnt vmcnt(40)
	v_pk_mul_f32 v[240:241], v[96:97], v[96:97]
	v_pk_mul_f32 v[242:243], v[112:113], v[112:113]
	v_pk_mul_f32 v[244:245], v[128:129], v[128:129]
	v_pk_mul_f32 v[246:247], v[144:145], v[144:145]
	v_pk_fma_f32 v[240:241], v[98:99], v[98:99], v[240:241]
	v_pk_fma_f32 v[242:243], v[114:115], v[114:115], v[242:243]
	v_pk_fma_f32 v[244:245], v[130:131], v[130:131], v[244:245]
	v_pk_fma_f32 v[246:247], v[146:147], v[146:147], v[246:247]
	v_pk_fma_f32 v[240:241], v[100:101], v[100:101], v[240:241]
	v_pk_fma_f32 v[242:243], v[116:117], v[116:117], v[242:243]
	v_pk_fma_f32 v[244:245], v[132:133], v[132:133], v[244:245]
	v_pk_fma_f32 v[246:247], v[148:149], v[148:149], v[246:247]
	v_pk_fma_f32 v[240:241], v[102:103], v[102:103], v[240:241]
	v_pk_fma_f32 v[242:243], v[118:119], v[118:119], v[242:243]
	v_pk_fma_f32 v[244:245], v[134:135], v[134:135], v[244:245]
	v_pk_fma_f32 v[246:247], v[150:151], v[150:151], v[246:247]
	v_pk_fma_f32 v[240:241], v[104:105], v[104:105], v[240:241]
	v_pk_fma_f32 v[242:243], v[120:121], v[120:121], v[242:243]
	v_pk_fma_f32 v[244:245], v[136:137], v[136:137], v[244:245]
	v_pk_fma_f32 v[246:247], v[152:153], v[152:153], v[246:247]
	v_pk_fma_f32 v[240:241], v[106:107], v[106:107], v[240:241]
	v_pk_fma_f32 v[242:243], v[122:123], v[122:123], v[242:243]
	v_pk_fma_f32 v[244:245], v[138:139], v[138:139], v[244:245]
	v_pk_fma_f32 v[246:247], v[154:155], v[154:155], v[246:247]
	v_pk_fma_f32 v[240:241], v[108:109], v[108:109], v[240:241]
	v_pk_fma_f32 v[242:243], v[124:125], v[124:125], v[242:243]
	v_pk_fma_f32 v[244:245], v[140:141], v[140:141], v[244:245]
	v_pk_fma_f32 v[246:247], v[156:157], v[156:157], v[246:247]
	v_pk_fma_f32 v[240:241], v[110:111], v[110:111], v[240:241]
	v_pk_fma_f32 v[242:243], v[126:127], v[126:127], v[242:243]
	v_pk_fma_f32 v[244:245], v[142:143], v[142:143], v[244:245]
	v_pk_fma_f32 v[246:247], v[158:159], v[158:159], v[246:247]
	v_add_f32_e32 v224, v240, v241
	v_add_f32_e32 v225, v242, v243
	v_add_f32_e32 v226, v244, v245
	v_add_f32_e32 v227, v246, v247
	ds_bpermute_b32 v228, v83, v224
	ds_bpermute_b32 v229, v83, v225
	ds_bpermute_b32 v230, v83, v226
	ds_bpermute_b32 v231, v83, v227
	s_waitcnt lgkmcnt(0)
; template <bool BF> __device__ __forceinline__ void prep_rows(const float* xp, const float* xs, const bf16* hb, const float* g, const float* MOD, int shoff, int scoff, bf16* U, int gw, int NGW, int lane) {
;     ...
; #pragma unroll
;         for (int o = 1; o < 64; o <<= 1) {
; #pragma unroll
;             for (int r = 0; r < R; ++r) s[r] += __shfl_xor(s[r], o); }
; #pragma unroll
;         for (int r = 0; r < R; ++r) { const int m = mb + r * NGW; if (m < MT) {
;             const float rstd = 1.0f / sqrtf(s[r] * (1.0f / DM) + RMS_EPS);
	v_add_f32_e32 v224, v224, v228
	v_add_f32_e32 v225, v225, v229
	v_add_f32_e32 v226, v226, v230
	v_add_f32_e32 v227, v227, v231
	ds_bpermute_b32 v228, v84, v224
	ds_bpermute_b32 v229, v84, v225
	ds_bpermute_b32 v230, v84, v226
	ds_bpermute_b32 v231, v84, v227
	s_waitcnt lgkmcnt(0)
	v_add_f32_e32 v224, v224, v228
	v_add_f32_e32 v225, v225, v229
	v_add_f32_e32 v226, v226, v230
	v_add_f32_e32 v227, v227, v231
	ds_bpermute_b32 v228, v85, v224
	ds_bpermute_b32 v229, v85, v225
	ds_bpermute_b32 v230, v85, v226
	ds_bpermute_b32 v231, v85, v227
	s_waitcnt lgkmcnt(0)
	v_add_f32_e32 v224, v224, v228
	v_add_f32_e32 v225, v225, v229
	v_add_f32_e32 v226, v226, v230
	v_add_f32_e32 v227, v227, v231
	ds_bpermute_b32 v228, v86, v224
	ds_bpermute_b32 v229, v86, v225
	ds_bpermute_b32 v230, v86, v226
	ds_bpermute_b32 v231, v86, v227
	s_waitcnt lgkmcnt(0)
	v_add_f32_e32 v224, v224, v228
	v_add_f32_e32 v225, v225, v229
	v_add_f32_e32 v226, v226, v230
	v_add_f32_e32 v227, v227, v231
	ds_bpermute_b32 v228, v87, v224
	ds_bpermute_b32 v229, v87, v225
	ds_bpermute_b32 v230, v87, v226
	ds_bpermute_b32 v231, v87, v227
	s_waitcnt lgkmcnt(0)
	v_add_f32_e32 v224, v224, v228
	v_add_f32_e32 v225, v225, v229
	v_add_f32_e32 v226, v226, v230
	v_add_f32_e32 v227, v227, v231
	ds_bpermute_b32 v228, v88, v224
	ds_bpermute_b32 v229, v88, v225
	ds_bpermute_b32 v230, v88, v226
	ds_bpermute_b32 v231, v88, v227
	s_waitcnt lgkmcnt(0)
	v_add_f32_e32 v224, v224, v228
	v_add_f32_e32 v225, v225, v229
	v_add_f32_e32 v226, v226, v230
	v_add_f32_e32 v227, v227, v231
	v_fmamk_f32 v240, v224, 0x3a800000, v89
	v_mul_f32_e32 v241, 0x4f800000, v240
	v_cmp_gt_f32_e32 vcc, s54, v240
	s_nop 1
	v_cndmask_b32_e32 v247, v240, v241, vcc
	v_sqrt_f32_e32 v242, v247
	s_nop 1
	v_add_u32_e32 v243, -1, v242
	v_add_u32_e32 v244, 1, v242
	v_fma_f32 v245, -v243, v242, v247
	v_fma_f32 v246, -v244, v242, v247
	v_cmp_ge_f32_e64 s[52:53], 0, v245
	s_nop 1
	v_cndmask_b32_e64 v242, v242, v243, s[52:53]
	v_cmp_lt_f32_e64 s[52:53], 0, v246
	s_nop 1
	v_cndmask_b32_e64 v242, v242, v244, s[52:53]
	v_mul_f32_e32 v243, 0x37800000, v242
	v_cndmask_b32_e32 v242, v242, v243, vcc
	v_cmp_class_f32_e32 vcc, v247, v90
	s_nop 1
	v_cndmask_b32_e32 v247, v242, v247, vcc
	v_div_scale_f32 v248, s[52:53], v247, v247, 1.0
	v_rcp_f32_e32 v249, v248
	v_div_scale_f32 v228, vcc, 1.0, v247, 1.0
	s_nop 0
	v_fma_f32 v229, -v248, v249, 1.0
	v_fmac_f32_e32 v249, v229, v249
	v_mul_f32_e32 v230, v228, v249
	v_fma_f32 v229, -v248, v230, v228
	v_fmac_f32_e32 v230, v229, v249
	v_fma_f32 v248, -v248, v230, v228
	v_div_fmas_f32 v248, v248, v249, v230
	v_div_fixup_f32 v232, v248, v247, 1.0
	v_fmamk_f32 v240, v225, 0x3a800000, v89
	v_mul_f32_e32 v241, 0x4f800000, v240
	v_cmp_gt_f32_e32 vcc, s54, v240
	s_nop 1
	v_cndmask_b32_e32 v247, v240, v241, vcc
	v_sqrt_f32_e32 v242, v247
	s_nop 1
	v_add_u32_e32 v243, -1, v242
	v_add_u32_e32 v244, 1, v242
	v_fma_f32 v245, -v243, v242, v247
	v_fma_f32 v246, -v244, v242, v247
	v_cmp_ge_f32_e64 s[52:53], 0, v245
	s_nop 1
	v_cndmask_b32_e64 v242, v242, v243, s[52:53]
	v_cmp_lt_f32_e64 s[52:53], 0, v246
	s_nop 1
	v_cndmask_b32_e64 v242, v242, v244, s[52:53]
	v_mul_f32_e32 v243, 0x37800000, v242
	v_cndmask_b32_e32 v242, v242, v243, vcc
	v_cmp_class_f32_e32 vcc, v247, v90
	s_nop 1
	v_cndmask_b32_e32 v247, v242, v247, vcc
	v_div_scale_f32 v248, s[52:53], v247, v247, 1.0
	v_rcp_f32_e32 v249, v248
	v_div_scale_f32 v228, vcc, 1.0, v247, 1.0
	s_nop 0
	v_fma_f32 v229, -v248, v249, 1.0
	v_fmac_f32_e32 v249, v229, v249
	v_mul_f32_e32 v230, v228, v249
	v_fma_f32 v229, -v248, v230, v228
	v_fmac_f32_e32 v230, v229, v249
	v_fma_f32 v248, -v248, v230, v228
	v_div_fmas_f32 v248, v248, v249, v230
	v_div_fixup_f32 v234, v248, v247, 1.0
	v_fmamk_f32 v240, v226, 0x3a800000, v89
	v_mul_f32_e32 v241, 0x4f800000, v240
	v_cmp_gt_f32_e32 vcc, s54, v240
	s_nop 1
	v_cndmask_b32_e32 v247, v240, v241, vcc
	v_sqrt_f32_e32 v242, v247
	s_nop 1
	v_add_u32_e32 v243, -1, v242
	v_add_u32_e32 v244, 1, v242
	v_fma_f32 v245, -v243, v242, v247
	v_fma_f32 v246, -v244, v242, v247
	v_cmp_ge_f32_e64 s[52:53], 0, v245
	s_nop 1
	v_cndmask_b32_e64 v242, v242, v243, s[52:53]
	v_cmp_lt_f32_e64 s[52:53], 0, v246
	s_nop 1
	v_cndmask_b32_e64 v242, v242, v244, s[52:53]
	v_mul_f32_e32 v243, 0x37800000, v242
	v_cndmask_b32_e32 v242, v242, v243, vcc
	v_cmp_class_f32_e32 vcc, v247, v90
	s_nop 1
	v_cndmask_b32_e32 v247, v242, v247, vcc
	v_div_scale_f32 v248, s[52:53], v247, v247, 1.0
	v_rcp_f32_e32 v249, v248
	v_div_scale_f32 v228, vcc, 1.0, v247, 1.0
	s_nop 0
	v_fma_f32 v229, -v248, v249, 1.0
	v_fmac_f32_e32 v249, v229, v249
	v_mul_f32_e32 v230, v228, v249
	v_fma_f32 v229, -v248, v230, v228
	v_fmac_f32_e32 v230, v229, v249
	v_fma_f32 v248, -v248, v230, v228
	v_div_fmas_f32 v248, v248, v249, v230
	v_div_fixup_f32 v236, v248, v247, 1.0
	v_fmamk_f32 v240, v227, 0x3a800000, v89
	v_mul_f32_e32 v241, 0x4f800000, v240
	v_cmp_gt_f32_e32 vcc, s54, v240
	s_nop 1
	v_cndmask_b32_e32 v247, v240, v241, vcc
	v_sqrt_f32_e32 v242, v247
	s_nop 1
	v_add_u32_e32 v243, -1, v242
	v_add_u32_e32 v244, 1, v242
	v_fma_f32 v245, -v243, v242, v247
	v_fma_f32 v246, -v244, v242, v247
	v_cmp_ge_f32_e64 s[52:53], 0, v245
	s_nop 1
	v_cndmask_b32_e64 v242, v242, v243, s[52:53]
	v_cmp_lt_f32_e64 s[52:53], 0, v246
	s_nop 1
	v_cndmask_b32_e64 v242, v242, v244, s[52:53]
	v_mul_f32_e32 v243, 0x37800000, v242
	v_cndmask_b32_e32 v242, v242, v243, vcc
	v_cmp_class_f32_e32 vcc, v247, v90
	s_nop 1
	v_cndmask_b32_e32 v247, v242, v247, vcc
	v_div_scale_f32 v248, s[52:53], v247, v247, 1.0
	v_rcp_f32_e32 v249, v248
	v_div_scale_f32 v228, vcc, 1.0, v247, 1.0
	s_nop 0
	v_fma_f32 v229, -v248, v249, 1.0
	v_fmac_f32_e32 v249, v229, v249
	v_mul_f32_e32 v230, v228, v249
	v_fma_f32 v229, -v248, v230, v228
	v_fmac_f32_e32 v230, v229, v249
	v_fma_f32 v248, -v248, v230, v228
	v_div_fmas_f32 v248, v248, v249, v230
	v_div_fixup_f32 v238, v248, v247, 1.0
	s_waitcnt vmcnt(16)
; __device__ __forceinline__ unsigned pk2(float lo, float hi) { return pg8::cvt_pk_bf16(lo, hi); }
; template <bool BF> __device__ __forceinline__ void prep_rows(const float* xp, const float* xs, const bf16* hb, const float* g, const float* MOD, int shoff, int scoff, bf16* U, int gw, int NGW, int lane) {
;     ...
;         for (int r = 0; r < R; ++r) { const int m = mb + r * NGW; if (m < MT) {
;             const float rstd = 1.0f / sqrtf(s[r] * (1.0f / DM) + RMS_EPS);
;             const float* mr = MOD + (size_t)(m < MP ? (m >> 13) : 8 + ((m - MP) >> 12)) * 6144;
; #pragma unroll
;             for (int j = 0; j < 4; ++j) { const int c = 4 * lane + 256 * j;
;                 const f32x4 gg = *(const f32x4*)(g + c), sc = *(const f32x4*)(mr + scoff + c), sh = *(const f32x4*)(mr + shoff + c);
;                 const f32x4 o = v[r][j] * rstd * gg * (sc + 1.0f) + sh; v2u w; w.x = pk2(o.x, o.y); w.y = pk2(o.z, o.w); *(v2u*)(U + (size_t)m * DM + c) = w; } } }
	v_pk_add_f32 v[160:161], v[160:161], 1.0 op_sel_hi:[1,0]
	v_pk_add_f32 v[162:163], v[162:163], 1.0 op_sel_hi:[1,0]
	v_pk_add_f32 v[164:165], v[164:165], 1.0 op_sel_hi:[1,0]
	v_pk_add_f32 v[166:167], v[166:167], 1.0 op_sel_hi:[1,0]
	v_pk_add_f32 v[168:169], v[168:169], 1.0 op_sel_hi:[1,0]
	v_pk_add_f32 v[170:171], v[170:171], 1.0 op_sel_hi:[1,0]
	v_pk_add_f32 v[172:173], v[172:173], 1.0 op_sel_hi:[1,0]
	v_pk_add_f32 v[174:175], v[174:175], 1.0 op_sel_hi:[1,0]
	v_pk_add_f32 v[192:193], v[192:193], 1.0 op_sel_hi:[1,0]
	v_pk_add_f32 v[194:195], v[194:195], 1.0 op_sel_hi:[1,0]
	v_pk_add_f32 v[196:197], v[196:197], 1.0 op_sel_hi:[1,0]
	v_pk_add_f32 v[198:199], v[198:199], 1.0 op_sel_hi:[1,0]
	v_pk_add_f32 v[200:201], v[200:201], 1.0 op_sel_hi:[1,0]
	v_pk_add_f32 v[202:203], v[202:203], 1.0 op_sel_hi:[1,0]
	v_pk_add_f32 v[204:205], v[204:205], 1.0 op_sel_hi:[1,0]
	v_pk_add_f32 v[206:207], v[206:207], 1.0 op_sel_hi:[1,0]
	s_add_u32 s38, s20, 0x3000000
	s_addc_u32 s39, s21, 0
	s_add_u32 s40, s20, 0x3400000
	s_addc_u32 s41, s21, 0
	s_add_u32 s46, s20, 0x3800000
	s_addc_u32 s47, s21, 0
	s_add_u32 s48, s20, 0x3c00000
	s_addc_u32 s49, s21, 0
	v_pk_mul_f32 v[96:97], v[96:97], v[232:233] op_sel_hi:[1,0]
	v_pk_mul_f32 v[98:99], v[98:99], v[232:233] op_sel_hi:[1,0]
	v_pk_mul_f32 v[96:97], v[64:65], v[96:97]
	v_pk_mul_f32 v[98:99], v[66:67], v[98:99]
	v_pk_fma_f32 v[96:97], v[160:161], v[96:97], v[176:177]
	v_pk_fma_f32 v[98:99], v[162:163], v[98:99], v[178:179]
	v_cvt_pk_bf16_f32 v244, v96, v97
	v_cvt_pk_bf16_f32 v245, v98, v99
	v_pk_mul_f32 v[100:101], v[100:101], v[232:233] op_sel_hi:[1,0]
	v_pk_mul_f32 v[102:103], v[102:103], v[232:233] op_sel_hi:[1,0]
	v_pk_mul_f32 v[100:101], v[68:69], v[100:101]
	v_pk_mul_f32 v[102:103], v[70:71], v[102:103]
	v_pk_fma_f32 v[100:101], v[164:165], v[100:101], v[180:181]
	v_pk_fma_f32 v[102:103], v[166:167], v[102:103], v[182:183]
	v_cvt_pk_bf16_f32 v246, v100, v101
	v_cvt_pk_bf16_f32 v247, v102, v103
	global_store_dwordx4 v82, v[244:247], s[38:39] offset:0
	v_pk_mul_f32 v[104:105], v[104:105], v[232:233] op_sel_hi:[1,0]
	v_pk_mul_f32 v[106:107], v[106:107], v[232:233] op_sel_hi:[1,0]
	v_pk_mul_f32 v[104:105], v[72:73], v[104:105]
	v_pk_mul_f32 v[106:107], v[74:75], v[106:107]
	v_pk_fma_f32 v[104:105], v[168:169], v[104:105], v[184:185]
	v_pk_fma_f32 v[106:107], v[170:171], v[106:107], v[186:187]
	v_cvt_pk_bf16_f32 v240, v104, v105
	v_cvt_pk_bf16_f32 v241, v106, v107
	v_pk_mul_f32 v[108:109], v[108:109], v[232:233] op_sel_hi:[1,0]
	v_pk_mul_f32 v[110:111], v[110:111], v[232:233] op_sel_hi:[1,0]
	v_pk_mul_f32 v[108:109], v[76:77], v[108:109]
	v_pk_mul_f32 v[110:111], v[78:79], v[110:111]
	v_pk_fma_f32 v[108:109], v[172:173], v[108:109], v[188:189]
	v_pk_fma_f32 v[110:111], v[174:175], v[110:111], v[190:191]
	v_cvt_pk_bf16_f32 v242, v108, v109
	v_cvt_pk_bf16_f32 v243, v110, v111
	global_store_dwordx4 v82, v[240:243], s[38:39] offset:1024
	v_pk_mul_f32 v[112:113], v[112:113], v[234:235] op_sel_hi:[1,0]
	v_pk_mul_f32 v[114:115], v[114:115], v[234:235] op_sel_hi:[1,0]
	v_pk_mul_f32 v[112:113], v[64:65], v[112:113]
	v_pk_mul_f32 v[114:115], v[66:67], v[114:115]
	v_pk_fma_f32 v[112:113], v[160:161], v[112:113], v[176:177]
	v_pk_fma_f32 v[114:115], v[162:163], v[114:115], v[178:179]
	v_cvt_pk_bf16_f32 v244, v112, v113
	v_cvt_pk_bf16_f32 v245, v114, v115
	v_pk_mul_f32 v[116:117], v[116:117], v[234:235] op_sel_hi:[1,0]
	v_pk_mul_f32 v[118:119], v[118:119], v[234:235] op_sel_hi:[1,0]
	v_pk_mul_f32 v[116:117], v[68:69], v[116:117]
	v_pk_mul_f32 v[118:119], v[70:71], v[118:119]
	v_pk_fma_f32 v[116:117], v[164:165], v[116:117], v[180:181]
	v_pk_fma_f32 v[118:119], v[166:167], v[118:119], v[182:183]
	v_cvt_pk_bf16_f32 v246, v116, v117
	v_cvt_pk_bf16_f32 v247, v118, v119
	global_store_dwordx4 v82, v[244:247], s[40:41] offset:0
	v_pk_mul_f32 v[120:121], v[120:121], v[234:235] op_sel_hi:[1,0]
	v_pk_mul_f32 v[122:123], v[122:123], v[234:235] op_sel_hi:[1,0]
	v_pk_mul_f32 v[120:121], v[72:73], v[120:121]
	v_pk_mul_f32 v[122:123], v[74:75], v[122:123]
	v_pk_fma_f32 v[120:121], v[168:169], v[120:121], v[184:185]
	v_pk_fma_f32 v[122:123], v[170:171], v[122:123], v[186:187]
	v_cvt_pk_bf16_f32 v240, v120, v121
	v_cvt_pk_bf16_f32 v241, v122, v123
	v_pk_mul_f32 v[124:125], v[124:125], v[234:235] op_sel_hi:[1,0]
	v_pk_mul_f32 v[126:127], v[126:127], v[234:235] op_sel_hi:[1,0]
	v_pk_mul_f32 v[124:125], v[76:77], v[124:125]
	v_pk_mul_f32 v[126:127], v[78:79], v[126:127]
	v_pk_fma_f32 v[124:125], v[172:173], v[124:125], v[188:189]
	v_pk_fma_f32 v[126:127], v[174:175], v[126:127], v[190:191]
	v_cvt_pk_bf16_f32 v242, v124, v125
	v_cvt_pk_bf16_f32 v243, v126, v127
	global_store_dwordx4 v82, v[240:243], s[40:41] offset:1024
	v_pk_mul_f32 v[128:129], v[128:129], v[236:237] op_sel_hi:[1,0]
	v_pk_mul_f32 v[130:131], v[130:131], v[236:237] op_sel_hi:[1,0]
	v_pk_mul_f32 v[128:129], v[64:65], v[128:129]
	v_pk_mul_f32 v[130:131], v[66:67], v[130:131]
	v_pk_fma_f32 v[128:129], v[192:193], v[128:129], v[208:209]
	v_pk_fma_f32 v[130:131], v[194:195], v[130:131], v[210:211]
	v_cvt_pk_bf16_f32 v244, v128, v129
	v_cvt_pk_bf16_f32 v245, v130, v131
	v_pk_mul_f32 v[132:133], v[132:133], v[236:237] op_sel_hi:[1,0]
	v_pk_mul_f32 v[134:135], v[134:135], v[236:237] op_sel_hi:[1,0]
	v_pk_mul_f32 v[132:133], v[68:69], v[132:133]
	v_pk_mul_f32 v[134:135], v[70:71], v[134:135]
	v_pk_fma_f32 v[132:133], v[196:197], v[132:133], v[212:213]
	v_pk_fma_f32 v[134:135], v[198:199], v[134:135], v[214:215]
	v_cvt_pk_bf16_f32 v246, v132, v133
	v_cvt_pk_bf16_f32 v247, v134, v135
	global_store_dwordx4 v82, v[244:247], s[46:47] offset:0
	v_pk_mul_f32 v[136:137], v[136:137], v[236:237] op_sel_hi:[1,0]
; __device__ __forceinline__ float bf_lo(unsigned w) { return __uint_as_float(w << 16); }
; __device__ __forceinline__ float bf_hi(unsigned w) { return __uint_as_float(w & 0xffff0000u); }
; template <bool BF> __device__ __forceinline__ void prep_rows(const float* xp, const float* xs, const bf16* hb, const float* g, const float* MOD, int shoff, int scoff, bf16* U, int gw, int NGW, int lane) {
;     ...
;         for (int r = 0; r < R; ++r) { const int m = mb + r * NGW; const int mc = m < MT ? m : mb;
; #pragma unroll
;             for (int j = 0; j < 4; ++j) {
;                 if (BF) { const v2u a0 = *(const v2u*)(hb + (size_t)mc * DM + 4 * lane + 256 * j);
;                     v[r][j].x = pg8::bf_lo(a0.x); v[r][j].y = pg8::bf_hi(a0.x); v[r][j].z = pg8::bf_lo(a0.y); v[r][j].w = pg8::bf_hi(a0.y); }
;                 else { const float* xr = mc < MP ? xp + (size_t)mc * DM : xs + (size_t)(mc - MP) * DM; v[r][j] = *(const f32x4*)(xr + 4 * lane + 256 * j); } } }
;     ...
;                 const f32x4 gg = *(const f32x4*)(g + c), sc = *(const f32x4*)(mr + scoff + c), sh = *(const f32x4*)(mr + shoff + c);
	v_pk_mul_f32 v[138:139], v[138:139], v[236:237] op_sel_hi:[1,0]
	v_pk_mul_f32 v[136:137], v[72:73], v[136:137]
	v_pk_mul_f32 v[138:139], v[74:75], v[138:139]
	v_pk_fma_f32 v[136:137], v[200:201], v[136:137], v[216:217]
	v_pk_fma_f32 v[138:139], v[202:203], v[138:139], v[218:219]
	v_cvt_pk_bf16_f32 v240, v136, v137
	v_cvt_pk_bf16_f32 v241, v138, v139
	v_pk_mul_f32 v[140:141], v[140:141], v[236:237] op_sel_hi:[1,0]
	v_pk_mul_f32 v[142:143], v[142:143], v[236:237] op_sel_hi:[1,0]
	v_pk_mul_f32 v[140:141], v[76:77], v[140:141]
	v_pk_mul_f32 v[142:143], v[78:79], v[142:143]
	v_pk_fma_f32 v[140:141], v[204:205], v[140:141], v[220:221]
	v_pk_fma_f32 v[142:143], v[206:207], v[142:143], v[222:223]
	v_cvt_pk_bf16_f32 v242, v140, v141
	v_cvt_pk_bf16_f32 v243, v142, v143
	global_store_dwordx4 v82, v[240:243], s[46:47] offset:1024
	v_pk_mul_f32 v[144:145], v[144:145], v[238:239] op_sel_hi:[1,0]
	v_pk_mul_f32 v[146:147], v[146:147], v[238:239] op_sel_hi:[1,0]
	v_pk_mul_f32 v[144:145], v[64:65], v[144:145]
	v_pk_mul_f32 v[146:147], v[66:67], v[146:147]
	v_pk_fma_f32 v[144:145], v[192:193], v[144:145], v[208:209]
	v_pk_fma_f32 v[146:147], v[194:195], v[146:147], v[210:211]
	v_cvt_pk_bf16_f32 v244, v144, v145
	v_cvt_pk_bf16_f32 v245, v146, v147
	v_pk_mul_f32 v[148:149], v[148:149], v[238:239] op_sel_hi:[1,0]
	v_pk_mul_f32 v[150:151], v[150:151], v[238:239] op_sel_hi:[1,0]
	v_pk_mul_f32 v[148:149], v[68:69], v[148:149]
	v_pk_mul_f32 v[150:151], v[70:71], v[150:151]
	v_pk_fma_f32 v[148:149], v[196:197], v[148:149], v[212:213]
	v_pk_fma_f32 v[150:151], v[198:199], v[150:151], v[214:215]
	v_cvt_pk_bf16_f32 v246, v148, v149
	v_cvt_pk_bf16_f32 v247, v150, v151
	global_store_dwordx4 v82, v[244:247], s[48:49] offset:0
	v_pk_mul_f32 v[152:153], v[152:153], v[238:239] op_sel_hi:[1,0]
	v_pk_mul_f32 v[154:155], v[154:155], v[238:239] op_sel_hi:[1,0]
	v_pk_mul_f32 v[152:153], v[72:73], v[152:153]
	v_pk_mul_f32 v[154:155], v[74:75], v[154:155]
	v_pk_fma_f32 v[152:153], v[200:201], v[152:153], v[216:217]
	v_pk_fma_f32 v[154:155], v[202:203], v[154:155], v[218:219]
	v_cvt_pk_bf16_f32 v240, v152, v153
	v_cvt_pk_bf16_f32 v241, v154, v155
	v_pk_mul_f32 v[156:157], v[156:157], v[238:239] op_sel_hi:[1,0]
	v_pk_mul_f32 v[158:159], v[158:159], v[238:239] op_sel_hi:[1,0]
	v_pk_mul_f32 v[156:157], v[76:77], v[156:157]
	v_pk_mul_f32 v[158:159], v[78:79], v[158:159]
	v_pk_fma_f32 v[156:157], v[204:205], v[156:157], v[220:221]
	v_pk_fma_f32 v[158:159], v[206:207], v[158:159], v[222:223]
	v_cvt_pk_bf16_f32 v242, v156, v157
	v_cvt_pk_bf16_f32 v243, v158, v159
	global_store_dwordx4 v82, v[240:243], s[48:49] offset:1024
	s_add_u32 s34, s8, 0x18000
	s_addc_u32 s35, s9, 0
	s_add_u32 s36, s8, 0x18000
	s_addc_u32 s37, s9, 0
	global_load_dwordx4 v[176:179], v80, s[34:35] offset:0
	global_load_dwordx4 v[180:183], v80, s[34:35] offset:16
	global_load_dwordx4 v[184:187], v80, s[34:35] offset:2048
	global_load_dwordx4 v[188:191], v80, s[34:35] offset:2064
	global_load_dwordx4 v[160:163], v81, s[34:35] offset:0
	global_load_dwordx4 v[164:167], v81, s[34:35] offset:16
	global_load_dwordx4 v[168:171], v81, s[34:35] offset:2048
	global_load_dwordx4 v[172:175], v81, s[34:35] offset:2064
	global_load_dwordx4 v[208:211], v80, s[36:37] offset:0
	global_load_dwordx4 v[212:215], v80, s[36:37] offset:16
	global_load_dwordx4 v[216:219], v80, s[36:37] offset:2048
	global_load_dwordx4 v[220:223], v80, s[36:37] offset:2064
	global_load_dwordx4 v[192:195], v81, s[36:37] offset:0
	global_load_dwordx4 v[196:199], v81, s[36:37] offset:16
	global_load_dwordx4 v[200:203], v81, s[36:37] offset:2048
	global_load_dwordx4 v[204:207], v81, s[36:37] offset:2064
	s_add_u32 s24, s16, 0xa000000
	s_addc_u32 s25, s17, 0
	s_add_u32 s26, s16, 0xa800000
	s_addc_u32 s27, s17, 0
	s_add_u32 s28, s16, 0xb000000
	s_addc_u32 s29, s17, 0
	s_add_u32 s30, s16, 0xb800000
	s_addc_u32 s31, s17, 0
	global_load_dwordx4 v[96:99], v80, s[24:25] offset:0 nt
	global_load_dwordx4 v[100:103], v80, s[24:25] offset:16 nt
	global_load_dwordx4 v[104:107], v80, s[24:25] offset:2048 nt
	global_load_dwordx4 v[108:111], v80, s[24:25] offset:2064 nt
	global_load_dwordx4 v[112:115], v80, s[26:27] offset:0 nt
	global_load_dwordx4 v[116:119], v80, s[26:27] offset:16 nt
	global_load_dwordx4 v[120:123], v80, s[26:27] offset:2048 nt
	global_load_dwordx4 v[124:127], v80, s[26:27] offset:2064 nt
	global_load_dwordx4 v[128:131], v80, s[28:29] offset:0 nt
	global_load_dwordx4 v[132:135], v80, s[28:29] offset:16 nt
	global_load_dwordx4 v[136:139], v80, s[28:29] offset:2048 nt
	global_load_dwordx4 v[140:143], v80, s[28:29] offset:2064 nt
	global_load_dwordx4 v[144:147], v80, s[30:31] offset:0 nt
	global_load_dwordx4 v[148:151], v80, s[30:31] offset:16 nt
	global_load_dwordx4 v[152:155], v80, s[30:31] offset:2048 nt
	global_load_dwordx4 v[156:159], v80, s[30:31] offset:2064 nt
	s_waitcnt vmcnt(40)
; template <bool BF> __device__ __forceinline__ void prep_rows(const float* xp, const float* xs, const bf16* hb, const float* g, const float* MOD, int shoff, int scoff, bf16* U, int gw, int NGW, int lane) {
;     ...
;         for (int r = 0; r < R; ++r) { float t = 0.f;
; #pragma unroll
;             for (int j = 0; j < 4; ++j) t += (v[r][j].x * v[r][j].x + v[r][j].y * v[r][j].y) + (v[r][j].z * v[r][j].z + v[r][j].w * v[r][j].w);
;             s[r] = t; }
; #pragma unroll
;         for (int o = 1; o < 64; o <<= 1) {
; #pragma unroll
;             for (int r = 0; r < R; ++r) s[r] += __shfl_xor(s[r], o); }
; #pragma unroll
;         for (int r = 0; r < R; ++r) { const int m = mb + r * NGW; if (m < MT) {
;             const float rstd = 1.0f / sqrtf(s[r] * (1.0f / DM) + RMS_EPS);
	v_pk_mul_f32 v[240:241], v[0:1], v[0:1]
	v_pk_mul_f32 v[242:243], v[16:17], v[16:17]
	v_pk_mul_f32 v[244:245], v[32:33], v[32:33]
	v_pk_mul_f32 v[246:247], v[48:49], v[48:49]
	v_pk_fma_f32 v[240:241], v[2:3], v[2:3], v[240:241]
	v_pk_fma_f32 v[242:243], v[18:19], v[18:19], v[242:243]
	v_pk_fma_f32 v[244:245], v[34:35], v[34:35], v[244:245]
	v_pk_fma_f32 v[246:247], v[50:51], v[50:51], v[246:247]
	v_pk_fma_f32 v[240:241], v[4:5], v[4:5], v[240:241]
	v_pk_fma_f32 v[242:243], v[20:21], v[20:21], v[242:243]
	v_pk_fma_f32 v[244:245], v[36:37], v[36:37], v[244:245]
	v_pk_fma_f32 v[246:247], v[52:53], v[52:53], v[246:247]
	v_pk_fma_f32 v[240:241], v[6:7], v[6:7], v[240:241]
	v_pk_fma_f32 v[242:243], v[22:23], v[22:23], v[242:243]
	v_pk_fma_f32 v[244:245], v[38:39], v[38:39], v[244:245]
	v_pk_fma_f32 v[246:247], v[54:55], v[54:55], v[246:247]
	v_pk_fma_f32 v[240:241], v[8:9], v[8:9], v[240:241]
	v_pk_fma_f32 v[242:243], v[24:25], v[24:25], v[242:243]
	v_pk_fma_f32 v[244:245], v[40:41], v[40:41], v[244:245]
	v_pk_fma_f32 v[246:247], v[56:57], v[56:57], v[246:247]
	v_pk_fma_f32 v[240:241], v[10:11], v[10:11], v[240:241]
	v_pk_fma_f32 v[242:243], v[26:27], v[26:27], v[242:243]
	v_pk_fma_f32 v[244:245], v[42:43], v[42:43], v[244:245]
	v_pk_fma_f32 v[246:247], v[58:59], v[58:59], v[246:247]
	v_pk_fma_f32 v[240:241], v[12:13], v[12:13], v[240:241]
	v_pk_fma_f32 v[242:243], v[28:29], v[28:29], v[242:243]
	v_pk_fma_f32 v[244:245], v[44:45], v[44:45], v[244:245]
	v_pk_fma_f32 v[246:247], v[60:61], v[60:61], v[246:247]
	v_pk_fma_f32 v[240:241], v[14:15], v[14:15], v[240:241]
	v_pk_fma_f32 v[242:243], v[30:31], v[30:31], v[242:243]
	v_pk_fma_f32 v[244:245], v[46:47], v[46:47], v[244:245]
	v_pk_fma_f32 v[246:247], v[62:63], v[62:63], v[246:247]
	v_add_f32_e32 v224, v240, v241
	v_add_f32_e32 v225, v242, v243
	v_add_f32_e32 v226, v244, v245
	v_add_f32_e32 v227, v246, v247
	ds_bpermute_b32 v228, v83, v224
	ds_bpermute_b32 v229, v83, v225
	ds_bpermute_b32 v230, v83, v226
	ds_bpermute_b32 v231, v83, v227
	s_waitcnt lgkmcnt(0)
	v_add_f32_e32 v224, v224, v228
	v_add_f32_e32 v225, v225, v229
	v_add_f32_e32 v226, v226, v230
	v_add_f32_e32 v227, v227, v231
	ds_bpermute_b32 v228, v84, v224
	ds_bpermute_b32 v229, v84, v225
	ds_bpermute_b32 v230, v84, v226
	ds_bpermute_b32 v231, v84, v227
	s_waitcnt lgkmcnt(0)
	v_add_f32_e32 v224, v224, v228
	v_add_f32_e32 v225, v225, v229
	v_add_f32_e32 v226, v226, v230
	v_add_f32_e32 v227, v227, v231
	ds_bpermute_b32 v228, v85, v224
	ds_bpermute_b32 v229, v85, v225
	ds_bpermute_b32 v230, v85, v226
	ds_bpermute_b32 v231, v85, v227
	s_waitcnt lgkmcnt(0)
	v_add_f32_e32 v224, v224, v228
	v_add_f32_e32 v225, v225, v229
	v_add_f32_e32 v226, v226, v230
	v_add_f32_e32 v227, v227, v231
	ds_bpermute_b32 v228, v86, v224
	ds_bpermute_b32 v229, v86, v225
	ds_bpermute_b32 v230, v86, v226
	ds_bpermute_b32 v231, v86, v227
	s_waitcnt lgkmcnt(0)
	v_add_f32_e32 v224, v224, v228
	v_add_f32_e32 v225, v225, v229
	v_add_f32_e32 v226, v226, v230
	v_add_f32_e32 v227, v227, v231
	ds_bpermute_b32 v228, v87, v224
	ds_bpermute_b32 v229, v87, v225
	ds_bpermute_b32 v230, v87, v226
	ds_bpermute_b32 v231, v87, v227
	s_waitcnt lgkmcnt(0)
	v_add_f32_e32 v224, v224, v228
	v_add_f32_e32 v225, v225, v229
	v_add_f32_e32 v226, v226, v230
	v_add_f32_e32 v227, v227, v231
	ds_bpermute_b32 v228, v88, v224
	ds_bpermute_b32 v229, v88, v225
	ds_bpermute_b32 v230, v88, v226
	ds_bpermute_b32 v231, v88, v227
	s_waitcnt lgkmcnt(0)
	v_add_f32_e32 v224, v224, v228
	v_add_f32_e32 v225, v225, v229
	v_add_f32_e32 v226, v226, v230
	v_add_f32_e32 v227, v227, v231
	v_fmamk_f32 v240, v224, 0x3a800000, v89
	v_mul_f32_e32 v241, 0x4f800000, v240
	v_cmp_gt_f32_e32 vcc, s54, v240
	s_nop 1
	v_cndmask_b32_e32 v247, v240, v241, vcc
	v_sqrt_f32_e32 v242, v247
	s_nop 1
	v_add_u32_e32 v243, -1, v242
	v_add_u32_e32 v244, 1, v242
	v_fma_f32 v245, -v243, v242, v247
	v_fma_f32 v246, -v244, v242, v247
	v_cmp_ge_f32_e64 s[52:53], 0, v245
	s_nop 1
	v_cndmask_b32_e64 v242, v242, v243, s[52:53]
	v_cmp_lt_f32_e64 s[52:53], 0, v246
	s_nop 1
	v_cndmask_b32_e64 v242, v242, v244, s[52:53]
	v_mul_f32_e32 v243, 0x37800000, v242
	v_cndmask_b32_e32 v242, v242, v243, vcc
	v_cmp_class_f32_e32 vcc, v247, v90
	s_nop 1
	v_cndmask_b32_e32 v247, v242, v247, vcc
	v_div_scale_f32 v248, s[52:53], v247, v247, 1.0
	v_rcp_f32_e32 v249, v248
	v_div_scale_f32 v228, vcc, 1.0, v247, 1.0
	s_nop 0
	v_fma_f32 v229, -v248, v249, 1.0
	v_fmac_f32_e32 v249, v229, v249
	v_mul_f32_e32 v230, v228, v249
	v_fma_f32 v229, -v248, v230, v228
	v_fmac_f32_e32 v230, v229, v249
	v_fma_f32 v248, -v248, v230, v228
	v_div_fmas_f32 v248, v248, v249, v230
	v_div_fixup_f32 v232, v248, v247, 1.0
	v_fmamk_f32 v240, v225, 0x3a800000, v89
	v_mul_f32_e32 v241, 0x4f800000, v240
	v_cmp_gt_f32_e32 vcc, s54, v240
	s_nop 1
	v_cndmask_b32_e32 v247, v240, v241, vcc
	v_sqrt_f32_e32 v242, v247
	s_nop 1
	v_add_u32_e32 v243, -1, v242
	v_add_u32_e32 v244, 1, v242
	v_fma_f32 v245, -v243, v242, v247
	v_fma_f32 v246, -v244, v242, v247
	v_cmp_ge_f32_e64 s[52:53], 0, v245
	s_nop 1
	v_cndmask_b32_e64 v242, v242, v243, s[52:53]
	v_cmp_lt_f32_e64 s[52:53], 0, v246
	s_nop 1
	v_cndmask_b32_e64 v242, v242, v244, s[52:53]
	v_mul_f32_e32 v243, 0x37800000, v242
	v_cndmask_b32_e32 v242, v242, v243, vcc
	v_cmp_class_f32_e32 vcc, v247, v90
	s_nop 1
	v_cndmask_b32_e32 v247, v242, v247, vcc
	v_div_scale_f32 v248, s[52:53], v247, v247, 1.0
	v_rcp_f32_e32 v249, v248
	v_div_scale_f32 v228, vcc, 1.0, v247, 1.0
	s_nop 0
	v_fma_f32 v229, -v248, v249, 1.0
	v_fmac_f32_e32 v249, v229, v249
	v_mul_f32_e32 v230, v228, v249
	v_fma_f32 v229, -v248, v230, v228
	v_fmac_f32_e32 v230, v229, v249
; __device__ __forceinline__ unsigned pk2(float lo, float hi) { return pg8::cvt_pk_bf16(lo, hi); }
; template <bool BF> __device__ __forceinline__ void prep_rows(const float* xp, const float* xs, const bf16* hb, const float* g, const float* MOD, int shoff, int scoff, bf16* U, int gw, int NGW, int lane) {
;     ...
;         for (int r = 0; r < R; ++r) { const int m = mb + r * NGW; if (m < MT) {
;             const float rstd = 1.0f / sqrtf(s[r] * (1.0f / DM) + RMS_EPS);
;             const float* mr = MOD + (size_t)(m < MP ? (m >> 13) : 8 + ((m - MP) >> 12)) * 6144;
; #pragma unroll
;             for (int j = 0; j < 4; ++j) { const int c = 4 * lane + 256 * j;
;                 const f32x4 gg = *(const f32x4*)(g + c), sc = *(const f32x4*)(mr + scoff + c), sh = *(const f32x4*)(mr + shoff + c);
;                 const f32x4 o = v[r][j] * rstd * gg * (sc + 1.0f) + sh; v2u w; w.x = pk2(o.x, o.y); w.y = pk2(o.z, o.w); *(v2u*)(U + (size_t)m * DM + c) = w; } } }
	v_fma_f32 v248, -v248, v230, v228
	v_div_fmas_f32 v248, v248, v249, v230
	v_div_fixup_f32 v234, v248, v247, 1.0
	v_fmamk_f32 v240, v226, 0x3a800000, v89
	v_mul_f32_e32 v241, 0x4f800000, v240
	v_cmp_gt_f32_e32 vcc, s54, v240
	s_nop 1
	v_cndmask_b32_e32 v247, v240, v241, vcc
	v_sqrt_f32_e32 v242, v247
	s_nop 1
	v_add_u32_e32 v243, -1, v242
	v_add_u32_e32 v244, 1, v242
	v_fma_f32 v245, -v243, v242, v247
	v_fma_f32 v246, -v244, v242, v247
	v_cmp_ge_f32_e64 s[52:53], 0, v245
	s_nop 1
	v_cndmask_b32_e64 v242, v242, v243, s[52:53]
	v_cmp_lt_f32_e64 s[52:53], 0, v246
	s_nop 1
	v_cndmask_b32_e64 v242, v242, v244, s[52:53]
	v_mul_f32_e32 v243, 0x37800000, v242
	v_cndmask_b32_e32 v242, v242, v243, vcc
	v_cmp_class_f32_e32 vcc, v247, v90
	s_nop 1
	v_cndmask_b32_e32 v247, v242, v247, vcc
	v_div_scale_f32 v248, s[52:53], v247, v247, 1.0
	v_rcp_f32_e32 v249, v248
	v_div_scale_f32 v228, vcc, 1.0, v247, 1.0
	s_nop 0
	v_fma_f32 v229, -v248, v249, 1.0
	v_fmac_f32_e32 v249, v229, v249
	v_mul_f32_e32 v230, v228, v249
	v_fma_f32 v229, -v248, v230, v228
	v_fmac_f32_e32 v230, v229, v249
	v_fma_f32 v248, -v248, v230, v228
	v_div_fmas_f32 v248, v248, v249, v230
	v_div_fixup_f32 v236, v248, v247, 1.0
	v_fmamk_f32 v240, v227, 0x3a800000, v89
	v_mul_f32_e32 v241, 0x4f800000, v240
	v_cmp_gt_f32_e32 vcc, s54, v240
	s_nop 1
	v_cndmask_b32_e32 v247, v240, v241, vcc
	v_sqrt_f32_e32 v242, v247
	s_nop 1
	v_add_u32_e32 v243, -1, v242
	v_add_u32_e32 v244, 1, v242
	v_fma_f32 v245, -v243, v242, v247
	v_fma_f32 v246, -v244, v242, v247
	v_cmp_ge_f32_e64 s[52:53], 0, v245
	s_nop 1
	v_cndmask_b32_e64 v242, v242, v243, s[52:53]
	v_cmp_lt_f32_e64 s[52:53], 0, v246
	s_nop 1
	v_cndmask_b32_e64 v242, v242, v244, s[52:53]
	v_mul_f32_e32 v243, 0x37800000, v242
	v_cndmask_b32_e32 v242, v242, v243, vcc
	v_cmp_class_f32_e32 vcc, v247, v90
	s_nop 1
	v_cndmask_b32_e32 v247, v242, v247, vcc
	v_div_scale_f32 v248, s[52:53], v247, v247, 1.0
	v_rcp_f32_e32 v249, v248
	v_div_scale_f32 v228, vcc, 1.0, v247, 1.0
	s_nop 0
	v_fma_f32 v229, -v248, v249, 1.0
	v_fmac_f32_e32 v249, v229, v249
	v_mul_f32_e32 v230, v228, v249
	v_fma_f32 v229, -v248, v230, v228
	v_fmac_f32_e32 v230, v229, v249
	v_fma_f32 v248, -v248, v230, v228
	v_div_fmas_f32 v248, v248, v249, v230
	v_div_fixup_f32 v238, v248, v247, 1.0
	s_waitcnt vmcnt(16)
	v_pk_add_f32 v[160:161], v[160:161], 1.0 op_sel_hi:[1,0]
	v_pk_add_f32 v[162:163], v[162:163], 1.0 op_sel_hi:[1,0]
	v_pk_add_f32 v[164:165], v[164:165], 1.0 op_sel_hi:[1,0]
	v_pk_add_f32 v[166:167], v[166:167], 1.0 op_sel_hi:[1,0]
	v_pk_add_f32 v[168:169], v[168:169], 1.0 op_sel_hi:[1,0]
	v_pk_add_f32 v[170:171], v[170:171], 1.0 op_sel_hi:[1,0]
	v_pk_add_f32 v[172:173], v[172:173], 1.0 op_sel_hi:[1,0]
	v_pk_add_f32 v[174:175], v[174:175], 1.0 op_sel_hi:[1,0]
	v_pk_add_f32 v[192:193], v[192:193], 1.0 op_sel_hi:[1,0]
	v_pk_add_f32 v[194:195], v[194:195], 1.0 op_sel_hi:[1,0]
	v_pk_add_f32 v[196:197], v[196:197], 1.0 op_sel_hi:[1,0]
	v_pk_add_f32 v[198:199], v[198:199], 1.0 op_sel_hi:[1,0]
	v_pk_add_f32 v[200:201], v[200:201], 1.0 op_sel_hi:[1,0]
	v_pk_add_f32 v[202:203], v[202:203], 1.0 op_sel_hi:[1,0]
	v_pk_add_f32 v[204:205], v[204:205], 1.0 op_sel_hi:[1,0]
	v_pk_add_f32 v[206:207], v[206:207], 1.0 op_sel_hi:[1,0]
	s_add_u32 s38, s20, 0x4000000
	s_addc_u32 s39, s21, 0
	s_add_u32 s40, s20, 0x4400000
	s_addc_u32 s41, s21, 0
	s_add_u32 s46, s20, 0x4800000
	s_addc_u32 s47, s21, 0
	s_add_u32 s48, s20, 0x4c00000
	s_addc_u32 s49, s21, 0
	v_pk_mul_f32 v[0:1], v[0:1], v[232:233] op_sel_hi:[1,0]
	v_pk_mul_f32 v[2:3], v[2:3], v[232:233] op_sel_hi:[1,0]
	v_pk_mul_f32 v[0:1], v[64:65], v[0:1]
	v_pk_mul_f32 v[2:3], v[66:67], v[2:3]
	v_pk_fma_f32 v[0:1], v[160:161], v[0:1], v[176:177]
	v_pk_fma_f32 v[2:3], v[162:163], v[2:3], v[178:179]
	v_cvt_pk_bf16_f32 v244, v0, v1
	v_cvt_pk_bf16_f32 v245, v2, v3
	v_pk_mul_f32 v[4:5], v[4:5], v[232:233] op_sel_hi:[1,0]
	v_pk_mul_f32 v[6:7], v[6:7], v[232:233] op_sel_hi:[1,0]
	v_pk_mul_f32 v[4:5], v[68:69], v[4:5]
	v_pk_mul_f32 v[6:7], v[70:71], v[6:7]
	v_pk_fma_f32 v[4:5], v[164:165], v[4:5], v[180:181]
	v_pk_fma_f32 v[6:7], v[166:167], v[6:7], v[182:183]
	v_cvt_pk_bf16_f32 v246, v4, v5
	v_cvt_pk_bf16_f32 v247, v6, v7
	global_store_dwordx4 v82, v[244:247], s[38:39] offset:0
	v_pk_mul_f32 v[8:9], v[8:9], v[232:233] op_sel_hi:[1,0]
	v_pk_mul_f32 v[10:11], v[10:11], v[232:233] op_sel_hi:[1,0]
	v_pk_mul_f32 v[8:9], v[72:73], v[8:9]
	v_pk_mul_f32 v[10:11], v[74:75], v[10:11]
	v_pk_fma_f32 v[8:9], v[168:169], v[8:9], v[184:185]
	v_pk_fma_f32 v[10:11], v[170:171], v[10:11], v[186:187]
	v_cvt_pk_bf16_f32 v240, v8, v9
	v_cvt_pk_bf16_f32 v241, v10, v11
	v_pk_mul_f32 v[12:13], v[12:13], v[232:233] op_sel_hi:[1,0]
	v_pk_mul_f32 v[14:15], v[14:15], v[232:233] op_sel_hi:[1,0]
	v_pk_mul_f32 v[12:13], v[76:77], v[12:13]
	v_pk_mul_f32 v[14:15], v[78:79], v[14:15]
	v_pk_fma_f32 v[12:13], v[172:173], v[12:13], v[188:189]
	v_pk_fma_f32 v[14:15], v[174:175], v[14:15], v[190:191]
	v_cvt_pk_bf16_f32 v242, v12, v13
	v_cvt_pk_bf16_f32 v243, v14, v15
	global_store_dwordx4 v82, v[240:243], s[38:39] offset:1024
	v_pk_mul_f32 v[16:17], v[16:17], v[234:235] op_sel_hi:[1,0]
	v_pk_mul_f32 v[18:19], v[18:19], v[234:235] op_sel_hi:[1,0]
	v_pk_mul_f32 v[16:17], v[64:65], v[16:17]
	v_pk_mul_f32 v[18:19], v[66:67], v[18:19]
	v_pk_fma_f32 v[16:17], v[160:161], v[16:17], v[176:177]
	v_pk_fma_f32 v[18:19], v[162:163], v[18:19], v[178:179]
	v_cvt_pk_bf16_f32 v244, v16, v17
	v_cvt_pk_bf16_f32 v245, v18, v19
	v_pk_mul_f32 v[20:21], v[20:21], v[234:235] op_sel_hi:[1,0]
	v_pk_mul_f32 v[22:23], v[22:23], v[234:235] op_sel_hi:[1,0]
	v_pk_mul_f32 v[20:21], v[68:69], v[20:21]
	v_pk_mul_f32 v[22:23], v[70:71], v[22:23]
; __device__ __forceinline__ float bf_lo(unsigned w) { return __uint_as_float(w << 16); }
; __device__ __forceinline__ float bf_hi(unsigned w) { return __uint_as_float(w & 0xffff0000u); }
; template <bool BF> __device__ __forceinline__ void prep_rows(const float* xp, const float* xs, const bf16* hb, const float* g, const float* MOD, int shoff, int scoff, bf16* U, int gw, int NGW, int lane) {
;     ...
;         for (int r = 0; r < R; ++r) { const int m = mb + r * NGW; const int mc = m < MT ? m : mb;
; #pragma unroll
;             for (int j = 0; j < 4; ++j) {
;                 if (BF) { const v2u a0 = *(const v2u*)(hb + (size_t)mc * DM + 4 * lane + 256 * j);
;                     v[r][j].x = pg8::bf_lo(a0.x); v[r][j].y = pg8::bf_hi(a0.x); v[r][j].z = pg8::bf_lo(a0.y); v[r][j].w = pg8::bf_hi(a0.y); }
;                 else { const float* xr = mc < MP ? xp + (size_t)mc * DM : xs + (size_t)(mc - MP) * DM; v[r][j] = *(const f32x4*)(xr + 4 * lane + 256 * j); } } }
;     ...
;                 const f32x4 gg = *(const f32x4*)(g + c), sc = *(const f32x4*)(mr + scoff + c), sh = *(const f32x4*)(mr + shoff + c);
	v_pk_fma_f32 v[20:21], v[164:165], v[20:21], v[180:181]
	v_pk_fma_f32 v[22:23], v[166:167], v[22:23], v[182:183]
	v_cvt_pk_bf16_f32 v246, v20, v21
	v_cvt_pk_bf16_f32 v247, v22, v23
	global_store_dwordx4 v82, v[244:247], s[40:41] offset:0
	v_pk_mul_f32 v[24:25], v[24:25], v[234:235] op_sel_hi:[1,0]
	v_pk_mul_f32 v[26:27], v[26:27], v[234:235] op_sel_hi:[1,0]
	v_pk_mul_f32 v[24:25], v[72:73], v[24:25]
	v_pk_mul_f32 v[26:27], v[74:75], v[26:27]
	v_pk_fma_f32 v[24:25], v[168:169], v[24:25], v[184:185]
	v_pk_fma_f32 v[26:27], v[170:171], v[26:27], v[186:187]
	v_cvt_pk_bf16_f32 v240, v24, v25
	v_cvt_pk_bf16_f32 v241, v26, v27
	v_pk_mul_f32 v[28:29], v[28:29], v[234:235] op_sel_hi:[1,0]
	v_pk_mul_f32 v[30:31], v[30:31], v[234:235] op_sel_hi:[1,0]
	v_pk_mul_f32 v[28:29], v[76:77], v[28:29]
	v_pk_mul_f32 v[30:31], v[78:79], v[30:31]
	v_pk_fma_f32 v[28:29], v[172:173], v[28:29], v[188:189]
	v_pk_fma_f32 v[30:31], v[174:175], v[30:31], v[190:191]
	v_cvt_pk_bf16_f32 v242, v28, v29
	v_cvt_pk_bf16_f32 v243, v30, v31
	global_store_dwordx4 v82, v[240:243], s[40:41] offset:1024
	v_pk_mul_f32 v[32:33], v[32:33], v[236:237] op_sel_hi:[1,0]
	v_pk_mul_f32 v[34:35], v[34:35], v[236:237] op_sel_hi:[1,0]
	v_pk_mul_f32 v[32:33], v[64:65], v[32:33]
	v_pk_mul_f32 v[34:35], v[66:67], v[34:35]
	v_pk_fma_f32 v[32:33], v[192:193], v[32:33], v[208:209]
	v_pk_fma_f32 v[34:35], v[194:195], v[34:35], v[210:211]
	v_cvt_pk_bf16_f32 v244, v32, v33
	v_cvt_pk_bf16_f32 v245, v34, v35
	v_pk_mul_f32 v[36:37], v[36:37], v[236:237] op_sel_hi:[1,0]
	v_pk_mul_f32 v[38:39], v[38:39], v[236:237] op_sel_hi:[1,0]
	v_pk_mul_f32 v[36:37], v[68:69], v[36:37]
	v_pk_mul_f32 v[38:39], v[70:71], v[38:39]
	v_pk_fma_f32 v[36:37], v[196:197], v[36:37], v[212:213]
	v_pk_fma_f32 v[38:39], v[198:199], v[38:39], v[214:215]
	v_cvt_pk_bf16_f32 v246, v36, v37
	v_cvt_pk_bf16_f32 v247, v38, v39
	global_store_dwordx4 v82, v[244:247], s[46:47] offset:0
	v_pk_mul_f32 v[40:41], v[40:41], v[236:237] op_sel_hi:[1,0]
	v_pk_mul_f32 v[42:43], v[42:43], v[236:237] op_sel_hi:[1,0]
	v_pk_mul_f32 v[40:41], v[72:73], v[40:41]
	v_pk_mul_f32 v[42:43], v[74:75], v[42:43]
	v_pk_fma_f32 v[40:41], v[200:201], v[40:41], v[216:217]
	v_pk_fma_f32 v[42:43], v[202:203], v[42:43], v[218:219]
	v_cvt_pk_bf16_f32 v240, v40, v41
	v_cvt_pk_bf16_f32 v241, v42, v43
	v_pk_mul_f32 v[44:45], v[44:45], v[236:237] op_sel_hi:[1,0]
	v_pk_mul_f32 v[46:47], v[46:47], v[236:237] op_sel_hi:[1,0]
	v_pk_mul_f32 v[44:45], v[76:77], v[44:45]
	v_pk_mul_f32 v[46:47], v[78:79], v[46:47]
	v_pk_fma_f32 v[44:45], v[204:205], v[44:45], v[220:221]
	v_pk_fma_f32 v[46:47], v[206:207], v[46:47], v[222:223]
	v_cvt_pk_bf16_f32 v242, v44, v45
	v_cvt_pk_bf16_f32 v243, v46, v47
	global_store_dwordx4 v82, v[240:243], s[46:47] offset:1024
	v_pk_mul_f32 v[48:49], v[48:49], v[238:239] op_sel_hi:[1,0]
	v_pk_mul_f32 v[50:51], v[50:51], v[238:239] op_sel_hi:[1,0]
	v_pk_mul_f32 v[48:49], v[64:65], v[48:49]
	v_pk_mul_f32 v[50:51], v[66:67], v[50:51]
	v_pk_fma_f32 v[48:49], v[192:193], v[48:49], v[208:209]
	v_pk_fma_f32 v[50:51], v[194:195], v[50:51], v[210:211]
	v_cvt_pk_bf16_f32 v244, v48, v49
	v_cvt_pk_bf16_f32 v245, v50, v51
	v_pk_mul_f32 v[52:53], v[52:53], v[238:239] op_sel_hi:[1,0]
	v_pk_mul_f32 v[54:55], v[54:55], v[238:239] op_sel_hi:[1,0]
	v_pk_mul_f32 v[52:53], v[68:69], v[52:53]
	v_pk_mul_f32 v[54:55], v[70:71], v[54:55]
	v_pk_fma_f32 v[52:53], v[196:197], v[52:53], v[212:213]
	v_pk_fma_f32 v[54:55], v[198:199], v[54:55], v[214:215]
	v_cvt_pk_bf16_f32 v246, v52, v53
	v_cvt_pk_bf16_f32 v247, v54, v55
	global_store_dwordx4 v82, v[244:247], s[48:49] offset:0
	v_pk_mul_f32 v[56:57], v[56:57], v[238:239] op_sel_hi:[1,0]
	v_pk_mul_f32 v[58:59], v[58:59], v[238:239] op_sel_hi:[1,0]
	v_pk_mul_f32 v[56:57], v[72:73], v[56:57]
	v_pk_mul_f32 v[58:59], v[74:75], v[58:59]
	v_pk_fma_f32 v[56:57], v[200:201], v[56:57], v[216:217]
	v_pk_fma_f32 v[58:59], v[202:203], v[58:59], v[218:219]
	v_cvt_pk_bf16_f32 v240, v56, v57
	v_cvt_pk_bf16_f32 v241, v58, v59
	v_pk_mul_f32 v[60:61], v[60:61], v[238:239] op_sel_hi:[1,0]
	v_pk_mul_f32 v[62:63], v[62:63], v[238:239] op_sel_hi:[1,0]
	v_pk_mul_f32 v[60:61], v[76:77], v[60:61]
	v_pk_mul_f32 v[62:63], v[78:79], v[62:63]
	v_pk_fma_f32 v[60:61], v[204:205], v[60:61], v[220:221]
	v_pk_fma_f32 v[62:63], v[206:207], v[62:63], v[222:223]
	v_cvt_pk_bf16_f32 v242, v60, v61
	v_cvt_pk_bf16_f32 v243, v62, v63
	global_store_dwordx4 v82, v[240:243], s[48:49] offset:1024
	s_add_u32 s34, s8, 0x1e000
	s_addc_u32 s35, s9, 0
	s_add_u32 s36, s8, 0x1e000
	s_addc_u32 s37, s9, 0
	global_load_dwordx4 v[176:179], v80, s[34:35] offset:0
	global_load_dwordx4 v[180:183], v80, s[34:35] offset:16
	global_load_dwordx4 v[184:187], v80, s[34:35] offset:2048
	global_load_dwordx4 v[188:191], v80, s[34:35] offset:2064
	global_load_dwordx4 v[160:163], v81, s[34:35] offset:0
	global_load_dwordx4 v[164:167], v81, s[34:35] offset:16
	global_load_dwordx4 v[168:171], v81, s[34:35] offset:2048
	global_load_dwordx4 v[172:175], v81, s[34:35] offset:2064
	global_load_dwordx4 v[208:211], v80, s[36:37] offset:0
	global_load_dwordx4 v[212:215], v80, s[36:37] offset:16
	global_load_dwordx4 v[216:219], v80, s[36:37] offset:2048
	global_load_dwordx4 v[220:223], v80, s[36:37] offset:2064
	global_load_dwordx4 v[192:195], v81, s[36:37] offset:0
	global_load_dwordx4 v[196:199], v81, s[36:37] offset:16
	global_load_dwordx4 v[200:203], v81, s[36:37] offset:2048
	global_load_dwordx4 v[204:207], v81, s[36:37] offset:2064
	s_add_u32 s24, s16, 0xc000000
	s_addc_u32 s25, s17, 0
	s_add_u32 s26, s16, 0xc800000
	s_addc_u32 s27, s17, 0
	s_add_u32 s28, s16, 0xd000000
	s_addc_u32 s29, s17, 0
	s_add_u32 s30, s16, 0xd800000
	s_addc_u32 s31, s17, 0
	global_load_dwordx4 v[0:3], v80, s[24:25] offset:0 nt
	global_load_dwordx4 v[4:7], v80, s[24:25] offset:16 nt
	global_load_dwordx4 v[8:11], v80, s[24:25] offset:2048 nt
	global_load_dwordx4 v[12:15], v80, s[24:25] offset:2064 nt
	global_load_dwordx4 v[16:19], v80, s[26:27] offset:0 nt
	global_load_dwordx4 v[20:23], v80, s[26:27] offset:16 nt
	global_load_dwordx4 v[24:27], v80, s[26:27] offset:2048 nt
	global_load_dwordx4 v[28:31], v80, s[26:27] offset:2064 nt
	global_load_dwordx4 v[32:35], v80, s[28:29] offset:0 nt
	global_load_dwordx4 v[36:39], v80, s[28:29] offset:16 nt
	global_load_dwordx4 v[40:43], v80, s[28:29] offset:2048 nt
	global_load_dwordx4 v[44:47], v80, s[28:29] offset:2064 nt
	global_load_dwordx4 v[48:51], v80, s[30:31] offset:0 nt
	global_load_dwordx4 v[52:55], v80, s[30:31] offset:16 nt
	global_load_dwordx4 v[56:59], v80, s[30:31] offset:2048 nt
	global_load_dwordx4 v[60:63], v80, s[30:31] offset:2064 nt
	s_waitcnt vmcnt(40)
; template <bool BF> __device__ __forceinline__ void prep_rows(const float* xp, const float* xs, const bf16* hb, const float* g, const float* MOD, int shoff, int scoff, bf16* U, int gw, int NGW, int lane) {
;     ...
;         for (int r = 0; r < R; ++r) { float t = 0.f;
; #pragma unroll
;             for (int j = 0; j < 4; ++j) t += (v[r][j].x * v[r][j].x + v[r][j].y * v[r][j].y) + (v[r][j].z * v[r][j].z + v[r][j].w * v[r][j].w);
;             s[r] = t; }
; #pragma unroll
;         for (int o = 1; o < 64; o <<= 1) {
; #pragma unroll
;             for (int r = 0; r < R; ++r) s[r] += __shfl_xor(s[r], o); }
; #pragma unroll
;         for (int r = 0; r < R; ++r) { const int m = mb + r * NGW; if (m < MT) {
;             const float rstd = 1.0f / sqrtf(s[r] * (1.0f / DM) + RMS_EPS);
	v_pk_mul_f32 v[240:241], v[96:97], v[96:97]
	v_pk_mul_f32 v[242:243], v[112:113], v[112:113]
	v_pk_mul_f32 v[244:245], v[128:129], v[128:129]
	v_pk_mul_f32 v[246:247], v[144:145], v[144:145]
	v_pk_fma_f32 v[240:241], v[98:99], v[98:99], v[240:241]
	v_pk_fma_f32 v[242:243], v[114:115], v[114:115], v[242:243]
	v_pk_fma_f32 v[244:245], v[130:131], v[130:131], v[244:245]
	v_pk_fma_f32 v[246:247], v[146:147], v[146:147], v[246:247]
	v_pk_fma_f32 v[240:241], v[100:101], v[100:101], v[240:241]
	v_pk_fma_f32 v[242:243], v[116:117], v[116:117], v[242:243]
	v_pk_fma_f32 v[244:245], v[132:133], v[132:133], v[244:245]
	v_pk_fma_f32 v[246:247], v[148:149], v[148:149], v[246:247]
	v_pk_fma_f32 v[240:241], v[102:103], v[102:103], v[240:241]
	v_pk_fma_f32 v[242:243], v[118:119], v[118:119], v[242:243]
	v_pk_fma_f32 v[244:245], v[134:135], v[134:135], v[244:245]
	v_pk_fma_f32 v[246:247], v[150:151], v[150:151], v[246:247]
	v_pk_fma_f32 v[240:241], v[104:105], v[104:105], v[240:241]
	v_pk_fma_f32 v[242:243], v[120:121], v[120:121], v[242:243]
	v_pk_fma_f32 v[244:245], v[136:137], v[136:137], v[244:245]
	v_pk_fma_f32 v[246:247], v[152:153], v[152:153], v[246:247]
	v_pk_fma_f32 v[240:241], v[106:107], v[106:107], v[240:241]
	v_pk_fma_f32 v[242:243], v[122:123], v[122:123], v[242:243]
	v_pk_fma_f32 v[244:245], v[138:139], v[138:139], v[244:245]
	v_pk_fma_f32 v[246:247], v[154:155], v[154:155], v[246:247]
	v_pk_fma_f32 v[240:241], v[108:109], v[108:109], v[240:241]
	v_pk_fma_f32 v[242:243], v[124:125], v[124:125], v[242:243]
	v_pk_fma_f32 v[244:245], v[140:141], v[140:141], v[244:245]
	v_pk_fma_f32 v[246:247], v[156:157], v[156:157], v[246:247]
	v_pk_fma_f32 v[240:241], v[110:111], v[110:111], v[240:241]
	v_pk_fma_f32 v[242:243], v[126:127], v[126:127], v[242:243]
	v_pk_fma_f32 v[244:245], v[142:143], v[142:143], v[244:245]
	v_pk_fma_f32 v[246:247], v[158:159], v[158:159], v[246:247]
	v_add_f32_e32 v224, v240, v241
	v_add_f32_e32 v225, v242, v243
	v_add_f32_e32 v226, v244, v245
	v_add_f32_e32 v227, v246, v247
	ds_bpermute_b32 v228, v83, v224
	ds_bpermute_b32 v229, v83, v225
	ds_bpermute_b32 v230, v83, v226
	ds_bpermute_b32 v231, v83, v227
	s_waitcnt lgkmcnt(0)
	v_add_f32_e32 v224, v224, v228
	v_add_f32_e32 v225, v225, v229
	v_add_f32_e32 v226, v226, v230
	v_add_f32_e32 v227, v227, v231
	ds_bpermute_b32 v228, v84, v224
	ds_bpermute_b32 v229, v84, v225
	ds_bpermute_b32 v230, v84, v226
	ds_bpermute_b32 v231, v84, v227
	s_waitcnt lgkmcnt(0)
	v_add_f32_e32 v224, v224, v228
	v_add_f32_e32 v225, v225, v229
	v_add_f32_e32 v226, v226, v230
	v_add_f32_e32 v227, v227, v231
	ds_bpermute_b32 v228, v85, v224
	ds_bpermute_b32 v229, v85, v225
	ds_bpermute_b32 v230, v85, v226
	ds_bpermute_b32 v231, v85, v227
	s_waitcnt lgkmcnt(0)
	v_add_f32_e32 v224, v224, v228
	v_add_f32_e32 v225, v225, v229
	v_add_f32_e32 v226, v226, v230
	v_add_f32_e32 v227, v227, v231
	ds_bpermute_b32 v228, v86, v224
	ds_bpermute_b32 v229, v86, v225
	ds_bpermute_b32 v230, v86, v226
	ds_bpermute_b32 v231, v86, v227
	s_waitcnt lgkmcnt(0)
	v_add_f32_e32 v224, v224, v228
	v_add_f32_e32 v225, v225, v229
	v_add_f32_e32 v226, v226, v230
	v_add_f32_e32 v227, v227, v231
	ds_bpermute_b32 v228, v87, v224
	ds_bpermute_b32 v229, v87, v225
	ds_bpermute_b32 v230, v87, v226
	ds_bpermute_b32 v231, v87, v227
	s_waitcnt lgkmcnt(0)
	v_add_f32_e32 v224, v224, v228
	v_add_f32_e32 v225, v225, v229
	v_add_f32_e32 v226, v226, v230
	v_add_f32_e32 v227, v227, v231
	ds_bpermute_b32 v228, v88, v224
	ds_bpermute_b32 v229, v88, v225
	ds_bpermute_b32 v230, v88, v226
	ds_bpermute_b32 v231, v88, v227
	s_waitcnt lgkmcnt(0)
	v_add_f32_e32 v224, v224, v228
	v_add_f32_e32 v225, v225, v229
	v_add_f32_e32 v226, v226, v230
	v_add_f32_e32 v227, v227, v231
	v_fmamk_f32 v240, v224, 0x3a800000, v89
	v_mul_f32_e32 v241, 0x4f800000, v240
	v_cmp_gt_f32_e32 vcc, s54, v240
	s_nop 1
	v_cndmask_b32_e32 v247, v240, v241, vcc
	v_sqrt_f32_e32 v242, v247
	s_nop 1
	v_add_u32_e32 v243, -1, v242
	v_add_u32_e32 v244, 1, v242
	v_fma_f32 v245, -v243, v242, v247
	v_fma_f32 v246, -v244, v242, v247
	v_cmp_ge_f32_e64 s[52:53], 0, v245
	s_nop 1
	v_cndmask_b32_e64 v242, v242, v243, s[52:53]
	v_cmp_lt_f32_e64 s[52:53], 0, v246
	s_nop 1
	v_cndmask_b32_e64 v242, v242, v244, s[52:53]
	v_mul_f32_e32 v243, 0x37800000, v242
	v_cndmask_b32_e32 v242, v242, v243, vcc
	v_cmp_class_f32_e32 vcc, v247, v90
	s_nop 1
	v_cndmask_b32_e32 v247, v242, v247, vcc
	v_div_scale_f32 v248, s[52:53], v247, v247, 1.0
	v_rcp_f32_e32 v249, v248
	v_div_scale_f32 v228, vcc, 1.0, v247, 1.0
	s_nop 0
	v_fma_f32 v229, -v248, v249, 1.0
	v_fmac_f32_e32 v249, v229, v249
	v_mul_f32_e32 v230, v228, v249
	v_fma_f32 v229, -v248, v230, v228
	v_fmac_f32_e32 v230, v229, v249
	v_fma_f32 v248, -v248, v230, v228
	v_div_fmas_f32 v248, v248, v249, v230
	v_div_fixup_f32 v232, v248, v247, 1.0
	v_fmamk_f32 v240, v225, 0x3a800000, v89
	v_mul_f32_e32 v241, 0x4f800000, v240
	v_cmp_gt_f32_e32 vcc, s54, v240
	s_nop 1
	v_cndmask_b32_e32 v247, v240, v241, vcc
	v_sqrt_f32_e32 v242, v247
	s_nop 1
	v_add_u32_e32 v243, -1, v242
	v_add_u32_e32 v244, 1, v242
	v_fma_f32 v245, -v243, v242, v247
	v_fma_f32 v246, -v244, v242, v247
	v_cmp_ge_f32_e64 s[52:53], 0, v245
	s_nop 1
	v_cndmask_b32_e64 v242, v242, v243, s[52:53]
	v_cmp_lt_f32_e64 s[52:53], 0, v246
	s_nop 1
	v_cndmask_b32_e64 v242, v242, v244, s[52:53]
	v_mul_f32_e32 v243, 0x37800000, v242
	v_cndmask_b32_e32 v242, v242, v243, vcc
	v_cmp_class_f32_e32 vcc, v247, v90
	s_nop 1
	v_cndmask_b32_e32 v247, v242, v247, vcc
	v_div_scale_f32 v248, s[52:53], v247, v247, 1.0
	v_rcp_f32_e32 v249, v248
	v_div_scale_f32 v228, vcc, 1.0, v247, 1.0
	s_nop 0
	v_fma_f32 v229, -v248, v249, 1.0
; __device__ __forceinline__ unsigned pk2(float lo, float hi) { return pg8::cvt_pk_bf16(lo, hi); }
; template <bool BF> __device__ __forceinline__ void prep_rows(const float* xp, const float* xs, const bf16* hb, const float* g, const float* MOD, int shoff, int scoff, bf16* U, int gw, int NGW, int lane) {
;     ...
;         for (int r = 0; r < R; ++r) { const int m = mb + r * NGW; if (m < MT) {
;             const float rstd = 1.0f / sqrtf(s[r] * (1.0f / DM) + RMS_EPS);
;             const float* mr = MOD + (size_t)(m < MP ? (m >> 13) : 8 + ((m - MP) >> 12)) * 6144;
; #pragma unroll
;             for (int j = 0; j < 4; ++j) { const int c = 4 * lane + 256 * j;
;                 const f32x4 gg = *(const f32x4*)(g + c), sc = *(const f32x4*)(mr + scoff + c), sh = *(const f32x4*)(mr + shoff + c);
;                 const f32x4 o = v[r][j] * rstd * gg * (sc + 1.0f) + sh; v2u w; w.x = pk2(o.x, o.y); w.y = pk2(o.z, o.w); *(v2u*)(U + (size_t)m * DM + c) = w; } } }
	v_fmac_f32_e32 v249, v229, v249
	v_mul_f32_e32 v230, v228, v249
	v_fma_f32 v229, -v248, v230, v228
	v_fmac_f32_e32 v230, v229, v249
	v_fma_f32 v248, -v248, v230, v228
	v_div_fmas_f32 v248, v248, v249, v230
	v_div_fixup_f32 v234, v248, v247, 1.0
	v_fmamk_f32 v240, v226, 0x3a800000, v89
	v_mul_f32_e32 v241, 0x4f800000, v240
	v_cmp_gt_f32_e32 vcc, s54, v240
	s_nop 1
	v_cndmask_b32_e32 v247, v240, v241, vcc
	v_sqrt_f32_e32 v242, v247
	s_nop 1
	v_add_u32_e32 v243, -1, v242
	v_add_u32_e32 v244, 1, v242
	v_fma_f32 v245, -v243, v242, v247
	v_fma_f32 v246, -v244, v242, v247
	v_cmp_ge_f32_e64 s[52:53], 0, v245
	s_nop 1
	v_cndmask_b32_e64 v242, v242, v243, s[52:53]
	v_cmp_lt_f32_e64 s[52:53], 0, v246
	s_nop 1
	v_cndmask_b32_e64 v242, v242, v244, s[52:53]
	v_mul_f32_e32 v243, 0x37800000, v242
	v_cndmask_b32_e32 v242, v242, v243, vcc
	v_cmp_class_f32_e32 vcc, v247, v90
	s_nop 1
	v_cndmask_b32_e32 v247, v242, v247, vcc
	v_div_scale_f32 v248, s[52:53], v247, v247, 1.0
	v_rcp_f32_e32 v249, v248
	v_div_scale_f32 v228, vcc, 1.0, v247, 1.0
	s_nop 0
	v_fma_f32 v229, -v248, v249, 1.0
	v_fmac_f32_e32 v249, v229, v249
	v_mul_f32_e32 v230, v228, v249
	v_fma_f32 v229, -v248, v230, v228
	v_fmac_f32_e32 v230, v229, v249
	v_fma_f32 v248, -v248, v230, v228
	v_div_fmas_f32 v248, v248, v249, v230
	v_div_fixup_f32 v236, v248, v247, 1.0
	v_fmamk_f32 v240, v227, 0x3a800000, v89
	v_mul_f32_e32 v241, 0x4f800000, v240
	v_cmp_gt_f32_e32 vcc, s54, v240
	s_nop 1
	v_cndmask_b32_e32 v247, v240, v241, vcc
	v_sqrt_f32_e32 v242, v247
	s_nop 1
	v_add_u32_e32 v243, -1, v242
	v_add_u32_e32 v244, 1, v242
	v_fma_f32 v245, -v243, v242, v247
	v_fma_f32 v246, -v244, v242, v247
	v_cmp_ge_f32_e64 s[52:53], 0, v245
	s_nop 1
	v_cndmask_b32_e64 v242, v242, v243, s[52:53]
	v_cmp_lt_f32_e64 s[52:53], 0, v246
	s_nop 1
	v_cndmask_b32_e64 v242, v242, v244, s[52:53]
	v_mul_f32_e32 v243, 0x37800000, v242
	v_cndmask_b32_e32 v242, v242, v243, vcc
	v_cmp_class_f32_e32 vcc, v247, v90
	s_nop 1
	v_cndmask_b32_e32 v247, v242, v247, vcc
	v_div_scale_f32 v248, s[52:53], v247, v247, 1.0
	v_rcp_f32_e32 v249, v248
	v_div_scale_f32 v228, vcc, 1.0, v247, 1.0
	s_nop 0
	v_fma_f32 v229, -v248, v249, 1.0
	v_fmac_f32_e32 v249, v229, v249
	v_mul_f32_e32 v230, v228, v249
	v_fma_f32 v229, -v248, v230, v228
	v_fmac_f32_e32 v230, v229, v249
	v_fma_f32 v248, -v248, v230, v228
	v_div_fmas_f32 v248, v248, v249, v230
	v_div_fixup_f32 v238, v248, v247, 1.0
	s_waitcnt vmcnt(16)
	v_pk_add_f32 v[160:161], v[160:161], 1.0 op_sel_hi:[1,0]
	v_pk_add_f32 v[162:163], v[162:163], 1.0 op_sel_hi:[1,0]
	v_pk_add_f32 v[164:165], v[164:165], 1.0 op_sel_hi:[1,0]
	v_pk_add_f32 v[166:167], v[166:167], 1.0 op_sel_hi:[1,0]
	v_pk_add_f32 v[168:169], v[168:169], 1.0 op_sel_hi:[1,0]
	v_pk_add_f32 v[170:171], v[170:171], 1.0 op_sel_hi:[1,0]
	v_pk_add_f32 v[172:173], v[172:173], 1.0 op_sel_hi:[1,0]
	v_pk_add_f32 v[174:175], v[174:175], 1.0 op_sel_hi:[1,0]
	v_pk_add_f32 v[192:193], v[192:193], 1.0 op_sel_hi:[1,0]
	v_pk_add_f32 v[194:195], v[194:195], 1.0 op_sel_hi:[1,0]
	v_pk_add_f32 v[196:197], v[196:197], 1.0 op_sel_hi:[1,0]
	v_pk_add_f32 v[198:199], v[198:199], 1.0 op_sel_hi:[1,0]
	v_pk_add_f32 v[200:201], v[200:201], 1.0 op_sel_hi:[1,0]
	v_pk_add_f32 v[202:203], v[202:203], 1.0 op_sel_hi:[1,0]
	v_pk_add_f32 v[204:205], v[204:205], 1.0 op_sel_hi:[1,0]
	v_pk_add_f32 v[206:207], v[206:207], 1.0 op_sel_hi:[1,0]
	s_add_u32 s38, s20, 0x5000000
	s_addc_u32 s39, s21, 0
	s_add_u32 s40, s20, 0x5400000
	s_addc_u32 s41, s21, 0
	s_add_u32 s46, s20, 0x5800000
	s_addc_u32 s47, s21, 0
	s_add_u32 s48, s20, 0x5c00000
	s_addc_u32 s49, s21, 0
	v_pk_mul_f32 v[96:97], v[96:97], v[232:233] op_sel_hi:[1,0]
	v_pk_mul_f32 v[98:99], v[98:99], v[232:233] op_sel_hi:[1,0]
	v_pk_mul_f32 v[96:97], v[64:65], v[96:97]
	v_pk_mul_f32 v[98:99], v[66:67], v[98:99]
	v_pk_fma_f32 v[96:97], v[160:161], v[96:97], v[176:177]
	v_pk_fma_f32 v[98:99], v[162:163], v[98:99], v[178:179]
	v_cvt_pk_bf16_f32 v244, v96, v97
	v_cvt_pk_bf16_f32 v245, v98, v99
	v_pk_mul_f32 v[100:101], v[100:101], v[232:233] op_sel_hi:[1,0]
	v_pk_mul_f32 v[102:103], v[102:103], v[232:233] op_sel_hi:[1,0]
	v_pk_mul_f32 v[100:101], v[68:69], v[100:101]
	v_pk_mul_f32 v[102:103], v[70:71], v[102:103]
	v_pk_fma_f32 v[100:101], v[164:165], v[100:101], v[180:181]
	v_pk_fma_f32 v[102:103], v[166:167], v[102:103], v[182:183]
	v_cvt_pk_bf16_f32 v246, v100, v101
	v_cvt_pk_bf16_f32 v247, v102, v103
	global_store_dwordx4 v82, v[244:247], s[38:39] offset:0
	v_pk_mul_f32 v[104:105], v[104:105], v[232:233] op_sel_hi:[1,0]
	v_pk_mul_f32 v[106:107], v[106:107], v[232:233] op_sel_hi:[1,0]
	v_pk_mul_f32 v[104:105], v[72:73], v[104:105]
	v_pk_mul_f32 v[106:107], v[74:75], v[106:107]
	v_pk_fma_f32 v[104:105], v[168:169], v[104:105], v[184:185]
	v_pk_fma_f32 v[106:107], v[170:171], v[106:107], v[186:187]
	v_cvt_pk_bf16_f32 v240, v104, v105
	v_cvt_pk_bf16_f32 v241, v106, v107
	v_pk_mul_f32 v[108:109], v[108:109], v[232:233] op_sel_hi:[1,0]
	v_pk_mul_f32 v[110:111], v[110:111], v[232:233] op_sel_hi:[1,0]
	v_pk_mul_f32 v[108:109], v[76:77], v[108:109]
	v_pk_mul_f32 v[110:111], v[78:79], v[110:111]
	v_pk_fma_f32 v[108:109], v[172:173], v[108:109], v[188:189]
	v_pk_fma_f32 v[110:111], v[174:175], v[110:111], v[190:191]
	v_cvt_pk_bf16_f32 v242, v108, v109
	v_cvt_pk_bf16_f32 v243, v110, v111
	global_store_dwordx4 v82, v[240:243], s[38:39] offset:1024
	v_pk_mul_f32 v[112:113], v[112:113], v[234:235] op_sel_hi:[1,0]
	v_pk_mul_f32 v[114:115], v[114:115], v[234:235] op_sel_hi:[1,0]
	v_pk_mul_f32 v[112:113], v[64:65], v[112:113]
	v_pk_mul_f32 v[114:115], v[66:67], v[114:115]
	v_pk_fma_f32 v[112:113], v[160:161], v[112:113], v[176:177]
; __device__ __forceinline__ float bf_lo(unsigned w) { return __uint_as_float(w << 16); }
; __device__ __forceinline__ float bf_hi(unsigned w) { return __uint_as_float(w & 0xffff0000u); }
; __device__ __forceinline__ unsigned pk2(float lo, float hi) { return pg8::cvt_pk_bf16(lo, hi); }
; template <bool BF> __device__ __forceinline__ void prep_rows(const float* xp, const float* xs, const bf16* hb, const float* g, const float* MOD, int shoff, int scoff, bf16* U, int gw, int NGW, int lane) {
;     ...
;         for (int r = 0; r < R; ++r) { const int m = mb + r * NGW; const int mc = m < MT ? m : mb;
; #pragma unroll
;             for (int j = 0; j < 4; ++j) {
;                 if (BF) { const v2u a0 = *(const v2u*)(hb + (size_t)mc * DM + 4 * lane + 256 * j);
;                     v[r][j].x = pg8::bf_lo(a0.x); v[r][j].y = pg8::bf_hi(a0.x); v[r][j].z = pg8::bf_lo(a0.y); v[r][j].w = pg8::bf_hi(a0.y); }
;                 else { const float* xr = mc < MP ? xp + (size_t)mc * DM : xs + (size_t)(mc - MP) * DM; v[r][j] = *(const f32x4*)(xr + 4 * lane + 256 * j); } } }
;     ...
;         for (int r = 0; r < R; ++r) { const int m = mb + r * NGW; if (m < MT) {
;             const float rstd = 1.0f / sqrtf(s[r] * (1.0f / DM) + RMS_EPS);
;             const float* mr = MOD + (size_t)(m < MP ? (m >> 13) : 8 + ((m - MP) >> 12)) * 6144;
; #pragma unroll
;             for (int j = 0; j < 4; ++j) { const int c = 4 * lane + 256 * j;
;                 const f32x4 gg = *(const f32x4*)(g + c), sc = *(const f32x4*)(mr + scoff + c), sh = *(const f32x4*)(mr + shoff + c);
;                 const f32x4 o = v[r][j] * rstd * gg * (sc + 1.0f) + sh; v2u w; w.x = pk2(o.x, o.y); w.y = pk2(o.z, o.w); *(v2u*)(U + (size_t)m * DM + c) = w; } } }
	v_pk_fma_f32 v[114:115], v[162:163], v[114:115], v[178:179]
	v_cvt_pk_bf16_f32 v244, v112, v113
	v_cvt_pk_bf16_f32 v245, v114, v115
	v_pk_mul_f32 v[116:117], v[116:117], v[234:235] op_sel_hi:[1,0]
	v_pk_mul_f32 v[118:119], v[118:119], v[234:235] op_sel_hi:[1,0]
	v_pk_mul_f32 v[116:117], v[68:69], v[116:117]
	v_pk_mul_f32 v[118:119], v[70:71], v[118:119]
	v_pk_fma_f32 v[116:117], v[164:165], v[116:117], v[180:181]
	v_pk_fma_f32 v[118:119], v[166:167], v[118:119], v[182:183]
	v_cvt_pk_bf16_f32 v246, v116, v117
	v_cvt_pk_bf16_f32 v247, v118, v119
	global_store_dwordx4 v82, v[244:247], s[40:41] offset:0
	v_pk_mul_f32 v[120:121], v[120:121], v[234:235] op_sel_hi:[1,0]
	v_pk_mul_f32 v[122:123], v[122:123], v[234:235] op_sel_hi:[1,0]
	v_pk_mul_f32 v[120:121], v[72:73], v[120:121]
	v_pk_mul_f32 v[122:123], v[74:75], v[122:123]
	v_pk_fma_f32 v[120:121], v[168:169], v[120:121], v[184:185]
	v_pk_fma_f32 v[122:123], v[170:171], v[122:123], v[186:187]
	v_cvt_pk_bf16_f32 v240, v120, v121
	v_cvt_pk_bf16_f32 v241, v122, v123
	v_pk_mul_f32 v[124:125], v[124:125], v[234:235] op_sel_hi:[1,0]
	v_pk_mul_f32 v[126:127], v[126:127], v[234:235] op_sel_hi:[1,0]
	v_pk_mul_f32 v[124:125], v[76:77], v[124:125]
	v_pk_mul_f32 v[126:127], v[78:79], v[126:127]
	v_pk_fma_f32 v[124:125], v[172:173], v[124:125], v[188:189]
	v_pk_fma_f32 v[126:127], v[174:175], v[126:127], v[190:191]
	v_cvt_pk_bf16_f32 v242, v124, v125
	v_cvt_pk_bf16_f32 v243, v126, v127
	global_store_dwordx4 v82, v[240:243], s[40:41] offset:1024
	v_pk_mul_f32 v[128:129], v[128:129], v[236:237] op_sel_hi:[1,0]
	v_pk_mul_f32 v[130:131], v[130:131], v[236:237] op_sel_hi:[1,0]
	v_pk_mul_f32 v[128:129], v[64:65], v[128:129]
	v_pk_mul_f32 v[130:131], v[66:67], v[130:131]
	v_pk_fma_f32 v[128:129], v[192:193], v[128:129], v[208:209]
	v_pk_fma_f32 v[130:131], v[194:195], v[130:131], v[210:211]
	v_cvt_pk_bf16_f32 v244, v128, v129
	v_cvt_pk_bf16_f32 v245, v130, v131
	v_pk_mul_f32 v[132:133], v[132:133], v[236:237] op_sel_hi:[1,0]
	v_pk_mul_f32 v[134:135], v[134:135], v[236:237] op_sel_hi:[1,0]
	v_pk_mul_f32 v[132:133], v[68:69], v[132:133]
	v_pk_mul_f32 v[134:135], v[70:71], v[134:135]
	v_pk_fma_f32 v[132:133], v[196:197], v[132:133], v[212:213]
	v_pk_fma_f32 v[134:135], v[198:199], v[134:135], v[214:215]
	v_cvt_pk_bf16_f32 v246, v132, v133
	v_cvt_pk_bf16_f32 v247, v134, v135
	global_store_dwordx4 v82, v[244:247], s[46:47] offset:0
	v_pk_mul_f32 v[136:137], v[136:137], v[236:237] op_sel_hi:[1,0]
	v_pk_mul_f32 v[138:139], v[138:139], v[236:237] op_sel_hi:[1,0]
	v_pk_mul_f32 v[136:137], v[72:73], v[136:137]
	v_pk_mul_f32 v[138:139], v[74:75], v[138:139]
	v_pk_fma_f32 v[136:137], v[200:201], v[136:137], v[216:217]
	v_pk_fma_f32 v[138:139], v[202:203], v[138:139], v[218:219]
	v_cvt_pk_bf16_f32 v240, v136, v137
	v_cvt_pk_bf16_f32 v241, v138, v139
	v_pk_mul_f32 v[140:141], v[140:141], v[236:237] op_sel_hi:[1,0]
	v_pk_mul_f32 v[142:143], v[142:143], v[236:237] op_sel_hi:[1,0]
	v_pk_mul_f32 v[140:141], v[76:77], v[140:141]
	v_pk_mul_f32 v[142:143], v[78:79], v[142:143]
	v_pk_fma_f32 v[140:141], v[204:205], v[140:141], v[220:221]
	v_pk_fma_f32 v[142:143], v[206:207], v[142:143], v[222:223]
	v_cvt_pk_bf16_f32 v242, v140, v141
	v_cvt_pk_bf16_f32 v243, v142, v143
	global_store_dwordx4 v82, v[240:243], s[46:47] offset:1024
	v_pk_mul_f32 v[144:145], v[144:145], v[238:239] op_sel_hi:[1,0]
	v_pk_mul_f32 v[146:147], v[146:147], v[238:239] op_sel_hi:[1,0]
	v_pk_mul_f32 v[144:145], v[64:65], v[144:145]
	v_pk_mul_f32 v[146:147], v[66:67], v[146:147]
	v_pk_fma_f32 v[144:145], v[192:193], v[144:145], v[208:209]
	v_pk_fma_f32 v[146:147], v[194:195], v[146:147], v[210:211]
	v_cvt_pk_bf16_f32 v244, v144, v145
	v_cvt_pk_bf16_f32 v245, v146, v147
	v_pk_mul_f32 v[148:149], v[148:149], v[238:239] op_sel_hi:[1,0]
	v_pk_mul_f32 v[150:151], v[150:151], v[238:239] op_sel_hi:[1,0]
	v_pk_mul_f32 v[148:149], v[68:69], v[148:149]
	v_pk_mul_f32 v[150:151], v[70:71], v[150:151]
	v_pk_fma_f32 v[148:149], v[196:197], v[148:149], v[212:213]
	v_pk_fma_f32 v[150:151], v[198:199], v[150:151], v[214:215]
	v_cvt_pk_bf16_f32 v246, v148, v149
	v_cvt_pk_bf16_f32 v247, v150, v151
	global_store_dwordx4 v82, v[244:247], s[48:49] offset:0
	v_pk_mul_f32 v[152:153], v[152:153], v[238:239] op_sel_hi:[1,0]
	v_pk_mul_f32 v[154:155], v[154:155], v[238:239] op_sel_hi:[1,0]
	v_pk_mul_f32 v[152:153], v[72:73], v[152:153]
	v_pk_mul_f32 v[154:155], v[74:75], v[154:155]
	v_pk_fma_f32 v[152:153], v[200:201], v[152:153], v[216:217]
	v_pk_fma_f32 v[154:155], v[202:203], v[154:155], v[218:219]
	v_cvt_pk_bf16_f32 v240, v152, v153
	v_cvt_pk_bf16_f32 v241, v154, v155
	v_pk_mul_f32 v[156:157], v[156:157], v[238:239] op_sel_hi:[1,0]
	v_pk_mul_f32 v[158:159], v[158:159], v[238:239] op_sel_hi:[1,0]
	v_pk_mul_f32 v[156:157], v[76:77], v[156:157]
	v_pk_mul_f32 v[158:159], v[78:79], v[158:159]
	v_pk_fma_f32 v[156:157], v[204:205], v[156:157], v[220:221]
	v_pk_fma_f32 v[158:159], v[206:207], v[158:159], v[222:223]
	v_cvt_pk_bf16_f32 v242, v156, v157
	v_cvt_pk_bf16_f32 v243, v158, v159
	global_store_dwordx4 v82, v[240:243], s[48:49] offset:1024
	s_add_u32 s34, s8, 0x24000
	s_addc_u32 s35, s9, 0
	s_add_u32 s36, s8, 0x24000
	s_addc_u32 s37, s9, 0
	global_load_dwordx4 v[176:179], v80, s[34:35] offset:0
	global_load_dwordx4 v[180:183], v80, s[34:35] offset:16
	global_load_dwordx4 v[184:187], v80, s[34:35] offset:2048
	global_load_dwordx4 v[188:191], v80, s[34:35] offset:2064
	global_load_dwordx4 v[160:163], v81, s[34:35] offset:0
	global_load_dwordx4 v[164:167], v81, s[34:35] offset:16
	global_load_dwordx4 v[168:171], v81, s[34:35] offset:2048
	global_load_dwordx4 v[172:175], v81, s[34:35] offset:2064
; __device__ __forceinline__ float bf_lo(unsigned w) { return __uint_as_float(w << 16); }
; __device__ __forceinline__ float bf_hi(unsigned w) { return __uint_as_float(w & 0xffff0000u); }
; template <bool BF> __device__ __forceinline__ void prep_rows(const float* xp, const float* xs, const bf16* hb, const float* g, const float* MOD, int shoff, int scoff, bf16* U, int gw, int NGW, int lane) {
;     ...
;         for (int r = 0; r < R; ++r) { const int m = mb + r * NGW; const int mc = m < MT ? m : mb;
; #pragma unroll
;             for (int j = 0; j < 4; ++j) {
;                 if (BF) { const v2u a0 = *(const v2u*)(hb + (size_t)mc * DM + 4 * lane + 256 * j);
;                     v[r][j].x = pg8::bf_lo(a0.x); v[r][j].y = pg8::bf_hi(a0.x); v[r][j].z = pg8::bf_lo(a0.y); v[r][j].w = pg8::bf_hi(a0.y); }
;                 else { const float* xr = mc < MP ? xp + (size_t)mc * DM : xs + (size_t)(mc - MP) * DM; v[r][j] = *(const f32x4*)(xr + 4 * lane + 256 * j); } } }
; #pragma unroll
;         for (int r = 0; r < R; ++r) { float t = 0.f;
; #pragma unroll
;             for (int j = 0; j < 4; ++j) t += (v[r][j].x * v[r][j].x + v[r][j].y * v[r][j].y) + (v[r][j].z * v[r][j].z + v[r][j].w * v[r][j].w);
;             s[r] = t; }
; #pragma unroll
;         for (int o = 1; o < 64; o <<= 1) {
; #pragma unroll
;             for (int r = 0; r < R; ++r) s[r] += __shfl_xor(s[r], o); }
	global_load_dwordx4 v[208:211], v80, s[36:37] offset:0
	global_load_dwordx4 v[212:215], v80, s[36:37] offset:16
	global_load_dwordx4 v[216:219], v80, s[36:37] offset:2048
	global_load_dwordx4 v[220:223], v80, s[36:37] offset:2064
	global_load_dwordx4 v[192:195], v81, s[36:37] offset:0
	global_load_dwordx4 v[196:199], v81, s[36:37] offset:16
	global_load_dwordx4 v[200:203], v81, s[36:37] offset:2048
	global_load_dwordx4 v[204:207], v81, s[36:37] offset:2064
	s_add_u32 s24, s16, 0xe000000
	s_addc_u32 s25, s17, 0
	s_add_u32 s26, s16, 0xe800000
	s_addc_u32 s27, s17, 0
	s_add_u32 s28, s16, 0xf000000
	s_addc_u32 s29, s17, 0
	s_add_u32 s30, s16, 0xf800000
	s_addc_u32 s31, s17, 0
	global_load_dwordx4 v[96:99], v80, s[24:25] offset:0 nt
	global_load_dwordx4 v[100:103], v80, s[24:25] offset:16 nt
	global_load_dwordx4 v[104:107], v80, s[24:25] offset:2048 nt
	global_load_dwordx4 v[108:111], v80, s[24:25] offset:2064 nt
	global_load_dwordx4 v[112:115], v80, s[26:27] offset:0 nt
	global_load_dwordx4 v[116:119], v80, s[26:27] offset:16 nt
	global_load_dwordx4 v[120:123], v80, s[26:27] offset:2048 nt
	global_load_dwordx4 v[124:127], v80, s[26:27] offset:2064 nt
	global_load_dwordx4 v[128:131], v80, s[28:29] offset:0 nt
	global_load_dwordx4 v[132:135], v80, s[28:29] offset:16 nt
	global_load_dwordx4 v[136:139], v80, s[28:29] offset:2048 nt
	global_load_dwordx4 v[140:143], v80, s[28:29] offset:2064 nt
	global_load_dwordx4 v[144:147], v80, s[30:31] offset:0 nt
	global_load_dwordx4 v[148:151], v80, s[30:31] offset:16 nt
	global_load_dwordx4 v[152:155], v80, s[30:31] offset:2048 nt
	global_load_dwordx4 v[156:159], v80, s[30:31] offset:2064 nt
	s_waitcnt vmcnt(40)
	v_pk_mul_f32 v[240:241], v[0:1], v[0:1]
	v_pk_mul_f32 v[242:243], v[16:17], v[16:17]
	v_pk_mul_f32 v[244:245], v[32:33], v[32:33]
	v_pk_mul_f32 v[246:247], v[48:49], v[48:49]
	v_pk_fma_f32 v[240:241], v[2:3], v[2:3], v[240:241]
	v_pk_fma_f32 v[242:243], v[18:19], v[18:19], v[242:243]
	v_pk_fma_f32 v[244:245], v[34:35], v[34:35], v[244:245]
	v_pk_fma_f32 v[246:247], v[50:51], v[50:51], v[246:247]
	v_pk_fma_f32 v[240:241], v[4:5], v[4:5], v[240:241]
	v_pk_fma_f32 v[242:243], v[20:21], v[20:21], v[242:243]
	v_pk_fma_f32 v[244:245], v[36:37], v[36:37], v[244:245]
	v_pk_fma_f32 v[246:247], v[52:53], v[52:53], v[246:247]
	v_pk_fma_f32 v[240:241], v[6:7], v[6:7], v[240:241]
	v_pk_fma_f32 v[242:243], v[22:23], v[22:23], v[242:243]
	v_pk_fma_f32 v[244:245], v[38:39], v[38:39], v[244:245]
	v_pk_fma_f32 v[246:247], v[54:55], v[54:55], v[246:247]
	v_pk_fma_f32 v[240:241], v[8:9], v[8:9], v[240:241]
	v_pk_fma_f32 v[242:243], v[24:25], v[24:25], v[242:243]
	v_pk_fma_f32 v[244:245], v[40:41], v[40:41], v[244:245]
	v_pk_fma_f32 v[246:247], v[56:57], v[56:57], v[246:247]
	v_pk_fma_f32 v[240:241], v[10:11], v[10:11], v[240:241]
	v_pk_fma_f32 v[242:243], v[26:27], v[26:27], v[242:243]
	v_pk_fma_f32 v[244:245], v[42:43], v[42:43], v[244:245]
	v_pk_fma_f32 v[246:247], v[58:59], v[58:59], v[246:247]
	v_pk_fma_f32 v[240:241], v[12:13], v[12:13], v[240:241]
	v_pk_fma_f32 v[242:243], v[28:29], v[28:29], v[242:243]
	v_pk_fma_f32 v[244:245], v[44:45], v[44:45], v[244:245]
	v_pk_fma_f32 v[246:247], v[60:61], v[60:61], v[246:247]
	v_pk_fma_f32 v[240:241], v[14:15], v[14:15], v[240:241]
	v_pk_fma_f32 v[242:243], v[30:31], v[30:31], v[242:243]
	v_pk_fma_f32 v[244:245], v[46:47], v[46:47], v[244:245]
	v_pk_fma_f32 v[246:247], v[62:63], v[62:63], v[246:247]
	v_add_f32_e32 v224, v240, v241
	v_add_f32_e32 v225, v242, v243
	v_add_f32_e32 v226, v244, v245
	v_add_f32_e32 v227, v246, v247
	ds_bpermute_b32 v228, v83, v224
	ds_bpermute_b32 v229, v83, v225
	ds_bpermute_b32 v230, v83, v226
	ds_bpermute_b32 v231, v83, v227
	s_waitcnt lgkmcnt(0)
	v_add_f32_e32 v224, v224, v228
	v_add_f32_e32 v225, v225, v229
	v_add_f32_e32 v226, v226, v230
	v_add_f32_e32 v227, v227, v231
	ds_bpermute_b32 v228, v84, v224
	ds_bpermute_b32 v229, v84, v225
	ds_bpermute_b32 v230, v84, v226
	ds_bpermute_b32 v231, v84, v227
	s_waitcnt lgkmcnt(0)
	v_add_f32_e32 v224, v224, v228
	v_add_f32_e32 v225, v225, v229
	v_add_f32_e32 v226, v226, v230
	v_add_f32_e32 v227, v227, v231
	ds_bpermute_b32 v228, v85, v224
	ds_bpermute_b32 v229, v85, v225
	ds_bpermute_b32 v230, v85, v226
	ds_bpermute_b32 v231, v85, v227
	s_waitcnt lgkmcnt(0)
	v_add_f32_e32 v224, v224, v228
	v_add_f32_e32 v225, v225, v229
	v_add_f32_e32 v226, v226, v230
	v_add_f32_e32 v227, v227, v231
	ds_bpermute_b32 v228, v86, v224
	ds_bpermute_b32 v229, v86, v225
	ds_bpermute_b32 v230, v86, v226
	ds_bpermute_b32 v231, v86, v227
	s_waitcnt lgkmcnt(0)
	v_add_f32_e32 v224, v224, v228
	v_add_f32_e32 v225, v225, v229
	v_add_f32_e32 v226, v226, v230
	v_add_f32_e32 v227, v227, v231
	ds_bpermute_b32 v228, v87, v224
	ds_bpermute_b32 v229, v87, v225
	ds_bpermute_b32 v230, v87, v226
	ds_bpermute_b32 v231, v87, v227
	s_waitcnt lgkmcnt(0)
	v_add_f32_e32 v224, v224, v228
	v_add_f32_e32 v225, v225, v229
	v_add_f32_e32 v226, v226, v230
	v_add_f32_e32 v227, v227, v231
	ds_bpermute_b32 v228, v88, v224
	ds_bpermute_b32 v229, v88, v225
	ds_bpermute_b32 v230, v88, v226
	ds_bpermute_b32 v231, v88, v227
	s_waitcnt lgkmcnt(0)
; template <bool BF> __device__ __forceinline__ void prep_rows(const float* xp, const float* xs, const bf16* hb, const float* g, const float* MOD, int shoff, int scoff, bf16* U, int gw, int NGW, int lane) {
;     ...
;         for (int r = 0; r < R; ++r) { const int m = mb + r * NGW; if (m < MT) {
;             const float rstd = 1.0f / sqrtf(s[r] * (1.0f / DM) + RMS_EPS);
	v_add_f32_e32 v224, v224, v228
	v_add_f32_e32 v225, v225, v229
	v_add_f32_e32 v226, v226, v230
	v_add_f32_e32 v227, v227, v231
	v_fmamk_f32 v240, v224, 0x3a800000, v89
	v_mul_f32_e32 v241, 0x4f800000, v240
	v_cmp_gt_f32_e32 vcc, s54, v240
	s_nop 1
	v_cndmask_b32_e32 v247, v240, v241, vcc
	v_sqrt_f32_e32 v242, v247
	s_nop 1
	v_add_u32_e32 v243, -1, v242
	v_add_u32_e32 v244, 1, v242
	v_fma_f32 v245, -v243, v242, v247
	v_fma_f32 v246, -v244, v242, v247
	v_cmp_ge_f32_e64 s[52:53], 0, v245
	s_nop 1
	v_cndmask_b32_e64 v242, v242, v243, s[52:53]
	v_cmp_lt_f32_e64 s[52:53], 0, v246
	s_nop 1
	v_cndmask_b32_e64 v242, v242, v244, s[52:53]
	v_mul_f32_e32 v243, 0x37800000, v242
	v_cndmask_b32_e32 v242, v242, v243, vcc
	v_cmp_class_f32_e32 vcc, v247, v90
	s_nop 1
	v_cndmask_b32_e32 v247, v242, v247, vcc
	v_div_scale_f32 v248, s[52:53], v247, v247, 1.0
	v_rcp_f32_e32 v249, v248
	v_div_scale_f32 v228, vcc, 1.0, v247, 1.0
	s_nop 0
	v_fma_f32 v229, -v248, v249, 1.0
	v_fmac_f32_e32 v249, v229, v249
	v_mul_f32_e32 v230, v228, v249
	v_fma_f32 v229, -v248, v230, v228
	v_fmac_f32_e32 v230, v229, v249
	v_fma_f32 v248, -v248, v230, v228
	v_div_fmas_f32 v248, v248, v249, v230
	v_div_fixup_f32 v232, v248, v247, 1.0
	v_fmamk_f32 v240, v225, 0x3a800000, v89
	v_mul_f32_e32 v241, 0x4f800000, v240
	v_cmp_gt_f32_e32 vcc, s54, v240
	s_nop 1
	v_cndmask_b32_e32 v247, v240, v241, vcc
	v_sqrt_f32_e32 v242, v247
	s_nop 1
	v_add_u32_e32 v243, -1, v242
	v_add_u32_e32 v244, 1, v242
	v_fma_f32 v245, -v243, v242, v247
	v_fma_f32 v246, -v244, v242, v247
	v_cmp_ge_f32_e64 s[52:53], 0, v245
	s_nop 1
	v_cndmask_b32_e64 v242, v242, v243, s[52:53]
	v_cmp_lt_f32_e64 s[52:53], 0, v246
	s_nop 1
	v_cndmask_b32_e64 v242, v242, v244, s[52:53]
	v_mul_f32_e32 v243, 0x37800000, v242
	v_cndmask_b32_e32 v242, v242, v243, vcc
	v_cmp_class_f32_e32 vcc, v247, v90
	s_nop 1
	v_cndmask_b32_e32 v247, v242, v247, vcc
	v_div_scale_f32 v248, s[52:53], v247, v247, 1.0
	v_rcp_f32_e32 v249, v248
	v_div_scale_f32 v228, vcc, 1.0, v247, 1.0
	s_nop 0
	v_fma_f32 v229, -v248, v249, 1.0
	v_fmac_f32_e32 v249, v229, v249
	v_mul_f32_e32 v230, v228, v249
	v_fma_f32 v229, -v248, v230, v228
	v_fmac_f32_e32 v230, v229, v249
	v_fma_f32 v248, -v248, v230, v228
	v_div_fmas_f32 v248, v248, v249, v230
	v_div_fixup_f32 v234, v248, v247, 1.0
	v_fmamk_f32 v240, v226, 0x3a800000, v89
	v_mul_f32_e32 v241, 0x4f800000, v240
	v_cmp_gt_f32_e32 vcc, s54, v240
	s_nop 1
	v_cndmask_b32_e32 v247, v240, v241, vcc
	v_sqrt_f32_e32 v242, v247
	s_nop 1
	v_add_u32_e32 v243, -1, v242
	v_add_u32_e32 v244, 1, v242
	v_fma_f32 v245, -v243, v242, v247
	v_fma_f32 v246, -v244, v242, v247
	v_cmp_ge_f32_e64 s[52:53], 0, v245
	s_nop 1
	v_cndmask_b32_e64 v242, v242, v243, s[52:53]
	v_cmp_lt_f32_e64 s[52:53], 0, v246
	s_nop 1
	v_cndmask_b32_e64 v242, v242, v244, s[52:53]
	v_mul_f32_e32 v243, 0x37800000, v242
	v_cndmask_b32_e32 v242, v242, v243, vcc
	v_cmp_class_f32_e32 vcc, v247, v90
	s_nop 1
	v_cndmask_b32_e32 v247, v242, v247, vcc
	v_div_scale_f32 v248, s[52:53], v247, v247, 1.0
	v_rcp_f32_e32 v249, v248
	v_div_scale_f32 v228, vcc, 1.0, v247, 1.0
	s_nop 0
	v_fma_f32 v229, -v248, v249, 1.0
	v_fmac_f32_e32 v249, v229, v249
	v_mul_f32_e32 v230, v228, v249
	v_fma_f32 v229, -v248, v230, v228
	v_fmac_f32_e32 v230, v229, v249
	v_fma_f32 v248, -v248, v230, v228
	v_div_fmas_f32 v248, v248, v249, v230
	v_div_fixup_f32 v236, v248, v247, 1.0
	v_fmamk_f32 v240, v227, 0x3a800000, v89
	v_mul_f32_e32 v241, 0x4f800000, v240
	v_cmp_gt_f32_e32 vcc, s54, v240
	s_nop 1
	v_cndmask_b32_e32 v247, v240, v241, vcc
	v_sqrt_f32_e32 v242, v247
	s_nop 1
	v_add_u32_e32 v243, -1, v242
	v_add_u32_e32 v244, 1, v242
	v_fma_f32 v245, -v243, v242, v247
	v_fma_f32 v246, -v244, v242, v247
	v_cmp_ge_f32_e64 s[52:53], 0, v245
	s_nop 1
	v_cndmask_b32_e64 v242, v242, v243, s[52:53]
	v_cmp_lt_f32_e64 s[52:53], 0, v246
	s_nop 1
	v_cndmask_b32_e64 v242, v242, v244, s[52:53]
	v_mul_f32_e32 v243, 0x37800000, v242
	v_cndmask_b32_e32 v242, v242, v243, vcc
	v_cmp_class_f32_e32 vcc, v247, v90
	s_nop 1
	v_cndmask_b32_e32 v247, v242, v247, vcc
	v_div_scale_f32 v248, s[52:53], v247, v247, 1.0
	v_rcp_f32_e32 v249, v248
	v_div_scale_f32 v228, vcc, 1.0, v247, 1.0
	s_nop 0
	v_fma_f32 v229, -v248, v249, 1.0
	v_fmac_f32_e32 v249, v229, v249
	v_mul_f32_e32 v230, v228, v249
	v_fma_f32 v229, -v248, v230, v228
	v_fmac_f32_e32 v230, v229, v249
	v_fma_f32 v248, -v248, v230, v228
	v_div_fmas_f32 v248, v248, v249, v230
	v_div_fixup_f32 v238, v248, v247, 1.0
	s_waitcnt vmcnt(16)
; __device__ __forceinline__ unsigned pk2(float lo, float hi) { return pg8::cvt_pk_bf16(lo, hi); }
; template <bool BF> __device__ __forceinline__ void prep_rows(const float* xp, const float* xs, const bf16* hb, const float* g, const float* MOD, int shoff, int scoff, bf16* U, int gw, int NGW, int lane) {
;     ...
;         for (int r = 0; r < R; ++r) { const int m = mb + r * NGW; if (m < MT) {
;             const float rstd = 1.0f / sqrtf(s[r] * (1.0f / DM) + RMS_EPS);
;             const float* mr = MOD + (size_t)(m < MP ? (m >> 13) : 8 + ((m - MP) >> 12)) * 6144;
; #pragma unroll
;             for (int j = 0; j < 4; ++j) { const int c = 4 * lane + 256 * j;
;                 const f32x4 gg = *(const f32x4*)(g + c), sc = *(const f32x4*)(mr + scoff + c), sh = *(const f32x4*)(mr + shoff + c);
;                 const f32x4 o = v[r][j] * rstd * gg * (sc + 1.0f) + sh; v2u w; w.x = pk2(o.x, o.y); w.y = pk2(o.z, o.w); *(v2u*)(U + (size_t)m * DM + c) = w; } } }
	v_pk_add_f32 v[160:161], v[160:161], 1.0 op_sel_hi:[1,0]
	v_pk_add_f32 v[162:163], v[162:163], 1.0 op_sel_hi:[1,0]
	v_pk_add_f32 v[164:165], v[164:165], 1.0 op_sel_hi:[1,0]
	v_pk_add_f32 v[166:167], v[166:167], 1.0 op_sel_hi:[1,0]
	v_pk_add_f32 v[168:169], v[168:169], 1.0 op_sel_hi:[1,0]
	v_pk_add_f32 v[170:171], v[170:171], 1.0 op_sel_hi:[1,0]
	v_pk_add_f32 v[172:173], v[172:173], 1.0 op_sel_hi:[1,0]
	v_pk_add_f32 v[174:175], v[174:175], 1.0 op_sel_hi:[1,0]
	v_pk_add_f32 v[192:193], v[192:193], 1.0 op_sel_hi:[1,0]
	v_pk_add_f32 v[194:195], v[194:195], 1.0 op_sel_hi:[1,0]
	v_pk_add_f32 v[196:197], v[196:197], 1.0 op_sel_hi:[1,0]
	v_pk_add_f32 v[198:199], v[198:199], 1.0 op_sel_hi:[1,0]
	v_pk_add_f32 v[200:201], v[200:201], 1.0 op_sel_hi:[1,0]
	v_pk_add_f32 v[202:203], v[202:203], 1.0 op_sel_hi:[1,0]
	v_pk_add_f32 v[204:205], v[204:205], 1.0 op_sel_hi:[1,0]
	v_pk_add_f32 v[206:207], v[206:207], 1.0 op_sel_hi:[1,0]
	s_add_u32 s38, s20, 0x6000000
	s_addc_u32 s39, s21, 0
	s_add_u32 s40, s20, 0x6400000
	s_addc_u32 s41, s21, 0
	s_add_u32 s46, s20, 0x6800000
	s_addc_u32 s47, s21, 0
	s_add_u32 s48, s20, 0x6c00000
	s_addc_u32 s49, s21, 0
	v_pk_mul_f32 v[0:1], v[0:1], v[232:233] op_sel_hi:[1,0]
	v_pk_mul_f32 v[2:3], v[2:3], v[232:233] op_sel_hi:[1,0]
	v_pk_mul_f32 v[0:1], v[64:65], v[0:1]
	v_pk_mul_f32 v[2:3], v[66:67], v[2:3]
	v_pk_fma_f32 v[0:1], v[160:161], v[0:1], v[176:177]
	v_pk_fma_f32 v[2:3], v[162:163], v[2:3], v[178:179]
	v_cvt_pk_bf16_f32 v244, v0, v1
	v_cvt_pk_bf16_f32 v245, v2, v3
	v_pk_mul_f32 v[4:5], v[4:5], v[232:233] op_sel_hi:[1,0]
	v_pk_mul_f32 v[6:7], v[6:7], v[232:233] op_sel_hi:[1,0]
	v_pk_mul_f32 v[4:5], v[68:69], v[4:5]
	v_pk_mul_f32 v[6:7], v[70:71], v[6:7]
	v_pk_fma_f32 v[4:5], v[164:165], v[4:5], v[180:181]
	v_pk_fma_f32 v[6:7], v[166:167], v[6:7], v[182:183]
	v_cvt_pk_bf16_f32 v246, v4, v5
	v_cvt_pk_bf16_f32 v247, v6, v7
	global_store_dwordx4 v82, v[244:247], s[38:39] offset:0
	v_pk_mul_f32 v[8:9], v[8:9], v[232:233] op_sel_hi:[1,0]
	v_pk_mul_f32 v[10:11], v[10:11], v[232:233] op_sel_hi:[1,0]
	v_pk_mul_f32 v[8:9], v[72:73], v[8:9]
	v_pk_mul_f32 v[10:11], v[74:75], v[10:11]
	v_pk_fma_f32 v[8:9], v[168:169], v[8:9], v[184:185]
	v_pk_fma_f32 v[10:11], v[170:171], v[10:11], v[186:187]
	v_cvt_pk_bf16_f32 v240, v8, v9
	v_cvt_pk_bf16_f32 v241, v10, v11
	v_pk_mul_f32 v[12:13], v[12:13], v[232:233] op_sel_hi:[1,0]
	v_pk_mul_f32 v[14:15], v[14:15], v[232:233] op_sel_hi:[1,0]
	v_pk_mul_f32 v[12:13], v[76:77], v[12:13]
	v_pk_mul_f32 v[14:15], v[78:79], v[14:15]
	v_pk_fma_f32 v[12:13], v[172:173], v[12:13], v[188:189]
	v_pk_fma_f32 v[14:15], v[174:175], v[14:15], v[190:191]
	v_cvt_pk_bf16_f32 v242, v12, v13
	v_cvt_pk_bf16_f32 v243, v14, v15
	global_store_dwordx4 v82, v[240:243], s[38:39] offset:1024
	v_pk_mul_f32 v[16:17], v[16:17], v[234:235] op_sel_hi:[1,0]
	v_pk_mul_f32 v[18:19], v[18:19], v[234:235] op_sel_hi:[1,0]
	v_pk_mul_f32 v[16:17], v[64:65], v[16:17]
	v_pk_mul_f32 v[18:19], v[66:67], v[18:19]
	v_pk_fma_f32 v[16:17], v[160:161], v[16:17], v[176:177]
	v_pk_fma_f32 v[18:19], v[162:163], v[18:19], v[178:179]
	v_cvt_pk_bf16_f32 v244, v16, v17
	v_cvt_pk_bf16_f32 v245, v18, v19
	v_pk_mul_f32 v[20:21], v[20:21], v[234:235] op_sel_hi:[1,0]
	v_pk_mul_f32 v[22:23], v[22:23], v[234:235] op_sel_hi:[1,0]
	v_pk_mul_f32 v[20:21], v[68:69], v[20:21]
	v_pk_mul_f32 v[22:23], v[70:71], v[22:23]
	v_pk_fma_f32 v[20:21], v[164:165], v[20:21], v[180:181]
	v_pk_fma_f32 v[22:23], v[166:167], v[22:23], v[182:183]
	v_cvt_pk_bf16_f32 v246, v20, v21
	v_cvt_pk_bf16_f32 v247, v22, v23
	global_store_dwordx4 v82, v[244:247], s[40:41] offset:0
	v_pk_mul_f32 v[24:25], v[24:25], v[234:235] op_sel_hi:[1,0]
	v_pk_mul_f32 v[26:27], v[26:27], v[234:235] op_sel_hi:[1,0]
	v_pk_mul_f32 v[24:25], v[72:73], v[24:25]
	v_pk_mul_f32 v[26:27], v[74:75], v[26:27]
	v_pk_fma_f32 v[24:25], v[168:169], v[24:25], v[184:185]
	v_pk_fma_f32 v[26:27], v[170:171], v[26:27], v[186:187]
	v_cvt_pk_bf16_f32 v240, v24, v25
	v_cvt_pk_bf16_f32 v241, v26, v27
	v_pk_mul_f32 v[28:29], v[28:29], v[234:235] op_sel_hi:[1,0]
	v_pk_mul_f32 v[30:31], v[30:31], v[234:235] op_sel_hi:[1,0]
	v_pk_mul_f32 v[28:29], v[76:77], v[28:29]
	v_pk_mul_f32 v[30:31], v[78:79], v[30:31]
	v_pk_fma_f32 v[28:29], v[172:173], v[28:29], v[188:189]
	v_pk_fma_f32 v[30:31], v[174:175], v[30:31], v[190:191]
	v_cvt_pk_bf16_f32 v242, v28, v29
	v_cvt_pk_bf16_f32 v243, v30, v31
	global_store_dwordx4 v82, v[240:243], s[40:41] offset:1024
	v_pk_mul_f32 v[32:33], v[32:33], v[236:237] op_sel_hi:[1,0]
	v_pk_mul_f32 v[34:35], v[34:35], v[236:237] op_sel_hi:[1,0]
	v_pk_mul_f32 v[32:33], v[64:65], v[32:33]
	v_pk_mul_f32 v[34:35], v[66:67], v[34:35]
	v_pk_fma_f32 v[32:33], v[192:193], v[32:33], v[208:209]
	v_pk_fma_f32 v[34:35], v[194:195], v[34:35], v[210:211]
	v_cvt_pk_bf16_f32 v244, v32, v33
	v_cvt_pk_bf16_f32 v245, v34, v35
	v_pk_mul_f32 v[36:37], v[36:37], v[236:237] op_sel_hi:[1,0]
	v_pk_mul_f32 v[38:39], v[38:39], v[236:237] op_sel_hi:[1,0]
	v_pk_mul_f32 v[36:37], v[68:69], v[36:37]
	v_pk_mul_f32 v[38:39], v[70:71], v[38:39]
	v_pk_fma_f32 v[36:37], v[196:197], v[36:37], v[212:213]
	v_pk_fma_f32 v[38:39], v[198:199], v[38:39], v[214:215]
	v_cvt_pk_bf16_f32 v246, v36, v37
	v_cvt_pk_bf16_f32 v247, v38, v39
	global_store_dwordx4 v82, v[244:247], s[46:47] offset:0
	v_pk_mul_f32 v[40:41], v[40:41], v[236:237] op_sel_hi:[1,0]
	v_pk_mul_f32 v[42:43], v[42:43], v[236:237] op_sel_hi:[1,0]
	v_pk_mul_f32 v[40:41], v[72:73], v[40:41]
	v_pk_mul_f32 v[42:43], v[74:75], v[42:43]
	v_pk_fma_f32 v[40:41], v[200:201], v[40:41], v[216:217]
	v_pk_fma_f32 v[42:43], v[202:203], v[42:43], v[218:219]
	v_cvt_pk_bf16_f32 v240, v40, v41
; __device__ __forceinline__ float bf_lo(unsigned w) { return __uint_as_float(w << 16); }
; __device__ __forceinline__ float bf_hi(unsigned w) { return __uint_as_float(w & 0xffff0000u); }
; template <bool BF> __device__ __forceinline__ void prep_rows(const float* xp, const float* xs, const bf16* hb, const float* g, const float* MOD, int shoff, int scoff, bf16* U, int gw, int NGW, int lane) {
;     ...
;         for (int r = 0; r < R; ++r) { const int m = mb + r * NGW; const int mc = m < MT ? m : mb;
; #pragma unroll
;             for (int j = 0; j < 4; ++j) {
;                 if (BF) { const v2u a0 = *(const v2u*)(hb + (size_t)mc * DM + 4 * lane + 256 * j);
;                     v[r][j].x = pg8::bf_lo(a0.x); v[r][j].y = pg8::bf_hi(a0.x); v[r][j].z = pg8::bf_lo(a0.y); v[r][j].w = pg8::bf_hi(a0.y); }
;                 else { const float* xr = mc < MP ? xp + (size_t)mc * DM : xs + (size_t)(mc - MP) * DM; v[r][j] = *(const f32x4*)(xr + 4 * lane + 256 * j); } } }
; #pragma unroll
;         for (int r = 0; r < R; ++r) { float t = 0.f;
; #pragma unroll
;             for (int j = 0; j < 4; ++j) t += (v[r][j].x * v[r][j].x + v[r][j].y * v[r][j].y) + (v[r][j].z * v[r][j].z + v[r][j].w * v[r][j].w);
;             s[r] = t; }
; #pragma unroll
;         for (int o = 1; o < 64; o <<= 1) {
; #pragma unroll
;             for (int r = 0; r < R; ++r) s[r] += __shfl_xor(s[r], o); }
	v_cvt_pk_bf16_f32 v241, v42, v43
	v_pk_mul_f32 v[44:45], v[44:45], v[236:237] op_sel_hi:[1,0]
	v_pk_mul_f32 v[46:47], v[46:47], v[236:237] op_sel_hi:[1,0]
	v_pk_mul_f32 v[44:45], v[76:77], v[44:45]
	v_pk_mul_f32 v[46:47], v[78:79], v[46:47]
	v_pk_fma_f32 v[44:45], v[204:205], v[44:45], v[220:221]
	v_pk_fma_f32 v[46:47], v[206:207], v[46:47], v[222:223]
	v_cvt_pk_bf16_f32 v242, v44, v45
	v_cvt_pk_bf16_f32 v243, v46, v47
	global_store_dwordx4 v82, v[240:243], s[46:47] offset:1024
	v_pk_mul_f32 v[48:49], v[48:49], v[238:239] op_sel_hi:[1,0]
	v_pk_mul_f32 v[50:51], v[50:51], v[238:239] op_sel_hi:[1,0]
	v_pk_mul_f32 v[48:49], v[64:65], v[48:49]
	v_pk_mul_f32 v[50:51], v[66:67], v[50:51]
	v_pk_fma_f32 v[48:49], v[192:193], v[48:49], v[208:209]
	v_pk_fma_f32 v[50:51], v[194:195], v[50:51], v[210:211]
	v_cvt_pk_bf16_f32 v244, v48, v49
	v_cvt_pk_bf16_f32 v245, v50, v51
	v_pk_mul_f32 v[52:53], v[52:53], v[238:239] op_sel_hi:[1,0]
	v_pk_mul_f32 v[54:55], v[54:55], v[238:239] op_sel_hi:[1,0]
	v_pk_mul_f32 v[52:53], v[68:69], v[52:53]
	v_pk_mul_f32 v[54:55], v[70:71], v[54:55]
	v_pk_fma_f32 v[52:53], v[196:197], v[52:53], v[212:213]
	v_pk_fma_f32 v[54:55], v[198:199], v[54:55], v[214:215]
	v_cvt_pk_bf16_f32 v246, v52, v53
	v_cvt_pk_bf16_f32 v247, v54, v55
	global_store_dwordx4 v82, v[244:247], s[48:49] offset:0
	v_pk_mul_f32 v[56:57], v[56:57], v[238:239] op_sel_hi:[1,0]
	v_pk_mul_f32 v[58:59], v[58:59], v[238:239] op_sel_hi:[1,0]
	v_pk_mul_f32 v[56:57], v[72:73], v[56:57]
	v_pk_mul_f32 v[58:59], v[74:75], v[58:59]
	v_pk_fma_f32 v[56:57], v[200:201], v[56:57], v[216:217]
	v_pk_fma_f32 v[58:59], v[202:203], v[58:59], v[218:219]
	v_cvt_pk_bf16_f32 v240, v56, v57
	v_cvt_pk_bf16_f32 v241, v58, v59
	v_pk_mul_f32 v[60:61], v[60:61], v[238:239] op_sel_hi:[1,0]
	v_pk_mul_f32 v[62:63], v[62:63], v[238:239] op_sel_hi:[1,0]
	v_pk_mul_f32 v[60:61], v[76:77], v[60:61]
	v_pk_mul_f32 v[62:63], v[78:79], v[62:63]
	v_pk_fma_f32 v[60:61], v[204:205], v[60:61], v[220:221]
	v_pk_fma_f32 v[62:63], v[206:207], v[62:63], v[222:223]
	v_cvt_pk_bf16_f32 v242, v60, v61
	v_cvt_pk_bf16_f32 v243, v62, v63
	global_store_dwordx4 v82, v[240:243], s[48:49] offset:1024
	s_add_u32 s34, s8, 0x2a000
	s_addc_u32 s35, s9, 0
	s_add_u32 s36, s8, 0x2a000
	s_addc_u32 s37, s9, 0
	global_load_dwordx4 v[176:179], v80, s[34:35] offset:0
	global_load_dwordx4 v[180:183], v80, s[34:35] offset:16
	global_load_dwordx4 v[184:187], v80, s[34:35] offset:2048
	global_load_dwordx4 v[188:191], v80, s[34:35] offset:2064
	global_load_dwordx4 v[160:163], v81, s[34:35] offset:0
	global_load_dwordx4 v[164:167], v81, s[34:35] offset:16
	global_load_dwordx4 v[168:171], v81, s[34:35] offset:2048
	global_load_dwordx4 v[172:175], v81, s[34:35] offset:2064
	global_load_dwordx4 v[208:211], v80, s[36:37] offset:0
	global_load_dwordx4 v[212:215], v80, s[36:37] offset:16
	global_load_dwordx4 v[216:219], v80, s[36:37] offset:2048
	global_load_dwordx4 v[220:223], v80, s[36:37] offset:2064
	global_load_dwordx4 v[192:195], v81, s[36:37] offset:0
	global_load_dwordx4 v[196:199], v81, s[36:37] offset:16
	global_load_dwordx4 v[200:203], v81, s[36:37] offset:2048
	global_load_dwordx4 v[204:207], v81, s[36:37] offset:2064
	s_mov_b64 s[24:25], s[18:19]
	s_add_u32 s26, s18, 0x800000
	s_addc_u32 s27, s19, 0
	s_add_u32 s28, s18, 0x1000000
	s_addc_u32 s29, s19, 0
	s_add_u32 s30, s18, 0x1800000
	s_addc_u32 s31, s19, 0
	global_load_dwordx4 v[0:3], v80, s[24:25] offset:0 nt
	global_load_dwordx4 v[4:7], v80, s[24:25] offset:16 nt
	global_load_dwordx4 v[8:11], v80, s[24:25] offset:2048 nt
	global_load_dwordx4 v[12:15], v80, s[24:25] offset:2064 nt
	global_load_dwordx4 v[16:19], v80, s[26:27] offset:0 nt
	global_load_dwordx4 v[20:23], v80, s[26:27] offset:16 nt
	global_load_dwordx4 v[24:27], v80, s[26:27] offset:2048 nt
	global_load_dwordx4 v[28:31], v80, s[26:27] offset:2064 nt
	global_load_dwordx4 v[32:35], v80, s[28:29] offset:0 nt
	global_load_dwordx4 v[36:39], v80, s[28:29] offset:16 nt
	global_load_dwordx4 v[40:43], v80, s[28:29] offset:2048 nt
	global_load_dwordx4 v[44:47], v80, s[28:29] offset:2064 nt
	global_load_dwordx4 v[48:51], v80, s[30:31] offset:0 nt
	global_load_dwordx4 v[52:55], v80, s[30:31] offset:16 nt
	global_load_dwordx4 v[56:59], v80, s[30:31] offset:2048 nt
	global_load_dwordx4 v[60:63], v80, s[30:31] offset:2064 nt
	s_waitcnt vmcnt(40)
	v_pk_mul_f32 v[240:241], v[96:97], v[96:97]
	v_pk_mul_f32 v[242:243], v[112:113], v[112:113]
	v_pk_mul_f32 v[244:245], v[128:129], v[128:129]
	v_pk_mul_f32 v[246:247], v[144:145], v[144:145]
	v_pk_fma_f32 v[240:241], v[98:99], v[98:99], v[240:241]
	v_pk_fma_f32 v[242:243], v[114:115], v[114:115], v[242:243]
	v_pk_fma_f32 v[244:245], v[130:131], v[130:131], v[244:245]
	v_pk_fma_f32 v[246:247], v[146:147], v[146:147], v[246:247]
	v_pk_fma_f32 v[240:241], v[100:101], v[100:101], v[240:241]
	v_pk_fma_f32 v[242:243], v[116:117], v[116:117], v[242:243]
	v_pk_fma_f32 v[244:245], v[132:133], v[132:133], v[244:245]
	v_pk_fma_f32 v[246:247], v[148:149], v[148:149], v[246:247]
	v_pk_fma_f32 v[240:241], v[102:103], v[102:103], v[240:241]
	v_pk_fma_f32 v[242:243], v[118:119], v[118:119], v[242:243]
	v_pk_fma_f32 v[244:245], v[134:135], v[134:135], v[244:245]
	v_pk_fma_f32 v[246:247], v[150:151], v[150:151], v[246:247]
	v_pk_fma_f32 v[240:241], v[104:105], v[104:105], v[240:241]
	v_pk_fma_f32 v[242:243], v[120:121], v[120:121], v[242:243]
	v_pk_fma_f32 v[244:245], v[136:137], v[136:137], v[244:245]
	v_pk_fma_f32 v[246:247], v[152:153], v[152:153], v[246:247]
	v_pk_fma_f32 v[240:241], v[106:107], v[106:107], v[240:241]
	v_pk_fma_f32 v[242:243], v[122:123], v[122:123], v[242:243]
	v_pk_fma_f32 v[244:245], v[138:139], v[138:139], v[244:245]
	v_pk_fma_f32 v[246:247], v[154:155], v[154:155], v[246:247]
	v_pk_fma_f32 v[240:241], v[108:109], v[108:109], v[240:241]
	v_pk_fma_f32 v[242:243], v[124:125], v[124:125], v[242:243]
	v_pk_fma_f32 v[244:245], v[140:141], v[140:141], v[244:245]
	v_pk_fma_f32 v[246:247], v[156:157], v[156:157], v[246:247]
	v_pk_fma_f32 v[240:241], v[110:111], v[110:111], v[240:241]
	v_pk_fma_f32 v[242:243], v[126:127], v[126:127], v[242:243]
	v_pk_fma_f32 v[244:245], v[142:143], v[142:143], v[244:245]
	v_pk_fma_f32 v[246:247], v[158:159], v[158:159], v[246:247]
	v_add_f32_e32 v224, v240, v241
	v_add_f32_e32 v225, v242, v243
	v_add_f32_e32 v226, v244, v245
	v_add_f32_e32 v227, v246, v247
	ds_bpermute_b32 v228, v83, v224
	ds_bpermute_b32 v229, v83, v225
	ds_bpermute_b32 v230, v83, v226
	ds_bpermute_b32 v231, v83, v227
	s_waitcnt lgkmcnt(0)
; template <bool BF> __device__ __forceinline__ void prep_rows(const float* xp, const float* xs, const bf16* hb, const float* g, const float* MOD, int shoff, int scoff, bf16* U, int gw, int NGW, int lane) {
;     ...
; #pragma unroll
;         for (int o = 1; o < 64; o <<= 1) {
; #pragma unroll
;             for (int r = 0; r < R; ++r) s[r] += __shfl_xor(s[r], o); }
; #pragma unroll
;         for (int r = 0; r < R; ++r) { const int m = mb + r * NGW; if (m < MT) {
;             const float rstd = 1.0f / sqrtf(s[r] * (1.0f / DM) + RMS_EPS);
	v_add_f32_e32 v224, v224, v228
	v_add_f32_e32 v225, v225, v229
	v_add_f32_e32 v226, v226, v230
	v_add_f32_e32 v227, v227, v231
	ds_bpermute_b32 v228, v84, v224
	ds_bpermute_b32 v229, v84, v225
	ds_bpermute_b32 v230, v84, v226
	ds_bpermute_b32 v231, v84, v227
	s_waitcnt lgkmcnt(0)
	v_add_f32_e32 v224, v224, v228
	v_add_f32_e32 v225, v225, v229
	v_add_f32_e32 v226, v226, v230
	v_add_f32_e32 v227, v227, v231
	ds_bpermute_b32 v228, v85, v224
	ds_bpermute_b32 v229, v85, v225
	ds_bpermute_b32 v230, v85, v226
	ds_bpermute_b32 v231, v85, v227
	s_waitcnt lgkmcnt(0)
	v_add_f32_e32 v224, v224, v228
	v_add_f32_e32 v225, v225, v229
	v_add_f32_e32 v226, v226, v230
	v_add_f32_e32 v227, v227, v231
	ds_bpermute_b32 v228, v86, v224
	ds_bpermute_b32 v229, v86, v225
	ds_bpermute_b32 v230, v86, v226
	ds_bpermute_b32 v231, v86, v227
	s_waitcnt lgkmcnt(0)
	v_add_f32_e32 v224, v224, v228
	v_add_f32_e32 v225, v225, v229
	v_add_f32_e32 v226, v226, v230
	v_add_f32_e32 v227, v227, v231
	ds_bpermute_b32 v228, v87, v224
	ds_bpermute_b32 v229, v87, v225
	ds_bpermute_b32 v230, v87, v226
	ds_bpermute_b32 v231, v87, v227
	s_waitcnt lgkmcnt(0)
	v_add_f32_e32 v224, v224, v228
	v_add_f32_e32 v225, v225, v229
	v_add_f32_e32 v226, v226, v230
	v_add_f32_e32 v227, v227, v231
	ds_bpermute_b32 v228, v88, v224
	ds_bpermute_b32 v229, v88, v225
	ds_bpermute_b32 v230, v88, v226
	ds_bpermute_b32 v231, v88, v227
	s_waitcnt lgkmcnt(0)
	v_add_f32_e32 v224, v224, v228
	v_add_f32_e32 v225, v225, v229
	v_add_f32_e32 v226, v226, v230
	v_add_f32_e32 v227, v227, v231
	v_fmamk_f32 v240, v224, 0x3a800000, v89
	v_mul_f32_e32 v241, 0x4f800000, v240
	v_cmp_gt_f32_e32 vcc, s54, v240
	s_nop 1
	v_cndmask_b32_e32 v247, v240, v241, vcc
	v_sqrt_f32_e32 v242, v247
	s_nop 1
	v_add_u32_e32 v243, -1, v242
	v_add_u32_e32 v244, 1, v242
	v_fma_f32 v245, -v243, v242, v247
	v_fma_f32 v246, -v244, v242, v247
	v_cmp_ge_f32_e64 s[52:53], 0, v245
	s_nop 1
	v_cndmask_b32_e64 v242, v242, v243, s[52:53]
	v_cmp_lt_f32_e64 s[52:53], 0, v246
	s_nop 1
	v_cndmask_b32_e64 v242, v242, v244, s[52:53]
	v_mul_f32_e32 v243, 0x37800000, v242
	v_cndmask_b32_e32 v242, v242, v243, vcc
	v_cmp_class_f32_e32 vcc, v247, v90
	s_nop 1
	v_cndmask_b32_e32 v247, v242, v247, vcc
	v_div_scale_f32 v248, s[52:53], v247, v247, 1.0
	v_rcp_f32_e32 v249, v248
	v_div_scale_f32 v228, vcc, 1.0, v247, 1.0
	s_nop 0
	v_fma_f32 v229, -v248, v249, 1.0
	v_fmac_f32_e32 v249, v229, v249
	v_mul_f32_e32 v230, v228, v249
	v_fma_f32 v229, -v248, v230, v228
	v_fmac_f32_e32 v230, v229, v249
	v_fma_f32 v248, -v248, v230, v228
	v_div_fmas_f32 v248, v248, v249, v230
	v_div_fixup_f32 v232, v248, v247, 1.0
	v_fmamk_f32 v240, v225, 0x3a800000, v89
	v_mul_f32_e32 v241, 0x4f800000, v240
	v_cmp_gt_f32_e32 vcc, s54, v240
	s_nop 1
	v_cndmask_b32_e32 v247, v240, v241, vcc
	v_sqrt_f32_e32 v242, v247
	s_nop 1
	v_add_u32_e32 v243, -1, v242
	v_add_u32_e32 v244, 1, v242
	v_fma_f32 v245, -v243, v242, v247
	v_fma_f32 v246, -v244, v242, v247
	v_cmp_ge_f32_e64 s[52:53], 0, v245
	s_nop 1
	v_cndmask_b32_e64 v242, v242, v243, s[52:53]
	v_cmp_lt_f32_e64 s[52:53], 0, v246
	s_nop 1
	v_cndmask_b32_e64 v242, v242, v244, s[52:53]
	v_mul_f32_e32 v243, 0x37800000, v242
	v_cndmask_b32_e32 v242, v242, v243, vcc
	v_cmp_class_f32_e32 vcc, v247, v90
	s_nop 1
	v_cndmask_b32_e32 v247, v242, v247, vcc
	v_div_scale_f32 v248, s[52:53], v247, v247, 1.0
	v_rcp_f32_e32 v249, v248
	v_div_scale_f32 v228, vcc, 1.0, v247, 1.0
	s_nop 0
	v_fma_f32 v229, -v248, v249, 1.0
	v_fmac_f32_e32 v249, v229, v249
	v_mul_f32_e32 v230, v228, v249
	v_fma_f32 v229, -v248, v230, v228
	v_fmac_f32_e32 v230, v229, v249
	v_fma_f32 v248, -v248, v230, v228
	v_div_fmas_f32 v248, v248, v249, v230
	v_div_fixup_f32 v234, v248, v247, 1.0
	v_fmamk_f32 v240, v226, 0x3a800000, v89
	v_mul_f32_e32 v241, 0x4f800000, v240
	v_cmp_gt_f32_e32 vcc, s54, v240
	s_nop 1
	v_cndmask_b32_e32 v247, v240, v241, vcc
	v_sqrt_f32_e32 v242, v247
	s_nop 1
	v_add_u32_e32 v243, -1, v242
	v_add_u32_e32 v244, 1, v242
	v_fma_f32 v245, -v243, v242, v247
	v_fma_f32 v246, -v244, v242, v247
	v_cmp_ge_f32_e64 s[52:53], 0, v245
	s_nop 1
	v_cndmask_b32_e64 v242, v242, v243, s[52:53]
	v_cmp_lt_f32_e64 s[52:53], 0, v246
	s_nop 1
	v_cndmask_b32_e64 v242, v242, v244, s[52:53]
	v_mul_f32_e32 v243, 0x37800000, v242
	v_cndmask_b32_e32 v242, v242, v243, vcc
	v_cmp_class_f32_e32 vcc, v247, v90
	s_nop 1
	v_cndmask_b32_e32 v247, v242, v247, vcc
	v_div_scale_f32 v248, s[52:53], v247, v247, 1.0
	v_rcp_f32_e32 v249, v248
	v_div_scale_f32 v228, vcc, 1.0, v247, 1.0
	s_nop 0
	v_fma_f32 v229, -v248, v249, 1.0
	v_fmac_f32_e32 v249, v229, v249
	v_mul_f32_e32 v230, v228, v249
	v_fma_f32 v229, -v248, v230, v228
	v_fmac_f32_e32 v230, v229, v249
	v_fma_f32 v248, -v248, v230, v228
	v_div_fmas_f32 v248, v248, v249, v230
	v_div_fixup_f32 v236, v248, v247, 1.0
	v_fmamk_f32 v240, v227, 0x3a800000, v89
	v_mul_f32_e32 v241, 0x4f800000, v240
	v_cmp_gt_f32_e32 vcc, s54, v240
	s_nop 1
	v_cndmask_b32_e32 v247, v240, v241, vcc
	v_sqrt_f32_e32 v242, v247
	s_nop 1
	v_add_u32_e32 v243, -1, v242
	v_add_u32_e32 v244, 1, v242
	v_fma_f32 v245, -v243, v242, v247
	v_fma_f32 v246, -v244, v242, v247
	v_cmp_ge_f32_e64 s[52:53], 0, v245
	s_nop 1
	v_cndmask_b32_e64 v242, v242, v243, s[52:53]
	v_cmp_lt_f32_e64 s[52:53], 0, v246
	s_nop 1
	v_cndmask_b32_e64 v242, v242, v244, s[52:53]
	v_mul_f32_e32 v243, 0x37800000, v242
	v_cndmask_b32_e32 v242, v242, v243, vcc
	v_cmp_class_f32_e32 vcc, v247, v90
	s_nop 1
	v_cndmask_b32_e32 v247, v242, v247, vcc
	v_div_scale_f32 v248, s[52:53], v247, v247, 1.0
	v_rcp_f32_e32 v249, v248
	v_div_scale_f32 v228, vcc, 1.0, v247, 1.0
	s_nop 0
	v_fma_f32 v229, -v248, v249, 1.0
	v_fmac_f32_e32 v249, v229, v249
	v_mul_f32_e32 v230, v228, v249
	v_fma_f32 v229, -v248, v230, v228
	v_fmac_f32_e32 v230, v229, v249
	v_fma_f32 v248, -v248, v230, v228
	v_div_fmas_f32 v248, v248, v249, v230
	v_div_fixup_f32 v238, v248, v247, 1.0
	s_waitcnt vmcnt(16)
; __device__ __forceinline__ unsigned pk2(float lo, float hi) { return pg8::cvt_pk_bf16(lo, hi); }
; template <bool BF> __device__ __forceinline__ void prep_rows(const float* xp, const float* xs, const bf16* hb, const float* g, const float* MOD, int shoff, int scoff, bf16* U, int gw, int NGW, int lane) {
;     ...
;         for (int r = 0; r < R; ++r) { const int m = mb + r * NGW; if (m < MT) {
;             const float rstd = 1.0f / sqrtf(s[r] * (1.0f / DM) + RMS_EPS);
;             const float* mr = MOD + (size_t)(m < MP ? (m >> 13) : 8 + ((m - MP) >> 12)) * 6144;
; #pragma unroll
;             for (int j = 0; j < 4; ++j) { const int c = 4 * lane + 256 * j;
;                 const f32x4 gg = *(const f32x4*)(g + c), sc = *(const f32x4*)(mr + scoff + c), sh = *(const f32x4*)(mr + shoff + c);
;                 const f32x4 o = v[r][j] * rstd * gg * (sc + 1.0f) + sh; v2u w; w.x = pk2(o.x, o.y); w.y = pk2(o.z, o.w); *(v2u*)(U + (size_t)m * DM + c) = w; } } }
	v_pk_add_f32 v[160:161], v[160:161], 1.0 op_sel_hi:[1,0]
	v_pk_add_f32 v[162:163], v[162:163], 1.0 op_sel_hi:[1,0]
	v_pk_add_f32 v[164:165], v[164:165], 1.0 op_sel_hi:[1,0]
	v_pk_add_f32 v[166:167], v[166:167], 1.0 op_sel_hi:[1,0]
	v_pk_add_f32 v[168:169], v[168:169], 1.0 op_sel_hi:[1,0]
	v_pk_add_f32 v[170:171], v[170:171], 1.0 op_sel_hi:[1,0]
	v_pk_add_f32 v[172:173], v[172:173], 1.0 op_sel_hi:[1,0]
	v_pk_add_f32 v[174:175], v[174:175], 1.0 op_sel_hi:[1,0]
	v_pk_add_f32 v[192:193], v[192:193], 1.0 op_sel_hi:[1,0]
	v_pk_add_f32 v[194:195], v[194:195], 1.0 op_sel_hi:[1,0]
	v_pk_add_f32 v[196:197], v[196:197], 1.0 op_sel_hi:[1,0]
	v_pk_add_f32 v[198:199], v[198:199], 1.0 op_sel_hi:[1,0]
	v_pk_add_f32 v[200:201], v[200:201], 1.0 op_sel_hi:[1,0]
	v_pk_add_f32 v[202:203], v[202:203], 1.0 op_sel_hi:[1,0]
	v_pk_add_f32 v[204:205], v[204:205], 1.0 op_sel_hi:[1,0]
	v_pk_add_f32 v[206:207], v[206:207], 1.0 op_sel_hi:[1,0]
	s_add_u32 s38, s20, 0x7000000
	s_addc_u32 s39, s21, 0
	s_add_u32 s40, s20, 0x7400000
	s_addc_u32 s41, s21, 0
	s_add_u32 s46, s20, 0x7800000
	s_addc_u32 s47, s21, 0
	s_add_u32 s48, s20, 0x7c00000
	s_addc_u32 s49, s21, 0
	v_pk_mul_f32 v[96:97], v[96:97], v[232:233] op_sel_hi:[1,0]
	v_pk_mul_f32 v[98:99], v[98:99], v[232:233] op_sel_hi:[1,0]
	v_pk_mul_f32 v[96:97], v[64:65], v[96:97]
	v_pk_mul_f32 v[98:99], v[66:67], v[98:99]
	v_pk_fma_f32 v[96:97], v[160:161], v[96:97], v[176:177]
	v_pk_fma_f32 v[98:99], v[162:163], v[98:99], v[178:179]
	v_cvt_pk_bf16_f32 v244, v96, v97
	v_cvt_pk_bf16_f32 v245, v98, v99
	v_pk_mul_f32 v[100:101], v[100:101], v[232:233] op_sel_hi:[1,0]
	v_pk_mul_f32 v[102:103], v[102:103], v[232:233] op_sel_hi:[1,0]
	v_pk_mul_f32 v[100:101], v[68:69], v[100:101]
	v_pk_mul_f32 v[102:103], v[70:71], v[102:103]
	v_pk_fma_f32 v[100:101], v[164:165], v[100:101], v[180:181]
	v_pk_fma_f32 v[102:103], v[166:167], v[102:103], v[182:183]
	v_cvt_pk_bf16_f32 v246, v100, v101
	v_cvt_pk_bf16_f32 v247, v102, v103
	global_store_dwordx4 v82, v[244:247], s[38:39] offset:0
	v_pk_mul_f32 v[104:105], v[104:105], v[232:233] op_sel_hi:[1,0]
	v_pk_mul_f32 v[106:107], v[106:107], v[232:233] op_sel_hi:[1,0]
	v_pk_mul_f32 v[104:105], v[72:73], v[104:105]
	v_pk_mul_f32 v[106:107], v[74:75], v[106:107]
	v_pk_fma_f32 v[104:105], v[168:169], v[104:105], v[184:185]
	v_pk_fma_f32 v[106:107], v[170:171], v[106:107], v[186:187]
	v_cvt_pk_bf16_f32 v240, v104, v105
	v_cvt_pk_bf16_f32 v241, v106, v107
	v_pk_mul_f32 v[108:109], v[108:109], v[232:233] op_sel_hi:[1,0]
	v_pk_mul_f32 v[110:111], v[110:111], v[232:233] op_sel_hi:[1,0]
	v_pk_mul_f32 v[108:109], v[76:77], v[108:109]
	v_pk_mul_f32 v[110:111], v[78:79], v[110:111]
	v_pk_fma_f32 v[108:109], v[172:173], v[108:109], v[188:189]
	v_pk_fma_f32 v[110:111], v[174:175], v[110:111], v[190:191]
	v_cvt_pk_bf16_f32 v242, v108, v109
	v_cvt_pk_bf16_f32 v243, v110, v111
	global_store_dwordx4 v82, v[240:243], s[38:39] offset:1024
	v_pk_mul_f32 v[112:113], v[112:113], v[234:235] op_sel_hi:[1,0]
	v_pk_mul_f32 v[114:115], v[114:115], v[234:235] op_sel_hi:[1,0]
	v_pk_mul_f32 v[112:113], v[64:65], v[112:113]
	v_pk_mul_f32 v[114:115], v[66:67], v[114:115]
	v_pk_fma_f32 v[112:113], v[160:161], v[112:113], v[176:177]
	v_pk_fma_f32 v[114:115], v[162:163], v[114:115], v[178:179]
	v_cvt_pk_bf16_f32 v244, v112, v113
	v_cvt_pk_bf16_f32 v245, v114, v115
	v_pk_mul_f32 v[116:117], v[116:117], v[234:235] op_sel_hi:[1,0]
	v_pk_mul_f32 v[118:119], v[118:119], v[234:235] op_sel_hi:[1,0]
	v_pk_mul_f32 v[116:117], v[68:69], v[116:117]
	v_pk_mul_f32 v[118:119], v[70:71], v[118:119]
	v_pk_fma_f32 v[116:117], v[164:165], v[116:117], v[180:181]
	v_pk_fma_f32 v[118:119], v[166:167], v[118:119], v[182:183]
	v_cvt_pk_bf16_f32 v246, v116, v117
	v_cvt_pk_bf16_f32 v247, v118, v119
	global_store_dwordx4 v82, v[244:247], s[40:41] offset:0
	v_pk_mul_f32 v[120:121], v[120:121], v[234:235] op_sel_hi:[1,0]
	v_pk_mul_f32 v[122:123], v[122:123], v[234:235] op_sel_hi:[1,0]
	v_pk_mul_f32 v[120:121], v[72:73], v[120:121]
	v_pk_mul_f32 v[122:123], v[74:75], v[122:123]
	v_pk_fma_f32 v[120:121], v[168:169], v[120:121], v[184:185]
	v_pk_fma_f32 v[122:123], v[170:171], v[122:123], v[186:187]
	v_cvt_pk_bf16_f32 v240, v120, v121
	v_cvt_pk_bf16_f32 v241, v122, v123
	v_pk_mul_f32 v[124:125], v[124:125], v[234:235] op_sel_hi:[1,0]
	v_pk_mul_f32 v[126:127], v[126:127], v[234:235] op_sel_hi:[1,0]
	v_pk_mul_f32 v[124:125], v[76:77], v[124:125]
	v_pk_mul_f32 v[126:127], v[78:79], v[126:127]
	v_pk_fma_f32 v[124:125], v[172:173], v[124:125], v[188:189]
	v_pk_fma_f32 v[126:127], v[174:175], v[126:127], v[190:191]
	v_cvt_pk_bf16_f32 v242, v124, v125
	v_cvt_pk_bf16_f32 v243, v126, v127
	global_store_dwordx4 v82, v[240:243], s[40:41] offset:1024
	v_pk_mul_f32 v[128:129], v[128:129], v[236:237] op_sel_hi:[1,0]
	v_pk_mul_f32 v[130:131], v[130:131], v[236:237] op_sel_hi:[1,0]
	v_pk_mul_f32 v[128:129], v[64:65], v[128:129]
	v_pk_mul_f32 v[130:131], v[66:67], v[130:131]
	v_pk_fma_f32 v[128:129], v[192:193], v[128:129], v[208:209]
	v_pk_fma_f32 v[130:131], v[194:195], v[130:131], v[210:211]
	v_cvt_pk_bf16_f32 v244, v128, v129
	v_cvt_pk_bf16_f32 v245, v130, v131
	v_pk_mul_f32 v[132:133], v[132:133], v[236:237] op_sel_hi:[1,0]
	v_pk_mul_f32 v[134:135], v[134:135], v[236:237] op_sel_hi:[1,0]
	v_pk_mul_f32 v[132:133], v[68:69], v[132:133]
	v_pk_mul_f32 v[134:135], v[70:71], v[134:135]
	v_pk_fma_f32 v[132:133], v[196:197], v[132:133], v[212:213]
	v_pk_fma_f32 v[134:135], v[198:199], v[134:135], v[214:215]
	v_cvt_pk_bf16_f32 v246, v132, v133
	v_cvt_pk_bf16_f32 v247, v134, v135
	global_store_dwordx4 v82, v[244:247], s[46:47] offset:0
	v_pk_mul_f32 v[136:137], v[136:137], v[236:237] op_sel_hi:[1,0]
; __device__ __forceinline__ float bf_lo(unsigned w) { return __uint_as_float(w << 16); }
; __device__ __forceinline__ float bf_hi(unsigned w) { return __uint_as_float(w & 0xffff0000u); }
; template <bool BF> __device__ __forceinline__ void prep_rows(const float* xp, const float* xs, const bf16* hb, const float* g, const float* MOD, int shoff, int scoff, bf16* U, int gw, int NGW, int lane) {
;     ...
;         for (int r = 0; r < R; ++r) { const int m = mb + r * NGW; const int mc = m < MT ? m : mb;
; #pragma unroll
;             for (int j = 0; j < 4; ++j) {
;                 if (BF) { const v2u a0 = *(const v2u*)(hb + (size_t)mc * DM + 4 * lane + 256 * j);
;                     v[r][j].x = pg8::bf_lo(a0.x); v[r][j].y = pg8::bf_hi(a0.x); v[r][j].z = pg8::bf_lo(a0.y); v[r][j].w = pg8::bf_hi(a0.y); }
;                 else { const float* xr = mc < MP ? xp + (size_t)mc * DM : xs + (size_t)(mc - MP) * DM; v[r][j] = *(const f32x4*)(xr + 4 * lane + 256 * j); } } }
;     ...
;             const float* mr = MOD + (size_t)(m < MP ? (m >> 13) : 8 + ((m - MP) >> 12)) * 6144;
;     ...
;                 const f32x4 gg = *(const f32x4*)(g + c), sc = *(const f32x4*)(mr + scoff + c), sh = *(const f32x4*)(mr + shoff + c);
	v_pk_mul_f32 v[138:139], v[138:139], v[236:237] op_sel_hi:[1,0]
	v_pk_mul_f32 v[136:137], v[72:73], v[136:137]
	v_pk_mul_f32 v[138:139], v[74:75], v[138:139]
	v_pk_fma_f32 v[136:137], v[200:201], v[136:137], v[216:217]
	v_pk_fma_f32 v[138:139], v[202:203], v[138:139], v[218:219]
	v_cvt_pk_bf16_f32 v240, v136, v137
	v_cvt_pk_bf16_f32 v241, v138, v139
	v_pk_mul_f32 v[140:141], v[140:141], v[236:237] op_sel_hi:[1,0]
	v_pk_mul_f32 v[142:143], v[142:143], v[236:237] op_sel_hi:[1,0]
	v_pk_mul_f32 v[140:141], v[76:77], v[140:141]
	v_pk_mul_f32 v[142:143], v[78:79], v[142:143]
	v_pk_fma_f32 v[140:141], v[204:205], v[140:141], v[220:221]
	v_pk_fma_f32 v[142:143], v[206:207], v[142:143], v[222:223]
	v_cvt_pk_bf16_f32 v242, v140, v141
	v_cvt_pk_bf16_f32 v243, v142, v143
	global_store_dwordx4 v82, v[240:243], s[46:47] offset:1024
	v_pk_mul_f32 v[144:145], v[144:145], v[238:239] op_sel_hi:[1,0]
	v_pk_mul_f32 v[146:147], v[146:147], v[238:239] op_sel_hi:[1,0]
	v_pk_mul_f32 v[144:145], v[64:65], v[144:145]
	v_pk_mul_f32 v[146:147], v[66:67], v[146:147]
	v_pk_fma_f32 v[144:145], v[192:193], v[144:145], v[208:209]
	v_pk_fma_f32 v[146:147], v[194:195], v[146:147], v[210:211]
	v_cvt_pk_bf16_f32 v244, v144, v145
	v_cvt_pk_bf16_f32 v245, v146, v147
	v_pk_mul_f32 v[148:149], v[148:149], v[238:239] op_sel_hi:[1,0]
	v_pk_mul_f32 v[150:151], v[150:151], v[238:239] op_sel_hi:[1,0]
	v_pk_mul_f32 v[148:149], v[68:69], v[148:149]
	v_pk_mul_f32 v[150:151], v[70:71], v[150:151]
	v_pk_fma_f32 v[148:149], v[196:197], v[148:149], v[212:213]
	v_pk_fma_f32 v[150:151], v[198:199], v[150:151], v[214:215]
	v_cvt_pk_bf16_f32 v246, v148, v149
	v_cvt_pk_bf16_f32 v247, v150, v151
	global_store_dwordx4 v82, v[244:247], s[48:49] offset:0
	v_pk_mul_f32 v[152:153], v[152:153], v[238:239] op_sel_hi:[1,0]
	v_pk_mul_f32 v[154:155], v[154:155], v[238:239] op_sel_hi:[1,0]
	v_pk_mul_f32 v[152:153], v[72:73], v[152:153]
	v_pk_mul_f32 v[154:155], v[74:75], v[154:155]
	v_pk_fma_f32 v[152:153], v[200:201], v[152:153], v[216:217]
	v_pk_fma_f32 v[154:155], v[202:203], v[154:155], v[218:219]
	v_cvt_pk_bf16_f32 v240, v152, v153
	v_cvt_pk_bf16_f32 v241, v154, v155
	v_pk_mul_f32 v[156:157], v[156:157], v[238:239] op_sel_hi:[1,0]
	v_pk_mul_f32 v[158:159], v[158:159], v[238:239] op_sel_hi:[1,0]
	v_pk_mul_f32 v[156:157], v[76:77], v[156:157]
	v_pk_mul_f32 v[158:159], v[78:79], v[158:159]
	v_pk_fma_f32 v[156:157], v[204:205], v[156:157], v[220:221]
	v_pk_fma_f32 v[158:159], v[206:207], v[158:159], v[222:223]
	v_cvt_pk_bf16_f32 v242, v156, v157
	v_cvt_pk_bf16_f32 v243, v158, v159
	global_store_dwordx4 v82, v[240:243], s[48:49] offset:1024
	s_add_u32 s34, s8, 0x30000
	s_addc_u32 s35, s9, 0
	s_add_u32 s36, s8, 0x36000
	s_addc_u32 s37, s9, 0
	global_load_dwordx4 v[176:179], v80, s[34:35] offset:0
	global_load_dwordx4 v[180:183], v80, s[34:35] offset:16
	global_load_dwordx4 v[184:187], v80, s[34:35] offset:2048
	global_load_dwordx4 v[188:191], v80, s[34:35] offset:2064
	global_load_dwordx4 v[160:163], v81, s[34:35] offset:0
	global_load_dwordx4 v[164:167], v81, s[34:35] offset:16
	global_load_dwordx4 v[168:171], v81, s[34:35] offset:2048
	global_load_dwordx4 v[172:175], v81, s[34:35] offset:2064
	global_load_dwordx4 v[208:211], v80, s[36:37] offset:0
	global_load_dwordx4 v[212:215], v80, s[36:37] offset:16
	global_load_dwordx4 v[216:219], v80, s[36:37] offset:2048
	global_load_dwordx4 v[220:223], v80, s[36:37] offset:2064
	global_load_dwordx4 v[192:195], v81, s[36:37] offset:0
	global_load_dwordx4 v[196:199], v81, s[36:37] offset:16
	global_load_dwordx4 v[200:203], v81, s[36:37] offset:2048
	global_load_dwordx4 v[204:207], v81, s[36:37] offset:2064
	s_add_u32 s24, s18, 0x2000000
	s_addc_u32 s25, s19, 0
	s_add_u32 s26, s18, 0x2800000
	s_addc_u32 s27, s19, 0
	s_add_u32 s28, s18, 0x3000000
	s_addc_u32 s29, s19, 0
	s_add_u32 s30, s18, 0x3800000
	s_addc_u32 s31, s19, 0
	global_load_dwordx4 v[96:99], v80, s[24:25] offset:0 nt
	global_load_dwordx4 v[100:103], v80, s[24:25] offset:16 nt
	global_load_dwordx4 v[104:107], v80, s[24:25] offset:2048 nt
	global_load_dwordx4 v[108:111], v80, s[24:25] offset:2064 nt
	global_load_dwordx4 v[112:115], v80, s[26:27] offset:0 nt
	global_load_dwordx4 v[116:119], v80, s[26:27] offset:16 nt
	global_load_dwordx4 v[120:123], v80, s[26:27] offset:2048 nt
	global_load_dwordx4 v[124:127], v80, s[26:27] offset:2064 nt
	global_load_dwordx4 v[128:131], v80, s[28:29] offset:0 nt
	global_load_dwordx4 v[132:135], v80, s[28:29] offset:16 nt
	global_load_dwordx4 v[136:139], v80, s[28:29] offset:2048 nt
	global_load_dwordx4 v[140:143], v80, s[28:29] offset:2064 nt
	global_load_dwordx4 v[144:147], v80, s[30:31] offset:0 nt
	global_load_dwordx4 v[148:151], v80, s[30:31] offset:16 nt
	global_load_dwordx4 v[152:155], v80, s[30:31] offset:2048 nt
	global_load_dwordx4 v[156:159], v80, s[30:31] offset:2064 nt
	s_waitcnt vmcnt(40)
; template <bool BF> __device__ __forceinline__ void prep_rows(const float* xp, const float* xs, const bf16* hb, const float* g, const float* MOD, int shoff, int scoff, bf16* U, int gw, int NGW, int lane) {
;     ...
;         for (int r = 0; r < R; ++r) { float t = 0.f;
; #pragma unroll
;             for (int j = 0; j < 4; ++j) t += (v[r][j].x * v[r][j].x + v[r][j].y * v[r][j].y) + (v[r][j].z * v[r][j].z + v[r][j].w * v[r][j].w);
;             s[r] = t; }
; #pragma unroll
;         for (int o = 1; o < 64; o <<= 1) {
; #pragma unroll
;             for (int r = 0; r < R; ++r) s[r] += __shfl_xor(s[r], o); }
; #pragma unroll
;         for (int r = 0; r < R; ++r) { const int m = mb + r * NGW; if (m < MT) {
;             const float rstd = 1.0f / sqrtf(s[r] * (1.0f / DM) + RMS_EPS);
	v_pk_mul_f32 v[240:241], v[0:1], v[0:1]
	v_pk_mul_f32 v[242:243], v[16:17], v[16:17]
	v_pk_mul_f32 v[244:245], v[32:33], v[32:33]
	v_pk_mul_f32 v[246:247], v[48:49], v[48:49]
	v_pk_fma_f32 v[240:241], v[2:3], v[2:3], v[240:241]
	v_pk_fma_f32 v[242:243], v[18:19], v[18:19], v[242:243]
	v_pk_fma_f32 v[244:245], v[34:35], v[34:35], v[244:245]
	v_pk_fma_f32 v[246:247], v[50:51], v[50:51], v[246:247]
	v_pk_fma_f32 v[240:241], v[4:5], v[4:5], v[240:241]
	v_pk_fma_f32 v[242:243], v[20:21], v[20:21], v[242:243]
	v_pk_fma_f32 v[244:245], v[36:37], v[36:37], v[244:245]
	v_pk_fma_f32 v[246:247], v[52:53], v[52:53], v[246:247]
	v_pk_fma_f32 v[240:241], v[6:7], v[6:7], v[240:241]
	v_pk_fma_f32 v[242:243], v[22:23], v[22:23], v[242:243]
	v_pk_fma_f32 v[244:245], v[38:39], v[38:39], v[244:245]
	v_pk_fma_f32 v[246:247], v[54:55], v[54:55], v[246:247]
	v_pk_fma_f32 v[240:241], v[8:9], v[8:9], v[240:241]
	v_pk_fma_f32 v[242:243], v[24:25], v[24:25], v[242:243]
	v_pk_fma_f32 v[244:245], v[40:41], v[40:41], v[244:245]
	v_pk_fma_f32 v[246:247], v[56:57], v[56:57], v[246:247]
	v_pk_fma_f32 v[240:241], v[10:11], v[10:11], v[240:241]
	v_pk_fma_f32 v[242:243], v[26:27], v[26:27], v[242:243]
	v_pk_fma_f32 v[244:245], v[42:43], v[42:43], v[244:245]
	v_pk_fma_f32 v[246:247], v[58:59], v[58:59], v[246:247]
	v_pk_fma_f32 v[240:241], v[12:13], v[12:13], v[240:241]
	v_pk_fma_f32 v[242:243], v[28:29], v[28:29], v[242:243]
	v_pk_fma_f32 v[244:245], v[44:45], v[44:45], v[244:245]
	v_pk_fma_f32 v[246:247], v[60:61], v[60:61], v[246:247]
	v_pk_fma_f32 v[240:241], v[14:15], v[14:15], v[240:241]
	v_pk_fma_f32 v[242:243], v[30:31], v[30:31], v[242:243]
	v_pk_fma_f32 v[244:245], v[46:47], v[46:47], v[244:245]
	v_pk_fma_f32 v[246:247], v[62:63], v[62:63], v[246:247]
	v_add_f32_e32 v224, v240, v241
	v_add_f32_e32 v225, v242, v243
	v_add_f32_e32 v226, v244, v245
	v_add_f32_e32 v227, v246, v247
	ds_bpermute_b32 v228, v83, v224
	ds_bpermute_b32 v229, v83, v225
	ds_bpermute_b32 v230, v83, v226
	ds_bpermute_b32 v231, v83, v227
	s_waitcnt lgkmcnt(0)
	v_add_f32_e32 v224, v224, v228
	v_add_f32_e32 v225, v225, v229
	v_add_f32_e32 v226, v226, v230
	v_add_f32_e32 v227, v227, v231
	ds_bpermute_b32 v228, v84, v224
	ds_bpermute_b32 v229, v84, v225
	ds_bpermute_b32 v230, v84, v226
	ds_bpermute_b32 v231, v84, v227
	s_waitcnt lgkmcnt(0)
	v_add_f32_e32 v224, v224, v228
	v_add_f32_e32 v225, v225, v229
	v_add_f32_e32 v226, v226, v230
	v_add_f32_e32 v227, v227, v231
	ds_bpermute_b32 v228, v85, v224
	ds_bpermute_b32 v229, v85, v225
	ds_bpermute_b32 v230, v85, v226
	ds_bpermute_b32 v231, v85, v227
	s_waitcnt lgkmcnt(0)
	v_add_f32_e32 v224, v224, v228
	v_add_f32_e32 v225, v225, v229
	v_add_f32_e32 v226, v226, v230
	v_add_f32_e32 v227, v227, v231
	ds_bpermute_b32 v228, v86, v224
	ds_bpermute_b32 v229, v86, v225
	ds_bpermute_b32 v230, v86, v226
	ds_bpermute_b32 v231, v86, v227
	s_waitcnt lgkmcnt(0)
	v_add_f32_e32 v224, v224, v228
	v_add_f32_e32 v225, v225, v229
	v_add_f32_e32 v226, v226, v230
	v_add_f32_e32 v227, v227, v231
	ds_bpermute_b32 v228, v87, v224
	ds_bpermute_b32 v229, v87, v225
	ds_bpermute_b32 v230, v87, v226
	ds_bpermute_b32 v231, v87, v227
	s_waitcnt lgkmcnt(0)
	v_add_f32_e32 v224, v224, v228
	v_add_f32_e32 v225, v225, v229
	v_add_f32_e32 v226, v226, v230
	v_add_f32_e32 v227, v227, v231
	ds_bpermute_b32 v228, v88, v224
	ds_bpermute_b32 v229, v88, v225
	ds_bpermute_b32 v230, v88, v226
	ds_bpermute_b32 v231, v88, v227
	s_waitcnt lgkmcnt(0)
	v_add_f32_e32 v224, v224, v228
	v_add_f32_e32 v225, v225, v229
	v_add_f32_e32 v226, v226, v230
	v_add_f32_e32 v227, v227, v231
	v_fmamk_f32 v240, v224, 0x3a800000, v89
	v_mul_f32_e32 v241, 0x4f800000, v240
	v_cmp_gt_f32_e32 vcc, s54, v240
	s_nop 1
	v_cndmask_b32_e32 v247, v240, v241, vcc
	v_sqrt_f32_e32 v242, v247
	s_nop 1
	v_add_u32_e32 v243, -1, v242
	v_add_u32_e32 v244, 1, v242
	v_fma_f32 v245, -v243, v242, v247
	v_fma_f32 v246, -v244, v242, v247
	v_cmp_ge_f32_e64 s[52:53], 0, v245
	s_nop 1
	v_cndmask_b32_e64 v242, v242, v243, s[52:53]
	v_cmp_lt_f32_e64 s[52:53], 0, v246
	s_nop 1
	v_cndmask_b32_e64 v242, v242, v244, s[52:53]
	v_mul_f32_e32 v243, 0x37800000, v242
	v_cndmask_b32_e32 v242, v242, v243, vcc
	v_cmp_class_f32_e32 vcc, v247, v90
	s_nop 1
	v_cndmask_b32_e32 v247, v242, v247, vcc
	v_div_scale_f32 v248, s[52:53], v247, v247, 1.0
	v_rcp_f32_e32 v249, v248
	v_div_scale_f32 v228, vcc, 1.0, v247, 1.0
	s_nop 0
	v_fma_f32 v229, -v248, v249, 1.0
	v_fmac_f32_e32 v249, v229, v249
	v_mul_f32_e32 v230, v228, v249
	v_fma_f32 v229, -v248, v230, v228
	v_fmac_f32_e32 v230, v229, v249
	v_fma_f32 v248, -v248, v230, v228
	v_div_fmas_f32 v248, v248, v249, v230
	v_div_fixup_f32 v232, v248, v247, 1.0
	v_fmamk_f32 v240, v225, 0x3a800000, v89
	v_mul_f32_e32 v241, 0x4f800000, v240
	v_cmp_gt_f32_e32 vcc, s54, v240
	s_nop 1
	v_cndmask_b32_e32 v247, v240, v241, vcc
	v_sqrt_f32_e32 v242, v247
	s_nop 1
	v_add_u32_e32 v243, -1, v242
	v_add_u32_e32 v244, 1, v242
	v_fma_f32 v245, -v243, v242, v247
	v_fma_f32 v246, -v244, v242, v247
	v_cmp_ge_f32_e64 s[52:53], 0, v245
	s_nop 1
	v_cndmask_b32_e64 v242, v242, v243, s[52:53]
	v_cmp_lt_f32_e64 s[52:53], 0, v246
	s_nop 1
	v_cndmask_b32_e64 v242, v242, v244, s[52:53]
	v_mul_f32_e32 v243, 0x37800000, v242
	v_cndmask_b32_e32 v242, v242, v243, vcc
	v_cmp_class_f32_e32 vcc, v247, v90
	s_nop 1
	v_cndmask_b32_e32 v247, v242, v247, vcc
	v_div_scale_f32 v248, s[52:53], v247, v247, 1.0
	v_rcp_f32_e32 v249, v248
	v_div_scale_f32 v228, vcc, 1.0, v247, 1.0
	s_nop 0
	v_fma_f32 v229, -v248, v249, 1.0
	v_fmac_f32_e32 v249, v229, v249
	v_mul_f32_e32 v230, v228, v249
	v_fma_f32 v229, -v248, v230, v228
	v_fmac_f32_e32 v230, v229, v249
; __device__ __forceinline__ unsigned pk2(float lo, float hi) { return pg8::cvt_pk_bf16(lo, hi); }
; template <bool BF> __device__ __forceinline__ void prep_rows(const float* xp, const float* xs, const bf16* hb, const float* g, const float* MOD, int shoff, int scoff, bf16* U, int gw, int NGW, int lane) {
;     ...
;         for (int r = 0; r < R; ++r) { const int m = mb + r * NGW; if (m < MT) {
;             const float rstd = 1.0f / sqrtf(s[r] * (1.0f / DM) + RMS_EPS);
;             const float* mr = MOD + (size_t)(m < MP ? (m >> 13) : 8 + ((m - MP) >> 12)) * 6144;
; #pragma unroll
;             for (int j = 0; j < 4; ++j) { const int c = 4 * lane + 256 * j;
;                 const f32x4 gg = *(const f32x4*)(g + c), sc = *(const f32x4*)(mr + scoff + c), sh = *(const f32x4*)(mr + shoff + c);
;                 const f32x4 o = v[r][j] * rstd * gg * (sc + 1.0f) + sh; v2u w; w.x = pk2(o.x, o.y); w.y = pk2(o.z, o.w); *(v2u*)(U + (size_t)m * DM + c) = w; } } }
	v_fma_f32 v248, -v248, v230, v228
	v_div_fmas_f32 v248, v248, v249, v230
	v_div_fixup_f32 v234, v248, v247, 1.0
	v_fmamk_f32 v240, v226, 0x3a800000, v89
	v_mul_f32_e32 v241, 0x4f800000, v240
	v_cmp_gt_f32_e32 vcc, s54, v240
	s_nop 1
	v_cndmask_b32_e32 v247, v240, v241, vcc
	v_sqrt_f32_e32 v242, v247
	s_nop 1
	v_add_u32_e32 v243, -1, v242
	v_add_u32_e32 v244, 1, v242
	v_fma_f32 v245, -v243, v242, v247
	v_fma_f32 v246, -v244, v242, v247
	v_cmp_ge_f32_e64 s[52:53], 0, v245
	s_nop 1
	v_cndmask_b32_e64 v242, v242, v243, s[52:53]
	v_cmp_lt_f32_e64 s[52:53], 0, v246
	s_nop 1
	v_cndmask_b32_e64 v242, v242, v244, s[52:53]
	v_mul_f32_e32 v243, 0x37800000, v242
	v_cndmask_b32_e32 v242, v242, v243, vcc
	v_cmp_class_f32_e32 vcc, v247, v90
	s_nop 1
	v_cndmask_b32_e32 v247, v242, v247, vcc
	v_div_scale_f32 v248, s[52:53], v247, v247, 1.0
	v_rcp_f32_e32 v249, v248
	v_div_scale_f32 v228, vcc, 1.0, v247, 1.0
	s_nop 0
	v_fma_f32 v229, -v248, v249, 1.0
	v_fmac_f32_e32 v249, v229, v249
	v_mul_f32_e32 v230, v228, v249
	v_fma_f32 v229, -v248, v230, v228
	v_fmac_f32_e32 v230, v229, v249
	v_fma_f32 v248, -v248, v230, v228
	v_div_fmas_f32 v248, v248, v249, v230
	v_div_fixup_f32 v236, v248, v247, 1.0
	v_fmamk_f32 v240, v227, 0x3a800000, v89
	v_mul_f32_e32 v241, 0x4f800000, v240
	v_cmp_gt_f32_e32 vcc, s54, v240
	s_nop 1
	v_cndmask_b32_e32 v247, v240, v241, vcc
	v_sqrt_f32_e32 v242, v247
	s_nop 1
	v_add_u32_e32 v243, -1, v242
	v_add_u32_e32 v244, 1, v242
	v_fma_f32 v245, -v243, v242, v247
	v_fma_f32 v246, -v244, v242, v247
	v_cmp_ge_f32_e64 s[52:53], 0, v245
	s_nop 1
	v_cndmask_b32_e64 v242, v242, v243, s[52:53]
	v_cmp_lt_f32_e64 s[52:53], 0, v246
	s_nop 1
	v_cndmask_b32_e64 v242, v242, v244, s[52:53]
	v_mul_f32_e32 v243, 0x37800000, v242
	v_cndmask_b32_e32 v242, v242, v243, vcc
	v_cmp_class_f32_e32 vcc, v247, v90
	s_nop 1
	v_cndmask_b32_e32 v247, v242, v247, vcc
	v_div_scale_f32 v248, s[52:53], v247, v247, 1.0
	v_rcp_f32_e32 v249, v248
	v_div_scale_f32 v228, vcc, 1.0, v247, 1.0
	s_nop 0
	v_fma_f32 v229, -v248, v249, 1.0
	v_fmac_f32_e32 v249, v229, v249
	v_mul_f32_e32 v230, v228, v249
	v_fma_f32 v229, -v248, v230, v228
	v_fmac_f32_e32 v230, v229, v249
	v_fma_f32 v248, -v248, v230, v228
	v_div_fmas_f32 v248, v248, v249, v230
	v_div_fixup_f32 v238, v248, v247, 1.0
	s_waitcnt vmcnt(16)
	v_pk_add_f32 v[160:161], v[160:161], 1.0 op_sel_hi:[1,0]
	v_pk_add_f32 v[162:163], v[162:163], 1.0 op_sel_hi:[1,0]
	v_pk_add_f32 v[164:165], v[164:165], 1.0 op_sel_hi:[1,0]
	v_pk_add_f32 v[166:167], v[166:167], 1.0 op_sel_hi:[1,0]
	v_pk_add_f32 v[168:169], v[168:169], 1.0 op_sel_hi:[1,0]
	v_pk_add_f32 v[170:171], v[170:171], 1.0 op_sel_hi:[1,0]
	v_pk_add_f32 v[172:173], v[172:173], 1.0 op_sel_hi:[1,0]
	v_pk_add_f32 v[174:175], v[174:175], 1.0 op_sel_hi:[1,0]
	v_pk_add_f32 v[192:193], v[192:193], 1.0 op_sel_hi:[1,0]
	v_pk_add_f32 v[194:195], v[194:195], 1.0 op_sel_hi:[1,0]
	v_pk_add_f32 v[196:197], v[196:197], 1.0 op_sel_hi:[1,0]
	v_pk_add_f32 v[198:199], v[198:199], 1.0 op_sel_hi:[1,0]
	v_pk_add_f32 v[200:201], v[200:201], 1.0 op_sel_hi:[1,0]
	v_pk_add_f32 v[202:203], v[202:203], 1.0 op_sel_hi:[1,0]
	v_pk_add_f32 v[204:205], v[204:205], 1.0 op_sel_hi:[1,0]
	v_pk_add_f32 v[206:207], v[206:207], 1.0 op_sel_hi:[1,0]
	s_add_u32 s38, s20, 0x8000000
	s_addc_u32 s39, s21, 0
	s_add_u32 s40, s20, 0x8400000
	s_addc_u32 s41, s21, 0
	s_add_u32 s46, s20, 0x8800000
	s_addc_u32 s47, s21, 0
	s_add_u32 s48, s20, 0x8c00000
	s_addc_u32 s49, s21, 0
	v_pk_mul_f32 v[0:1], v[0:1], v[232:233] op_sel_hi:[1,0]
	v_pk_mul_f32 v[2:3], v[2:3], v[232:233] op_sel_hi:[1,0]
	v_pk_mul_f32 v[0:1], v[64:65], v[0:1]
	v_pk_mul_f32 v[2:3], v[66:67], v[2:3]
	v_pk_fma_f32 v[0:1], v[160:161], v[0:1], v[176:177]
	v_pk_fma_f32 v[2:3], v[162:163], v[2:3], v[178:179]
	v_cvt_pk_bf16_f32 v244, v0, v1
	v_cvt_pk_bf16_f32 v245, v2, v3
	v_pk_mul_f32 v[4:5], v[4:5], v[232:233] op_sel_hi:[1,0]
	v_pk_mul_f32 v[6:7], v[6:7], v[232:233] op_sel_hi:[1,0]
	v_pk_mul_f32 v[4:5], v[68:69], v[4:5]
	v_pk_mul_f32 v[6:7], v[70:71], v[6:7]
	v_pk_fma_f32 v[4:5], v[164:165], v[4:5], v[180:181]
	v_pk_fma_f32 v[6:7], v[166:167], v[6:7], v[182:183]
	v_cvt_pk_bf16_f32 v246, v4, v5
	v_cvt_pk_bf16_f32 v247, v6, v7
	global_store_dwordx4 v82, v[244:247], s[38:39] offset:0
	v_pk_mul_f32 v[8:9], v[8:9], v[232:233] op_sel_hi:[1,0]
	v_pk_mul_f32 v[10:11], v[10:11], v[232:233] op_sel_hi:[1,0]
	v_pk_mul_f32 v[8:9], v[72:73], v[8:9]
	v_pk_mul_f32 v[10:11], v[74:75], v[10:11]
	v_pk_fma_f32 v[8:9], v[168:169], v[8:9], v[184:185]
	v_pk_fma_f32 v[10:11], v[170:171], v[10:11], v[186:187]
	v_cvt_pk_bf16_f32 v240, v8, v9
	v_cvt_pk_bf16_f32 v241, v10, v11
	v_pk_mul_f32 v[12:13], v[12:13], v[232:233] op_sel_hi:[1,0]
	v_pk_mul_f32 v[14:15], v[14:15], v[232:233] op_sel_hi:[1,0]
	v_pk_mul_f32 v[12:13], v[76:77], v[12:13]
	v_pk_mul_f32 v[14:15], v[78:79], v[14:15]
	v_pk_fma_f32 v[12:13], v[172:173], v[12:13], v[188:189]
	v_pk_fma_f32 v[14:15], v[174:175], v[14:15], v[190:191]
	v_cvt_pk_bf16_f32 v242, v12, v13
	v_cvt_pk_bf16_f32 v243, v14, v15
	global_store_dwordx4 v82, v[240:243], s[38:39] offset:1024
	v_pk_mul_f32 v[16:17], v[16:17], v[234:235] op_sel_hi:[1,0]
	v_pk_mul_f32 v[18:19], v[18:19], v[234:235] op_sel_hi:[1,0]
	v_pk_mul_f32 v[16:17], v[64:65], v[16:17]
	v_pk_mul_f32 v[18:19], v[66:67], v[18:19]
	v_pk_fma_f32 v[16:17], v[160:161], v[16:17], v[176:177]
	v_pk_fma_f32 v[18:19], v[162:163], v[18:19], v[178:179]
	v_cvt_pk_bf16_f32 v244, v16, v17
	v_cvt_pk_bf16_f32 v245, v18, v19
	v_pk_mul_f32 v[20:21], v[20:21], v[234:235] op_sel_hi:[1,0]
	v_pk_mul_f32 v[22:23], v[22:23], v[234:235] op_sel_hi:[1,0]
	v_pk_mul_f32 v[20:21], v[68:69], v[20:21]
	v_pk_mul_f32 v[22:23], v[70:71], v[22:23]
; __device__ __forceinline__ float bf_lo(unsigned w) { return __uint_as_float(w << 16); }
; __device__ __forceinline__ float bf_hi(unsigned w) { return __uint_as_float(w & 0xffff0000u); }
; __device__ __forceinline__ unsigned pk2(float lo, float hi) { return pg8::cvt_pk_bf16(lo, hi); }
; template <bool BF> __device__ __forceinline__ void prep_rows(const float* xp, const float* xs, const bf16* hb, const float* g, const float* MOD, int shoff, int scoff, bf16* U, int gw, int NGW, int lane) {
;     ...
;     for (int mb = gw; mb < MT; mb += R * NGW) {
;         f32x4 v[R][4]; float s[R];
; #pragma unroll
;         for (int r = 0; r < R; ++r) { const int m = mb + r * NGW; const int mc = m < MT ? m : mb;
; #pragma unroll
;             for (int j = 0; j < 4; ++j) {
;                 if (BF) { const v2u a0 = *(const v2u*)(hb + (size_t)mc * DM + 4 * lane + 256 * j);
;                     v[r][j].x = pg8::bf_lo(a0.x); v[r][j].y = pg8::bf_hi(a0.x); v[r][j].z = pg8::bf_lo(a0.y); v[r][j].w = pg8::bf_hi(a0.y); }
;                 else { const float* xr = mc < MP ? xp + (size_t)mc * DM : xs + (size_t)(mc - MP) * DM; v[r][j] = *(const f32x4*)(xr + 4 * lane + 256 * j); } } }
;     ...
;         for (int r = 0; r < R; ++r) { const int m = mb + r * NGW; if (m < MT) {
;             const float rstd = 1.0f / sqrtf(s[r] * (1.0f / DM) + RMS_EPS);
;             const float* mr = MOD + (size_t)(m < MP ? (m >> 13) : 8 + ((m - MP) >> 12)) * 6144;
; #pragma unroll
;             for (int j = 0; j < 4; ++j) { const int c = 4 * lane + 256 * j;
;                 const f32x4 gg = *(const f32x4*)(g + c), sc = *(const f32x4*)(mr + scoff + c), sh = *(const f32x4*)(mr + shoff + c);
;                 const f32x4 o = v[r][j] * rstd * gg * (sc + 1.0f) + sh; v2u w; w.x = pk2(o.x, o.y); w.y = pk2(o.z, o.w); *(v2u*)(U + (size_t)m * DM + c) = w; } } }
	v_pk_fma_f32 v[20:21], v[164:165], v[20:21], v[180:181]
	v_pk_fma_f32 v[22:23], v[166:167], v[22:23], v[182:183]
	v_cvt_pk_bf16_f32 v246, v20, v21
	v_cvt_pk_bf16_f32 v247, v22, v23
	global_store_dwordx4 v82, v[244:247], s[40:41] offset:0
	v_pk_mul_f32 v[24:25], v[24:25], v[234:235] op_sel_hi:[1,0]
	v_pk_mul_f32 v[26:27], v[26:27], v[234:235] op_sel_hi:[1,0]
	v_pk_mul_f32 v[24:25], v[72:73], v[24:25]
	v_pk_mul_f32 v[26:27], v[74:75], v[26:27]
	v_pk_fma_f32 v[24:25], v[168:169], v[24:25], v[184:185]
	v_pk_fma_f32 v[26:27], v[170:171], v[26:27], v[186:187]
	v_cvt_pk_bf16_f32 v240, v24, v25
	v_cvt_pk_bf16_f32 v241, v26, v27
	v_pk_mul_f32 v[28:29], v[28:29], v[234:235] op_sel_hi:[1,0]
	v_pk_mul_f32 v[30:31], v[30:31], v[234:235] op_sel_hi:[1,0]
	v_pk_mul_f32 v[28:29], v[76:77], v[28:29]
	v_pk_mul_f32 v[30:31], v[78:79], v[30:31]
	v_pk_fma_f32 v[28:29], v[172:173], v[28:29], v[188:189]
	v_pk_fma_f32 v[30:31], v[174:175], v[30:31], v[190:191]
	v_cvt_pk_bf16_f32 v242, v28, v29
	v_cvt_pk_bf16_f32 v243, v30, v31
	global_store_dwordx4 v82, v[240:243], s[40:41] offset:1024
	v_pk_mul_f32 v[32:33], v[32:33], v[236:237] op_sel_hi:[1,0]
	v_pk_mul_f32 v[34:35], v[34:35], v[236:237] op_sel_hi:[1,0]
	v_pk_mul_f32 v[32:33], v[64:65], v[32:33]
	v_pk_mul_f32 v[34:35], v[66:67], v[34:35]
	v_pk_fma_f32 v[32:33], v[192:193], v[32:33], v[208:209]
	v_pk_fma_f32 v[34:35], v[194:195], v[34:35], v[210:211]
	v_cvt_pk_bf16_f32 v244, v32, v33
	v_cvt_pk_bf16_f32 v245, v34, v35
	v_pk_mul_f32 v[36:37], v[36:37], v[236:237] op_sel_hi:[1,0]
	v_pk_mul_f32 v[38:39], v[38:39], v[236:237] op_sel_hi:[1,0]
	v_pk_mul_f32 v[36:37], v[68:69], v[36:37]
	v_pk_mul_f32 v[38:39], v[70:71], v[38:39]
	v_pk_fma_f32 v[36:37], v[196:197], v[36:37], v[212:213]
	v_pk_fma_f32 v[38:39], v[198:199], v[38:39], v[214:215]
	v_cvt_pk_bf16_f32 v246, v36, v37
	v_cvt_pk_bf16_f32 v247, v38, v39
	global_store_dwordx4 v82, v[244:247], s[46:47] offset:0
	v_pk_mul_f32 v[40:41], v[40:41], v[236:237] op_sel_hi:[1,0]
	v_pk_mul_f32 v[42:43], v[42:43], v[236:237] op_sel_hi:[1,0]
	v_pk_mul_f32 v[40:41], v[72:73], v[40:41]
	v_pk_mul_f32 v[42:43], v[74:75], v[42:43]
	v_pk_fma_f32 v[40:41], v[200:201], v[40:41], v[216:217]
	v_pk_fma_f32 v[42:43], v[202:203], v[42:43], v[218:219]
	v_cvt_pk_bf16_f32 v240, v40, v41
	v_cvt_pk_bf16_f32 v241, v42, v43
	v_pk_mul_f32 v[44:45], v[44:45], v[236:237] op_sel_hi:[1,0]
	v_pk_mul_f32 v[46:47], v[46:47], v[236:237] op_sel_hi:[1,0]
	v_pk_mul_f32 v[44:45], v[76:77], v[44:45]
	v_pk_mul_f32 v[46:47], v[78:79], v[46:47]
	v_pk_fma_f32 v[44:45], v[204:205], v[44:45], v[220:221]
	v_pk_fma_f32 v[46:47], v[206:207], v[46:47], v[222:223]
	v_cvt_pk_bf16_f32 v242, v44, v45
	v_cvt_pk_bf16_f32 v243, v46, v47
	global_store_dwordx4 v82, v[240:243], s[46:47] offset:1024
	v_pk_mul_f32 v[48:49], v[48:49], v[238:239] op_sel_hi:[1,0]
	v_pk_mul_f32 v[50:51], v[50:51], v[238:239] op_sel_hi:[1,0]
	v_pk_mul_f32 v[48:49], v[64:65], v[48:49]
	v_pk_mul_f32 v[50:51], v[66:67], v[50:51]
	v_pk_fma_f32 v[48:49], v[192:193], v[48:49], v[208:209]
	v_pk_fma_f32 v[50:51], v[194:195], v[50:51], v[210:211]
	v_cvt_pk_bf16_f32 v244, v48, v49
	v_cvt_pk_bf16_f32 v245, v50, v51
	v_pk_mul_f32 v[52:53], v[52:53], v[238:239] op_sel_hi:[1,0]
	v_pk_mul_f32 v[54:55], v[54:55], v[238:239] op_sel_hi:[1,0]
	v_pk_mul_f32 v[52:53], v[68:69], v[52:53]
	v_pk_mul_f32 v[54:55], v[70:71], v[54:55]
	v_pk_fma_f32 v[52:53], v[196:197], v[52:53], v[212:213]
	v_pk_fma_f32 v[54:55], v[198:199], v[54:55], v[214:215]
	v_cvt_pk_bf16_f32 v246, v52, v53
	v_cvt_pk_bf16_f32 v247, v54, v55
	global_store_dwordx4 v82, v[244:247], s[48:49] offset:0
	v_pk_mul_f32 v[56:57], v[56:57], v[238:239] op_sel_hi:[1,0]
	v_pk_mul_f32 v[58:59], v[58:59], v[238:239] op_sel_hi:[1,0]
	v_pk_mul_f32 v[56:57], v[72:73], v[56:57]
	v_pk_mul_f32 v[58:59], v[74:75], v[58:59]
	v_pk_fma_f32 v[56:57], v[200:201], v[56:57], v[216:217]
	v_pk_fma_f32 v[58:59], v[202:203], v[58:59], v[218:219]
	v_cvt_pk_bf16_f32 v240, v56, v57
	v_cvt_pk_bf16_f32 v241, v58, v59
	v_pk_mul_f32 v[60:61], v[60:61], v[238:239] op_sel_hi:[1,0]
	v_pk_mul_f32 v[62:63], v[62:63], v[238:239] op_sel_hi:[1,0]
	v_pk_mul_f32 v[60:61], v[76:77], v[60:61]
	v_pk_mul_f32 v[62:63], v[78:79], v[62:63]
	v_pk_fma_f32 v[60:61], v[204:205], v[60:61], v[220:221]
	v_pk_fma_f32 v[62:63], v[206:207], v[62:63], v[222:223]
	v_cvt_pk_bf16_f32 v242, v60, v61
	v_cvt_pk_bf16_f32 v243, v62, v63
	global_store_dwordx4 v82, v[240:243], s[48:49] offset:1024
	s_add_u32 s34, s8, 0x3c000
	s_addc_u32 s35, s9, 0
	s_add_u32 s36, s8, 0x42000
	s_addc_u32 s37, s9, 0
	global_load_dwordx4 v[176:179], v80, s[34:35] offset:0
	global_load_dwordx4 v[180:183], v80, s[34:35] offset:16
	global_load_dwordx4 v[184:187], v80, s[34:35] offset:2048
	global_load_dwordx4 v[188:191], v80, s[34:35] offset:2064
	global_load_dwordx4 v[160:163], v81, s[34:35] offset:0
	global_load_dwordx4 v[164:167], v81, s[34:35] offset:16
	global_load_dwordx4 v[168:171], v81, s[34:35] offset:2048
	global_load_dwordx4 v[172:175], v81, s[34:35] offset:2064
	global_load_dwordx4 v[208:211], v80, s[36:37] offset:0
	global_load_dwordx4 v[212:215], v80, s[36:37] offset:16
	global_load_dwordx4 v[216:219], v80, s[36:37] offset:2048
	global_load_dwordx4 v[220:223], v80, s[36:37] offset:2064
	global_load_dwordx4 v[192:195], v81, s[36:37] offset:0
	global_load_dwordx4 v[196:199], v81, s[36:37] offset:16
	global_load_dwordx4 v[200:203], v81, s[36:37] offset:2048
	global_load_dwordx4 v[204:207], v81, s[36:37] offset:2064
	s_add_u32 s24, s18, 0x4000000
	s_addc_u32 s25, s19, 0
	s_add_u32 s26, s18, 0x4800000
	s_addc_u32 s27, s19, 0
	s_add_u32 s28, s18, 0x5000000
	s_addc_u32 s29, s19, 0
	s_add_u32 s30, s18, 0x5800000
	s_addc_u32 s31, s19, 0
	global_load_dwordx4 v[0:3], v80, s[24:25] offset:0 nt
	global_load_dwordx4 v[4:7], v80, s[24:25] offset:16 nt
	global_load_dwordx4 v[8:11], v80, s[24:25] offset:2048 nt
	global_load_dwordx4 v[12:15], v80, s[24:25] offset:2064 nt
	global_load_dwordx4 v[16:19], v80, s[26:27] offset:0 nt
	global_load_dwordx4 v[20:23], v80, s[26:27] offset:16 nt
	global_load_dwordx4 v[24:27], v80, s[26:27] offset:2048 nt
	global_load_dwordx4 v[28:31], v80, s[26:27] offset:2064 nt
	global_load_dwordx4 v[32:35], v80, s[28:29] offset:0 nt
	global_load_dwordx4 v[36:39], v80, s[28:29] offset:16 nt
	global_load_dwordx4 v[40:43], v80, s[28:29] offset:2048 nt
	global_load_dwordx4 v[44:47], v80, s[28:29] offset:2064 nt
	global_load_dwordx4 v[48:51], v80, s[30:31] offset:0 nt
	global_load_dwordx4 v[52:55], v80, s[30:31] offset:16 nt
	global_load_dwordx4 v[56:59], v80, s[30:31] offset:2048 nt
	global_load_dwordx4 v[60:63], v80, s[30:31] offset:2064 nt
	s_waitcnt vmcnt(40)
; template <bool BF> __device__ __forceinline__ void prep_rows(const float* xp, const float* xs, const bf16* hb, const float* g, const float* MOD, int shoff, int scoff, bf16* U, int gw, int NGW, int lane) {
;     ...
;         for (int r = 0; r < R; ++r) { float t = 0.f;
; #pragma unroll
;             for (int j = 0; j < 4; ++j) t += (v[r][j].x * v[r][j].x + v[r][j].y * v[r][j].y) + (v[r][j].z * v[r][j].z + v[r][j].w * v[r][j].w);
;             s[r] = t; }
; #pragma unroll
;         for (int o = 1; o < 64; o <<= 1) {
; #pragma unroll
;             for (int r = 0; r < R; ++r) s[r] += __shfl_xor(s[r], o); }
; #pragma unroll
;         for (int r = 0; r < R; ++r) { const int m = mb + r * NGW; if (m < MT) {
;             const float rstd = 1.0f / sqrtf(s[r] * (1.0f / DM) + RMS_EPS);
	v_pk_mul_f32 v[240:241], v[96:97], v[96:97]
	v_pk_mul_f32 v[242:243], v[112:113], v[112:113]
	v_pk_mul_f32 v[244:245], v[128:129], v[128:129]
	v_pk_mul_f32 v[246:247], v[144:145], v[144:145]
	v_pk_fma_f32 v[240:241], v[98:99], v[98:99], v[240:241]
	v_pk_fma_f32 v[242:243], v[114:115], v[114:115], v[242:243]
	v_pk_fma_f32 v[244:245], v[130:131], v[130:131], v[244:245]
	v_pk_fma_f32 v[246:247], v[146:147], v[146:147], v[246:247]
	v_pk_fma_f32 v[240:241], v[100:101], v[100:101], v[240:241]
	v_pk_fma_f32 v[242:243], v[116:117], v[116:117], v[242:243]
	v_pk_fma_f32 v[244:245], v[132:133], v[132:133], v[244:245]
	v_pk_fma_f32 v[246:247], v[148:149], v[148:149], v[246:247]
	v_pk_fma_f32 v[240:241], v[102:103], v[102:103], v[240:241]
	v_pk_fma_f32 v[242:243], v[118:119], v[118:119], v[242:243]
	v_pk_fma_f32 v[244:245], v[134:135], v[134:135], v[244:245]
	v_pk_fma_f32 v[246:247], v[150:151], v[150:151], v[246:247]
	v_pk_fma_f32 v[240:241], v[104:105], v[104:105], v[240:241]
	v_pk_fma_f32 v[242:243], v[120:121], v[120:121], v[242:243]
	v_pk_fma_f32 v[244:245], v[136:137], v[136:137], v[244:245]
	v_pk_fma_f32 v[246:247], v[152:153], v[152:153], v[246:247]
	v_pk_fma_f32 v[240:241], v[106:107], v[106:107], v[240:241]
	v_pk_fma_f32 v[242:243], v[122:123], v[122:123], v[242:243]
	v_pk_fma_f32 v[244:245], v[138:139], v[138:139], v[244:245]
	v_pk_fma_f32 v[246:247], v[154:155], v[154:155], v[246:247]
	v_pk_fma_f32 v[240:241], v[108:109], v[108:109], v[240:241]
	v_pk_fma_f32 v[242:243], v[124:125], v[124:125], v[242:243]
	v_pk_fma_f32 v[244:245], v[140:141], v[140:141], v[244:245]
	v_pk_fma_f32 v[246:247], v[156:157], v[156:157], v[246:247]
	v_pk_fma_f32 v[240:241], v[110:111], v[110:111], v[240:241]
	v_pk_fma_f32 v[242:243], v[126:127], v[126:127], v[242:243]
	v_pk_fma_f32 v[244:245], v[142:143], v[142:143], v[244:245]
	v_pk_fma_f32 v[246:247], v[158:159], v[158:159], v[246:247]
	v_add_f32_e32 v224, v240, v241
	v_add_f32_e32 v225, v242, v243
	v_add_f32_e32 v226, v244, v245
	v_add_f32_e32 v227, v246, v247
	ds_bpermute_b32 v228, v83, v224
	ds_bpermute_b32 v229, v83, v225
	ds_bpermute_b32 v230, v83, v226
	ds_bpermute_b32 v231, v83, v227
	s_waitcnt lgkmcnt(0)
	v_add_f32_e32 v224, v224, v228
	v_add_f32_e32 v225, v225, v229
	v_add_f32_e32 v226, v226, v230
	v_add_f32_e32 v227, v227, v231
	ds_bpermute_b32 v228, v84, v224
	ds_bpermute_b32 v229, v84, v225
	ds_bpermute_b32 v230, v84, v226
	ds_bpermute_b32 v231, v84, v227
	s_waitcnt lgkmcnt(0)
	v_add_f32_e32 v224, v224, v228
	v_add_f32_e32 v225, v225, v229
	v_add_f32_e32 v226, v226, v230
	v_add_f32_e32 v227, v227, v231
	ds_bpermute_b32 v228, v85, v224
	ds_bpermute_b32 v229, v85, v225
	ds_bpermute_b32 v230, v85, v226
	ds_bpermute_b32 v231, v85, v227
	s_waitcnt lgkmcnt(0)
	v_add_f32_e32 v224, v224, v228
	v_add_f32_e32 v225, v225, v229
	v_add_f32_e32 v226, v226, v230
	v_add_f32_e32 v227, v227, v231
	ds_bpermute_b32 v228, v86, v224
	ds_bpermute_b32 v229, v86, v225
	ds_bpermute_b32 v230, v86, v226
	ds_bpermute_b32 v231, v86, v227
	s_waitcnt lgkmcnt(0)
	v_add_f32_e32 v224, v224, v228
	v_add_f32_e32 v225, v225, v229
	v_add_f32_e32 v226, v226, v230
	v_add_f32_e32 v227, v227, v231
	ds_bpermute_b32 v228, v87, v224
	ds_bpermute_b32 v229, v87, v225
	ds_bpermute_b32 v230, v87, v226
	ds_bpermute_b32 v231, v87, v227
	s_waitcnt lgkmcnt(0)
	v_add_f32_e32 v224, v224, v228
	v_add_f32_e32 v225, v225, v229
	v_add_f32_e32 v226, v226, v230
	v_add_f32_e32 v227, v227, v231
	ds_bpermute_b32 v228, v88, v224
	ds_bpermute_b32 v229, v88, v225
	ds_bpermute_b32 v230, v88, v226
	ds_bpermute_b32 v231, v88, v227
	s_waitcnt lgkmcnt(0)
	v_add_f32_e32 v224, v224, v228
	v_add_f32_e32 v225, v225, v229
	v_add_f32_e32 v226, v226, v230
	v_add_f32_e32 v227, v227, v231
	v_fmamk_f32 v240, v224, 0x3a800000, v89
	v_mul_f32_e32 v241, 0x4f800000, v240
	v_cmp_gt_f32_e32 vcc, s54, v240
	s_nop 1
	v_cndmask_b32_e32 v247, v240, v241, vcc
	v_sqrt_f32_e32 v242, v247
	s_nop 1
	v_add_u32_e32 v243, -1, v242
	v_add_u32_e32 v244, 1, v242
	v_fma_f32 v245, -v243, v242, v247
	v_fma_f32 v246, -v244, v242, v247
	v_cmp_ge_f32_e64 s[52:53], 0, v245
	s_nop 1
	v_cndmask_b32_e64 v242, v242, v243, s[52:53]
	v_cmp_lt_f32_e64 s[52:53], 0, v246
	s_nop 1
	v_cndmask_b32_e64 v242, v242, v244, s[52:53]
	v_mul_f32_e32 v243, 0x37800000, v242
	v_cndmask_b32_e32 v242, v242, v243, vcc
	v_cmp_class_f32_e32 vcc, v247, v90
	s_nop 1
	v_cndmask_b32_e32 v247, v242, v247, vcc
	v_div_scale_f32 v248, s[52:53], v247, v247, 1.0
	v_rcp_f32_e32 v249, v248
	v_div_scale_f32 v228, vcc, 1.0, v247, 1.0
	s_nop 0
	v_fma_f32 v229, -v248, v249, 1.0
	v_fmac_f32_e32 v249, v229, v249
	v_mul_f32_e32 v230, v228, v249
	v_fma_f32 v229, -v248, v230, v228
	v_fmac_f32_e32 v230, v229, v249
	v_fma_f32 v248, -v248, v230, v228
	v_div_fmas_f32 v248, v248, v249, v230
	v_div_fixup_f32 v232, v248, v247, 1.0
	v_fmamk_f32 v240, v225, 0x3a800000, v89
	v_mul_f32_e32 v241, 0x4f800000, v240
	v_cmp_gt_f32_e32 vcc, s54, v240
	s_nop 1
	v_cndmask_b32_e32 v247, v240, v241, vcc
	v_sqrt_f32_e32 v242, v247
	s_nop 1
	v_add_u32_e32 v243, -1, v242
	v_add_u32_e32 v244, 1, v242
	v_fma_f32 v245, -v243, v242, v247
	v_fma_f32 v246, -v244, v242, v247
	v_cmp_ge_f32_e64 s[52:53], 0, v245
	s_nop 1
	v_cndmask_b32_e64 v242, v242, v243, s[52:53]
	v_cmp_lt_f32_e64 s[52:53], 0, v246
	s_nop 1
	v_cndmask_b32_e64 v242, v242, v244, s[52:53]
	v_mul_f32_e32 v243, 0x37800000, v242
	v_cndmask_b32_e32 v242, v242, v243, vcc
	v_cmp_class_f32_e32 vcc, v247, v90
	s_nop 1
	v_cndmask_b32_e32 v247, v242, v247, vcc
	v_div_scale_f32 v248, s[52:53], v247, v247, 1.0
	v_rcp_f32_e32 v249, v248
	v_div_scale_f32 v228, vcc, 1.0, v247, 1.0
	s_nop 0
	v_fma_f32 v229, -v248, v249, 1.0
; __device__ __forceinline__ unsigned pk2(float lo, float hi) { return pg8::cvt_pk_bf16(lo, hi); }
; template <bool BF> __device__ __forceinline__ void prep_rows(const float* xp, const float* xs, const bf16* hb, const float* g, const float* MOD, int shoff, int scoff, bf16* U, int gw, int NGW, int lane) {
;     ...
;             const float rstd = 1.0f / sqrtf(s[r] * (1.0f / DM) + RMS_EPS);
;             const float* mr = MOD + (size_t)(m < MP ? (m >> 13) : 8 + ((m - MP) >> 12)) * 6144;
; #pragma unroll
;             for (int j = 0; j < 4; ++j) { const int c = 4 * lane + 256 * j;
;                 const f32x4 gg = *(const f32x4*)(g + c), sc = *(const f32x4*)(mr + scoff + c), sh = *(const f32x4*)(mr + shoff + c);
;                 const f32x4 o = v[r][j] * rstd * gg * (sc + 1.0f) + sh; v2u w; w.x = pk2(o.x, o.y); w.y = pk2(o.z, o.w); *(v2u*)(U + (size_t)m * DM + c) = w; } } }
	v_fmac_f32_e32 v249, v229, v249
	v_mul_f32_e32 v230, v228, v249
	v_fma_f32 v229, -v248, v230, v228
	v_fmac_f32_e32 v230, v229, v249
	v_fma_f32 v248, -v248, v230, v228
	v_div_fmas_f32 v248, v248, v249, v230
	v_div_fixup_f32 v234, v248, v247, 1.0
	v_fmamk_f32 v240, v226, 0x3a800000, v89
	v_mul_f32_e32 v241, 0x4f800000, v240
	v_cmp_gt_f32_e32 vcc, s54, v240
	s_nop 1
	v_cndmask_b32_e32 v247, v240, v241, vcc
	v_sqrt_f32_e32 v242, v247
	s_nop 1
	v_add_u32_e32 v243, -1, v242
	v_add_u32_e32 v244, 1, v242
	v_fma_f32 v245, -v243, v242, v247
	v_fma_f32 v246, -v244, v242, v247
	v_cmp_ge_f32_e64 s[52:53], 0, v245
	s_nop 1
	v_cndmask_b32_e64 v242, v242, v243, s[52:53]
	v_cmp_lt_f32_e64 s[52:53], 0, v246
	s_nop 1
	v_cndmask_b32_e64 v242, v242, v244, s[52:53]
	v_mul_f32_e32 v243, 0x37800000, v242
	v_cndmask_b32_e32 v242, v242, v243, vcc
	v_cmp_class_f32_e32 vcc, v247, v90
	s_nop 1
	v_cndmask_b32_e32 v247, v242, v247, vcc
	v_div_scale_f32 v248, s[52:53], v247, v247, 1.0
	v_rcp_f32_e32 v249, v248
	v_div_scale_f32 v228, vcc, 1.0, v247, 1.0
	s_nop 0
	v_fma_f32 v229, -v248, v249, 1.0
	v_fmac_f32_e32 v249, v229, v249
	v_mul_f32_e32 v230, v228, v249
	v_fma_f32 v229, -v248, v230, v228
	v_fmac_f32_e32 v230, v229, v249
	v_fma_f32 v248, -v248, v230, v228
	v_div_fmas_f32 v248, v248, v249, v230
	v_div_fixup_f32 v236, v248, v247, 1.0
	v_fmamk_f32 v240, v227, 0x3a800000, v89
	v_mul_f32_e32 v241, 0x4f800000, v240
	v_cmp_gt_f32_e32 vcc, s54, v240
	s_nop 1
	v_cndmask_b32_e32 v247, v240, v241, vcc
	v_sqrt_f32_e32 v242, v247
	s_nop 1
	v_add_u32_e32 v243, -1, v242
	v_add_u32_e32 v244, 1, v242
	v_fma_f32 v245, -v243, v242, v247
	v_fma_f32 v246, -v244, v242, v247
	v_cmp_ge_f32_e64 s[52:53], 0, v245
	s_nop 1
	v_cndmask_b32_e64 v242, v242, v243, s[52:53]
	v_cmp_lt_f32_e64 s[52:53], 0, v246
	s_nop 1
	v_cndmask_b32_e64 v242, v242, v244, s[52:53]
	v_mul_f32_e32 v243, 0x37800000, v242
	v_cndmask_b32_e32 v242, v242, v243, vcc
	v_cmp_class_f32_e32 vcc, v247, v90
	s_nop 1
	v_cndmask_b32_e32 v247, v242, v247, vcc
	v_div_scale_f32 v248, s[52:53], v247, v247, 1.0
	v_rcp_f32_e32 v249, v248
	v_div_scale_f32 v228, vcc, 1.0, v247, 1.0
	s_nop 0
	v_fma_f32 v229, -v248, v249, 1.0
	v_fmac_f32_e32 v249, v229, v249
	v_mul_f32_e32 v230, v228, v249
	v_fma_f32 v229, -v248, v230, v228
	v_fmac_f32_e32 v230, v229, v249
	v_fma_f32 v248, -v248, v230, v228
	v_div_fmas_f32 v248, v248, v249, v230
	v_div_fixup_f32 v238, v248, v247, 1.0
	s_waitcnt vmcnt(16)
	v_pk_add_f32 v[160:161], v[160:161], 1.0 op_sel_hi:[1,0]
	v_pk_add_f32 v[162:163], v[162:163], 1.0 op_sel_hi:[1,0]
	v_pk_add_f32 v[164:165], v[164:165], 1.0 op_sel_hi:[1,0]
	v_pk_add_f32 v[166:167], v[166:167], 1.0 op_sel_hi:[1,0]
	v_pk_add_f32 v[168:169], v[168:169], 1.0 op_sel_hi:[1,0]
	v_pk_add_f32 v[170:171], v[170:171], 1.0 op_sel_hi:[1,0]
	v_pk_add_f32 v[172:173], v[172:173], 1.0 op_sel_hi:[1,0]
	v_pk_add_f32 v[174:175], v[174:175], 1.0 op_sel_hi:[1,0]
	v_pk_add_f32 v[192:193], v[192:193], 1.0 op_sel_hi:[1,0]
	v_pk_add_f32 v[194:195], v[194:195], 1.0 op_sel_hi:[1,0]
	v_pk_add_f32 v[196:197], v[196:197], 1.0 op_sel_hi:[1,0]
	v_pk_add_f32 v[198:199], v[198:199], 1.0 op_sel_hi:[1,0]
	v_pk_add_f32 v[200:201], v[200:201], 1.0 op_sel_hi:[1,0]
	v_pk_add_f32 v[202:203], v[202:203], 1.0 op_sel_hi:[1,0]
	v_pk_add_f32 v[204:205], v[204:205], 1.0 op_sel_hi:[1,0]
	v_pk_add_f32 v[206:207], v[206:207], 1.0 op_sel_hi:[1,0]
	s_add_u32 s38, s20, 0x9000000
	s_addc_u32 s39, s21, 0
	s_add_u32 s40, s20, 0x9400000
	s_addc_u32 s41, s21, 0
	s_add_u32 s46, s20, 0x9800000
	s_addc_u32 s47, s21, 0
	s_add_u32 s48, s20, 0x9c00000
	s_addc_u32 s49, s21, 0
	v_pk_mul_f32 v[96:97], v[96:97], v[232:233] op_sel_hi:[1,0]
	v_pk_mul_f32 v[98:99], v[98:99], v[232:233] op_sel_hi:[1,0]
	v_pk_mul_f32 v[96:97], v[64:65], v[96:97]
	v_pk_mul_f32 v[98:99], v[66:67], v[98:99]
	v_pk_fma_f32 v[96:97], v[160:161], v[96:97], v[176:177]
	v_pk_fma_f32 v[98:99], v[162:163], v[98:99], v[178:179]
	v_cvt_pk_bf16_f32 v244, v96, v97
	v_cvt_pk_bf16_f32 v245, v98, v99
	v_pk_mul_f32 v[100:101], v[100:101], v[232:233] op_sel_hi:[1,0]
	v_pk_mul_f32 v[102:103], v[102:103], v[232:233] op_sel_hi:[1,0]
	v_pk_mul_f32 v[100:101], v[68:69], v[100:101]
	v_pk_mul_f32 v[102:103], v[70:71], v[102:103]
	v_pk_fma_f32 v[100:101], v[164:165], v[100:101], v[180:181]
	v_pk_fma_f32 v[102:103], v[166:167], v[102:103], v[182:183]
	v_cvt_pk_bf16_f32 v246, v100, v101
	v_cvt_pk_bf16_f32 v247, v102, v103
	global_store_dwordx4 v82, v[244:247], s[38:39] offset:0
	v_pk_mul_f32 v[104:105], v[104:105], v[232:233] op_sel_hi:[1,0]
	v_pk_mul_f32 v[106:107], v[106:107], v[232:233] op_sel_hi:[1,0]
	v_pk_mul_f32 v[104:105], v[72:73], v[104:105]
	v_pk_mul_f32 v[106:107], v[74:75], v[106:107]
	v_pk_fma_f32 v[104:105], v[168:169], v[104:105], v[184:185]
	v_pk_fma_f32 v[106:107], v[170:171], v[106:107], v[186:187]
	v_cvt_pk_bf16_f32 v240, v104, v105
	v_cvt_pk_bf16_f32 v241, v106, v107
	v_pk_mul_f32 v[108:109], v[108:109], v[232:233] op_sel_hi:[1,0]
	v_pk_mul_f32 v[110:111], v[110:111], v[232:233] op_sel_hi:[1,0]
	v_pk_mul_f32 v[108:109], v[76:77], v[108:109]
	v_pk_mul_f32 v[110:111], v[78:79], v[110:111]
	v_pk_fma_f32 v[108:109], v[172:173], v[108:109], v[188:189]
	v_pk_fma_f32 v[110:111], v[174:175], v[110:111], v[190:191]
	v_cvt_pk_bf16_f32 v242, v108, v109
	v_cvt_pk_bf16_f32 v243, v110, v111
	global_store_dwordx4 v82, v[240:243], s[38:39] offset:1024
	v_pk_mul_f32 v[112:113], v[112:113], v[234:235] op_sel_hi:[1,0]
	v_pk_mul_f32 v[114:115], v[114:115], v[234:235] op_sel_hi:[1,0]
	v_pk_mul_f32 v[112:113], v[64:65], v[112:113]
	v_pk_mul_f32 v[114:115], v[66:67], v[114:115]
	v_pk_fma_f32 v[112:113], v[160:161], v[112:113], v[176:177]
; __device__ __forceinline__ unsigned pk2(float lo, float hi) { return pg8::cvt_pk_bf16(lo, hi); }
; template <bool BF> __device__ __forceinline__ void prep_rows(const float* xp, const float* xs, const bf16* hb, const float* g, const float* MOD, int shoff, int scoff, bf16* U, int gw, int NGW, int lane) {
;     ...
; #pragma unroll
;             for (int j = 0; j < 4; ++j) { const int c = 4 * lane + 256 * j;
;                 const f32x4 gg = *(const f32x4*)(g + c), sc = *(const f32x4*)(mr + scoff + c), sh = *(const f32x4*)(mr + shoff + c);
;                 const f32x4 o = v[r][j] * rstd * gg * (sc + 1.0f) + sh; v2u w; w.x = pk2(o.x, o.y); w.y = pk2(o.z, o.w); *(v2u*)(U + (size_t)m * DM + c) = w; } } }
	v_pk_fma_f32 v[114:115], v[162:163], v[114:115], v[178:179]
	v_cvt_pk_bf16_f32 v244, v112, v113
	v_cvt_pk_bf16_f32 v245, v114, v115
	v_pk_mul_f32 v[116:117], v[116:117], v[234:235] op_sel_hi:[1,0]
	v_pk_mul_f32 v[118:119], v[118:119], v[234:235] op_sel_hi:[1,0]
	v_pk_mul_f32 v[116:117], v[68:69], v[116:117]
	v_pk_mul_f32 v[118:119], v[70:71], v[118:119]
	v_pk_fma_f32 v[116:117], v[164:165], v[116:117], v[180:181]
	v_pk_fma_f32 v[118:119], v[166:167], v[118:119], v[182:183]
	v_cvt_pk_bf16_f32 v246, v116, v117
	v_cvt_pk_bf16_f32 v247, v118, v119
	global_store_dwordx4 v82, v[244:247], s[40:41] offset:0
	v_pk_mul_f32 v[120:121], v[120:121], v[234:235] op_sel_hi:[1,0]
	v_pk_mul_f32 v[122:123], v[122:123], v[234:235] op_sel_hi:[1,0]
	v_pk_mul_f32 v[120:121], v[72:73], v[120:121]
	v_pk_mul_f32 v[122:123], v[74:75], v[122:123]
	v_pk_fma_f32 v[120:121], v[168:169], v[120:121], v[184:185]
	v_pk_fma_f32 v[122:123], v[170:171], v[122:123], v[186:187]
	v_cvt_pk_bf16_f32 v240, v120, v121
	v_cvt_pk_bf16_f32 v241, v122, v123
	v_pk_mul_f32 v[124:125], v[124:125], v[234:235] op_sel_hi:[1,0]
	v_pk_mul_f32 v[126:127], v[126:127], v[234:235] op_sel_hi:[1,0]
	v_pk_mul_f32 v[124:125], v[76:77], v[124:125]
	v_pk_mul_f32 v[126:127], v[78:79], v[126:127]
	v_pk_fma_f32 v[124:125], v[172:173], v[124:125], v[188:189]
	v_pk_fma_f32 v[126:127], v[174:175], v[126:127], v[190:191]
	v_cvt_pk_bf16_f32 v242, v124, v125
	v_cvt_pk_bf16_f32 v243, v126, v127
	global_store_dwordx4 v82, v[240:243], s[40:41] offset:1024
	v_pk_mul_f32 v[128:129], v[128:129], v[236:237] op_sel_hi:[1,0]
	v_pk_mul_f32 v[130:131], v[130:131], v[236:237] op_sel_hi:[1,0]
	v_pk_mul_f32 v[128:129], v[64:65], v[128:129]
	v_pk_mul_f32 v[130:131], v[66:67], v[130:131]
	v_pk_fma_f32 v[128:129], v[192:193], v[128:129], v[208:209]
	v_pk_fma_f32 v[130:131], v[194:195], v[130:131], v[210:211]
	v_cvt_pk_bf16_f32 v244, v128, v129
	v_cvt_pk_bf16_f32 v245, v130, v131
	v_pk_mul_f32 v[132:133], v[132:133], v[236:237] op_sel_hi:[1,0]
	v_pk_mul_f32 v[134:135], v[134:135], v[236:237] op_sel_hi:[1,0]
	v_pk_mul_f32 v[132:133], v[68:69], v[132:133]
	v_pk_mul_f32 v[134:135], v[70:71], v[134:135]
	v_pk_fma_f32 v[132:133], v[196:197], v[132:133], v[212:213]
	v_pk_fma_f32 v[134:135], v[198:199], v[134:135], v[214:215]
	v_cvt_pk_bf16_f32 v246, v132, v133
	v_cvt_pk_bf16_f32 v247, v134, v135
	global_store_dwordx4 v82, v[244:247], s[46:47] offset:0
	v_pk_mul_f32 v[136:137], v[136:137], v[236:237] op_sel_hi:[1,0]
	v_pk_mul_f32 v[138:139], v[138:139], v[236:237] op_sel_hi:[1,0]
	v_pk_mul_f32 v[136:137], v[72:73], v[136:137]
	v_pk_mul_f32 v[138:139], v[74:75], v[138:139]
	v_pk_fma_f32 v[136:137], v[200:201], v[136:137], v[216:217]
	v_pk_fma_f32 v[138:139], v[202:203], v[138:139], v[218:219]
	v_cvt_pk_bf16_f32 v240, v136, v137
	v_cvt_pk_bf16_f32 v241, v138, v139
	v_pk_mul_f32 v[140:141], v[140:141], v[236:237] op_sel_hi:[1,0]
	v_pk_mul_f32 v[142:143], v[142:143], v[236:237] op_sel_hi:[1,0]
	v_pk_mul_f32 v[140:141], v[76:77], v[140:141]
	v_pk_mul_f32 v[142:143], v[78:79], v[142:143]
	v_pk_fma_f32 v[140:141], v[204:205], v[140:141], v[220:221]
	v_pk_fma_f32 v[142:143], v[206:207], v[142:143], v[222:223]
	v_cvt_pk_bf16_f32 v242, v140, v141
	v_cvt_pk_bf16_f32 v243, v142, v143
	global_store_dwordx4 v82, v[240:243], s[46:47] offset:1024
	v_pk_mul_f32 v[144:145], v[144:145], v[238:239] op_sel_hi:[1,0]
	v_pk_mul_f32 v[146:147], v[146:147], v[238:239] op_sel_hi:[1,0]
	v_pk_mul_f32 v[144:145], v[64:65], v[144:145]
	v_pk_mul_f32 v[146:147], v[66:67], v[146:147]
	v_pk_fma_f32 v[144:145], v[192:193], v[144:145], v[208:209]
	v_pk_fma_f32 v[146:147], v[194:195], v[146:147], v[210:211]
	v_cvt_pk_bf16_f32 v244, v144, v145
	v_cvt_pk_bf16_f32 v245, v146, v147
	v_pk_mul_f32 v[148:149], v[148:149], v[238:239] op_sel_hi:[1,0]
	v_pk_mul_f32 v[150:151], v[150:151], v[238:239] op_sel_hi:[1,0]
	v_pk_mul_f32 v[148:149], v[68:69], v[148:149]
	v_pk_mul_f32 v[150:151], v[70:71], v[150:151]
	v_pk_fma_f32 v[148:149], v[196:197], v[148:149], v[212:213]
	v_pk_fma_f32 v[150:151], v[198:199], v[150:151], v[214:215]
	v_cvt_pk_bf16_f32 v246, v148, v149
	v_cvt_pk_bf16_f32 v247, v150, v151
	global_store_dwordx4 v82, v[244:247], s[48:49] offset:0
	v_pk_mul_f32 v[152:153], v[152:153], v[238:239] op_sel_hi:[1,0]
	v_pk_mul_f32 v[154:155], v[154:155], v[238:239] op_sel_hi:[1,0]
	v_pk_mul_f32 v[152:153], v[72:73], v[152:153]
	v_pk_mul_f32 v[154:155], v[74:75], v[154:155]
	v_pk_fma_f32 v[152:153], v[200:201], v[152:153], v[216:217]
	v_pk_fma_f32 v[154:155], v[202:203], v[154:155], v[218:219]
	v_cvt_pk_bf16_f32 v240, v152, v153
	v_cvt_pk_bf16_f32 v241, v154, v155
	v_pk_mul_f32 v[156:157], v[156:157], v[238:239] op_sel_hi:[1,0]
	v_pk_mul_f32 v[158:159], v[158:159], v[238:239] op_sel_hi:[1,0]
	v_pk_mul_f32 v[156:157], v[76:77], v[156:157]
	v_pk_mul_f32 v[158:159], v[78:79], v[158:159]
	v_pk_fma_f32 v[156:157], v[204:205], v[156:157], v[220:221]
	v_pk_fma_f32 v[158:159], v[206:207], v[158:159], v[222:223]
	v_cvt_pk_bf16_f32 v242, v156, v157
	v_cvt_pk_bf16_f32 v243, v158, v159
	global_store_dwordx4 v82, v[240:243], s[48:49] offset:1024
	s_add_u32 s34, s8, 0x48000
	s_addc_u32 s35, s9, 0
	s_add_u32 s36, s8, 0x4e000
	s_addc_u32 s37, s9, 0
	global_load_dwordx4 v[176:179], v80, s[34:35] offset:0
	global_load_dwordx4 v[180:183], v80, s[34:35] offset:16
	global_load_dwordx4 v[184:187], v80, s[34:35] offset:2048
	global_load_dwordx4 v[188:191], v80, s[34:35] offset:2064
	global_load_dwordx4 v[160:163], v81, s[34:35] offset:0
	global_load_dwordx4 v[164:167], v81, s[34:35] offset:16
	global_load_dwordx4 v[168:171], v81, s[34:35] offset:2048
	global_load_dwordx4 v[172:175], v81, s[34:35] offset:2064
; __device__ __forceinline__ float bf_lo(unsigned w) { return __uint_as_float(w << 16); }
; __device__ __forceinline__ float bf_hi(unsigned w) { return __uint_as_float(w & 0xffff0000u); }
; template <bool BF> __device__ __forceinline__ void prep_rows(const float* xp, const float* xs, const bf16* hb, const float* g, const float* MOD, int shoff, int scoff, bf16* U, int gw, int NGW, int lane) {
;     ...
;     for (int mb = gw; mb < MT; mb += R * NGW) {
;         f32x4 v[R][4]; float s[R];
; #pragma unroll
;         for (int r = 0; r < R; ++r) { const int m = mb + r * NGW; const int mc = m < MT ? m : mb;
; #pragma unroll
;             for (int j = 0; j < 4; ++j) {
;                 if (BF) { const v2u a0 = *(const v2u*)(hb + (size_t)mc * DM + 4 * lane + 256 * j);
;                     v[r][j].x = pg8::bf_lo(a0.x); v[r][j].y = pg8::bf_hi(a0.x); v[r][j].z = pg8::bf_lo(a0.y); v[r][j].w = pg8::bf_hi(a0.y); }
;                 else { const float* xr = mc < MP ? xp + (size_t)mc * DM : xs + (size_t)(mc - MP) * DM; v[r][j] = *(const f32x4*)(xr + 4 * lane + 256 * j); } } }
; #pragma unroll
;         for (int r = 0; r < R; ++r) { float t = 0.f;
; #pragma unroll
;             for (int j = 0; j < 4; ++j) t += (v[r][j].x * v[r][j].x + v[r][j].y * v[r][j].y) + (v[r][j].z * v[r][j].z + v[r][j].w * v[r][j].w);
;             s[r] = t; }
	global_load_dwordx4 v[208:211], v80, s[36:37] offset:0
	global_load_dwordx4 v[212:215], v80, s[36:37] offset:16
	global_load_dwordx4 v[216:219], v80, s[36:37] offset:2048
	global_load_dwordx4 v[220:223], v80, s[36:37] offset:2064
	global_load_dwordx4 v[192:195], v81, s[36:37] offset:0
	global_load_dwordx4 v[196:199], v81, s[36:37] offset:16
	global_load_dwordx4 v[200:203], v81, s[36:37] offset:2048
	global_load_dwordx4 v[204:207], v81, s[36:37] offset:2064
	s_add_u32 s24, s18, 0x6000000
	s_addc_u32 s25, s19, 0
	s_add_u32 s26, s18, 0x6800000
	s_addc_u32 s27, s19, 0
	s_add_u32 s28, s18, 0x7000000
	s_addc_u32 s29, s19, 0
	s_add_u32 s30, s18, 0x7800000
	s_addc_u32 s31, s19, 0
	global_load_dwordx4 v[96:99], v80, s[24:25] offset:0 nt
	global_load_dwordx4 v[100:103], v80, s[24:25] offset:16 nt
	global_load_dwordx4 v[104:107], v80, s[24:25] offset:2048 nt
	global_load_dwordx4 v[108:111], v80, s[24:25] offset:2064 nt
	global_load_dwordx4 v[112:115], v80, s[26:27] offset:0 nt
	global_load_dwordx4 v[116:119], v80, s[26:27] offset:16 nt
	global_load_dwordx4 v[120:123], v80, s[26:27] offset:2048 nt
	global_load_dwordx4 v[124:127], v80, s[26:27] offset:2064 nt
	global_load_dwordx4 v[128:131], v80, s[28:29] offset:0 nt
	global_load_dwordx4 v[132:135], v80, s[28:29] offset:16 nt
	global_load_dwordx4 v[136:139], v80, s[28:29] offset:2048 nt
	global_load_dwordx4 v[140:143], v80, s[28:29] offset:2064 nt
	global_load_dwordx4 v[144:147], v80, s[30:31] offset:0 nt
	global_load_dwordx4 v[148:151], v80, s[30:31] offset:16 nt
	global_load_dwordx4 v[152:155], v80, s[30:31] offset:2048 nt
	global_load_dwordx4 v[156:159], v80, s[30:31] offset:2064 nt
	s_waitcnt vmcnt(40)
	v_pk_mul_f32 v[240:241], v[0:1], v[0:1]
	v_pk_mul_f32 v[242:243], v[16:17], v[16:17]
	v_pk_mul_f32 v[244:245], v[32:33], v[32:33]
	v_pk_mul_f32 v[246:247], v[48:49], v[48:49]
	v_pk_fma_f32 v[240:241], v[2:3], v[2:3], v[240:241]
	v_pk_fma_f32 v[242:243], v[18:19], v[18:19], v[242:243]
	v_pk_fma_f32 v[244:245], v[34:35], v[34:35], v[244:245]
	v_pk_fma_f32 v[246:247], v[50:51], v[50:51], v[246:247]
	v_pk_fma_f32 v[240:241], v[4:5], v[4:5], v[240:241]
	v_pk_fma_f32 v[242:243], v[20:21], v[20:21], v[242:243]
	v_pk_fma_f32 v[244:245], v[36:37], v[36:37], v[244:245]
	v_pk_fma_f32 v[246:247], v[52:53], v[52:53], v[246:247]
	v_pk_fma_f32 v[240:241], v[6:7], v[6:7], v[240:241]
	v_pk_fma_f32 v[242:243], v[22:23], v[22:23], v[242:243]
	v_pk_fma_f32 v[244:245], v[38:39], v[38:39], v[244:245]
	v_pk_fma_f32 v[246:247], v[54:55], v[54:55], v[246:247]
	v_pk_fma_f32 v[240:241], v[8:9], v[8:9], v[240:241]
	v_pk_fma_f32 v[242:243], v[24:25], v[24:25], v[242:243]
	v_pk_fma_f32 v[244:245], v[40:41], v[40:41], v[244:245]
	v_pk_fma_f32 v[246:247], v[56:57], v[56:57], v[246:247]
	v_pk_fma_f32 v[240:241], v[10:11], v[10:11], v[240:241]
	v_pk_fma_f32 v[242:243], v[26:27], v[26:27], v[242:243]
	v_pk_fma_f32 v[244:245], v[42:43], v[42:43], v[244:245]
	v_pk_fma_f32 v[246:247], v[58:59], v[58:59], v[246:247]
	v_pk_fma_f32 v[240:241], v[12:13], v[12:13], v[240:241]
	v_pk_fma_f32 v[242:243], v[28:29], v[28:29], v[242:243]
	v_pk_fma_f32 v[244:245], v[44:45], v[44:45], v[244:245]
	v_pk_fma_f32 v[246:247], v[60:61], v[60:61], v[246:247]
	v_pk_fma_f32 v[240:241], v[14:15], v[14:15], v[240:241]
	v_pk_fma_f32 v[242:243], v[30:31], v[30:31], v[242:243]
	v_pk_fma_f32 v[244:245], v[46:47], v[46:47], v[244:245]
	v_pk_fma_f32 v[246:247], v[62:63], v[62:63], v[246:247]
	v_add_f32_e32 v224, v240, v241
	v_add_f32_e32 v225, v242, v243
	v_add_f32_e32 v226, v244, v245
	v_add_f32_e32 v227, v246, v247
	ds_bpermute_b32 v228, v83, v224
	ds_bpermute_b32 v229, v83, v225
	ds_bpermute_b32 v230, v83, v226
	ds_bpermute_b32 v231, v83, v227
	s_waitcnt lgkmcnt(0)
	v_add_f32_e32 v224, v224, v228
	v_add_f32_e32 v225, v225, v229
	v_add_f32_e32 v226, v226, v230
	v_add_f32_e32 v227, v227, v231
	ds_bpermute_b32 v228, v84, v224
	ds_bpermute_b32 v229, v84, v225
	ds_bpermute_b32 v230, v84, v226
	ds_bpermute_b32 v231, v84, v227
	s_waitcnt lgkmcnt(0)
	v_add_f32_e32 v224, v224, v228
	v_add_f32_e32 v225, v225, v229
	v_add_f32_e32 v226, v226, v230
	v_add_f32_e32 v227, v227, v231
	ds_bpermute_b32 v228, v85, v224
	ds_bpermute_b32 v229, v85, v225
	ds_bpermute_b32 v230, v85, v226
	ds_bpermute_b32 v231, v85, v227
	s_waitcnt lgkmcnt(0)
	v_add_f32_e32 v224, v224, v228
	v_add_f32_e32 v225, v225, v229
	v_add_f32_e32 v226, v226, v230
	v_add_f32_e32 v227, v227, v231
	ds_bpermute_b32 v228, v86, v224
	ds_bpermute_b32 v229, v86, v225
	ds_bpermute_b32 v230, v86, v226
	ds_bpermute_b32 v231, v86, v227
	s_waitcnt lgkmcnt(0)
	v_add_f32_e32 v224, v224, v228
	v_add_f32_e32 v225, v225, v229
	v_add_f32_e32 v226, v226, v230
	v_add_f32_e32 v227, v227, v231
	ds_bpermute_b32 v228, v87, v224
	ds_bpermute_b32 v229, v87, v225
	ds_bpermute_b32 v230, v87, v226
	ds_bpermute_b32 v231, v87, v227
	s_waitcnt lgkmcnt(0)
	v_add_f32_e32 v224, v224, v228
	v_add_f32_e32 v225, v225, v229
	v_add_f32_e32 v226, v226, v230
	v_add_f32_e32 v227, v227, v231
	ds_bpermute_b32 v228, v88, v224
	ds_bpermute_b32 v229, v88, v225
	ds_bpermute_b32 v230, v88, v226
	ds_bpermute_b32 v231, v88, v227
	s_waitcnt lgkmcnt(0)
; template <bool BF> __device__ __forceinline__ void prep_rows(const float* xp, const float* xs, const bf16* hb, const float* g, const float* MOD, int shoff, int scoff, bf16* U, int gw, int NGW, int lane) {
;     ...
;             for (int r = 0; r < R; ++r) s[r] += __shfl_xor(s[r], o); }
; #pragma unroll
;         for (int r = 0; r < R; ++r) { const int m = mb + r * NGW; if (m < MT) {
;             const float rstd = 1.0f / sqrtf(s[r] * (1.0f / DM) + RMS_EPS);
	v_add_f32_e32 v224, v224, v228
	v_add_f32_e32 v225, v225, v229
	v_add_f32_e32 v226, v226, v230
	v_add_f32_e32 v227, v227, v231
	v_fmamk_f32 v240, v224, 0x3a800000, v89
	v_mul_f32_e32 v241, 0x4f800000, v240
	v_cmp_gt_f32_e32 vcc, s54, v240
	s_nop 1
	v_cndmask_b32_e32 v247, v240, v241, vcc
	v_sqrt_f32_e32 v242, v247
	s_nop 1
	v_add_u32_e32 v243, -1, v242
	v_add_u32_e32 v244, 1, v242
	v_fma_f32 v245, -v243, v242, v247
	v_fma_f32 v246, -v244, v242, v247
	v_cmp_ge_f32_e64 s[52:53], 0, v245
	s_nop 1
	v_cndmask_b32_e64 v242, v242, v243, s[52:53]
	v_cmp_lt_f32_e64 s[52:53], 0, v246
	s_nop 1
	v_cndmask_b32_e64 v242, v242, v244, s[52:53]
	v_mul_f32_e32 v243, 0x37800000, v242
	v_cndmask_b32_e32 v242, v242, v243, vcc
	v_cmp_class_f32_e32 vcc, v247, v90
	s_nop 1
	v_cndmask_b32_e32 v247, v242, v247, vcc
	v_div_scale_f32 v248, s[52:53], v247, v247, 1.0
	v_rcp_f32_e32 v249, v248
	v_div_scale_f32 v228, vcc, 1.0, v247, 1.0
	s_nop 0
	v_fma_f32 v229, -v248, v249, 1.0
	v_fmac_f32_e32 v249, v229, v249
	v_mul_f32_e32 v230, v228, v249
	v_fma_f32 v229, -v248, v230, v228
	v_fmac_f32_e32 v230, v229, v249
	v_fma_f32 v248, -v248, v230, v228
	v_div_fmas_f32 v248, v248, v249, v230
	v_div_fixup_f32 v232, v248, v247, 1.0
	v_fmamk_f32 v240, v225, 0x3a800000, v89
	v_mul_f32_e32 v241, 0x4f800000, v240
	v_cmp_gt_f32_e32 vcc, s54, v240
	s_nop 1
	v_cndmask_b32_e32 v247, v240, v241, vcc
	v_sqrt_f32_e32 v242, v247
	s_nop 1
	v_add_u32_e32 v243, -1, v242
	v_add_u32_e32 v244, 1, v242
	v_fma_f32 v245, -v243, v242, v247
	v_fma_f32 v246, -v244, v242, v247
	v_cmp_ge_f32_e64 s[52:53], 0, v245
	s_nop 1
	v_cndmask_b32_e64 v242, v242, v243, s[52:53]
	v_cmp_lt_f32_e64 s[52:53], 0, v246
	s_nop 1
	v_cndmask_b32_e64 v242, v242, v244, s[52:53]
	v_mul_f32_e32 v243, 0x37800000, v242
	v_cndmask_b32_e32 v242, v242, v243, vcc
	v_cmp_class_f32_e32 vcc, v247, v90
	s_nop 1
	v_cndmask_b32_e32 v247, v242, v247, vcc
	v_div_scale_f32 v248, s[52:53], v247, v247, 1.0
	v_rcp_f32_e32 v249, v248
	v_div_scale_f32 v228, vcc, 1.0, v247, 1.0
	s_nop 0
	v_fma_f32 v229, -v248, v249, 1.0
	v_fmac_f32_e32 v249, v229, v249
	v_mul_f32_e32 v230, v228, v249
	v_fma_f32 v229, -v248, v230, v228
	v_fmac_f32_e32 v230, v229, v249
	v_fma_f32 v248, -v248, v230, v228
	v_div_fmas_f32 v248, v248, v249, v230
	v_div_fixup_f32 v234, v248, v247, 1.0
	v_fmamk_f32 v240, v226, 0x3a800000, v89
	v_mul_f32_e32 v241, 0x4f800000, v240
	v_cmp_gt_f32_e32 vcc, s54, v240
	s_nop 1
	v_cndmask_b32_e32 v247, v240, v241, vcc
	v_sqrt_f32_e32 v242, v247
	s_nop 1
	v_add_u32_e32 v243, -1, v242
	v_add_u32_e32 v244, 1, v242
	v_fma_f32 v245, -v243, v242, v247
	v_fma_f32 v246, -v244, v242, v247
	v_cmp_ge_f32_e64 s[52:53], 0, v245
	s_nop 1
	v_cndmask_b32_e64 v242, v242, v243, s[52:53]
	v_cmp_lt_f32_e64 s[52:53], 0, v246
	s_nop 1
	v_cndmask_b32_e64 v242, v242, v244, s[52:53]
	v_mul_f32_e32 v243, 0x37800000, v242
	v_cndmask_b32_e32 v242, v242, v243, vcc
	v_cmp_class_f32_e32 vcc, v247, v90
	s_nop 1
	v_cndmask_b32_e32 v247, v242, v247, vcc
	v_div_scale_f32 v248, s[52:53], v247, v247, 1.0
	v_rcp_f32_e32 v249, v248
	v_div_scale_f32 v228, vcc, 1.0, v247, 1.0
	s_nop 0
	v_fma_f32 v229, -v248, v249, 1.0
	v_fmac_f32_e32 v249, v229, v249
	v_mul_f32_e32 v230, v228, v249
	v_fma_f32 v229, -v248, v230, v228
	v_fmac_f32_e32 v230, v229, v249
	v_fma_f32 v248, -v248, v230, v228
	v_div_fmas_f32 v248, v248, v249, v230
	v_div_fixup_f32 v236, v248, v247, 1.0
	v_fmamk_f32 v240, v227, 0x3a800000, v89
	v_mul_f32_e32 v241, 0x4f800000, v240
	v_cmp_gt_f32_e32 vcc, s54, v240
	s_nop 1
	v_cndmask_b32_e32 v247, v240, v241, vcc
	v_sqrt_f32_e32 v242, v247
	s_nop 1
	v_add_u32_e32 v243, -1, v242
	v_add_u32_e32 v244, 1, v242
	v_fma_f32 v245, -v243, v242, v247
	v_fma_f32 v246, -v244, v242, v247
	v_cmp_ge_f32_e64 s[52:53], 0, v245
	s_nop 1
	v_cndmask_b32_e64 v242, v242, v243, s[52:53]
	v_cmp_lt_f32_e64 s[52:53], 0, v246
	s_nop 1
	v_cndmask_b32_e64 v242, v242, v244, s[52:53]
	v_mul_f32_e32 v243, 0x37800000, v242
	v_cndmask_b32_e32 v242, v242, v243, vcc
	v_cmp_class_f32_e32 vcc, v247, v90
	s_nop 1
	v_cndmask_b32_e32 v247, v242, v247, vcc
	v_div_scale_f32 v248, s[52:53], v247, v247, 1.0
	v_rcp_f32_e32 v249, v248
	v_div_scale_f32 v228, vcc, 1.0, v247, 1.0
	s_nop 0
	v_fma_f32 v229, -v248, v249, 1.0
	v_fmac_f32_e32 v249, v229, v249
	v_mul_f32_e32 v230, v228, v249
	v_fma_f32 v229, -v248, v230, v228
	v_fmac_f32_e32 v230, v229, v249
	v_fma_f32 v248, -v248, v230, v228
	v_div_fmas_f32 v248, v248, v249, v230
	v_div_fixup_f32 v238, v248, v247, 1.0
	s_waitcnt vmcnt(16)
; __device__ __forceinline__ unsigned pk2(float lo, float hi) { return pg8::cvt_pk_bf16(lo, hi); }
; template <bool BF> __device__ __forceinline__ void prep_rows(const float* xp, const float* xs, const bf16* hb, const float* g, const float* MOD, int shoff, int scoff, bf16* U, int gw, int NGW, int lane) {
;     ...
; #pragma unroll
;             for (int j = 0; j < 4; ++j) { const int c = 4 * lane + 256 * j;
;                 const f32x4 gg = *(const f32x4*)(g + c), sc = *(const f32x4*)(mr + scoff + c), sh = *(const f32x4*)(mr + shoff + c);
;                 const f32x4 o = v[r][j] * rstd * gg * (sc + 1.0f) + sh; v2u w; w.x = pk2(o.x, o.y); w.y = pk2(o.z, o.w); *(v2u*)(U + (size_t)m * DM + c) = w; } } }
	v_pk_add_f32 v[160:161], v[160:161], 1.0 op_sel_hi:[1,0]
	v_pk_add_f32 v[162:163], v[162:163], 1.0 op_sel_hi:[1,0]
	v_pk_add_f32 v[164:165], v[164:165], 1.0 op_sel_hi:[1,0]
	v_pk_add_f32 v[166:167], v[166:167], 1.0 op_sel_hi:[1,0]
	v_pk_add_f32 v[168:169], v[168:169], 1.0 op_sel_hi:[1,0]
	v_pk_add_f32 v[170:171], v[170:171], 1.0 op_sel_hi:[1,0]
	v_pk_add_f32 v[172:173], v[172:173], 1.0 op_sel_hi:[1,0]
	v_pk_add_f32 v[174:175], v[174:175], 1.0 op_sel_hi:[1,0]
	v_pk_add_f32 v[192:193], v[192:193], 1.0 op_sel_hi:[1,0]
	v_pk_add_f32 v[194:195], v[194:195], 1.0 op_sel_hi:[1,0]
	v_pk_add_f32 v[196:197], v[196:197], 1.0 op_sel_hi:[1,0]
	v_pk_add_f32 v[198:199], v[198:199], 1.0 op_sel_hi:[1,0]
	v_pk_add_f32 v[200:201], v[200:201], 1.0 op_sel_hi:[1,0]
	v_pk_add_f32 v[202:203], v[202:203], 1.0 op_sel_hi:[1,0]
	v_pk_add_f32 v[204:205], v[204:205], 1.0 op_sel_hi:[1,0]
	v_pk_add_f32 v[206:207], v[206:207], 1.0 op_sel_hi:[1,0]
	s_add_u32 s38, s20, 0xa000000
	s_addc_u32 s39, s21, 0
	s_add_u32 s40, s20, 0xa400000
	s_addc_u32 s41, s21, 0
	s_add_u32 s46, s20, 0xa800000
	s_addc_u32 s47, s21, 0
	s_add_u32 s48, s20, 0xac00000
	s_addc_u32 s49, s21, 0
	v_pk_mul_f32 v[0:1], v[0:1], v[232:233] op_sel_hi:[1,0]
	v_pk_mul_f32 v[2:3], v[2:3], v[232:233] op_sel_hi:[1,0]
	v_pk_mul_f32 v[0:1], v[64:65], v[0:1]
	v_pk_mul_f32 v[2:3], v[66:67], v[2:3]
	v_pk_fma_f32 v[0:1], v[160:161], v[0:1], v[176:177]
	v_pk_fma_f32 v[2:3], v[162:163], v[2:3], v[178:179]
	v_cvt_pk_bf16_f32 v244, v0, v1
	v_cvt_pk_bf16_f32 v245, v2, v3
	v_pk_mul_f32 v[4:5], v[4:5], v[232:233] op_sel_hi:[1,0]
	v_pk_mul_f32 v[6:7], v[6:7], v[232:233] op_sel_hi:[1,0]
	v_pk_mul_f32 v[4:5], v[68:69], v[4:5]
	v_pk_mul_f32 v[6:7], v[70:71], v[6:7]
	v_pk_fma_f32 v[4:5], v[164:165], v[4:5], v[180:181]
	v_pk_fma_f32 v[6:7], v[166:167], v[6:7], v[182:183]
	v_cvt_pk_bf16_f32 v246, v4, v5
	v_cvt_pk_bf16_f32 v247, v6, v7
	global_store_dwordx4 v82, v[244:247], s[38:39] offset:0
	v_pk_mul_f32 v[8:9], v[8:9], v[232:233] op_sel_hi:[1,0]
	v_pk_mul_f32 v[10:11], v[10:11], v[232:233] op_sel_hi:[1,0]
	v_pk_mul_f32 v[8:9], v[72:73], v[8:9]
	v_pk_mul_f32 v[10:11], v[74:75], v[10:11]
	v_pk_fma_f32 v[8:9], v[168:169], v[8:9], v[184:185]
	v_pk_fma_f32 v[10:11], v[170:171], v[10:11], v[186:187]
	v_cvt_pk_bf16_f32 v240, v8, v9
	v_cvt_pk_bf16_f32 v241, v10, v11
	v_pk_mul_f32 v[12:13], v[12:13], v[232:233] op_sel_hi:[1,0]
	v_pk_mul_f32 v[14:15], v[14:15], v[232:233] op_sel_hi:[1,0]
	v_pk_mul_f32 v[12:13], v[76:77], v[12:13]
	v_pk_mul_f32 v[14:15], v[78:79], v[14:15]
	v_pk_fma_f32 v[12:13], v[172:173], v[12:13], v[188:189]
	v_pk_fma_f32 v[14:15], v[174:175], v[14:15], v[190:191]
	v_cvt_pk_bf16_f32 v242, v12, v13
	v_cvt_pk_bf16_f32 v243, v14, v15
	global_store_dwordx4 v82, v[240:243], s[38:39] offset:1024
	v_pk_mul_f32 v[16:17], v[16:17], v[234:235] op_sel_hi:[1,0]
	v_pk_mul_f32 v[18:19], v[18:19], v[234:235] op_sel_hi:[1,0]
	v_pk_mul_f32 v[16:17], v[64:65], v[16:17]
	v_pk_mul_f32 v[18:19], v[66:67], v[18:19]
	v_pk_fma_f32 v[16:17], v[160:161], v[16:17], v[176:177]
	v_pk_fma_f32 v[18:19], v[162:163], v[18:19], v[178:179]
	v_cvt_pk_bf16_f32 v244, v16, v17
	v_cvt_pk_bf16_f32 v245, v18, v19
	v_pk_mul_f32 v[20:21], v[20:21], v[234:235] op_sel_hi:[1,0]
	v_pk_mul_f32 v[22:23], v[22:23], v[234:235] op_sel_hi:[1,0]
	v_pk_mul_f32 v[20:21], v[68:69], v[20:21]
	v_pk_mul_f32 v[22:23], v[70:71], v[22:23]
	v_pk_fma_f32 v[20:21], v[164:165], v[20:21], v[180:181]
	v_pk_fma_f32 v[22:23], v[166:167], v[22:23], v[182:183]
	v_cvt_pk_bf16_f32 v246, v20, v21
	v_cvt_pk_bf16_f32 v247, v22, v23
	global_store_dwordx4 v82, v[244:247], s[40:41] offset:0
	v_pk_mul_f32 v[24:25], v[24:25], v[234:235] op_sel_hi:[1,0]
	v_pk_mul_f32 v[26:27], v[26:27], v[234:235] op_sel_hi:[1,0]
	v_pk_mul_f32 v[24:25], v[72:73], v[24:25]
	v_pk_mul_f32 v[26:27], v[74:75], v[26:27]
	v_pk_fma_f32 v[24:25], v[168:169], v[24:25], v[184:185]
	v_pk_fma_f32 v[26:27], v[170:171], v[26:27], v[186:187]
	v_cvt_pk_bf16_f32 v240, v24, v25
	v_cvt_pk_bf16_f32 v241, v26, v27
	v_pk_mul_f32 v[28:29], v[28:29], v[234:235] op_sel_hi:[1,0]
	v_pk_mul_f32 v[30:31], v[30:31], v[234:235] op_sel_hi:[1,0]
	v_pk_mul_f32 v[28:29], v[76:77], v[28:29]
	v_pk_mul_f32 v[30:31], v[78:79], v[30:31]
	v_pk_fma_f32 v[28:29], v[172:173], v[28:29], v[188:189]
	v_pk_fma_f32 v[30:31], v[174:175], v[30:31], v[190:191]
	v_cvt_pk_bf16_f32 v242, v28, v29
	v_cvt_pk_bf16_f32 v243, v30, v31
	global_store_dwordx4 v82, v[240:243], s[40:41] offset:1024
	v_pk_mul_f32 v[32:33], v[32:33], v[236:237] op_sel_hi:[1,0]
	v_pk_mul_f32 v[34:35], v[34:35], v[236:237] op_sel_hi:[1,0]
	v_pk_mul_f32 v[32:33], v[64:65], v[32:33]
	v_pk_mul_f32 v[34:35], v[66:67], v[34:35]
	v_pk_fma_f32 v[32:33], v[192:193], v[32:33], v[208:209]
	v_pk_fma_f32 v[34:35], v[194:195], v[34:35], v[210:211]
	v_cvt_pk_bf16_f32 v244, v32, v33
	v_cvt_pk_bf16_f32 v245, v34, v35
	v_pk_mul_f32 v[36:37], v[36:37], v[236:237] op_sel_hi:[1,0]
	v_pk_mul_f32 v[38:39], v[38:39], v[236:237] op_sel_hi:[1,0]
	v_pk_mul_f32 v[36:37], v[68:69], v[36:37]
	v_pk_mul_f32 v[38:39], v[70:71], v[38:39]
	v_pk_fma_f32 v[36:37], v[196:197], v[36:37], v[212:213]
	v_pk_fma_f32 v[38:39], v[198:199], v[38:39], v[214:215]
	v_cvt_pk_bf16_f32 v246, v36, v37
	v_cvt_pk_bf16_f32 v247, v38, v39
	global_store_dwordx4 v82, v[244:247], s[46:47] offset:0
	v_pk_mul_f32 v[40:41], v[40:41], v[236:237] op_sel_hi:[1,0]
	v_pk_mul_f32 v[42:43], v[42:43], v[236:237] op_sel_hi:[1,0]
	v_pk_mul_f32 v[40:41], v[72:73], v[40:41]
	v_pk_mul_f32 v[42:43], v[74:75], v[42:43]
	v_pk_fma_f32 v[40:41], v[200:201], v[40:41], v[216:217]
	v_pk_fma_f32 v[42:43], v[202:203], v[42:43], v[218:219]
	v_cvt_pk_bf16_f32 v240, v40, v41
; __device__ __forceinline__ unsigned pk2(float lo, float hi) { return pg8::cvt_pk_bf16(lo, hi); }
; template <bool BF> __device__ __forceinline__ void prep_rows(const float* xp, const float* xs, const bf16* hb, const float* g, const float* MOD, int shoff, int scoff, bf16* U, int gw, int NGW, int lane) {
;     ...
;         for (int r = 0; r < R; ++r) { float t = 0.f;
; #pragma unroll
;             for (int j = 0; j < 4; ++j) t += (v[r][j].x * v[r][j].x + v[r][j].y * v[r][j].y) + (v[r][j].z * v[r][j].z + v[r][j].w * v[r][j].w);
;             s[r] = t; }
; #pragma unroll
;         for (int o = 1; o < 64; o <<= 1) {
; #pragma unroll
;             for (int r = 0; r < R; ++r) s[r] += __shfl_xor(s[r], o); }
;     ...
; #pragma unroll
;             for (int j = 0; j < 4; ++j) { const int c = 4 * lane + 256 * j;
;                 const f32x4 gg = *(const f32x4*)(g + c), sc = *(const f32x4*)(mr + scoff + c), sh = *(const f32x4*)(mr + shoff + c);
;                 const f32x4 o = v[r][j] * rstd * gg * (sc + 1.0f) + sh; v2u w; w.x = pk2(o.x, o.y); w.y = pk2(o.z, o.w); *(v2u*)(U + (size_t)m * DM + c) = w; } } }
	v_cvt_pk_bf16_f32 v241, v42, v43
	v_pk_mul_f32 v[44:45], v[44:45], v[236:237] op_sel_hi:[1,0]
	v_pk_mul_f32 v[46:47], v[46:47], v[236:237] op_sel_hi:[1,0]
	v_pk_mul_f32 v[44:45], v[76:77], v[44:45]
	v_pk_mul_f32 v[46:47], v[78:79], v[46:47]
	v_pk_fma_f32 v[44:45], v[204:205], v[44:45], v[220:221]
	v_pk_fma_f32 v[46:47], v[206:207], v[46:47], v[222:223]
	v_cvt_pk_bf16_f32 v242, v44, v45
	v_cvt_pk_bf16_f32 v243, v46, v47
	global_store_dwordx4 v82, v[240:243], s[46:47] offset:1024
	v_pk_mul_f32 v[48:49], v[48:49], v[238:239] op_sel_hi:[1,0]
	v_pk_mul_f32 v[50:51], v[50:51], v[238:239] op_sel_hi:[1,0]
	v_pk_mul_f32 v[48:49], v[64:65], v[48:49]
	v_pk_mul_f32 v[50:51], v[66:67], v[50:51]
	v_pk_fma_f32 v[48:49], v[192:193], v[48:49], v[208:209]
	v_pk_fma_f32 v[50:51], v[194:195], v[50:51], v[210:211]
	v_cvt_pk_bf16_f32 v244, v48, v49
	v_cvt_pk_bf16_f32 v245, v50, v51
	v_pk_mul_f32 v[52:53], v[52:53], v[238:239] op_sel_hi:[1,0]
	v_pk_mul_f32 v[54:55], v[54:55], v[238:239] op_sel_hi:[1,0]
	v_pk_mul_f32 v[52:53], v[68:69], v[52:53]
	v_pk_mul_f32 v[54:55], v[70:71], v[54:55]
	v_pk_fma_f32 v[52:53], v[196:197], v[52:53], v[212:213]
	v_pk_fma_f32 v[54:55], v[198:199], v[54:55], v[214:215]
	v_cvt_pk_bf16_f32 v246, v52, v53
	v_cvt_pk_bf16_f32 v247, v54, v55
	global_store_dwordx4 v82, v[244:247], s[48:49] offset:0
	v_pk_mul_f32 v[56:57], v[56:57], v[238:239] op_sel_hi:[1,0]
	v_pk_mul_f32 v[58:59], v[58:59], v[238:239] op_sel_hi:[1,0]
	v_pk_mul_f32 v[56:57], v[72:73], v[56:57]
	v_pk_mul_f32 v[58:59], v[74:75], v[58:59]
	v_pk_fma_f32 v[56:57], v[200:201], v[56:57], v[216:217]
	v_pk_fma_f32 v[58:59], v[202:203], v[58:59], v[218:219]
	v_cvt_pk_bf16_f32 v240, v56, v57
	v_cvt_pk_bf16_f32 v241, v58, v59
	v_pk_mul_f32 v[60:61], v[60:61], v[238:239] op_sel_hi:[1,0]
	v_pk_mul_f32 v[62:63], v[62:63], v[238:239] op_sel_hi:[1,0]
	v_pk_mul_f32 v[60:61], v[76:77], v[60:61]
	v_pk_mul_f32 v[62:63], v[78:79], v[62:63]
	v_pk_fma_f32 v[60:61], v[204:205], v[60:61], v[220:221]
	v_pk_fma_f32 v[62:63], v[206:207], v[62:63], v[222:223]
	v_cvt_pk_bf16_f32 v242, v60, v61
	v_cvt_pk_bf16_f32 v243, v62, v63
	global_store_dwordx4 v82, v[240:243], s[48:49] offset:1024
	s_add_u32 s34, s8, 0x54000
	s_addc_u32 s35, s9, 0
	s_add_u32 s36, s8, 0x5a000
	s_addc_u32 s37, s9, 0
	global_load_dwordx4 v[176:179], v80, s[34:35] offset:0
	global_load_dwordx4 v[180:183], v80, s[34:35] offset:16
	global_load_dwordx4 v[184:187], v80, s[34:35] offset:2048
	global_load_dwordx4 v[188:191], v80, s[34:35] offset:2064
	global_load_dwordx4 v[160:163], v81, s[34:35] offset:0
	global_load_dwordx4 v[164:167], v81, s[34:35] offset:16
	global_load_dwordx4 v[168:171], v81, s[34:35] offset:2048
	global_load_dwordx4 v[172:175], v81, s[34:35] offset:2064
	global_load_dwordx4 v[208:211], v80, s[36:37] offset:0
	global_load_dwordx4 v[212:215], v80, s[36:37] offset:16
	global_load_dwordx4 v[216:219], v80, s[36:37] offset:2048
	global_load_dwordx4 v[220:223], v80, s[36:37] offset:2064
	global_load_dwordx4 v[192:195], v81, s[36:37] offset:0
	global_load_dwordx4 v[196:199], v81, s[36:37] offset:16
	global_load_dwordx4 v[200:203], v81, s[36:37] offset:2048
	global_load_dwordx4 v[204:207], v81, s[36:37] offset:2064
	s_waitcnt vmcnt(24)
	v_pk_mul_f32 v[240:241], v[96:97], v[96:97]
	v_pk_mul_f32 v[242:243], v[112:113], v[112:113]
	v_pk_mul_f32 v[244:245], v[128:129], v[128:129]
	v_pk_mul_f32 v[246:247], v[144:145], v[144:145]
	v_pk_fma_f32 v[240:241], v[98:99], v[98:99], v[240:241]
	v_pk_fma_f32 v[242:243], v[114:115], v[114:115], v[242:243]
	v_pk_fma_f32 v[244:245], v[130:131], v[130:131], v[244:245]
	v_pk_fma_f32 v[246:247], v[146:147], v[146:147], v[246:247]
	v_pk_fma_f32 v[240:241], v[100:101], v[100:101], v[240:241]
	v_pk_fma_f32 v[242:243], v[116:117], v[116:117], v[242:243]
	v_pk_fma_f32 v[244:245], v[132:133], v[132:133], v[244:245]
	v_pk_fma_f32 v[246:247], v[148:149], v[148:149], v[246:247]
	v_pk_fma_f32 v[240:241], v[102:103], v[102:103], v[240:241]
	v_pk_fma_f32 v[242:243], v[118:119], v[118:119], v[242:243]
	v_pk_fma_f32 v[244:245], v[134:135], v[134:135], v[244:245]
	v_pk_fma_f32 v[246:247], v[150:151], v[150:151], v[246:247]
	v_pk_fma_f32 v[240:241], v[104:105], v[104:105], v[240:241]
	v_pk_fma_f32 v[242:243], v[120:121], v[120:121], v[242:243]
	v_pk_fma_f32 v[244:245], v[136:137], v[136:137], v[244:245]
	v_pk_fma_f32 v[246:247], v[152:153], v[152:153], v[246:247]
	v_pk_fma_f32 v[240:241], v[106:107], v[106:107], v[240:241]
	v_pk_fma_f32 v[242:243], v[122:123], v[122:123], v[242:243]
	v_pk_fma_f32 v[244:245], v[138:139], v[138:139], v[244:245]
	v_pk_fma_f32 v[246:247], v[154:155], v[154:155], v[246:247]
	v_pk_fma_f32 v[240:241], v[108:109], v[108:109], v[240:241]
	v_pk_fma_f32 v[242:243], v[124:125], v[124:125], v[242:243]
	v_pk_fma_f32 v[244:245], v[140:141], v[140:141], v[244:245]
	v_pk_fma_f32 v[246:247], v[156:157], v[156:157], v[246:247]
	v_pk_fma_f32 v[240:241], v[110:111], v[110:111], v[240:241]
	v_pk_fma_f32 v[242:243], v[126:127], v[126:127], v[242:243]
	v_pk_fma_f32 v[244:245], v[142:143], v[142:143], v[244:245]
	v_pk_fma_f32 v[246:247], v[158:159], v[158:159], v[246:247]
	v_add_f32_e32 v224, v240, v241
	v_add_f32_e32 v225, v242, v243
	v_add_f32_e32 v226, v244, v245
	v_add_f32_e32 v227, v246, v247
	ds_bpermute_b32 v228, v83, v224
	ds_bpermute_b32 v229, v83, v225
	ds_bpermute_b32 v230, v83, v226
	ds_bpermute_b32 v231, v83, v227
	s_waitcnt lgkmcnt(0)
	v_add_f32_e32 v224, v224, v228
	v_add_f32_e32 v225, v225, v229
	v_add_f32_e32 v226, v226, v230
	v_add_f32_e32 v227, v227, v231
	ds_bpermute_b32 v228, v84, v224
	ds_bpermute_b32 v229, v84, v225
	ds_bpermute_b32 v230, v84, v226
	ds_bpermute_b32 v231, v84, v227
	s_waitcnt lgkmcnt(0)
; template <bool BF> __device__ __forceinline__ void prep_rows(const float* xp, const float* xs, const bf16* hb, const float* g, const float* MOD, int shoff, int scoff, bf16* U, int gw, int NGW, int lane) {
;     ...
;             for (int r = 0; r < R; ++r) s[r] += __shfl_xor(s[r], o); }
; #pragma unroll
;         for (int r = 0; r < R; ++r) { const int m = mb + r * NGW; if (m < MT) {
;             const float rstd = 1.0f / sqrtf(s[r] * (1.0f / DM) + RMS_EPS);
	v_add_f32_e32 v224, v224, v228
	v_add_f32_e32 v225, v225, v229
	v_add_f32_e32 v226, v226, v230
	v_add_f32_e32 v227, v227, v231
	ds_bpermute_b32 v228, v85, v224
	ds_bpermute_b32 v229, v85, v225
	ds_bpermute_b32 v230, v85, v226
	ds_bpermute_b32 v231, v85, v227
	s_waitcnt lgkmcnt(0)
	v_add_f32_e32 v224, v224, v228
	v_add_f32_e32 v225, v225, v229
	v_add_f32_e32 v226, v226, v230
	v_add_f32_e32 v227, v227, v231
	ds_bpermute_b32 v228, v86, v224
	ds_bpermute_b32 v229, v86, v225
	ds_bpermute_b32 v230, v86, v226
	ds_bpermute_b32 v231, v86, v227
	s_waitcnt lgkmcnt(0)
	v_add_f32_e32 v224, v224, v228
	v_add_f32_e32 v225, v225, v229
	v_add_f32_e32 v226, v226, v230
	v_add_f32_e32 v227, v227, v231
	ds_bpermute_b32 v228, v87, v224
	ds_bpermute_b32 v229, v87, v225
	ds_bpermute_b32 v230, v87, v226
	ds_bpermute_b32 v231, v87, v227
	s_waitcnt lgkmcnt(0)
	v_add_f32_e32 v224, v224, v228
	v_add_f32_e32 v225, v225, v229
	v_add_f32_e32 v226, v226, v230
	v_add_f32_e32 v227, v227, v231
	ds_bpermute_b32 v228, v88, v224
	ds_bpermute_b32 v229, v88, v225
	ds_bpermute_b32 v230, v88, v226
	ds_bpermute_b32 v231, v88, v227
	s_waitcnt lgkmcnt(0)
	v_add_f32_e32 v224, v224, v228
	v_add_f32_e32 v225, v225, v229
	v_add_f32_e32 v226, v226, v230
	v_add_f32_e32 v227, v227, v231
	v_fmamk_f32 v240, v224, 0x3a800000, v89
	v_mul_f32_e32 v241, 0x4f800000, v240
	v_cmp_gt_f32_e32 vcc, s54, v240
	s_nop 1
	v_cndmask_b32_e32 v247, v240, v241, vcc
	v_sqrt_f32_e32 v242, v247
	s_nop 1
	v_add_u32_e32 v243, -1, v242
	v_add_u32_e32 v244, 1, v242
	v_fma_f32 v245, -v243, v242, v247
	v_fma_f32 v246, -v244, v242, v247
	v_cmp_ge_f32_e64 s[52:53], 0, v245
	s_nop 1
	v_cndmask_b32_e64 v242, v242, v243, s[52:53]
	v_cmp_lt_f32_e64 s[52:53], 0, v246
	s_nop 1
	v_cndmask_b32_e64 v242, v242, v244, s[52:53]
	v_mul_f32_e32 v243, 0x37800000, v242
	v_cndmask_b32_e32 v242, v242, v243, vcc
	v_cmp_class_f32_e32 vcc, v247, v90
	s_nop 1
	v_cndmask_b32_e32 v247, v242, v247, vcc
	v_div_scale_f32 v248, s[52:53], v247, v247, 1.0
	v_rcp_f32_e32 v249, v248
	v_div_scale_f32 v228, vcc, 1.0, v247, 1.0
	s_nop 0
	v_fma_f32 v229, -v248, v249, 1.0
	v_fmac_f32_e32 v249, v229, v249
	v_mul_f32_e32 v230, v228, v249
	v_fma_f32 v229, -v248, v230, v228
	v_fmac_f32_e32 v230, v229, v249
	v_fma_f32 v248, -v248, v230, v228
	v_div_fmas_f32 v248, v248, v249, v230
	v_div_fixup_f32 v232, v248, v247, 1.0
	v_fmamk_f32 v240, v225, 0x3a800000, v89
	v_mul_f32_e32 v241, 0x4f800000, v240
	v_cmp_gt_f32_e32 vcc, s54, v240
	s_nop 1
	v_cndmask_b32_e32 v247, v240, v241, vcc
	v_sqrt_f32_e32 v242, v247
	s_nop 1
	v_add_u32_e32 v243, -1, v242
	v_add_u32_e32 v244, 1, v242
	v_fma_f32 v245, -v243, v242, v247
	v_fma_f32 v246, -v244, v242, v247
	v_cmp_ge_f32_e64 s[52:53], 0, v245
	s_nop 1
	v_cndmask_b32_e64 v242, v242, v243, s[52:53]
	v_cmp_lt_f32_e64 s[52:53], 0, v246
	s_nop 1
	v_cndmask_b32_e64 v242, v242, v244, s[52:53]
	v_mul_f32_e32 v243, 0x37800000, v242
	v_cndmask_b32_e32 v242, v242, v243, vcc
	v_cmp_class_f32_e32 vcc, v247, v90
	s_nop 1
	v_cndmask_b32_e32 v247, v242, v247, vcc
	v_div_scale_f32 v248, s[52:53], v247, v247, 1.0
	v_rcp_f32_e32 v249, v248
	v_div_scale_f32 v228, vcc, 1.0, v247, 1.0
	s_nop 0
	v_fma_f32 v229, -v248, v249, 1.0
	v_fmac_f32_e32 v249, v229, v249
	v_mul_f32_e32 v230, v228, v249
	v_fma_f32 v229, -v248, v230, v228
	v_fmac_f32_e32 v230, v229, v249
	v_fma_f32 v248, -v248, v230, v228
	v_div_fmas_f32 v248, v248, v249, v230
	v_div_fixup_f32 v234, v248, v247, 1.0
	v_fmamk_f32 v240, v226, 0x3a800000, v89
	v_mul_f32_e32 v241, 0x4f800000, v240
	v_cmp_gt_f32_e32 vcc, s54, v240
	s_nop 1
	v_cndmask_b32_e32 v247, v240, v241, vcc
	v_sqrt_f32_e32 v242, v247
	s_nop 1
	v_add_u32_e32 v243, -1, v242
	v_add_u32_e32 v244, 1, v242
	v_fma_f32 v245, -v243, v242, v247
	v_fma_f32 v246, -v244, v242, v247
	v_cmp_ge_f32_e64 s[52:53], 0, v245
	s_nop 1
	v_cndmask_b32_e64 v242, v242, v243, s[52:53]
	v_cmp_lt_f32_e64 s[52:53], 0, v246
	s_nop 1
	v_cndmask_b32_e64 v242, v242, v244, s[52:53]
	v_mul_f32_e32 v243, 0x37800000, v242
	v_cndmask_b32_e32 v242, v242, v243, vcc
	v_cmp_class_f32_e32 vcc, v247, v90
	s_nop 1
	v_cndmask_b32_e32 v247, v242, v247, vcc
	v_div_scale_f32 v248, s[52:53], v247, v247, 1.0
	v_rcp_f32_e32 v249, v248
	v_div_scale_f32 v228, vcc, 1.0, v247, 1.0
	s_nop 0
	v_fma_f32 v229, -v248, v249, 1.0
	v_fmac_f32_e32 v249, v229, v249
	v_mul_f32_e32 v230, v228, v249
	v_fma_f32 v229, -v248, v230, v228
	v_fmac_f32_e32 v230, v229, v249
	v_fma_f32 v248, -v248, v230, v228
	v_div_fmas_f32 v248, v248, v249, v230
	v_div_fixup_f32 v236, v248, v247, 1.0
	v_fmamk_f32 v240, v227, 0x3a800000, v89
	v_mul_f32_e32 v241, 0x4f800000, v240
	v_cmp_gt_f32_e32 vcc, s54, v240
	s_nop 1
	v_cndmask_b32_e32 v247, v240, v241, vcc
	v_sqrt_f32_e32 v242, v247
	s_nop 1
	v_add_u32_e32 v243, -1, v242
	v_add_u32_e32 v244, 1, v242
	v_fma_f32 v245, -v243, v242, v247
	v_fma_f32 v246, -v244, v242, v247
	v_cmp_ge_f32_e64 s[52:53], 0, v245
	s_nop 1
	v_cndmask_b32_e64 v242, v242, v243, s[52:53]
	v_cmp_lt_f32_e64 s[52:53], 0, v246
	s_nop 1
	v_cndmask_b32_e64 v242, v242, v244, s[52:53]
	v_mul_f32_e32 v243, 0x37800000, v242
	v_cndmask_b32_e32 v242, v242, v243, vcc
	v_cmp_class_f32_e32 vcc, v247, v90
	s_nop 1
	v_cndmask_b32_e32 v247, v242, v247, vcc
	v_div_scale_f32 v248, s[52:53], v247, v247, 1.0
	v_rcp_f32_e32 v249, v248
	v_div_scale_f32 v228, vcc, 1.0, v247, 1.0
	s_nop 0
	v_fma_f32 v229, -v248, v249, 1.0
	v_fmac_f32_e32 v249, v229, v249
	v_mul_f32_e32 v230, v228, v249
	v_fma_f32 v229, -v248, v230, v228
	v_fmac_f32_e32 v230, v229, v249
	v_fma_f32 v248, -v248, v230, v228
	v_div_fmas_f32 v248, v248, v249, v230
	v_div_fixup_f32 v238, v248, v247, 1.0
	s_waitcnt vmcnt(0)
; __device__ __forceinline__ unsigned pk2(float lo, float hi) { return pg8::cvt_pk_bf16(lo, hi); }
; template <bool BF> __device__ __forceinline__ void prep_rows(const float* xp, const float* xs, const bf16* hb, const float* g, const float* MOD, int shoff, int scoff, bf16* U, int gw, int NGW, int lane) {
;     ...
; #pragma unroll
;             for (int j = 0; j < 4; ++j) { const int c = 4 * lane + 256 * j;
;                 const f32x4 gg = *(const f32x4*)(g + c), sc = *(const f32x4*)(mr + scoff + c), sh = *(const f32x4*)(mr + shoff + c);
;                 const f32x4 o = v[r][j] * rstd * gg * (sc + 1.0f) + sh; v2u w; w.x = pk2(o.x, o.y); w.y = pk2(o.z, o.w); *(v2u*)(U + (size_t)m * DM + c) = w; } } }
	v_pk_add_f32 v[160:161], v[160:161], 1.0 op_sel_hi:[1,0]
	v_pk_add_f32 v[162:163], v[162:163], 1.0 op_sel_hi:[1,0]
	v_pk_add_f32 v[164:165], v[164:165], 1.0 op_sel_hi:[1,0]
	v_pk_add_f32 v[166:167], v[166:167], 1.0 op_sel_hi:[1,0]
	v_pk_add_f32 v[168:169], v[168:169], 1.0 op_sel_hi:[1,0]
	v_pk_add_f32 v[170:171], v[170:171], 1.0 op_sel_hi:[1,0]
	v_pk_add_f32 v[172:173], v[172:173], 1.0 op_sel_hi:[1,0]
	v_pk_add_f32 v[174:175], v[174:175], 1.0 op_sel_hi:[1,0]
	v_pk_add_f32 v[192:193], v[192:193], 1.0 op_sel_hi:[1,0]
	v_pk_add_f32 v[194:195], v[194:195], 1.0 op_sel_hi:[1,0]
	v_pk_add_f32 v[196:197], v[196:197], 1.0 op_sel_hi:[1,0]
	v_pk_add_f32 v[198:199], v[198:199], 1.0 op_sel_hi:[1,0]
	v_pk_add_f32 v[200:201], v[200:201], 1.0 op_sel_hi:[1,0]
	v_pk_add_f32 v[202:203], v[202:203], 1.0 op_sel_hi:[1,0]
	v_pk_add_f32 v[204:205], v[204:205], 1.0 op_sel_hi:[1,0]
	v_pk_add_f32 v[206:207], v[206:207], 1.0 op_sel_hi:[1,0]
	s_add_u32 s38, s20, 0xb000000
	s_addc_u32 s39, s21, 0
	s_add_u32 s40, s20, 0xb400000
	s_addc_u32 s41, s21, 0
	s_add_u32 s46, s20, 0xb800000
	s_addc_u32 s47, s21, 0
	s_add_u32 s48, s20, 0xbc00000
	s_addc_u32 s49, s21, 0
	v_pk_mul_f32 v[96:97], v[96:97], v[232:233] op_sel_hi:[1,0]
	v_pk_mul_f32 v[98:99], v[98:99], v[232:233] op_sel_hi:[1,0]
	v_pk_mul_f32 v[96:97], v[64:65], v[96:97]
	v_pk_mul_f32 v[98:99], v[66:67], v[98:99]
	v_pk_fma_f32 v[96:97], v[160:161], v[96:97], v[176:177]
	v_pk_fma_f32 v[98:99], v[162:163], v[98:99], v[178:179]
	v_cvt_pk_bf16_f32 v244, v96, v97
	v_cvt_pk_bf16_f32 v245, v98, v99
	v_pk_mul_f32 v[100:101], v[100:101], v[232:233] op_sel_hi:[1,0]
	v_pk_mul_f32 v[102:103], v[102:103], v[232:233] op_sel_hi:[1,0]
	v_pk_mul_f32 v[100:101], v[68:69], v[100:101]
	v_pk_mul_f32 v[102:103], v[70:71], v[102:103]
	v_pk_fma_f32 v[100:101], v[164:165], v[100:101], v[180:181]
	v_pk_fma_f32 v[102:103], v[166:167], v[102:103], v[182:183]
	v_cvt_pk_bf16_f32 v246, v100, v101
	v_cvt_pk_bf16_f32 v247, v102, v103
	global_store_dwordx4 v82, v[244:247], s[38:39] offset:0
	v_pk_mul_f32 v[104:105], v[104:105], v[232:233] op_sel_hi:[1,0]
	v_pk_mul_f32 v[106:107], v[106:107], v[232:233] op_sel_hi:[1,0]
	v_pk_mul_f32 v[104:105], v[72:73], v[104:105]
	v_pk_mul_f32 v[106:107], v[74:75], v[106:107]
	v_pk_fma_f32 v[104:105], v[168:169], v[104:105], v[184:185]
	v_pk_fma_f32 v[106:107], v[170:171], v[106:107], v[186:187]
	v_cvt_pk_bf16_f32 v240, v104, v105
	v_cvt_pk_bf16_f32 v241, v106, v107
	v_pk_mul_f32 v[108:109], v[108:109], v[232:233] op_sel_hi:[1,0]
	v_pk_mul_f32 v[110:111], v[110:111], v[232:233] op_sel_hi:[1,0]
	v_pk_mul_f32 v[108:109], v[76:77], v[108:109]
	v_pk_mul_f32 v[110:111], v[78:79], v[110:111]
	v_pk_fma_f32 v[108:109], v[172:173], v[108:109], v[188:189]
	v_pk_fma_f32 v[110:111], v[174:175], v[110:111], v[190:191]
	v_cvt_pk_bf16_f32 v242, v108, v109
	v_cvt_pk_bf16_f32 v243, v110, v111
	global_store_dwordx4 v82, v[240:243], s[38:39] offset:1024
	v_pk_mul_f32 v[112:113], v[112:113], v[234:235] op_sel_hi:[1,0]
	v_pk_mul_f32 v[114:115], v[114:115], v[234:235] op_sel_hi:[1,0]
	v_pk_mul_f32 v[112:113], v[64:65], v[112:113]
	v_pk_mul_f32 v[114:115], v[66:67], v[114:115]
	v_pk_fma_f32 v[112:113], v[160:161], v[112:113], v[176:177]
	v_pk_fma_f32 v[114:115], v[162:163], v[114:115], v[178:179]
	v_cvt_pk_bf16_f32 v244, v112, v113
	v_cvt_pk_bf16_f32 v245, v114, v115
	v_pk_mul_f32 v[116:117], v[116:117], v[234:235] op_sel_hi:[1,0]
	v_pk_mul_f32 v[118:119], v[118:119], v[234:235] op_sel_hi:[1,0]
	v_pk_mul_f32 v[116:117], v[68:69], v[116:117]
	v_pk_mul_f32 v[118:119], v[70:71], v[118:119]
	v_pk_fma_f32 v[116:117], v[164:165], v[116:117], v[180:181]
	v_pk_fma_f32 v[118:119], v[166:167], v[118:119], v[182:183]
	v_cvt_pk_bf16_f32 v246, v116, v117
	v_cvt_pk_bf16_f32 v247, v118, v119
	global_store_dwordx4 v82, v[244:247], s[40:41] offset:0
	v_pk_mul_f32 v[120:121], v[120:121], v[234:235] op_sel_hi:[1,0]
	v_pk_mul_f32 v[122:123], v[122:123], v[234:235] op_sel_hi:[1,0]
	v_pk_mul_f32 v[120:121], v[72:73], v[120:121]
	v_pk_mul_f32 v[122:123], v[74:75], v[122:123]
	v_pk_fma_f32 v[120:121], v[168:169], v[120:121], v[184:185]
	v_pk_fma_f32 v[122:123], v[170:171], v[122:123], v[186:187]
; __device__ __forceinline__ unsigned pk2(float lo, float hi) { return pg8::cvt_pk_bf16(lo, hi); }
; template <bool BF> __device__ __forceinline__ void prep_rows(const float* xp, const float* xs, const bf16* hb, const float* g, const float* MOD, int shoff, int scoff, bf16* U, int gw, int NGW, int lane) {
;     ...
; #pragma unroll
;             for (int j = 0; j < 4; ++j) { const int c = 4 * lane + 256 * j;
;                 const f32x4 gg = *(const f32x4*)(g + c), sc = *(const f32x4*)(mr + scoff + c), sh = *(const f32x4*)(mr + shoff + c);
;                 const f32x4 o = v[r][j] * rstd * gg * (sc + 1.0f) + sh; v2u w; w.x = pk2(o.x, o.y); w.y = pk2(o.z, o.w); *(v2u*)(U + (size_t)m * DM + c) = w; } } }
	v_cvt_pk_bf16_f32 v240, v120, v121
	v_cvt_pk_bf16_f32 v241, v122, v123
	v_pk_mul_f32 v[124:125], v[124:125], v[234:235] op_sel_hi:[1,0]
	v_pk_mul_f32 v[126:127], v[126:127], v[234:235] op_sel_hi:[1,0]
	v_pk_mul_f32 v[124:125], v[76:77], v[124:125]
	v_pk_mul_f32 v[126:127], v[78:79], v[126:127]
	v_pk_fma_f32 v[124:125], v[172:173], v[124:125], v[188:189]
	v_pk_fma_f32 v[126:127], v[174:175], v[126:127], v[190:191]
	v_cvt_pk_bf16_f32 v242, v124, v125
	v_cvt_pk_bf16_f32 v243, v126, v127
	global_store_dwordx4 v82, v[240:243], s[40:41] offset:1024
	v_pk_mul_f32 v[128:129], v[128:129], v[236:237] op_sel_hi:[1,0]
	v_pk_mul_f32 v[130:131], v[130:131], v[236:237] op_sel_hi:[1,0]
	v_pk_mul_f32 v[128:129], v[64:65], v[128:129]
	v_pk_mul_f32 v[130:131], v[66:67], v[130:131]
	v_pk_fma_f32 v[128:129], v[192:193], v[128:129], v[208:209]
	v_pk_fma_f32 v[130:131], v[194:195], v[130:131], v[210:211]
	v_cvt_pk_bf16_f32 v244, v128, v129
	v_cvt_pk_bf16_f32 v245, v130, v131
	v_pk_mul_f32 v[132:133], v[132:133], v[236:237] op_sel_hi:[1,0]
	v_pk_mul_f32 v[134:135], v[134:135], v[236:237] op_sel_hi:[1,0]
	v_pk_mul_f32 v[132:133], v[68:69], v[132:133]
	v_pk_mul_f32 v[134:135], v[70:71], v[134:135]
	v_pk_fma_f32 v[132:133], v[196:197], v[132:133], v[212:213]
	v_pk_fma_f32 v[134:135], v[198:199], v[134:135], v[214:215]
	v_cvt_pk_bf16_f32 v246, v132, v133
	v_cvt_pk_bf16_f32 v247, v134, v135
	global_store_dwordx4 v82, v[244:247], s[46:47] offset:0
	v_pk_mul_f32 v[136:137], v[136:137], v[236:237] op_sel_hi:[1,0]
	v_pk_mul_f32 v[138:139], v[138:139], v[236:237] op_sel_hi:[1,0]
	v_pk_mul_f32 v[136:137], v[72:73], v[136:137]
	v_pk_mul_f32 v[138:139], v[74:75], v[138:139]
	v_pk_fma_f32 v[136:137], v[200:201], v[136:137], v[216:217]
	v_pk_fma_f32 v[138:139], v[202:203], v[138:139], v[218:219]
	v_cvt_pk_bf16_f32 v240, v136, v137
	v_cvt_pk_bf16_f32 v241, v138, v139
	v_pk_mul_f32 v[140:141], v[140:141], v[236:237] op_sel_hi:[1,0]
	v_pk_mul_f32 v[142:143], v[142:143], v[236:237] op_sel_hi:[1,0]
	v_pk_mul_f32 v[140:141], v[76:77], v[140:141]
	v_pk_mul_f32 v[142:143], v[78:79], v[142:143]
	v_pk_fma_f32 v[140:141], v[204:205], v[140:141], v[220:221]
	v_pk_fma_f32 v[142:143], v[206:207], v[142:143], v[222:223]
	v_cvt_pk_bf16_f32 v242, v140, v141
	v_cvt_pk_bf16_f32 v243, v142, v143
	global_store_dwordx4 v82, v[240:243], s[46:47] offset:1024
	v_pk_mul_f32 v[144:145], v[144:145], v[238:239] op_sel_hi:[1,0]
	v_pk_mul_f32 v[146:147], v[146:147], v[238:239] op_sel_hi:[1,0]
	v_pk_mul_f32 v[144:145], v[64:65], v[144:145]
	v_pk_mul_f32 v[146:147], v[66:67], v[146:147]
	v_pk_fma_f32 v[144:145], v[192:193], v[144:145], v[208:209]
	v_pk_fma_f32 v[146:147], v[194:195], v[146:147], v[210:211]
	v_cvt_pk_bf16_f32 v244, v144, v145
	v_cvt_pk_bf16_f32 v245, v146, v147
	v_pk_mul_f32 v[148:149], v[148:149], v[238:239] op_sel_hi:[1,0]
	v_pk_mul_f32 v[150:151], v[150:151], v[238:239] op_sel_hi:[1,0]
	v_pk_mul_f32 v[148:149], v[68:69], v[148:149]
	v_pk_mul_f32 v[150:151], v[70:71], v[150:151]
	v_pk_fma_f32 v[148:149], v[196:197], v[148:149], v[212:213]
	v_pk_fma_f32 v[150:151], v[198:199], v[150:151], v[214:215]
	v_cvt_pk_bf16_f32 v246, v148, v149
	v_cvt_pk_bf16_f32 v247, v150, v151
	global_store_dwordx4 v82, v[244:247], s[48:49] offset:0
	v_pk_mul_f32 v[152:153], v[152:153], v[238:239] op_sel_hi:[1,0]
	v_pk_mul_f32 v[154:155], v[154:155], v[238:239] op_sel_hi:[1,0]
	v_pk_mul_f32 v[152:153], v[72:73], v[152:153]
	v_pk_mul_f32 v[154:155], v[74:75], v[154:155]
	v_pk_fma_f32 v[152:153], v[200:201], v[152:153], v[216:217]
	v_pk_fma_f32 v[154:155], v[202:203], v[154:155], v[218:219]
	v_cvt_pk_bf16_f32 v240, v152, v153
	v_cvt_pk_bf16_f32 v241, v154, v155
	v_pk_mul_f32 v[156:157], v[156:157], v[238:239] op_sel_hi:[1,0]
	v_pk_mul_f32 v[158:159], v[158:159], v[238:239] op_sel_hi:[1,0]
	v_pk_mul_f32 v[156:157], v[76:77], v[156:157]
	v_pk_mul_f32 v[158:159], v[78:79], v[158:159]
	v_pk_fma_f32 v[156:157], v[204:205], v[156:157], v[220:221]
	v_pk_fma_f32 v[158:159], v[206:207], v[158:159], v[222:223]
	v_cvt_pk_bf16_f32 v242, v156, v157
	v_cvt_pk_bf16_f32 v243, v158, v159
	global_store_dwordx4 v82, v[240:243], s[48:49] offset:1024
	s_branch .LBB0_116

; __device__ __forceinline__ float bf_lo(unsigned w) { return __uint_as_float(w << 16); }
; __device__ __forceinline__ float bf_hi(unsigned w) { return __uint_as_float(w & 0xffff0000u); }
; #define PH_IDS() const int tid = lnd((int)threadIdx.x), lane = tid & 63, wave = __builtin_amdgcn_readfirstlane(tid >> 6), gw = bid * 8 + wave; (void)lane; (void)gw
; #define REPS(k) for (int rep_ = 0; rep_ < (((REP_MASK >> (k)) & 1) ? 2 : 1); ++rep_)
; template <bool BF> __device__ __forceinline__ void prep_rows(const float* xp, const float* xs, const bf16* hb, const float* g, const float* MOD, int shoff, int scoff, bf16* U, int gw, int NGW, int lane) {
;     ...
;     for (int mb = gw; mb < MT; mb += R * NGW) {
;         f32x4 v[R][4]; float s[R];
; #pragma unroll
;         for (int r = 0; r < R; ++r) { const int m = mb + r * NGW; const int mc = m < MT ? m : mb;
; #pragma unroll
;             for (int j = 0; j < 4; ++j) {
;                 if (BF) { const v2u a0 = *(const v2u*)(hb + (size_t)mc * DM + 4 * lane + 256 * j);
;                     v[r][j].x = pg8::bf_lo(a0.x); v[r][j].y = pg8::bf_hi(a0.x); v[r][j].z = pg8::bf_lo(a0.y); v[r][j].w = pg8::bf_hi(a0.y); }
;                 else { const float* xr = mc < MP ? xp + (size_t)mc * DM : xs + (size_t)(mc - MP) * DM; v[r][j] = *(const f32x4*)(xr + 4 * lane + 256 * j); } } }
; template <int PHM> __global__ void __launch_bounds__(512, 2) mk_fwd(Args karg) {
;     ...
;     if (IN(11)) REPS(11) { PH_ARGS(); PH_IDS(); prep_rows<true>(nullptr, nullptr, (const bf16*)(ws + WS_H16), a.in[I_N2G], MOD, 3072, 4096, (bf16*)(ws + WS_U2), gw, NGW, lane); }
.LBB0_1168:
	s_cmp_lt_i32 s78, 12
	s_cselect_b64 s[0:1], -1, 0
	s_and_b64 s[0:1], s[0:1], s[4:5]
	s_andn2_b64 vcc, exec, s[0:1]
	s_cbranch_vccnz .LBB0_1178
	s_mov_b64 s[2:3], s[72:73]
	s_waitcnt vmcnt(0)
	v_mov_b32_e32 v8, v254
	s_lshl_b32 s6, s96, 3
	v_readfirstlane_b32 s4, v8
	s_ashr_i32 s7, s4, 6
	s_add_i32 s26, s7, s6
	s_cmp_gt_i32 s26, 0x17fff
	s_cbranch_scc1 .LBB0_1178
	s_cmp_eq_u32 s70, 0x100
	s_cbranch_scc0 .Lorig_prep11
	s_load_dwordx2 s[6:7], s[72:73], 0xc8
	s_load_dwordx2 s[8:9], s[72:73], 0xe8
	v_and_b32_e32 v82, 63, v254
	v_lshlrev_b32_e32 v80, 5, v82
	v_add_u32_e32 v81, 0x1000, v80
	v_xor_b32_e32 v83, 1, v82
	v_xor_b32_e32 v84, 2, v82
	v_xor_b32_e32 v85, 4, v82
	v_xor_b32_e32 v86, 8, v82
	v_xor_b32_e32 v87, 16, v82
	v_xor_b32_e32 v88, 32, v82
	v_lshlrev_b32_e32 v83, 2, v83
	v_lshlrev_b32_e32 v84, 2, v84
	v_lshlrev_b32_e32 v85, 2, v85
	v_lshlrev_b32_e32 v86, 2, v86
	v_lshlrev_b32_e32 v87, 2, v87
	v_lshlrev_b32_e32 v88, 2, v88
	v_lshlrev_b32_e32 v82, 4, v82
	v_mov_b32_e32 v89, 0x358637bd
	v_mov_b32_e32 v90, 0x260
	s_mov_b32 s54, 0xf800000
	v_readfirstlane_b32 s45, v254
	s_nop 3
	s_lshl_b32 s50, s96, 3
	s_lshr_b32 s45, s45, 6
	s_add_i32 s45, s45, s50
	s_waitcnt lgkmcnt(0)
	s_lshl_b32 s50, s45, 11
	s_add_u32 s16, s8, s50
	s_addc_u32 s17, s9, 0
	s_add_u32 s16, s16, 0xf000000
	s_addc_u32 s17, s17, 0
	s_add_u32 s20, s8, s50
	s_addc_u32 s21, s9, 0
	s_add_u32 s20, s20, 0x33000000
	s_addc_u32 s21, s21, 0
	global_load_dwordx4 v[64:67], v80, s[6:7] offset:0
	global_load_dwordx4 v[68:71], v80, s[6:7] offset:16
	global_load_dwordx4 v[72:75], v80, s[6:7] offset:2048
	global_load_dwordx4 v[76:79], v80, s[6:7] offset:2064
	s_mov_b64 s[24:25], s[16:17]
	s_add_u32 s26, s16, 0x400000
	s_addc_u32 s27, s17, 0
	s_add_u32 s28, s16, 0x800000
	s_addc_u32 s29, s17, 0
	s_add_u32 s30, s16, 0xc00000
	s_addc_u32 s31, s17, 0
	global_load_dwordx4 v[96:99], v82, s[24:25] offset:0 nt
	global_load_dwordx4 v[100:103], v82, s[24:25] offset:1024 nt
	global_load_dwordx4 v[104:107], v82, s[26:27] offset:0 nt
	global_load_dwordx4 v[108:111], v82, s[26:27] offset:1024 nt
	global_load_dwordx4 v[112:115], v82, s[28:29] offset:0 nt
	global_load_dwordx4 v[116:119], v82, s[28:29] offset:1024 nt
	global_load_dwordx4 v[120:123], v82, s[30:31] offset:0 nt
	global_load_dwordx4 v[124:127], v82, s[30:31] offset:1024 nt
	s_add_u32 s34, s8, 0x3000
	s_addc_u32 s35, s9, 0
	s_add_u32 s36, s8, 0x3000
	s_addc_u32 s37, s9, 0
	global_load_dwordx4 v[176:179], v80, s[34:35] offset:0
	global_load_dwordx4 v[180:183], v80, s[34:35] offset:16
	global_load_dwordx4 v[184:187], v80, s[34:35] offset:2048
	global_load_dwordx4 v[188:191], v80, s[34:35] offset:2064
	global_load_dwordx4 v[160:163], v81, s[34:35] offset:0
	global_load_dwordx4 v[164:167], v81, s[34:35] offset:16
	global_load_dwordx4 v[168:171], v81, s[34:35] offset:2048
	global_load_dwordx4 v[172:175], v81, s[34:35] offset:2064
	global_load_dwordx4 v[208:211], v80, s[36:37] offset:0
	global_load_dwordx4 v[212:215], v80, s[36:37] offset:16
	global_load_dwordx4 v[216:219], v80, s[36:37] offset:2048
	global_load_dwordx4 v[220:223], v80, s[36:37] offset:2064
	global_load_dwordx4 v[192:195], v81, s[36:37] offset:0
	global_load_dwordx4 v[196:199], v81, s[36:37] offset:16
	global_load_dwordx4 v[200:203], v81, s[36:37] offset:2048
	global_load_dwordx4 v[204:207], v81, s[36:37] offset:2064
	s_add_u32 s24, s16, 0x1000000
	s_addc_u32 s25, s17, 0
	s_add_u32 s26, s16, 0x1400000
	s_addc_u32 s27, s17, 0
	s_add_u32 s28, s16, 0x1800000
	s_addc_u32 s29, s17, 0
	s_add_u32 s30, s16, 0x1c00000
	s_addc_u32 s31, s17, 0
	global_load_dwordx4 v[128:131], v82, s[24:25] offset:0 nt
	global_load_dwordx4 v[132:135], v82, s[24:25] offset:1024 nt
	global_load_dwordx4 v[136:139], v82, s[26:27] offset:0 nt
	global_load_dwordx4 v[140:143], v82, s[26:27] offset:1024 nt
	global_load_dwordx4 v[144:147], v82, s[28:29] offset:0 nt
	global_load_dwordx4 v[148:151], v82, s[28:29] offset:1024 nt
	global_load_dwordx4 v[152:155], v82, s[30:31] offset:0 nt
	global_load_dwordx4 v[156:159], v82, s[30:31] offset:1024 nt
	s_waitcnt vmcnt(24)
	v_lshlrev_b32_e32 v0, 16, v96
	v_and_b32_e32 v1, 0xffff0000, v96
	v_lshlrev_b32_e32 v2, 16, v97
	v_and_b32_e32 v3, 0xffff0000, v97
	v_lshlrev_b32_e32 v4, 16, v98
	v_and_b32_e32 v5, 0xffff0000, v98
	v_lshlrev_b32_e32 v6, 16, v99
	v_and_b32_e32 v7, 0xffff0000, v99
	v_lshlrev_b32_e32 v8, 16, v100
	v_and_b32_e32 v9, 0xffff0000, v100
	v_lshlrev_b32_e32 v10, 16, v101
	v_and_b32_e32 v11, 0xffff0000, v101
	v_lshlrev_b32_e32 v12, 16, v102
	v_and_b32_e32 v13, 0xffff0000, v102
	v_lshlrev_b32_e32 v14, 16, v103
	v_and_b32_e32 v15, 0xffff0000, v103
	v_lshlrev_b32_e32 v16, 16, v104
	v_and_b32_e32 v17, 0xffff0000, v104
	v_lshlrev_b32_e32 v18, 16, v105
	v_and_b32_e32 v19, 0xffff0000, v105
	v_lshlrev_b32_e32 v20, 16, v106
	v_and_b32_e32 v21, 0xffff0000, v106
	v_lshlrev_b32_e32 v22, 16, v107
	v_and_b32_e32 v23, 0xffff0000, v107
	v_lshlrev_b32_e32 v24, 16, v108
	v_and_b32_e32 v25, 0xffff0000, v108
	v_lshlrev_b32_e32 v26, 16, v109
	v_and_b32_e32 v27, 0xffff0000, v109
	v_lshlrev_b32_e32 v28, 16, v110
	v_and_b32_e32 v29, 0xffff0000, v110
	v_lshlrev_b32_e32 v30, 16, v111
	v_and_b32_e32 v31, 0xffff0000, v111
	v_lshlrev_b32_e32 v32, 16, v112
	v_and_b32_e32 v33, 0xffff0000, v112
	v_lshlrev_b32_e32 v34, 16, v113
	v_and_b32_e32 v35, 0xffff0000, v113
	v_lshlrev_b32_e32 v36, 16, v114
	v_and_b32_e32 v37, 0xffff0000, v114
	v_lshlrev_b32_e32 v38, 16, v115
	v_and_b32_e32 v39, 0xffff0000, v115
	v_lshlrev_b32_e32 v40, 16, v116
	v_and_b32_e32 v41, 0xffff0000, v116
	v_lshlrev_b32_e32 v42, 16, v117
	v_and_b32_e32 v43, 0xffff0000, v117
	v_lshlrev_b32_e32 v44, 16, v118
; __device__ __forceinline__ float bf_lo(unsigned w) { return __uint_as_float(w << 16); }
; __device__ __forceinline__ float bf_hi(unsigned w) { return __uint_as_float(w & 0xffff0000u); }
; template <bool BF> __device__ __forceinline__ void prep_rows(const float* xp, const float* xs, const bf16* hb, const float* g, const float* MOD, int shoff, int scoff, bf16* U, int gw, int NGW, int lane) {
;     ...
;                 if (BF) { const v2u a0 = *(const v2u*)(hb + (size_t)mc * DM + 4 * lane + 256 * j);
;                     v[r][j].x = pg8::bf_lo(a0.x); v[r][j].y = pg8::bf_hi(a0.x); v[r][j].z = pg8::bf_lo(a0.y); v[r][j].w = pg8::bf_hi(a0.y); }
;                 else { const float* xr = mc < MP ? xp + (size_t)mc * DM : xs + (size_t)(mc - MP) * DM; v[r][j] = *(const f32x4*)(xr + 4 * lane + 256 * j); } } }
; #pragma unroll
;         for (int r = 0; r < R; ++r) { float t = 0.f;
; #pragma unroll
;             for (int j = 0; j < 4; ++j) t += (v[r][j].x * v[r][j].x + v[r][j].y * v[r][j].y) + (v[r][j].z * v[r][j].z + v[r][j].w * v[r][j].w);
;             s[r] = t; }
; #pragma unroll
;         for (int o = 1; o < 64; o <<= 1) {
; #pragma unroll
;             for (int r = 0; r < R; ++r) s[r] += __shfl_xor(s[r], o); }
; #pragma unroll
;         for (int r = 0; r < R; ++r) { const int m = mb + r * NGW; if (m < MT) {
;             const float rstd = 1.0f / sqrtf(s[r] * (1.0f / DM) + RMS_EPS);
	v_and_b32_e32 v45, 0xffff0000, v118
	v_lshlrev_b32_e32 v46, 16, v119
	v_and_b32_e32 v47, 0xffff0000, v119
	v_lshlrev_b32_e32 v48, 16, v120
	v_and_b32_e32 v49, 0xffff0000, v120
	v_lshlrev_b32_e32 v50, 16, v121
	v_and_b32_e32 v51, 0xffff0000, v121
	v_lshlrev_b32_e32 v52, 16, v122
	v_and_b32_e32 v53, 0xffff0000, v122
	v_lshlrev_b32_e32 v54, 16, v123
	v_and_b32_e32 v55, 0xffff0000, v123
	v_lshlrev_b32_e32 v56, 16, v124
	v_and_b32_e32 v57, 0xffff0000, v124
	v_lshlrev_b32_e32 v58, 16, v125
	v_and_b32_e32 v59, 0xffff0000, v125
	v_lshlrev_b32_e32 v60, 16, v126
	v_and_b32_e32 v61, 0xffff0000, v126
	v_lshlrev_b32_e32 v62, 16, v127
	v_and_b32_e32 v63, 0xffff0000, v127
	v_pk_mul_f32 v[240:241], v[0:1], v[0:1]
	v_pk_mul_f32 v[242:243], v[16:17], v[16:17]
	v_pk_mul_f32 v[244:245], v[32:33], v[32:33]
	v_pk_mul_f32 v[246:247], v[48:49], v[48:49]
	v_pk_fma_f32 v[240:241], v[2:3], v[2:3], v[240:241]
	v_pk_fma_f32 v[242:243], v[18:19], v[18:19], v[242:243]
	v_pk_fma_f32 v[244:245], v[34:35], v[34:35], v[244:245]
	v_pk_fma_f32 v[246:247], v[50:51], v[50:51], v[246:247]
	v_pk_fma_f32 v[240:241], v[4:5], v[4:5], v[240:241]
	v_pk_fma_f32 v[242:243], v[20:21], v[20:21], v[242:243]
	v_pk_fma_f32 v[244:245], v[36:37], v[36:37], v[244:245]
	v_pk_fma_f32 v[246:247], v[52:53], v[52:53], v[246:247]
	v_pk_fma_f32 v[240:241], v[6:7], v[6:7], v[240:241]
	v_pk_fma_f32 v[242:243], v[22:23], v[22:23], v[242:243]
	v_pk_fma_f32 v[244:245], v[38:39], v[38:39], v[244:245]
	v_pk_fma_f32 v[246:247], v[54:55], v[54:55], v[246:247]
	v_pk_fma_f32 v[240:241], v[8:9], v[8:9], v[240:241]
	v_pk_fma_f32 v[242:243], v[24:25], v[24:25], v[242:243]
	v_pk_fma_f32 v[244:245], v[40:41], v[40:41], v[244:245]
	v_pk_fma_f32 v[246:247], v[56:57], v[56:57], v[246:247]
	v_pk_fma_f32 v[240:241], v[10:11], v[10:11], v[240:241]
	v_pk_fma_f32 v[242:243], v[26:27], v[26:27], v[242:243]
	v_pk_fma_f32 v[244:245], v[42:43], v[42:43], v[244:245]
	v_pk_fma_f32 v[246:247], v[58:59], v[58:59], v[246:247]
	v_pk_fma_f32 v[240:241], v[12:13], v[12:13], v[240:241]
	v_pk_fma_f32 v[242:243], v[28:29], v[28:29], v[242:243]
	v_pk_fma_f32 v[244:245], v[44:45], v[44:45], v[244:245]
	v_pk_fma_f32 v[246:247], v[60:61], v[60:61], v[246:247]
	v_pk_fma_f32 v[240:241], v[14:15], v[14:15], v[240:241]
	v_pk_fma_f32 v[242:243], v[30:31], v[30:31], v[242:243]
	v_pk_fma_f32 v[244:245], v[46:47], v[46:47], v[244:245]
	v_pk_fma_f32 v[246:247], v[62:63], v[62:63], v[246:247]
	v_add_f32_e32 v224, v240, v241
	v_add_f32_e32 v225, v242, v243
	v_add_f32_e32 v226, v244, v245
	v_add_f32_e32 v227, v246, v247
	ds_bpermute_b32 v228, v83, v224
	ds_bpermute_b32 v229, v83, v225
	ds_bpermute_b32 v230, v83, v226
	ds_bpermute_b32 v231, v83, v227
	s_waitcnt lgkmcnt(0)
	v_add_f32_e32 v224, v224, v228
	v_add_f32_e32 v225, v225, v229
	v_add_f32_e32 v226, v226, v230
	v_add_f32_e32 v227, v227, v231
	ds_bpermute_b32 v228, v84, v224
	ds_bpermute_b32 v229, v84, v225
	ds_bpermute_b32 v230, v84, v226
	ds_bpermute_b32 v231, v84, v227
	s_waitcnt lgkmcnt(0)
	v_add_f32_e32 v224, v224, v228
	v_add_f32_e32 v225, v225, v229
	v_add_f32_e32 v226, v226, v230
	v_add_f32_e32 v227, v227, v231
	ds_bpermute_b32 v228, v85, v224
	ds_bpermute_b32 v229, v85, v225
	ds_bpermute_b32 v230, v85, v226
	ds_bpermute_b32 v231, v85, v227
	s_waitcnt lgkmcnt(0)
	v_add_f32_e32 v224, v224, v228
	v_add_f32_e32 v225, v225, v229
	v_add_f32_e32 v226, v226, v230
	v_add_f32_e32 v227, v227, v231
	ds_bpermute_b32 v228, v86, v224
	ds_bpermute_b32 v229, v86, v225
	ds_bpermute_b32 v230, v86, v226
	ds_bpermute_b32 v231, v86, v227
	s_waitcnt lgkmcnt(0)
	v_add_f32_e32 v224, v224, v228
	v_add_f32_e32 v225, v225, v229
	v_add_f32_e32 v226, v226, v230
	v_add_f32_e32 v227, v227, v231
	ds_bpermute_b32 v228, v87, v224
	ds_bpermute_b32 v229, v87, v225
	ds_bpermute_b32 v230, v87, v226
	ds_bpermute_b32 v231, v87, v227
	s_waitcnt lgkmcnt(0)
	v_add_f32_e32 v224, v224, v228
	v_add_f32_e32 v225, v225, v229
	v_add_f32_e32 v226, v226, v230
	v_add_f32_e32 v227, v227, v231
	ds_bpermute_b32 v228, v88, v224
	ds_bpermute_b32 v229, v88, v225
	ds_bpermute_b32 v230, v88, v226
	ds_bpermute_b32 v231, v88, v227
	s_waitcnt lgkmcnt(0)
	v_add_f32_e32 v224, v224, v228
	v_add_f32_e32 v225, v225, v229
	v_add_f32_e32 v226, v226, v230
	v_add_f32_e32 v227, v227, v231
	v_fmamk_f32 v240, v224, 0x3a800000, v89
	v_mul_f32_e32 v241, 0x4f800000, v240
	v_cmp_gt_f32_e32 vcc, s54, v240
	s_nop 1
	v_cndmask_b32_e32 v247, v240, v241, vcc
	v_sqrt_f32_e32 v242, v247
	s_nop 1
	v_add_u32_e32 v243, -1, v242
	v_add_u32_e32 v244, 1, v242
	v_fma_f32 v245, -v243, v242, v247
	v_fma_f32 v246, -v244, v242, v247
	v_cmp_ge_f32_e64 s[52:53], 0, v245
	s_nop 1
	v_cndmask_b32_e64 v242, v242, v243, s[52:53]
	v_cmp_lt_f32_e64 s[52:53], 0, v246
	s_nop 1
	v_cndmask_b32_e64 v242, v242, v244, s[52:53]
	v_mul_f32_e32 v243, 0x37800000, v242
	v_cndmask_b32_e32 v242, v242, v243, vcc
	v_cmp_class_f32_e32 vcc, v247, v90
	s_nop 1
	v_cndmask_b32_e32 v247, v242, v247, vcc
	v_div_scale_f32 v248, s[52:53], v247, v247, 1.0
	v_rcp_f32_e32 v249, v248
	v_div_scale_f32 v228, vcc, 1.0, v247, 1.0
	s_nop 0
	v_fma_f32 v229, -v248, v249, 1.0
	v_fmac_f32_e32 v249, v229, v249
	v_mul_f32_e32 v230, v228, v249
	v_fma_f32 v229, -v248, v230, v228
	v_fmac_f32_e32 v230, v229, v249
	v_fma_f32 v248, -v248, v230, v228
	v_div_fmas_f32 v248, v248, v249, v230
	v_div_fixup_f32 v232, v248, v247, 1.0
	v_fmamk_f32 v240, v225, 0x3a800000, v89
	v_mul_f32_e32 v241, 0x4f800000, v240
	v_cmp_gt_f32_e32 vcc, s54, v240
	s_nop 1
	v_cndmask_b32_e32 v247, v240, v241, vcc
	v_sqrt_f32_e32 v242, v247
	s_nop 1
	v_add_u32_e32 v243, -1, v242
	v_add_u32_e32 v244, 1, v242
	v_fma_f32 v245, -v243, v242, v247
	v_fma_f32 v246, -v244, v242, v247
; __device__ __forceinline__ unsigned pk2(float lo, float hi) { return pg8::cvt_pk_bf16(lo, hi); }
; template <bool BF> __device__ __forceinline__ void prep_rows(const float* xp, const float* xs, const bf16* hb, const float* g, const float* MOD, int shoff, int scoff, bf16* U, int gw, int NGW, int lane) {
;     ...
;             const float rstd = 1.0f / sqrtf(s[r] * (1.0f / DM) + RMS_EPS);
;             const float* mr = MOD + (size_t)(m < MP ? (m >> 13) : 8 + ((m - MP) >> 12)) * 6144;
; #pragma unroll
;             for (int j = 0; j < 4; ++j) { const int c = 4 * lane + 256 * j;
;                 const f32x4 gg = *(const f32x4*)(g + c), sc = *(const f32x4*)(mr + scoff + c), sh = *(const f32x4*)(mr + shoff + c);
;                 const f32x4 o = v[r][j] * rstd * gg * (sc + 1.0f) + sh; v2u w; w.x = pk2(o.x, o.y); w.y = pk2(o.z, o.w); *(v2u*)(U + (size_t)m * DM + c) = w; } } }
	v_cmp_ge_f32_e64 s[52:53], 0, v245
	s_nop 1
	v_cndmask_b32_e64 v242, v242, v243, s[52:53]
	v_cmp_lt_f32_e64 s[52:53], 0, v246
	s_nop 1
	v_cndmask_b32_e64 v242, v242, v244, s[52:53]
	v_mul_f32_e32 v243, 0x37800000, v242
	v_cndmask_b32_e32 v242, v242, v243, vcc
	v_cmp_class_f32_e32 vcc, v247, v90
	s_nop 1
	v_cndmask_b32_e32 v247, v242, v247, vcc
	v_div_scale_f32 v248, s[52:53], v247, v247, 1.0
	v_rcp_f32_e32 v249, v248
	v_div_scale_f32 v228, vcc, 1.0, v247, 1.0
	s_nop 0
	v_fma_f32 v229, -v248, v249, 1.0
	v_fmac_f32_e32 v249, v229, v249
	v_mul_f32_e32 v230, v228, v249
	v_fma_f32 v229, -v248, v230, v228
	v_fmac_f32_e32 v230, v229, v249
	v_fma_f32 v248, -v248, v230, v228
	v_div_fmas_f32 v248, v248, v249, v230
	v_div_fixup_f32 v234, v248, v247, 1.0
	v_fmamk_f32 v240, v226, 0x3a800000, v89
	v_mul_f32_e32 v241, 0x4f800000, v240
	v_cmp_gt_f32_e32 vcc, s54, v240
	s_nop 1
	v_cndmask_b32_e32 v247, v240, v241, vcc
	v_sqrt_f32_e32 v242, v247
	s_nop 1
	v_add_u32_e32 v243, -1, v242
	v_add_u32_e32 v244, 1, v242
	v_fma_f32 v245, -v243, v242, v247
	v_fma_f32 v246, -v244, v242, v247
	v_cmp_ge_f32_e64 s[52:53], 0, v245
	s_nop 1
	v_cndmask_b32_e64 v242, v242, v243, s[52:53]
	v_cmp_lt_f32_e64 s[52:53], 0, v246
	s_nop 1
	v_cndmask_b32_e64 v242, v242, v244, s[52:53]
	v_mul_f32_e32 v243, 0x37800000, v242
	v_cndmask_b32_e32 v242, v242, v243, vcc
	v_cmp_class_f32_e32 vcc, v247, v90
	s_nop 1
	v_cndmask_b32_e32 v247, v242, v247, vcc
	v_div_scale_f32 v248, s[52:53], v247, v247, 1.0
	v_rcp_f32_e32 v249, v248
	v_div_scale_f32 v228, vcc, 1.0, v247, 1.0
	s_nop 0
	v_fma_f32 v229, -v248, v249, 1.0
	v_fmac_f32_e32 v249, v229, v249
	v_mul_f32_e32 v230, v228, v249
	v_fma_f32 v229, -v248, v230, v228
	v_fmac_f32_e32 v230, v229, v249
	v_fma_f32 v248, -v248, v230, v228
	v_div_fmas_f32 v248, v248, v249, v230
	v_div_fixup_f32 v236, v248, v247, 1.0
	v_fmamk_f32 v240, v227, 0x3a800000, v89
	v_mul_f32_e32 v241, 0x4f800000, v240
	v_cmp_gt_f32_e32 vcc, s54, v240
	s_nop 1
	v_cndmask_b32_e32 v247, v240, v241, vcc
	v_sqrt_f32_e32 v242, v247
	s_nop 1
	v_add_u32_e32 v243, -1, v242
	v_add_u32_e32 v244, 1, v242
	v_fma_f32 v245, -v243, v242, v247
	v_fma_f32 v246, -v244, v242, v247
	v_cmp_ge_f32_e64 s[52:53], 0, v245
	s_nop 1
	v_cndmask_b32_e64 v242, v242, v243, s[52:53]
	v_cmp_lt_f32_e64 s[52:53], 0, v246
	s_nop 1
	v_cndmask_b32_e64 v242, v242, v244, s[52:53]
	v_mul_f32_e32 v243, 0x37800000, v242
	v_cndmask_b32_e32 v242, v242, v243, vcc
	v_cmp_class_f32_e32 vcc, v247, v90
	s_nop 1
	v_cndmask_b32_e32 v247, v242, v247, vcc
	v_div_scale_f32 v248, s[52:53], v247, v247, 1.0
	v_rcp_f32_e32 v249, v248
	v_div_scale_f32 v228, vcc, 1.0, v247, 1.0
	s_nop 0
	v_fma_f32 v229, -v248, v249, 1.0
	v_fmac_f32_e32 v249, v229, v249
	v_mul_f32_e32 v230, v228, v249
	v_fma_f32 v229, -v248, v230, v228
	v_fmac_f32_e32 v230, v229, v249
	v_fma_f32 v248, -v248, v230, v228
	v_div_fmas_f32 v248, v248, v249, v230
	v_div_fixup_f32 v238, v248, v247, 1.0
	s_waitcnt vmcnt(8)
	v_pk_add_f32 v[160:161], v[160:161], 1.0 op_sel_hi:[1,0]
	v_pk_add_f32 v[162:163], v[162:163], 1.0 op_sel_hi:[1,0]
	v_pk_add_f32 v[164:165], v[164:165], 1.0 op_sel_hi:[1,0]
	v_pk_add_f32 v[166:167], v[166:167], 1.0 op_sel_hi:[1,0]
	v_pk_add_f32 v[168:169], v[168:169], 1.0 op_sel_hi:[1,0]
	v_pk_add_f32 v[170:171], v[170:171], 1.0 op_sel_hi:[1,0]
	v_pk_add_f32 v[172:173], v[172:173], 1.0 op_sel_hi:[1,0]
	v_pk_add_f32 v[174:175], v[174:175], 1.0 op_sel_hi:[1,0]
	v_pk_add_f32 v[192:193], v[192:193], 1.0 op_sel_hi:[1,0]
	v_pk_add_f32 v[194:195], v[194:195], 1.0 op_sel_hi:[1,0]
	v_pk_add_f32 v[196:197], v[196:197], 1.0 op_sel_hi:[1,0]
	v_pk_add_f32 v[198:199], v[198:199], 1.0 op_sel_hi:[1,0]
	v_pk_add_f32 v[200:201], v[200:201], 1.0 op_sel_hi:[1,0]
	v_pk_add_f32 v[202:203], v[202:203], 1.0 op_sel_hi:[1,0]
	v_pk_add_f32 v[204:205], v[204:205], 1.0 op_sel_hi:[1,0]
	v_pk_add_f32 v[206:207], v[206:207], 1.0 op_sel_hi:[1,0]
	s_mov_b64 s[38:39], s[20:21]
	s_add_u32 s40, s20, 0x400000
	s_addc_u32 s41, s21, 0
	s_add_u32 s46, s20, 0x800000
	s_addc_u32 s47, s21, 0
	s_add_u32 s48, s20, 0xc00000
	s_addc_u32 s49, s21, 0
	v_pk_mul_f32 v[0:1], v[0:1], v[232:233] op_sel_hi:[1,0]
	v_pk_mul_f32 v[2:3], v[2:3], v[232:233] op_sel_hi:[1,0]
	v_pk_mul_f32 v[0:1], v[64:65], v[0:1]
	v_pk_mul_f32 v[2:3], v[66:67], v[2:3]
	v_pk_fma_f32 v[0:1], v[160:161], v[0:1], v[176:177]
	v_pk_fma_f32 v[2:3], v[162:163], v[2:3], v[178:179]
	v_cvt_pk_bf16_f32 v244, v0, v1
	v_cvt_pk_bf16_f32 v245, v2, v3
	v_pk_mul_f32 v[4:5], v[4:5], v[232:233] op_sel_hi:[1,0]
	v_pk_mul_f32 v[6:7], v[6:7], v[232:233] op_sel_hi:[1,0]
	v_pk_mul_f32 v[4:5], v[68:69], v[4:5]
	v_pk_mul_f32 v[6:7], v[70:71], v[6:7]
	v_pk_fma_f32 v[4:5], v[164:165], v[4:5], v[180:181]
	v_pk_fma_f32 v[6:7], v[166:167], v[6:7], v[182:183]
	v_cvt_pk_bf16_f32 v246, v4, v5
	v_cvt_pk_bf16_f32 v247, v6, v7
	global_store_dwordx4 v82, v[244:247], s[38:39] offset:0
	v_pk_mul_f32 v[8:9], v[8:9], v[232:233] op_sel_hi:[1,0]
	v_pk_mul_f32 v[10:11], v[10:11], v[232:233] op_sel_hi:[1,0]
	v_pk_mul_f32 v[8:9], v[72:73], v[8:9]
	v_pk_mul_f32 v[10:11], v[74:75], v[10:11]
	v_pk_fma_f32 v[8:9], v[168:169], v[8:9], v[184:185]
	v_pk_fma_f32 v[10:11], v[170:171], v[10:11], v[186:187]
	v_cvt_pk_bf16_f32 v240, v8, v9
	v_cvt_pk_bf16_f32 v241, v10, v11
	v_pk_mul_f32 v[12:13], v[12:13], v[232:233] op_sel_hi:[1,0]
	v_pk_mul_f32 v[14:15], v[14:15], v[232:233] op_sel_hi:[1,0]
	v_pk_mul_f32 v[12:13], v[76:77], v[12:13]
	v_pk_mul_f32 v[14:15], v[78:79], v[14:15]
	v_pk_fma_f32 v[12:13], v[172:173], v[12:13], v[188:189]
	v_pk_fma_f32 v[14:15], v[174:175], v[14:15], v[190:191]
	v_cvt_pk_bf16_f32 v242, v12, v13
	v_cvt_pk_bf16_f32 v243, v14, v15
	global_store_dwordx4 v82, v[240:243], s[38:39] offset:1024
; __device__ __forceinline__ float bf_lo(unsigned w) { return __uint_as_float(w << 16); }
; __device__ __forceinline__ float bf_hi(unsigned w) { return __uint_as_float(w & 0xffff0000u); }
; __device__ __forceinline__ unsigned pk2(float lo, float hi) { return pg8::cvt_pk_bf16(lo, hi); }
; template <bool BF> __device__ __forceinline__ void prep_rows(const float* xp, const float* xs, const bf16* hb, const float* g, const float* MOD, int shoff, int scoff, bf16* U, int gw, int NGW, int lane) {
;     ...
;     for (int mb = gw; mb < MT; mb += R * NGW) {
;         f32x4 v[R][4]; float s[R];
; #pragma unroll
;         for (int r = 0; r < R; ++r) { const int m = mb + r * NGW; const int mc = m < MT ? m : mb;
; #pragma unroll
;             for (int j = 0; j < 4; ++j) {
;                 if (BF) { const v2u a0 = *(const v2u*)(hb + (size_t)mc * DM + 4 * lane + 256 * j);
;                     v[r][j].x = pg8::bf_lo(a0.x); v[r][j].y = pg8::bf_hi(a0.x); v[r][j].z = pg8::bf_lo(a0.y); v[r][j].w = pg8::bf_hi(a0.y); }
;                 else { const float* xr = mc < MP ? xp + (size_t)mc * DM : xs + (size_t)(mc - MP) * DM; v[r][j] = *(const f32x4*)(xr + 4 * lane + 256 * j); } } }
;     ...
; #pragma unroll
;             for (int j = 0; j < 4; ++j) { const int c = 4 * lane + 256 * j;
;                 const f32x4 gg = *(const f32x4*)(g + c), sc = *(const f32x4*)(mr + scoff + c), sh = *(const f32x4*)(mr + shoff + c);
;                 const f32x4 o = v[r][j] * rstd * gg * (sc + 1.0f) + sh; v2u w; w.x = pk2(o.x, o.y); w.y = pk2(o.z, o.w); *(v2u*)(U + (size_t)m * DM + c) = w; } } }
	v_pk_mul_f32 v[16:17], v[16:17], v[234:235] op_sel_hi:[1,0]
	v_pk_mul_f32 v[18:19], v[18:19], v[234:235] op_sel_hi:[1,0]
	v_pk_mul_f32 v[16:17], v[64:65], v[16:17]
	v_pk_mul_f32 v[18:19], v[66:67], v[18:19]
	v_pk_fma_f32 v[16:17], v[160:161], v[16:17], v[176:177]
	v_pk_fma_f32 v[18:19], v[162:163], v[18:19], v[178:179]
	v_cvt_pk_bf16_f32 v244, v16, v17
	v_cvt_pk_bf16_f32 v245, v18, v19
	v_pk_mul_f32 v[20:21], v[20:21], v[234:235] op_sel_hi:[1,0]
	v_pk_mul_f32 v[22:23], v[22:23], v[234:235] op_sel_hi:[1,0]
	v_pk_mul_f32 v[20:21], v[68:69], v[20:21]
	v_pk_mul_f32 v[22:23], v[70:71], v[22:23]
	v_pk_fma_f32 v[20:21], v[164:165], v[20:21], v[180:181]
	v_pk_fma_f32 v[22:23], v[166:167], v[22:23], v[182:183]
	v_cvt_pk_bf16_f32 v246, v20, v21
	v_cvt_pk_bf16_f32 v247, v22, v23
	global_store_dwordx4 v82, v[244:247], s[40:41] offset:0
	v_pk_mul_f32 v[24:25], v[24:25], v[234:235] op_sel_hi:[1,0]
	v_pk_mul_f32 v[26:27], v[26:27], v[234:235] op_sel_hi:[1,0]
	v_pk_mul_f32 v[24:25], v[72:73], v[24:25]
	v_pk_mul_f32 v[26:27], v[74:75], v[26:27]
	v_pk_fma_f32 v[24:25], v[168:169], v[24:25], v[184:185]
	v_pk_fma_f32 v[26:27], v[170:171], v[26:27], v[186:187]
	v_cvt_pk_bf16_f32 v240, v24, v25
	v_cvt_pk_bf16_f32 v241, v26, v27
	v_pk_mul_f32 v[28:29], v[28:29], v[234:235] op_sel_hi:[1,0]
	v_pk_mul_f32 v[30:31], v[30:31], v[234:235] op_sel_hi:[1,0]
	v_pk_mul_f32 v[28:29], v[76:77], v[28:29]
	v_pk_mul_f32 v[30:31], v[78:79], v[30:31]
	v_pk_fma_f32 v[28:29], v[172:173], v[28:29], v[188:189]
	v_pk_fma_f32 v[30:31], v[174:175], v[30:31], v[190:191]
	v_cvt_pk_bf16_f32 v242, v28, v29
	v_cvt_pk_bf16_f32 v243, v30, v31
	global_store_dwordx4 v82, v[240:243], s[40:41] offset:1024
	v_pk_mul_f32 v[32:33], v[32:33], v[236:237] op_sel_hi:[1,0]
	v_pk_mul_f32 v[34:35], v[34:35], v[236:237] op_sel_hi:[1,0]
	v_pk_mul_f32 v[32:33], v[64:65], v[32:33]
	v_pk_mul_f32 v[34:35], v[66:67], v[34:35]
	v_pk_fma_f32 v[32:33], v[192:193], v[32:33], v[208:209]
	v_pk_fma_f32 v[34:35], v[194:195], v[34:35], v[210:211]
	v_cvt_pk_bf16_f32 v244, v32, v33
	v_cvt_pk_bf16_f32 v245, v34, v35
	v_pk_mul_f32 v[36:37], v[36:37], v[236:237] op_sel_hi:[1,0]
	v_pk_mul_f32 v[38:39], v[38:39], v[236:237] op_sel_hi:[1,0]
	v_pk_mul_f32 v[36:37], v[68:69], v[36:37]
	v_pk_mul_f32 v[38:39], v[70:71], v[38:39]
	v_pk_fma_f32 v[36:37], v[196:197], v[36:37], v[212:213]
	v_pk_fma_f32 v[38:39], v[198:199], v[38:39], v[214:215]
	v_cvt_pk_bf16_f32 v246, v36, v37
	v_cvt_pk_bf16_f32 v247, v38, v39
	global_store_dwordx4 v82, v[244:247], s[46:47] offset:0
	v_pk_mul_f32 v[40:41], v[40:41], v[236:237] op_sel_hi:[1,0]
	v_pk_mul_f32 v[42:43], v[42:43], v[236:237] op_sel_hi:[1,0]
	v_pk_mul_f32 v[40:41], v[72:73], v[40:41]
	v_pk_mul_f32 v[42:43], v[74:75], v[42:43]
	v_pk_fma_f32 v[40:41], v[200:201], v[40:41], v[216:217]
	v_pk_fma_f32 v[42:43], v[202:203], v[42:43], v[218:219]
	v_cvt_pk_bf16_f32 v240, v40, v41
	v_cvt_pk_bf16_f32 v241, v42, v43
	v_pk_mul_f32 v[44:45], v[44:45], v[236:237] op_sel_hi:[1,0]
	v_pk_mul_f32 v[46:47], v[46:47], v[236:237] op_sel_hi:[1,0]
	v_pk_mul_f32 v[44:45], v[76:77], v[44:45]
	v_pk_mul_f32 v[46:47], v[78:79], v[46:47]
	v_pk_fma_f32 v[44:45], v[204:205], v[44:45], v[220:221]
	v_pk_fma_f32 v[46:47], v[206:207], v[46:47], v[222:223]
	v_cvt_pk_bf16_f32 v242, v44, v45
	v_cvt_pk_bf16_f32 v243, v46, v47
	global_store_dwordx4 v82, v[240:243], s[46:47] offset:1024
	v_pk_mul_f32 v[48:49], v[48:49], v[238:239] op_sel_hi:[1,0]
	v_pk_mul_f32 v[50:51], v[50:51], v[238:239] op_sel_hi:[1,0]
	v_pk_mul_f32 v[48:49], v[64:65], v[48:49]
	v_pk_mul_f32 v[50:51], v[66:67], v[50:51]
	v_pk_fma_f32 v[48:49], v[192:193], v[48:49], v[208:209]
	v_pk_fma_f32 v[50:51], v[194:195], v[50:51], v[210:211]
	v_cvt_pk_bf16_f32 v244, v48, v49
	v_cvt_pk_bf16_f32 v245, v50, v51
	v_pk_mul_f32 v[52:53], v[52:53], v[238:239] op_sel_hi:[1,0]
	v_pk_mul_f32 v[54:55], v[54:55], v[238:239] op_sel_hi:[1,0]
	v_pk_mul_f32 v[52:53], v[68:69], v[52:53]
	v_pk_mul_f32 v[54:55], v[70:71], v[54:55]
	v_pk_fma_f32 v[52:53], v[196:197], v[52:53], v[212:213]
	v_pk_fma_f32 v[54:55], v[198:199], v[54:55], v[214:215]
	v_cvt_pk_bf16_f32 v246, v52, v53
	v_cvt_pk_bf16_f32 v247, v54, v55
	global_store_dwordx4 v82, v[244:247], s[48:49] offset:0
	v_pk_mul_f32 v[56:57], v[56:57], v[238:239] op_sel_hi:[1,0]
	v_pk_mul_f32 v[58:59], v[58:59], v[238:239] op_sel_hi:[1,0]
	v_pk_mul_f32 v[56:57], v[72:73], v[56:57]
	v_pk_mul_f32 v[58:59], v[74:75], v[58:59]
	v_pk_fma_f32 v[56:57], v[200:201], v[56:57], v[216:217]
	v_pk_fma_f32 v[58:59], v[202:203], v[58:59], v[218:219]
	v_cvt_pk_bf16_f32 v240, v56, v57
	v_cvt_pk_bf16_f32 v241, v58, v59
	v_pk_mul_f32 v[60:61], v[60:61], v[238:239] op_sel_hi:[1,0]
	v_pk_mul_f32 v[62:63], v[62:63], v[238:239] op_sel_hi:[1,0]
	v_pk_mul_f32 v[60:61], v[76:77], v[60:61]
	v_pk_mul_f32 v[62:63], v[78:79], v[62:63]
	v_pk_fma_f32 v[60:61], v[204:205], v[60:61], v[220:221]
	v_pk_fma_f32 v[62:63], v[206:207], v[62:63], v[222:223]
	v_cvt_pk_bf16_f32 v242, v60, v61
	v_cvt_pk_bf16_f32 v243, v62, v63
	global_store_dwordx4 v82, v[240:243], s[48:49] offset:1024
	s_add_u32 s34, s8, 0x9000
	s_addc_u32 s35, s9, 0
	s_add_u32 s36, s8, 0x9000
	s_addc_u32 s37, s9, 0
	global_load_dwordx4 v[176:179], v80, s[34:35] offset:0
	global_load_dwordx4 v[180:183], v80, s[34:35] offset:16
	global_load_dwordx4 v[184:187], v80, s[34:35] offset:2048
	global_load_dwordx4 v[188:191], v80, s[34:35] offset:2064
	global_load_dwordx4 v[160:163], v81, s[34:35] offset:0
	global_load_dwordx4 v[164:167], v81, s[34:35] offset:16
	global_load_dwordx4 v[168:171], v81, s[34:35] offset:2048
	global_load_dwordx4 v[172:175], v81, s[34:35] offset:2064
	global_load_dwordx4 v[208:211], v80, s[36:37] offset:0
	global_load_dwordx4 v[212:215], v80, s[36:37] offset:16
	global_load_dwordx4 v[216:219], v80, s[36:37] offset:2048
	global_load_dwordx4 v[220:223], v80, s[36:37] offset:2064
	global_load_dwordx4 v[192:195], v81, s[36:37] offset:0
	global_load_dwordx4 v[196:199], v81, s[36:37] offset:16
	global_load_dwordx4 v[200:203], v81, s[36:37] offset:2048
	global_load_dwordx4 v[204:207], v81, s[36:37] offset:2064
	s_add_u32 s24, s16, 0x2000000
	s_addc_u32 s25, s17, 0
	s_add_u32 s26, s16, 0x2400000
	s_addc_u32 s27, s17, 0
	s_add_u32 s28, s16, 0x2800000
	s_addc_u32 s29, s17, 0
	s_add_u32 s30, s16, 0x2c00000
	s_addc_u32 s31, s17, 0
	global_load_dwordx4 v[96:99], v82, s[24:25] offset:0 nt
	global_load_dwordx4 v[100:103], v82, s[24:25] offset:1024 nt
	global_load_dwordx4 v[104:107], v82, s[26:27] offset:0 nt
	global_load_dwordx4 v[108:111], v82, s[26:27] offset:1024 nt
	global_load_dwordx4 v[112:115], v82, s[28:29] offset:0 nt
	global_load_dwordx4 v[116:119], v82, s[28:29] offset:1024 nt
	global_load_dwordx4 v[120:123], v82, s[30:31] offset:0 nt
	global_load_dwordx4 v[124:127], v82, s[30:31] offset:1024 nt
	s_waitcnt vmcnt(32)
; __device__ __forceinline__ float bf_lo(unsigned w) { return __uint_as_float(w << 16); }
; __device__ __forceinline__ float bf_hi(unsigned w) { return __uint_as_float(w & 0xffff0000u); }
; template <bool BF> __device__ __forceinline__ void prep_rows(const float* xp, const float* xs, const bf16* hb, const float* g, const float* MOD, int shoff, int scoff, bf16* U, int gw, int NGW, int lane) {
;     ...
;                 if (BF) { const v2u a0 = *(const v2u*)(hb + (size_t)mc * DM + 4 * lane + 256 * j);
;                     v[r][j].x = pg8::bf_lo(a0.x); v[r][j].y = pg8::bf_hi(a0.x); v[r][j].z = pg8::bf_lo(a0.y); v[r][j].w = pg8::bf_hi(a0.y); }
;                 else { const float* xr = mc < MP ? xp + (size_t)mc * DM : xs + (size_t)(mc - MP) * DM; v[r][j] = *(const f32x4*)(xr + 4 * lane + 256 * j); } } }
; #pragma unroll
;         for (int r = 0; r < R; ++r) { float t = 0.f;
; #pragma unroll
;             for (int j = 0; j < 4; ++j) t += (v[r][j].x * v[r][j].x + v[r][j].y * v[r][j].y) + (v[r][j].z * v[r][j].z + v[r][j].w * v[r][j].w);
;             s[r] = t; }
; #pragma unroll
;         for (int o = 1; o < 64; o <<= 1) {
; #pragma unroll
;             for (int r = 0; r < R; ++r) s[r] += __shfl_xor(s[r], o); }
	v_lshlrev_b32_e32 v0, 16, v128
	v_and_b32_e32 v1, 0xffff0000, v128
	v_lshlrev_b32_e32 v2, 16, v129
	v_and_b32_e32 v3, 0xffff0000, v129
	v_lshlrev_b32_e32 v4, 16, v130
	v_and_b32_e32 v5, 0xffff0000, v130
	v_lshlrev_b32_e32 v6, 16, v131
	v_and_b32_e32 v7, 0xffff0000, v131
	v_lshlrev_b32_e32 v8, 16, v132
	v_and_b32_e32 v9, 0xffff0000, v132
	v_lshlrev_b32_e32 v10, 16, v133
	v_and_b32_e32 v11, 0xffff0000, v133
	v_lshlrev_b32_e32 v12, 16, v134
	v_and_b32_e32 v13, 0xffff0000, v134
	v_lshlrev_b32_e32 v14, 16, v135
	v_and_b32_e32 v15, 0xffff0000, v135
	v_lshlrev_b32_e32 v16, 16, v136
	v_and_b32_e32 v17, 0xffff0000, v136
	v_lshlrev_b32_e32 v18, 16, v137
	v_and_b32_e32 v19, 0xffff0000, v137
	v_lshlrev_b32_e32 v20, 16, v138
	v_and_b32_e32 v21, 0xffff0000, v138
	v_lshlrev_b32_e32 v22, 16, v139
	v_and_b32_e32 v23, 0xffff0000, v139
	v_lshlrev_b32_e32 v24, 16, v140
	v_and_b32_e32 v25, 0xffff0000, v140
	v_lshlrev_b32_e32 v26, 16, v141
	v_and_b32_e32 v27, 0xffff0000, v141
	v_lshlrev_b32_e32 v28, 16, v142
	v_and_b32_e32 v29, 0xffff0000, v142
	v_lshlrev_b32_e32 v30, 16, v143
	v_and_b32_e32 v31, 0xffff0000, v143
	v_lshlrev_b32_e32 v32, 16, v144
	v_and_b32_e32 v33, 0xffff0000, v144
	v_lshlrev_b32_e32 v34, 16, v145
	v_and_b32_e32 v35, 0xffff0000, v145
	v_lshlrev_b32_e32 v36, 16, v146
	v_and_b32_e32 v37, 0xffff0000, v146
	v_lshlrev_b32_e32 v38, 16, v147
	v_and_b32_e32 v39, 0xffff0000, v147
	v_lshlrev_b32_e32 v40, 16, v148
	v_and_b32_e32 v41, 0xffff0000, v148
	v_lshlrev_b32_e32 v42, 16, v149
	v_and_b32_e32 v43, 0xffff0000, v149
	v_lshlrev_b32_e32 v44, 16, v150
	v_and_b32_e32 v45, 0xffff0000, v150
	v_lshlrev_b32_e32 v46, 16, v151
	v_and_b32_e32 v47, 0xffff0000, v151
	v_lshlrev_b32_e32 v48, 16, v152
	v_and_b32_e32 v49, 0xffff0000, v152
	v_lshlrev_b32_e32 v50, 16, v153
	v_and_b32_e32 v51, 0xffff0000, v153
	v_lshlrev_b32_e32 v52, 16, v154
	v_and_b32_e32 v53, 0xffff0000, v154
	v_lshlrev_b32_e32 v54, 16, v155
	v_and_b32_e32 v55, 0xffff0000, v155
	v_lshlrev_b32_e32 v56, 16, v156
	v_and_b32_e32 v57, 0xffff0000, v156
	v_lshlrev_b32_e32 v58, 16, v157
	v_and_b32_e32 v59, 0xffff0000, v157
	v_lshlrev_b32_e32 v60, 16, v158
	v_and_b32_e32 v61, 0xffff0000, v158
	v_lshlrev_b32_e32 v62, 16, v159
	v_and_b32_e32 v63, 0xffff0000, v159
	v_pk_mul_f32 v[240:241], v[0:1], v[0:1]
	v_pk_mul_f32 v[242:243], v[16:17], v[16:17]
	v_pk_mul_f32 v[244:245], v[32:33], v[32:33]
	v_pk_mul_f32 v[246:247], v[48:49], v[48:49]
	v_pk_fma_f32 v[240:241], v[2:3], v[2:3], v[240:241]
	v_pk_fma_f32 v[242:243], v[18:19], v[18:19], v[242:243]
	v_pk_fma_f32 v[244:245], v[34:35], v[34:35], v[244:245]
	v_pk_fma_f32 v[246:247], v[50:51], v[50:51], v[246:247]
	v_pk_fma_f32 v[240:241], v[4:5], v[4:5], v[240:241]
	v_pk_fma_f32 v[242:243], v[20:21], v[20:21], v[242:243]
	v_pk_fma_f32 v[244:245], v[36:37], v[36:37], v[244:245]
	v_pk_fma_f32 v[246:247], v[52:53], v[52:53], v[246:247]
	v_pk_fma_f32 v[240:241], v[6:7], v[6:7], v[240:241]
	v_pk_fma_f32 v[242:243], v[22:23], v[22:23], v[242:243]
	v_pk_fma_f32 v[244:245], v[38:39], v[38:39], v[244:245]
	v_pk_fma_f32 v[246:247], v[54:55], v[54:55], v[246:247]
	v_pk_fma_f32 v[240:241], v[8:9], v[8:9], v[240:241]
	v_pk_fma_f32 v[242:243], v[24:25], v[24:25], v[242:243]
	v_pk_fma_f32 v[244:245], v[40:41], v[40:41], v[244:245]
	v_pk_fma_f32 v[246:247], v[56:57], v[56:57], v[246:247]
	v_pk_fma_f32 v[240:241], v[10:11], v[10:11], v[240:241]
	v_pk_fma_f32 v[242:243], v[26:27], v[26:27], v[242:243]
	v_pk_fma_f32 v[244:245], v[42:43], v[42:43], v[244:245]
	v_pk_fma_f32 v[246:247], v[58:59], v[58:59], v[246:247]
	v_pk_fma_f32 v[240:241], v[12:13], v[12:13], v[240:241]
	v_pk_fma_f32 v[242:243], v[28:29], v[28:29], v[242:243]
	v_pk_fma_f32 v[244:245], v[44:45], v[44:45], v[244:245]
	v_pk_fma_f32 v[246:247], v[60:61], v[60:61], v[246:247]
	v_pk_fma_f32 v[240:241], v[14:15], v[14:15], v[240:241]
	v_pk_fma_f32 v[242:243], v[30:31], v[30:31], v[242:243]
	v_pk_fma_f32 v[244:245], v[46:47], v[46:47], v[244:245]
	v_pk_fma_f32 v[246:247], v[62:63], v[62:63], v[246:247]
	v_add_f32_e32 v224, v240, v241
	v_add_f32_e32 v225, v242, v243
	v_add_f32_e32 v226, v244, v245
	v_add_f32_e32 v227, v246, v247
	ds_bpermute_b32 v228, v83, v224
	ds_bpermute_b32 v229, v83, v225
	ds_bpermute_b32 v230, v83, v226
	ds_bpermute_b32 v231, v83, v227
	s_waitcnt lgkmcnt(0)
	v_add_f32_e32 v224, v224, v228
	v_add_f32_e32 v225, v225, v229
	v_add_f32_e32 v226, v226, v230
	v_add_f32_e32 v227, v227, v231
	ds_bpermute_b32 v228, v84, v224
	ds_bpermute_b32 v229, v84, v225
	ds_bpermute_b32 v230, v84, v226
	ds_bpermute_b32 v231, v84, v227
	s_waitcnt lgkmcnt(0)
	v_add_f32_e32 v224, v224, v228
	v_add_f32_e32 v225, v225, v229
	v_add_f32_e32 v226, v226, v230
	v_add_f32_e32 v227, v227, v231
	ds_bpermute_b32 v228, v85, v224
	ds_bpermute_b32 v229, v85, v225
	ds_bpermute_b32 v230, v85, v226
	ds_bpermute_b32 v231, v85, v227
	s_waitcnt lgkmcnt(0)
	v_add_f32_e32 v224, v224, v228
	v_add_f32_e32 v225, v225, v229
	v_add_f32_e32 v226, v226, v230
	v_add_f32_e32 v227, v227, v231
	ds_bpermute_b32 v228, v86, v224
	ds_bpermute_b32 v229, v86, v225
	ds_bpermute_b32 v230, v86, v226
	ds_bpermute_b32 v231, v86, v227
	s_waitcnt lgkmcnt(0)
	v_add_f32_e32 v224, v224, v228
	v_add_f32_e32 v225, v225, v229
	v_add_f32_e32 v226, v226, v230
	v_add_f32_e32 v227, v227, v231
	ds_bpermute_b32 v228, v87, v224
	ds_bpermute_b32 v229, v87, v225
	ds_bpermute_b32 v230, v87, v226
	ds_bpermute_b32 v231, v87, v227
	s_waitcnt lgkmcnt(0)
	v_add_f32_e32 v224, v224, v228
	v_add_f32_e32 v225, v225, v229
	v_add_f32_e32 v226, v226, v230
	v_add_f32_e32 v227, v227, v231
	ds_bpermute_b32 v228, v88, v224
	ds_bpermute_b32 v229, v88, v225
	ds_bpermute_b32 v230, v88, v226
	ds_bpermute_b32 v231, v88, v227
	s_waitcnt lgkmcnt(0)
; template <bool BF> __device__ __forceinline__ void prep_rows(const float* xp, const float* xs, const bf16* hb, const float* g, const float* MOD, int shoff, int scoff, bf16* U, int gw, int NGW, int lane) {
;     ...
;             for (int r = 0; r < R; ++r) s[r] += __shfl_xor(s[r], o); }
; #pragma unroll
;         for (int r = 0; r < R; ++r) { const int m = mb + r * NGW; if (m < MT) {
;             const float rstd = 1.0f / sqrtf(s[r] * (1.0f / DM) + RMS_EPS);
	v_add_f32_e32 v224, v224, v228
	v_add_f32_e32 v225, v225, v229
	v_add_f32_e32 v226, v226, v230
	v_add_f32_e32 v227, v227, v231
	v_fmamk_f32 v240, v224, 0x3a800000, v89
	v_mul_f32_e32 v241, 0x4f800000, v240
	v_cmp_gt_f32_e32 vcc, s54, v240
	s_nop 1
	v_cndmask_b32_e32 v247, v240, v241, vcc
	v_sqrt_f32_e32 v242, v247
	s_nop 1
	v_add_u32_e32 v243, -1, v242
	v_add_u32_e32 v244, 1, v242
	v_fma_f32 v245, -v243, v242, v247
	v_fma_f32 v246, -v244, v242, v247
	v_cmp_ge_f32_e64 s[52:53], 0, v245
	s_nop 1
	v_cndmask_b32_e64 v242, v242, v243, s[52:53]
	v_cmp_lt_f32_e64 s[52:53], 0, v246
	s_nop 1
	v_cndmask_b32_e64 v242, v242, v244, s[52:53]
	v_mul_f32_e32 v243, 0x37800000, v242
	v_cndmask_b32_e32 v242, v242, v243, vcc
	v_cmp_class_f32_e32 vcc, v247, v90
	s_nop 1
	v_cndmask_b32_e32 v247, v242, v247, vcc
	v_div_scale_f32 v248, s[52:53], v247, v247, 1.0
	v_rcp_f32_e32 v249, v248
	v_div_scale_f32 v228, vcc, 1.0, v247, 1.0
	s_nop 0
	v_fma_f32 v229, -v248, v249, 1.0
	v_fmac_f32_e32 v249, v229, v249
	v_mul_f32_e32 v230, v228, v249
	v_fma_f32 v229, -v248, v230, v228
	v_fmac_f32_e32 v230, v229, v249
	v_fma_f32 v248, -v248, v230, v228
	v_div_fmas_f32 v248, v248, v249, v230
	v_div_fixup_f32 v232, v248, v247, 1.0
	v_fmamk_f32 v240, v225, 0x3a800000, v89
	v_mul_f32_e32 v241, 0x4f800000, v240
	v_cmp_gt_f32_e32 vcc, s54, v240
	s_nop 1
	v_cndmask_b32_e32 v247, v240, v241, vcc
	v_sqrt_f32_e32 v242, v247
	s_nop 1
	v_add_u32_e32 v243, -1, v242
	v_add_u32_e32 v244, 1, v242
	v_fma_f32 v245, -v243, v242, v247
	v_fma_f32 v246, -v244, v242, v247
	v_cmp_ge_f32_e64 s[52:53], 0, v245
	s_nop 1
	v_cndmask_b32_e64 v242, v242, v243, s[52:53]
	v_cmp_lt_f32_e64 s[52:53], 0, v246
	s_nop 1
	v_cndmask_b32_e64 v242, v242, v244, s[52:53]
	v_mul_f32_e32 v243, 0x37800000, v242
	v_cndmask_b32_e32 v242, v242, v243, vcc
	v_cmp_class_f32_e32 vcc, v247, v90
	s_nop 1
	v_cndmask_b32_e32 v247, v242, v247, vcc
	v_div_scale_f32 v248, s[52:53], v247, v247, 1.0
	v_rcp_f32_e32 v249, v248
	v_div_scale_f32 v228, vcc, 1.0, v247, 1.0
	s_nop 0
	v_fma_f32 v229, -v248, v249, 1.0
	v_fmac_f32_e32 v249, v229, v249
	v_mul_f32_e32 v230, v228, v249
	v_fma_f32 v229, -v248, v230, v228
	v_fmac_f32_e32 v230, v229, v249
	v_fma_f32 v248, -v248, v230, v228
	v_div_fmas_f32 v248, v248, v249, v230
	v_div_fixup_f32 v234, v248, v247, 1.0
	v_fmamk_f32 v240, v226, 0x3a800000, v89
	v_mul_f32_e32 v241, 0x4f800000, v240
	v_cmp_gt_f32_e32 vcc, s54, v240
	s_nop 1
	v_cndmask_b32_e32 v247, v240, v241, vcc
	v_sqrt_f32_e32 v242, v247
	s_nop 1
	v_add_u32_e32 v243, -1, v242
	v_add_u32_e32 v244, 1, v242
	v_fma_f32 v245, -v243, v242, v247
	v_fma_f32 v246, -v244, v242, v247
	v_cmp_ge_f32_e64 s[52:53], 0, v245
	s_nop 1
	v_cndmask_b32_e64 v242, v242, v243, s[52:53]
	v_cmp_lt_f32_e64 s[52:53], 0, v246
	s_nop 1
	v_cndmask_b32_e64 v242, v242, v244, s[52:53]
	v_mul_f32_e32 v243, 0x37800000, v242
	v_cndmask_b32_e32 v242, v242, v243, vcc
	v_cmp_class_f32_e32 vcc, v247, v90
	s_nop 1
	v_cndmask_b32_e32 v247, v242, v247, vcc
	v_div_scale_f32 v248, s[52:53], v247, v247, 1.0
	v_rcp_f32_e32 v249, v248
	v_div_scale_f32 v228, vcc, 1.0, v247, 1.0
	s_nop 0
	v_fma_f32 v229, -v248, v249, 1.0
	v_fmac_f32_e32 v249, v229, v249
	v_mul_f32_e32 v230, v228, v249
	v_fma_f32 v229, -v248, v230, v228
	v_fmac_f32_e32 v230, v229, v249
	v_fma_f32 v248, -v248, v230, v228
	v_div_fmas_f32 v248, v248, v249, v230
	v_div_fixup_f32 v236, v248, v247, 1.0
	v_fmamk_f32 v240, v227, 0x3a800000, v89
	v_mul_f32_e32 v241, 0x4f800000, v240
	v_cmp_gt_f32_e32 vcc, s54, v240
	s_nop 1
	v_cndmask_b32_e32 v247, v240, v241, vcc
	v_sqrt_f32_e32 v242, v247
	s_nop 1
	v_add_u32_e32 v243, -1, v242
	v_add_u32_e32 v244, 1, v242
	v_fma_f32 v245, -v243, v242, v247
	v_fma_f32 v246, -v244, v242, v247
	v_cmp_ge_f32_e64 s[52:53], 0, v245
	s_nop 1
	v_cndmask_b32_e64 v242, v242, v243, s[52:53]
	v_cmp_lt_f32_e64 s[52:53], 0, v246
	s_nop 1
	v_cndmask_b32_e64 v242, v242, v244, s[52:53]
	v_mul_f32_e32 v243, 0x37800000, v242
	v_cndmask_b32_e32 v242, v242, v243, vcc
	v_cmp_class_f32_e32 vcc, v247, v90
	s_nop 1
	v_cndmask_b32_e32 v247, v242, v247, vcc
	v_div_scale_f32 v248, s[52:53], v247, v247, 1.0
	v_rcp_f32_e32 v249, v248
	v_div_scale_f32 v228, vcc, 1.0, v247, 1.0
	s_nop 0
	v_fma_f32 v229, -v248, v249, 1.0
	v_fmac_f32_e32 v249, v229, v249
	v_mul_f32_e32 v230, v228, v249
	v_fma_f32 v229, -v248, v230, v228
	v_fmac_f32_e32 v230, v229, v249
	v_fma_f32 v248, -v248, v230, v228
	v_div_fmas_f32 v248, v248, v249, v230
	v_div_fixup_f32 v238, v248, v247, 1.0
	s_waitcnt vmcnt(8)
; __device__ __forceinline__ unsigned pk2(float lo, float hi) { return pg8::cvt_pk_bf16(lo, hi); }
; template <bool BF> __device__ __forceinline__ void prep_rows(const float* xp, const float* xs, const bf16* hb, const float* g, const float* MOD, int shoff, int scoff, bf16* U, int gw, int NGW, int lane) {
;     ...
; #pragma unroll
;             for (int j = 0; j < 4; ++j) { const int c = 4 * lane + 256 * j;
;                 const f32x4 gg = *(const f32x4*)(g + c), sc = *(const f32x4*)(mr + scoff + c), sh = *(const f32x4*)(mr + shoff + c);
;                 const f32x4 o = v[r][j] * rstd * gg * (sc + 1.0f) + sh; v2u w; w.x = pk2(o.x, o.y); w.y = pk2(o.z, o.w); *(v2u*)(U + (size_t)m * DM + c) = w; } } }
	v_pk_add_f32 v[160:161], v[160:161], 1.0 op_sel_hi:[1,0]
	v_pk_add_f32 v[162:163], v[162:163], 1.0 op_sel_hi:[1,0]
	v_pk_add_f32 v[164:165], v[164:165], 1.0 op_sel_hi:[1,0]
	v_pk_add_f32 v[166:167], v[166:167], 1.0 op_sel_hi:[1,0]
	v_pk_add_f32 v[168:169], v[168:169], 1.0 op_sel_hi:[1,0]
	v_pk_add_f32 v[170:171], v[170:171], 1.0 op_sel_hi:[1,0]
	v_pk_add_f32 v[172:173], v[172:173], 1.0 op_sel_hi:[1,0]
	v_pk_add_f32 v[174:175], v[174:175], 1.0 op_sel_hi:[1,0]
	v_pk_add_f32 v[192:193], v[192:193], 1.0 op_sel_hi:[1,0]
	v_pk_add_f32 v[194:195], v[194:195], 1.0 op_sel_hi:[1,0]
	v_pk_add_f32 v[196:197], v[196:197], 1.0 op_sel_hi:[1,0]
	v_pk_add_f32 v[198:199], v[198:199], 1.0 op_sel_hi:[1,0]
	v_pk_add_f32 v[200:201], v[200:201], 1.0 op_sel_hi:[1,0]
	v_pk_add_f32 v[202:203], v[202:203], 1.0 op_sel_hi:[1,0]
	v_pk_add_f32 v[204:205], v[204:205], 1.0 op_sel_hi:[1,0]
	v_pk_add_f32 v[206:207], v[206:207], 1.0 op_sel_hi:[1,0]
	s_add_u32 s38, s20, 0x1000000
	s_addc_u32 s39, s21, 0
	s_add_u32 s40, s20, 0x1400000
	s_addc_u32 s41, s21, 0
	s_add_u32 s46, s20, 0x1800000
	s_addc_u32 s47, s21, 0
	s_add_u32 s48, s20, 0x1c00000
	s_addc_u32 s49, s21, 0
	v_pk_mul_f32 v[0:1], v[0:1], v[232:233] op_sel_hi:[1,0]
	v_pk_mul_f32 v[2:3], v[2:3], v[232:233] op_sel_hi:[1,0]
	v_pk_mul_f32 v[0:1], v[64:65], v[0:1]
	v_pk_mul_f32 v[2:3], v[66:67], v[2:3]
	v_pk_fma_f32 v[0:1], v[160:161], v[0:1], v[176:177]
	v_pk_fma_f32 v[2:3], v[162:163], v[2:3], v[178:179]
	v_cvt_pk_bf16_f32 v244, v0, v1
	v_cvt_pk_bf16_f32 v245, v2, v3
	v_pk_mul_f32 v[4:5], v[4:5], v[232:233] op_sel_hi:[1,0]
	v_pk_mul_f32 v[6:7], v[6:7], v[232:233] op_sel_hi:[1,0]
	v_pk_mul_f32 v[4:5], v[68:69], v[4:5]
	v_pk_mul_f32 v[6:7], v[70:71], v[6:7]
	v_pk_fma_f32 v[4:5], v[164:165], v[4:5], v[180:181]
	v_pk_fma_f32 v[6:7], v[166:167], v[6:7], v[182:183]
	v_cvt_pk_bf16_f32 v246, v4, v5
	v_cvt_pk_bf16_f32 v247, v6, v7
	global_store_dwordx4 v82, v[244:247], s[38:39] offset:0
	v_pk_mul_f32 v[8:9], v[8:9], v[232:233] op_sel_hi:[1,0]
	v_pk_mul_f32 v[10:11], v[10:11], v[232:233] op_sel_hi:[1,0]
	v_pk_mul_f32 v[8:9], v[72:73], v[8:9]
	v_pk_mul_f32 v[10:11], v[74:75], v[10:11]
	v_pk_fma_f32 v[8:9], v[168:169], v[8:9], v[184:185]
	v_pk_fma_f32 v[10:11], v[170:171], v[10:11], v[186:187]
	v_cvt_pk_bf16_f32 v240, v8, v9
	v_cvt_pk_bf16_f32 v241, v10, v11
	v_pk_mul_f32 v[12:13], v[12:13], v[232:233] op_sel_hi:[1,0]
	v_pk_mul_f32 v[14:15], v[14:15], v[232:233] op_sel_hi:[1,0]
	v_pk_mul_f32 v[12:13], v[76:77], v[12:13]
	v_pk_mul_f32 v[14:15], v[78:79], v[14:15]
	v_pk_fma_f32 v[12:13], v[172:173], v[12:13], v[188:189]
	v_pk_fma_f32 v[14:15], v[174:175], v[14:15], v[190:191]
	v_cvt_pk_bf16_f32 v242, v12, v13
	v_cvt_pk_bf16_f32 v243, v14, v15
	global_store_dwordx4 v82, v[240:243], s[38:39] offset:1024
	v_pk_mul_f32 v[16:17], v[16:17], v[234:235] op_sel_hi:[1,0]
	v_pk_mul_f32 v[18:19], v[18:19], v[234:235] op_sel_hi:[1,0]
	v_pk_mul_f32 v[16:17], v[64:65], v[16:17]
	v_pk_mul_f32 v[18:19], v[66:67], v[18:19]
	v_pk_fma_f32 v[16:17], v[160:161], v[16:17], v[176:177]
	v_pk_fma_f32 v[18:19], v[162:163], v[18:19], v[178:179]
	v_cvt_pk_bf16_f32 v244, v16, v17
	v_cvt_pk_bf16_f32 v245, v18, v19
	v_pk_mul_f32 v[20:21], v[20:21], v[234:235] op_sel_hi:[1,0]
	v_pk_mul_f32 v[22:23], v[22:23], v[234:235] op_sel_hi:[1,0]
	v_pk_mul_f32 v[20:21], v[68:69], v[20:21]
	v_pk_mul_f32 v[22:23], v[70:71], v[22:23]
	v_pk_fma_f32 v[20:21], v[164:165], v[20:21], v[180:181]
	v_pk_fma_f32 v[22:23], v[166:167], v[22:23], v[182:183]
	v_cvt_pk_bf16_f32 v246, v20, v21
	v_cvt_pk_bf16_f32 v247, v22, v23
	global_store_dwordx4 v82, v[244:247], s[40:41] offset:0
	v_pk_mul_f32 v[24:25], v[24:25], v[234:235] op_sel_hi:[1,0]
	v_pk_mul_f32 v[26:27], v[26:27], v[234:235] op_sel_hi:[1,0]
	v_pk_mul_f32 v[24:25], v[72:73], v[24:25]
	v_pk_mul_f32 v[26:27], v[74:75], v[26:27]
	v_pk_fma_f32 v[24:25], v[168:169], v[24:25], v[184:185]
	v_pk_fma_f32 v[26:27], v[170:171], v[26:27], v[186:187]
	v_cvt_pk_bf16_f32 v240, v24, v25
	v_cvt_pk_bf16_f32 v241, v26, v27
	v_pk_mul_f32 v[28:29], v[28:29], v[234:235] op_sel_hi:[1,0]
	v_pk_mul_f32 v[30:31], v[30:31], v[234:235] op_sel_hi:[1,0]
	v_pk_mul_f32 v[28:29], v[76:77], v[28:29]
	v_pk_mul_f32 v[30:31], v[78:79], v[30:31]
	v_pk_fma_f32 v[28:29], v[172:173], v[28:29], v[188:189]
	v_pk_fma_f32 v[30:31], v[174:175], v[30:31], v[190:191]
	v_cvt_pk_bf16_f32 v242, v28, v29
	v_cvt_pk_bf16_f32 v243, v30, v31
	global_store_dwordx4 v82, v[240:243], s[40:41] offset:1024
	v_pk_mul_f32 v[32:33], v[32:33], v[236:237] op_sel_hi:[1,0]
	v_pk_mul_f32 v[34:35], v[34:35], v[236:237] op_sel_hi:[1,0]
	v_pk_mul_f32 v[32:33], v[64:65], v[32:33]
	v_pk_mul_f32 v[34:35], v[66:67], v[34:35]
	v_pk_fma_f32 v[32:33], v[192:193], v[32:33], v[208:209]
	v_pk_fma_f32 v[34:35], v[194:195], v[34:35], v[210:211]
	v_cvt_pk_bf16_f32 v244, v32, v33
	v_cvt_pk_bf16_f32 v245, v34, v35
	v_pk_mul_f32 v[36:37], v[36:37], v[236:237] op_sel_hi:[1,0]
	v_pk_mul_f32 v[38:39], v[38:39], v[236:237] op_sel_hi:[1,0]
	v_pk_mul_f32 v[36:37], v[68:69], v[36:37]
	v_pk_mul_f32 v[38:39], v[70:71], v[38:39]
	v_pk_fma_f32 v[36:37], v[196:197], v[36:37], v[212:213]
	v_pk_fma_f32 v[38:39], v[198:199], v[38:39], v[214:215]
	v_cvt_pk_bf16_f32 v246, v36, v37
	v_cvt_pk_bf16_f32 v247, v38, v39
	global_store_dwordx4 v82, v[244:247], s[46:47] offset:0
	v_pk_mul_f32 v[40:41], v[40:41], v[236:237] op_sel_hi:[1,0]
	v_pk_mul_f32 v[42:43], v[42:43], v[236:237] op_sel_hi:[1,0]
	v_pk_mul_f32 v[40:41], v[72:73], v[40:41]
	v_pk_mul_f32 v[42:43], v[74:75], v[42:43]
	v_pk_fma_f32 v[40:41], v[200:201], v[40:41], v[216:217]
	v_pk_fma_f32 v[42:43], v[202:203], v[42:43], v[218:219]
	v_cvt_pk_bf16_f32 v240, v40, v41
; __device__ __forceinline__ float bf_lo(unsigned w) { return __uint_as_float(w << 16); }
; __device__ __forceinline__ float bf_hi(unsigned w) { return __uint_as_float(w & 0xffff0000u); }
; __device__ __forceinline__ unsigned pk2(float lo, float hi) { return pg8::cvt_pk_bf16(lo, hi); }
; template <bool BF> __device__ __forceinline__ void prep_rows(const float* xp, const float* xs, const bf16* hb, const float* g, const float* MOD, int shoff, int scoff, bf16* U, int gw, int NGW, int lane) {
;     ...
;     for (int mb = gw; mb < MT; mb += R * NGW) {
;         f32x4 v[R][4]; float s[R];
; #pragma unroll
;         for (int r = 0; r < R; ++r) { const int m = mb + r * NGW; const int mc = m < MT ? m : mb;
; #pragma unroll
;             for (int j = 0; j < 4; ++j) {
;                 if (BF) { const v2u a0 = *(const v2u*)(hb + (size_t)mc * DM + 4 * lane + 256 * j);
;                     v[r][j].x = pg8::bf_lo(a0.x); v[r][j].y = pg8::bf_hi(a0.x); v[r][j].z = pg8::bf_lo(a0.y); v[r][j].w = pg8::bf_hi(a0.y); }
;                 else { const float* xr = mc < MP ? xp + (size_t)mc * DM : xs + (size_t)(mc - MP) * DM; v[r][j] = *(const f32x4*)(xr + 4 * lane + 256 * j); } } }
;     ...
; #pragma unroll
;             for (int j = 0; j < 4; ++j) { const int c = 4 * lane + 256 * j;
;                 const f32x4 gg = *(const f32x4*)(g + c), sc = *(const f32x4*)(mr + scoff + c), sh = *(const f32x4*)(mr + shoff + c);
;                 const f32x4 o = v[r][j] * rstd * gg * (sc + 1.0f) + sh; v2u w; w.x = pk2(o.x, o.y); w.y = pk2(o.z, o.w); *(v2u*)(U + (size_t)m * DM + c) = w; } } }
	v_cvt_pk_bf16_f32 v241, v42, v43
	v_pk_mul_f32 v[44:45], v[44:45], v[236:237] op_sel_hi:[1,0]
	v_pk_mul_f32 v[46:47], v[46:47], v[236:237] op_sel_hi:[1,0]
	v_pk_mul_f32 v[44:45], v[76:77], v[44:45]
	v_pk_mul_f32 v[46:47], v[78:79], v[46:47]
	v_pk_fma_f32 v[44:45], v[204:205], v[44:45], v[220:221]
	v_pk_fma_f32 v[46:47], v[206:207], v[46:47], v[222:223]
	v_cvt_pk_bf16_f32 v242, v44, v45
	v_cvt_pk_bf16_f32 v243, v46, v47
	global_store_dwordx4 v82, v[240:243], s[46:47] offset:1024
	v_pk_mul_f32 v[48:49], v[48:49], v[238:239] op_sel_hi:[1,0]
	v_pk_mul_f32 v[50:51], v[50:51], v[238:239] op_sel_hi:[1,0]
	v_pk_mul_f32 v[48:49], v[64:65], v[48:49]
	v_pk_mul_f32 v[50:51], v[66:67], v[50:51]
	v_pk_fma_f32 v[48:49], v[192:193], v[48:49], v[208:209]
	v_pk_fma_f32 v[50:51], v[194:195], v[50:51], v[210:211]
	v_cvt_pk_bf16_f32 v244, v48, v49
	v_cvt_pk_bf16_f32 v245, v50, v51
	v_pk_mul_f32 v[52:53], v[52:53], v[238:239] op_sel_hi:[1,0]
	v_pk_mul_f32 v[54:55], v[54:55], v[238:239] op_sel_hi:[1,0]
	v_pk_mul_f32 v[52:53], v[68:69], v[52:53]
	v_pk_mul_f32 v[54:55], v[70:71], v[54:55]
	v_pk_fma_f32 v[52:53], v[196:197], v[52:53], v[212:213]
	v_pk_fma_f32 v[54:55], v[198:199], v[54:55], v[214:215]
	v_cvt_pk_bf16_f32 v246, v52, v53
	v_cvt_pk_bf16_f32 v247, v54, v55
	global_store_dwordx4 v82, v[244:247], s[48:49] offset:0
	v_pk_mul_f32 v[56:57], v[56:57], v[238:239] op_sel_hi:[1,0]
	v_pk_mul_f32 v[58:59], v[58:59], v[238:239] op_sel_hi:[1,0]
	v_pk_mul_f32 v[56:57], v[72:73], v[56:57]
	v_pk_mul_f32 v[58:59], v[74:75], v[58:59]
	v_pk_fma_f32 v[56:57], v[200:201], v[56:57], v[216:217]
	v_pk_fma_f32 v[58:59], v[202:203], v[58:59], v[218:219]
	v_cvt_pk_bf16_f32 v240, v56, v57
	v_cvt_pk_bf16_f32 v241, v58, v59
	v_pk_mul_f32 v[60:61], v[60:61], v[238:239] op_sel_hi:[1,0]
	v_pk_mul_f32 v[62:63], v[62:63], v[238:239] op_sel_hi:[1,0]
	v_pk_mul_f32 v[60:61], v[76:77], v[60:61]
	v_pk_mul_f32 v[62:63], v[78:79], v[62:63]
	v_pk_fma_f32 v[60:61], v[204:205], v[60:61], v[220:221]
	v_pk_fma_f32 v[62:63], v[206:207], v[62:63], v[222:223]
	v_cvt_pk_bf16_f32 v242, v60, v61
	v_cvt_pk_bf16_f32 v243, v62, v63
	global_store_dwordx4 v82, v[240:243], s[48:49] offset:1024
	s_add_u32 s34, s8, 0xf000
	s_addc_u32 s35, s9, 0
	s_add_u32 s36, s8, 0xf000
	s_addc_u32 s37, s9, 0
	global_load_dwordx4 v[176:179], v80, s[34:35] offset:0
	global_load_dwordx4 v[180:183], v80, s[34:35] offset:16
	global_load_dwordx4 v[184:187], v80, s[34:35] offset:2048
	global_load_dwordx4 v[188:191], v80, s[34:35] offset:2064
	global_load_dwordx4 v[160:163], v81, s[34:35] offset:0
	global_load_dwordx4 v[164:167], v81, s[34:35] offset:16
	global_load_dwordx4 v[168:171], v81, s[34:35] offset:2048
	global_load_dwordx4 v[172:175], v81, s[34:35] offset:2064
	global_load_dwordx4 v[208:211], v80, s[36:37] offset:0
	global_load_dwordx4 v[212:215], v80, s[36:37] offset:16
	global_load_dwordx4 v[216:219], v80, s[36:37] offset:2048
	global_load_dwordx4 v[220:223], v80, s[36:37] offset:2064
	global_load_dwordx4 v[192:195], v81, s[36:37] offset:0
	global_load_dwordx4 v[196:199], v81, s[36:37] offset:16
	global_load_dwordx4 v[200:203], v81, s[36:37] offset:2048
	global_load_dwordx4 v[204:207], v81, s[36:37] offset:2064
	s_add_u32 s24, s16, 0x3000000
	s_addc_u32 s25, s17, 0
	s_add_u32 s26, s16, 0x3400000
	s_addc_u32 s27, s17, 0
	s_add_u32 s28, s16, 0x3800000
	s_addc_u32 s29, s17, 0
	s_add_u32 s30, s16, 0x3c00000
	s_addc_u32 s31, s17, 0
	global_load_dwordx4 v[128:131], v82, s[24:25] offset:0 nt
	global_load_dwordx4 v[132:135], v82, s[24:25] offset:1024 nt
	global_load_dwordx4 v[136:139], v82, s[26:27] offset:0 nt
	global_load_dwordx4 v[140:143], v82, s[26:27] offset:1024 nt
	global_load_dwordx4 v[144:147], v82, s[28:29] offset:0 nt
	global_load_dwordx4 v[148:151], v82, s[28:29] offset:1024 nt
	global_load_dwordx4 v[152:155], v82, s[30:31] offset:0 nt
	global_load_dwordx4 v[156:159], v82, s[30:31] offset:1024 nt
	s_waitcnt vmcnt(32)
	v_lshlrev_b32_e32 v0, 16, v96
	v_and_b32_e32 v1, 0xffff0000, v96
	v_lshlrev_b32_e32 v2, 16, v97
	v_and_b32_e32 v3, 0xffff0000, v97
	v_lshlrev_b32_e32 v4, 16, v98
	v_and_b32_e32 v5, 0xffff0000, v98
	v_lshlrev_b32_e32 v6, 16, v99
	v_and_b32_e32 v7, 0xffff0000, v99
	v_lshlrev_b32_e32 v8, 16, v100
	v_and_b32_e32 v9, 0xffff0000, v100
	v_lshlrev_b32_e32 v10, 16, v101
	v_and_b32_e32 v11, 0xffff0000, v101
	v_lshlrev_b32_e32 v12, 16, v102
	v_and_b32_e32 v13, 0xffff0000, v102
	v_lshlrev_b32_e32 v14, 16, v103
	v_and_b32_e32 v15, 0xffff0000, v103
	v_lshlrev_b32_e32 v16, 16, v104
	v_and_b32_e32 v17, 0xffff0000, v104
	v_lshlrev_b32_e32 v18, 16, v105
	v_and_b32_e32 v19, 0xffff0000, v105
	v_lshlrev_b32_e32 v20, 16, v106
	v_and_b32_e32 v21, 0xffff0000, v106
	v_lshlrev_b32_e32 v22, 16, v107
	v_and_b32_e32 v23, 0xffff0000, v107
	v_lshlrev_b32_e32 v24, 16, v108
	v_and_b32_e32 v25, 0xffff0000, v108
	v_lshlrev_b32_e32 v26, 16, v109
	v_and_b32_e32 v27, 0xffff0000, v109
	v_lshlrev_b32_e32 v28, 16, v110
	v_and_b32_e32 v29, 0xffff0000, v110
	v_lshlrev_b32_e32 v30, 16, v111
	v_and_b32_e32 v31, 0xffff0000, v111
	v_lshlrev_b32_e32 v32, 16, v112
	v_and_b32_e32 v33, 0xffff0000, v112
	v_lshlrev_b32_e32 v34, 16, v113
	v_and_b32_e32 v35, 0xffff0000, v113
	v_lshlrev_b32_e32 v36, 16, v114
	v_and_b32_e32 v37, 0xffff0000, v114
	v_lshlrev_b32_e32 v38, 16, v115
	v_and_b32_e32 v39, 0xffff0000, v115
	v_lshlrev_b32_e32 v40, 16, v116
	v_and_b32_e32 v41, 0xffff0000, v116
	v_lshlrev_b32_e32 v42, 16, v117
	v_and_b32_e32 v43, 0xffff0000, v117
	v_lshlrev_b32_e32 v44, 16, v118
	v_and_b32_e32 v45, 0xffff0000, v118
	v_lshlrev_b32_e32 v46, 16, v119
	v_and_b32_e32 v47, 0xffff0000, v119
	v_lshlrev_b32_e32 v48, 16, v120
	v_and_b32_e32 v49, 0xffff0000, v120
; __device__ __forceinline__ float bf_lo(unsigned w) { return __uint_as_float(w << 16); }
; __device__ __forceinline__ float bf_hi(unsigned w) { return __uint_as_float(w & 0xffff0000u); }
; template <bool BF> __device__ __forceinline__ void prep_rows(const float* xp, const float* xs, const bf16* hb, const float* g, const float* MOD, int shoff, int scoff, bf16* U, int gw, int NGW, int lane) {
;     ...
;                 if (BF) { const v2u a0 = *(const v2u*)(hb + (size_t)mc * DM + 4 * lane + 256 * j);
;                     v[r][j].x = pg8::bf_lo(a0.x); v[r][j].y = pg8::bf_hi(a0.x); v[r][j].z = pg8::bf_lo(a0.y); v[r][j].w = pg8::bf_hi(a0.y); }
;                 else { const float* xr = mc < MP ? xp + (size_t)mc * DM : xs + (size_t)(mc - MP) * DM; v[r][j] = *(const f32x4*)(xr + 4 * lane + 256 * j); } } }
; #pragma unroll
;         for (int r = 0; r < R; ++r) { float t = 0.f;
; #pragma unroll
;             for (int j = 0; j < 4; ++j) t += (v[r][j].x * v[r][j].x + v[r][j].y * v[r][j].y) + (v[r][j].z * v[r][j].z + v[r][j].w * v[r][j].w);
;             s[r] = t; }
; #pragma unroll
;         for (int o = 1; o < 64; o <<= 1) {
; #pragma unroll
;             for (int r = 0; r < R; ++r) s[r] += __shfl_xor(s[r], o); }
; #pragma unroll
;         for (int r = 0; r < R; ++r) { const int m = mb + r * NGW; if (m < MT) {
;             const float rstd = 1.0f / sqrtf(s[r] * (1.0f / DM) + RMS_EPS);
	v_lshlrev_b32_e32 v50, 16, v121
	v_and_b32_e32 v51, 0xffff0000, v121
	v_lshlrev_b32_e32 v52, 16, v122
	v_and_b32_e32 v53, 0xffff0000, v122
	v_lshlrev_b32_e32 v54, 16, v123
	v_and_b32_e32 v55, 0xffff0000, v123
	v_lshlrev_b32_e32 v56, 16, v124
	v_and_b32_e32 v57, 0xffff0000, v124
	v_lshlrev_b32_e32 v58, 16, v125
	v_and_b32_e32 v59, 0xffff0000, v125
	v_lshlrev_b32_e32 v60, 16, v126
	v_and_b32_e32 v61, 0xffff0000, v126
	v_lshlrev_b32_e32 v62, 16, v127
	v_and_b32_e32 v63, 0xffff0000, v127
	v_pk_mul_f32 v[240:241], v[0:1], v[0:1]
	v_pk_mul_f32 v[242:243], v[16:17], v[16:17]
	v_pk_mul_f32 v[244:245], v[32:33], v[32:33]
	v_pk_mul_f32 v[246:247], v[48:49], v[48:49]
	v_pk_fma_f32 v[240:241], v[2:3], v[2:3], v[240:241]
	v_pk_fma_f32 v[242:243], v[18:19], v[18:19], v[242:243]
	v_pk_fma_f32 v[244:245], v[34:35], v[34:35], v[244:245]
	v_pk_fma_f32 v[246:247], v[50:51], v[50:51], v[246:247]
	v_pk_fma_f32 v[240:241], v[4:5], v[4:5], v[240:241]
	v_pk_fma_f32 v[242:243], v[20:21], v[20:21], v[242:243]
	v_pk_fma_f32 v[244:245], v[36:37], v[36:37], v[244:245]
	v_pk_fma_f32 v[246:247], v[52:53], v[52:53], v[246:247]
	v_pk_fma_f32 v[240:241], v[6:7], v[6:7], v[240:241]
	v_pk_fma_f32 v[242:243], v[22:23], v[22:23], v[242:243]
	v_pk_fma_f32 v[244:245], v[38:39], v[38:39], v[244:245]
	v_pk_fma_f32 v[246:247], v[54:55], v[54:55], v[246:247]
	v_pk_fma_f32 v[240:241], v[8:9], v[8:9], v[240:241]
	v_pk_fma_f32 v[242:243], v[24:25], v[24:25], v[242:243]
	v_pk_fma_f32 v[244:245], v[40:41], v[40:41], v[244:245]
	v_pk_fma_f32 v[246:247], v[56:57], v[56:57], v[246:247]
	v_pk_fma_f32 v[240:241], v[10:11], v[10:11], v[240:241]
	v_pk_fma_f32 v[242:243], v[26:27], v[26:27], v[242:243]
	v_pk_fma_f32 v[244:245], v[42:43], v[42:43], v[244:245]
	v_pk_fma_f32 v[246:247], v[58:59], v[58:59], v[246:247]
	v_pk_fma_f32 v[240:241], v[12:13], v[12:13], v[240:241]
	v_pk_fma_f32 v[242:243], v[28:29], v[28:29], v[242:243]
	v_pk_fma_f32 v[244:245], v[44:45], v[44:45], v[244:245]
	v_pk_fma_f32 v[246:247], v[60:61], v[60:61], v[246:247]
	v_pk_fma_f32 v[240:241], v[14:15], v[14:15], v[240:241]
	v_pk_fma_f32 v[242:243], v[30:31], v[30:31], v[242:243]
	v_pk_fma_f32 v[244:245], v[46:47], v[46:47], v[244:245]
	v_pk_fma_f32 v[246:247], v[62:63], v[62:63], v[246:247]
	v_add_f32_e32 v224, v240, v241
	v_add_f32_e32 v225, v242, v243
	v_add_f32_e32 v226, v244, v245
	v_add_f32_e32 v227, v246, v247
	ds_bpermute_b32 v228, v83, v224
	ds_bpermute_b32 v229, v83, v225
	ds_bpermute_b32 v230, v83, v226
	ds_bpermute_b32 v231, v83, v227
	s_waitcnt lgkmcnt(0)
	v_add_f32_e32 v224, v224, v228
	v_add_f32_e32 v225, v225, v229
	v_add_f32_e32 v226, v226, v230
	v_add_f32_e32 v227, v227, v231
	ds_bpermute_b32 v228, v84, v224
	ds_bpermute_b32 v229, v84, v225
	ds_bpermute_b32 v230, v84, v226
	ds_bpermute_b32 v231, v84, v227
	s_waitcnt lgkmcnt(0)
	v_add_f32_e32 v224, v224, v228
	v_add_f32_e32 v225, v225, v229
	v_add_f32_e32 v226, v226, v230
	v_add_f32_e32 v227, v227, v231
	ds_bpermute_b32 v228, v85, v224
	ds_bpermute_b32 v229, v85, v225
	ds_bpermute_b32 v230, v85, v226
	ds_bpermute_b32 v231, v85, v227
	s_waitcnt lgkmcnt(0)
	v_add_f32_e32 v224, v224, v228
	v_add_f32_e32 v225, v225, v229
	v_add_f32_e32 v226, v226, v230
	v_add_f32_e32 v227, v227, v231
	ds_bpermute_b32 v228, v86, v224
	ds_bpermute_b32 v229, v86, v225
	ds_bpermute_b32 v230, v86, v226
	ds_bpermute_b32 v231, v86, v227
	s_waitcnt lgkmcnt(0)
	v_add_f32_e32 v224, v224, v228
	v_add_f32_e32 v225, v225, v229
	v_add_f32_e32 v226, v226, v230
	v_add_f32_e32 v227, v227, v231
	ds_bpermute_b32 v228, v87, v224
	ds_bpermute_b32 v229, v87, v225
	ds_bpermute_b32 v230, v87, v226
	ds_bpermute_b32 v231, v87, v227
	s_waitcnt lgkmcnt(0)
	v_add_f32_e32 v224, v224, v228
	v_add_f32_e32 v225, v225, v229
	v_add_f32_e32 v226, v226, v230
	v_add_f32_e32 v227, v227, v231
	ds_bpermute_b32 v228, v88, v224
	ds_bpermute_b32 v229, v88, v225
	ds_bpermute_b32 v230, v88, v226
	ds_bpermute_b32 v231, v88, v227
	s_waitcnt lgkmcnt(0)
	v_add_f32_e32 v224, v224, v228
	v_add_f32_e32 v225, v225, v229
	v_add_f32_e32 v226, v226, v230
	v_add_f32_e32 v227, v227, v231
	v_fmamk_f32 v240, v224, 0x3a800000, v89
	v_mul_f32_e32 v241, 0x4f800000, v240
	v_cmp_gt_f32_e32 vcc, s54, v240
	s_nop 1
	v_cndmask_b32_e32 v247, v240, v241, vcc
	v_sqrt_f32_e32 v242, v247
	s_nop 1
	v_add_u32_e32 v243, -1, v242
	v_add_u32_e32 v244, 1, v242
	v_fma_f32 v245, -v243, v242, v247
	v_fma_f32 v246, -v244, v242, v247
	v_cmp_ge_f32_e64 s[52:53], 0, v245
	s_nop 1
	v_cndmask_b32_e64 v242, v242, v243, s[52:53]
	v_cmp_lt_f32_e64 s[52:53], 0, v246
	s_nop 1
	v_cndmask_b32_e64 v242, v242, v244, s[52:53]
	v_mul_f32_e32 v243, 0x37800000, v242
	v_cndmask_b32_e32 v242, v242, v243, vcc
	v_cmp_class_f32_e32 vcc, v247, v90
	s_nop 1
	v_cndmask_b32_e32 v247, v242, v247, vcc
	v_div_scale_f32 v248, s[52:53], v247, v247, 1.0
	v_rcp_f32_e32 v249, v248
	v_div_scale_f32 v228, vcc, 1.0, v247, 1.0
	s_nop 0
	v_fma_f32 v229, -v248, v249, 1.0
	v_fmac_f32_e32 v249, v229, v249
	v_mul_f32_e32 v230, v228, v249
	v_fma_f32 v229, -v248, v230, v228
	v_fmac_f32_e32 v230, v229, v249
	v_fma_f32 v248, -v248, v230, v228
	v_div_fmas_f32 v248, v248, v249, v230
	v_div_fixup_f32 v232, v248, v247, 1.0
	v_fmamk_f32 v240, v225, 0x3a800000, v89
	v_mul_f32_e32 v241, 0x4f800000, v240
	v_cmp_gt_f32_e32 vcc, s54, v240
	s_nop 1
	v_cndmask_b32_e32 v247, v240, v241, vcc
	v_sqrt_f32_e32 v242, v247
	s_nop 1
	v_add_u32_e32 v243, -1, v242
	v_add_u32_e32 v244, 1, v242
	v_fma_f32 v245, -v243, v242, v247
	v_fma_f32 v246, -v244, v242, v247
	v_cmp_ge_f32_e64 s[52:53], 0, v245
	s_nop 1
	v_cndmask_b32_e64 v242, v242, v243, s[52:53]
	v_cmp_lt_f32_e64 s[52:53], 0, v246
	s_nop 1
	v_cndmask_b32_e64 v242, v242, v244, s[52:53]
; __device__ __forceinline__ unsigned pk2(float lo, float hi) { return pg8::cvt_pk_bf16(lo, hi); }
; template <bool BF> __device__ __forceinline__ void prep_rows(const float* xp, const float* xs, const bf16* hb, const float* g, const float* MOD, int shoff, int scoff, bf16* U, int gw, int NGW, int lane) {
;     ...
;             const float rstd = 1.0f / sqrtf(s[r] * (1.0f / DM) + RMS_EPS);
;             const float* mr = MOD + (size_t)(m < MP ? (m >> 13) : 8 + ((m - MP) >> 12)) * 6144;
; #pragma unroll
;             for (int j = 0; j < 4; ++j) { const int c = 4 * lane + 256 * j;
;                 const f32x4 gg = *(const f32x4*)(g + c), sc = *(const f32x4*)(mr + scoff + c), sh = *(const f32x4*)(mr + shoff + c);
;                 const f32x4 o = v[r][j] * rstd * gg * (sc + 1.0f) + sh; v2u w; w.x = pk2(o.x, o.y); w.y = pk2(o.z, o.w); *(v2u*)(U + (size_t)m * DM + c) = w; } } }
	v_mul_f32_e32 v243, 0x37800000, v242
	v_cndmask_b32_e32 v242, v242, v243, vcc
	v_cmp_class_f32_e32 vcc, v247, v90
	s_nop 1
	v_cndmask_b32_e32 v247, v242, v247, vcc
	v_div_scale_f32 v248, s[52:53], v247, v247, 1.0
	v_rcp_f32_e32 v249, v248
	v_div_scale_f32 v228, vcc, 1.0, v247, 1.0
	s_nop 0
	v_fma_f32 v229, -v248, v249, 1.0
	v_fmac_f32_e32 v249, v229, v249
	v_mul_f32_e32 v230, v228, v249
	v_fma_f32 v229, -v248, v230, v228
	v_fmac_f32_e32 v230, v229, v249
	v_fma_f32 v248, -v248, v230, v228
	v_div_fmas_f32 v248, v248, v249, v230
	v_div_fixup_f32 v234, v248, v247, 1.0
	v_fmamk_f32 v240, v226, 0x3a800000, v89
	v_mul_f32_e32 v241, 0x4f800000, v240
	v_cmp_gt_f32_e32 vcc, s54, v240
	s_nop 1
	v_cndmask_b32_e32 v247, v240, v241, vcc
	v_sqrt_f32_e32 v242, v247
	s_nop 1
	v_add_u32_e32 v243, -1, v242
	v_add_u32_e32 v244, 1, v242
	v_fma_f32 v245, -v243, v242, v247
	v_fma_f32 v246, -v244, v242, v247
	v_cmp_ge_f32_e64 s[52:53], 0, v245
	s_nop 1
	v_cndmask_b32_e64 v242, v242, v243, s[52:53]
	v_cmp_lt_f32_e64 s[52:53], 0, v246
	s_nop 1
	v_cndmask_b32_e64 v242, v242, v244, s[52:53]
	v_mul_f32_e32 v243, 0x37800000, v242
	v_cndmask_b32_e32 v242, v242, v243, vcc
	v_cmp_class_f32_e32 vcc, v247, v90
	s_nop 1
	v_cndmask_b32_e32 v247, v242, v247, vcc
	v_div_scale_f32 v248, s[52:53], v247, v247, 1.0
	v_rcp_f32_e32 v249, v248
	v_div_scale_f32 v228, vcc, 1.0, v247, 1.0
	s_nop 0
	v_fma_f32 v229, -v248, v249, 1.0
	v_fmac_f32_e32 v249, v229, v249
	v_mul_f32_e32 v230, v228, v249
	v_fma_f32 v229, -v248, v230, v228
	v_fmac_f32_e32 v230, v229, v249
	v_fma_f32 v248, -v248, v230, v228
	v_div_fmas_f32 v248, v248, v249, v230
	v_div_fixup_f32 v236, v248, v247, 1.0
	v_fmamk_f32 v240, v227, 0x3a800000, v89
	v_mul_f32_e32 v241, 0x4f800000, v240
	v_cmp_gt_f32_e32 vcc, s54, v240
	s_nop 1
	v_cndmask_b32_e32 v247, v240, v241, vcc
	v_sqrt_f32_e32 v242, v247
	s_nop 1
	v_add_u32_e32 v243, -1, v242
	v_add_u32_e32 v244, 1, v242
	v_fma_f32 v245, -v243, v242, v247
	v_fma_f32 v246, -v244, v242, v247
	v_cmp_ge_f32_e64 s[52:53], 0, v245
	s_nop 1
	v_cndmask_b32_e64 v242, v242, v243, s[52:53]
	v_cmp_lt_f32_e64 s[52:53], 0, v246
	s_nop 1
	v_cndmask_b32_e64 v242, v242, v244, s[52:53]
	v_mul_f32_e32 v243, 0x37800000, v242
	v_cndmask_b32_e32 v242, v242, v243, vcc
	v_cmp_class_f32_e32 vcc, v247, v90
	s_nop 1
	v_cndmask_b32_e32 v247, v242, v247, vcc
	v_div_scale_f32 v248, s[52:53], v247, v247, 1.0
	v_rcp_f32_e32 v249, v248
	v_div_scale_f32 v228, vcc, 1.0, v247, 1.0
	s_nop 0
	v_fma_f32 v229, -v248, v249, 1.0
	v_fmac_f32_e32 v249, v229, v249
	v_mul_f32_e32 v230, v228, v249
	v_fma_f32 v229, -v248, v230, v228
	v_fmac_f32_e32 v230, v229, v249
	v_fma_f32 v248, -v248, v230, v228
	v_div_fmas_f32 v248, v248, v249, v230
	v_div_fixup_f32 v238, v248, v247, 1.0
	s_waitcnt vmcnt(8)
	v_pk_add_f32 v[160:161], v[160:161], 1.0 op_sel_hi:[1,0]
	v_pk_add_f32 v[162:163], v[162:163], 1.0 op_sel_hi:[1,0]
	v_pk_add_f32 v[164:165], v[164:165], 1.0 op_sel_hi:[1,0]
	v_pk_add_f32 v[166:167], v[166:167], 1.0 op_sel_hi:[1,0]
	v_pk_add_f32 v[168:169], v[168:169], 1.0 op_sel_hi:[1,0]
	v_pk_add_f32 v[170:171], v[170:171], 1.0 op_sel_hi:[1,0]
	v_pk_add_f32 v[172:173], v[172:173], 1.0 op_sel_hi:[1,0]
	v_pk_add_f32 v[174:175], v[174:175], 1.0 op_sel_hi:[1,0]
	v_pk_add_f32 v[192:193], v[192:193], 1.0 op_sel_hi:[1,0]
	v_pk_add_f32 v[194:195], v[194:195], 1.0 op_sel_hi:[1,0]
	v_pk_add_f32 v[196:197], v[196:197], 1.0 op_sel_hi:[1,0]
	v_pk_add_f32 v[198:199], v[198:199], 1.0 op_sel_hi:[1,0]
	v_pk_add_f32 v[200:201], v[200:201], 1.0 op_sel_hi:[1,0]
	v_pk_add_f32 v[202:203], v[202:203], 1.0 op_sel_hi:[1,0]
	v_pk_add_f32 v[204:205], v[204:205], 1.0 op_sel_hi:[1,0]
	v_pk_add_f32 v[206:207], v[206:207], 1.0 op_sel_hi:[1,0]
	s_add_u32 s38, s20, 0x2000000
	s_addc_u32 s39, s21, 0
	s_add_u32 s40, s20, 0x2400000
	s_addc_u32 s41, s21, 0
	s_add_u32 s46, s20, 0x2800000
	s_addc_u32 s47, s21, 0
	s_add_u32 s48, s20, 0x2c00000
	s_addc_u32 s49, s21, 0
	v_pk_mul_f32 v[0:1], v[0:1], v[232:233] op_sel_hi:[1,0]
	v_pk_mul_f32 v[2:3], v[2:3], v[232:233] op_sel_hi:[1,0]
	v_pk_mul_f32 v[0:1], v[64:65], v[0:1]
	v_pk_mul_f32 v[2:3], v[66:67], v[2:3]
	v_pk_fma_f32 v[0:1], v[160:161], v[0:1], v[176:177]
	v_pk_fma_f32 v[2:3], v[162:163], v[2:3], v[178:179]
	v_cvt_pk_bf16_f32 v244, v0, v1
	v_cvt_pk_bf16_f32 v245, v2, v3
	v_pk_mul_f32 v[4:5], v[4:5], v[232:233] op_sel_hi:[1,0]
	v_pk_mul_f32 v[6:7], v[6:7], v[232:233] op_sel_hi:[1,0]
	v_pk_mul_f32 v[4:5], v[68:69], v[4:5]
	v_pk_mul_f32 v[6:7], v[70:71], v[6:7]
	v_pk_fma_f32 v[4:5], v[164:165], v[4:5], v[180:181]
	v_pk_fma_f32 v[6:7], v[166:167], v[6:7], v[182:183]
	v_cvt_pk_bf16_f32 v246, v4, v5
	v_cvt_pk_bf16_f32 v247, v6, v7
	global_store_dwordx4 v82, v[244:247], s[38:39] offset:0
	v_pk_mul_f32 v[8:9], v[8:9], v[232:233] op_sel_hi:[1,0]
	v_pk_mul_f32 v[10:11], v[10:11], v[232:233] op_sel_hi:[1,0]
	v_pk_mul_f32 v[8:9], v[72:73], v[8:9]
	v_pk_mul_f32 v[10:11], v[74:75], v[10:11]
	v_pk_fma_f32 v[8:9], v[168:169], v[8:9], v[184:185]
	v_pk_fma_f32 v[10:11], v[170:171], v[10:11], v[186:187]
	v_cvt_pk_bf16_f32 v240, v8, v9
	v_cvt_pk_bf16_f32 v241, v10, v11
	v_pk_mul_f32 v[12:13], v[12:13], v[232:233] op_sel_hi:[1,0]
	v_pk_mul_f32 v[14:15], v[14:15], v[232:233] op_sel_hi:[1,0]
	v_pk_mul_f32 v[12:13], v[76:77], v[12:13]
	v_pk_mul_f32 v[14:15], v[78:79], v[14:15]
	v_pk_fma_f32 v[12:13], v[172:173], v[12:13], v[188:189]
	v_pk_fma_f32 v[14:15], v[174:175], v[14:15], v[190:191]
	v_cvt_pk_bf16_f32 v242, v12, v13
	v_cvt_pk_bf16_f32 v243, v14, v15
	global_store_dwordx4 v82, v[240:243], s[38:39] offset:1024
	v_pk_mul_f32 v[16:17], v[16:17], v[234:235] op_sel_hi:[1,0]
	v_pk_mul_f32 v[18:19], v[18:19], v[234:235] op_sel_hi:[1,0]
; __device__ __forceinline__ float bf_lo(unsigned w) { return __uint_as_float(w << 16); }
; __device__ __forceinline__ float bf_hi(unsigned w) { return __uint_as_float(w & 0xffff0000u); }
; __device__ __forceinline__ unsigned pk2(float lo, float hi) { return pg8::cvt_pk_bf16(lo, hi); }
; template <bool BF> __device__ __forceinline__ void prep_rows(const float* xp, const float* xs, const bf16* hb, const float* g, const float* MOD, int shoff, int scoff, bf16* U, int gw, int NGW, int lane) {
;     ...
;         for (int r = 0; r < R; ++r) { const int m = mb + r * NGW; const int mc = m < MT ? m : mb;
; #pragma unroll
;             for (int j = 0; j < 4; ++j) {
;                 if (BF) { const v2u a0 = *(const v2u*)(hb + (size_t)mc * DM + 4 * lane + 256 * j);
;                     v[r][j].x = pg8::bf_lo(a0.x); v[r][j].y = pg8::bf_hi(a0.x); v[r][j].z = pg8::bf_lo(a0.y); v[r][j].w = pg8::bf_hi(a0.y); }
;                 else { const float* xr = mc < MP ? xp + (size_t)mc * DM : xs + (size_t)(mc - MP) * DM; v[r][j] = *(const f32x4*)(xr + 4 * lane + 256 * j); } } }
;     ...
;             for (int j = 0; j < 4; ++j) { const int c = 4 * lane + 256 * j;
;                 const f32x4 gg = *(const f32x4*)(g + c), sc = *(const f32x4*)(mr + scoff + c), sh = *(const f32x4*)(mr + shoff + c);
;                 const f32x4 o = v[r][j] * rstd * gg * (sc + 1.0f) + sh; v2u w; w.x = pk2(o.x, o.y); w.y = pk2(o.z, o.w); *(v2u*)(U + (size_t)m * DM + c) = w; } } }
	v_pk_mul_f32 v[16:17], v[64:65], v[16:17]
	v_pk_mul_f32 v[18:19], v[66:67], v[18:19]
	v_pk_fma_f32 v[16:17], v[160:161], v[16:17], v[176:177]
	v_pk_fma_f32 v[18:19], v[162:163], v[18:19], v[178:179]
	v_cvt_pk_bf16_f32 v244, v16, v17
	v_cvt_pk_bf16_f32 v245, v18, v19
	v_pk_mul_f32 v[20:21], v[20:21], v[234:235] op_sel_hi:[1,0]
	v_pk_mul_f32 v[22:23], v[22:23], v[234:235] op_sel_hi:[1,0]
	v_pk_mul_f32 v[20:21], v[68:69], v[20:21]
	v_pk_mul_f32 v[22:23], v[70:71], v[22:23]
	v_pk_fma_f32 v[20:21], v[164:165], v[20:21], v[180:181]
	v_pk_fma_f32 v[22:23], v[166:167], v[22:23], v[182:183]
	v_cvt_pk_bf16_f32 v246, v20, v21
	v_cvt_pk_bf16_f32 v247, v22, v23
	global_store_dwordx4 v82, v[244:247], s[40:41] offset:0
	v_pk_mul_f32 v[24:25], v[24:25], v[234:235] op_sel_hi:[1,0]
	v_pk_mul_f32 v[26:27], v[26:27], v[234:235] op_sel_hi:[1,0]
	v_pk_mul_f32 v[24:25], v[72:73], v[24:25]
	v_pk_mul_f32 v[26:27], v[74:75], v[26:27]
	v_pk_fma_f32 v[24:25], v[168:169], v[24:25], v[184:185]
	v_pk_fma_f32 v[26:27], v[170:171], v[26:27], v[186:187]
	v_cvt_pk_bf16_f32 v240, v24, v25
	v_cvt_pk_bf16_f32 v241, v26, v27
	v_pk_mul_f32 v[28:29], v[28:29], v[234:235] op_sel_hi:[1,0]
	v_pk_mul_f32 v[30:31], v[30:31], v[234:235] op_sel_hi:[1,0]
	v_pk_mul_f32 v[28:29], v[76:77], v[28:29]
	v_pk_mul_f32 v[30:31], v[78:79], v[30:31]
	v_pk_fma_f32 v[28:29], v[172:173], v[28:29], v[188:189]
	v_pk_fma_f32 v[30:31], v[174:175], v[30:31], v[190:191]
	v_cvt_pk_bf16_f32 v242, v28, v29
	v_cvt_pk_bf16_f32 v243, v30, v31
	global_store_dwordx4 v82, v[240:243], s[40:41] offset:1024
	v_pk_mul_f32 v[32:33], v[32:33], v[236:237] op_sel_hi:[1,0]
	v_pk_mul_f32 v[34:35], v[34:35], v[236:237] op_sel_hi:[1,0]
	v_pk_mul_f32 v[32:33], v[64:65], v[32:33]
	v_pk_mul_f32 v[34:35], v[66:67], v[34:35]
	v_pk_fma_f32 v[32:33], v[192:193], v[32:33], v[208:209]
	v_pk_fma_f32 v[34:35], v[194:195], v[34:35], v[210:211]
	v_cvt_pk_bf16_f32 v244, v32, v33
	v_cvt_pk_bf16_f32 v245, v34, v35
	v_pk_mul_f32 v[36:37], v[36:37], v[236:237] op_sel_hi:[1,0]
	v_pk_mul_f32 v[38:39], v[38:39], v[236:237] op_sel_hi:[1,0]
	v_pk_mul_f32 v[36:37], v[68:69], v[36:37]
	v_pk_mul_f32 v[38:39], v[70:71], v[38:39]
	v_pk_fma_f32 v[36:37], v[196:197], v[36:37], v[212:213]
	v_pk_fma_f32 v[38:39], v[198:199], v[38:39], v[214:215]
	v_cvt_pk_bf16_f32 v246, v36, v37
	v_cvt_pk_bf16_f32 v247, v38, v39
	global_store_dwordx4 v82, v[244:247], s[46:47] offset:0
	v_pk_mul_f32 v[40:41], v[40:41], v[236:237] op_sel_hi:[1,0]
	v_pk_mul_f32 v[42:43], v[42:43], v[236:237] op_sel_hi:[1,0]
	v_pk_mul_f32 v[40:41], v[72:73], v[40:41]
	v_pk_mul_f32 v[42:43], v[74:75], v[42:43]
	v_pk_fma_f32 v[40:41], v[200:201], v[40:41], v[216:217]
	v_pk_fma_f32 v[42:43], v[202:203], v[42:43], v[218:219]
	v_cvt_pk_bf16_f32 v240, v40, v41
	v_cvt_pk_bf16_f32 v241, v42, v43
	v_pk_mul_f32 v[44:45], v[44:45], v[236:237] op_sel_hi:[1,0]
	v_pk_mul_f32 v[46:47], v[46:47], v[236:237] op_sel_hi:[1,0]
	v_pk_mul_f32 v[44:45], v[76:77], v[44:45]
	v_pk_mul_f32 v[46:47], v[78:79], v[46:47]
	v_pk_fma_f32 v[44:45], v[204:205], v[44:45], v[220:221]
	v_pk_fma_f32 v[46:47], v[206:207], v[46:47], v[222:223]
	v_cvt_pk_bf16_f32 v242, v44, v45
	v_cvt_pk_bf16_f32 v243, v46, v47
	global_store_dwordx4 v82, v[240:243], s[46:47] offset:1024
	v_pk_mul_f32 v[48:49], v[48:49], v[238:239] op_sel_hi:[1,0]
	v_pk_mul_f32 v[50:51], v[50:51], v[238:239] op_sel_hi:[1,0]
	v_pk_mul_f32 v[48:49], v[64:65], v[48:49]
	v_pk_mul_f32 v[50:51], v[66:67], v[50:51]
	v_pk_fma_f32 v[48:49], v[192:193], v[48:49], v[208:209]
	v_pk_fma_f32 v[50:51], v[194:195], v[50:51], v[210:211]
	v_cvt_pk_bf16_f32 v244, v48, v49
	v_cvt_pk_bf16_f32 v245, v50, v51
	v_pk_mul_f32 v[52:53], v[52:53], v[238:239] op_sel_hi:[1,0]
	v_pk_mul_f32 v[54:55], v[54:55], v[238:239] op_sel_hi:[1,0]
	v_pk_mul_f32 v[52:53], v[68:69], v[52:53]
	v_pk_mul_f32 v[54:55], v[70:71], v[54:55]
	v_pk_fma_f32 v[52:53], v[196:197], v[52:53], v[212:213]
	v_pk_fma_f32 v[54:55], v[198:199], v[54:55], v[214:215]
	v_cvt_pk_bf16_f32 v246, v52, v53
	v_cvt_pk_bf16_f32 v247, v54, v55
	global_store_dwordx4 v82, v[244:247], s[48:49] offset:0
	v_pk_mul_f32 v[56:57], v[56:57], v[238:239] op_sel_hi:[1,0]
	v_pk_mul_f32 v[58:59], v[58:59], v[238:239] op_sel_hi:[1,0]
	v_pk_mul_f32 v[56:57], v[72:73], v[56:57]
	v_pk_mul_f32 v[58:59], v[74:75], v[58:59]
	v_pk_fma_f32 v[56:57], v[200:201], v[56:57], v[216:217]
	v_pk_fma_f32 v[58:59], v[202:203], v[58:59], v[218:219]
	v_cvt_pk_bf16_f32 v240, v56, v57
	v_cvt_pk_bf16_f32 v241, v58, v59
	v_pk_mul_f32 v[60:61], v[60:61], v[238:239] op_sel_hi:[1,0]
	v_pk_mul_f32 v[62:63], v[62:63], v[238:239] op_sel_hi:[1,0]
	v_pk_mul_f32 v[60:61], v[76:77], v[60:61]
	v_pk_mul_f32 v[62:63], v[78:79], v[62:63]
	v_pk_fma_f32 v[60:61], v[204:205], v[60:61], v[220:221]
	v_pk_fma_f32 v[62:63], v[206:207], v[62:63], v[222:223]
	v_cvt_pk_bf16_f32 v242, v60, v61
	v_cvt_pk_bf16_f32 v243, v62, v63
	global_store_dwordx4 v82, v[240:243], s[48:49] offset:1024
	s_add_u32 s34, s8, 0x15000
	s_addc_u32 s35, s9, 0
	s_add_u32 s36, s8, 0x15000
	s_addc_u32 s37, s9, 0
	global_load_dwordx4 v[176:179], v80, s[34:35] offset:0
	global_load_dwordx4 v[180:183], v80, s[34:35] offset:16
	global_load_dwordx4 v[184:187], v80, s[34:35] offset:2048
	global_load_dwordx4 v[188:191], v80, s[34:35] offset:2064
	global_load_dwordx4 v[160:163], v81, s[34:35] offset:0
	global_load_dwordx4 v[164:167], v81, s[34:35] offset:16
	global_load_dwordx4 v[168:171], v81, s[34:35] offset:2048
	global_load_dwordx4 v[172:175], v81, s[34:35] offset:2064
	global_load_dwordx4 v[208:211], v80, s[36:37] offset:0
	global_load_dwordx4 v[212:215], v80, s[36:37] offset:16
	global_load_dwordx4 v[216:219], v80, s[36:37] offset:2048
	global_load_dwordx4 v[220:223], v80, s[36:37] offset:2064
	global_load_dwordx4 v[192:195], v81, s[36:37] offset:0
	global_load_dwordx4 v[196:199], v81, s[36:37] offset:16
	global_load_dwordx4 v[200:203], v81, s[36:37] offset:2048
	global_load_dwordx4 v[204:207], v81, s[36:37] offset:2064
	s_add_u32 s24, s16, 0x4000000
	s_addc_u32 s25, s17, 0
	s_add_u32 s26, s16, 0x4400000
	s_addc_u32 s27, s17, 0
	s_add_u32 s28, s16, 0x4800000
	s_addc_u32 s29, s17, 0
	s_add_u32 s30, s16, 0x4c00000
	s_addc_u32 s31, s17, 0
	global_load_dwordx4 v[96:99], v82, s[24:25] offset:0 nt
	global_load_dwordx4 v[100:103], v82, s[24:25] offset:1024 nt
	global_load_dwordx4 v[104:107], v82, s[26:27] offset:0 nt
	global_load_dwordx4 v[108:111], v82, s[26:27] offset:1024 nt
	global_load_dwordx4 v[112:115], v82, s[28:29] offset:0 nt
	global_load_dwordx4 v[116:119], v82, s[28:29] offset:1024 nt
	global_load_dwordx4 v[120:123], v82, s[30:31] offset:0 nt
	global_load_dwordx4 v[124:127], v82, s[30:31] offset:1024 nt
	s_waitcnt vmcnt(32)
; __device__ __forceinline__ float bf_lo(unsigned w) { return __uint_as_float(w << 16); }
; __device__ __forceinline__ float bf_hi(unsigned w) { return __uint_as_float(w & 0xffff0000u); }
; template <bool BF> __device__ __forceinline__ void prep_rows(const float* xp, const float* xs, const bf16* hb, const float* g, const float* MOD, int shoff, int scoff, bf16* U, int gw, int NGW, int lane) {
;     ...
;                 if (BF) { const v2u a0 = *(const v2u*)(hb + (size_t)mc * DM + 4 * lane + 256 * j);
;                     v[r][j].x = pg8::bf_lo(a0.x); v[r][j].y = pg8::bf_hi(a0.x); v[r][j].z = pg8::bf_lo(a0.y); v[r][j].w = pg8::bf_hi(a0.y); }
;                 else { const float* xr = mc < MP ? xp + (size_t)mc * DM : xs + (size_t)(mc - MP) * DM; v[r][j] = *(const f32x4*)(xr + 4 * lane + 256 * j); } } }
; #pragma unroll
;         for (int r = 0; r < R; ++r) { float t = 0.f;
; #pragma unroll
;             for (int j = 0; j < 4; ++j) t += (v[r][j].x * v[r][j].x + v[r][j].y * v[r][j].y) + (v[r][j].z * v[r][j].z + v[r][j].w * v[r][j].w);
;             s[r] = t; }
; #pragma unroll
;         for (int o = 1; o < 64; o <<= 1) {
; #pragma unroll
;             for (int r = 0; r < R; ++r) s[r] += __shfl_xor(s[r], o); }
	v_lshlrev_b32_e32 v0, 16, v128
	v_and_b32_e32 v1, 0xffff0000, v128
	v_lshlrev_b32_e32 v2, 16, v129
	v_and_b32_e32 v3, 0xffff0000, v129
	v_lshlrev_b32_e32 v4, 16, v130
	v_and_b32_e32 v5, 0xffff0000, v130
	v_lshlrev_b32_e32 v6, 16, v131
	v_and_b32_e32 v7, 0xffff0000, v131
	v_lshlrev_b32_e32 v8, 16, v132
	v_and_b32_e32 v9, 0xffff0000, v132
	v_lshlrev_b32_e32 v10, 16, v133
	v_and_b32_e32 v11, 0xffff0000, v133
	v_lshlrev_b32_e32 v12, 16, v134
	v_and_b32_e32 v13, 0xffff0000, v134
	v_lshlrev_b32_e32 v14, 16, v135
	v_and_b32_e32 v15, 0xffff0000, v135
	v_lshlrev_b32_e32 v16, 16, v136
	v_and_b32_e32 v17, 0xffff0000, v136
	v_lshlrev_b32_e32 v18, 16, v137
	v_and_b32_e32 v19, 0xffff0000, v137
	v_lshlrev_b32_e32 v20, 16, v138
	v_and_b32_e32 v21, 0xffff0000, v138
	v_lshlrev_b32_e32 v22, 16, v139
	v_and_b32_e32 v23, 0xffff0000, v139
	v_lshlrev_b32_e32 v24, 16, v140
	v_and_b32_e32 v25, 0xffff0000, v140
	v_lshlrev_b32_e32 v26, 16, v141
	v_and_b32_e32 v27, 0xffff0000, v141
	v_lshlrev_b32_e32 v28, 16, v142
	v_and_b32_e32 v29, 0xffff0000, v142
	v_lshlrev_b32_e32 v30, 16, v143
	v_and_b32_e32 v31, 0xffff0000, v143
	v_lshlrev_b32_e32 v32, 16, v144
	v_and_b32_e32 v33, 0xffff0000, v144
	v_lshlrev_b32_e32 v34, 16, v145
	v_and_b32_e32 v35, 0xffff0000, v145
	v_lshlrev_b32_e32 v36, 16, v146
	v_and_b32_e32 v37, 0xffff0000, v146
	v_lshlrev_b32_e32 v38, 16, v147
	v_and_b32_e32 v39, 0xffff0000, v147
	v_lshlrev_b32_e32 v40, 16, v148
	v_and_b32_e32 v41, 0xffff0000, v148
	v_lshlrev_b32_e32 v42, 16, v149
	v_and_b32_e32 v43, 0xffff0000, v149
	v_lshlrev_b32_e32 v44, 16, v150
	v_and_b32_e32 v45, 0xffff0000, v150
	v_lshlrev_b32_e32 v46, 16, v151
	v_and_b32_e32 v47, 0xffff0000, v151
	v_lshlrev_b32_e32 v48, 16, v152
	v_and_b32_e32 v49, 0xffff0000, v152
	v_lshlrev_b32_e32 v50, 16, v153
	v_and_b32_e32 v51, 0xffff0000, v153
	v_lshlrev_b32_e32 v52, 16, v154
	v_and_b32_e32 v53, 0xffff0000, v154
	v_lshlrev_b32_e32 v54, 16, v155
	v_and_b32_e32 v55, 0xffff0000, v155
	v_lshlrev_b32_e32 v56, 16, v156
	v_and_b32_e32 v57, 0xffff0000, v156
	v_lshlrev_b32_e32 v58, 16, v157
	v_and_b32_e32 v59, 0xffff0000, v157
	v_lshlrev_b32_e32 v60, 16, v158
	v_and_b32_e32 v61, 0xffff0000, v158
	v_lshlrev_b32_e32 v62, 16, v159
	v_and_b32_e32 v63, 0xffff0000, v159
	v_pk_mul_f32 v[240:241], v[0:1], v[0:1]
	v_pk_mul_f32 v[242:243], v[16:17], v[16:17]
	v_pk_mul_f32 v[244:245], v[32:33], v[32:33]
	v_pk_mul_f32 v[246:247], v[48:49], v[48:49]
	v_pk_fma_f32 v[240:241], v[2:3], v[2:3], v[240:241]
	v_pk_fma_f32 v[242:243], v[18:19], v[18:19], v[242:243]
	v_pk_fma_f32 v[244:245], v[34:35], v[34:35], v[244:245]
	v_pk_fma_f32 v[246:247], v[50:51], v[50:51], v[246:247]
	v_pk_fma_f32 v[240:241], v[4:5], v[4:5], v[240:241]
	v_pk_fma_f32 v[242:243], v[20:21], v[20:21], v[242:243]
	v_pk_fma_f32 v[244:245], v[36:37], v[36:37], v[244:245]
	v_pk_fma_f32 v[246:247], v[52:53], v[52:53], v[246:247]
	v_pk_fma_f32 v[240:241], v[6:7], v[6:7], v[240:241]
	v_pk_fma_f32 v[242:243], v[22:23], v[22:23], v[242:243]
	v_pk_fma_f32 v[244:245], v[38:39], v[38:39], v[244:245]
	v_pk_fma_f32 v[246:247], v[54:55], v[54:55], v[246:247]
	v_pk_fma_f32 v[240:241], v[8:9], v[8:9], v[240:241]
	v_pk_fma_f32 v[242:243], v[24:25], v[24:25], v[242:243]
	v_pk_fma_f32 v[244:245], v[40:41], v[40:41], v[244:245]
	v_pk_fma_f32 v[246:247], v[56:57], v[56:57], v[246:247]
	v_pk_fma_f32 v[240:241], v[10:11], v[10:11], v[240:241]
	v_pk_fma_f32 v[242:243], v[26:27], v[26:27], v[242:243]
	v_pk_fma_f32 v[244:245], v[42:43], v[42:43], v[244:245]
	v_pk_fma_f32 v[246:247], v[58:59], v[58:59], v[246:247]
	v_pk_fma_f32 v[240:241], v[12:13], v[12:13], v[240:241]
	v_pk_fma_f32 v[242:243], v[28:29], v[28:29], v[242:243]
	v_pk_fma_f32 v[244:245], v[44:45], v[44:45], v[244:245]
	v_pk_fma_f32 v[246:247], v[60:61], v[60:61], v[246:247]
	v_pk_fma_f32 v[240:241], v[14:15], v[14:15], v[240:241]
	v_pk_fma_f32 v[242:243], v[30:31], v[30:31], v[242:243]
	v_pk_fma_f32 v[244:245], v[46:47], v[46:47], v[244:245]
	v_pk_fma_f32 v[246:247], v[62:63], v[62:63], v[246:247]
	v_add_f32_e32 v224, v240, v241
	v_add_f32_e32 v225, v242, v243
	v_add_f32_e32 v226, v244, v245
	v_add_f32_e32 v227, v246, v247
	ds_bpermute_b32 v228, v83, v224
	ds_bpermute_b32 v229, v83, v225
	ds_bpermute_b32 v230, v83, v226
	ds_bpermute_b32 v231, v83, v227
	s_waitcnt lgkmcnt(0)
	v_add_f32_e32 v224, v224, v228
	v_add_f32_e32 v225, v225, v229
	v_add_f32_e32 v226, v226, v230
	v_add_f32_e32 v227, v227, v231
	ds_bpermute_b32 v228, v84, v224
	ds_bpermute_b32 v229, v84, v225
	ds_bpermute_b32 v230, v84, v226
	ds_bpermute_b32 v231, v84, v227
	s_waitcnt lgkmcnt(0)
	v_add_f32_e32 v224, v224, v228
	v_add_f32_e32 v225, v225, v229
	v_add_f32_e32 v226, v226, v230
	v_add_f32_e32 v227, v227, v231
	ds_bpermute_b32 v228, v85, v224
	ds_bpermute_b32 v229, v85, v225
	ds_bpermute_b32 v230, v85, v226
	ds_bpermute_b32 v231, v85, v227
	s_waitcnt lgkmcnt(0)
	v_add_f32_e32 v224, v224, v228
	v_add_f32_e32 v225, v225, v229
	v_add_f32_e32 v226, v226, v230
	v_add_f32_e32 v227, v227, v231
	ds_bpermute_b32 v228, v86, v224
	ds_bpermute_b32 v229, v86, v225
	ds_bpermute_b32 v230, v86, v226
	ds_bpermute_b32 v231, v86, v227
	s_waitcnt lgkmcnt(0)
	v_add_f32_e32 v224, v224, v228
	v_add_f32_e32 v225, v225, v229
	v_add_f32_e32 v226, v226, v230
	v_add_f32_e32 v227, v227, v231
	ds_bpermute_b32 v228, v87, v224
	ds_bpermute_b32 v229, v87, v225
	ds_bpermute_b32 v230, v87, v226
	ds_bpermute_b32 v231, v87, v227
	s_waitcnt lgkmcnt(0)
	v_add_f32_e32 v224, v224, v228
	v_add_f32_e32 v225, v225, v229
	v_add_f32_e32 v226, v226, v230
	v_add_f32_e32 v227, v227, v231
	ds_bpermute_b32 v228, v88, v224
	ds_bpermute_b32 v229, v88, v225
	ds_bpermute_b32 v230, v88, v226
	ds_bpermute_b32 v231, v88, v227
	s_waitcnt lgkmcnt(0)
; template <bool BF> __device__ __forceinline__ void prep_rows(const float* xp, const float* xs, const bf16* hb, const float* g, const float* MOD, int shoff, int scoff, bf16* U, int gw, int NGW, int lane) {
;     ...
;             for (int r = 0; r < R; ++r) s[r] += __shfl_xor(s[r], o); }
; #pragma unroll
;         for (int r = 0; r < R; ++r) { const int m = mb + r * NGW; if (m < MT) {
;             const float rstd = 1.0f / sqrtf(s[r] * (1.0f / DM) + RMS_EPS);
	v_add_f32_e32 v224, v224, v228
	v_add_f32_e32 v225, v225, v229
	v_add_f32_e32 v226, v226, v230
	v_add_f32_e32 v227, v227, v231
	v_fmamk_f32 v240, v224, 0x3a800000, v89
	v_mul_f32_e32 v241, 0x4f800000, v240
	v_cmp_gt_f32_e32 vcc, s54, v240
	s_nop 1
	v_cndmask_b32_e32 v247, v240, v241, vcc
	v_sqrt_f32_e32 v242, v247
	s_nop 1
	v_add_u32_e32 v243, -1, v242
	v_add_u32_e32 v244, 1, v242
	v_fma_f32 v245, -v243, v242, v247
	v_fma_f32 v246, -v244, v242, v247
	v_cmp_ge_f32_e64 s[52:53], 0, v245
	s_nop 1
	v_cndmask_b32_e64 v242, v242, v243, s[52:53]
	v_cmp_lt_f32_e64 s[52:53], 0, v246
	s_nop 1
	v_cndmask_b32_e64 v242, v242, v244, s[52:53]
	v_mul_f32_e32 v243, 0x37800000, v242
	v_cndmask_b32_e32 v242, v242, v243, vcc
	v_cmp_class_f32_e32 vcc, v247, v90
	s_nop 1
	v_cndmask_b32_e32 v247, v242, v247, vcc
	v_div_scale_f32 v248, s[52:53], v247, v247, 1.0
	v_rcp_f32_e32 v249, v248
	v_div_scale_f32 v228, vcc, 1.0, v247, 1.0
	s_nop 0
	v_fma_f32 v229, -v248, v249, 1.0
	v_fmac_f32_e32 v249, v229, v249
	v_mul_f32_e32 v230, v228, v249
	v_fma_f32 v229, -v248, v230, v228
	v_fmac_f32_e32 v230, v229, v249
	v_fma_f32 v248, -v248, v230, v228
	v_div_fmas_f32 v248, v248, v249, v230
	v_div_fixup_f32 v232, v248, v247, 1.0
	v_fmamk_f32 v240, v225, 0x3a800000, v89
	v_mul_f32_e32 v241, 0x4f800000, v240
	v_cmp_gt_f32_e32 vcc, s54, v240
	s_nop 1
	v_cndmask_b32_e32 v247, v240, v241, vcc
	v_sqrt_f32_e32 v242, v247
	s_nop 1
	v_add_u32_e32 v243, -1, v242
	v_add_u32_e32 v244, 1, v242
	v_fma_f32 v245, -v243, v242, v247
	v_fma_f32 v246, -v244, v242, v247
	v_cmp_ge_f32_e64 s[52:53], 0, v245
	s_nop 1
	v_cndmask_b32_e64 v242, v242, v243, s[52:53]
	v_cmp_lt_f32_e64 s[52:53], 0, v246
	s_nop 1
	v_cndmask_b32_e64 v242, v242, v244, s[52:53]
	v_mul_f32_e32 v243, 0x37800000, v242
	v_cndmask_b32_e32 v242, v242, v243, vcc
	v_cmp_class_f32_e32 vcc, v247, v90
	s_nop 1
	v_cndmask_b32_e32 v247, v242, v247, vcc
	v_div_scale_f32 v248, s[52:53], v247, v247, 1.0
	v_rcp_f32_e32 v249, v248
	v_div_scale_f32 v228, vcc, 1.0, v247, 1.0
	s_nop 0
	v_fma_f32 v229, -v248, v249, 1.0
	v_fmac_f32_e32 v249, v229, v249
	v_mul_f32_e32 v230, v228, v249
	v_fma_f32 v229, -v248, v230, v228
	v_fmac_f32_e32 v230, v229, v249
	v_fma_f32 v248, -v248, v230, v228
	v_div_fmas_f32 v248, v248, v249, v230
	v_div_fixup_f32 v234, v248, v247, 1.0
	v_fmamk_f32 v240, v226, 0x3a800000, v89
	v_mul_f32_e32 v241, 0x4f800000, v240
	v_cmp_gt_f32_e32 vcc, s54, v240
	s_nop 1
	v_cndmask_b32_e32 v247, v240, v241, vcc
	v_sqrt_f32_e32 v242, v247
	s_nop 1
	v_add_u32_e32 v243, -1, v242
	v_add_u32_e32 v244, 1, v242
	v_fma_f32 v245, -v243, v242, v247
	v_fma_f32 v246, -v244, v242, v247
	v_cmp_ge_f32_e64 s[52:53], 0, v245
	s_nop 1
	v_cndmask_b32_e64 v242, v242, v243, s[52:53]
	v_cmp_lt_f32_e64 s[52:53], 0, v246
	s_nop 1
	v_cndmask_b32_e64 v242, v242, v244, s[52:53]
	v_mul_f32_e32 v243, 0x37800000, v242
	v_cndmask_b32_e32 v242, v242, v243, vcc
	v_cmp_class_f32_e32 vcc, v247, v90
	s_nop 1
	v_cndmask_b32_e32 v247, v242, v247, vcc
	v_div_scale_f32 v248, s[52:53], v247, v247, 1.0
	v_rcp_f32_e32 v249, v248
	v_div_scale_f32 v228, vcc, 1.0, v247, 1.0
	s_nop 0
	v_fma_f32 v229, -v248, v249, 1.0
	v_fmac_f32_e32 v249, v229, v249
	v_mul_f32_e32 v230, v228, v249
	v_fma_f32 v229, -v248, v230, v228
	v_fmac_f32_e32 v230, v229, v249
	v_fma_f32 v248, -v248, v230, v228
	v_div_fmas_f32 v248, v248, v249, v230
	v_div_fixup_f32 v236, v248, v247, 1.0
	v_fmamk_f32 v240, v227, 0x3a800000, v89
	v_mul_f32_e32 v241, 0x4f800000, v240
	v_cmp_gt_f32_e32 vcc, s54, v240
	s_nop 1
	v_cndmask_b32_e32 v247, v240, v241, vcc
	v_sqrt_f32_e32 v242, v247
	s_nop 1
	v_add_u32_e32 v243, -1, v242
	v_add_u32_e32 v244, 1, v242
	v_fma_f32 v245, -v243, v242, v247
	v_fma_f32 v246, -v244, v242, v247
	v_cmp_ge_f32_e64 s[52:53], 0, v245
	s_nop 1
	v_cndmask_b32_e64 v242, v242, v243, s[52:53]
	v_cmp_lt_f32_e64 s[52:53], 0, v246
	s_nop 1
	v_cndmask_b32_e64 v242, v242, v244, s[52:53]
	v_mul_f32_e32 v243, 0x37800000, v242
	v_cndmask_b32_e32 v242, v242, v243, vcc
	v_cmp_class_f32_e32 vcc, v247, v90
	s_nop 1
	v_cndmask_b32_e32 v247, v242, v247, vcc
	v_div_scale_f32 v248, s[52:53], v247, v247, 1.0
	v_rcp_f32_e32 v249, v248
	v_div_scale_f32 v228, vcc, 1.0, v247, 1.0
	s_nop 0
	v_fma_f32 v229, -v248, v249, 1.0
	v_fmac_f32_e32 v249, v229, v249
	v_mul_f32_e32 v230, v228, v249
	v_fma_f32 v229, -v248, v230, v228
	v_fmac_f32_e32 v230, v229, v249
	v_fma_f32 v248, -v248, v230, v228
	v_div_fmas_f32 v248, v248, v249, v230
	v_div_fixup_f32 v238, v248, v247, 1.0
	s_waitcnt vmcnt(8)
; __device__ __forceinline__ unsigned pk2(float lo, float hi) { return pg8::cvt_pk_bf16(lo, hi); }
; template <bool BF> __device__ __forceinline__ void prep_rows(const float* xp, const float* xs, const bf16* hb, const float* g, const float* MOD, int shoff, int scoff, bf16* U, int gw, int NGW, int lane) {
;     ...
;             const float* mr = MOD + (size_t)(m < MP ? (m >> 13) : 8 + ((m - MP) >> 12)) * 6144;
; #pragma unroll
;             for (int j = 0; j < 4; ++j) { const int c = 4 * lane + 256 * j;
;                 const f32x4 gg = *(const f32x4*)(g + c), sc = *(const f32x4*)(mr + scoff + c), sh = *(const f32x4*)(mr + shoff + c);
;                 const f32x4 o = v[r][j] * rstd * gg * (sc + 1.0f) + sh; v2u w; w.x = pk2(o.x, o.y); w.y = pk2(o.z, o.w); *(v2u*)(U + (size_t)m * DM + c) = w; } } }
	v_pk_add_f32 v[160:161], v[160:161], 1.0 op_sel_hi:[1,0]
	v_pk_add_f32 v[162:163], v[162:163], 1.0 op_sel_hi:[1,0]
	v_pk_add_f32 v[164:165], v[164:165], 1.0 op_sel_hi:[1,0]
	v_pk_add_f32 v[166:167], v[166:167], 1.0 op_sel_hi:[1,0]
	v_pk_add_f32 v[168:169], v[168:169], 1.0 op_sel_hi:[1,0]
	v_pk_add_f32 v[170:171], v[170:171], 1.0 op_sel_hi:[1,0]
	v_pk_add_f32 v[172:173], v[172:173], 1.0 op_sel_hi:[1,0]
	v_pk_add_f32 v[174:175], v[174:175], 1.0 op_sel_hi:[1,0]
	v_pk_add_f32 v[192:193], v[192:193], 1.0 op_sel_hi:[1,0]
	v_pk_add_f32 v[194:195], v[194:195], 1.0 op_sel_hi:[1,0]
	v_pk_add_f32 v[196:197], v[196:197], 1.0 op_sel_hi:[1,0]
	v_pk_add_f32 v[198:199], v[198:199], 1.0 op_sel_hi:[1,0]
	v_pk_add_f32 v[200:201], v[200:201], 1.0 op_sel_hi:[1,0]
	v_pk_add_f32 v[202:203], v[202:203], 1.0 op_sel_hi:[1,0]
	v_pk_add_f32 v[204:205], v[204:205], 1.0 op_sel_hi:[1,0]
	v_pk_add_f32 v[206:207], v[206:207], 1.0 op_sel_hi:[1,0]
	s_add_u32 s38, s20, 0x3000000
	s_addc_u32 s39, s21, 0
	s_add_u32 s40, s20, 0x3400000
	s_addc_u32 s41, s21, 0
	s_add_u32 s46, s20, 0x3800000
	s_addc_u32 s47, s21, 0
	s_add_u32 s48, s20, 0x3c00000
	s_addc_u32 s49, s21, 0
	v_pk_mul_f32 v[0:1], v[0:1], v[232:233] op_sel_hi:[1,0]
	v_pk_mul_f32 v[2:3], v[2:3], v[232:233] op_sel_hi:[1,0]
	v_pk_mul_f32 v[0:1], v[64:65], v[0:1]
	v_pk_mul_f32 v[2:3], v[66:67], v[2:3]
	v_pk_fma_f32 v[0:1], v[160:161], v[0:1], v[176:177]
	v_pk_fma_f32 v[2:3], v[162:163], v[2:3], v[178:179]
	v_cvt_pk_bf16_f32 v244, v0, v1
	v_cvt_pk_bf16_f32 v245, v2, v3
	v_pk_mul_f32 v[4:5], v[4:5], v[232:233] op_sel_hi:[1,0]
	v_pk_mul_f32 v[6:7], v[6:7], v[232:233] op_sel_hi:[1,0]
	v_pk_mul_f32 v[4:5], v[68:69], v[4:5]
	v_pk_mul_f32 v[6:7], v[70:71], v[6:7]
	v_pk_fma_f32 v[4:5], v[164:165], v[4:5], v[180:181]
	v_pk_fma_f32 v[6:7], v[166:167], v[6:7], v[182:183]
	v_cvt_pk_bf16_f32 v246, v4, v5
	v_cvt_pk_bf16_f32 v247, v6, v7
	global_store_dwordx4 v82, v[244:247], s[38:39] offset:0
	v_pk_mul_f32 v[8:9], v[8:9], v[232:233] op_sel_hi:[1,0]
	v_pk_mul_f32 v[10:11], v[10:11], v[232:233] op_sel_hi:[1,0]
	v_pk_mul_f32 v[8:9], v[72:73], v[8:9]
	v_pk_mul_f32 v[10:11], v[74:75], v[10:11]
	v_pk_fma_f32 v[8:9], v[168:169], v[8:9], v[184:185]
	v_pk_fma_f32 v[10:11], v[170:171], v[10:11], v[186:187]
	v_cvt_pk_bf16_f32 v240, v8, v9
	v_cvt_pk_bf16_f32 v241, v10, v11
	v_pk_mul_f32 v[12:13], v[12:13], v[232:233] op_sel_hi:[1,0]
	v_pk_mul_f32 v[14:15], v[14:15], v[232:233] op_sel_hi:[1,0]
	v_pk_mul_f32 v[12:13], v[76:77], v[12:13]
	v_pk_mul_f32 v[14:15], v[78:79], v[14:15]
	v_pk_fma_f32 v[12:13], v[172:173], v[12:13], v[188:189]
	v_pk_fma_f32 v[14:15], v[174:175], v[14:15], v[190:191]
	v_cvt_pk_bf16_f32 v242, v12, v13
	v_cvt_pk_bf16_f32 v243, v14, v15
	global_store_dwordx4 v82, v[240:243], s[38:39] offset:1024
	v_pk_mul_f32 v[16:17], v[16:17], v[234:235] op_sel_hi:[1,0]
	v_pk_mul_f32 v[18:19], v[18:19], v[234:235] op_sel_hi:[1,0]
	v_pk_mul_f32 v[16:17], v[64:65], v[16:17]
	v_pk_mul_f32 v[18:19], v[66:67], v[18:19]
	v_pk_fma_f32 v[16:17], v[160:161], v[16:17], v[176:177]
	v_pk_fma_f32 v[18:19], v[162:163], v[18:19], v[178:179]
	v_cvt_pk_bf16_f32 v244, v16, v17
	v_cvt_pk_bf16_f32 v245, v18, v19
	v_pk_mul_f32 v[20:21], v[20:21], v[234:235] op_sel_hi:[1,0]
	v_pk_mul_f32 v[22:23], v[22:23], v[234:235] op_sel_hi:[1,0]
	v_pk_mul_f32 v[20:21], v[68:69], v[20:21]
	v_pk_mul_f32 v[22:23], v[70:71], v[22:23]
	v_pk_fma_f32 v[20:21], v[164:165], v[20:21], v[180:181]
	v_pk_fma_f32 v[22:23], v[166:167], v[22:23], v[182:183]
	v_cvt_pk_bf16_f32 v246, v20, v21
	v_cvt_pk_bf16_f32 v247, v22, v23
	global_store_dwordx4 v82, v[244:247], s[40:41] offset:0
	v_pk_mul_f32 v[24:25], v[24:25], v[234:235] op_sel_hi:[1,0]
	v_pk_mul_f32 v[26:27], v[26:27], v[234:235] op_sel_hi:[1,0]
	v_pk_mul_f32 v[24:25], v[72:73], v[24:25]
	v_pk_mul_f32 v[26:27], v[74:75], v[26:27]
	v_pk_fma_f32 v[24:25], v[168:169], v[24:25], v[184:185]
	v_pk_fma_f32 v[26:27], v[170:171], v[26:27], v[186:187]
	v_cvt_pk_bf16_f32 v240, v24, v25
	v_cvt_pk_bf16_f32 v241, v26, v27
	v_pk_mul_f32 v[28:29], v[28:29], v[234:235] op_sel_hi:[1,0]
	v_pk_mul_f32 v[30:31], v[30:31], v[234:235] op_sel_hi:[1,0]
	v_pk_mul_f32 v[28:29], v[76:77], v[28:29]
	v_pk_mul_f32 v[30:31], v[78:79], v[30:31]
	v_pk_fma_f32 v[28:29], v[172:173], v[28:29], v[188:189]
	v_pk_fma_f32 v[30:31], v[174:175], v[30:31], v[190:191]
	v_cvt_pk_bf16_f32 v242, v28, v29
	v_cvt_pk_bf16_f32 v243, v30, v31
	global_store_dwordx4 v82, v[240:243], s[40:41] offset:1024
	v_pk_mul_f32 v[32:33], v[32:33], v[236:237] op_sel_hi:[1,0]
	v_pk_mul_f32 v[34:35], v[34:35], v[236:237] op_sel_hi:[1,0]
	v_pk_mul_f32 v[32:33], v[64:65], v[32:33]
	v_pk_mul_f32 v[34:35], v[66:67], v[34:35]
	v_pk_fma_f32 v[32:33], v[192:193], v[32:33], v[208:209]
	v_pk_fma_f32 v[34:35], v[194:195], v[34:35], v[210:211]
	v_cvt_pk_bf16_f32 v244, v32, v33
	v_cvt_pk_bf16_f32 v245, v34, v35
	v_pk_mul_f32 v[36:37], v[36:37], v[236:237] op_sel_hi:[1,0]
	v_pk_mul_f32 v[38:39], v[38:39], v[236:237] op_sel_hi:[1,0]
	v_pk_mul_f32 v[36:37], v[68:69], v[36:37]
	v_pk_mul_f32 v[38:39], v[70:71], v[38:39]
	v_pk_fma_f32 v[36:37], v[196:197], v[36:37], v[212:213]
	v_pk_fma_f32 v[38:39], v[198:199], v[38:39], v[214:215]
	v_cvt_pk_bf16_f32 v246, v36, v37
	v_cvt_pk_bf16_f32 v247, v38, v39
	global_store_dwordx4 v82, v[244:247], s[46:47] offset:0
	v_pk_mul_f32 v[40:41], v[40:41], v[236:237] op_sel_hi:[1,0]
	v_pk_mul_f32 v[42:43], v[42:43], v[236:237] op_sel_hi:[1,0]
	v_pk_mul_f32 v[40:41], v[72:73], v[40:41]
	v_pk_mul_f32 v[42:43], v[74:75], v[42:43]
	v_pk_fma_f32 v[40:41], v[200:201], v[40:41], v[216:217]
	v_pk_fma_f32 v[42:43], v[202:203], v[42:43], v[218:219]
	v_cvt_pk_bf16_f32 v240, v40, v41
; __device__ __forceinline__ float bf_lo(unsigned w) { return __uint_as_float(w << 16); }
; __device__ __forceinline__ float bf_hi(unsigned w) { return __uint_as_float(w & 0xffff0000u); }
; __device__ __forceinline__ unsigned pk2(float lo, float hi) { return pg8::cvt_pk_bf16(lo, hi); }
; template <bool BF> __device__ __forceinline__ void prep_rows(const float* xp, const float* xs, const bf16* hb, const float* g, const float* MOD, int shoff, int scoff, bf16* U, int gw, int NGW, int lane) {
;     ...
;         for (int r = 0; r < R; ++r) { const int m = mb + r * NGW; const int mc = m < MT ? m : mb;
; #pragma unroll
;             for (int j = 0; j < 4; ++j) {
;                 if (BF) { const v2u a0 = *(const v2u*)(hb + (size_t)mc * DM + 4 * lane + 256 * j);
;                     v[r][j].x = pg8::bf_lo(a0.x); v[r][j].y = pg8::bf_hi(a0.x); v[r][j].z = pg8::bf_lo(a0.y); v[r][j].w = pg8::bf_hi(a0.y); }
;     ...
;             for (int j = 0; j < 4; ++j) { const int c = 4 * lane + 256 * j;
;                 const f32x4 gg = *(const f32x4*)(g + c), sc = *(const f32x4*)(mr + scoff + c), sh = *(const f32x4*)(mr + shoff + c);
;                 const f32x4 o = v[r][j] * rstd * gg * (sc + 1.0f) + sh; v2u w; w.x = pk2(o.x, o.y); w.y = pk2(o.z, o.w); *(v2u*)(U + (size_t)m * DM + c) = w; } } }
	v_cvt_pk_bf16_f32 v241, v42, v43
	v_pk_mul_f32 v[44:45], v[44:45], v[236:237] op_sel_hi:[1,0]
	v_pk_mul_f32 v[46:47], v[46:47], v[236:237] op_sel_hi:[1,0]
	v_pk_mul_f32 v[44:45], v[76:77], v[44:45]
	v_pk_mul_f32 v[46:47], v[78:79], v[46:47]
	v_pk_fma_f32 v[44:45], v[204:205], v[44:45], v[220:221]
	v_pk_fma_f32 v[46:47], v[206:207], v[46:47], v[222:223]
	v_cvt_pk_bf16_f32 v242, v44, v45
	v_cvt_pk_bf16_f32 v243, v46, v47
	global_store_dwordx4 v82, v[240:243], s[46:47] offset:1024
	v_pk_mul_f32 v[48:49], v[48:49], v[238:239] op_sel_hi:[1,0]
	v_pk_mul_f32 v[50:51], v[50:51], v[238:239] op_sel_hi:[1,0]
	v_pk_mul_f32 v[48:49], v[64:65], v[48:49]
	v_pk_mul_f32 v[50:51], v[66:67], v[50:51]
	v_pk_fma_f32 v[48:49], v[192:193], v[48:49], v[208:209]
	v_pk_fma_f32 v[50:51], v[194:195], v[50:51], v[210:211]
	v_cvt_pk_bf16_f32 v244, v48, v49
	v_cvt_pk_bf16_f32 v245, v50, v51
	v_pk_mul_f32 v[52:53], v[52:53], v[238:239] op_sel_hi:[1,0]
	v_pk_mul_f32 v[54:55], v[54:55], v[238:239] op_sel_hi:[1,0]
	v_pk_mul_f32 v[52:53], v[68:69], v[52:53]
	v_pk_mul_f32 v[54:55], v[70:71], v[54:55]
	v_pk_fma_f32 v[52:53], v[196:197], v[52:53], v[212:213]
	v_pk_fma_f32 v[54:55], v[198:199], v[54:55], v[214:215]
	v_cvt_pk_bf16_f32 v246, v52, v53
	v_cvt_pk_bf16_f32 v247, v54, v55
	global_store_dwordx4 v82, v[244:247], s[48:49] offset:0
	v_pk_mul_f32 v[56:57], v[56:57], v[238:239] op_sel_hi:[1,0]
	v_pk_mul_f32 v[58:59], v[58:59], v[238:239] op_sel_hi:[1,0]
	v_pk_mul_f32 v[56:57], v[72:73], v[56:57]
	v_pk_mul_f32 v[58:59], v[74:75], v[58:59]
	v_pk_fma_f32 v[56:57], v[200:201], v[56:57], v[216:217]
	v_pk_fma_f32 v[58:59], v[202:203], v[58:59], v[218:219]
	v_cvt_pk_bf16_f32 v240, v56, v57
	v_cvt_pk_bf16_f32 v241, v58, v59
	v_pk_mul_f32 v[60:61], v[60:61], v[238:239] op_sel_hi:[1,0]
	v_pk_mul_f32 v[62:63], v[62:63], v[238:239] op_sel_hi:[1,0]
	v_pk_mul_f32 v[60:61], v[76:77], v[60:61]
	v_pk_mul_f32 v[62:63], v[78:79], v[62:63]
	v_pk_fma_f32 v[60:61], v[204:205], v[60:61], v[220:221]
	v_pk_fma_f32 v[62:63], v[206:207], v[62:63], v[222:223]
	v_cvt_pk_bf16_f32 v242, v60, v61
	v_cvt_pk_bf16_f32 v243, v62, v63
	global_store_dwordx4 v82, v[240:243], s[48:49] offset:1024
	s_add_u32 s34, s8, 0x1b000
	s_addc_u32 s35, s9, 0
	s_add_u32 s36, s8, 0x1b000
	s_addc_u32 s37, s9, 0
	global_load_dwordx4 v[176:179], v80, s[34:35] offset:0
	global_load_dwordx4 v[180:183], v80, s[34:35] offset:16
	global_load_dwordx4 v[184:187], v80, s[34:35] offset:2048
	global_load_dwordx4 v[188:191], v80, s[34:35] offset:2064
	global_load_dwordx4 v[160:163], v81, s[34:35] offset:0
	global_load_dwordx4 v[164:167], v81, s[34:35] offset:16
	global_load_dwordx4 v[168:171], v81, s[34:35] offset:2048
	global_load_dwordx4 v[172:175], v81, s[34:35] offset:2064
	global_load_dwordx4 v[208:211], v80, s[36:37] offset:0
	global_load_dwordx4 v[212:215], v80, s[36:37] offset:16
	global_load_dwordx4 v[216:219], v80, s[36:37] offset:2048
	global_load_dwordx4 v[220:223], v80, s[36:37] offset:2064
	global_load_dwordx4 v[192:195], v81, s[36:37] offset:0
	global_load_dwordx4 v[196:199], v81, s[36:37] offset:16
	global_load_dwordx4 v[200:203], v81, s[36:37] offset:2048
	global_load_dwordx4 v[204:207], v81, s[36:37] offset:2064
	s_add_u32 s24, s16, 0x5000000
	s_addc_u32 s25, s17, 0
	s_add_u32 s26, s16, 0x5400000
	s_addc_u32 s27, s17, 0
	s_add_u32 s28, s16, 0x5800000
	s_addc_u32 s29, s17, 0
	s_add_u32 s30, s16, 0x5c00000
	s_addc_u32 s31, s17, 0
	global_load_dwordx4 v[128:131], v82, s[24:25] offset:0 nt
	global_load_dwordx4 v[132:135], v82, s[24:25] offset:1024 nt
	global_load_dwordx4 v[136:139], v82, s[26:27] offset:0 nt
	global_load_dwordx4 v[140:143], v82, s[26:27] offset:1024 nt
	global_load_dwordx4 v[144:147], v82, s[28:29] offset:0 nt
	global_load_dwordx4 v[148:151], v82, s[28:29] offset:1024 nt
	global_load_dwordx4 v[152:155], v82, s[30:31] offset:0 nt
	global_load_dwordx4 v[156:159], v82, s[30:31] offset:1024 nt
	s_waitcnt vmcnt(32)
	v_lshlrev_b32_e32 v0, 16, v96
	v_and_b32_e32 v1, 0xffff0000, v96
	v_lshlrev_b32_e32 v2, 16, v97
	v_and_b32_e32 v3, 0xffff0000, v97
	v_lshlrev_b32_e32 v4, 16, v98
	v_and_b32_e32 v5, 0xffff0000, v98
	v_lshlrev_b32_e32 v6, 16, v99
	v_and_b32_e32 v7, 0xffff0000, v99
	v_lshlrev_b32_e32 v8, 16, v100
	v_and_b32_e32 v9, 0xffff0000, v100
	v_lshlrev_b32_e32 v10, 16, v101
	v_and_b32_e32 v11, 0xffff0000, v101
	v_lshlrev_b32_e32 v12, 16, v102
	v_and_b32_e32 v13, 0xffff0000, v102
	v_lshlrev_b32_e32 v14, 16, v103
	v_and_b32_e32 v15, 0xffff0000, v103
	v_lshlrev_b32_e32 v16, 16, v104
	v_and_b32_e32 v17, 0xffff0000, v104
	v_lshlrev_b32_e32 v18, 16, v105
	v_and_b32_e32 v19, 0xffff0000, v105
	v_lshlrev_b32_e32 v20, 16, v106
	v_and_b32_e32 v21, 0xffff0000, v106
	v_lshlrev_b32_e32 v22, 16, v107
	v_and_b32_e32 v23, 0xffff0000, v107
	v_lshlrev_b32_e32 v24, 16, v108
	v_and_b32_e32 v25, 0xffff0000, v108
	v_lshlrev_b32_e32 v26, 16, v109
	v_and_b32_e32 v27, 0xffff0000, v109
	v_lshlrev_b32_e32 v28, 16, v110
	v_and_b32_e32 v29, 0xffff0000, v110
	v_lshlrev_b32_e32 v30, 16, v111
	v_and_b32_e32 v31, 0xffff0000, v111
	v_lshlrev_b32_e32 v32, 16, v112
	v_and_b32_e32 v33, 0xffff0000, v112
	v_lshlrev_b32_e32 v34, 16, v113
	v_and_b32_e32 v35, 0xffff0000, v113
	v_lshlrev_b32_e32 v36, 16, v114
	v_and_b32_e32 v37, 0xffff0000, v114
	v_lshlrev_b32_e32 v38, 16, v115
	v_and_b32_e32 v39, 0xffff0000, v115
	v_lshlrev_b32_e32 v40, 16, v116
	v_and_b32_e32 v41, 0xffff0000, v116
	v_lshlrev_b32_e32 v42, 16, v117
	v_and_b32_e32 v43, 0xffff0000, v117
	v_lshlrev_b32_e32 v44, 16, v118
	v_and_b32_e32 v45, 0xffff0000, v118
	v_lshlrev_b32_e32 v46, 16, v119
	v_and_b32_e32 v47, 0xffff0000, v119
	v_lshlrev_b32_e32 v48, 16, v120
	v_and_b32_e32 v49, 0xffff0000, v120
; __device__ __forceinline__ float bf_lo(unsigned w) { return __uint_as_float(w << 16); }
; __device__ __forceinline__ float bf_hi(unsigned w) { return __uint_as_float(w & 0xffff0000u); }
; template <bool BF> __device__ __forceinline__ void prep_rows(const float* xp, const float* xs, const bf16* hb, const float* g, const float* MOD, int shoff, int scoff, bf16* U, int gw, int NGW, int lane) {
;     ...
;                 if (BF) { const v2u a0 = *(const v2u*)(hb + (size_t)mc * DM + 4 * lane + 256 * j);
;                     v[r][j].x = pg8::bf_lo(a0.x); v[r][j].y = pg8::bf_hi(a0.x); v[r][j].z = pg8::bf_lo(a0.y); v[r][j].w = pg8::bf_hi(a0.y); }
;                 else { const float* xr = mc < MP ? xp + (size_t)mc * DM : xs + (size_t)(mc - MP) * DM; v[r][j] = *(const f32x4*)(xr + 4 * lane + 256 * j); } } }
; #pragma unroll
;         for (int r = 0; r < R; ++r) { float t = 0.f;
; #pragma unroll
;             for (int j = 0; j < 4; ++j) t += (v[r][j].x * v[r][j].x + v[r][j].y * v[r][j].y) + (v[r][j].z * v[r][j].z + v[r][j].w * v[r][j].w);
;             s[r] = t; }
; #pragma unroll
;         for (int o = 1; o < 64; o <<= 1) {
; #pragma unroll
;             for (int r = 0; r < R; ++r) s[r] += __shfl_xor(s[r], o); }
; #pragma unroll
;         for (int r = 0; r < R; ++r) { const int m = mb + r * NGW; if (m < MT) {
;             const float rstd = 1.0f / sqrtf(s[r] * (1.0f / DM) + RMS_EPS);
	v_lshlrev_b32_e32 v50, 16, v121
	v_and_b32_e32 v51, 0xffff0000, v121
	v_lshlrev_b32_e32 v52, 16, v122
	v_and_b32_e32 v53, 0xffff0000, v122
	v_lshlrev_b32_e32 v54, 16, v123
	v_and_b32_e32 v55, 0xffff0000, v123
	v_lshlrev_b32_e32 v56, 16, v124
	v_and_b32_e32 v57, 0xffff0000, v124
	v_lshlrev_b32_e32 v58, 16, v125
	v_and_b32_e32 v59, 0xffff0000, v125
	v_lshlrev_b32_e32 v60, 16, v126
	v_and_b32_e32 v61, 0xffff0000, v126
	v_lshlrev_b32_e32 v62, 16, v127
	v_and_b32_e32 v63, 0xffff0000, v127
	v_pk_mul_f32 v[240:241], v[0:1], v[0:1]
	v_pk_mul_f32 v[242:243], v[16:17], v[16:17]
	v_pk_mul_f32 v[244:245], v[32:33], v[32:33]
	v_pk_mul_f32 v[246:247], v[48:49], v[48:49]
	v_pk_fma_f32 v[240:241], v[2:3], v[2:3], v[240:241]
	v_pk_fma_f32 v[242:243], v[18:19], v[18:19], v[242:243]
	v_pk_fma_f32 v[244:245], v[34:35], v[34:35], v[244:245]
	v_pk_fma_f32 v[246:247], v[50:51], v[50:51], v[246:247]
	v_pk_fma_f32 v[240:241], v[4:5], v[4:5], v[240:241]
	v_pk_fma_f32 v[242:243], v[20:21], v[20:21], v[242:243]
	v_pk_fma_f32 v[244:245], v[36:37], v[36:37], v[244:245]
	v_pk_fma_f32 v[246:247], v[52:53], v[52:53], v[246:247]
	v_pk_fma_f32 v[240:241], v[6:7], v[6:7], v[240:241]
	v_pk_fma_f32 v[242:243], v[22:23], v[22:23], v[242:243]
	v_pk_fma_f32 v[244:245], v[38:39], v[38:39], v[244:245]
	v_pk_fma_f32 v[246:247], v[54:55], v[54:55], v[246:247]
	v_pk_fma_f32 v[240:241], v[8:9], v[8:9], v[240:241]
	v_pk_fma_f32 v[242:243], v[24:25], v[24:25], v[242:243]
	v_pk_fma_f32 v[244:245], v[40:41], v[40:41], v[244:245]
	v_pk_fma_f32 v[246:247], v[56:57], v[56:57], v[246:247]
	v_pk_fma_f32 v[240:241], v[10:11], v[10:11], v[240:241]
	v_pk_fma_f32 v[242:243], v[26:27], v[26:27], v[242:243]
	v_pk_fma_f32 v[244:245], v[42:43], v[42:43], v[244:245]
	v_pk_fma_f32 v[246:247], v[58:59], v[58:59], v[246:247]
	v_pk_fma_f32 v[240:241], v[12:13], v[12:13], v[240:241]
	v_pk_fma_f32 v[242:243], v[28:29], v[28:29], v[242:243]
	v_pk_fma_f32 v[244:245], v[44:45], v[44:45], v[244:245]
	v_pk_fma_f32 v[246:247], v[60:61], v[60:61], v[246:247]
	v_pk_fma_f32 v[240:241], v[14:15], v[14:15], v[240:241]
	v_pk_fma_f32 v[242:243], v[30:31], v[30:31], v[242:243]
	v_pk_fma_f32 v[244:245], v[46:47], v[46:47], v[244:245]
	v_pk_fma_f32 v[246:247], v[62:63], v[62:63], v[246:247]
	v_add_f32_e32 v224, v240, v241
	v_add_f32_e32 v225, v242, v243
	v_add_f32_e32 v226, v244, v245
	v_add_f32_e32 v227, v246, v247
	ds_bpermute_b32 v228, v83, v224
	ds_bpermute_b32 v229, v83, v225
	ds_bpermute_b32 v230, v83, v226
	ds_bpermute_b32 v231, v83, v227
	s_waitcnt lgkmcnt(0)
	v_add_f32_e32 v224, v224, v228
	v_add_f32_e32 v225, v225, v229
	v_add_f32_e32 v226, v226, v230
	v_add_f32_e32 v227, v227, v231
	ds_bpermute_b32 v228, v84, v224
	ds_bpermute_b32 v229, v84, v225
	ds_bpermute_b32 v230, v84, v226
	ds_bpermute_b32 v231, v84, v227
	s_waitcnt lgkmcnt(0)
	v_add_f32_e32 v224, v224, v228
	v_add_f32_e32 v225, v225, v229
	v_add_f32_e32 v226, v226, v230
	v_add_f32_e32 v227, v227, v231
	ds_bpermute_b32 v228, v85, v224
	ds_bpermute_b32 v229, v85, v225
	ds_bpermute_b32 v230, v85, v226
	ds_bpermute_b32 v231, v85, v227
	s_waitcnt lgkmcnt(0)
	v_add_f32_e32 v224, v224, v228
	v_add_f32_e32 v225, v225, v229
	v_add_f32_e32 v226, v226, v230
	v_add_f32_e32 v227, v227, v231
	ds_bpermute_b32 v228, v86, v224
	ds_bpermute_b32 v229, v86, v225
	ds_bpermute_b32 v230, v86, v226
	ds_bpermute_b32 v231, v86, v227
	s_waitcnt lgkmcnt(0)
	v_add_f32_e32 v224, v224, v228
	v_add_f32_e32 v225, v225, v229
	v_add_f32_e32 v226, v226, v230
	v_add_f32_e32 v227, v227, v231
	ds_bpermute_b32 v228, v87, v224
	ds_bpermute_b32 v229, v87, v225
	ds_bpermute_b32 v230, v87, v226
	ds_bpermute_b32 v231, v87, v227
	s_waitcnt lgkmcnt(0)
	v_add_f32_e32 v224, v224, v228
	v_add_f32_e32 v225, v225, v229
	v_add_f32_e32 v226, v226, v230
	v_add_f32_e32 v227, v227, v231
	ds_bpermute_b32 v228, v88, v224
	ds_bpermute_b32 v229, v88, v225
	ds_bpermute_b32 v230, v88, v226
	ds_bpermute_b32 v231, v88, v227
	s_waitcnt lgkmcnt(0)
	v_add_f32_e32 v224, v224, v228
	v_add_f32_e32 v225, v225, v229
	v_add_f32_e32 v226, v226, v230
	v_add_f32_e32 v227, v227, v231
	v_fmamk_f32 v240, v224, 0x3a800000, v89
	v_mul_f32_e32 v241, 0x4f800000, v240
	v_cmp_gt_f32_e32 vcc, s54, v240
	s_nop 1
	v_cndmask_b32_e32 v247, v240, v241, vcc
	v_sqrt_f32_e32 v242, v247
	s_nop 1
	v_add_u32_e32 v243, -1, v242
	v_add_u32_e32 v244, 1, v242
	v_fma_f32 v245, -v243, v242, v247
	v_fma_f32 v246, -v244, v242, v247
	v_cmp_ge_f32_e64 s[52:53], 0, v245
	s_nop 1
	v_cndmask_b32_e64 v242, v242, v243, s[52:53]
	v_cmp_lt_f32_e64 s[52:53], 0, v246
	s_nop 1
	v_cndmask_b32_e64 v242, v242, v244, s[52:53]
	v_mul_f32_e32 v243, 0x37800000, v242
	v_cndmask_b32_e32 v242, v242, v243, vcc
	v_cmp_class_f32_e32 vcc, v247, v90
	s_nop 1
	v_cndmask_b32_e32 v247, v242, v247, vcc
	v_div_scale_f32 v248, s[52:53], v247, v247, 1.0
	v_rcp_f32_e32 v249, v248
	v_div_scale_f32 v228, vcc, 1.0, v247, 1.0
	s_nop 0
	v_fma_f32 v229, -v248, v249, 1.0
	v_fmac_f32_e32 v249, v229, v249
	v_mul_f32_e32 v230, v228, v249
	v_fma_f32 v229, -v248, v230, v228
	v_fmac_f32_e32 v230, v229, v249
	v_fma_f32 v248, -v248, v230, v228
	v_div_fmas_f32 v248, v248, v249, v230
	v_div_fixup_f32 v232, v248, v247, 1.0
	v_fmamk_f32 v240, v225, 0x3a800000, v89
	v_mul_f32_e32 v241, 0x4f800000, v240
	v_cmp_gt_f32_e32 vcc, s54, v240
	s_nop 1
	v_cndmask_b32_e32 v247, v240, v241, vcc
	v_sqrt_f32_e32 v242, v247
	s_nop 1
	v_add_u32_e32 v243, -1, v242
	v_add_u32_e32 v244, 1, v242
	v_fma_f32 v245, -v243, v242, v247
	v_fma_f32 v246, -v244, v242, v247
	v_cmp_ge_f32_e64 s[52:53], 0, v245
	s_nop 1
	v_cndmask_b32_e64 v242, v242, v243, s[52:53]
	v_cmp_lt_f32_e64 s[52:53], 0, v246
	s_nop 1
	v_cndmask_b32_e64 v242, v242, v244, s[52:53]
; __device__ __forceinline__ unsigned pk2(float lo, float hi) { return pg8::cvt_pk_bf16(lo, hi); }
; template <bool BF> __device__ __forceinline__ void prep_rows(const float* xp, const float* xs, const bf16* hb, const float* g, const float* MOD, int shoff, int scoff, bf16* U, int gw, int NGW, int lane) {
;     ...
;             const float rstd = 1.0f / sqrtf(s[r] * (1.0f / DM) + RMS_EPS);
;             const float* mr = MOD + (size_t)(m < MP ? (m >> 13) : 8 + ((m - MP) >> 12)) * 6144;
; #pragma unroll
;             for (int j = 0; j < 4; ++j) { const int c = 4 * lane + 256 * j;
;                 const f32x4 gg = *(const f32x4*)(g + c), sc = *(const f32x4*)(mr + scoff + c), sh = *(const f32x4*)(mr + shoff + c);
;                 const f32x4 o = v[r][j] * rstd * gg * (sc + 1.0f) + sh; v2u w; w.x = pk2(o.x, o.y); w.y = pk2(o.z, o.w); *(v2u*)(U + (size_t)m * DM + c) = w; } } }
	v_mul_f32_e32 v243, 0x37800000, v242
	v_cndmask_b32_e32 v242, v242, v243, vcc
	v_cmp_class_f32_e32 vcc, v247, v90
	s_nop 1
	v_cndmask_b32_e32 v247, v242, v247, vcc
	v_div_scale_f32 v248, s[52:53], v247, v247, 1.0
	v_rcp_f32_e32 v249, v248
	v_div_scale_f32 v228, vcc, 1.0, v247, 1.0
	s_nop 0
	v_fma_f32 v229, -v248, v249, 1.0
	v_fmac_f32_e32 v249, v229, v249
	v_mul_f32_e32 v230, v228, v249
	v_fma_f32 v229, -v248, v230, v228
	v_fmac_f32_e32 v230, v229, v249
	v_fma_f32 v248, -v248, v230, v228
	v_div_fmas_f32 v248, v248, v249, v230
	v_div_fixup_f32 v234, v248, v247, 1.0
	v_fmamk_f32 v240, v226, 0x3a800000, v89
	v_mul_f32_e32 v241, 0x4f800000, v240
	v_cmp_gt_f32_e32 vcc, s54, v240
	s_nop 1
	v_cndmask_b32_e32 v247, v240, v241, vcc
	v_sqrt_f32_e32 v242, v247
	s_nop 1
	v_add_u32_e32 v243, -1, v242
	v_add_u32_e32 v244, 1, v242
	v_fma_f32 v245, -v243, v242, v247
	v_fma_f32 v246, -v244, v242, v247
	v_cmp_ge_f32_e64 s[52:53], 0, v245
	s_nop 1
	v_cndmask_b32_e64 v242, v242, v243, s[52:53]
	v_cmp_lt_f32_e64 s[52:53], 0, v246
	s_nop 1
	v_cndmask_b32_e64 v242, v242, v244, s[52:53]
	v_mul_f32_e32 v243, 0x37800000, v242
	v_cndmask_b32_e32 v242, v242, v243, vcc
	v_cmp_class_f32_e32 vcc, v247, v90
	s_nop 1
	v_cndmask_b32_e32 v247, v242, v247, vcc
	v_div_scale_f32 v248, s[52:53], v247, v247, 1.0
	v_rcp_f32_e32 v249, v248
	v_div_scale_f32 v228, vcc, 1.0, v247, 1.0
	s_nop 0
	v_fma_f32 v229, -v248, v249, 1.0
	v_fmac_f32_e32 v249, v229, v249
	v_mul_f32_e32 v230, v228, v249
	v_fma_f32 v229, -v248, v230, v228
	v_fmac_f32_e32 v230, v229, v249
	v_fma_f32 v248, -v248, v230, v228
	v_div_fmas_f32 v248, v248, v249, v230
	v_div_fixup_f32 v236, v248, v247, 1.0
	v_fmamk_f32 v240, v227, 0x3a800000, v89
	v_mul_f32_e32 v241, 0x4f800000, v240
	v_cmp_gt_f32_e32 vcc, s54, v240
	s_nop 1
	v_cndmask_b32_e32 v247, v240, v241, vcc
	v_sqrt_f32_e32 v242, v247
	s_nop 1
	v_add_u32_e32 v243, -1, v242
	v_add_u32_e32 v244, 1, v242
	v_fma_f32 v245, -v243, v242, v247
	v_fma_f32 v246, -v244, v242, v247
	v_cmp_ge_f32_e64 s[52:53], 0, v245
	s_nop 1
	v_cndmask_b32_e64 v242, v242, v243, s[52:53]
	v_cmp_lt_f32_e64 s[52:53], 0, v246
	s_nop 1
	v_cndmask_b32_e64 v242, v242, v244, s[52:53]
	v_mul_f32_e32 v243, 0x37800000, v242
	v_cndmask_b32_e32 v242, v242, v243, vcc
	v_cmp_class_f32_e32 vcc, v247, v90
	s_nop 1
	v_cndmask_b32_e32 v247, v242, v247, vcc
	v_div_scale_f32 v248, s[52:53], v247, v247, 1.0
	v_rcp_f32_e32 v249, v248
	v_div_scale_f32 v228, vcc, 1.0, v247, 1.0
	s_nop 0
	v_fma_f32 v229, -v248, v249, 1.0
	v_fmac_f32_e32 v249, v229, v249
	v_mul_f32_e32 v230, v228, v249
	v_fma_f32 v229, -v248, v230, v228
	v_fmac_f32_e32 v230, v229, v249
	v_fma_f32 v248, -v248, v230, v228
	v_div_fmas_f32 v248, v248, v249, v230
	v_div_fixup_f32 v238, v248, v247, 1.0
	s_waitcnt vmcnt(8)
	v_pk_add_f32 v[160:161], v[160:161], 1.0 op_sel_hi:[1,0]
	v_pk_add_f32 v[162:163], v[162:163], 1.0 op_sel_hi:[1,0]
	v_pk_add_f32 v[164:165], v[164:165], 1.0 op_sel_hi:[1,0]
	v_pk_add_f32 v[166:167], v[166:167], 1.0 op_sel_hi:[1,0]
	v_pk_add_f32 v[168:169], v[168:169], 1.0 op_sel_hi:[1,0]
	v_pk_add_f32 v[170:171], v[170:171], 1.0 op_sel_hi:[1,0]
	v_pk_add_f32 v[172:173], v[172:173], 1.0 op_sel_hi:[1,0]
	v_pk_add_f32 v[174:175], v[174:175], 1.0 op_sel_hi:[1,0]
	v_pk_add_f32 v[192:193], v[192:193], 1.0 op_sel_hi:[1,0]
	v_pk_add_f32 v[194:195], v[194:195], 1.0 op_sel_hi:[1,0]
	v_pk_add_f32 v[196:197], v[196:197], 1.0 op_sel_hi:[1,0]
	v_pk_add_f32 v[198:199], v[198:199], 1.0 op_sel_hi:[1,0]
	v_pk_add_f32 v[200:201], v[200:201], 1.0 op_sel_hi:[1,0]
	v_pk_add_f32 v[202:203], v[202:203], 1.0 op_sel_hi:[1,0]
	v_pk_add_f32 v[204:205], v[204:205], 1.0 op_sel_hi:[1,0]
	v_pk_add_f32 v[206:207], v[206:207], 1.0 op_sel_hi:[1,0]
	s_add_u32 s38, s20, 0x4000000
	s_addc_u32 s39, s21, 0
	s_add_u32 s40, s20, 0x4400000
	s_addc_u32 s41, s21, 0
	s_add_u32 s46, s20, 0x4800000
	s_addc_u32 s47, s21, 0
	s_add_u32 s48, s20, 0x4c00000
	s_addc_u32 s49, s21, 0
	v_pk_mul_f32 v[0:1], v[0:1], v[232:233] op_sel_hi:[1,0]
	v_pk_mul_f32 v[2:3], v[2:3], v[232:233] op_sel_hi:[1,0]
	v_pk_mul_f32 v[0:1], v[64:65], v[0:1]
	v_pk_mul_f32 v[2:3], v[66:67], v[2:3]
	v_pk_fma_f32 v[0:1], v[160:161], v[0:1], v[176:177]
	v_pk_fma_f32 v[2:3], v[162:163], v[2:3], v[178:179]
	v_cvt_pk_bf16_f32 v244, v0, v1
	v_cvt_pk_bf16_f32 v245, v2, v3
	v_pk_mul_f32 v[4:5], v[4:5], v[232:233] op_sel_hi:[1,0]
	v_pk_mul_f32 v[6:7], v[6:7], v[232:233] op_sel_hi:[1,0]
	v_pk_mul_f32 v[4:5], v[68:69], v[4:5]
	v_pk_mul_f32 v[6:7], v[70:71], v[6:7]
	v_pk_fma_f32 v[4:5], v[164:165], v[4:5], v[180:181]
	v_pk_fma_f32 v[6:7], v[166:167], v[6:7], v[182:183]
	v_cvt_pk_bf16_f32 v246, v4, v5
	v_cvt_pk_bf16_f32 v247, v6, v7
	global_store_dwordx4 v82, v[244:247], s[38:39] offset:0
	v_pk_mul_f32 v[8:9], v[8:9], v[232:233] op_sel_hi:[1,0]
	v_pk_mul_f32 v[10:11], v[10:11], v[232:233] op_sel_hi:[1,0]
	v_pk_mul_f32 v[8:9], v[72:73], v[8:9]
	v_pk_mul_f32 v[10:11], v[74:75], v[10:11]
	v_pk_fma_f32 v[8:9], v[168:169], v[8:9], v[184:185]
	v_pk_fma_f32 v[10:11], v[170:171], v[10:11], v[186:187]
	v_cvt_pk_bf16_f32 v240, v8, v9
	v_cvt_pk_bf16_f32 v241, v10, v11
	v_pk_mul_f32 v[12:13], v[12:13], v[232:233] op_sel_hi:[1,0]
	v_pk_mul_f32 v[14:15], v[14:15], v[232:233] op_sel_hi:[1,0]
	v_pk_mul_f32 v[12:13], v[76:77], v[12:13]
	v_pk_mul_f32 v[14:15], v[78:79], v[14:15]
	v_pk_fma_f32 v[12:13], v[172:173], v[12:13], v[188:189]
	v_pk_fma_f32 v[14:15], v[174:175], v[14:15], v[190:191]
	v_cvt_pk_bf16_f32 v242, v12, v13
	v_cvt_pk_bf16_f32 v243, v14, v15
	global_store_dwordx4 v82, v[240:243], s[38:39] offset:1024
	v_pk_mul_f32 v[16:17], v[16:17], v[234:235] op_sel_hi:[1,0]
	v_pk_mul_f32 v[18:19], v[18:19], v[234:235] op_sel_hi:[1,0]
; __device__ __forceinline__ float bf_lo(unsigned w) { return __uint_as_float(w << 16); }
; __device__ __forceinline__ float bf_hi(unsigned w) { return __uint_as_float(w & 0xffff0000u); }
; __device__ __forceinline__ unsigned pk2(float lo, float hi) { return pg8::cvt_pk_bf16(lo, hi); }
; template <bool BF> __device__ __forceinline__ void prep_rows(const float* xp, const float* xs, const bf16* hb, const float* g, const float* MOD, int shoff, int scoff, bf16* U, int gw, int NGW, int lane) {
;     ...
;         for (int r = 0; r < R; ++r) { const int m = mb + r * NGW; const int mc = m < MT ? m : mb;
; #pragma unroll
;             for (int j = 0; j < 4; ++j) {
;                 if (BF) { const v2u a0 = *(const v2u*)(hb + (size_t)mc * DM + 4 * lane + 256 * j);
;                     v[r][j].x = pg8::bf_lo(a0.x); v[r][j].y = pg8::bf_hi(a0.x); v[r][j].z = pg8::bf_lo(a0.y); v[r][j].w = pg8::bf_hi(a0.y); }
;                 else { const float* xr = mc < MP ? xp + (size_t)mc * DM : xs + (size_t)(mc - MP) * DM; v[r][j] = *(const f32x4*)(xr + 4 * lane + 256 * j); } } }
;     ...
;             for (int j = 0; j < 4; ++j) { const int c = 4 * lane + 256 * j;
;                 const f32x4 gg = *(const f32x4*)(g + c), sc = *(const f32x4*)(mr + scoff + c), sh = *(const f32x4*)(mr + shoff + c);
;                 const f32x4 o = v[r][j] * rstd * gg * (sc + 1.0f) + sh; v2u w; w.x = pk2(o.x, o.y); w.y = pk2(o.z, o.w); *(v2u*)(U + (size_t)m * DM + c) = w; } } }
	v_pk_mul_f32 v[16:17], v[64:65], v[16:17]
	v_pk_mul_f32 v[18:19], v[66:67], v[18:19]
	v_pk_fma_f32 v[16:17], v[160:161], v[16:17], v[176:177]
	v_pk_fma_f32 v[18:19], v[162:163], v[18:19], v[178:179]
	v_cvt_pk_bf16_f32 v244, v16, v17
	v_cvt_pk_bf16_f32 v245, v18, v19
	v_pk_mul_f32 v[20:21], v[20:21], v[234:235] op_sel_hi:[1,0]
	v_pk_mul_f32 v[22:23], v[22:23], v[234:235] op_sel_hi:[1,0]
	v_pk_mul_f32 v[20:21], v[68:69], v[20:21]
	v_pk_mul_f32 v[22:23], v[70:71], v[22:23]
	v_pk_fma_f32 v[20:21], v[164:165], v[20:21], v[180:181]
	v_pk_fma_f32 v[22:23], v[166:167], v[22:23], v[182:183]
	v_cvt_pk_bf16_f32 v246, v20, v21
	v_cvt_pk_bf16_f32 v247, v22, v23
	global_store_dwordx4 v82, v[244:247], s[40:41] offset:0
	v_pk_mul_f32 v[24:25], v[24:25], v[234:235] op_sel_hi:[1,0]
	v_pk_mul_f32 v[26:27], v[26:27], v[234:235] op_sel_hi:[1,0]
	v_pk_mul_f32 v[24:25], v[72:73], v[24:25]
	v_pk_mul_f32 v[26:27], v[74:75], v[26:27]
	v_pk_fma_f32 v[24:25], v[168:169], v[24:25], v[184:185]
	v_pk_fma_f32 v[26:27], v[170:171], v[26:27], v[186:187]
	v_cvt_pk_bf16_f32 v240, v24, v25
	v_cvt_pk_bf16_f32 v241, v26, v27
	v_pk_mul_f32 v[28:29], v[28:29], v[234:235] op_sel_hi:[1,0]
	v_pk_mul_f32 v[30:31], v[30:31], v[234:235] op_sel_hi:[1,0]
	v_pk_mul_f32 v[28:29], v[76:77], v[28:29]
	v_pk_mul_f32 v[30:31], v[78:79], v[30:31]
	v_pk_fma_f32 v[28:29], v[172:173], v[28:29], v[188:189]
	v_pk_fma_f32 v[30:31], v[174:175], v[30:31], v[190:191]
	v_cvt_pk_bf16_f32 v242, v28, v29
	v_cvt_pk_bf16_f32 v243, v30, v31
	global_store_dwordx4 v82, v[240:243], s[40:41] offset:1024
	v_pk_mul_f32 v[32:33], v[32:33], v[236:237] op_sel_hi:[1,0]
	v_pk_mul_f32 v[34:35], v[34:35], v[236:237] op_sel_hi:[1,0]
	v_pk_mul_f32 v[32:33], v[64:65], v[32:33]
	v_pk_mul_f32 v[34:35], v[66:67], v[34:35]
	v_pk_fma_f32 v[32:33], v[192:193], v[32:33], v[208:209]
	v_pk_fma_f32 v[34:35], v[194:195], v[34:35], v[210:211]
	v_cvt_pk_bf16_f32 v244, v32, v33
	v_cvt_pk_bf16_f32 v245, v34, v35
	v_pk_mul_f32 v[36:37], v[36:37], v[236:237] op_sel_hi:[1,0]
	v_pk_mul_f32 v[38:39], v[38:39], v[236:237] op_sel_hi:[1,0]
	v_pk_mul_f32 v[36:37], v[68:69], v[36:37]
	v_pk_mul_f32 v[38:39], v[70:71], v[38:39]
	v_pk_fma_f32 v[36:37], v[196:197], v[36:37], v[212:213]
	v_pk_fma_f32 v[38:39], v[198:199], v[38:39], v[214:215]
	v_cvt_pk_bf16_f32 v246, v36, v37
	v_cvt_pk_bf16_f32 v247, v38, v39
	global_store_dwordx4 v82, v[244:247], s[46:47] offset:0
	v_pk_mul_f32 v[40:41], v[40:41], v[236:237] op_sel_hi:[1,0]
	v_pk_mul_f32 v[42:43], v[42:43], v[236:237] op_sel_hi:[1,0]
	v_pk_mul_f32 v[40:41], v[72:73], v[40:41]
	v_pk_mul_f32 v[42:43], v[74:75], v[42:43]
	v_pk_fma_f32 v[40:41], v[200:201], v[40:41], v[216:217]
	v_pk_fma_f32 v[42:43], v[202:203], v[42:43], v[218:219]
	v_cvt_pk_bf16_f32 v240, v40, v41
	v_cvt_pk_bf16_f32 v241, v42, v43
	v_pk_mul_f32 v[44:45], v[44:45], v[236:237] op_sel_hi:[1,0]
	v_pk_mul_f32 v[46:47], v[46:47], v[236:237] op_sel_hi:[1,0]
	v_pk_mul_f32 v[44:45], v[76:77], v[44:45]
	v_pk_mul_f32 v[46:47], v[78:79], v[46:47]
	v_pk_fma_f32 v[44:45], v[204:205], v[44:45], v[220:221]
	v_pk_fma_f32 v[46:47], v[206:207], v[46:47], v[222:223]
	v_cvt_pk_bf16_f32 v242, v44, v45
	v_cvt_pk_bf16_f32 v243, v46, v47
	global_store_dwordx4 v82, v[240:243], s[46:47] offset:1024
	v_pk_mul_f32 v[48:49], v[48:49], v[238:239] op_sel_hi:[1,0]
	v_pk_mul_f32 v[50:51], v[50:51], v[238:239] op_sel_hi:[1,0]
	v_pk_mul_f32 v[48:49], v[64:65], v[48:49]
	v_pk_mul_f32 v[50:51], v[66:67], v[50:51]
	v_pk_fma_f32 v[48:49], v[192:193], v[48:49], v[208:209]
	v_pk_fma_f32 v[50:51], v[194:195], v[50:51], v[210:211]
	v_cvt_pk_bf16_f32 v244, v48, v49
	v_cvt_pk_bf16_f32 v245, v50, v51
	v_pk_mul_f32 v[52:53], v[52:53], v[238:239] op_sel_hi:[1,0]
	v_pk_mul_f32 v[54:55], v[54:55], v[238:239] op_sel_hi:[1,0]
	v_pk_mul_f32 v[52:53], v[68:69], v[52:53]
	v_pk_mul_f32 v[54:55], v[70:71], v[54:55]
	v_pk_fma_f32 v[52:53], v[196:197], v[52:53], v[212:213]
	v_pk_fma_f32 v[54:55], v[198:199], v[54:55], v[214:215]
	v_cvt_pk_bf16_f32 v246, v52, v53
	v_cvt_pk_bf16_f32 v247, v54, v55
	global_store_dwordx4 v82, v[244:247], s[48:49] offset:0
	v_pk_mul_f32 v[56:57], v[56:57], v[238:239] op_sel_hi:[1,0]
	v_pk_mul_f32 v[58:59], v[58:59], v[238:239] op_sel_hi:[1,0]
	v_pk_mul_f32 v[56:57], v[72:73], v[56:57]
	v_pk_mul_f32 v[58:59], v[74:75], v[58:59]
	v_pk_fma_f32 v[56:57], v[200:201], v[56:57], v[216:217]
	v_pk_fma_f32 v[58:59], v[202:203], v[58:59], v[218:219]
	v_cvt_pk_bf16_f32 v240, v56, v57
	v_cvt_pk_bf16_f32 v241, v58, v59
	v_pk_mul_f32 v[60:61], v[60:61], v[238:239] op_sel_hi:[1,0]
	v_pk_mul_f32 v[62:63], v[62:63], v[238:239] op_sel_hi:[1,0]
	v_pk_mul_f32 v[60:61], v[76:77], v[60:61]
	v_pk_mul_f32 v[62:63], v[78:79], v[62:63]
	v_pk_fma_f32 v[60:61], v[204:205], v[60:61], v[220:221]
	v_pk_fma_f32 v[62:63], v[206:207], v[62:63], v[222:223]
	v_cvt_pk_bf16_f32 v242, v60, v61
	v_cvt_pk_bf16_f32 v243, v62, v63
	global_store_dwordx4 v82, v[240:243], s[48:49] offset:1024
	s_add_u32 s34, s8, 0x21000
	s_addc_u32 s35, s9, 0
	s_add_u32 s36, s8, 0x21000
	s_addc_u32 s37, s9, 0
	global_load_dwordx4 v[176:179], v80, s[34:35] offset:0
	global_load_dwordx4 v[180:183], v80, s[34:35] offset:16
	global_load_dwordx4 v[184:187], v80, s[34:35] offset:2048
	global_load_dwordx4 v[188:191], v80, s[34:35] offset:2064
	global_load_dwordx4 v[160:163], v81, s[34:35] offset:0
	global_load_dwordx4 v[164:167], v81, s[34:35] offset:16
	global_load_dwordx4 v[168:171], v81, s[34:35] offset:2048
	global_load_dwordx4 v[172:175], v81, s[34:35] offset:2064
	global_load_dwordx4 v[208:211], v80, s[36:37] offset:0
	global_load_dwordx4 v[212:215], v80, s[36:37] offset:16
	global_load_dwordx4 v[216:219], v80, s[36:37] offset:2048
	global_load_dwordx4 v[220:223], v80, s[36:37] offset:2064
	global_load_dwordx4 v[192:195], v81, s[36:37] offset:0
	global_load_dwordx4 v[196:199], v81, s[36:37] offset:16
	global_load_dwordx4 v[200:203], v81, s[36:37] offset:2048
	global_load_dwordx4 v[204:207], v81, s[36:37] offset:2064
	s_add_u32 s24, s16, 0x6000000
	s_addc_u32 s25, s17, 0
	s_add_u32 s26, s16, 0x6400000
	s_addc_u32 s27, s17, 0
	s_add_u32 s28, s16, 0x6800000
	s_addc_u32 s29, s17, 0
	s_add_u32 s30, s16, 0x6c00000
	s_addc_u32 s31, s17, 0
	global_load_dwordx4 v[96:99], v82, s[24:25] offset:0 nt
	global_load_dwordx4 v[100:103], v82, s[24:25] offset:1024 nt
	global_load_dwordx4 v[104:107], v82, s[26:27] offset:0 nt
	global_load_dwordx4 v[108:111], v82, s[26:27] offset:1024 nt
	global_load_dwordx4 v[112:115], v82, s[28:29] offset:0 nt
	global_load_dwordx4 v[116:119], v82, s[28:29] offset:1024 nt
	global_load_dwordx4 v[120:123], v82, s[30:31] offset:0 nt
	global_load_dwordx4 v[124:127], v82, s[30:31] offset:1024 nt
	s_waitcnt vmcnt(32)
; __device__ __forceinline__ float bf_lo(unsigned w) { return __uint_as_float(w << 16); }
; __device__ __forceinline__ float bf_hi(unsigned w) { return __uint_as_float(w & 0xffff0000u); }
; template <bool BF> __device__ __forceinline__ void prep_rows(const float* xp, const float* xs, const bf16* hb, const float* g, const float* MOD, int shoff, int scoff, bf16* U, int gw, int NGW, int lane) {
;     ...
;                 if (BF) { const v2u a0 = *(const v2u*)(hb + (size_t)mc * DM + 4 * lane + 256 * j);
;                     v[r][j].x = pg8::bf_lo(a0.x); v[r][j].y = pg8::bf_hi(a0.x); v[r][j].z = pg8::bf_lo(a0.y); v[r][j].w = pg8::bf_hi(a0.y); }
;                 else { const float* xr = mc < MP ? xp + (size_t)mc * DM : xs + (size_t)(mc - MP) * DM; v[r][j] = *(const f32x4*)(xr + 4 * lane + 256 * j); } } }
; #pragma unroll
;         for (int r = 0; r < R; ++r) { float t = 0.f;
; #pragma unroll
;             for (int j = 0; j < 4; ++j) t += (v[r][j].x * v[r][j].x + v[r][j].y * v[r][j].y) + (v[r][j].z * v[r][j].z + v[r][j].w * v[r][j].w);
;             s[r] = t; }
; #pragma unroll
;         for (int o = 1; o < 64; o <<= 1) {
; #pragma unroll
;             for (int r = 0; r < R; ++r) s[r] += __shfl_xor(s[r], o); }
	v_lshlrev_b32_e32 v0, 16, v128
	v_and_b32_e32 v1, 0xffff0000, v128
	v_lshlrev_b32_e32 v2, 16, v129
	v_and_b32_e32 v3, 0xffff0000, v129
	v_lshlrev_b32_e32 v4, 16, v130
	v_and_b32_e32 v5, 0xffff0000, v130
	v_lshlrev_b32_e32 v6, 16, v131
	v_and_b32_e32 v7, 0xffff0000, v131
	v_lshlrev_b32_e32 v8, 16, v132
	v_and_b32_e32 v9, 0xffff0000, v132
	v_lshlrev_b32_e32 v10, 16, v133
	v_and_b32_e32 v11, 0xffff0000, v133
	v_lshlrev_b32_e32 v12, 16, v134
	v_and_b32_e32 v13, 0xffff0000, v134
	v_lshlrev_b32_e32 v14, 16, v135
	v_and_b32_e32 v15, 0xffff0000, v135
	v_lshlrev_b32_e32 v16, 16, v136
	v_and_b32_e32 v17, 0xffff0000, v136
	v_lshlrev_b32_e32 v18, 16, v137
	v_and_b32_e32 v19, 0xffff0000, v137
	v_lshlrev_b32_e32 v20, 16, v138
	v_and_b32_e32 v21, 0xffff0000, v138
	v_lshlrev_b32_e32 v22, 16, v139
	v_and_b32_e32 v23, 0xffff0000, v139
	v_lshlrev_b32_e32 v24, 16, v140
	v_and_b32_e32 v25, 0xffff0000, v140
	v_lshlrev_b32_e32 v26, 16, v141
	v_and_b32_e32 v27, 0xffff0000, v141
	v_lshlrev_b32_e32 v28, 16, v142
	v_and_b32_e32 v29, 0xffff0000, v142
	v_lshlrev_b32_e32 v30, 16, v143
	v_and_b32_e32 v31, 0xffff0000, v143
	v_lshlrev_b32_e32 v32, 16, v144
	v_and_b32_e32 v33, 0xffff0000, v144
	v_lshlrev_b32_e32 v34, 16, v145
	v_and_b32_e32 v35, 0xffff0000, v145
	v_lshlrev_b32_e32 v36, 16, v146
	v_and_b32_e32 v37, 0xffff0000, v146
	v_lshlrev_b32_e32 v38, 16, v147
	v_and_b32_e32 v39, 0xffff0000, v147
	v_lshlrev_b32_e32 v40, 16, v148
	v_and_b32_e32 v41, 0xffff0000, v148
	v_lshlrev_b32_e32 v42, 16, v149
	v_and_b32_e32 v43, 0xffff0000, v149
	v_lshlrev_b32_e32 v44, 16, v150
	v_and_b32_e32 v45, 0xffff0000, v150
	v_lshlrev_b32_e32 v46, 16, v151
	v_and_b32_e32 v47, 0xffff0000, v151
	v_lshlrev_b32_e32 v48, 16, v152
	v_and_b32_e32 v49, 0xffff0000, v152
	v_lshlrev_b32_e32 v50, 16, v153
	v_and_b32_e32 v51, 0xffff0000, v153
	v_lshlrev_b32_e32 v52, 16, v154
	v_and_b32_e32 v53, 0xffff0000, v154
	v_lshlrev_b32_e32 v54, 16, v155
	v_and_b32_e32 v55, 0xffff0000, v155
	v_lshlrev_b32_e32 v56, 16, v156
	v_and_b32_e32 v57, 0xffff0000, v156
	v_lshlrev_b32_e32 v58, 16, v157
	v_and_b32_e32 v59, 0xffff0000, v157
	v_lshlrev_b32_e32 v60, 16, v158
	v_and_b32_e32 v61, 0xffff0000, v158
	v_lshlrev_b32_e32 v62, 16, v159
	v_and_b32_e32 v63, 0xffff0000, v159
	v_pk_mul_f32 v[240:241], v[0:1], v[0:1]
	v_pk_mul_f32 v[242:243], v[16:17], v[16:17]
	v_pk_mul_f32 v[244:245], v[32:33], v[32:33]
	v_pk_mul_f32 v[246:247], v[48:49], v[48:49]
	v_pk_fma_f32 v[240:241], v[2:3], v[2:3], v[240:241]
	v_pk_fma_f32 v[242:243], v[18:19], v[18:19], v[242:243]
	v_pk_fma_f32 v[244:245], v[34:35], v[34:35], v[244:245]
	v_pk_fma_f32 v[246:247], v[50:51], v[50:51], v[246:247]
	v_pk_fma_f32 v[240:241], v[4:5], v[4:5], v[240:241]
	v_pk_fma_f32 v[242:243], v[20:21], v[20:21], v[242:243]
	v_pk_fma_f32 v[244:245], v[36:37], v[36:37], v[244:245]
	v_pk_fma_f32 v[246:247], v[52:53], v[52:53], v[246:247]
	v_pk_fma_f32 v[240:241], v[6:7], v[6:7], v[240:241]
	v_pk_fma_f32 v[242:243], v[22:23], v[22:23], v[242:243]
	v_pk_fma_f32 v[244:245], v[38:39], v[38:39], v[244:245]
	v_pk_fma_f32 v[246:247], v[54:55], v[54:55], v[246:247]
	v_pk_fma_f32 v[240:241], v[8:9], v[8:9], v[240:241]
	v_pk_fma_f32 v[242:243], v[24:25], v[24:25], v[242:243]
	v_pk_fma_f32 v[244:245], v[40:41], v[40:41], v[244:245]
	v_pk_fma_f32 v[246:247], v[56:57], v[56:57], v[246:247]
	v_pk_fma_f32 v[240:241], v[10:11], v[10:11], v[240:241]
	v_pk_fma_f32 v[242:243], v[26:27], v[26:27], v[242:243]
	v_pk_fma_f32 v[244:245], v[42:43], v[42:43], v[244:245]
	v_pk_fma_f32 v[246:247], v[58:59], v[58:59], v[246:247]
	v_pk_fma_f32 v[240:241], v[12:13], v[12:13], v[240:241]
	v_pk_fma_f32 v[242:243], v[28:29], v[28:29], v[242:243]
	v_pk_fma_f32 v[244:245], v[44:45], v[44:45], v[244:245]
	v_pk_fma_f32 v[246:247], v[60:61], v[60:61], v[246:247]
	v_pk_fma_f32 v[240:241], v[14:15], v[14:15], v[240:241]
	v_pk_fma_f32 v[242:243], v[30:31], v[30:31], v[242:243]
	v_pk_fma_f32 v[244:245], v[46:47], v[46:47], v[244:245]
	v_pk_fma_f32 v[246:247], v[62:63], v[62:63], v[246:247]
	v_add_f32_e32 v224, v240, v241
	v_add_f32_e32 v225, v242, v243
	v_add_f32_e32 v226, v244, v245
	v_add_f32_e32 v227, v246, v247
	ds_bpermute_b32 v228, v83, v224
	ds_bpermute_b32 v229, v83, v225
	ds_bpermute_b32 v230, v83, v226
	ds_bpermute_b32 v231, v83, v227
	s_waitcnt lgkmcnt(0)
	v_add_f32_e32 v224, v224, v228
	v_add_f32_e32 v225, v225, v229
	v_add_f32_e32 v226, v226, v230
	v_add_f32_e32 v227, v227, v231
	ds_bpermute_b32 v228, v84, v224
	ds_bpermute_b32 v229, v84, v225
	ds_bpermute_b32 v230, v84, v226
	ds_bpermute_b32 v231, v84, v227
	s_waitcnt lgkmcnt(0)
	v_add_f32_e32 v224, v224, v228
	v_add_f32_e32 v225, v225, v229
	v_add_f32_e32 v226, v226, v230
	v_add_f32_e32 v227, v227, v231
	ds_bpermute_b32 v228, v85, v224
	ds_bpermute_b32 v229, v85, v225
	ds_bpermute_b32 v230, v85, v226
	ds_bpermute_b32 v231, v85, v227
	s_waitcnt lgkmcnt(0)
	v_add_f32_e32 v224, v224, v228
	v_add_f32_e32 v225, v225, v229
	v_add_f32_e32 v226, v226, v230
	v_add_f32_e32 v227, v227, v231
	ds_bpermute_b32 v228, v86, v224
	ds_bpermute_b32 v229, v86, v225
	ds_bpermute_b32 v230, v86, v226
	ds_bpermute_b32 v231, v86, v227
	s_waitcnt lgkmcnt(0)
	v_add_f32_e32 v224, v224, v228
	v_add_f32_e32 v225, v225, v229
	v_add_f32_e32 v226, v226, v230
	v_add_f32_e32 v227, v227, v231
	ds_bpermute_b32 v228, v87, v224
	ds_bpermute_b32 v229, v87, v225
	ds_bpermute_b32 v230, v87, v226
	ds_bpermute_b32 v231, v87, v227
	s_waitcnt lgkmcnt(0)
	v_add_f32_e32 v224, v224, v228
	v_add_f32_e32 v225, v225, v229
	v_add_f32_e32 v226, v226, v230
	v_add_f32_e32 v227, v227, v231
	ds_bpermute_b32 v228, v88, v224
	ds_bpermute_b32 v229, v88, v225
	ds_bpermute_b32 v230, v88, v226
	ds_bpermute_b32 v231, v88, v227
	s_waitcnt lgkmcnt(0)
; template <bool BF> __device__ __forceinline__ void prep_rows(const float* xp, const float* xs, const bf16* hb, const float* g, const float* MOD, int shoff, int scoff, bf16* U, int gw, int NGW, int lane) {
;     ...
;             for (int r = 0; r < R; ++r) s[r] += __shfl_xor(s[r], o); }
; #pragma unroll
;         for (int r = 0; r < R; ++r) { const int m = mb + r * NGW; if (m < MT) {
;             const float rstd = 1.0f / sqrtf(s[r] * (1.0f / DM) + RMS_EPS);
	v_add_f32_e32 v224, v224, v228
	v_add_f32_e32 v225, v225, v229
	v_add_f32_e32 v226, v226, v230
	v_add_f32_e32 v227, v227, v231
	v_fmamk_f32 v240, v224, 0x3a800000, v89
	v_mul_f32_e32 v241, 0x4f800000, v240
	v_cmp_gt_f32_e32 vcc, s54, v240
	s_nop 1
	v_cndmask_b32_e32 v247, v240, v241, vcc
	v_sqrt_f32_e32 v242, v247
	s_nop 1
	v_add_u32_e32 v243, -1, v242
	v_add_u32_e32 v244, 1, v242
	v_fma_f32 v245, -v243, v242, v247
	v_fma_f32 v246, -v244, v242, v247
	v_cmp_ge_f32_e64 s[52:53], 0, v245
	s_nop 1
	v_cndmask_b32_e64 v242, v242, v243, s[52:53]
	v_cmp_lt_f32_e64 s[52:53], 0, v246
	s_nop 1
	v_cndmask_b32_e64 v242, v242, v244, s[52:53]
	v_mul_f32_e32 v243, 0x37800000, v242
	v_cndmask_b32_e32 v242, v242, v243, vcc
	v_cmp_class_f32_e32 vcc, v247, v90
	s_nop 1
	v_cndmask_b32_e32 v247, v242, v247, vcc
	v_div_scale_f32 v248, s[52:53], v247, v247, 1.0
	v_rcp_f32_e32 v249, v248
	v_div_scale_f32 v228, vcc, 1.0, v247, 1.0
	s_nop 0
	v_fma_f32 v229, -v248, v249, 1.0
	v_fmac_f32_e32 v249, v229, v249
	v_mul_f32_e32 v230, v228, v249
	v_fma_f32 v229, -v248, v230, v228
	v_fmac_f32_e32 v230, v229, v249
	v_fma_f32 v248, -v248, v230, v228
	v_div_fmas_f32 v248, v248, v249, v230
	v_div_fixup_f32 v232, v248, v247, 1.0
	v_fmamk_f32 v240, v225, 0x3a800000, v89
	v_mul_f32_e32 v241, 0x4f800000, v240
	v_cmp_gt_f32_e32 vcc, s54, v240
	s_nop 1
	v_cndmask_b32_e32 v247, v240, v241, vcc
	v_sqrt_f32_e32 v242, v247
	s_nop 1
	v_add_u32_e32 v243, -1, v242
	v_add_u32_e32 v244, 1, v242
	v_fma_f32 v245, -v243, v242, v247
	v_fma_f32 v246, -v244, v242, v247
	v_cmp_ge_f32_e64 s[52:53], 0, v245
	s_nop 1
	v_cndmask_b32_e64 v242, v242, v243, s[52:53]
	v_cmp_lt_f32_e64 s[52:53], 0, v246
	s_nop 1
	v_cndmask_b32_e64 v242, v242, v244, s[52:53]
	v_mul_f32_e32 v243, 0x37800000, v242
	v_cndmask_b32_e32 v242, v242, v243, vcc
	v_cmp_class_f32_e32 vcc, v247, v90
	s_nop 1
	v_cndmask_b32_e32 v247, v242, v247, vcc
	v_div_scale_f32 v248, s[52:53], v247, v247, 1.0
	v_rcp_f32_e32 v249, v248
	v_div_scale_f32 v228, vcc, 1.0, v247, 1.0
	s_nop 0
	v_fma_f32 v229, -v248, v249, 1.0
	v_fmac_f32_e32 v249, v229, v249
	v_mul_f32_e32 v230, v228, v249
	v_fma_f32 v229, -v248, v230, v228
	v_fmac_f32_e32 v230, v229, v249
	v_fma_f32 v248, -v248, v230, v228
	v_div_fmas_f32 v248, v248, v249, v230
	v_div_fixup_f32 v234, v248, v247, 1.0
	v_fmamk_f32 v240, v226, 0x3a800000, v89
	v_mul_f32_e32 v241, 0x4f800000, v240
	v_cmp_gt_f32_e32 vcc, s54, v240
	s_nop 1
	v_cndmask_b32_e32 v247, v240, v241, vcc
	v_sqrt_f32_e32 v242, v247
	s_nop 1
	v_add_u32_e32 v243, -1, v242
	v_add_u32_e32 v244, 1, v242
	v_fma_f32 v245, -v243, v242, v247
	v_fma_f32 v246, -v244, v242, v247
	v_cmp_ge_f32_e64 s[52:53], 0, v245
	s_nop 1
	v_cndmask_b32_e64 v242, v242, v243, s[52:53]
	v_cmp_lt_f32_e64 s[52:53], 0, v246
	s_nop 1
	v_cndmask_b32_e64 v242, v242, v244, s[52:53]
	v_mul_f32_e32 v243, 0x37800000, v242
	v_cndmask_b32_e32 v242, v242, v243, vcc
	v_cmp_class_f32_e32 vcc, v247, v90
	s_nop 1
	v_cndmask_b32_e32 v247, v242, v247, vcc
	v_div_scale_f32 v248, s[52:53], v247, v247, 1.0
	v_rcp_f32_e32 v249, v248
	v_div_scale_f32 v228, vcc, 1.0, v247, 1.0
	s_nop 0
	v_fma_f32 v229, -v248, v249, 1.0
	v_fmac_f32_e32 v249, v229, v249
	v_mul_f32_e32 v230, v228, v249
	v_fma_f32 v229, -v248, v230, v228
	v_fmac_f32_e32 v230, v229, v249
	v_fma_f32 v248, -v248, v230, v228
	v_div_fmas_f32 v248, v248, v249, v230
	v_div_fixup_f32 v236, v248, v247, 1.0
	v_fmamk_f32 v240, v227, 0x3a800000, v89
	v_mul_f32_e32 v241, 0x4f800000, v240
	v_cmp_gt_f32_e32 vcc, s54, v240
	s_nop 1
	v_cndmask_b32_e32 v247, v240, v241, vcc
	v_sqrt_f32_e32 v242, v247
	s_nop 1
	v_add_u32_e32 v243, -1, v242
	v_add_u32_e32 v244, 1, v242
	v_fma_f32 v245, -v243, v242, v247
	v_fma_f32 v246, -v244, v242, v247
	v_cmp_ge_f32_e64 s[52:53], 0, v245
	s_nop 1
	v_cndmask_b32_e64 v242, v242, v243, s[52:53]
	v_cmp_lt_f32_e64 s[52:53], 0, v246
	s_nop 1
	v_cndmask_b32_e64 v242, v242, v244, s[52:53]
	v_mul_f32_e32 v243, 0x37800000, v242
	v_cndmask_b32_e32 v242, v242, v243, vcc
	v_cmp_class_f32_e32 vcc, v247, v90
	s_nop 1
	v_cndmask_b32_e32 v247, v242, v247, vcc
	v_div_scale_f32 v248, s[52:53], v247, v247, 1.0
	v_rcp_f32_e32 v249, v248
	v_div_scale_f32 v228, vcc, 1.0, v247, 1.0
	s_nop 0
	v_fma_f32 v229, -v248, v249, 1.0
	v_fmac_f32_e32 v249, v229, v249
	v_mul_f32_e32 v230, v228, v249
	v_fma_f32 v229, -v248, v230, v228
	v_fmac_f32_e32 v230, v229, v249
	v_fma_f32 v248, -v248, v230, v228
	v_div_fmas_f32 v248, v248, v249, v230
	v_div_fixup_f32 v238, v248, v247, 1.0
	s_waitcnt vmcnt(8)
; __device__ __forceinline__ unsigned pk2(float lo, float hi) { return pg8::cvt_pk_bf16(lo, hi); }
; template <bool BF> __device__ __forceinline__ void prep_rows(const float* xp, const float* xs, const bf16* hb, const float* g, const float* MOD, int shoff, int scoff, bf16* U, int gw, int NGW, int lane) {
;     ...
;             const float* mr = MOD + (size_t)(m < MP ? (m >> 13) : 8 + ((m - MP) >> 12)) * 6144;
; #pragma unroll
;             for (int j = 0; j < 4; ++j) { const int c = 4 * lane + 256 * j;
;                 const f32x4 gg = *(const f32x4*)(g + c), sc = *(const f32x4*)(mr + scoff + c), sh = *(const f32x4*)(mr + shoff + c);
;                 const f32x4 o = v[r][j] * rstd * gg * (sc + 1.0f) + sh; v2u w; w.x = pk2(o.x, o.y); w.y = pk2(o.z, o.w); *(v2u*)(U + (size_t)m * DM + c) = w; } } }
	v_pk_add_f32 v[160:161], v[160:161], 1.0 op_sel_hi:[1,0]
	v_pk_add_f32 v[162:163], v[162:163], 1.0 op_sel_hi:[1,0]
	v_pk_add_f32 v[164:165], v[164:165], 1.0 op_sel_hi:[1,0]
	v_pk_add_f32 v[166:167], v[166:167], 1.0 op_sel_hi:[1,0]
	v_pk_add_f32 v[168:169], v[168:169], 1.0 op_sel_hi:[1,0]
	v_pk_add_f32 v[170:171], v[170:171], 1.0 op_sel_hi:[1,0]
	v_pk_add_f32 v[172:173], v[172:173], 1.0 op_sel_hi:[1,0]
	v_pk_add_f32 v[174:175], v[174:175], 1.0 op_sel_hi:[1,0]
	v_pk_add_f32 v[192:193], v[192:193], 1.0 op_sel_hi:[1,0]
	v_pk_add_f32 v[194:195], v[194:195], 1.0 op_sel_hi:[1,0]
	v_pk_add_f32 v[196:197], v[196:197], 1.0 op_sel_hi:[1,0]
	v_pk_add_f32 v[198:199], v[198:199], 1.0 op_sel_hi:[1,0]
	v_pk_add_f32 v[200:201], v[200:201], 1.0 op_sel_hi:[1,0]
	v_pk_add_f32 v[202:203], v[202:203], 1.0 op_sel_hi:[1,0]
	v_pk_add_f32 v[204:205], v[204:205], 1.0 op_sel_hi:[1,0]
	v_pk_add_f32 v[206:207], v[206:207], 1.0 op_sel_hi:[1,0]
	s_add_u32 s38, s20, 0x5000000
	s_addc_u32 s39, s21, 0
	s_add_u32 s40, s20, 0x5400000
	s_addc_u32 s41, s21, 0
	s_add_u32 s46, s20, 0x5800000
	s_addc_u32 s47, s21, 0
	s_add_u32 s48, s20, 0x5c00000
	s_addc_u32 s49, s21, 0
	v_pk_mul_f32 v[0:1], v[0:1], v[232:233] op_sel_hi:[1,0]
	v_pk_mul_f32 v[2:3], v[2:3], v[232:233] op_sel_hi:[1,0]
	v_pk_mul_f32 v[0:1], v[64:65], v[0:1]
	v_pk_mul_f32 v[2:3], v[66:67], v[2:3]
	v_pk_fma_f32 v[0:1], v[160:161], v[0:1], v[176:177]
	v_pk_fma_f32 v[2:3], v[162:163], v[2:3], v[178:179]
	v_cvt_pk_bf16_f32 v244, v0, v1
	v_cvt_pk_bf16_f32 v245, v2, v3
	v_pk_mul_f32 v[4:5], v[4:5], v[232:233] op_sel_hi:[1,0]
	v_pk_mul_f32 v[6:7], v[6:7], v[232:233] op_sel_hi:[1,0]
	v_pk_mul_f32 v[4:5], v[68:69], v[4:5]
	v_pk_mul_f32 v[6:7], v[70:71], v[6:7]
	v_pk_fma_f32 v[4:5], v[164:165], v[4:5], v[180:181]
	v_pk_fma_f32 v[6:7], v[166:167], v[6:7], v[182:183]
	v_cvt_pk_bf16_f32 v246, v4, v5
	v_cvt_pk_bf16_f32 v247, v6, v7
	global_store_dwordx4 v82, v[244:247], s[38:39] offset:0
	v_pk_mul_f32 v[8:9], v[8:9], v[232:233] op_sel_hi:[1,0]
	v_pk_mul_f32 v[10:11], v[10:11], v[232:233] op_sel_hi:[1,0]
	v_pk_mul_f32 v[8:9], v[72:73], v[8:9]
	v_pk_mul_f32 v[10:11], v[74:75], v[10:11]
	v_pk_fma_f32 v[8:9], v[168:169], v[8:9], v[184:185]
	v_pk_fma_f32 v[10:11], v[170:171], v[10:11], v[186:187]
	v_cvt_pk_bf16_f32 v240, v8, v9
	v_cvt_pk_bf16_f32 v241, v10, v11
	v_pk_mul_f32 v[12:13], v[12:13], v[232:233] op_sel_hi:[1,0]
	v_pk_mul_f32 v[14:15], v[14:15], v[232:233] op_sel_hi:[1,0]
	v_pk_mul_f32 v[12:13], v[76:77], v[12:13]
	v_pk_mul_f32 v[14:15], v[78:79], v[14:15]
	v_pk_fma_f32 v[12:13], v[172:173], v[12:13], v[188:189]
	v_pk_fma_f32 v[14:15], v[174:175], v[14:15], v[190:191]
	v_cvt_pk_bf16_f32 v242, v12, v13
	v_cvt_pk_bf16_f32 v243, v14, v15
	global_store_dwordx4 v82, v[240:243], s[38:39] offset:1024
	v_pk_mul_f32 v[16:17], v[16:17], v[234:235] op_sel_hi:[1,0]
	v_pk_mul_f32 v[18:19], v[18:19], v[234:235] op_sel_hi:[1,0]
	v_pk_mul_f32 v[16:17], v[64:65], v[16:17]
	v_pk_mul_f32 v[18:19], v[66:67], v[18:19]
	v_pk_fma_f32 v[16:17], v[160:161], v[16:17], v[176:177]
	v_pk_fma_f32 v[18:19], v[162:163], v[18:19], v[178:179]
	v_cvt_pk_bf16_f32 v244, v16, v17
	v_cvt_pk_bf16_f32 v245, v18, v19
	v_pk_mul_f32 v[20:21], v[20:21], v[234:235] op_sel_hi:[1,0]
	v_pk_mul_f32 v[22:23], v[22:23], v[234:235] op_sel_hi:[1,0]
	v_pk_mul_f32 v[20:21], v[68:69], v[20:21]
	v_pk_mul_f32 v[22:23], v[70:71], v[22:23]
	v_pk_fma_f32 v[20:21], v[164:165], v[20:21], v[180:181]
	v_pk_fma_f32 v[22:23], v[166:167], v[22:23], v[182:183]
	v_cvt_pk_bf16_f32 v246, v20, v21
	v_cvt_pk_bf16_f32 v247, v22, v23
	global_store_dwordx4 v82, v[244:247], s[40:41] offset:0
	v_pk_mul_f32 v[24:25], v[24:25], v[234:235] op_sel_hi:[1,0]
	v_pk_mul_f32 v[26:27], v[26:27], v[234:235] op_sel_hi:[1,0]
	v_pk_mul_f32 v[24:25], v[72:73], v[24:25]
	v_pk_mul_f32 v[26:27], v[74:75], v[26:27]
	v_pk_fma_f32 v[24:25], v[168:169], v[24:25], v[184:185]
	v_pk_fma_f32 v[26:27], v[170:171], v[26:27], v[186:187]
	v_cvt_pk_bf16_f32 v240, v24, v25
	v_cvt_pk_bf16_f32 v241, v26, v27
	v_pk_mul_f32 v[28:29], v[28:29], v[234:235] op_sel_hi:[1,0]
	v_pk_mul_f32 v[30:31], v[30:31], v[234:235] op_sel_hi:[1,0]
	v_pk_mul_f32 v[28:29], v[76:77], v[28:29]
	v_pk_mul_f32 v[30:31], v[78:79], v[30:31]
	v_pk_fma_f32 v[28:29], v[172:173], v[28:29], v[188:189]
	v_pk_fma_f32 v[30:31], v[174:175], v[30:31], v[190:191]
	v_cvt_pk_bf16_f32 v242, v28, v29
	v_cvt_pk_bf16_f32 v243, v30, v31
	global_store_dwordx4 v82, v[240:243], s[40:41] offset:1024
	v_pk_mul_f32 v[32:33], v[32:33], v[236:237] op_sel_hi:[1,0]
	v_pk_mul_f32 v[34:35], v[34:35], v[236:237] op_sel_hi:[1,0]
	v_pk_mul_f32 v[32:33], v[64:65], v[32:33]
	v_pk_mul_f32 v[34:35], v[66:67], v[34:35]
	v_pk_fma_f32 v[32:33], v[192:193], v[32:33], v[208:209]
	v_pk_fma_f32 v[34:35], v[194:195], v[34:35], v[210:211]
	v_cvt_pk_bf16_f32 v244, v32, v33
	v_cvt_pk_bf16_f32 v245, v34, v35
	v_pk_mul_f32 v[36:37], v[36:37], v[236:237] op_sel_hi:[1,0]
	v_pk_mul_f32 v[38:39], v[38:39], v[236:237] op_sel_hi:[1,0]
	v_pk_mul_f32 v[36:37], v[68:69], v[36:37]
	v_pk_mul_f32 v[38:39], v[70:71], v[38:39]
	v_pk_fma_f32 v[36:37], v[196:197], v[36:37], v[212:213]
	v_pk_fma_f32 v[38:39], v[198:199], v[38:39], v[214:215]
	v_cvt_pk_bf16_f32 v246, v36, v37
	v_cvt_pk_bf16_f32 v247, v38, v39
	global_store_dwordx4 v82, v[244:247], s[46:47] offset:0
	v_pk_mul_f32 v[40:41], v[40:41], v[236:237] op_sel_hi:[1,0]
	v_pk_mul_f32 v[42:43], v[42:43], v[236:237] op_sel_hi:[1,0]
	v_pk_mul_f32 v[40:41], v[72:73], v[40:41]
	v_pk_mul_f32 v[42:43], v[74:75], v[42:43]
	v_pk_fma_f32 v[40:41], v[200:201], v[40:41], v[216:217]
	v_pk_fma_f32 v[42:43], v[202:203], v[42:43], v[218:219]
	v_cvt_pk_bf16_f32 v240, v40, v41
; __device__ __forceinline__ float bf_lo(unsigned w) { return __uint_as_float(w << 16); }
; __device__ __forceinline__ float bf_hi(unsigned w) { return __uint_as_float(w & 0xffff0000u); }
; __device__ __forceinline__ unsigned pk2(float lo, float hi) { return pg8::cvt_pk_bf16(lo, hi); }
; template <bool BF> __device__ __forceinline__ void prep_rows(const float* xp, const float* xs, const bf16* hb, const float* g, const float* MOD, int shoff, int scoff, bf16* U, int gw, int NGW, int lane) {
;     ...
;         for (int r = 0; r < R; ++r) { const int m = mb + r * NGW; const int mc = m < MT ? m : mb;
; #pragma unroll
;             for (int j = 0; j < 4; ++j) {
;                 if (BF) { const v2u a0 = *(const v2u*)(hb + (size_t)mc * DM + 4 * lane + 256 * j);
;                     v[r][j].x = pg8::bf_lo(a0.x); v[r][j].y = pg8::bf_hi(a0.x); v[r][j].z = pg8::bf_lo(a0.y); v[r][j].w = pg8::bf_hi(a0.y); }
;     ...
;             for (int j = 0; j < 4; ++j) { const int c = 4 * lane + 256 * j;
;                 const f32x4 gg = *(const f32x4*)(g + c), sc = *(const f32x4*)(mr + scoff + c), sh = *(const f32x4*)(mr + shoff + c);
;                 const f32x4 o = v[r][j] * rstd * gg * (sc + 1.0f) + sh; v2u w; w.x = pk2(o.x, o.y); w.y = pk2(o.z, o.w); *(v2u*)(U + (size_t)m * DM + c) = w; } } }
	v_cvt_pk_bf16_f32 v241, v42, v43
	v_pk_mul_f32 v[44:45], v[44:45], v[236:237] op_sel_hi:[1,0]
	v_pk_mul_f32 v[46:47], v[46:47], v[236:237] op_sel_hi:[1,0]
	v_pk_mul_f32 v[44:45], v[76:77], v[44:45]
	v_pk_mul_f32 v[46:47], v[78:79], v[46:47]
	v_pk_fma_f32 v[44:45], v[204:205], v[44:45], v[220:221]
	v_pk_fma_f32 v[46:47], v[206:207], v[46:47], v[222:223]
	v_cvt_pk_bf16_f32 v242, v44, v45
	v_cvt_pk_bf16_f32 v243, v46, v47
	global_store_dwordx4 v82, v[240:243], s[46:47] offset:1024
	v_pk_mul_f32 v[48:49], v[48:49], v[238:239] op_sel_hi:[1,0]
	v_pk_mul_f32 v[50:51], v[50:51], v[238:239] op_sel_hi:[1,0]
	v_pk_mul_f32 v[48:49], v[64:65], v[48:49]
	v_pk_mul_f32 v[50:51], v[66:67], v[50:51]
	v_pk_fma_f32 v[48:49], v[192:193], v[48:49], v[208:209]
	v_pk_fma_f32 v[50:51], v[194:195], v[50:51], v[210:211]
	v_cvt_pk_bf16_f32 v244, v48, v49
	v_cvt_pk_bf16_f32 v245, v50, v51
	v_pk_mul_f32 v[52:53], v[52:53], v[238:239] op_sel_hi:[1,0]
	v_pk_mul_f32 v[54:55], v[54:55], v[238:239] op_sel_hi:[1,0]
	v_pk_mul_f32 v[52:53], v[68:69], v[52:53]
	v_pk_mul_f32 v[54:55], v[70:71], v[54:55]
	v_pk_fma_f32 v[52:53], v[196:197], v[52:53], v[212:213]
	v_pk_fma_f32 v[54:55], v[198:199], v[54:55], v[214:215]
	v_cvt_pk_bf16_f32 v246, v52, v53
	v_cvt_pk_bf16_f32 v247, v54, v55
	global_store_dwordx4 v82, v[244:247], s[48:49] offset:0
	v_pk_mul_f32 v[56:57], v[56:57], v[238:239] op_sel_hi:[1,0]
	v_pk_mul_f32 v[58:59], v[58:59], v[238:239] op_sel_hi:[1,0]
	v_pk_mul_f32 v[56:57], v[72:73], v[56:57]
	v_pk_mul_f32 v[58:59], v[74:75], v[58:59]
	v_pk_fma_f32 v[56:57], v[200:201], v[56:57], v[216:217]
	v_pk_fma_f32 v[58:59], v[202:203], v[58:59], v[218:219]
	v_cvt_pk_bf16_f32 v240, v56, v57
	v_cvt_pk_bf16_f32 v241, v58, v59
	v_pk_mul_f32 v[60:61], v[60:61], v[238:239] op_sel_hi:[1,0]
	v_pk_mul_f32 v[62:63], v[62:63], v[238:239] op_sel_hi:[1,0]
	v_pk_mul_f32 v[60:61], v[76:77], v[60:61]
	v_pk_mul_f32 v[62:63], v[78:79], v[62:63]
	v_pk_fma_f32 v[60:61], v[204:205], v[60:61], v[220:221]
	v_pk_fma_f32 v[62:63], v[206:207], v[62:63], v[222:223]
	v_cvt_pk_bf16_f32 v242, v60, v61
	v_cvt_pk_bf16_f32 v243, v62, v63
	global_store_dwordx4 v82, v[240:243], s[48:49] offset:1024
	s_add_u32 s34, s8, 0x27000
	s_addc_u32 s35, s9, 0
	s_add_u32 s36, s8, 0x27000
	s_addc_u32 s37, s9, 0
	global_load_dwordx4 v[176:179], v80, s[34:35] offset:0
	global_load_dwordx4 v[180:183], v80, s[34:35] offset:16
	global_load_dwordx4 v[184:187], v80, s[34:35] offset:2048
	global_load_dwordx4 v[188:191], v80, s[34:35] offset:2064
	global_load_dwordx4 v[160:163], v81, s[34:35] offset:0
	global_load_dwordx4 v[164:167], v81, s[34:35] offset:16
	global_load_dwordx4 v[168:171], v81, s[34:35] offset:2048
	global_load_dwordx4 v[172:175], v81, s[34:35] offset:2064
	global_load_dwordx4 v[208:211], v80, s[36:37] offset:0
	global_load_dwordx4 v[212:215], v80, s[36:37] offset:16
	global_load_dwordx4 v[216:219], v80, s[36:37] offset:2048
	global_load_dwordx4 v[220:223], v80, s[36:37] offset:2064
	global_load_dwordx4 v[192:195], v81, s[36:37] offset:0
	global_load_dwordx4 v[196:199], v81, s[36:37] offset:16
	global_load_dwordx4 v[200:203], v81, s[36:37] offset:2048
	global_load_dwordx4 v[204:207], v81, s[36:37] offset:2064
	s_add_u32 s24, s16, 0x7000000
	s_addc_u32 s25, s17, 0
	s_add_u32 s26, s16, 0x7400000
	s_addc_u32 s27, s17, 0
	s_add_u32 s28, s16, 0x7800000
	s_addc_u32 s29, s17, 0
	s_add_u32 s30, s16, 0x7c00000
	s_addc_u32 s31, s17, 0
	global_load_dwordx4 v[128:131], v82, s[24:25] offset:0 nt
	global_load_dwordx4 v[132:135], v82, s[24:25] offset:1024 nt
	global_load_dwordx4 v[136:139], v82, s[26:27] offset:0 nt
	global_load_dwordx4 v[140:143], v82, s[26:27] offset:1024 nt
	global_load_dwordx4 v[144:147], v82, s[28:29] offset:0 nt
	global_load_dwordx4 v[148:151], v82, s[28:29] offset:1024 nt
	global_load_dwordx4 v[152:155], v82, s[30:31] offset:0 nt
	global_load_dwordx4 v[156:159], v82, s[30:31] offset:1024 nt
	s_waitcnt vmcnt(32)
	v_lshlrev_b32_e32 v0, 16, v96
	v_and_b32_e32 v1, 0xffff0000, v96
	v_lshlrev_b32_e32 v2, 16, v97
	v_and_b32_e32 v3, 0xffff0000, v97
	v_lshlrev_b32_e32 v4, 16, v98
	v_and_b32_e32 v5, 0xffff0000, v98
	v_lshlrev_b32_e32 v6, 16, v99
	v_and_b32_e32 v7, 0xffff0000, v99
	v_lshlrev_b32_e32 v8, 16, v100
	v_and_b32_e32 v9, 0xffff0000, v100
	v_lshlrev_b32_e32 v10, 16, v101
	v_and_b32_e32 v11, 0xffff0000, v101
	v_lshlrev_b32_e32 v12, 16, v102
	v_and_b32_e32 v13, 0xffff0000, v102
	v_lshlrev_b32_e32 v14, 16, v103
	v_and_b32_e32 v15, 0xffff0000, v103
	v_lshlrev_b32_e32 v16, 16, v104
	v_and_b32_e32 v17, 0xffff0000, v104
	v_lshlrev_b32_e32 v18, 16, v105
	v_and_b32_e32 v19, 0xffff0000, v105
	v_lshlrev_b32_e32 v20, 16, v106
	v_and_b32_e32 v21, 0xffff0000, v106
	v_lshlrev_b32_e32 v22, 16, v107
	v_and_b32_e32 v23, 0xffff0000, v107
	v_lshlrev_b32_e32 v24, 16, v108
	v_and_b32_e32 v25, 0xffff0000, v108
	v_lshlrev_b32_e32 v26, 16, v109
	v_and_b32_e32 v27, 0xffff0000, v109
	v_lshlrev_b32_e32 v28, 16, v110
	v_and_b32_e32 v29, 0xffff0000, v110
	v_lshlrev_b32_e32 v30, 16, v111
	v_and_b32_e32 v31, 0xffff0000, v111
	v_lshlrev_b32_e32 v32, 16, v112
	v_and_b32_e32 v33, 0xffff0000, v112
	v_lshlrev_b32_e32 v34, 16, v113
	v_and_b32_e32 v35, 0xffff0000, v113
	v_lshlrev_b32_e32 v36, 16, v114
	v_and_b32_e32 v37, 0xffff0000, v114
	v_lshlrev_b32_e32 v38, 16, v115
	v_and_b32_e32 v39, 0xffff0000, v115
	v_lshlrev_b32_e32 v40, 16, v116
	v_and_b32_e32 v41, 0xffff0000, v116
	v_lshlrev_b32_e32 v42, 16, v117
	v_and_b32_e32 v43, 0xffff0000, v117
	v_lshlrev_b32_e32 v44, 16, v118
	v_and_b32_e32 v45, 0xffff0000, v118
	v_lshlrev_b32_e32 v46, 16, v119
	v_and_b32_e32 v47, 0xffff0000, v119
	v_lshlrev_b32_e32 v48, 16, v120
	v_and_b32_e32 v49, 0xffff0000, v120
; __device__ __forceinline__ float bf_lo(unsigned w) { return __uint_as_float(w << 16); }
; __device__ __forceinline__ float bf_hi(unsigned w) { return __uint_as_float(w & 0xffff0000u); }
; template <bool BF> __device__ __forceinline__ void prep_rows(const float* xp, const float* xs, const bf16* hb, const float* g, const float* MOD, int shoff, int scoff, bf16* U, int gw, int NGW, int lane) {
;     ...
;                 if (BF) { const v2u a0 = *(const v2u*)(hb + (size_t)mc * DM + 4 * lane + 256 * j);
;                     v[r][j].x = pg8::bf_lo(a0.x); v[r][j].y = pg8::bf_hi(a0.x); v[r][j].z = pg8::bf_lo(a0.y); v[r][j].w = pg8::bf_hi(a0.y); }
;                 else { const float* xr = mc < MP ? xp + (size_t)mc * DM : xs + (size_t)(mc - MP) * DM; v[r][j] = *(const f32x4*)(xr + 4 * lane + 256 * j); } } }
; #pragma unroll
;         for (int r = 0; r < R; ++r) { float t = 0.f;
; #pragma unroll
;             for (int j = 0; j < 4; ++j) t += (v[r][j].x * v[r][j].x + v[r][j].y * v[r][j].y) + (v[r][j].z * v[r][j].z + v[r][j].w * v[r][j].w);
;             s[r] = t; }
; #pragma unroll
;         for (int o = 1; o < 64; o <<= 1) {
; #pragma unroll
;             for (int r = 0; r < R; ++r) s[r] += __shfl_xor(s[r], o); }
; #pragma unroll
;         for (int r = 0; r < R; ++r) { const int m = mb + r * NGW; if (m < MT) {
;             const float rstd = 1.0f / sqrtf(s[r] * (1.0f / DM) + RMS_EPS);
	v_lshlrev_b32_e32 v50, 16, v121
	v_and_b32_e32 v51, 0xffff0000, v121
	v_lshlrev_b32_e32 v52, 16, v122
	v_and_b32_e32 v53, 0xffff0000, v122
	v_lshlrev_b32_e32 v54, 16, v123
	v_and_b32_e32 v55, 0xffff0000, v123
	v_lshlrev_b32_e32 v56, 16, v124
	v_and_b32_e32 v57, 0xffff0000, v124
	v_lshlrev_b32_e32 v58, 16, v125
	v_and_b32_e32 v59, 0xffff0000, v125
	v_lshlrev_b32_e32 v60, 16, v126
	v_and_b32_e32 v61, 0xffff0000, v126
	v_lshlrev_b32_e32 v62, 16, v127
	v_and_b32_e32 v63, 0xffff0000, v127
	v_pk_mul_f32 v[240:241], v[0:1], v[0:1]
	v_pk_mul_f32 v[242:243], v[16:17], v[16:17]
	v_pk_mul_f32 v[244:245], v[32:33], v[32:33]
	v_pk_mul_f32 v[246:247], v[48:49], v[48:49]
	v_pk_fma_f32 v[240:241], v[2:3], v[2:3], v[240:241]
	v_pk_fma_f32 v[242:243], v[18:19], v[18:19], v[242:243]
	v_pk_fma_f32 v[244:245], v[34:35], v[34:35], v[244:245]
	v_pk_fma_f32 v[246:247], v[50:51], v[50:51], v[246:247]
	v_pk_fma_f32 v[240:241], v[4:5], v[4:5], v[240:241]
	v_pk_fma_f32 v[242:243], v[20:21], v[20:21], v[242:243]
	v_pk_fma_f32 v[244:245], v[36:37], v[36:37], v[244:245]
	v_pk_fma_f32 v[246:247], v[52:53], v[52:53], v[246:247]
	v_pk_fma_f32 v[240:241], v[6:7], v[6:7], v[240:241]
	v_pk_fma_f32 v[242:243], v[22:23], v[22:23], v[242:243]
	v_pk_fma_f32 v[244:245], v[38:39], v[38:39], v[244:245]
	v_pk_fma_f32 v[246:247], v[54:55], v[54:55], v[246:247]
	v_pk_fma_f32 v[240:241], v[8:9], v[8:9], v[240:241]
	v_pk_fma_f32 v[242:243], v[24:25], v[24:25], v[242:243]
	v_pk_fma_f32 v[244:245], v[40:41], v[40:41], v[244:245]
	v_pk_fma_f32 v[246:247], v[56:57], v[56:57], v[246:247]
	v_pk_fma_f32 v[240:241], v[10:11], v[10:11], v[240:241]
	v_pk_fma_f32 v[242:243], v[26:27], v[26:27], v[242:243]
	v_pk_fma_f32 v[244:245], v[42:43], v[42:43], v[244:245]
	v_pk_fma_f32 v[246:247], v[58:59], v[58:59], v[246:247]
	v_pk_fma_f32 v[240:241], v[12:13], v[12:13], v[240:241]
	v_pk_fma_f32 v[242:243], v[28:29], v[28:29], v[242:243]
	v_pk_fma_f32 v[244:245], v[44:45], v[44:45], v[244:245]
	v_pk_fma_f32 v[246:247], v[60:61], v[60:61], v[246:247]
	v_pk_fma_f32 v[240:241], v[14:15], v[14:15], v[240:241]
	v_pk_fma_f32 v[242:243], v[30:31], v[30:31], v[242:243]
	v_pk_fma_f32 v[244:245], v[46:47], v[46:47], v[244:245]
	v_pk_fma_f32 v[246:247], v[62:63], v[62:63], v[246:247]
	v_add_f32_e32 v224, v240, v241
	v_add_f32_e32 v225, v242, v243
	v_add_f32_e32 v226, v244, v245
	v_add_f32_e32 v227, v246, v247
	ds_bpermute_b32 v228, v83, v224
	ds_bpermute_b32 v229, v83, v225
	ds_bpermute_b32 v230, v83, v226
	ds_bpermute_b32 v231, v83, v227
	s_waitcnt lgkmcnt(0)
	v_add_f32_e32 v224, v224, v228
	v_add_f32_e32 v225, v225, v229
	v_add_f32_e32 v226, v226, v230
	v_add_f32_e32 v227, v227, v231
	ds_bpermute_b32 v228, v84, v224
	ds_bpermute_b32 v229, v84, v225
	ds_bpermute_b32 v230, v84, v226
	ds_bpermute_b32 v231, v84, v227
	s_waitcnt lgkmcnt(0)
	v_add_f32_e32 v224, v224, v228
	v_add_f32_e32 v225, v225, v229
	v_add_f32_e32 v226, v226, v230
	v_add_f32_e32 v227, v227, v231
	ds_bpermute_b32 v228, v85, v224
	ds_bpermute_b32 v229, v85, v225
	ds_bpermute_b32 v230, v85, v226
	ds_bpermute_b32 v231, v85, v227
	s_waitcnt lgkmcnt(0)
	v_add_f32_e32 v224, v224, v228
	v_add_f32_e32 v225, v225, v229
	v_add_f32_e32 v226, v226, v230
	v_add_f32_e32 v227, v227, v231
	ds_bpermute_b32 v228, v86, v224
	ds_bpermute_b32 v229, v86, v225
	ds_bpermute_b32 v230, v86, v226
	ds_bpermute_b32 v231, v86, v227
	s_waitcnt lgkmcnt(0)
	v_add_f32_e32 v224, v224, v228
	v_add_f32_e32 v225, v225, v229
	v_add_f32_e32 v226, v226, v230
	v_add_f32_e32 v227, v227, v231
	ds_bpermute_b32 v228, v87, v224
	ds_bpermute_b32 v229, v87, v225
	ds_bpermute_b32 v230, v87, v226
	ds_bpermute_b32 v231, v87, v227
	s_waitcnt lgkmcnt(0)
	v_add_f32_e32 v224, v224, v228
	v_add_f32_e32 v225, v225, v229
	v_add_f32_e32 v226, v226, v230
	v_add_f32_e32 v227, v227, v231
	ds_bpermute_b32 v228, v88, v224
	ds_bpermute_b32 v229, v88, v225
	ds_bpermute_b32 v230, v88, v226
	ds_bpermute_b32 v231, v88, v227
	s_waitcnt lgkmcnt(0)
	v_add_f32_e32 v224, v224, v228
	v_add_f32_e32 v225, v225, v229
	v_add_f32_e32 v226, v226, v230
	v_add_f32_e32 v227, v227, v231
	v_fmamk_f32 v240, v224, 0x3a800000, v89
	v_mul_f32_e32 v241, 0x4f800000, v240
	v_cmp_gt_f32_e32 vcc, s54, v240
	s_nop 1
	v_cndmask_b32_e32 v247, v240, v241, vcc
	v_sqrt_f32_e32 v242, v247
	s_nop 1
	v_add_u32_e32 v243, -1, v242
	v_add_u32_e32 v244, 1, v242
	v_fma_f32 v245, -v243, v242, v247
	v_fma_f32 v246, -v244, v242, v247
	v_cmp_ge_f32_e64 s[52:53], 0, v245
	s_nop 1
	v_cndmask_b32_e64 v242, v242, v243, s[52:53]
	v_cmp_lt_f32_e64 s[52:53], 0, v246
	s_nop 1
	v_cndmask_b32_e64 v242, v242, v244, s[52:53]
	v_mul_f32_e32 v243, 0x37800000, v242
	v_cndmask_b32_e32 v242, v242, v243, vcc
	v_cmp_class_f32_e32 vcc, v247, v90
	s_nop 1
	v_cndmask_b32_e32 v247, v242, v247, vcc
	v_div_scale_f32 v248, s[52:53], v247, v247, 1.0
	v_rcp_f32_e32 v249, v248
	v_div_scale_f32 v228, vcc, 1.0, v247, 1.0
	s_nop 0
	v_fma_f32 v229, -v248, v249, 1.0
	v_fmac_f32_e32 v249, v229, v249
	v_mul_f32_e32 v230, v228, v249
	v_fma_f32 v229, -v248, v230, v228
	v_fmac_f32_e32 v230, v229, v249
	v_fma_f32 v248, -v248, v230, v228
	v_div_fmas_f32 v248, v248, v249, v230
	v_div_fixup_f32 v232, v248, v247, 1.0
	v_fmamk_f32 v240, v225, 0x3a800000, v89
	v_mul_f32_e32 v241, 0x4f800000, v240
	v_cmp_gt_f32_e32 vcc, s54, v240
	s_nop 1
	v_cndmask_b32_e32 v247, v240, v241, vcc
	v_sqrt_f32_e32 v242, v247
	s_nop 1
	v_add_u32_e32 v243, -1, v242
	v_add_u32_e32 v244, 1, v242
	v_fma_f32 v245, -v243, v242, v247
	v_fma_f32 v246, -v244, v242, v247
	v_cmp_ge_f32_e64 s[52:53], 0, v245
	s_nop 1
	v_cndmask_b32_e64 v242, v242, v243, s[52:53]
	v_cmp_lt_f32_e64 s[52:53], 0, v246
	s_nop 1
	v_cndmask_b32_e64 v242, v242, v244, s[52:53]
; __device__ __forceinline__ unsigned pk2(float lo, float hi) { return pg8::cvt_pk_bf16(lo, hi); }
; template <bool BF> __device__ __forceinline__ void prep_rows(const float* xp, const float* xs, const bf16* hb, const float* g, const float* MOD, int shoff, int scoff, bf16* U, int gw, int NGW, int lane) {
;     ...
;             const float rstd = 1.0f / sqrtf(s[r] * (1.0f / DM) + RMS_EPS);
;             const float* mr = MOD + (size_t)(m < MP ? (m >> 13) : 8 + ((m - MP) >> 12)) * 6144;
; #pragma unroll
;             for (int j = 0; j < 4; ++j) { const int c = 4 * lane + 256 * j;
;                 const f32x4 gg = *(const f32x4*)(g + c), sc = *(const f32x4*)(mr + scoff + c), sh = *(const f32x4*)(mr + shoff + c);
;                 const f32x4 o = v[r][j] * rstd * gg * (sc + 1.0f) + sh; v2u w; w.x = pk2(o.x, o.y); w.y = pk2(o.z, o.w); *(v2u*)(U + (size_t)m * DM + c) = w; } } }
	v_mul_f32_e32 v243, 0x37800000, v242
	v_cndmask_b32_e32 v242, v242, v243, vcc
	v_cmp_class_f32_e32 vcc, v247, v90
	s_nop 1
	v_cndmask_b32_e32 v247, v242, v247, vcc
	v_div_scale_f32 v248, s[52:53], v247, v247, 1.0
	v_rcp_f32_e32 v249, v248
	v_div_scale_f32 v228, vcc, 1.0, v247, 1.0
	s_nop 0
	v_fma_f32 v229, -v248, v249, 1.0
	v_fmac_f32_e32 v249, v229, v249
	v_mul_f32_e32 v230, v228, v249
	v_fma_f32 v229, -v248, v230, v228
	v_fmac_f32_e32 v230, v229, v249
	v_fma_f32 v248, -v248, v230, v228
	v_div_fmas_f32 v248, v248, v249, v230
	v_div_fixup_f32 v234, v248, v247, 1.0
	v_fmamk_f32 v240, v226, 0x3a800000, v89
	v_mul_f32_e32 v241, 0x4f800000, v240
	v_cmp_gt_f32_e32 vcc, s54, v240
	s_nop 1
	v_cndmask_b32_e32 v247, v240, v241, vcc
	v_sqrt_f32_e32 v242, v247
	s_nop 1
	v_add_u32_e32 v243, -1, v242
	v_add_u32_e32 v244, 1, v242
	v_fma_f32 v245, -v243, v242, v247
	v_fma_f32 v246, -v244, v242, v247
	v_cmp_ge_f32_e64 s[52:53], 0, v245
	s_nop 1
	v_cndmask_b32_e64 v242, v242, v243, s[52:53]
	v_cmp_lt_f32_e64 s[52:53], 0, v246
	s_nop 1
	v_cndmask_b32_e64 v242, v242, v244, s[52:53]
	v_mul_f32_e32 v243, 0x37800000, v242
	v_cndmask_b32_e32 v242, v242, v243, vcc
	v_cmp_class_f32_e32 vcc, v247, v90
	s_nop 1
	v_cndmask_b32_e32 v247, v242, v247, vcc
	v_div_scale_f32 v248, s[52:53], v247, v247, 1.0
	v_rcp_f32_e32 v249, v248
	v_div_scale_f32 v228, vcc, 1.0, v247, 1.0
	s_nop 0
	v_fma_f32 v229, -v248, v249, 1.0
	v_fmac_f32_e32 v249, v229, v249
	v_mul_f32_e32 v230, v228, v249
	v_fma_f32 v229, -v248, v230, v228
	v_fmac_f32_e32 v230, v229, v249
	v_fma_f32 v248, -v248, v230, v228
	v_div_fmas_f32 v248, v248, v249, v230
	v_div_fixup_f32 v236, v248, v247, 1.0
	v_fmamk_f32 v240, v227, 0x3a800000, v89
	v_mul_f32_e32 v241, 0x4f800000, v240
	v_cmp_gt_f32_e32 vcc, s54, v240
	s_nop 1
	v_cndmask_b32_e32 v247, v240, v241, vcc
	v_sqrt_f32_e32 v242, v247
	s_nop 1
	v_add_u32_e32 v243, -1, v242
	v_add_u32_e32 v244, 1, v242
	v_fma_f32 v245, -v243, v242, v247
	v_fma_f32 v246, -v244, v242, v247
	v_cmp_ge_f32_e64 s[52:53], 0, v245
	s_nop 1
	v_cndmask_b32_e64 v242, v242, v243, s[52:53]
	v_cmp_lt_f32_e64 s[52:53], 0, v246
	s_nop 1
	v_cndmask_b32_e64 v242, v242, v244, s[52:53]
	v_mul_f32_e32 v243, 0x37800000, v242
	v_cndmask_b32_e32 v242, v242, v243, vcc
	v_cmp_class_f32_e32 vcc, v247, v90
	s_nop 1
	v_cndmask_b32_e32 v247, v242, v247, vcc
	v_div_scale_f32 v248, s[52:53], v247, v247, 1.0
	v_rcp_f32_e32 v249, v248
	v_div_scale_f32 v228, vcc, 1.0, v247, 1.0
	s_nop 0
	v_fma_f32 v229, -v248, v249, 1.0
	v_fmac_f32_e32 v249, v229, v249
	v_mul_f32_e32 v230, v228, v249
	v_fma_f32 v229, -v248, v230, v228
	v_fmac_f32_e32 v230, v229, v249
	v_fma_f32 v248, -v248, v230, v228
	v_div_fmas_f32 v248, v248, v249, v230
	v_div_fixup_f32 v238, v248, v247, 1.0
	s_waitcnt vmcnt(8)
	v_pk_add_f32 v[160:161], v[160:161], 1.0 op_sel_hi:[1,0]
	v_pk_add_f32 v[162:163], v[162:163], 1.0 op_sel_hi:[1,0]
	v_pk_add_f32 v[164:165], v[164:165], 1.0 op_sel_hi:[1,0]
	v_pk_add_f32 v[166:167], v[166:167], 1.0 op_sel_hi:[1,0]
	v_pk_add_f32 v[168:169], v[168:169], 1.0 op_sel_hi:[1,0]
	v_pk_add_f32 v[170:171], v[170:171], 1.0 op_sel_hi:[1,0]
	v_pk_add_f32 v[172:173], v[172:173], 1.0 op_sel_hi:[1,0]
	v_pk_add_f32 v[174:175], v[174:175], 1.0 op_sel_hi:[1,0]
	v_pk_add_f32 v[192:193], v[192:193], 1.0 op_sel_hi:[1,0]
	v_pk_add_f32 v[194:195], v[194:195], 1.0 op_sel_hi:[1,0]
	v_pk_add_f32 v[196:197], v[196:197], 1.0 op_sel_hi:[1,0]
	v_pk_add_f32 v[198:199], v[198:199], 1.0 op_sel_hi:[1,0]
	v_pk_add_f32 v[200:201], v[200:201], 1.0 op_sel_hi:[1,0]
	v_pk_add_f32 v[202:203], v[202:203], 1.0 op_sel_hi:[1,0]
	v_pk_add_f32 v[204:205], v[204:205], 1.0 op_sel_hi:[1,0]
	v_pk_add_f32 v[206:207], v[206:207], 1.0 op_sel_hi:[1,0]
	s_add_u32 s38, s20, 0x6000000
	s_addc_u32 s39, s21, 0
	s_add_u32 s40, s20, 0x6400000
	s_addc_u32 s41, s21, 0
	s_add_u32 s46, s20, 0x6800000
	s_addc_u32 s47, s21, 0
	s_add_u32 s48, s20, 0x6c00000
	s_addc_u32 s49, s21, 0
	v_pk_mul_f32 v[0:1], v[0:1], v[232:233] op_sel_hi:[1,0]
	v_pk_mul_f32 v[2:3], v[2:3], v[232:233] op_sel_hi:[1,0]
	v_pk_mul_f32 v[0:1], v[64:65], v[0:1]
	v_pk_mul_f32 v[2:3], v[66:67], v[2:3]
	v_pk_fma_f32 v[0:1], v[160:161], v[0:1], v[176:177]
	v_pk_fma_f32 v[2:3], v[162:163], v[2:3], v[178:179]
	v_cvt_pk_bf16_f32 v244, v0, v1
	v_cvt_pk_bf16_f32 v245, v2, v3
	v_pk_mul_f32 v[4:5], v[4:5], v[232:233] op_sel_hi:[1,0]
	v_pk_mul_f32 v[6:7], v[6:7], v[232:233] op_sel_hi:[1,0]
	v_pk_mul_f32 v[4:5], v[68:69], v[4:5]
	v_pk_mul_f32 v[6:7], v[70:71], v[6:7]
	v_pk_fma_f32 v[4:5], v[164:165], v[4:5], v[180:181]
	v_pk_fma_f32 v[6:7], v[166:167], v[6:7], v[182:183]
	v_cvt_pk_bf16_f32 v246, v4, v5
	v_cvt_pk_bf16_f32 v247, v6, v7
	global_store_dwordx4 v82, v[244:247], s[38:39] offset:0
	v_pk_mul_f32 v[8:9], v[8:9], v[232:233] op_sel_hi:[1,0]
	v_pk_mul_f32 v[10:11], v[10:11], v[232:233] op_sel_hi:[1,0]
	v_pk_mul_f32 v[8:9], v[72:73], v[8:9]
	v_pk_mul_f32 v[10:11], v[74:75], v[10:11]
	v_pk_fma_f32 v[8:9], v[168:169], v[8:9], v[184:185]
	v_pk_fma_f32 v[10:11], v[170:171], v[10:11], v[186:187]
	v_cvt_pk_bf16_f32 v240, v8, v9
	v_cvt_pk_bf16_f32 v241, v10, v11
	v_pk_mul_f32 v[12:13], v[12:13], v[232:233] op_sel_hi:[1,0]
	v_pk_mul_f32 v[14:15], v[14:15], v[232:233] op_sel_hi:[1,0]
	v_pk_mul_f32 v[12:13], v[76:77], v[12:13]
	v_pk_mul_f32 v[14:15], v[78:79], v[14:15]
	v_pk_fma_f32 v[12:13], v[172:173], v[12:13], v[188:189]
	v_pk_fma_f32 v[14:15], v[174:175], v[14:15], v[190:191]
	v_cvt_pk_bf16_f32 v242, v12, v13
	v_cvt_pk_bf16_f32 v243, v14, v15
	global_store_dwordx4 v82, v[240:243], s[38:39] offset:1024
	v_pk_mul_f32 v[16:17], v[16:17], v[234:235] op_sel_hi:[1,0]
	v_pk_mul_f32 v[18:19], v[18:19], v[234:235] op_sel_hi:[1,0]
; __device__ __forceinline__ float bf_lo(unsigned w) { return __uint_as_float(w << 16); }
; __device__ __forceinline__ float bf_hi(unsigned w) { return __uint_as_float(w & 0xffff0000u); }
; __device__ __forceinline__ unsigned pk2(float lo, float hi) { return pg8::cvt_pk_bf16(lo, hi); }
; template <bool BF> __device__ __forceinline__ void prep_rows(const float* xp, const float* xs, const bf16* hb, const float* g, const float* MOD, int shoff, int scoff, bf16* U, int gw, int NGW, int lane) {
;     ...
;         for (int r = 0; r < R; ++r) { const int m = mb + r * NGW; const int mc = m < MT ? m : mb;
; #pragma unroll
;             for (int j = 0; j < 4; ++j) {
;                 if (BF) { const v2u a0 = *(const v2u*)(hb + (size_t)mc * DM + 4 * lane + 256 * j);
;                     v[r][j].x = pg8::bf_lo(a0.x); v[r][j].y = pg8::bf_hi(a0.x); v[r][j].z = pg8::bf_lo(a0.y); v[r][j].w = pg8::bf_hi(a0.y); }
;                 else { const float* xr = mc < MP ? xp + (size_t)mc * DM : xs + (size_t)(mc - MP) * DM; v[r][j] = *(const f32x4*)(xr + 4 * lane + 256 * j); } } }
;     ...
;             for (int j = 0; j < 4; ++j) { const int c = 4 * lane + 256 * j;
;                 const f32x4 gg = *(const f32x4*)(g + c), sc = *(const f32x4*)(mr + scoff + c), sh = *(const f32x4*)(mr + shoff + c);
;                 const f32x4 o = v[r][j] * rstd * gg * (sc + 1.0f) + sh; v2u w; w.x = pk2(o.x, o.y); w.y = pk2(o.z, o.w); *(v2u*)(U + (size_t)m * DM + c) = w; } } }
	v_pk_mul_f32 v[16:17], v[64:65], v[16:17]
	v_pk_mul_f32 v[18:19], v[66:67], v[18:19]
	v_pk_fma_f32 v[16:17], v[160:161], v[16:17], v[176:177]
	v_pk_fma_f32 v[18:19], v[162:163], v[18:19], v[178:179]
	v_cvt_pk_bf16_f32 v244, v16, v17
	v_cvt_pk_bf16_f32 v245, v18, v19
	v_pk_mul_f32 v[20:21], v[20:21], v[234:235] op_sel_hi:[1,0]
	v_pk_mul_f32 v[22:23], v[22:23], v[234:235] op_sel_hi:[1,0]
	v_pk_mul_f32 v[20:21], v[68:69], v[20:21]
	v_pk_mul_f32 v[22:23], v[70:71], v[22:23]
	v_pk_fma_f32 v[20:21], v[164:165], v[20:21], v[180:181]
	v_pk_fma_f32 v[22:23], v[166:167], v[22:23], v[182:183]
	v_cvt_pk_bf16_f32 v246, v20, v21
	v_cvt_pk_bf16_f32 v247, v22, v23
	global_store_dwordx4 v82, v[244:247], s[40:41] offset:0
	v_pk_mul_f32 v[24:25], v[24:25], v[234:235] op_sel_hi:[1,0]
	v_pk_mul_f32 v[26:27], v[26:27], v[234:235] op_sel_hi:[1,0]
	v_pk_mul_f32 v[24:25], v[72:73], v[24:25]
	v_pk_mul_f32 v[26:27], v[74:75], v[26:27]
	v_pk_fma_f32 v[24:25], v[168:169], v[24:25], v[184:185]
	v_pk_fma_f32 v[26:27], v[170:171], v[26:27], v[186:187]
	v_cvt_pk_bf16_f32 v240, v24, v25
	v_cvt_pk_bf16_f32 v241, v26, v27
	v_pk_mul_f32 v[28:29], v[28:29], v[234:235] op_sel_hi:[1,0]
	v_pk_mul_f32 v[30:31], v[30:31], v[234:235] op_sel_hi:[1,0]
	v_pk_mul_f32 v[28:29], v[76:77], v[28:29]
	v_pk_mul_f32 v[30:31], v[78:79], v[30:31]
	v_pk_fma_f32 v[28:29], v[172:173], v[28:29], v[188:189]
	v_pk_fma_f32 v[30:31], v[174:175], v[30:31], v[190:191]
	v_cvt_pk_bf16_f32 v242, v28, v29
	v_cvt_pk_bf16_f32 v243, v30, v31
	global_store_dwordx4 v82, v[240:243], s[40:41] offset:1024
	v_pk_mul_f32 v[32:33], v[32:33], v[236:237] op_sel_hi:[1,0]
	v_pk_mul_f32 v[34:35], v[34:35], v[236:237] op_sel_hi:[1,0]
	v_pk_mul_f32 v[32:33], v[64:65], v[32:33]
	v_pk_mul_f32 v[34:35], v[66:67], v[34:35]
	v_pk_fma_f32 v[32:33], v[192:193], v[32:33], v[208:209]
	v_pk_fma_f32 v[34:35], v[194:195], v[34:35], v[210:211]
	v_cvt_pk_bf16_f32 v244, v32, v33
	v_cvt_pk_bf16_f32 v245, v34, v35
	v_pk_mul_f32 v[36:37], v[36:37], v[236:237] op_sel_hi:[1,0]
	v_pk_mul_f32 v[38:39], v[38:39], v[236:237] op_sel_hi:[1,0]
	v_pk_mul_f32 v[36:37], v[68:69], v[36:37]
	v_pk_mul_f32 v[38:39], v[70:71], v[38:39]
	v_pk_fma_f32 v[36:37], v[196:197], v[36:37], v[212:213]
	v_pk_fma_f32 v[38:39], v[198:199], v[38:39], v[214:215]
	v_cvt_pk_bf16_f32 v246, v36, v37
	v_cvt_pk_bf16_f32 v247, v38, v39
	global_store_dwordx4 v82, v[244:247], s[46:47] offset:0
	v_pk_mul_f32 v[40:41], v[40:41], v[236:237] op_sel_hi:[1,0]
	v_pk_mul_f32 v[42:43], v[42:43], v[236:237] op_sel_hi:[1,0]
	v_pk_mul_f32 v[40:41], v[72:73], v[40:41]
	v_pk_mul_f32 v[42:43], v[74:75], v[42:43]
	v_pk_fma_f32 v[40:41], v[200:201], v[40:41], v[216:217]
	v_pk_fma_f32 v[42:43], v[202:203], v[42:43], v[218:219]
	v_cvt_pk_bf16_f32 v240, v40, v41
	v_cvt_pk_bf16_f32 v241, v42, v43
	v_pk_mul_f32 v[44:45], v[44:45], v[236:237] op_sel_hi:[1,0]
	v_pk_mul_f32 v[46:47], v[46:47], v[236:237] op_sel_hi:[1,0]
	v_pk_mul_f32 v[44:45], v[76:77], v[44:45]
	v_pk_mul_f32 v[46:47], v[78:79], v[46:47]
	v_pk_fma_f32 v[44:45], v[204:205], v[44:45], v[220:221]
	v_pk_fma_f32 v[46:47], v[206:207], v[46:47], v[222:223]
	v_cvt_pk_bf16_f32 v242, v44, v45
	v_cvt_pk_bf16_f32 v243, v46, v47
	global_store_dwordx4 v82, v[240:243], s[46:47] offset:1024
	v_pk_mul_f32 v[48:49], v[48:49], v[238:239] op_sel_hi:[1,0]
	v_pk_mul_f32 v[50:51], v[50:51], v[238:239] op_sel_hi:[1,0]
	v_pk_mul_f32 v[48:49], v[64:65], v[48:49]
	v_pk_mul_f32 v[50:51], v[66:67], v[50:51]
	v_pk_fma_f32 v[48:49], v[192:193], v[48:49], v[208:209]
	v_pk_fma_f32 v[50:51], v[194:195], v[50:51], v[210:211]
	v_cvt_pk_bf16_f32 v244, v48, v49
	v_cvt_pk_bf16_f32 v245, v50, v51
	v_pk_mul_f32 v[52:53], v[52:53], v[238:239] op_sel_hi:[1,0]
	v_pk_mul_f32 v[54:55], v[54:55], v[238:239] op_sel_hi:[1,0]
	v_pk_mul_f32 v[52:53], v[68:69], v[52:53]
	v_pk_mul_f32 v[54:55], v[70:71], v[54:55]
	v_pk_fma_f32 v[52:53], v[196:197], v[52:53], v[212:213]
	v_pk_fma_f32 v[54:55], v[198:199], v[54:55], v[214:215]
	v_cvt_pk_bf16_f32 v246, v52, v53
	v_cvt_pk_bf16_f32 v247, v54, v55
	global_store_dwordx4 v82, v[244:247], s[48:49] offset:0
	v_pk_mul_f32 v[56:57], v[56:57], v[238:239] op_sel_hi:[1,0]
	v_pk_mul_f32 v[58:59], v[58:59], v[238:239] op_sel_hi:[1,0]
	v_pk_mul_f32 v[56:57], v[72:73], v[56:57]
	v_pk_mul_f32 v[58:59], v[74:75], v[58:59]
	v_pk_fma_f32 v[56:57], v[200:201], v[56:57], v[216:217]
	v_pk_fma_f32 v[58:59], v[202:203], v[58:59], v[218:219]
	v_cvt_pk_bf16_f32 v240, v56, v57
	v_cvt_pk_bf16_f32 v241, v58, v59
	v_pk_mul_f32 v[60:61], v[60:61], v[238:239] op_sel_hi:[1,0]
	v_pk_mul_f32 v[62:63], v[62:63], v[238:239] op_sel_hi:[1,0]
	v_pk_mul_f32 v[60:61], v[76:77], v[60:61]
	v_pk_mul_f32 v[62:63], v[78:79], v[62:63]
	v_pk_fma_f32 v[60:61], v[204:205], v[60:61], v[220:221]
	v_pk_fma_f32 v[62:63], v[206:207], v[62:63], v[222:223]
	v_cvt_pk_bf16_f32 v242, v60, v61
	v_cvt_pk_bf16_f32 v243, v62, v63
	global_store_dwordx4 v82, v[240:243], s[48:49] offset:1024
	s_add_u32 s34, s8, 0x2d000
	s_addc_u32 s35, s9, 0
	s_add_u32 s36, s8, 0x2d000
	s_addc_u32 s37, s9, 0
	global_load_dwordx4 v[176:179], v80, s[34:35] offset:0
	global_load_dwordx4 v[180:183], v80, s[34:35] offset:16
	global_load_dwordx4 v[184:187], v80, s[34:35] offset:2048
	global_load_dwordx4 v[188:191], v80, s[34:35] offset:2064
	global_load_dwordx4 v[160:163], v81, s[34:35] offset:0
	global_load_dwordx4 v[164:167], v81, s[34:35] offset:16
	global_load_dwordx4 v[168:171], v81, s[34:35] offset:2048
	global_load_dwordx4 v[172:175], v81, s[34:35] offset:2064
	global_load_dwordx4 v[208:211], v80, s[36:37] offset:0
	global_load_dwordx4 v[212:215], v80, s[36:37] offset:16
	global_load_dwordx4 v[216:219], v80, s[36:37] offset:2048
	global_load_dwordx4 v[220:223], v80, s[36:37] offset:2064
	global_load_dwordx4 v[192:195], v81, s[36:37] offset:0
	global_load_dwordx4 v[196:199], v81, s[36:37] offset:16
	global_load_dwordx4 v[200:203], v81, s[36:37] offset:2048
	global_load_dwordx4 v[204:207], v81, s[36:37] offset:2064
	s_add_u32 s24, s16, 0x8000000
	s_addc_u32 s25, s17, 0
	s_add_u32 s26, s16, 0x8400000
	s_addc_u32 s27, s17, 0
	s_add_u32 s28, s16, 0x8800000
	s_addc_u32 s29, s17, 0
	s_add_u32 s30, s16, 0x8c00000
	s_addc_u32 s31, s17, 0
	global_load_dwordx4 v[96:99], v82, s[24:25] offset:0 nt
	global_load_dwordx4 v[100:103], v82, s[24:25] offset:1024 nt
	global_load_dwordx4 v[104:107], v82, s[26:27] offset:0 nt
	global_load_dwordx4 v[108:111], v82, s[26:27] offset:1024 nt
	global_load_dwordx4 v[112:115], v82, s[28:29] offset:0 nt
	global_load_dwordx4 v[116:119], v82, s[28:29] offset:1024 nt
	global_load_dwordx4 v[120:123], v82, s[30:31] offset:0 nt
	global_load_dwordx4 v[124:127], v82, s[30:31] offset:1024 nt
	s_waitcnt vmcnt(32)
; __device__ __forceinline__ float bf_lo(unsigned w) { return __uint_as_float(w << 16); }
; __device__ __forceinline__ float bf_hi(unsigned w) { return __uint_as_float(w & 0xffff0000u); }
; template <bool BF> __device__ __forceinline__ void prep_rows(const float* xp, const float* xs, const bf16* hb, const float* g, const float* MOD, int shoff, int scoff, bf16* U, int gw, int NGW, int lane) {
;     ...
;                 if (BF) { const v2u a0 = *(const v2u*)(hb + (size_t)mc * DM + 4 * lane + 256 * j);
;                     v[r][j].x = pg8::bf_lo(a0.x); v[r][j].y = pg8::bf_hi(a0.x); v[r][j].z = pg8::bf_lo(a0.y); v[r][j].w = pg8::bf_hi(a0.y); }
;                 else { const float* xr = mc < MP ? xp + (size_t)mc * DM : xs + (size_t)(mc - MP) * DM; v[r][j] = *(const f32x4*)(xr + 4 * lane + 256 * j); } } }
; #pragma unroll
;         for (int r = 0; r < R; ++r) { float t = 0.f;
; #pragma unroll
;             for (int j = 0; j < 4; ++j) t += (v[r][j].x * v[r][j].x + v[r][j].y * v[r][j].y) + (v[r][j].z * v[r][j].z + v[r][j].w * v[r][j].w);
;             s[r] = t; }
; #pragma unroll
;         for (int o = 1; o < 64; o <<= 1) {
; #pragma unroll
;             for (int r = 0; r < R; ++r) s[r] += __shfl_xor(s[r], o); }
	v_lshlrev_b32_e32 v0, 16, v128
	v_and_b32_e32 v1, 0xffff0000, v128
	v_lshlrev_b32_e32 v2, 16, v129
	v_and_b32_e32 v3, 0xffff0000, v129
	v_lshlrev_b32_e32 v4, 16, v130
	v_and_b32_e32 v5, 0xffff0000, v130
	v_lshlrev_b32_e32 v6, 16, v131
	v_and_b32_e32 v7, 0xffff0000, v131
	v_lshlrev_b32_e32 v8, 16, v132
	v_and_b32_e32 v9, 0xffff0000, v132
	v_lshlrev_b32_e32 v10, 16, v133
	v_and_b32_e32 v11, 0xffff0000, v133
	v_lshlrev_b32_e32 v12, 16, v134
	v_and_b32_e32 v13, 0xffff0000, v134
	v_lshlrev_b32_e32 v14, 16, v135
	v_and_b32_e32 v15, 0xffff0000, v135
	v_lshlrev_b32_e32 v16, 16, v136
	v_and_b32_e32 v17, 0xffff0000, v136
	v_lshlrev_b32_e32 v18, 16, v137
	v_and_b32_e32 v19, 0xffff0000, v137
	v_lshlrev_b32_e32 v20, 16, v138
	v_and_b32_e32 v21, 0xffff0000, v138
	v_lshlrev_b32_e32 v22, 16, v139
	v_and_b32_e32 v23, 0xffff0000, v139
	v_lshlrev_b32_e32 v24, 16, v140
	v_and_b32_e32 v25, 0xffff0000, v140
	v_lshlrev_b32_e32 v26, 16, v141
	v_and_b32_e32 v27, 0xffff0000, v141
	v_lshlrev_b32_e32 v28, 16, v142
	v_and_b32_e32 v29, 0xffff0000, v142
	v_lshlrev_b32_e32 v30, 16, v143
	v_and_b32_e32 v31, 0xffff0000, v143
	v_lshlrev_b32_e32 v32, 16, v144
	v_and_b32_e32 v33, 0xffff0000, v144
	v_lshlrev_b32_e32 v34, 16, v145
	v_and_b32_e32 v35, 0xffff0000, v145
	v_lshlrev_b32_e32 v36, 16, v146
	v_and_b32_e32 v37, 0xffff0000, v146
	v_lshlrev_b32_e32 v38, 16, v147
	v_and_b32_e32 v39, 0xffff0000, v147
	v_lshlrev_b32_e32 v40, 16, v148
	v_and_b32_e32 v41, 0xffff0000, v148
	v_lshlrev_b32_e32 v42, 16, v149
	v_and_b32_e32 v43, 0xffff0000, v149
	v_lshlrev_b32_e32 v44, 16, v150
	v_and_b32_e32 v45, 0xffff0000, v150
	v_lshlrev_b32_e32 v46, 16, v151
	v_and_b32_e32 v47, 0xffff0000, v151
	v_lshlrev_b32_e32 v48, 16, v152
	v_and_b32_e32 v49, 0xffff0000, v152
	v_lshlrev_b32_e32 v50, 16, v153
	v_and_b32_e32 v51, 0xffff0000, v153
	v_lshlrev_b32_e32 v52, 16, v154
	v_and_b32_e32 v53, 0xffff0000, v154
	v_lshlrev_b32_e32 v54, 16, v155
	v_and_b32_e32 v55, 0xffff0000, v155
	v_lshlrev_b32_e32 v56, 16, v156
	v_and_b32_e32 v57, 0xffff0000, v156
	v_lshlrev_b32_e32 v58, 16, v157
	v_and_b32_e32 v59, 0xffff0000, v157
	v_lshlrev_b32_e32 v60, 16, v158
	v_and_b32_e32 v61, 0xffff0000, v158
	v_lshlrev_b32_e32 v62, 16, v159
	v_and_b32_e32 v63, 0xffff0000, v159
	v_pk_mul_f32 v[240:241], v[0:1], v[0:1]
	v_pk_mul_f32 v[242:243], v[16:17], v[16:17]
	v_pk_mul_f32 v[244:245], v[32:33], v[32:33]
	v_pk_mul_f32 v[246:247], v[48:49], v[48:49]
	v_pk_fma_f32 v[240:241], v[2:3], v[2:3], v[240:241]
	v_pk_fma_f32 v[242:243], v[18:19], v[18:19], v[242:243]
	v_pk_fma_f32 v[244:245], v[34:35], v[34:35], v[244:245]
	v_pk_fma_f32 v[246:247], v[50:51], v[50:51], v[246:247]
	v_pk_fma_f32 v[240:241], v[4:5], v[4:5], v[240:241]
	v_pk_fma_f32 v[242:243], v[20:21], v[20:21], v[242:243]
	v_pk_fma_f32 v[244:245], v[36:37], v[36:37], v[244:245]
	v_pk_fma_f32 v[246:247], v[52:53], v[52:53], v[246:247]
	v_pk_fma_f32 v[240:241], v[6:7], v[6:7], v[240:241]
	v_pk_fma_f32 v[242:243], v[22:23], v[22:23], v[242:243]
	v_pk_fma_f32 v[244:245], v[38:39], v[38:39], v[244:245]
	v_pk_fma_f32 v[246:247], v[54:55], v[54:55], v[246:247]
	v_pk_fma_f32 v[240:241], v[8:9], v[8:9], v[240:241]
	v_pk_fma_f32 v[242:243], v[24:25], v[24:25], v[242:243]
	v_pk_fma_f32 v[244:245], v[40:41], v[40:41], v[244:245]
	v_pk_fma_f32 v[246:247], v[56:57], v[56:57], v[246:247]
	v_pk_fma_f32 v[240:241], v[10:11], v[10:11], v[240:241]
	v_pk_fma_f32 v[242:243], v[26:27], v[26:27], v[242:243]
	v_pk_fma_f32 v[244:245], v[42:43], v[42:43], v[244:245]
	v_pk_fma_f32 v[246:247], v[58:59], v[58:59], v[246:247]
	v_pk_fma_f32 v[240:241], v[12:13], v[12:13], v[240:241]
	v_pk_fma_f32 v[242:243], v[28:29], v[28:29], v[242:243]
	v_pk_fma_f32 v[244:245], v[44:45], v[44:45], v[244:245]
	v_pk_fma_f32 v[246:247], v[60:61], v[60:61], v[246:247]
	v_pk_fma_f32 v[240:241], v[14:15], v[14:15], v[240:241]
	v_pk_fma_f32 v[242:243], v[30:31], v[30:31], v[242:243]
	v_pk_fma_f32 v[244:245], v[46:47], v[46:47], v[244:245]
	v_pk_fma_f32 v[246:247], v[62:63], v[62:63], v[246:247]
	v_add_f32_e32 v224, v240, v241
	v_add_f32_e32 v225, v242, v243
	v_add_f32_e32 v226, v244, v245
	v_add_f32_e32 v227, v246, v247
	ds_bpermute_b32 v228, v83, v224
	ds_bpermute_b32 v229, v83, v225
	ds_bpermute_b32 v230, v83, v226
	ds_bpermute_b32 v231, v83, v227
	s_waitcnt lgkmcnt(0)
	v_add_f32_e32 v224, v224, v228
	v_add_f32_e32 v225, v225, v229
	v_add_f32_e32 v226, v226, v230
	v_add_f32_e32 v227, v227, v231
	ds_bpermute_b32 v228, v84, v224
	ds_bpermute_b32 v229, v84, v225
	ds_bpermute_b32 v230, v84, v226
	ds_bpermute_b32 v231, v84, v227
	s_waitcnt lgkmcnt(0)
	v_add_f32_e32 v224, v224, v228
	v_add_f32_e32 v225, v225, v229
	v_add_f32_e32 v226, v226, v230
	v_add_f32_e32 v227, v227, v231
	ds_bpermute_b32 v228, v85, v224
	ds_bpermute_b32 v229, v85, v225
	ds_bpermute_b32 v230, v85, v226
	ds_bpermute_b32 v231, v85, v227
	s_waitcnt lgkmcnt(0)
	v_add_f32_e32 v224, v224, v228
	v_add_f32_e32 v225, v225, v229
	v_add_f32_e32 v226, v226, v230
	v_add_f32_e32 v227, v227, v231
	ds_bpermute_b32 v228, v86, v224
	ds_bpermute_b32 v229, v86, v225
	ds_bpermute_b32 v230, v86, v226
	ds_bpermute_b32 v231, v86, v227
	s_waitcnt lgkmcnt(0)
	v_add_f32_e32 v224, v224, v228
	v_add_f32_e32 v225, v225, v229
	v_add_f32_e32 v226, v226, v230
	v_add_f32_e32 v227, v227, v231
	ds_bpermute_b32 v228, v87, v224
	ds_bpermute_b32 v229, v87, v225
	ds_bpermute_b32 v230, v87, v226
	ds_bpermute_b32 v231, v87, v227
	s_waitcnt lgkmcnt(0)
	v_add_f32_e32 v224, v224, v228
	v_add_f32_e32 v225, v225, v229
	v_add_f32_e32 v226, v226, v230
	v_add_f32_e32 v227, v227, v231
	ds_bpermute_b32 v228, v88, v224
	ds_bpermute_b32 v229, v88, v225
	ds_bpermute_b32 v230, v88, v226
	ds_bpermute_b32 v231, v88, v227
	s_waitcnt lgkmcnt(0)
; template <bool BF> __device__ __forceinline__ void prep_rows(const float* xp, const float* xs, const bf16* hb, const float* g, const float* MOD, int shoff, int scoff, bf16* U, int gw, int NGW, int lane) {
;     ...
;             for (int r = 0; r < R; ++r) s[r] += __shfl_xor(s[r], o); }
; #pragma unroll
;         for (int r = 0; r < R; ++r) { const int m = mb + r * NGW; if (m < MT) {
;             const float rstd = 1.0f / sqrtf(s[r] * (1.0f / DM) + RMS_EPS);
	v_add_f32_e32 v224, v224, v228
	v_add_f32_e32 v225, v225, v229
	v_add_f32_e32 v226, v226, v230
	v_add_f32_e32 v227, v227, v231
	v_fmamk_f32 v240, v224, 0x3a800000, v89
	v_mul_f32_e32 v241, 0x4f800000, v240
	v_cmp_gt_f32_e32 vcc, s54, v240
	s_nop 1
	v_cndmask_b32_e32 v247, v240, v241, vcc
	v_sqrt_f32_e32 v242, v247
	s_nop 1
	v_add_u32_e32 v243, -1, v242
	v_add_u32_e32 v244, 1, v242
	v_fma_f32 v245, -v243, v242, v247
	v_fma_f32 v246, -v244, v242, v247
	v_cmp_ge_f32_e64 s[52:53], 0, v245
	s_nop 1
	v_cndmask_b32_e64 v242, v242, v243, s[52:53]
	v_cmp_lt_f32_e64 s[52:53], 0, v246
	s_nop 1
	v_cndmask_b32_e64 v242, v242, v244, s[52:53]
	v_mul_f32_e32 v243, 0x37800000, v242
	v_cndmask_b32_e32 v242, v242, v243, vcc
	v_cmp_class_f32_e32 vcc, v247, v90
	s_nop 1
	v_cndmask_b32_e32 v247, v242, v247, vcc
	v_div_scale_f32 v248, s[52:53], v247, v247, 1.0
	v_rcp_f32_e32 v249, v248
	v_div_scale_f32 v228, vcc, 1.0, v247, 1.0
	s_nop 0
	v_fma_f32 v229, -v248, v249, 1.0
	v_fmac_f32_e32 v249, v229, v249
	v_mul_f32_e32 v230, v228, v249
	v_fma_f32 v229, -v248, v230, v228
	v_fmac_f32_e32 v230, v229, v249
	v_fma_f32 v248, -v248, v230, v228
	v_div_fmas_f32 v248, v248, v249, v230
	v_div_fixup_f32 v232, v248, v247, 1.0
	v_fmamk_f32 v240, v225, 0x3a800000, v89
	v_mul_f32_e32 v241, 0x4f800000, v240
	v_cmp_gt_f32_e32 vcc, s54, v240
	s_nop 1
	v_cndmask_b32_e32 v247, v240, v241, vcc
	v_sqrt_f32_e32 v242, v247
	s_nop 1
	v_add_u32_e32 v243, -1, v242
	v_add_u32_e32 v244, 1, v242
	v_fma_f32 v245, -v243, v242, v247
	v_fma_f32 v246, -v244, v242, v247
	v_cmp_ge_f32_e64 s[52:53], 0, v245
	s_nop 1
	v_cndmask_b32_e64 v242, v242, v243, s[52:53]
	v_cmp_lt_f32_e64 s[52:53], 0, v246
	s_nop 1
	v_cndmask_b32_e64 v242, v242, v244, s[52:53]
	v_mul_f32_e32 v243, 0x37800000, v242
	v_cndmask_b32_e32 v242, v242, v243, vcc
	v_cmp_class_f32_e32 vcc, v247, v90
	s_nop 1
	v_cndmask_b32_e32 v247, v242, v247, vcc
	v_div_scale_f32 v248, s[52:53], v247, v247, 1.0
	v_rcp_f32_e32 v249, v248
	v_div_scale_f32 v228, vcc, 1.0, v247, 1.0
	s_nop 0
	v_fma_f32 v229, -v248, v249, 1.0
	v_fmac_f32_e32 v249, v229, v249
	v_mul_f32_e32 v230, v228, v249
	v_fma_f32 v229, -v248, v230, v228
	v_fmac_f32_e32 v230, v229, v249
	v_fma_f32 v248, -v248, v230, v228
	v_div_fmas_f32 v248, v248, v249, v230
	v_div_fixup_f32 v234, v248, v247, 1.0
	v_fmamk_f32 v240, v226, 0x3a800000, v89
	v_mul_f32_e32 v241, 0x4f800000, v240
	v_cmp_gt_f32_e32 vcc, s54, v240
	s_nop 1
	v_cndmask_b32_e32 v247, v240, v241, vcc
	v_sqrt_f32_e32 v242, v247
	s_nop 1
	v_add_u32_e32 v243, -1, v242
	v_add_u32_e32 v244, 1, v242
	v_fma_f32 v245, -v243, v242, v247
	v_fma_f32 v246, -v244, v242, v247
	v_cmp_ge_f32_e64 s[52:53], 0, v245
	s_nop 1
	v_cndmask_b32_e64 v242, v242, v243, s[52:53]
	v_cmp_lt_f32_e64 s[52:53], 0, v246
	s_nop 1
	v_cndmask_b32_e64 v242, v242, v244, s[52:53]
	v_mul_f32_e32 v243, 0x37800000, v242
	v_cndmask_b32_e32 v242, v242, v243, vcc
	v_cmp_class_f32_e32 vcc, v247, v90
	s_nop 1
	v_cndmask_b32_e32 v247, v242, v247, vcc
	v_div_scale_f32 v248, s[52:53], v247, v247, 1.0
	v_rcp_f32_e32 v249, v248
	v_div_scale_f32 v228, vcc, 1.0, v247, 1.0
	s_nop 0
	v_fma_f32 v229, -v248, v249, 1.0
	v_fmac_f32_e32 v249, v229, v249
	v_mul_f32_e32 v230, v228, v249
	v_fma_f32 v229, -v248, v230, v228
	v_fmac_f32_e32 v230, v229, v249
	v_fma_f32 v248, -v248, v230, v228
	v_div_fmas_f32 v248, v248, v249, v230
	v_div_fixup_f32 v236, v248, v247, 1.0
	v_fmamk_f32 v240, v227, 0x3a800000, v89
	v_mul_f32_e32 v241, 0x4f800000, v240
	v_cmp_gt_f32_e32 vcc, s54, v240
	s_nop 1
	v_cndmask_b32_e32 v247, v240, v241, vcc
	v_sqrt_f32_e32 v242, v247
	s_nop 1
	v_add_u32_e32 v243, -1, v242
	v_add_u32_e32 v244, 1, v242
	v_fma_f32 v245, -v243, v242, v247
	v_fma_f32 v246, -v244, v242, v247
	v_cmp_ge_f32_e64 s[52:53], 0, v245
	s_nop 1
	v_cndmask_b32_e64 v242, v242, v243, s[52:53]
	v_cmp_lt_f32_e64 s[52:53], 0, v246
	s_nop 1
	v_cndmask_b32_e64 v242, v242, v244, s[52:53]
	v_mul_f32_e32 v243, 0x37800000, v242
	v_cndmask_b32_e32 v242, v242, v243, vcc
	v_cmp_class_f32_e32 vcc, v247, v90
	s_nop 1
	v_cndmask_b32_e32 v247, v242, v247, vcc
	v_div_scale_f32 v248, s[52:53], v247, v247, 1.0
	v_rcp_f32_e32 v249, v248
	v_div_scale_f32 v228, vcc, 1.0, v247, 1.0
	s_nop 0
	v_fma_f32 v229, -v248, v249, 1.0
	v_fmac_f32_e32 v249, v229, v249
	v_mul_f32_e32 v230, v228, v249
	v_fma_f32 v229, -v248, v230, v228
	v_fmac_f32_e32 v230, v229, v249
	v_fma_f32 v248, -v248, v230, v228
	v_div_fmas_f32 v248, v248, v249, v230
	v_div_fixup_f32 v238, v248, v247, 1.0
	s_waitcnt vmcnt(8)
; __device__ __forceinline__ unsigned pk2(float lo, float hi) { return pg8::cvt_pk_bf16(lo, hi); }
; template <bool BF> __device__ __forceinline__ void prep_rows(const float* xp, const float* xs, const bf16* hb, const float* g, const float* MOD, int shoff, int scoff, bf16* U, int gw, int NGW, int lane) {
;     ...
;             const float* mr = MOD + (size_t)(m < MP ? (m >> 13) : 8 + ((m - MP) >> 12)) * 6144;
; #pragma unroll
;             for (int j = 0; j < 4; ++j) { const int c = 4 * lane + 256 * j;
;                 const f32x4 gg = *(const f32x4*)(g + c), sc = *(const f32x4*)(mr + scoff + c), sh = *(const f32x4*)(mr + shoff + c);
;                 const f32x4 o = v[r][j] * rstd * gg * (sc + 1.0f) + sh; v2u w; w.x = pk2(o.x, o.y); w.y = pk2(o.z, o.w); *(v2u*)(U + (size_t)m * DM + c) = w; } } }
	v_pk_add_f32 v[160:161], v[160:161], 1.0 op_sel_hi:[1,0]
	v_pk_add_f32 v[162:163], v[162:163], 1.0 op_sel_hi:[1,0]
	v_pk_add_f32 v[164:165], v[164:165], 1.0 op_sel_hi:[1,0]
	v_pk_add_f32 v[166:167], v[166:167], 1.0 op_sel_hi:[1,0]
	v_pk_add_f32 v[168:169], v[168:169], 1.0 op_sel_hi:[1,0]
	v_pk_add_f32 v[170:171], v[170:171], 1.0 op_sel_hi:[1,0]
	v_pk_add_f32 v[172:173], v[172:173], 1.0 op_sel_hi:[1,0]
	v_pk_add_f32 v[174:175], v[174:175], 1.0 op_sel_hi:[1,0]
	v_pk_add_f32 v[192:193], v[192:193], 1.0 op_sel_hi:[1,0]
	v_pk_add_f32 v[194:195], v[194:195], 1.0 op_sel_hi:[1,0]
	v_pk_add_f32 v[196:197], v[196:197], 1.0 op_sel_hi:[1,0]
	v_pk_add_f32 v[198:199], v[198:199], 1.0 op_sel_hi:[1,0]
	v_pk_add_f32 v[200:201], v[200:201], 1.0 op_sel_hi:[1,0]
	v_pk_add_f32 v[202:203], v[202:203], 1.0 op_sel_hi:[1,0]
	v_pk_add_f32 v[204:205], v[204:205], 1.0 op_sel_hi:[1,0]
	v_pk_add_f32 v[206:207], v[206:207], 1.0 op_sel_hi:[1,0]
	s_add_u32 s38, s20, 0x7000000
	s_addc_u32 s39, s21, 0
	s_add_u32 s40, s20, 0x7400000
	s_addc_u32 s41, s21, 0
	s_add_u32 s46, s20, 0x7800000
	s_addc_u32 s47, s21, 0
	s_add_u32 s48, s20, 0x7c00000
	s_addc_u32 s49, s21, 0
	v_pk_mul_f32 v[0:1], v[0:1], v[232:233] op_sel_hi:[1,0]
	v_pk_mul_f32 v[2:3], v[2:3], v[232:233] op_sel_hi:[1,0]
	v_pk_mul_f32 v[0:1], v[64:65], v[0:1]
	v_pk_mul_f32 v[2:3], v[66:67], v[2:3]
	v_pk_fma_f32 v[0:1], v[160:161], v[0:1], v[176:177]
	v_pk_fma_f32 v[2:3], v[162:163], v[2:3], v[178:179]
	v_cvt_pk_bf16_f32 v244, v0, v1
	v_cvt_pk_bf16_f32 v245, v2, v3
	v_pk_mul_f32 v[4:5], v[4:5], v[232:233] op_sel_hi:[1,0]
	v_pk_mul_f32 v[6:7], v[6:7], v[232:233] op_sel_hi:[1,0]
	v_pk_mul_f32 v[4:5], v[68:69], v[4:5]
	v_pk_mul_f32 v[6:7], v[70:71], v[6:7]
	v_pk_fma_f32 v[4:5], v[164:165], v[4:5], v[180:181]
	v_pk_fma_f32 v[6:7], v[166:167], v[6:7], v[182:183]
	v_cvt_pk_bf16_f32 v246, v4, v5
	v_cvt_pk_bf16_f32 v247, v6, v7
	global_store_dwordx4 v82, v[244:247], s[38:39] offset:0
	v_pk_mul_f32 v[8:9], v[8:9], v[232:233] op_sel_hi:[1,0]
	v_pk_mul_f32 v[10:11], v[10:11], v[232:233] op_sel_hi:[1,0]
	v_pk_mul_f32 v[8:9], v[72:73], v[8:9]
	v_pk_mul_f32 v[10:11], v[74:75], v[10:11]
	v_pk_fma_f32 v[8:9], v[168:169], v[8:9], v[184:185]
	v_pk_fma_f32 v[10:11], v[170:171], v[10:11], v[186:187]
	v_cvt_pk_bf16_f32 v240, v8, v9
	v_cvt_pk_bf16_f32 v241, v10, v11
	v_pk_mul_f32 v[12:13], v[12:13], v[232:233] op_sel_hi:[1,0]
	v_pk_mul_f32 v[14:15], v[14:15], v[232:233] op_sel_hi:[1,0]
	v_pk_mul_f32 v[12:13], v[76:77], v[12:13]
	v_pk_mul_f32 v[14:15], v[78:79], v[14:15]
	v_pk_fma_f32 v[12:13], v[172:173], v[12:13], v[188:189]
	v_pk_fma_f32 v[14:15], v[174:175], v[14:15], v[190:191]
	v_cvt_pk_bf16_f32 v242, v12, v13
	v_cvt_pk_bf16_f32 v243, v14, v15
	global_store_dwordx4 v82, v[240:243], s[38:39] offset:1024
	v_pk_mul_f32 v[16:17], v[16:17], v[234:235] op_sel_hi:[1,0]
	v_pk_mul_f32 v[18:19], v[18:19], v[234:235] op_sel_hi:[1,0]
	v_pk_mul_f32 v[16:17], v[64:65], v[16:17]
	v_pk_mul_f32 v[18:19], v[66:67], v[18:19]
	v_pk_fma_f32 v[16:17], v[160:161], v[16:17], v[176:177]
	v_pk_fma_f32 v[18:19], v[162:163], v[18:19], v[178:179]
	v_cvt_pk_bf16_f32 v244, v16, v17
	v_cvt_pk_bf16_f32 v245, v18, v19
	v_pk_mul_f32 v[20:21], v[20:21], v[234:235] op_sel_hi:[1,0]
	v_pk_mul_f32 v[22:23], v[22:23], v[234:235] op_sel_hi:[1,0]
	v_pk_mul_f32 v[20:21], v[68:69], v[20:21]
	v_pk_mul_f32 v[22:23], v[70:71], v[22:23]
	v_pk_fma_f32 v[20:21], v[164:165], v[20:21], v[180:181]
	v_pk_fma_f32 v[22:23], v[166:167], v[22:23], v[182:183]
	v_cvt_pk_bf16_f32 v246, v20, v21
	v_cvt_pk_bf16_f32 v247, v22, v23
	global_store_dwordx4 v82, v[244:247], s[40:41] offset:0
	v_pk_mul_f32 v[24:25], v[24:25], v[234:235] op_sel_hi:[1,0]
	v_pk_mul_f32 v[26:27], v[26:27], v[234:235] op_sel_hi:[1,0]
	v_pk_mul_f32 v[24:25], v[72:73], v[24:25]
	v_pk_mul_f32 v[26:27], v[74:75], v[26:27]
	v_pk_fma_f32 v[24:25], v[168:169], v[24:25], v[184:185]
	v_pk_fma_f32 v[26:27], v[170:171], v[26:27], v[186:187]
	v_cvt_pk_bf16_f32 v240, v24, v25
	v_cvt_pk_bf16_f32 v241, v26, v27
	v_pk_mul_f32 v[28:29], v[28:29], v[234:235] op_sel_hi:[1,0]
	v_pk_mul_f32 v[30:31], v[30:31], v[234:235] op_sel_hi:[1,0]
	v_pk_mul_f32 v[28:29], v[76:77], v[28:29]
	v_pk_mul_f32 v[30:31], v[78:79], v[30:31]
	v_pk_fma_f32 v[28:29], v[172:173], v[28:29], v[188:189]
	v_pk_fma_f32 v[30:31], v[174:175], v[30:31], v[190:191]
	v_cvt_pk_bf16_f32 v242, v28, v29
	v_cvt_pk_bf16_f32 v243, v30, v31
	global_store_dwordx4 v82, v[240:243], s[40:41] offset:1024
	v_pk_mul_f32 v[32:33], v[32:33], v[236:237] op_sel_hi:[1,0]
	v_pk_mul_f32 v[34:35], v[34:35], v[236:237] op_sel_hi:[1,0]
	v_pk_mul_f32 v[32:33], v[64:65], v[32:33]
	v_pk_mul_f32 v[34:35], v[66:67], v[34:35]
	v_pk_fma_f32 v[32:33], v[192:193], v[32:33], v[208:209]
	v_pk_fma_f32 v[34:35], v[194:195], v[34:35], v[210:211]
	v_cvt_pk_bf16_f32 v244, v32, v33
	v_cvt_pk_bf16_f32 v245, v34, v35
	v_pk_mul_f32 v[36:37], v[36:37], v[236:237] op_sel_hi:[1,0]
	v_pk_mul_f32 v[38:39], v[38:39], v[236:237] op_sel_hi:[1,0]
	v_pk_mul_f32 v[36:37], v[68:69], v[36:37]
	v_pk_mul_f32 v[38:39], v[70:71], v[38:39]
	v_pk_fma_f32 v[36:37], v[196:197], v[36:37], v[212:213]
	v_pk_fma_f32 v[38:39], v[198:199], v[38:39], v[214:215]
	v_cvt_pk_bf16_f32 v246, v36, v37
	v_cvt_pk_bf16_f32 v247, v38, v39
	global_store_dwordx4 v82, v[244:247], s[46:47] offset:0
	v_pk_mul_f32 v[40:41], v[40:41], v[236:237] op_sel_hi:[1,0]
	v_pk_mul_f32 v[42:43], v[42:43], v[236:237] op_sel_hi:[1,0]
	v_pk_mul_f32 v[40:41], v[72:73], v[40:41]
	v_pk_mul_f32 v[42:43], v[74:75], v[42:43]
	v_pk_fma_f32 v[40:41], v[200:201], v[40:41], v[216:217]
	v_pk_fma_f32 v[42:43], v[202:203], v[42:43], v[218:219]
	v_cvt_pk_bf16_f32 v240, v40, v41
; __device__ __forceinline__ float bf_lo(unsigned w) { return __uint_as_float(w << 16); }
; __device__ __forceinline__ float bf_hi(unsigned w) { return __uint_as_float(w & 0xffff0000u); }
; __device__ __forceinline__ unsigned pk2(float lo, float hi) { return pg8::cvt_pk_bf16(lo, hi); }
; template <bool BF> __device__ __forceinline__ void prep_rows(const float* xp, const float* xs, const bf16* hb, const float* g, const float* MOD, int shoff, int scoff, bf16* U, int gw, int NGW, int lane) {
;     ...
;         for (int r = 0; r < R; ++r) { const int m = mb + r * NGW; const int mc = m < MT ? m : mb;
; #pragma unroll
;             for (int j = 0; j < 4; ++j) {
;                 if (BF) { const v2u a0 = *(const v2u*)(hb + (size_t)mc * DM + 4 * lane + 256 * j);
;                     v[r][j].x = pg8::bf_lo(a0.x); v[r][j].y = pg8::bf_hi(a0.x); v[r][j].z = pg8::bf_lo(a0.y); v[r][j].w = pg8::bf_hi(a0.y); }
;     ...
;             for (int j = 0; j < 4; ++j) { const int c = 4 * lane + 256 * j;
;                 const f32x4 gg = *(const f32x4*)(g + c), sc = *(const f32x4*)(mr + scoff + c), sh = *(const f32x4*)(mr + shoff + c);
;                 const f32x4 o = v[r][j] * rstd * gg * (sc + 1.0f) + sh; v2u w; w.x = pk2(o.x, o.y); w.y = pk2(o.z, o.w); *(v2u*)(U + (size_t)m * DM + c) = w; } } }
	v_cvt_pk_bf16_f32 v241, v42, v43
	v_pk_mul_f32 v[44:45], v[44:45], v[236:237] op_sel_hi:[1,0]
	v_pk_mul_f32 v[46:47], v[46:47], v[236:237] op_sel_hi:[1,0]
	v_pk_mul_f32 v[44:45], v[76:77], v[44:45]
	v_pk_mul_f32 v[46:47], v[78:79], v[46:47]
	v_pk_fma_f32 v[44:45], v[204:205], v[44:45], v[220:221]
	v_pk_fma_f32 v[46:47], v[206:207], v[46:47], v[222:223]
	v_cvt_pk_bf16_f32 v242, v44, v45
	v_cvt_pk_bf16_f32 v243, v46, v47
	global_store_dwordx4 v82, v[240:243], s[46:47] offset:1024
	v_pk_mul_f32 v[48:49], v[48:49], v[238:239] op_sel_hi:[1,0]
	v_pk_mul_f32 v[50:51], v[50:51], v[238:239] op_sel_hi:[1,0]
	v_pk_mul_f32 v[48:49], v[64:65], v[48:49]
	v_pk_mul_f32 v[50:51], v[66:67], v[50:51]
	v_pk_fma_f32 v[48:49], v[192:193], v[48:49], v[208:209]
	v_pk_fma_f32 v[50:51], v[194:195], v[50:51], v[210:211]
	v_cvt_pk_bf16_f32 v244, v48, v49
	v_cvt_pk_bf16_f32 v245, v50, v51
	v_pk_mul_f32 v[52:53], v[52:53], v[238:239] op_sel_hi:[1,0]
	v_pk_mul_f32 v[54:55], v[54:55], v[238:239] op_sel_hi:[1,0]
	v_pk_mul_f32 v[52:53], v[68:69], v[52:53]
	v_pk_mul_f32 v[54:55], v[70:71], v[54:55]
	v_pk_fma_f32 v[52:53], v[196:197], v[52:53], v[212:213]
	v_pk_fma_f32 v[54:55], v[198:199], v[54:55], v[214:215]
	v_cvt_pk_bf16_f32 v246, v52, v53
	v_cvt_pk_bf16_f32 v247, v54, v55
	global_store_dwordx4 v82, v[244:247], s[48:49] offset:0
	v_pk_mul_f32 v[56:57], v[56:57], v[238:239] op_sel_hi:[1,0]
	v_pk_mul_f32 v[58:59], v[58:59], v[238:239] op_sel_hi:[1,0]
	v_pk_mul_f32 v[56:57], v[72:73], v[56:57]
	v_pk_mul_f32 v[58:59], v[74:75], v[58:59]
	v_pk_fma_f32 v[56:57], v[200:201], v[56:57], v[216:217]
	v_pk_fma_f32 v[58:59], v[202:203], v[58:59], v[218:219]
	v_cvt_pk_bf16_f32 v240, v56, v57
	v_cvt_pk_bf16_f32 v241, v58, v59
	v_pk_mul_f32 v[60:61], v[60:61], v[238:239] op_sel_hi:[1,0]
	v_pk_mul_f32 v[62:63], v[62:63], v[238:239] op_sel_hi:[1,0]
	v_pk_mul_f32 v[60:61], v[76:77], v[60:61]
	v_pk_mul_f32 v[62:63], v[78:79], v[62:63]
	v_pk_fma_f32 v[60:61], v[204:205], v[60:61], v[220:221]
	v_pk_fma_f32 v[62:63], v[206:207], v[62:63], v[222:223]
	v_cvt_pk_bf16_f32 v242, v60, v61
	v_cvt_pk_bf16_f32 v243, v62, v63
	global_store_dwordx4 v82, v[240:243], s[48:49] offset:1024
	s_add_u32 s34, s8, 0x33000
	s_addc_u32 s35, s9, 0
	s_add_u32 s36, s8, 0x39000
	s_addc_u32 s37, s9, 0
	global_load_dwordx4 v[176:179], v80, s[34:35] offset:0
	global_load_dwordx4 v[180:183], v80, s[34:35] offset:16
	global_load_dwordx4 v[184:187], v80, s[34:35] offset:2048
	global_load_dwordx4 v[188:191], v80, s[34:35] offset:2064
	global_load_dwordx4 v[160:163], v81, s[34:35] offset:0
	global_load_dwordx4 v[164:167], v81, s[34:35] offset:16
	global_load_dwordx4 v[168:171], v81, s[34:35] offset:2048
	global_load_dwordx4 v[172:175], v81, s[34:35] offset:2064
	global_load_dwordx4 v[208:211], v80, s[36:37] offset:0
	global_load_dwordx4 v[212:215], v80, s[36:37] offset:16
	global_load_dwordx4 v[216:219], v80, s[36:37] offset:2048
	global_load_dwordx4 v[220:223], v80, s[36:37] offset:2064
	global_load_dwordx4 v[192:195], v81, s[36:37] offset:0
	global_load_dwordx4 v[196:199], v81, s[36:37] offset:16
	global_load_dwordx4 v[200:203], v81, s[36:37] offset:2048
	global_load_dwordx4 v[204:207], v81, s[36:37] offset:2064
	s_add_u32 s24, s16, 0x9000000
	s_addc_u32 s25, s17, 0
	s_add_u32 s26, s16, 0x9400000
	s_addc_u32 s27, s17, 0
	s_add_u32 s28, s16, 0x9800000
	s_addc_u32 s29, s17, 0
	s_add_u32 s30, s16, 0x9c00000
	s_addc_u32 s31, s17, 0
	global_load_dwordx4 v[128:131], v82, s[24:25] offset:0 nt
	global_load_dwordx4 v[132:135], v82, s[24:25] offset:1024 nt
	global_load_dwordx4 v[136:139], v82, s[26:27] offset:0 nt
	global_load_dwordx4 v[140:143], v82, s[26:27] offset:1024 nt
	global_load_dwordx4 v[144:147], v82, s[28:29] offset:0 nt
	global_load_dwordx4 v[148:151], v82, s[28:29] offset:1024 nt
	global_load_dwordx4 v[152:155], v82, s[30:31] offset:0 nt
	global_load_dwordx4 v[156:159], v82, s[30:31] offset:1024 nt
	s_waitcnt vmcnt(32)
	v_lshlrev_b32_e32 v0, 16, v96
	v_and_b32_e32 v1, 0xffff0000, v96
	v_lshlrev_b32_e32 v2, 16, v97
	v_and_b32_e32 v3, 0xffff0000, v97
	v_lshlrev_b32_e32 v4, 16, v98
	v_and_b32_e32 v5, 0xffff0000, v98
	v_lshlrev_b32_e32 v6, 16, v99
	v_and_b32_e32 v7, 0xffff0000, v99
	v_lshlrev_b32_e32 v8, 16, v100
	v_and_b32_e32 v9, 0xffff0000, v100
	v_lshlrev_b32_e32 v10, 16, v101
	v_and_b32_e32 v11, 0xffff0000, v101
	v_lshlrev_b32_e32 v12, 16, v102
	v_and_b32_e32 v13, 0xffff0000, v102
	v_lshlrev_b32_e32 v14, 16, v103
	v_and_b32_e32 v15, 0xffff0000, v103
	v_lshlrev_b32_e32 v16, 16, v104
	v_and_b32_e32 v17, 0xffff0000, v104
	v_lshlrev_b32_e32 v18, 16, v105
	v_and_b32_e32 v19, 0xffff0000, v105
	v_lshlrev_b32_e32 v20, 16, v106
	v_and_b32_e32 v21, 0xffff0000, v106
	v_lshlrev_b32_e32 v22, 16, v107
	v_and_b32_e32 v23, 0xffff0000, v107
	v_lshlrev_b32_e32 v24, 16, v108
	v_and_b32_e32 v25, 0xffff0000, v108
	v_lshlrev_b32_e32 v26, 16, v109
	v_and_b32_e32 v27, 0xffff0000, v109
	v_lshlrev_b32_e32 v28, 16, v110
	v_and_b32_e32 v29, 0xffff0000, v110
	v_lshlrev_b32_e32 v30, 16, v111
	v_and_b32_e32 v31, 0xffff0000, v111
	v_lshlrev_b32_e32 v32, 16, v112
	v_and_b32_e32 v33, 0xffff0000, v112
	v_lshlrev_b32_e32 v34, 16, v113
	v_and_b32_e32 v35, 0xffff0000, v113
	v_lshlrev_b32_e32 v36, 16, v114
	v_and_b32_e32 v37, 0xffff0000, v114
	v_lshlrev_b32_e32 v38, 16, v115
	v_and_b32_e32 v39, 0xffff0000, v115
	v_lshlrev_b32_e32 v40, 16, v116
	v_and_b32_e32 v41, 0xffff0000, v116
	v_lshlrev_b32_e32 v42, 16, v117
	v_and_b32_e32 v43, 0xffff0000, v117
	v_lshlrev_b32_e32 v44, 16, v118
	v_and_b32_e32 v45, 0xffff0000, v118
	v_lshlrev_b32_e32 v46, 16, v119
	v_and_b32_e32 v47, 0xffff0000, v119
	v_lshlrev_b32_e32 v48, 16, v120
	v_and_b32_e32 v49, 0xffff0000, v120
; __device__ __forceinline__ float bf_lo(unsigned w) { return __uint_as_float(w << 16); }
; __device__ __forceinline__ float bf_hi(unsigned w) { return __uint_as_float(w & 0xffff0000u); }
; template <bool BF> __device__ __forceinline__ void prep_rows(const float* xp, const float* xs, const bf16* hb, const float* g, const float* MOD, int shoff, int scoff, bf16* U, int gw, int NGW, int lane) {
;     ...
;                 if (BF) { const v2u a0 = *(const v2u*)(hb + (size_t)mc * DM + 4 * lane + 256 * j);
;                     v[r][j].x = pg8::bf_lo(a0.x); v[r][j].y = pg8::bf_hi(a0.x); v[r][j].z = pg8::bf_lo(a0.y); v[r][j].w = pg8::bf_hi(a0.y); }
;                 else { const float* xr = mc < MP ? xp + (size_t)mc * DM : xs + (size_t)(mc - MP) * DM; v[r][j] = *(const f32x4*)(xr + 4 * lane + 256 * j); } } }
; #pragma unroll
;         for (int r = 0; r < R; ++r) { float t = 0.f;
; #pragma unroll
;             for (int j = 0; j < 4; ++j) t += (v[r][j].x * v[r][j].x + v[r][j].y * v[r][j].y) + (v[r][j].z * v[r][j].z + v[r][j].w * v[r][j].w);
;             s[r] = t; }
; #pragma unroll
;         for (int o = 1; o < 64; o <<= 1) {
; #pragma unroll
;             for (int r = 0; r < R; ++r) s[r] += __shfl_xor(s[r], o); }
; #pragma unroll
;         for (int r = 0; r < R; ++r) { const int m = mb + r * NGW; if (m < MT) {
;             const float rstd = 1.0f / sqrtf(s[r] * (1.0f / DM) + RMS_EPS);
	v_lshlrev_b32_e32 v50, 16, v121
	v_and_b32_e32 v51, 0xffff0000, v121
	v_lshlrev_b32_e32 v52, 16, v122
	v_and_b32_e32 v53, 0xffff0000, v122
	v_lshlrev_b32_e32 v54, 16, v123
	v_and_b32_e32 v55, 0xffff0000, v123
	v_lshlrev_b32_e32 v56, 16, v124
	v_and_b32_e32 v57, 0xffff0000, v124
	v_lshlrev_b32_e32 v58, 16, v125
	v_and_b32_e32 v59, 0xffff0000, v125
	v_lshlrev_b32_e32 v60, 16, v126
	v_and_b32_e32 v61, 0xffff0000, v126
	v_lshlrev_b32_e32 v62, 16, v127
	v_and_b32_e32 v63, 0xffff0000, v127
	v_pk_mul_f32 v[240:241], v[0:1], v[0:1]
	v_pk_mul_f32 v[242:243], v[16:17], v[16:17]
	v_pk_mul_f32 v[244:245], v[32:33], v[32:33]
	v_pk_mul_f32 v[246:247], v[48:49], v[48:49]
	v_pk_fma_f32 v[240:241], v[2:3], v[2:3], v[240:241]
	v_pk_fma_f32 v[242:243], v[18:19], v[18:19], v[242:243]
	v_pk_fma_f32 v[244:245], v[34:35], v[34:35], v[244:245]
	v_pk_fma_f32 v[246:247], v[50:51], v[50:51], v[246:247]
	v_pk_fma_f32 v[240:241], v[4:5], v[4:5], v[240:241]
	v_pk_fma_f32 v[242:243], v[20:21], v[20:21], v[242:243]
	v_pk_fma_f32 v[244:245], v[36:37], v[36:37], v[244:245]
	v_pk_fma_f32 v[246:247], v[52:53], v[52:53], v[246:247]
	v_pk_fma_f32 v[240:241], v[6:7], v[6:7], v[240:241]
	v_pk_fma_f32 v[242:243], v[22:23], v[22:23], v[242:243]
	v_pk_fma_f32 v[244:245], v[38:39], v[38:39], v[244:245]
	v_pk_fma_f32 v[246:247], v[54:55], v[54:55], v[246:247]
	v_pk_fma_f32 v[240:241], v[8:9], v[8:9], v[240:241]
	v_pk_fma_f32 v[242:243], v[24:25], v[24:25], v[242:243]
	v_pk_fma_f32 v[244:245], v[40:41], v[40:41], v[244:245]
	v_pk_fma_f32 v[246:247], v[56:57], v[56:57], v[246:247]
	v_pk_fma_f32 v[240:241], v[10:11], v[10:11], v[240:241]
	v_pk_fma_f32 v[242:243], v[26:27], v[26:27], v[242:243]
	v_pk_fma_f32 v[244:245], v[42:43], v[42:43], v[244:245]
	v_pk_fma_f32 v[246:247], v[58:59], v[58:59], v[246:247]
	v_pk_fma_f32 v[240:241], v[12:13], v[12:13], v[240:241]
	v_pk_fma_f32 v[242:243], v[28:29], v[28:29], v[242:243]
	v_pk_fma_f32 v[244:245], v[44:45], v[44:45], v[244:245]
	v_pk_fma_f32 v[246:247], v[60:61], v[60:61], v[246:247]
	v_pk_fma_f32 v[240:241], v[14:15], v[14:15], v[240:241]
	v_pk_fma_f32 v[242:243], v[30:31], v[30:31], v[242:243]
	v_pk_fma_f32 v[244:245], v[46:47], v[46:47], v[244:245]
	v_pk_fma_f32 v[246:247], v[62:63], v[62:63], v[246:247]
	v_add_f32_e32 v224, v240, v241
	v_add_f32_e32 v225, v242, v243
	v_add_f32_e32 v226, v244, v245
	v_add_f32_e32 v227, v246, v247
	ds_bpermute_b32 v228, v83, v224
	ds_bpermute_b32 v229, v83, v225
	ds_bpermute_b32 v230, v83, v226
	ds_bpermute_b32 v231, v83, v227
	s_waitcnt lgkmcnt(0)
	v_add_f32_e32 v224, v224, v228
	v_add_f32_e32 v225, v225, v229
	v_add_f32_e32 v226, v226, v230
	v_add_f32_e32 v227, v227, v231
	ds_bpermute_b32 v228, v84, v224
	ds_bpermute_b32 v229, v84, v225
	ds_bpermute_b32 v230, v84, v226
	ds_bpermute_b32 v231, v84, v227
	s_waitcnt lgkmcnt(0)
	v_add_f32_e32 v224, v224, v228
	v_add_f32_e32 v225, v225, v229
	v_add_f32_e32 v226, v226, v230
	v_add_f32_e32 v227, v227, v231
	ds_bpermute_b32 v228, v85, v224
	ds_bpermute_b32 v229, v85, v225
	ds_bpermute_b32 v230, v85, v226
	ds_bpermute_b32 v231, v85, v227
	s_waitcnt lgkmcnt(0)
	v_add_f32_e32 v224, v224, v228
	v_add_f32_e32 v225, v225, v229
	v_add_f32_e32 v226, v226, v230
	v_add_f32_e32 v227, v227, v231
	ds_bpermute_b32 v228, v86, v224
	ds_bpermute_b32 v229, v86, v225
	ds_bpermute_b32 v230, v86, v226
	ds_bpermute_b32 v231, v86, v227
	s_waitcnt lgkmcnt(0)
	v_add_f32_e32 v224, v224, v228
	v_add_f32_e32 v225, v225, v229
	v_add_f32_e32 v226, v226, v230
	v_add_f32_e32 v227, v227, v231
	ds_bpermute_b32 v228, v87, v224
	ds_bpermute_b32 v229, v87, v225
	ds_bpermute_b32 v230, v87, v226
	ds_bpermute_b32 v231, v87, v227
	s_waitcnt lgkmcnt(0)
	v_add_f32_e32 v224, v224, v228
	v_add_f32_e32 v225, v225, v229
	v_add_f32_e32 v226, v226, v230
	v_add_f32_e32 v227, v227, v231
	ds_bpermute_b32 v228, v88, v224
	ds_bpermute_b32 v229, v88, v225
	ds_bpermute_b32 v230, v88, v226
	ds_bpermute_b32 v231, v88, v227
	s_waitcnt lgkmcnt(0)
	v_add_f32_e32 v224, v224, v228
	v_add_f32_e32 v225, v225, v229
	v_add_f32_e32 v226, v226, v230
	v_add_f32_e32 v227, v227, v231
	v_fmamk_f32 v240, v224, 0x3a800000, v89
	v_mul_f32_e32 v241, 0x4f800000, v240
	v_cmp_gt_f32_e32 vcc, s54, v240
	s_nop 1
	v_cndmask_b32_e32 v247, v240, v241, vcc
	v_sqrt_f32_e32 v242, v247
	s_nop 1
	v_add_u32_e32 v243, -1, v242
	v_add_u32_e32 v244, 1, v242
	v_fma_f32 v245, -v243, v242, v247
	v_fma_f32 v246, -v244, v242, v247
	v_cmp_ge_f32_e64 s[52:53], 0, v245
	s_nop 1
	v_cndmask_b32_e64 v242, v242, v243, s[52:53]
	v_cmp_lt_f32_e64 s[52:53], 0, v246
	s_nop 1
	v_cndmask_b32_e64 v242, v242, v244, s[52:53]
	v_mul_f32_e32 v243, 0x37800000, v242
	v_cndmask_b32_e32 v242, v242, v243, vcc
	v_cmp_class_f32_e32 vcc, v247, v90
	s_nop 1
	v_cndmask_b32_e32 v247, v242, v247, vcc
	v_div_scale_f32 v248, s[52:53], v247, v247, 1.0
	v_rcp_f32_e32 v249, v248
	v_div_scale_f32 v228, vcc, 1.0, v247, 1.0
	s_nop 0
	v_fma_f32 v229, -v248, v249, 1.0
	v_fmac_f32_e32 v249, v229, v249
	v_mul_f32_e32 v230, v228, v249
	v_fma_f32 v229, -v248, v230, v228
	v_fmac_f32_e32 v230, v229, v249
	v_fma_f32 v248, -v248, v230, v228
	v_div_fmas_f32 v248, v248, v249, v230
	v_div_fixup_f32 v232, v248, v247, 1.0
	v_fmamk_f32 v240, v225, 0x3a800000, v89
	v_mul_f32_e32 v241, 0x4f800000, v240
	v_cmp_gt_f32_e32 vcc, s54, v240
	s_nop 1
	v_cndmask_b32_e32 v247, v240, v241, vcc
	v_sqrt_f32_e32 v242, v247
	s_nop 1
	v_add_u32_e32 v243, -1, v242
	v_add_u32_e32 v244, 1, v242
	v_fma_f32 v245, -v243, v242, v247
	v_fma_f32 v246, -v244, v242, v247
	v_cmp_ge_f32_e64 s[52:53], 0, v245
	s_nop 1
	v_cndmask_b32_e64 v242, v242, v243, s[52:53]
	v_cmp_lt_f32_e64 s[52:53], 0, v246
	s_nop 1
	v_cndmask_b32_e64 v242, v242, v244, s[52:53]
; __device__ __forceinline__ unsigned pk2(float lo, float hi) { return pg8::cvt_pk_bf16(lo, hi); }
; template <bool BF> __device__ __forceinline__ void prep_rows(const float* xp, const float* xs, const bf16* hb, const float* g, const float* MOD, int shoff, int scoff, bf16* U, int gw, int NGW, int lane) {
;     ...
;             const float rstd = 1.0f / sqrtf(s[r] * (1.0f / DM) + RMS_EPS);
;             const float* mr = MOD + (size_t)(m < MP ? (m >> 13) : 8 + ((m - MP) >> 12)) * 6144;
; #pragma unroll
;             for (int j = 0; j < 4; ++j) { const int c = 4 * lane + 256 * j;
;                 const f32x4 gg = *(const f32x4*)(g + c), sc = *(const f32x4*)(mr + scoff + c), sh = *(const f32x4*)(mr + shoff + c);
;                 const f32x4 o = v[r][j] * rstd * gg * (sc + 1.0f) + sh; v2u w; w.x = pk2(o.x, o.y); w.y = pk2(o.z, o.w); *(v2u*)(U + (size_t)m * DM + c) = w; } } }
	v_mul_f32_e32 v243, 0x37800000, v242
	v_cndmask_b32_e32 v242, v242, v243, vcc
	v_cmp_class_f32_e32 vcc, v247, v90
	s_nop 1
	v_cndmask_b32_e32 v247, v242, v247, vcc
	v_div_scale_f32 v248, s[52:53], v247, v247, 1.0
	v_rcp_f32_e32 v249, v248
	v_div_scale_f32 v228, vcc, 1.0, v247, 1.0
	s_nop 0
	v_fma_f32 v229, -v248, v249, 1.0
	v_fmac_f32_e32 v249, v229, v249
	v_mul_f32_e32 v230, v228, v249
	v_fma_f32 v229, -v248, v230, v228
	v_fmac_f32_e32 v230, v229, v249
	v_fma_f32 v248, -v248, v230, v228
	v_div_fmas_f32 v248, v248, v249, v230
	v_div_fixup_f32 v234, v248, v247, 1.0
	v_fmamk_f32 v240, v226, 0x3a800000, v89
	v_mul_f32_e32 v241, 0x4f800000, v240
	v_cmp_gt_f32_e32 vcc, s54, v240
	s_nop 1
	v_cndmask_b32_e32 v247, v240, v241, vcc
	v_sqrt_f32_e32 v242, v247
	s_nop 1
	v_add_u32_e32 v243, -1, v242
	v_add_u32_e32 v244, 1, v242
	v_fma_f32 v245, -v243, v242, v247
	v_fma_f32 v246, -v244, v242, v247
	v_cmp_ge_f32_e64 s[52:53], 0, v245
	s_nop 1
	v_cndmask_b32_e64 v242, v242, v243, s[52:53]
	v_cmp_lt_f32_e64 s[52:53], 0, v246
	s_nop 1
	v_cndmask_b32_e64 v242, v242, v244, s[52:53]
	v_mul_f32_e32 v243, 0x37800000, v242
	v_cndmask_b32_e32 v242, v242, v243, vcc
	v_cmp_class_f32_e32 vcc, v247, v90
	s_nop 1
	v_cndmask_b32_e32 v247, v242, v247, vcc
	v_div_scale_f32 v248, s[52:53], v247, v247, 1.0
	v_rcp_f32_e32 v249, v248
	v_div_scale_f32 v228, vcc, 1.0, v247, 1.0
	s_nop 0
	v_fma_f32 v229, -v248, v249, 1.0
	v_fmac_f32_e32 v249, v229, v249
	v_mul_f32_e32 v230, v228, v249
	v_fma_f32 v229, -v248, v230, v228
	v_fmac_f32_e32 v230, v229, v249
	v_fma_f32 v248, -v248, v230, v228
	v_div_fmas_f32 v248, v248, v249, v230
	v_div_fixup_f32 v236, v248, v247, 1.0
	v_fmamk_f32 v240, v227, 0x3a800000, v89
	v_mul_f32_e32 v241, 0x4f800000, v240
	v_cmp_gt_f32_e32 vcc, s54, v240
	s_nop 1
	v_cndmask_b32_e32 v247, v240, v241, vcc
	v_sqrt_f32_e32 v242, v247
	s_nop 1
	v_add_u32_e32 v243, -1, v242
	v_add_u32_e32 v244, 1, v242
	v_fma_f32 v245, -v243, v242, v247
	v_fma_f32 v246, -v244, v242, v247
	v_cmp_ge_f32_e64 s[52:53], 0, v245
	s_nop 1
	v_cndmask_b32_e64 v242, v242, v243, s[52:53]
	v_cmp_lt_f32_e64 s[52:53], 0, v246
	s_nop 1
	v_cndmask_b32_e64 v242, v242, v244, s[52:53]
	v_mul_f32_e32 v243, 0x37800000, v242
	v_cndmask_b32_e32 v242, v242, v243, vcc
	v_cmp_class_f32_e32 vcc, v247, v90
	s_nop 1
	v_cndmask_b32_e32 v247, v242, v247, vcc
	v_div_scale_f32 v248, s[52:53], v247, v247, 1.0
	v_rcp_f32_e32 v249, v248
	v_div_scale_f32 v228, vcc, 1.0, v247, 1.0
	s_nop 0
	v_fma_f32 v229, -v248, v249, 1.0
	v_fmac_f32_e32 v249, v229, v249
	v_mul_f32_e32 v230, v228, v249
	v_fma_f32 v229, -v248, v230, v228
	v_fmac_f32_e32 v230, v229, v249
	v_fma_f32 v248, -v248, v230, v228
	v_div_fmas_f32 v248, v248, v249, v230
	v_div_fixup_f32 v238, v248, v247, 1.0
	s_waitcnt vmcnt(8)
	v_pk_add_f32 v[160:161], v[160:161], 1.0 op_sel_hi:[1,0]
	v_pk_add_f32 v[162:163], v[162:163], 1.0 op_sel_hi:[1,0]
	v_pk_add_f32 v[164:165], v[164:165], 1.0 op_sel_hi:[1,0]
	v_pk_add_f32 v[166:167], v[166:167], 1.0 op_sel_hi:[1,0]
	v_pk_add_f32 v[168:169], v[168:169], 1.0 op_sel_hi:[1,0]
	v_pk_add_f32 v[170:171], v[170:171], 1.0 op_sel_hi:[1,0]
	v_pk_add_f32 v[172:173], v[172:173], 1.0 op_sel_hi:[1,0]
	v_pk_add_f32 v[174:175], v[174:175], 1.0 op_sel_hi:[1,0]
	v_pk_add_f32 v[192:193], v[192:193], 1.0 op_sel_hi:[1,0]
	v_pk_add_f32 v[194:195], v[194:195], 1.0 op_sel_hi:[1,0]
	v_pk_add_f32 v[196:197], v[196:197], 1.0 op_sel_hi:[1,0]
	v_pk_add_f32 v[198:199], v[198:199], 1.0 op_sel_hi:[1,0]
	v_pk_add_f32 v[200:201], v[200:201], 1.0 op_sel_hi:[1,0]
	v_pk_add_f32 v[202:203], v[202:203], 1.0 op_sel_hi:[1,0]
	v_pk_add_f32 v[204:205], v[204:205], 1.0 op_sel_hi:[1,0]
	v_pk_add_f32 v[206:207], v[206:207], 1.0 op_sel_hi:[1,0]
	s_add_u32 s38, s20, 0x8000000
	s_addc_u32 s39, s21, 0
	s_add_u32 s40, s20, 0x8400000
	s_addc_u32 s41, s21, 0
	s_add_u32 s46, s20, 0x8800000
	s_addc_u32 s47, s21, 0
	s_add_u32 s48, s20, 0x8c00000
	s_addc_u32 s49, s21, 0
	v_pk_mul_f32 v[0:1], v[0:1], v[232:233] op_sel_hi:[1,0]
	v_pk_mul_f32 v[2:3], v[2:3], v[232:233] op_sel_hi:[1,0]
	v_pk_mul_f32 v[0:1], v[64:65], v[0:1]
	v_pk_mul_f32 v[2:3], v[66:67], v[2:3]
	v_pk_fma_f32 v[0:1], v[160:161], v[0:1], v[176:177]
	v_pk_fma_f32 v[2:3], v[162:163], v[2:3], v[178:179]
	v_cvt_pk_bf16_f32 v244, v0, v1
	v_cvt_pk_bf16_f32 v245, v2, v3
	v_pk_mul_f32 v[4:5], v[4:5], v[232:233] op_sel_hi:[1,0]
	v_pk_mul_f32 v[6:7], v[6:7], v[232:233] op_sel_hi:[1,0]
	v_pk_mul_f32 v[4:5], v[68:69], v[4:5]
	v_pk_mul_f32 v[6:7], v[70:71], v[6:7]
	v_pk_fma_f32 v[4:5], v[164:165], v[4:5], v[180:181]
	v_pk_fma_f32 v[6:7], v[166:167], v[6:7], v[182:183]
	v_cvt_pk_bf16_f32 v246, v4, v5
	v_cvt_pk_bf16_f32 v247, v6, v7
	global_store_dwordx4 v82, v[244:247], s[38:39] offset:0
	v_pk_mul_f32 v[8:9], v[8:9], v[232:233] op_sel_hi:[1,0]
	v_pk_mul_f32 v[10:11], v[10:11], v[232:233] op_sel_hi:[1,0]
	v_pk_mul_f32 v[8:9], v[72:73], v[8:9]
	v_pk_mul_f32 v[10:11], v[74:75], v[10:11]
	v_pk_fma_f32 v[8:9], v[168:169], v[8:9], v[184:185]
	v_pk_fma_f32 v[10:11], v[170:171], v[10:11], v[186:187]
	v_cvt_pk_bf16_f32 v240, v8, v9
	v_cvt_pk_bf16_f32 v241, v10, v11
	v_pk_mul_f32 v[12:13], v[12:13], v[232:233] op_sel_hi:[1,0]
	v_pk_mul_f32 v[14:15], v[14:15], v[232:233] op_sel_hi:[1,0]
	v_pk_mul_f32 v[12:13], v[76:77], v[12:13]
	v_pk_mul_f32 v[14:15], v[78:79], v[14:15]
	v_pk_fma_f32 v[12:13], v[172:173], v[12:13], v[188:189]
	v_pk_fma_f32 v[14:15], v[174:175], v[14:15], v[190:191]
	v_cvt_pk_bf16_f32 v242, v12, v13
	v_cvt_pk_bf16_f32 v243, v14, v15
	global_store_dwordx4 v82, v[240:243], s[38:39] offset:1024
	v_pk_mul_f32 v[16:17], v[16:17], v[234:235] op_sel_hi:[1,0]
	v_pk_mul_f32 v[18:19], v[18:19], v[234:235] op_sel_hi:[1,0]
; __device__ __forceinline__ float bf_lo(unsigned w) { return __uint_as_float(w << 16); }
; __device__ __forceinline__ float bf_hi(unsigned w) { return __uint_as_float(w & 0xffff0000u); }
; __device__ __forceinline__ unsigned pk2(float lo, float hi) { return pg8::cvt_pk_bf16(lo, hi); }
; template <bool BF> __device__ __forceinline__ void prep_rows(const float* xp, const float* xs, const bf16* hb, const float* g, const float* MOD, int shoff, int scoff, bf16* U, int gw, int NGW, int lane) {
;     ...
;         for (int r = 0; r < R; ++r) { const int m = mb + r * NGW; const int mc = m < MT ? m : mb;
; #pragma unroll
;             for (int j = 0; j < 4; ++j) {
;                 if (BF) { const v2u a0 = *(const v2u*)(hb + (size_t)mc * DM + 4 * lane + 256 * j);
;                     v[r][j].x = pg8::bf_lo(a0.x); v[r][j].y = pg8::bf_hi(a0.x); v[r][j].z = pg8::bf_lo(a0.y); v[r][j].w = pg8::bf_hi(a0.y); }
;                 else { const float* xr = mc < MP ? xp + (size_t)mc * DM : xs + (size_t)(mc - MP) * DM; v[r][j] = *(const f32x4*)(xr + 4 * lane + 256 * j); } } }
; #pragma unroll
;         for (int r = 0; r < R; ++r) { float t = 0.f;
; #pragma unroll
;             for (int j = 0; j < 4; ++j) t += (v[r][j].x * v[r][j].x + v[r][j].y * v[r][j].y) + (v[r][j].z * v[r][j].z + v[r][j].w * v[r][j].w);
;             s[r] = t; }
; #pragma unroll
;         for (int o = 1; o < 64; o <<= 1) {
; #pragma unroll
;             for (int r = 0; r < R; ++r) s[r] += __shfl_xor(s[r], o); }
; #pragma unroll
;         for (int r = 0; r < R; ++r) { const int m = mb + r * NGW; if (m < MT) {
;             const float rstd = 1.0f / sqrtf(s[r] * (1.0f / DM) + RMS_EPS);
;             const float* mr = MOD + (size_t)(m < MP ? (m >> 13) : 8 + ((m - MP) >> 12)) * 6144;
; #pragma unroll
;             for (int j = 0; j < 4; ++j) { const int c = 4 * lane + 256 * j;
;                 const f32x4 gg = *(const f32x4*)(g + c), sc = *(const f32x4*)(mr + scoff + c), sh = *(const f32x4*)(mr + shoff + c);
;                 const f32x4 o = v[r][j] * rstd * gg * (sc + 1.0f) + sh; v2u w; w.x = pk2(o.x, o.y); w.y = pk2(o.z, o.w); *(v2u*)(U + (size_t)m * DM + c) = w; } } }
	v_pk_mul_f32 v[16:17], v[64:65], v[16:17]
	v_pk_mul_f32 v[18:19], v[66:67], v[18:19]
	v_pk_fma_f32 v[16:17], v[160:161], v[16:17], v[176:177]
	v_pk_fma_f32 v[18:19], v[162:163], v[18:19], v[178:179]
	v_cvt_pk_bf16_f32 v244, v16, v17
	v_cvt_pk_bf16_f32 v245, v18, v19
	v_pk_mul_f32 v[20:21], v[20:21], v[234:235] op_sel_hi:[1,0]
	v_pk_mul_f32 v[22:23], v[22:23], v[234:235] op_sel_hi:[1,0]
	v_pk_mul_f32 v[20:21], v[68:69], v[20:21]
	v_pk_mul_f32 v[22:23], v[70:71], v[22:23]
	v_pk_fma_f32 v[20:21], v[164:165], v[20:21], v[180:181]
	v_pk_fma_f32 v[22:23], v[166:167], v[22:23], v[182:183]
	v_cvt_pk_bf16_f32 v246, v20, v21
	v_cvt_pk_bf16_f32 v247, v22, v23
	global_store_dwordx4 v82, v[244:247], s[40:41] offset:0
	v_pk_mul_f32 v[24:25], v[24:25], v[234:235] op_sel_hi:[1,0]
	v_pk_mul_f32 v[26:27], v[26:27], v[234:235] op_sel_hi:[1,0]
	v_pk_mul_f32 v[24:25], v[72:73], v[24:25]
	v_pk_mul_f32 v[26:27], v[74:75], v[26:27]
	v_pk_fma_f32 v[24:25], v[168:169], v[24:25], v[184:185]
	v_pk_fma_f32 v[26:27], v[170:171], v[26:27], v[186:187]
	v_cvt_pk_bf16_f32 v240, v24, v25
	v_cvt_pk_bf16_f32 v241, v26, v27
	v_pk_mul_f32 v[28:29], v[28:29], v[234:235] op_sel_hi:[1,0]
	v_pk_mul_f32 v[30:31], v[30:31], v[234:235] op_sel_hi:[1,0]
	v_pk_mul_f32 v[28:29], v[76:77], v[28:29]
	v_pk_mul_f32 v[30:31], v[78:79], v[30:31]
	v_pk_fma_f32 v[28:29], v[172:173], v[28:29], v[188:189]
	v_pk_fma_f32 v[30:31], v[174:175], v[30:31], v[190:191]
	v_cvt_pk_bf16_f32 v242, v28, v29
	v_cvt_pk_bf16_f32 v243, v30, v31
	global_store_dwordx4 v82, v[240:243], s[40:41] offset:1024
	v_pk_mul_f32 v[32:33], v[32:33], v[236:237] op_sel_hi:[1,0]
	v_pk_mul_f32 v[34:35], v[34:35], v[236:237] op_sel_hi:[1,0]
	v_pk_mul_f32 v[32:33], v[64:65], v[32:33]
	v_pk_mul_f32 v[34:35], v[66:67], v[34:35]
	v_pk_fma_f32 v[32:33], v[192:193], v[32:33], v[208:209]
	v_pk_fma_f32 v[34:35], v[194:195], v[34:35], v[210:211]
	v_cvt_pk_bf16_f32 v244, v32, v33
	v_cvt_pk_bf16_f32 v245, v34, v35
	v_pk_mul_f32 v[36:37], v[36:37], v[236:237] op_sel_hi:[1,0]
	v_pk_mul_f32 v[38:39], v[38:39], v[236:237] op_sel_hi:[1,0]
	v_pk_mul_f32 v[36:37], v[68:69], v[36:37]
	v_pk_mul_f32 v[38:39], v[70:71], v[38:39]
	v_pk_fma_f32 v[36:37], v[196:197], v[36:37], v[212:213]
	v_pk_fma_f32 v[38:39], v[198:199], v[38:39], v[214:215]
	v_cvt_pk_bf16_f32 v246, v36, v37
	v_cvt_pk_bf16_f32 v247, v38, v39
	global_store_dwordx4 v82, v[244:247], s[46:47] offset:0
	v_pk_mul_f32 v[40:41], v[40:41], v[236:237] op_sel_hi:[1,0]
	v_pk_mul_f32 v[42:43], v[42:43], v[236:237] op_sel_hi:[1,0]
	v_pk_mul_f32 v[40:41], v[72:73], v[40:41]
	v_pk_mul_f32 v[42:43], v[74:75], v[42:43]
	v_pk_fma_f32 v[40:41], v[200:201], v[40:41], v[216:217]
	v_pk_fma_f32 v[42:43], v[202:203], v[42:43], v[218:219]
	v_cvt_pk_bf16_f32 v240, v40, v41
	v_cvt_pk_bf16_f32 v241, v42, v43
	v_pk_mul_f32 v[44:45], v[44:45], v[236:237] op_sel_hi:[1,0]
	v_pk_mul_f32 v[46:47], v[46:47], v[236:237] op_sel_hi:[1,0]
	v_pk_mul_f32 v[44:45], v[76:77], v[44:45]
	v_pk_mul_f32 v[46:47], v[78:79], v[46:47]
	v_pk_fma_f32 v[44:45], v[204:205], v[44:45], v[220:221]
	v_pk_fma_f32 v[46:47], v[206:207], v[46:47], v[222:223]
	v_cvt_pk_bf16_f32 v242, v44, v45
	v_cvt_pk_bf16_f32 v243, v46, v47
	global_store_dwordx4 v82, v[240:243], s[46:47] offset:1024
	v_pk_mul_f32 v[48:49], v[48:49], v[238:239] op_sel_hi:[1,0]
	v_pk_mul_f32 v[50:51], v[50:51], v[238:239] op_sel_hi:[1,0]
	v_pk_mul_f32 v[48:49], v[64:65], v[48:49]
	v_pk_mul_f32 v[50:51], v[66:67], v[50:51]
	v_pk_fma_f32 v[48:49], v[192:193], v[48:49], v[208:209]
	v_pk_fma_f32 v[50:51], v[194:195], v[50:51], v[210:211]
	v_cvt_pk_bf16_f32 v244, v48, v49
	v_cvt_pk_bf16_f32 v245, v50, v51
	v_pk_mul_f32 v[52:53], v[52:53], v[238:239] op_sel_hi:[1,0]
	v_pk_mul_f32 v[54:55], v[54:55], v[238:239] op_sel_hi:[1,0]
	v_pk_mul_f32 v[52:53], v[68:69], v[52:53]
	v_pk_mul_f32 v[54:55], v[70:71], v[54:55]
	v_pk_fma_f32 v[52:53], v[196:197], v[52:53], v[212:213]
	v_pk_fma_f32 v[54:55], v[198:199], v[54:55], v[214:215]
	v_cvt_pk_bf16_f32 v246, v52, v53
	v_cvt_pk_bf16_f32 v247, v54, v55
	global_store_dwordx4 v82, v[244:247], s[48:49] offset:0
	v_pk_mul_f32 v[56:57], v[56:57], v[238:239] op_sel_hi:[1,0]
	v_pk_mul_f32 v[58:59], v[58:59], v[238:239] op_sel_hi:[1,0]
	v_pk_mul_f32 v[56:57], v[72:73], v[56:57]
	v_pk_mul_f32 v[58:59], v[74:75], v[58:59]
	v_pk_fma_f32 v[56:57], v[200:201], v[56:57], v[216:217]
	v_pk_fma_f32 v[58:59], v[202:203], v[58:59], v[218:219]
	v_cvt_pk_bf16_f32 v240, v56, v57
	v_cvt_pk_bf16_f32 v241, v58, v59
	v_pk_mul_f32 v[60:61], v[60:61], v[238:239] op_sel_hi:[1,0]
	v_pk_mul_f32 v[62:63], v[62:63], v[238:239] op_sel_hi:[1,0]
	v_pk_mul_f32 v[60:61], v[76:77], v[60:61]
	v_pk_mul_f32 v[62:63], v[78:79], v[62:63]
	v_pk_fma_f32 v[60:61], v[204:205], v[60:61], v[220:221]
	v_pk_fma_f32 v[62:63], v[206:207], v[62:63], v[222:223]
	v_cvt_pk_bf16_f32 v242, v60, v61
	v_cvt_pk_bf16_f32 v243, v62, v63
	global_store_dwordx4 v82, v[240:243], s[48:49] offset:1024
	s_add_u32 s34, s8, 0x3f000
	s_addc_u32 s35, s9, 0
	s_add_u32 s36, s8, 0x45000
	s_addc_u32 s37, s9, 0
	global_load_dwordx4 v[176:179], v80, s[34:35] offset:0
	global_load_dwordx4 v[180:183], v80, s[34:35] offset:16
	global_load_dwordx4 v[184:187], v80, s[34:35] offset:2048
	global_load_dwordx4 v[188:191], v80, s[34:35] offset:2064
	global_load_dwordx4 v[160:163], v81, s[34:35] offset:0
	global_load_dwordx4 v[164:167], v81, s[34:35] offset:16
	global_load_dwordx4 v[168:171], v81, s[34:35] offset:2048
	global_load_dwordx4 v[172:175], v81, s[34:35] offset:2064
	global_load_dwordx4 v[208:211], v80, s[36:37] offset:0
	global_load_dwordx4 v[212:215], v80, s[36:37] offset:16
	global_load_dwordx4 v[216:219], v80, s[36:37] offset:2048
	global_load_dwordx4 v[220:223], v80, s[36:37] offset:2064
	global_load_dwordx4 v[192:195], v81, s[36:37] offset:0
	global_load_dwordx4 v[196:199], v81, s[36:37] offset:16
	global_load_dwordx4 v[200:203], v81, s[36:37] offset:2048
	global_load_dwordx4 v[204:207], v81, s[36:37] offset:2064
	s_add_u32 s24, s16, 0xa000000
	s_addc_u32 s25, s17, 0
	s_add_u32 s26, s16, 0xa400000
	s_addc_u32 s27, s17, 0
	s_add_u32 s28, s16, 0xa800000
	s_addc_u32 s29, s17, 0
	s_add_u32 s30, s16, 0xac00000
	s_addc_u32 s31, s17, 0
	global_load_dwordx4 v[96:99], v82, s[24:25] offset:0 nt
	global_load_dwordx4 v[100:103], v82, s[24:25] offset:1024 nt
	global_load_dwordx4 v[104:107], v82, s[26:27] offset:0 nt
	global_load_dwordx4 v[108:111], v82, s[26:27] offset:1024 nt
	global_load_dwordx4 v[112:115], v82, s[28:29] offset:0 nt
	global_load_dwordx4 v[116:119], v82, s[28:29] offset:1024 nt
	global_load_dwordx4 v[120:123], v82, s[30:31] offset:0 nt
	global_load_dwordx4 v[124:127], v82, s[30:31] offset:1024 nt
	s_waitcnt vmcnt(32)
; __device__ __forceinline__ float bf_lo(unsigned w) { return __uint_as_float(w << 16); }
; __device__ __forceinline__ float bf_hi(unsigned w) { return __uint_as_float(w & 0xffff0000u); }
; template <bool BF> __device__ __forceinline__ void prep_rows(const float* xp, const float* xs, const bf16* hb, const float* g, const float* MOD, int shoff, int scoff, bf16* U, int gw, int NGW, int lane) {
;     ...
;                 if (BF) { const v2u a0 = *(const v2u*)(hb + (size_t)mc * DM + 4 * lane + 256 * j);
;                     v[r][j].x = pg8::bf_lo(a0.x); v[r][j].y = pg8::bf_hi(a0.x); v[r][j].z = pg8::bf_lo(a0.y); v[r][j].w = pg8::bf_hi(a0.y); }
;                 else { const float* xr = mc < MP ? xp + (size_t)mc * DM : xs + (size_t)(mc - MP) * DM; v[r][j] = *(const f32x4*)(xr + 4 * lane + 256 * j); } } }
; #pragma unroll
;         for (int r = 0; r < R; ++r) { float t = 0.f;
; #pragma unroll
;             for (int j = 0; j < 4; ++j) t += (v[r][j].x * v[r][j].x + v[r][j].y * v[r][j].y) + (v[r][j].z * v[r][j].z + v[r][j].w * v[r][j].w);
;             s[r] = t; }
; #pragma unroll
;         for (int o = 1; o < 64; o <<= 1) {
; #pragma unroll
;             for (int r = 0; r < R; ++r) s[r] += __shfl_xor(s[r], o); }
	v_lshlrev_b32_e32 v0, 16, v128
	v_and_b32_e32 v1, 0xffff0000, v128
	v_lshlrev_b32_e32 v2, 16, v129
	v_and_b32_e32 v3, 0xffff0000, v129
	v_lshlrev_b32_e32 v4, 16, v130
	v_and_b32_e32 v5, 0xffff0000, v130
	v_lshlrev_b32_e32 v6, 16, v131
	v_and_b32_e32 v7, 0xffff0000, v131
	v_lshlrev_b32_e32 v8, 16, v132
	v_and_b32_e32 v9, 0xffff0000, v132
	v_lshlrev_b32_e32 v10, 16, v133
	v_and_b32_e32 v11, 0xffff0000, v133
	v_lshlrev_b32_e32 v12, 16, v134
	v_and_b32_e32 v13, 0xffff0000, v134
	v_lshlrev_b32_e32 v14, 16, v135
	v_and_b32_e32 v15, 0xffff0000, v135
	v_lshlrev_b32_e32 v16, 16, v136
	v_and_b32_e32 v17, 0xffff0000, v136
	v_lshlrev_b32_e32 v18, 16, v137
	v_and_b32_e32 v19, 0xffff0000, v137
	v_lshlrev_b32_e32 v20, 16, v138
	v_and_b32_e32 v21, 0xffff0000, v138
	v_lshlrev_b32_e32 v22, 16, v139
	v_and_b32_e32 v23, 0xffff0000, v139
	v_lshlrev_b32_e32 v24, 16, v140
	v_and_b32_e32 v25, 0xffff0000, v140
	v_lshlrev_b32_e32 v26, 16, v141
	v_and_b32_e32 v27, 0xffff0000, v141
	v_lshlrev_b32_e32 v28, 16, v142
	v_and_b32_e32 v29, 0xffff0000, v142
	v_lshlrev_b32_e32 v30, 16, v143
	v_and_b32_e32 v31, 0xffff0000, v143
	v_lshlrev_b32_e32 v32, 16, v144
	v_and_b32_e32 v33, 0xffff0000, v144
	v_lshlrev_b32_e32 v34, 16, v145
	v_and_b32_e32 v35, 0xffff0000, v145
	v_lshlrev_b32_e32 v36, 16, v146
	v_and_b32_e32 v37, 0xffff0000, v146
	v_lshlrev_b32_e32 v38, 16, v147
	v_and_b32_e32 v39, 0xffff0000, v147
	v_lshlrev_b32_e32 v40, 16, v148
	v_and_b32_e32 v41, 0xffff0000, v148
	v_lshlrev_b32_e32 v42, 16, v149
	v_and_b32_e32 v43, 0xffff0000, v149
	v_lshlrev_b32_e32 v44, 16, v150
	v_and_b32_e32 v45, 0xffff0000, v150
	v_lshlrev_b32_e32 v46, 16, v151
	v_and_b32_e32 v47, 0xffff0000, v151
	v_lshlrev_b32_e32 v48, 16, v152
	v_and_b32_e32 v49, 0xffff0000, v152
	v_lshlrev_b32_e32 v50, 16, v153
	v_and_b32_e32 v51, 0xffff0000, v153
	v_lshlrev_b32_e32 v52, 16, v154
	v_and_b32_e32 v53, 0xffff0000, v154
	v_lshlrev_b32_e32 v54, 16, v155
	v_and_b32_e32 v55, 0xffff0000, v155
	v_lshlrev_b32_e32 v56, 16, v156
	v_and_b32_e32 v57, 0xffff0000, v156
	v_lshlrev_b32_e32 v58, 16, v157
	v_and_b32_e32 v59, 0xffff0000, v157
	v_lshlrev_b32_e32 v60, 16, v158
	v_and_b32_e32 v61, 0xffff0000, v158
	v_lshlrev_b32_e32 v62, 16, v159
	v_and_b32_e32 v63, 0xffff0000, v159
	v_pk_mul_f32 v[240:241], v[0:1], v[0:1]
	v_pk_mul_f32 v[242:243], v[16:17], v[16:17]
	v_pk_mul_f32 v[244:245], v[32:33], v[32:33]
	v_pk_mul_f32 v[246:247], v[48:49], v[48:49]
	v_pk_fma_f32 v[240:241], v[2:3], v[2:3], v[240:241]
	v_pk_fma_f32 v[242:243], v[18:19], v[18:19], v[242:243]
	v_pk_fma_f32 v[244:245], v[34:35], v[34:35], v[244:245]
	v_pk_fma_f32 v[246:247], v[50:51], v[50:51], v[246:247]
	v_pk_fma_f32 v[240:241], v[4:5], v[4:5], v[240:241]
	v_pk_fma_f32 v[242:243], v[20:21], v[20:21], v[242:243]
	v_pk_fma_f32 v[244:245], v[36:37], v[36:37], v[244:245]
	v_pk_fma_f32 v[246:247], v[52:53], v[52:53], v[246:247]
	v_pk_fma_f32 v[240:241], v[6:7], v[6:7], v[240:241]
	v_pk_fma_f32 v[242:243], v[22:23], v[22:23], v[242:243]
	v_pk_fma_f32 v[244:245], v[38:39], v[38:39], v[244:245]
	v_pk_fma_f32 v[246:247], v[54:55], v[54:55], v[246:247]
	v_pk_fma_f32 v[240:241], v[8:9], v[8:9], v[240:241]
	v_pk_fma_f32 v[242:243], v[24:25], v[24:25], v[242:243]
	v_pk_fma_f32 v[244:245], v[40:41], v[40:41], v[244:245]
	v_pk_fma_f32 v[246:247], v[56:57], v[56:57], v[246:247]
	v_pk_fma_f32 v[240:241], v[10:11], v[10:11], v[240:241]
	v_pk_fma_f32 v[242:243], v[26:27], v[26:27], v[242:243]
	v_pk_fma_f32 v[244:245], v[42:43], v[42:43], v[244:245]
	v_pk_fma_f32 v[246:247], v[58:59], v[58:59], v[246:247]
	v_pk_fma_f32 v[240:241], v[12:13], v[12:13], v[240:241]
	v_pk_fma_f32 v[242:243], v[28:29], v[28:29], v[242:243]
	v_pk_fma_f32 v[244:245], v[44:45], v[44:45], v[244:245]
	v_pk_fma_f32 v[246:247], v[60:61], v[60:61], v[246:247]
	v_pk_fma_f32 v[240:241], v[14:15], v[14:15], v[240:241]
	v_pk_fma_f32 v[242:243], v[30:31], v[30:31], v[242:243]
	v_pk_fma_f32 v[244:245], v[46:47], v[46:47], v[244:245]
	v_pk_fma_f32 v[246:247], v[62:63], v[62:63], v[246:247]
	v_add_f32_e32 v224, v240, v241
	v_add_f32_e32 v225, v242, v243
	v_add_f32_e32 v226, v244, v245
	v_add_f32_e32 v227, v246, v247
	ds_bpermute_b32 v228, v83, v224
	ds_bpermute_b32 v229, v83, v225
	ds_bpermute_b32 v230, v83, v226
	ds_bpermute_b32 v231, v83, v227
	s_waitcnt lgkmcnt(0)
	v_add_f32_e32 v224, v224, v228
	v_add_f32_e32 v225, v225, v229
	v_add_f32_e32 v226, v226, v230
	v_add_f32_e32 v227, v227, v231
	ds_bpermute_b32 v228, v84, v224
	ds_bpermute_b32 v229, v84, v225
	ds_bpermute_b32 v230, v84, v226
	ds_bpermute_b32 v231, v84, v227
	s_waitcnt lgkmcnt(0)
	v_add_f32_e32 v224, v224, v228
	v_add_f32_e32 v225, v225, v229
	v_add_f32_e32 v226, v226, v230
	v_add_f32_e32 v227, v227, v231
	ds_bpermute_b32 v228, v85, v224
	ds_bpermute_b32 v229, v85, v225
	ds_bpermute_b32 v230, v85, v226
	ds_bpermute_b32 v231, v85, v227
	s_waitcnt lgkmcnt(0)
	v_add_f32_e32 v224, v224, v228
	v_add_f32_e32 v225, v225, v229
	v_add_f32_e32 v226, v226, v230
	v_add_f32_e32 v227, v227, v231
	ds_bpermute_b32 v228, v86, v224
	ds_bpermute_b32 v229, v86, v225
	ds_bpermute_b32 v230, v86, v226
	ds_bpermute_b32 v231, v86, v227
	s_waitcnt lgkmcnt(0)
	v_add_f32_e32 v224, v224, v228
	v_add_f32_e32 v225, v225, v229
	v_add_f32_e32 v226, v226, v230
	v_add_f32_e32 v227, v227, v231
	ds_bpermute_b32 v228, v87, v224
	ds_bpermute_b32 v229, v87, v225
	ds_bpermute_b32 v230, v87, v226
	ds_bpermute_b32 v231, v87, v227
	s_waitcnt lgkmcnt(0)
	v_add_f32_e32 v224, v224, v228
	v_add_f32_e32 v225, v225, v229
	v_add_f32_e32 v226, v226, v230
	v_add_f32_e32 v227, v227, v231
	ds_bpermute_b32 v228, v88, v224
	ds_bpermute_b32 v229, v88, v225
	ds_bpermute_b32 v230, v88, v226
	ds_bpermute_b32 v231, v88, v227
	s_waitcnt lgkmcnt(0)
; template <bool BF> __device__ __forceinline__ void prep_rows(const float* xp, const float* xs, const bf16* hb, const float* g, const float* MOD, int shoff, int scoff, bf16* U, int gw, int NGW, int lane) {
;     ...
;             for (int r = 0; r < R; ++r) s[r] += __shfl_xor(s[r], o); }
; #pragma unroll
;         for (int r = 0; r < R; ++r) { const int m = mb + r * NGW; if (m < MT) {
;             const float rstd = 1.0f / sqrtf(s[r] * (1.0f / DM) + RMS_EPS);
	v_add_f32_e32 v224, v224, v228
	v_add_f32_e32 v225, v225, v229
	v_add_f32_e32 v226, v226, v230
	v_add_f32_e32 v227, v227, v231
	v_fmamk_f32 v240, v224, 0x3a800000, v89
	v_mul_f32_e32 v241, 0x4f800000, v240
	v_cmp_gt_f32_e32 vcc, s54, v240
	s_nop 1
	v_cndmask_b32_e32 v247, v240, v241, vcc
	v_sqrt_f32_e32 v242, v247
	s_nop 1
	v_add_u32_e32 v243, -1, v242
	v_add_u32_e32 v244, 1, v242
	v_fma_f32 v245, -v243, v242, v247
	v_fma_f32 v246, -v244, v242, v247
	v_cmp_ge_f32_e64 s[52:53], 0, v245
	s_nop 1
	v_cndmask_b32_e64 v242, v242, v243, s[52:53]
	v_cmp_lt_f32_e64 s[52:53], 0, v246
	s_nop 1
	v_cndmask_b32_e64 v242, v242, v244, s[52:53]
	v_mul_f32_e32 v243, 0x37800000, v242
	v_cndmask_b32_e32 v242, v242, v243, vcc
	v_cmp_class_f32_e32 vcc, v247, v90
	s_nop 1
	v_cndmask_b32_e32 v247, v242, v247, vcc
	v_div_scale_f32 v248, s[52:53], v247, v247, 1.0
	v_rcp_f32_e32 v249, v248
	v_div_scale_f32 v228, vcc, 1.0, v247, 1.0
	s_nop 0
	v_fma_f32 v229, -v248, v249, 1.0
	v_fmac_f32_e32 v249, v229, v249
	v_mul_f32_e32 v230, v228, v249
	v_fma_f32 v229, -v248, v230, v228
	v_fmac_f32_e32 v230, v229, v249
	v_fma_f32 v248, -v248, v230, v228
	v_div_fmas_f32 v248, v248, v249, v230
	v_div_fixup_f32 v232, v248, v247, 1.0
	v_fmamk_f32 v240, v225, 0x3a800000, v89
	v_mul_f32_e32 v241, 0x4f800000, v240
	v_cmp_gt_f32_e32 vcc, s54, v240
	s_nop 1
	v_cndmask_b32_e32 v247, v240, v241, vcc
	v_sqrt_f32_e32 v242, v247
	s_nop 1
	v_add_u32_e32 v243, -1, v242
	v_add_u32_e32 v244, 1, v242
	v_fma_f32 v245, -v243, v242, v247
	v_fma_f32 v246, -v244, v242, v247
	v_cmp_ge_f32_e64 s[52:53], 0, v245
	s_nop 1
	v_cndmask_b32_e64 v242, v242, v243, s[52:53]
	v_cmp_lt_f32_e64 s[52:53], 0, v246
	s_nop 1
	v_cndmask_b32_e64 v242, v242, v244, s[52:53]
	v_mul_f32_e32 v243, 0x37800000, v242
	v_cndmask_b32_e32 v242, v242, v243, vcc
	v_cmp_class_f32_e32 vcc, v247, v90
	s_nop 1
	v_cndmask_b32_e32 v247, v242, v247, vcc
	v_div_scale_f32 v248, s[52:53], v247, v247, 1.0
	v_rcp_f32_e32 v249, v248
	v_div_scale_f32 v228, vcc, 1.0, v247, 1.0
	s_nop 0
	v_fma_f32 v229, -v248, v249, 1.0
	v_fmac_f32_e32 v249, v229, v249
	v_mul_f32_e32 v230, v228, v249
	v_fma_f32 v229, -v248, v230, v228
	v_fmac_f32_e32 v230, v229, v249
	v_fma_f32 v248, -v248, v230, v228
	v_div_fmas_f32 v248, v248, v249, v230
	v_div_fixup_f32 v234, v248, v247, 1.0
	v_fmamk_f32 v240, v226, 0x3a800000, v89
	v_mul_f32_e32 v241, 0x4f800000, v240
	v_cmp_gt_f32_e32 vcc, s54, v240
	s_nop 1
	v_cndmask_b32_e32 v247, v240, v241, vcc
	v_sqrt_f32_e32 v242, v247
	s_nop 1
	v_add_u32_e32 v243, -1, v242
	v_add_u32_e32 v244, 1, v242
	v_fma_f32 v245, -v243, v242, v247
	v_fma_f32 v246, -v244, v242, v247
	v_cmp_ge_f32_e64 s[52:53], 0, v245
	s_nop 1
	v_cndmask_b32_e64 v242, v242, v243, s[52:53]
	v_cmp_lt_f32_e64 s[52:53], 0, v246
	s_nop 1
	v_cndmask_b32_e64 v242, v242, v244, s[52:53]
	v_mul_f32_e32 v243, 0x37800000, v242
	v_cndmask_b32_e32 v242, v242, v243, vcc
	v_cmp_class_f32_e32 vcc, v247, v90
	s_nop 1
	v_cndmask_b32_e32 v247, v242, v247, vcc
	v_div_scale_f32 v248, s[52:53], v247, v247, 1.0
	v_rcp_f32_e32 v249, v248
	v_div_scale_f32 v228, vcc, 1.0, v247, 1.0
	s_nop 0
	v_fma_f32 v229, -v248, v249, 1.0
	v_fmac_f32_e32 v249, v229, v249
	v_mul_f32_e32 v230, v228, v249
	v_fma_f32 v229, -v248, v230, v228
	v_fmac_f32_e32 v230, v229, v249
	v_fma_f32 v248, -v248, v230, v228
	v_div_fmas_f32 v248, v248, v249, v230
	v_div_fixup_f32 v236, v248, v247, 1.0
	v_fmamk_f32 v240, v227, 0x3a800000, v89
	v_mul_f32_e32 v241, 0x4f800000, v240
	v_cmp_gt_f32_e32 vcc, s54, v240
	s_nop 1
	v_cndmask_b32_e32 v247, v240, v241, vcc
	v_sqrt_f32_e32 v242, v247
	s_nop 1
	v_add_u32_e32 v243, -1, v242
	v_add_u32_e32 v244, 1, v242
	v_fma_f32 v245, -v243, v242, v247
	v_fma_f32 v246, -v244, v242, v247
	v_cmp_ge_f32_e64 s[52:53], 0, v245
	s_nop 1
	v_cndmask_b32_e64 v242, v242, v243, s[52:53]
	v_cmp_lt_f32_e64 s[52:53], 0, v246
	s_nop 1
	v_cndmask_b32_e64 v242, v242, v244, s[52:53]
	v_mul_f32_e32 v243, 0x37800000, v242
	v_cndmask_b32_e32 v242, v242, v243, vcc
	v_cmp_class_f32_e32 vcc, v247, v90
	s_nop 1
	v_cndmask_b32_e32 v247, v242, v247, vcc
	v_div_scale_f32 v248, s[52:53], v247, v247, 1.0
	v_rcp_f32_e32 v249, v248
	v_div_scale_f32 v228, vcc, 1.0, v247, 1.0
	s_nop 0
	v_fma_f32 v229, -v248, v249, 1.0
	v_fmac_f32_e32 v249, v229, v249
	v_mul_f32_e32 v230, v228, v249
	v_fma_f32 v229, -v248, v230, v228
	v_fmac_f32_e32 v230, v229, v249
	v_fma_f32 v248, -v248, v230, v228
	v_div_fmas_f32 v248, v248, v249, v230
	v_div_fixup_f32 v238, v248, v247, 1.0
	s_waitcnt vmcnt(8)
; __device__ __forceinline__ unsigned pk2(float lo, float hi) { return pg8::cvt_pk_bf16(lo, hi); }
; template <bool BF> __device__ __forceinline__ void prep_rows(const float* xp, const float* xs, const bf16* hb, const float* g, const float* MOD, int shoff, int scoff, bf16* U, int gw, int NGW, int lane) {
;     ...
;             const float* mr = MOD + (size_t)(m < MP ? (m >> 13) : 8 + ((m - MP) >> 12)) * 6144;
; #pragma unroll
;             for (int j = 0; j < 4; ++j) { const int c = 4 * lane + 256 * j;
;                 const f32x4 gg = *(const f32x4*)(g + c), sc = *(const f32x4*)(mr + scoff + c), sh = *(const f32x4*)(mr + shoff + c);
;                 const f32x4 o = v[r][j] * rstd * gg * (sc + 1.0f) + sh; v2u w; w.x = pk2(o.x, o.y); w.y = pk2(o.z, o.w); *(v2u*)(U + (size_t)m * DM + c) = w; } } }
	v_pk_add_f32 v[160:161], v[160:161], 1.0 op_sel_hi:[1,0]
	v_pk_add_f32 v[162:163], v[162:163], 1.0 op_sel_hi:[1,0]
	v_pk_add_f32 v[164:165], v[164:165], 1.0 op_sel_hi:[1,0]
	v_pk_add_f32 v[166:167], v[166:167], 1.0 op_sel_hi:[1,0]
	v_pk_add_f32 v[168:169], v[168:169], 1.0 op_sel_hi:[1,0]
	v_pk_add_f32 v[170:171], v[170:171], 1.0 op_sel_hi:[1,0]
	v_pk_add_f32 v[172:173], v[172:173], 1.0 op_sel_hi:[1,0]
	v_pk_add_f32 v[174:175], v[174:175], 1.0 op_sel_hi:[1,0]
	v_pk_add_f32 v[192:193], v[192:193], 1.0 op_sel_hi:[1,0]
	v_pk_add_f32 v[194:195], v[194:195], 1.0 op_sel_hi:[1,0]
	v_pk_add_f32 v[196:197], v[196:197], 1.0 op_sel_hi:[1,0]
	v_pk_add_f32 v[198:199], v[198:199], 1.0 op_sel_hi:[1,0]
	v_pk_add_f32 v[200:201], v[200:201], 1.0 op_sel_hi:[1,0]
	v_pk_add_f32 v[202:203], v[202:203], 1.0 op_sel_hi:[1,0]
	v_pk_add_f32 v[204:205], v[204:205], 1.0 op_sel_hi:[1,0]
	v_pk_add_f32 v[206:207], v[206:207], 1.0 op_sel_hi:[1,0]
	s_add_u32 s38, s20, 0x9000000
	s_addc_u32 s39, s21, 0
	s_add_u32 s40, s20, 0x9400000
	s_addc_u32 s41, s21, 0
	s_add_u32 s46, s20, 0x9800000
	s_addc_u32 s47, s21, 0
	s_add_u32 s48, s20, 0x9c00000
	s_addc_u32 s49, s21, 0
	v_pk_mul_f32 v[0:1], v[0:1], v[232:233] op_sel_hi:[1,0]
	v_pk_mul_f32 v[2:3], v[2:3], v[232:233] op_sel_hi:[1,0]
	v_pk_mul_f32 v[0:1], v[64:65], v[0:1]
	v_pk_mul_f32 v[2:3], v[66:67], v[2:3]
	v_pk_fma_f32 v[0:1], v[160:161], v[0:1], v[176:177]
	v_pk_fma_f32 v[2:3], v[162:163], v[2:3], v[178:179]
	v_cvt_pk_bf16_f32 v244, v0, v1
	v_cvt_pk_bf16_f32 v245, v2, v3
	v_pk_mul_f32 v[4:5], v[4:5], v[232:233] op_sel_hi:[1,0]
	v_pk_mul_f32 v[6:7], v[6:7], v[232:233] op_sel_hi:[1,0]
	v_pk_mul_f32 v[4:5], v[68:69], v[4:5]
	v_pk_mul_f32 v[6:7], v[70:71], v[6:7]
	v_pk_fma_f32 v[4:5], v[164:165], v[4:5], v[180:181]
	v_pk_fma_f32 v[6:7], v[166:167], v[6:7], v[182:183]
	v_cvt_pk_bf16_f32 v246, v4, v5
	v_cvt_pk_bf16_f32 v247, v6, v7
	global_store_dwordx4 v82, v[244:247], s[38:39] offset:0
	v_pk_mul_f32 v[8:9], v[8:9], v[232:233] op_sel_hi:[1,0]
	v_pk_mul_f32 v[10:11], v[10:11], v[232:233] op_sel_hi:[1,0]
	v_pk_mul_f32 v[8:9], v[72:73], v[8:9]
	v_pk_mul_f32 v[10:11], v[74:75], v[10:11]
	v_pk_fma_f32 v[8:9], v[168:169], v[8:9], v[184:185]
	v_pk_fma_f32 v[10:11], v[170:171], v[10:11], v[186:187]
	v_cvt_pk_bf16_f32 v240, v8, v9
	v_cvt_pk_bf16_f32 v241, v10, v11
	v_pk_mul_f32 v[12:13], v[12:13], v[232:233] op_sel_hi:[1,0]
	v_pk_mul_f32 v[14:15], v[14:15], v[232:233] op_sel_hi:[1,0]
	v_pk_mul_f32 v[12:13], v[76:77], v[12:13]
	v_pk_mul_f32 v[14:15], v[78:79], v[14:15]
	v_pk_fma_f32 v[12:13], v[172:173], v[12:13], v[188:189]
	v_pk_fma_f32 v[14:15], v[174:175], v[14:15], v[190:191]
	v_cvt_pk_bf16_f32 v242, v12, v13
	v_cvt_pk_bf16_f32 v243, v14, v15
	global_store_dwordx4 v82, v[240:243], s[38:39] offset:1024
	v_pk_mul_f32 v[16:17], v[16:17], v[234:235] op_sel_hi:[1,0]
	v_pk_mul_f32 v[18:19], v[18:19], v[234:235] op_sel_hi:[1,0]
	v_pk_mul_f32 v[16:17], v[64:65], v[16:17]
	v_pk_mul_f32 v[18:19], v[66:67], v[18:19]
	v_pk_fma_f32 v[16:17], v[160:161], v[16:17], v[176:177]
	v_pk_fma_f32 v[18:19], v[162:163], v[18:19], v[178:179]
	v_cvt_pk_bf16_f32 v244, v16, v17
	v_cvt_pk_bf16_f32 v245, v18, v19
	v_pk_mul_f32 v[20:21], v[20:21], v[234:235] op_sel_hi:[1,0]
	v_pk_mul_f32 v[22:23], v[22:23], v[234:235] op_sel_hi:[1,0]
	v_pk_mul_f32 v[20:21], v[68:69], v[20:21]
	v_pk_mul_f32 v[22:23], v[70:71], v[22:23]
	v_pk_fma_f32 v[20:21], v[164:165], v[20:21], v[180:181]
	v_pk_fma_f32 v[22:23], v[166:167], v[22:23], v[182:183]
	v_cvt_pk_bf16_f32 v246, v20, v21
	v_cvt_pk_bf16_f32 v247, v22, v23
	global_store_dwordx4 v82, v[244:247], s[40:41] offset:0
	v_pk_mul_f32 v[24:25], v[24:25], v[234:235] op_sel_hi:[1,0]
	v_pk_mul_f32 v[26:27], v[26:27], v[234:235] op_sel_hi:[1,0]
	v_pk_mul_f32 v[24:25], v[72:73], v[24:25]
	v_pk_mul_f32 v[26:27], v[74:75], v[26:27]
	v_pk_fma_f32 v[24:25], v[168:169], v[24:25], v[184:185]
	v_pk_fma_f32 v[26:27], v[170:171], v[26:27], v[186:187]
	v_cvt_pk_bf16_f32 v240, v24, v25
	v_cvt_pk_bf16_f32 v241, v26, v27
	v_pk_mul_f32 v[28:29], v[28:29], v[234:235] op_sel_hi:[1,0]
	v_pk_mul_f32 v[30:31], v[30:31], v[234:235] op_sel_hi:[1,0]
	v_pk_mul_f32 v[28:29], v[76:77], v[28:29]
	v_pk_mul_f32 v[30:31], v[78:79], v[30:31]
	v_pk_fma_f32 v[28:29], v[172:173], v[28:29], v[188:189]
	v_pk_fma_f32 v[30:31], v[174:175], v[30:31], v[190:191]
	v_cvt_pk_bf16_f32 v242, v28, v29
	v_cvt_pk_bf16_f32 v243, v30, v31
	global_store_dwordx4 v82, v[240:243], s[40:41] offset:1024
	v_pk_mul_f32 v[32:33], v[32:33], v[236:237] op_sel_hi:[1,0]
	v_pk_mul_f32 v[34:35], v[34:35], v[236:237] op_sel_hi:[1,0]
	v_pk_mul_f32 v[32:33], v[64:65], v[32:33]
	v_pk_mul_f32 v[34:35], v[66:67], v[34:35]
	v_pk_fma_f32 v[32:33], v[192:193], v[32:33], v[208:209]
	v_pk_fma_f32 v[34:35], v[194:195], v[34:35], v[210:211]
	v_cvt_pk_bf16_f32 v244, v32, v33
	v_cvt_pk_bf16_f32 v245, v34, v35
	v_pk_mul_f32 v[36:37], v[36:37], v[236:237] op_sel_hi:[1,0]
	v_pk_mul_f32 v[38:39], v[38:39], v[236:237] op_sel_hi:[1,0]
	v_pk_mul_f32 v[36:37], v[68:69], v[36:37]
	v_pk_mul_f32 v[38:39], v[70:71], v[38:39]
	v_pk_fma_f32 v[36:37], v[196:197], v[36:37], v[212:213]
	v_pk_fma_f32 v[38:39], v[198:199], v[38:39], v[214:215]
	v_cvt_pk_bf16_f32 v246, v36, v37
	v_cvt_pk_bf16_f32 v247, v38, v39
	global_store_dwordx4 v82, v[244:247], s[46:47] offset:0
	v_pk_mul_f32 v[40:41], v[40:41], v[236:237] op_sel_hi:[1,0]
	v_pk_mul_f32 v[42:43], v[42:43], v[236:237] op_sel_hi:[1,0]
	v_pk_mul_f32 v[40:41], v[72:73], v[40:41]
	v_pk_mul_f32 v[42:43], v[74:75], v[42:43]
	v_pk_fma_f32 v[40:41], v[200:201], v[40:41], v[216:217]
	v_pk_fma_f32 v[42:43], v[202:203], v[42:43], v[218:219]
	v_cvt_pk_bf16_f32 v240, v40, v41
; __device__ __forceinline__ float bf_lo(unsigned w) { return __uint_as_float(w << 16); }
; __device__ __forceinline__ float bf_hi(unsigned w) { return __uint_as_float(w & 0xffff0000u); }
; __device__ __forceinline__ unsigned pk2(float lo, float hi) { return pg8::cvt_pk_bf16(lo, hi); }
; template <bool BF> __device__ __forceinline__ void prep_rows(const float* xp, const float* xs, const bf16* hb, const float* g, const float* MOD, int shoff, int scoff, bf16* U, int gw, int NGW, int lane) {
;     ...
;         for (int r = 0; r < R; ++r) { const int m = mb + r * NGW; const int mc = m < MT ? m : mb;
; #pragma unroll
;             for (int j = 0; j < 4; ++j) {
;                 if (BF) { const v2u a0 = *(const v2u*)(hb + (size_t)mc * DM + 4 * lane + 256 * j);
;                     v[r][j].x = pg8::bf_lo(a0.x); v[r][j].y = pg8::bf_hi(a0.x); v[r][j].z = pg8::bf_lo(a0.y); v[r][j].w = pg8::bf_hi(a0.y); }
;                 else { const float* xr = mc < MP ? xp + (size_t)mc * DM : xs + (size_t)(mc - MP) * DM; v[r][j] = *(const f32x4*)(xr + 4 * lane + 256 * j); } } }
;     ...
;             for (int j = 0; j < 4; ++j) { const int c = 4 * lane + 256 * j;
;                 const f32x4 gg = *(const f32x4*)(g + c), sc = *(const f32x4*)(mr + scoff + c), sh = *(const f32x4*)(mr + shoff + c);
;                 const f32x4 o = v[r][j] * rstd * gg * (sc + 1.0f) + sh; v2u w; w.x = pk2(o.x, o.y); w.y = pk2(o.z, o.w); *(v2u*)(U + (size_t)m * DM + c) = w; } } }
	v_cvt_pk_bf16_f32 v241, v42, v43
	v_pk_mul_f32 v[44:45], v[44:45], v[236:237] op_sel_hi:[1,0]
	v_pk_mul_f32 v[46:47], v[46:47], v[236:237] op_sel_hi:[1,0]
	v_pk_mul_f32 v[44:45], v[76:77], v[44:45]
	v_pk_mul_f32 v[46:47], v[78:79], v[46:47]
	v_pk_fma_f32 v[44:45], v[204:205], v[44:45], v[220:221]
	v_pk_fma_f32 v[46:47], v[206:207], v[46:47], v[222:223]
	v_cvt_pk_bf16_f32 v242, v44, v45
	v_cvt_pk_bf16_f32 v243, v46, v47
	global_store_dwordx4 v82, v[240:243], s[46:47] offset:1024
	v_pk_mul_f32 v[48:49], v[48:49], v[238:239] op_sel_hi:[1,0]
	v_pk_mul_f32 v[50:51], v[50:51], v[238:239] op_sel_hi:[1,0]
	v_pk_mul_f32 v[48:49], v[64:65], v[48:49]
	v_pk_mul_f32 v[50:51], v[66:67], v[50:51]
	v_pk_fma_f32 v[48:49], v[192:193], v[48:49], v[208:209]
	v_pk_fma_f32 v[50:51], v[194:195], v[50:51], v[210:211]
	v_cvt_pk_bf16_f32 v244, v48, v49
	v_cvt_pk_bf16_f32 v245, v50, v51
	v_pk_mul_f32 v[52:53], v[52:53], v[238:239] op_sel_hi:[1,0]
	v_pk_mul_f32 v[54:55], v[54:55], v[238:239] op_sel_hi:[1,0]
	v_pk_mul_f32 v[52:53], v[68:69], v[52:53]
	v_pk_mul_f32 v[54:55], v[70:71], v[54:55]
	v_pk_fma_f32 v[52:53], v[196:197], v[52:53], v[212:213]
	v_pk_fma_f32 v[54:55], v[198:199], v[54:55], v[214:215]
	v_cvt_pk_bf16_f32 v246, v52, v53
	v_cvt_pk_bf16_f32 v247, v54, v55
	global_store_dwordx4 v82, v[244:247], s[48:49] offset:0
	v_pk_mul_f32 v[56:57], v[56:57], v[238:239] op_sel_hi:[1,0]
	v_pk_mul_f32 v[58:59], v[58:59], v[238:239] op_sel_hi:[1,0]
	v_pk_mul_f32 v[56:57], v[72:73], v[56:57]
	v_pk_mul_f32 v[58:59], v[74:75], v[58:59]
	v_pk_fma_f32 v[56:57], v[200:201], v[56:57], v[216:217]
	v_pk_fma_f32 v[58:59], v[202:203], v[58:59], v[218:219]
	v_cvt_pk_bf16_f32 v240, v56, v57
	v_cvt_pk_bf16_f32 v241, v58, v59
	v_pk_mul_f32 v[60:61], v[60:61], v[238:239] op_sel_hi:[1,0]
	v_pk_mul_f32 v[62:63], v[62:63], v[238:239] op_sel_hi:[1,0]
	v_pk_mul_f32 v[60:61], v[76:77], v[60:61]
	v_pk_mul_f32 v[62:63], v[78:79], v[62:63]
	v_pk_fma_f32 v[60:61], v[204:205], v[60:61], v[220:221]
	v_pk_fma_f32 v[62:63], v[206:207], v[62:63], v[222:223]
	v_cvt_pk_bf16_f32 v242, v60, v61
	v_cvt_pk_bf16_f32 v243, v62, v63
	global_store_dwordx4 v82, v[240:243], s[48:49] offset:1024
	s_add_u32 s34, s8, 0x4b000
	s_addc_u32 s35, s9, 0
	s_add_u32 s36, s8, 0x51000
	s_addc_u32 s37, s9, 0
	global_load_dwordx4 v[176:179], v80, s[34:35] offset:0
	global_load_dwordx4 v[180:183], v80, s[34:35] offset:16
	global_load_dwordx4 v[184:187], v80, s[34:35] offset:2048
	global_load_dwordx4 v[188:191], v80, s[34:35] offset:2064
	global_load_dwordx4 v[160:163], v81, s[34:35] offset:0
	global_load_dwordx4 v[164:167], v81, s[34:35] offset:16
	global_load_dwordx4 v[168:171], v81, s[34:35] offset:2048
	global_load_dwordx4 v[172:175], v81, s[34:35] offset:2064
	global_load_dwordx4 v[208:211], v80, s[36:37] offset:0
	global_load_dwordx4 v[212:215], v80, s[36:37] offset:16
	global_load_dwordx4 v[216:219], v80, s[36:37] offset:2048
	global_load_dwordx4 v[220:223], v80, s[36:37] offset:2064
	global_load_dwordx4 v[192:195], v81, s[36:37] offset:0
	global_load_dwordx4 v[196:199], v81, s[36:37] offset:16
	global_load_dwordx4 v[200:203], v81, s[36:37] offset:2048
	global_load_dwordx4 v[204:207], v81, s[36:37] offset:2064
	s_add_u32 s24, s16, 0xb000000
	s_addc_u32 s25, s17, 0
	s_add_u32 s26, s16, 0xb400000
	s_addc_u32 s27, s17, 0
	s_add_u32 s28, s16, 0xb800000
	s_addc_u32 s29, s17, 0
	s_add_u32 s30, s16, 0xbc00000
	s_addc_u32 s31, s17, 0
	global_load_dwordx4 v[128:131], v82, s[24:25] offset:0 nt
	global_load_dwordx4 v[132:135], v82, s[24:25] offset:1024 nt
	global_load_dwordx4 v[136:139], v82, s[26:27] offset:0 nt
	global_load_dwordx4 v[140:143], v82, s[26:27] offset:1024 nt
	global_load_dwordx4 v[144:147], v82, s[28:29] offset:0 nt
	global_load_dwordx4 v[148:151], v82, s[28:29] offset:1024 nt
	global_load_dwordx4 v[152:155], v82, s[30:31] offset:0 nt
	global_load_dwordx4 v[156:159], v82, s[30:31] offset:1024 nt
	s_waitcnt vmcnt(32)
	v_lshlrev_b32_e32 v0, 16, v96
	v_and_b32_e32 v1, 0xffff0000, v96
	v_lshlrev_b32_e32 v2, 16, v97
	v_and_b32_e32 v3, 0xffff0000, v97
	v_lshlrev_b32_e32 v4, 16, v98
	v_and_b32_e32 v5, 0xffff0000, v98
	v_lshlrev_b32_e32 v6, 16, v99
	v_and_b32_e32 v7, 0xffff0000, v99
	v_lshlrev_b32_e32 v8, 16, v100
	v_and_b32_e32 v9, 0xffff0000, v100
	v_lshlrev_b32_e32 v10, 16, v101
	v_and_b32_e32 v11, 0xffff0000, v101
	v_lshlrev_b32_e32 v12, 16, v102
	v_and_b32_e32 v13, 0xffff0000, v102
	v_lshlrev_b32_e32 v14, 16, v103
	v_and_b32_e32 v15, 0xffff0000, v103
	v_lshlrev_b32_e32 v16, 16, v104
	v_and_b32_e32 v17, 0xffff0000, v104
	v_lshlrev_b32_e32 v18, 16, v105
	v_and_b32_e32 v19, 0xffff0000, v105
	v_lshlrev_b32_e32 v20, 16, v106
	v_and_b32_e32 v21, 0xffff0000, v106
	v_lshlrev_b32_e32 v22, 16, v107
	v_and_b32_e32 v23, 0xffff0000, v107
	v_lshlrev_b32_e32 v24, 16, v108
	v_and_b32_e32 v25, 0xffff0000, v108
	v_lshlrev_b32_e32 v26, 16, v109
	v_and_b32_e32 v27, 0xffff0000, v109
	v_lshlrev_b32_e32 v28, 16, v110
	v_and_b32_e32 v29, 0xffff0000, v110
	v_lshlrev_b32_e32 v30, 16, v111
	v_and_b32_e32 v31, 0xffff0000, v111
	v_lshlrev_b32_e32 v32, 16, v112
	v_and_b32_e32 v33, 0xffff0000, v112
	v_lshlrev_b32_e32 v34, 16, v113
	v_and_b32_e32 v35, 0xffff0000, v113
	v_lshlrev_b32_e32 v36, 16, v114
	v_and_b32_e32 v37, 0xffff0000, v114
	v_lshlrev_b32_e32 v38, 16, v115
	v_and_b32_e32 v39, 0xffff0000, v115
	v_lshlrev_b32_e32 v40, 16, v116
	v_and_b32_e32 v41, 0xffff0000, v116
	v_lshlrev_b32_e32 v42, 16, v117
	v_and_b32_e32 v43, 0xffff0000, v117
	v_lshlrev_b32_e32 v44, 16, v118
	v_and_b32_e32 v45, 0xffff0000, v118
	v_lshlrev_b32_e32 v46, 16, v119
	v_and_b32_e32 v47, 0xffff0000, v119
	v_lshlrev_b32_e32 v48, 16, v120
	v_and_b32_e32 v49, 0xffff0000, v120
; __device__ __forceinline__ float bf_lo(unsigned w) { return __uint_as_float(w << 16); }
; __device__ __forceinline__ float bf_hi(unsigned w) { return __uint_as_float(w & 0xffff0000u); }
; template <bool BF> __device__ __forceinline__ void prep_rows(const float* xp, const float* xs, const bf16* hb, const float* g, const float* MOD, int shoff, int scoff, bf16* U, int gw, int NGW, int lane) {
;     ...
;                 if (BF) { const v2u a0 = *(const v2u*)(hb + (size_t)mc * DM + 4 * lane + 256 * j);
;                     v[r][j].x = pg8::bf_lo(a0.x); v[r][j].y = pg8::bf_hi(a0.x); v[r][j].z = pg8::bf_lo(a0.y); v[r][j].w = pg8::bf_hi(a0.y); }
;                 else { const float* xr = mc < MP ? xp + (size_t)mc * DM : xs + (size_t)(mc - MP) * DM; v[r][j] = *(const f32x4*)(xr + 4 * lane + 256 * j); } } }
; #pragma unroll
;         for (int r = 0; r < R; ++r) { float t = 0.f;
; #pragma unroll
;             for (int j = 0; j < 4; ++j) t += (v[r][j].x * v[r][j].x + v[r][j].y * v[r][j].y) + (v[r][j].z * v[r][j].z + v[r][j].w * v[r][j].w);
;             s[r] = t; }
; #pragma unroll
;         for (int o = 1; o < 64; o <<= 1) {
; #pragma unroll
;             for (int r = 0; r < R; ++r) s[r] += __shfl_xor(s[r], o); }
; #pragma unroll
;         for (int r = 0; r < R; ++r) { const int m = mb + r * NGW; if (m < MT) {
;             const float rstd = 1.0f / sqrtf(s[r] * (1.0f / DM) + RMS_EPS);
	v_lshlrev_b32_e32 v50, 16, v121
	v_and_b32_e32 v51, 0xffff0000, v121
	v_lshlrev_b32_e32 v52, 16, v122
	v_and_b32_e32 v53, 0xffff0000, v122
	v_lshlrev_b32_e32 v54, 16, v123
	v_and_b32_e32 v55, 0xffff0000, v123
	v_lshlrev_b32_e32 v56, 16, v124
	v_and_b32_e32 v57, 0xffff0000, v124
	v_lshlrev_b32_e32 v58, 16, v125
	v_and_b32_e32 v59, 0xffff0000, v125
	v_lshlrev_b32_e32 v60, 16, v126
	v_and_b32_e32 v61, 0xffff0000, v126
	v_lshlrev_b32_e32 v62, 16, v127
	v_and_b32_e32 v63, 0xffff0000, v127
	v_pk_mul_f32 v[240:241], v[0:1], v[0:1]
	v_pk_mul_f32 v[242:243], v[16:17], v[16:17]
	v_pk_mul_f32 v[244:245], v[32:33], v[32:33]
	v_pk_mul_f32 v[246:247], v[48:49], v[48:49]
	v_pk_fma_f32 v[240:241], v[2:3], v[2:3], v[240:241]
	v_pk_fma_f32 v[242:243], v[18:19], v[18:19], v[242:243]
	v_pk_fma_f32 v[244:245], v[34:35], v[34:35], v[244:245]
	v_pk_fma_f32 v[246:247], v[50:51], v[50:51], v[246:247]
	v_pk_fma_f32 v[240:241], v[4:5], v[4:5], v[240:241]
	v_pk_fma_f32 v[242:243], v[20:21], v[20:21], v[242:243]
	v_pk_fma_f32 v[244:245], v[36:37], v[36:37], v[244:245]
	v_pk_fma_f32 v[246:247], v[52:53], v[52:53], v[246:247]
	v_pk_fma_f32 v[240:241], v[6:7], v[6:7], v[240:241]
	v_pk_fma_f32 v[242:243], v[22:23], v[22:23], v[242:243]
	v_pk_fma_f32 v[244:245], v[38:39], v[38:39], v[244:245]
	v_pk_fma_f32 v[246:247], v[54:55], v[54:55], v[246:247]
	v_pk_fma_f32 v[240:241], v[8:9], v[8:9], v[240:241]
	v_pk_fma_f32 v[242:243], v[24:25], v[24:25], v[242:243]
	v_pk_fma_f32 v[244:245], v[40:41], v[40:41], v[244:245]
	v_pk_fma_f32 v[246:247], v[56:57], v[56:57], v[246:247]
	v_pk_fma_f32 v[240:241], v[10:11], v[10:11], v[240:241]
	v_pk_fma_f32 v[242:243], v[26:27], v[26:27], v[242:243]
	v_pk_fma_f32 v[244:245], v[42:43], v[42:43], v[244:245]
	v_pk_fma_f32 v[246:247], v[58:59], v[58:59], v[246:247]
	v_pk_fma_f32 v[240:241], v[12:13], v[12:13], v[240:241]
	v_pk_fma_f32 v[242:243], v[28:29], v[28:29], v[242:243]
	v_pk_fma_f32 v[244:245], v[44:45], v[44:45], v[244:245]
	v_pk_fma_f32 v[246:247], v[60:61], v[60:61], v[246:247]
	v_pk_fma_f32 v[240:241], v[14:15], v[14:15], v[240:241]
	v_pk_fma_f32 v[242:243], v[30:31], v[30:31], v[242:243]
	v_pk_fma_f32 v[244:245], v[46:47], v[46:47], v[244:245]
	v_pk_fma_f32 v[246:247], v[62:63], v[62:63], v[246:247]
	v_add_f32_e32 v224, v240, v241
	v_add_f32_e32 v225, v242, v243
	v_add_f32_e32 v226, v244, v245
	v_add_f32_e32 v227, v246, v247
	ds_bpermute_b32 v228, v83, v224
	ds_bpermute_b32 v229, v83, v225
	ds_bpermute_b32 v230, v83, v226
	ds_bpermute_b32 v231, v83, v227
	s_waitcnt lgkmcnt(0)
	v_add_f32_e32 v224, v224, v228
	v_add_f32_e32 v225, v225, v229
	v_add_f32_e32 v226, v226, v230
	v_add_f32_e32 v227, v227, v231
	ds_bpermute_b32 v228, v84, v224
	ds_bpermute_b32 v229, v84, v225
	ds_bpermute_b32 v230, v84, v226
	ds_bpermute_b32 v231, v84, v227
	s_waitcnt lgkmcnt(0)
	v_add_f32_e32 v224, v224, v228
	v_add_f32_e32 v225, v225, v229
	v_add_f32_e32 v226, v226, v230
	v_add_f32_e32 v227, v227, v231
	ds_bpermute_b32 v228, v85, v224
	ds_bpermute_b32 v229, v85, v225
	ds_bpermute_b32 v230, v85, v226
	ds_bpermute_b32 v231, v85, v227
	s_waitcnt lgkmcnt(0)
	v_add_f32_e32 v224, v224, v228
	v_add_f32_e32 v225, v225, v229
	v_add_f32_e32 v226, v226, v230
	v_add_f32_e32 v227, v227, v231
	ds_bpermute_b32 v228, v86, v224
	ds_bpermute_b32 v229, v86, v225
	ds_bpermute_b32 v230, v86, v226
	ds_bpermute_b32 v231, v86, v227
	s_waitcnt lgkmcnt(0)
	v_add_f32_e32 v224, v224, v228
	v_add_f32_e32 v225, v225, v229
	v_add_f32_e32 v226, v226, v230
	v_add_f32_e32 v227, v227, v231
	ds_bpermute_b32 v228, v87, v224
	ds_bpermute_b32 v229, v87, v225
	ds_bpermute_b32 v230, v87, v226
	ds_bpermute_b32 v231, v87, v227
	s_waitcnt lgkmcnt(0)
	v_add_f32_e32 v224, v224, v228
	v_add_f32_e32 v225, v225, v229
	v_add_f32_e32 v226, v226, v230
	v_add_f32_e32 v227, v227, v231
	ds_bpermute_b32 v228, v88, v224
	ds_bpermute_b32 v229, v88, v225
	ds_bpermute_b32 v230, v88, v226
	ds_bpermute_b32 v231, v88, v227
	s_waitcnt lgkmcnt(0)
	v_add_f32_e32 v224, v224, v228
	v_add_f32_e32 v225, v225, v229
	v_add_f32_e32 v226, v226, v230
	v_add_f32_e32 v227, v227, v231
	v_fmamk_f32 v240, v224, 0x3a800000, v89
	v_mul_f32_e32 v241, 0x4f800000, v240
	v_cmp_gt_f32_e32 vcc, s54, v240
	s_nop 1
	v_cndmask_b32_e32 v247, v240, v241, vcc
	v_sqrt_f32_e32 v242, v247
	s_nop 1
	v_add_u32_e32 v243, -1, v242
	v_add_u32_e32 v244, 1, v242
	v_fma_f32 v245, -v243, v242, v247
	v_fma_f32 v246, -v244, v242, v247
	v_cmp_ge_f32_e64 s[52:53], 0, v245
	s_nop 1
	v_cndmask_b32_e64 v242, v242, v243, s[52:53]
	v_cmp_lt_f32_e64 s[52:53], 0, v246
	s_nop 1
	v_cndmask_b32_e64 v242, v242, v244, s[52:53]
	v_mul_f32_e32 v243, 0x37800000, v242
	v_cndmask_b32_e32 v242, v242, v243, vcc
	v_cmp_class_f32_e32 vcc, v247, v90
	s_nop 1
	v_cndmask_b32_e32 v247, v242, v247, vcc
	v_div_scale_f32 v248, s[52:53], v247, v247, 1.0
	v_rcp_f32_e32 v249, v248
	v_div_scale_f32 v228, vcc, 1.0, v247, 1.0
	s_nop 0
	v_fma_f32 v229, -v248, v249, 1.0
	v_fmac_f32_e32 v249, v229, v249
	v_mul_f32_e32 v230, v228, v249
	v_fma_f32 v229, -v248, v230, v228
	v_fmac_f32_e32 v230, v229, v249
	v_fma_f32 v248, -v248, v230, v228
	v_div_fmas_f32 v248, v248, v249, v230
	v_div_fixup_f32 v232, v248, v247, 1.0
	v_fmamk_f32 v240, v225, 0x3a800000, v89
	v_mul_f32_e32 v241, 0x4f800000, v240
	v_cmp_gt_f32_e32 vcc, s54, v240
	s_nop 1
	v_cndmask_b32_e32 v247, v240, v241, vcc
	v_sqrt_f32_e32 v242, v247
	s_nop 1
	v_add_u32_e32 v243, -1, v242
	v_add_u32_e32 v244, 1, v242
	v_fma_f32 v245, -v243, v242, v247
	v_fma_f32 v246, -v244, v242, v247
	v_cmp_ge_f32_e64 s[52:53], 0, v245
	s_nop 1
	v_cndmask_b32_e64 v242, v242, v243, s[52:53]
	v_cmp_lt_f32_e64 s[52:53], 0, v246
	s_nop 1
	v_cndmask_b32_e64 v242, v242, v244, s[52:53]
; __device__ __forceinline__ unsigned pk2(float lo, float hi) { return pg8::cvt_pk_bf16(lo, hi); }
; template <bool BF> __device__ __forceinline__ void prep_rows(const float* xp, const float* xs, const bf16* hb, const float* g, const float* MOD, int shoff, int scoff, bf16* U, int gw, int NGW, int lane) {
;     ...
;             const float rstd = 1.0f / sqrtf(s[r] * (1.0f / DM) + RMS_EPS);
;             const float* mr = MOD + (size_t)(m < MP ? (m >> 13) : 8 + ((m - MP) >> 12)) * 6144;
; #pragma unroll
;             for (int j = 0; j < 4; ++j) { const int c = 4 * lane + 256 * j;
;                 const f32x4 gg = *(const f32x4*)(g + c), sc = *(const f32x4*)(mr + scoff + c), sh = *(const f32x4*)(mr + shoff + c);
;                 const f32x4 o = v[r][j] * rstd * gg * (sc + 1.0f) + sh; v2u w; w.x = pk2(o.x, o.y); w.y = pk2(o.z, o.w); *(v2u*)(U + (size_t)m * DM + c) = w; } } }
	v_mul_f32_e32 v243, 0x37800000, v242
	v_cndmask_b32_e32 v242, v242, v243, vcc
	v_cmp_class_f32_e32 vcc, v247, v90
	s_nop 1
	v_cndmask_b32_e32 v247, v242, v247, vcc
	v_div_scale_f32 v248, s[52:53], v247, v247, 1.0
	v_rcp_f32_e32 v249, v248
	v_div_scale_f32 v228, vcc, 1.0, v247, 1.0
	s_nop 0
	v_fma_f32 v229, -v248, v249, 1.0
	v_fmac_f32_e32 v249, v229, v249
	v_mul_f32_e32 v230, v228, v249
	v_fma_f32 v229, -v248, v230, v228
	v_fmac_f32_e32 v230, v229, v249
	v_fma_f32 v248, -v248, v230, v228
	v_div_fmas_f32 v248, v248, v249, v230
	v_div_fixup_f32 v234, v248, v247, 1.0
	v_fmamk_f32 v240, v226, 0x3a800000, v89
	v_mul_f32_e32 v241, 0x4f800000, v240
	v_cmp_gt_f32_e32 vcc, s54, v240
	s_nop 1
	v_cndmask_b32_e32 v247, v240, v241, vcc
	v_sqrt_f32_e32 v242, v247
	s_nop 1
	v_add_u32_e32 v243, -1, v242
	v_add_u32_e32 v244, 1, v242
	v_fma_f32 v245, -v243, v242, v247
	v_fma_f32 v246, -v244, v242, v247
	v_cmp_ge_f32_e64 s[52:53], 0, v245
	s_nop 1
	v_cndmask_b32_e64 v242, v242, v243, s[52:53]
	v_cmp_lt_f32_e64 s[52:53], 0, v246
	s_nop 1
	v_cndmask_b32_e64 v242, v242, v244, s[52:53]
	v_mul_f32_e32 v243, 0x37800000, v242
	v_cndmask_b32_e32 v242, v242, v243, vcc
	v_cmp_class_f32_e32 vcc, v247, v90
	s_nop 1
	v_cndmask_b32_e32 v247, v242, v247, vcc
	v_div_scale_f32 v248, s[52:53], v247, v247, 1.0
	v_rcp_f32_e32 v249, v248
	v_div_scale_f32 v228, vcc, 1.0, v247, 1.0
	s_nop 0
	v_fma_f32 v229, -v248, v249, 1.0
	v_fmac_f32_e32 v249, v229, v249
	v_mul_f32_e32 v230, v228, v249
	v_fma_f32 v229, -v248, v230, v228
	v_fmac_f32_e32 v230, v229, v249
	v_fma_f32 v248, -v248, v230, v228
	v_div_fmas_f32 v248, v248, v249, v230
	v_div_fixup_f32 v236, v248, v247, 1.0
	v_fmamk_f32 v240, v227, 0x3a800000, v89
	v_mul_f32_e32 v241, 0x4f800000, v240
	v_cmp_gt_f32_e32 vcc, s54, v240
	s_nop 1
	v_cndmask_b32_e32 v247, v240, v241, vcc
	v_sqrt_f32_e32 v242, v247
	s_nop 1
	v_add_u32_e32 v243, -1, v242
	v_add_u32_e32 v244, 1, v242
	v_fma_f32 v245, -v243, v242, v247
	v_fma_f32 v246, -v244, v242, v247
	v_cmp_ge_f32_e64 s[52:53], 0, v245
	s_nop 1
	v_cndmask_b32_e64 v242, v242, v243, s[52:53]
	v_cmp_lt_f32_e64 s[52:53], 0, v246
	s_nop 1
	v_cndmask_b32_e64 v242, v242, v244, s[52:53]
	v_mul_f32_e32 v243, 0x37800000, v242
	v_cndmask_b32_e32 v242, v242, v243, vcc
	v_cmp_class_f32_e32 vcc, v247, v90
	s_nop 1
	v_cndmask_b32_e32 v247, v242, v247, vcc
	v_div_scale_f32 v248, s[52:53], v247, v247, 1.0
	v_rcp_f32_e32 v249, v248
	v_div_scale_f32 v228, vcc, 1.0, v247, 1.0
	s_nop 0
	v_fma_f32 v229, -v248, v249, 1.0
	v_fmac_f32_e32 v249, v229, v249
	v_mul_f32_e32 v230, v228, v249
	v_fma_f32 v229, -v248, v230, v228
	v_fmac_f32_e32 v230, v229, v249
	v_fma_f32 v248, -v248, v230, v228
	v_div_fmas_f32 v248, v248, v249, v230
	v_div_fixup_f32 v238, v248, v247, 1.0
	s_waitcnt vmcnt(8)
	v_pk_add_f32 v[160:161], v[160:161], 1.0 op_sel_hi:[1,0]
	v_pk_add_f32 v[162:163], v[162:163], 1.0 op_sel_hi:[1,0]
	v_pk_add_f32 v[164:165], v[164:165], 1.0 op_sel_hi:[1,0]
	v_pk_add_f32 v[166:167], v[166:167], 1.0 op_sel_hi:[1,0]
	v_pk_add_f32 v[168:169], v[168:169], 1.0 op_sel_hi:[1,0]
	v_pk_add_f32 v[170:171], v[170:171], 1.0 op_sel_hi:[1,0]
	v_pk_add_f32 v[172:173], v[172:173], 1.0 op_sel_hi:[1,0]
	v_pk_add_f32 v[174:175], v[174:175], 1.0 op_sel_hi:[1,0]
	v_pk_add_f32 v[192:193], v[192:193], 1.0 op_sel_hi:[1,0]
	v_pk_add_f32 v[194:195], v[194:195], 1.0 op_sel_hi:[1,0]
	v_pk_add_f32 v[196:197], v[196:197], 1.0 op_sel_hi:[1,0]
	v_pk_add_f32 v[198:199], v[198:199], 1.0 op_sel_hi:[1,0]
	v_pk_add_f32 v[200:201], v[200:201], 1.0 op_sel_hi:[1,0]
	v_pk_add_f32 v[202:203], v[202:203], 1.0 op_sel_hi:[1,0]
	v_pk_add_f32 v[204:205], v[204:205], 1.0 op_sel_hi:[1,0]
	v_pk_add_f32 v[206:207], v[206:207], 1.0 op_sel_hi:[1,0]
	s_add_u32 s38, s20, 0xa000000
	s_addc_u32 s39, s21, 0
	s_add_u32 s40, s20, 0xa400000
	s_addc_u32 s41, s21, 0
	s_add_u32 s46, s20, 0xa800000
	s_addc_u32 s47, s21, 0
	s_add_u32 s48, s20, 0xac00000
	s_addc_u32 s49, s21, 0
	v_pk_mul_f32 v[0:1], v[0:1], v[232:233] op_sel_hi:[1,0]
	v_pk_mul_f32 v[2:3], v[2:3], v[232:233] op_sel_hi:[1,0]
	v_pk_mul_f32 v[0:1], v[64:65], v[0:1]
	v_pk_mul_f32 v[2:3], v[66:67], v[2:3]
	v_pk_fma_f32 v[0:1], v[160:161], v[0:1], v[176:177]
	v_pk_fma_f32 v[2:3], v[162:163], v[2:3], v[178:179]
	v_cvt_pk_bf16_f32 v244, v0, v1
	v_cvt_pk_bf16_f32 v245, v2, v3
	v_pk_mul_f32 v[4:5], v[4:5], v[232:233] op_sel_hi:[1,0]
	v_pk_mul_f32 v[6:7], v[6:7], v[232:233] op_sel_hi:[1,0]
	v_pk_mul_f32 v[4:5], v[68:69], v[4:5]
	v_pk_mul_f32 v[6:7], v[70:71], v[6:7]
	v_pk_fma_f32 v[4:5], v[164:165], v[4:5], v[180:181]
	v_pk_fma_f32 v[6:7], v[166:167], v[6:7], v[182:183]
	v_cvt_pk_bf16_f32 v246, v4, v5
	v_cvt_pk_bf16_f32 v247, v6, v7
	global_store_dwordx4 v82, v[244:247], s[38:39] offset:0
	v_pk_mul_f32 v[8:9], v[8:9], v[232:233] op_sel_hi:[1,0]
	v_pk_mul_f32 v[10:11], v[10:11], v[232:233] op_sel_hi:[1,0]
	v_pk_mul_f32 v[8:9], v[72:73], v[8:9]
	v_pk_mul_f32 v[10:11], v[74:75], v[10:11]
	v_pk_fma_f32 v[8:9], v[168:169], v[8:9], v[184:185]
	v_pk_fma_f32 v[10:11], v[170:171], v[10:11], v[186:187]
	v_cvt_pk_bf16_f32 v240, v8, v9
	v_cvt_pk_bf16_f32 v241, v10, v11
	v_pk_mul_f32 v[12:13], v[12:13], v[232:233] op_sel_hi:[1,0]
	v_pk_mul_f32 v[14:15], v[14:15], v[232:233] op_sel_hi:[1,0]
	v_pk_mul_f32 v[12:13], v[76:77], v[12:13]
	v_pk_mul_f32 v[14:15], v[78:79], v[14:15]
	v_pk_fma_f32 v[12:13], v[172:173], v[12:13], v[188:189]
	v_pk_fma_f32 v[14:15], v[174:175], v[14:15], v[190:191]
	v_cvt_pk_bf16_f32 v242, v12, v13
	v_cvt_pk_bf16_f32 v243, v14, v15
	global_store_dwordx4 v82, v[240:243], s[38:39] offset:1024
	v_pk_mul_f32 v[16:17], v[16:17], v[234:235] op_sel_hi:[1,0]
	v_pk_mul_f32 v[18:19], v[18:19], v[234:235] op_sel_hi:[1,0]
; __device__ __forceinline__ unsigned pk2(float lo, float hi) { return pg8::cvt_pk_bf16(lo, hi); }
; template <bool BF> __device__ __forceinline__ void prep_rows(const float* xp, const float* xs, const bf16* hb, const float* g, const float* MOD, int shoff, int scoff, bf16* U, int gw, int NGW, int lane) {
;     ...
;             for (int j = 0; j < 4; ++j) { const int c = 4 * lane + 256 * j;
;                 const f32x4 gg = *(const f32x4*)(g + c), sc = *(const f32x4*)(mr + scoff + c), sh = *(const f32x4*)(mr + shoff + c);
;                 const f32x4 o = v[r][j] * rstd * gg * (sc + 1.0f) + sh; v2u w; w.x = pk2(o.x, o.y); w.y = pk2(o.z, o.w); *(v2u*)(U + (size_t)m * DM + c) = w; } } }
	v_pk_mul_f32 v[16:17], v[64:65], v[16:17]
	v_pk_mul_f32 v[18:19], v[66:67], v[18:19]
	v_pk_fma_f32 v[16:17], v[160:161], v[16:17], v[176:177]
	v_pk_fma_f32 v[18:19], v[162:163], v[18:19], v[178:179]
	v_cvt_pk_bf16_f32 v244, v16, v17
	v_cvt_pk_bf16_f32 v245, v18, v19
	v_pk_mul_f32 v[20:21], v[20:21], v[234:235] op_sel_hi:[1,0]
	v_pk_mul_f32 v[22:23], v[22:23], v[234:235] op_sel_hi:[1,0]
	v_pk_mul_f32 v[20:21], v[68:69], v[20:21]
	v_pk_mul_f32 v[22:23], v[70:71], v[22:23]
	v_pk_fma_f32 v[20:21], v[164:165], v[20:21], v[180:181]
	v_pk_fma_f32 v[22:23], v[166:167], v[22:23], v[182:183]
	v_cvt_pk_bf16_f32 v246, v20, v21
	v_cvt_pk_bf16_f32 v247, v22, v23
	global_store_dwordx4 v82, v[244:247], s[40:41] offset:0
	v_pk_mul_f32 v[24:25], v[24:25], v[234:235] op_sel_hi:[1,0]
	v_pk_mul_f32 v[26:27], v[26:27], v[234:235] op_sel_hi:[1,0]
	v_pk_mul_f32 v[24:25], v[72:73], v[24:25]
	v_pk_mul_f32 v[26:27], v[74:75], v[26:27]
	v_pk_fma_f32 v[24:25], v[168:169], v[24:25], v[184:185]
	v_pk_fma_f32 v[26:27], v[170:171], v[26:27], v[186:187]
	v_cvt_pk_bf16_f32 v240, v24, v25
	v_cvt_pk_bf16_f32 v241, v26, v27
	v_pk_mul_f32 v[28:29], v[28:29], v[234:235] op_sel_hi:[1,0]
	v_pk_mul_f32 v[30:31], v[30:31], v[234:235] op_sel_hi:[1,0]
	v_pk_mul_f32 v[28:29], v[76:77], v[28:29]
	v_pk_mul_f32 v[30:31], v[78:79], v[30:31]
	v_pk_fma_f32 v[28:29], v[172:173], v[28:29], v[188:189]
	v_pk_fma_f32 v[30:31], v[174:175], v[30:31], v[190:191]
	v_cvt_pk_bf16_f32 v242, v28, v29
	v_cvt_pk_bf16_f32 v243, v30, v31
	global_store_dwordx4 v82, v[240:243], s[40:41] offset:1024
	v_pk_mul_f32 v[32:33], v[32:33], v[236:237] op_sel_hi:[1,0]
	v_pk_mul_f32 v[34:35], v[34:35], v[236:237] op_sel_hi:[1,0]
	v_pk_mul_f32 v[32:33], v[64:65], v[32:33]
	v_pk_mul_f32 v[34:35], v[66:67], v[34:35]
	v_pk_fma_f32 v[32:33], v[192:193], v[32:33], v[208:209]
	v_pk_fma_f32 v[34:35], v[194:195], v[34:35], v[210:211]
	v_cvt_pk_bf16_f32 v244, v32, v33
	v_cvt_pk_bf16_f32 v245, v34, v35
	v_pk_mul_f32 v[36:37], v[36:37], v[236:237] op_sel_hi:[1,0]
	v_pk_mul_f32 v[38:39], v[38:39], v[236:237] op_sel_hi:[1,0]
	v_pk_mul_f32 v[36:37], v[68:69], v[36:37]
	v_pk_mul_f32 v[38:39], v[70:71], v[38:39]
	v_pk_fma_f32 v[36:37], v[196:197], v[36:37], v[212:213]
	v_pk_fma_f32 v[38:39], v[198:199], v[38:39], v[214:215]
	v_cvt_pk_bf16_f32 v246, v36, v37
	v_cvt_pk_bf16_f32 v247, v38, v39
	global_store_dwordx4 v82, v[244:247], s[46:47] offset:0
	v_pk_mul_f32 v[40:41], v[40:41], v[236:237] op_sel_hi:[1,0]
	v_pk_mul_f32 v[42:43], v[42:43], v[236:237] op_sel_hi:[1,0]
	v_pk_mul_f32 v[40:41], v[72:73], v[40:41]
	v_pk_mul_f32 v[42:43], v[74:75], v[42:43]
	v_pk_fma_f32 v[40:41], v[200:201], v[40:41], v[216:217]
	v_pk_fma_f32 v[42:43], v[202:203], v[42:43], v[218:219]
	v_cvt_pk_bf16_f32 v240, v40, v41
	v_cvt_pk_bf16_f32 v241, v42, v43
	v_pk_mul_f32 v[44:45], v[44:45], v[236:237] op_sel_hi:[1,0]
	v_pk_mul_f32 v[46:47], v[46:47], v[236:237] op_sel_hi:[1,0]
	v_pk_mul_f32 v[44:45], v[76:77], v[44:45]
	v_pk_mul_f32 v[46:47], v[78:79], v[46:47]
	v_pk_fma_f32 v[44:45], v[204:205], v[44:45], v[220:221]
	v_pk_fma_f32 v[46:47], v[206:207], v[46:47], v[222:223]
	v_cvt_pk_bf16_f32 v242, v44, v45
	v_cvt_pk_bf16_f32 v243, v46, v47
	global_store_dwordx4 v82, v[240:243], s[46:47] offset:1024
	v_pk_mul_f32 v[48:49], v[48:49], v[238:239] op_sel_hi:[1,0]
	v_pk_mul_f32 v[50:51], v[50:51], v[238:239] op_sel_hi:[1,0]
	v_pk_mul_f32 v[48:49], v[64:65], v[48:49]
	v_pk_mul_f32 v[50:51], v[66:67], v[50:51]
	v_pk_fma_f32 v[48:49], v[192:193], v[48:49], v[208:209]
	v_pk_fma_f32 v[50:51], v[194:195], v[50:51], v[210:211]
	v_cvt_pk_bf16_f32 v244, v48, v49
	v_cvt_pk_bf16_f32 v245, v50, v51
	v_pk_mul_f32 v[52:53], v[52:53], v[238:239] op_sel_hi:[1,0]
	v_pk_mul_f32 v[54:55], v[54:55], v[238:239] op_sel_hi:[1,0]
	v_pk_mul_f32 v[52:53], v[68:69], v[52:53]
	v_pk_mul_f32 v[54:55], v[70:71], v[54:55]
	v_pk_fma_f32 v[52:53], v[196:197], v[52:53], v[212:213]
	v_pk_fma_f32 v[54:55], v[198:199], v[54:55], v[214:215]
	v_cvt_pk_bf16_f32 v246, v52, v53
	v_cvt_pk_bf16_f32 v247, v54, v55
	global_store_dwordx4 v82, v[244:247], s[48:49] offset:0
	v_pk_mul_f32 v[56:57], v[56:57], v[238:239] op_sel_hi:[1,0]
	v_pk_mul_f32 v[58:59], v[58:59], v[238:239] op_sel_hi:[1,0]
	v_pk_mul_f32 v[56:57], v[72:73], v[56:57]
	v_pk_mul_f32 v[58:59], v[74:75], v[58:59]
	v_pk_fma_f32 v[56:57], v[200:201], v[56:57], v[216:217]
	v_pk_fma_f32 v[58:59], v[202:203], v[58:59], v[218:219]
	v_cvt_pk_bf16_f32 v240, v56, v57
	v_cvt_pk_bf16_f32 v241, v58, v59
	v_pk_mul_f32 v[60:61], v[60:61], v[238:239] op_sel_hi:[1,0]
	v_pk_mul_f32 v[62:63], v[62:63], v[238:239] op_sel_hi:[1,0]
	v_pk_mul_f32 v[60:61], v[76:77], v[60:61]
	v_pk_mul_f32 v[62:63], v[78:79], v[62:63]
	v_pk_fma_f32 v[60:61], v[204:205], v[60:61], v[220:221]
	v_pk_fma_f32 v[62:63], v[206:207], v[62:63], v[222:223]
	v_cvt_pk_bf16_f32 v242, v60, v61
	v_cvt_pk_bf16_f32 v243, v62, v63
	global_store_dwordx4 v82, v[240:243], s[48:49] offset:1024
	s_add_u32 s34, s8, 0x57000
	s_addc_u32 s35, s9, 0
	s_add_u32 s36, s8, 0x5d000
	s_addc_u32 s37, s9, 0
	global_load_dwordx4 v[176:179], v80, s[34:35] offset:0
	global_load_dwordx4 v[180:183], v80, s[34:35] offset:16
	global_load_dwordx4 v[184:187], v80, s[34:35] offset:2048
	global_load_dwordx4 v[188:191], v80, s[34:35] offset:2064
	global_load_dwordx4 v[160:163], v81, s[34:35] offset:0
	global_load_dwordx4 v[164:167], v81, s[34:35] offset:16
	global_load_dwordx4 v[168:171], v81, s[34:35] offset:2048
	global_load_dwordx4 v[172:175], v81, s[34:35] offset:2064
	global_load_dwordx4 v[208:211], v80, s[36:37] offset:0
	global_load_dwordx4 v[212:215], v80, s[36:37] offset:16
	global_load_dwordx4 v[216:219], v80, s[36:37] offset:2048
	global_load_dwordx4 v[220:223], v80, s[36:37] offset:2064
	global_load_dwordx4 v[192:195], v81, s[36:37] offset:0
	global_load_dwordx4 v[196:199], v81, s[36:37] offset:16
	global_load_dwordx4 v[200:203], v81, s[36:37] offset:2048
	global_load_dwordx4 v[204:207], v81, s[36:37] offset:2064
	s_waitcnt vmcnt(24)
; __device__ __forceinline__ float bf_lo(unsigned w) { return __uint_as_float(w << 16); }
; __device__ __forceinline__ float bf_hi(unsigned w) { return __uint_as_float(w & 0xffff0000u); }
; template <bool BF> __device__ __forceinline__ void prep_rows(const float* xp, const float* xs, const bf16* hb, const float* g, const float* MOD, int shoff, int scoff, bf16* U, int gw, int NGW, int lane) {
;     ...
;                 if (BF) { const v2u a0 = *(const v2u*)(hb + (size_t)mc * DM + 4 * lane + 256 * j);
;                     v[r][j].x = pg8::bf_lo(a0.x); v[r][j].y = pg8::bf_hi(a0.x); v[r][j].z = pg8::bf_lo(a0.y); v[r][j].w = pg8::bf_hi(a0.y); }
;                 else { const float* xr = mc < MP ? xp + (size_t)mc * DM : xs + (size_t)(mc - MP) * DM; v[r][j] = *(const f32x4*)(xr + 4 * lane + 256 * j); } } }
; #pragma unroll
;         for (int r = 0; r < R; ++r) { float t = 0.f;
; #pragma unroll
;             for (int j = 0; j < 4; ++j) t += (v[r][j].x * v[r][j].x + v[r][j].y * v[r][j].y) + (v[r][j].z * v[r][j].z + v[r][j].w * v[r][j].w);
;             s[r] = t; }
; #pragma unroll
;         for (int o = 1; o < 64; o <<= 1) {
; #pragma unroll
;             for (int r = 0; r < R; ++r) s[r] += __shfl_xor(s[r], o); }
	v_lshlrev_b32_e32 v0, 16, v128
	v_and_b32_e32 v1, 0xffff0000, v128
	v_lshlrev_b32_e32 v2, 16, v129
	v_and_b32_e32 v3, 0xffff0000, v129
	v_lshlrev_b32_e32 v4, 16, v130
	v_and_b32_e32 v5, 0xffff0000, v130
	v_lshlrev_b32_e32 v6, 16, v131
	v_and_b32_e32 v7, 0xffff0000, v131
	v_lshlrev_b32_e32 v8, 16, v132
	v_and_b32_e32 v9, 0xffff0000, v132
	v_lshlrev_b32_e32 v10, 16, v133
	v_and_b32_e32 v11, 0xffff0000, v133
	v_lshlrev_b32_e32 v12, 16, v134
	v_and_b32_e32 v13, 0xffff0000, v134
	v_lshlrev_b32_e32 v14, 16, v135
	v_and_b32_e32 v15, 0xffff0000, v135
	v_lshlrev_b32_e32 v16, 16, v136
	v_and_b32_e32 v17, 0xffff0000, v136
	v_lshlrev_b32_e32 v18, 16, v137
	v_and_b32_e32 v19, 0xffff0000, v137
	v_lshlrev_b32_e32 v20, 16, v138
	v_and_b32_e32 v21, 0xffff0000, v138
	v_lshlrev_b32_e32 v22, 16, v139
	v_and_b32_e32 v23, 0xffff0000, v139
	v_lshlrev_b32_e32 v24, 16, v140
	v_and_b32_e32 v25, 0xffff0000, v140
	v_lshlrev_b32_e32 v26, 16, v141
	v_and_b32_e32 v27, 0xffff0000, v141
	v_lshlrev_b32_e32 v28, 16, v142
	v_and_b32_e32 v29, 0xffff0000, v142
	v_lshlrev_b32_e32 v30, 16, v143
	v_and_b32_e32 v31, 0xffff0000, v143
	v_lshlrev_b32_e32 v32, 16, v144
	v_and_b32_e32 v33, 0xffff0000, v144
	v_lshlrev_b32_e32 v34, 16, v145
	v_and_b32_e32 v35, 0xffff0000, v145
	v_lshlrev_b32_e32 v36, 16, v146
	v_and_b32_e32 v37, 0xffff0000, v146
	v_lshlrev_b32_e32 v38, 16, v147
	v_and_b32_e32 v39, 0xffff0000, v147
	v_lshlrev_b32_e32 v40, 16, v148
	v_and_b32_e32 v41, 0xffff0000, v148
	v_lshlrev_b32_e32 v42, 16, v149
	v_and_b32_e32 v43, 0xffff0000, v149
	v_lshlrev_b32_e32 v44, 16, v150
	v_and_b32_e32 v45, 0xffff0000, v150
	v_lshlrev_b32_e32 v46, 16, v151
	v_and_b32_e32 v47, 0xffff0000, v151
	v_lshlrev_b32_e32 v48, 16, v152
	v_and_b32_e32 v49, 0xffff0000, v152
	v_lshlrev_b32_e32 v50, 16, v153
	v_and_b32_e32 v51, 0xffff0000, v153
	v_lshlrev_b32_e32 v52, 16, v154
	v_and_b32_e32 v53, 0xffff0000, v154
	v_lshlrev_b32_e32 v54, 16, v155
	v_and_b32_e32 v55, 0xffff0000, v155
	v_lshlrev_b32_e32 v56, 16, v156
	v_and_b32_e32 v57, 0xffff0000, v156
	v_lshlrev_b32_e32 v58, 16, v157
	v_and_b32_e32 v59, 0xffff0000, v157
	v_lshlrev_b32_e32 v60, 16, v158
	v_and_b32_e32 v61, 0xffff0000, v158
	v_lshlrev_b32_e32 v62, 16, v159
	v_and_b32_e32 v63, 0xffff0000, v159
	v_pk_mul_f32 v[240:241], v[0:1], v[0:1]
	v_pk_mul_f32 v[242:243], v[16:17], v[16:17]
	v_pk_mul_f32 v[244:245], v[32:33], v[32:33]
	v_pk_mul_f32 v[246:247], v[48:49], v[48:49]
	v_pk_fma_f32 v[240:241], v[2:3], v[2:3], v[240:241]
	v_pk_fma_f32 v[242:243], v[18:19], v[18:19], v[242:243]
	v_pk_fma_f32 v[244:245], v[34:35], v[34:35], v[244:245]
	v_pk_fma_f32 v[246:247], v[50:51], v[50:51], v[246:247]
	v_pk_fma_f32 v[240:241], v[4:5], v[4:5], v[240:241]
	v_pk_fma_f32 v[242:243], v[20:21], v[20:21], v[242:243]
	v_pk_fma_f32 v[244:245], v[36:37], v[36:37], v[244:245]
	v_pk_fma_f32 v[246:247], v[52:53], v[52:53], v[246:247]
	v_pk_fma_f32 v[240:241], v[6:7], v[6:7], v[240:241]
	v_pk_fma_f32 v[242:243], v[22:23], v[22:23], v[242:243]
	v_pk_fma_f32 v[244:245], v[38:39], v[38:39], v[244:245]
	v_pk_fma_f32 v[246:247], v[54:55], v[54:55], v[246:247]
	v_pk_fma_f32 v[240:241], v[8:9], v[8:9], v[240:241]
	v_pk_fma_f32 v[242:243], v[24:25], v[24:25], v[242:243]
	v_pk_fma_f32 v[244:245], v[40:41], v[40:41], v[244:245]
	v_pk_fma_f32 v[246:247], v[56:57], v[56:57], v[246:247]
	v_pk_fma_f32 v[240:241], v[10:11], v[10:11], v[240:241]
	v_pk_fma_f32 v[242:243], v[26:27], v[26:27], v[242:243]
	v_pk_fma_f32 v[244:245], v[42:43], v[42:43], v[244:245]
	v_pk_fma_f32 v[246:247], v[58:59], v[58:59], v[246:247]
	v_pk_fma_f32 v[240:241], v[12:13], v[12:13], v[240:241]
	v_pk_fma_f32 v[242:243], v[28:29], v[28:29], v[242:243]
	v_pk_fma_f32 v[244:245], v[44:45], v[44:45], v[244:245]
	v_pk_fma_f32 v[246:247], v[60:61], v[60:61], v[246:247]
	v_pk_fma_f32 v[240:241], v[14:15], v[14:15], v[240:241]
	v_pk_fma_f32 v[242:243], v[30:31], v[30:31], v[242:243]
	v_pk_fma_f32 v[244:245], v[46:47], v[46:47], v[244:245]
	v_pk_fma_f32 v[246:247], v[62:63], v[62:63], v[246:247]
	v_add_f32_e32 v224, v240, v241
	v_add_f32_e32 v225, v242, v243
	v_add_f32_e32 v226, v244, v245
	v_add_f32_e32 v227, v246, v247
	ds_bpermute_b32 v228, v83, v224
	ds_bpermute_b32 v229, v83, v225
	ds_bpermute_b32 v230, v83, v226
	ds_bpermute_b32 v231, v83, v227
	s_waitcnt lgkmcnt(0)
	v_add_f32_e32 v224, v224, v228
	v_add_f32_e32 v225, v225, v229
	v_add_f32_e32 v226, v226, v230
	v_add_f32_e32 v227, v227, v231
	ds_bpermute_b32 v228, v84, v224
	ds_bpermute_b32 v229, v84, v225
	ds_bpermute_b32 v230, v84, v226
	ds_bpermute_b32 v231, v84, v227
	s_waitcnt lgkmcnt(0)
	v_add_f32_e32 v224, v224, v228
	v_add_f32_e32 v225, v225, v229
	v_add_f32_e32 v226, v226, v230
	v_add_f32_e32 v227, v227, v231
	ds_bpermute_b32 v228, v85, v224
	ds_bpermute_b32 v229, v85, v225
	ds_bpermute_b32 v230, v85, v226
	ds_bpermute_b32 v231, v85, v227
	s_waitcnt lgkmcnt(0)
	v_add_f32_e32 v224, v224, v228
	v_add_f32_e32 v225, v225, v229
	v_add_f32_e32 v226, v226, v230
	v_add_f32_e32 v227, v227, v231
	ds_bpermute_b32 v228, v86, v224
	ds_bpermute_b32 v229, v86, v225
	ds_bpermute_b32 v230, v86, v226
	ds_bpermute_b32 v231, v86, v227
	s_waitcnt lgkmcnt(0)
	v_add_f32_e32 v224, v224, v228
	v_add_f32_e32 v225, v225, v229
	v_add_f32_e32 v226, v226, v230
	v_add_f32_e32 v227, v227, v231
	ds_bpermute_b32 v228, v87, v224
	ds_bpermute_b32 v229, v87, v225
	ds_bpermute_b32 v230, v87, v226
	ds_bpermute_b32 v231, v87, v227
	s_waitcnt lgkmcnt(0)
	v_add_f32_e32 v224, v224, v228
	v_add_f32_e32 v225, v225, v229
	v_add_f32_e32 v226, v226, v230
	v_add_f32_e32 v227, v227, v231
	ds_bpermute_b32 v228, v88, v224
	ds_bpermute_b32 v229, v88, v225
	ds_bpermute_b32 v230, v88, v226
	ds_bpermute_b32 v231, v88, v227
	s_waitcnt lgkmcnt(0)
; template <bool BF> __device__ __forceinline__ void prep_rows(const float* xp, const float* xs, const bf16* hb, const float* g, const float* MOD, int shoff, int scoff, bf16* U, int gw, int NGW, int lane) {
;     ...
;             for (int r = 0; r < R; ++r) s[r] += __shfl_xor(s[r], o); }
; #pragma unroll
;         for (int r = 0; r < R; ++r) { const int m = mb + r * NGW; if (m < MT) {
;             const float rstd = 1.0f / sqrtf(s[r] * (1.0f / DM) + RMS_EPS);
	v_add_f32_e32 v224, v224, v228
	v_add_f32_e32 v225, v225, v229
	v_add_f32_e32 v226, v226, v230
	v_add_f32_e32 v227, v227, v231
	v_fmamk_f32 v240, v224, 0x3a800000, v89
	v_mul_f32_e32 v241, 0x4f800000, v240
	v_cmp_gt_f32_e32 vcc, s54, v240
	s_nop 1
	v_cndmask_b32_e32 v247, v240, v241, vcc
	v_sqrt_f32_e32 v242, v247
	s_nop 1
	v_add_u32_e32 v243, -1, v242
	v_add_u32_e32 v244, 1, v242
	v_fma_f32 v245, -v243, v242, v247
	v_fma_f32 v246, -v244, v242, v247
	v_cmp_ge_f32_e64 s[52:53], 0, v245
	s_nop 1
	v_cndmask_b32_e64 v242, v242, v243, s[52:53]
	v_cmp_lt_f32_e64 s[52:53], 0, v246
	s_nop 1
	v_cndmask_b32_e64 v242, v242, v244, s[52:53]
	v_mul_f32_e32 v243, 0x37800000, v242
	v_cndmask_b32_e32 v242, v242, v243, vcc
	v_cmp_class_f32_e32 vcc, v247, v90
	s_nop 1
	v_cndmask_b32_e32 v247, v242, v247, vcc
	v_div_scale_f32 v248, s[52:53], v247, v247, 1.0
	v_rcp_f32_e32 v249, v248
	v_div_scale_f32 v228, vcc, 1.0, v247, 1.0
	s_nop 0
	v_fma_f32 v229, -v248, v249, 1.0
	v_fmac_f32_e32 v249, v229, v249
	v_mul_f32_e32 v230, v228, v249
	v_fma_f32 v229, -v248, v230, v228
	v_fmac_f32_e32 v230, v229, v249
	v_fma_f32 v248, -v248, v230, v228
	v_div_fmas_f32 v248, v248, v249, v230
	v_div_fixup_f32 v232, v248, v247, 1.0
	v_fmamk_f32 v240, v225, 0x3a800000, v89
	v_mul_f32_e32 v241, 0x4f800000, v240
	v_cmp_gt_f32_e32 vcc, s54, v240
	s_nop 1
	v_cndmask_b32_e32 v247, v240, v241, vcc
	v_sqrt_f32_e32 v242, v247
	s_nop 1
	v_add_u32_e32 v243, -1, v242
	v_add_u32_e32 v244, 1, v242
	v_fma_f32 v245, -v243, v242, v247
	v_fma_f32 v246, -v244, v242, v247
	v_cmp_ge_f32_e64 s[52:53], 0, v245
	s_nop 1
	v_cndmask_b32_e64 v242, v242, v243, s[52:53]
	v_cmp_lt_f32_e64 s[52:53], 0, v246
	s_nop 1
	v_cndmask_b32_e64 v242, v242, v244, s[52:53]
	v_mul_f32_e32 v243, 0x37800000, v242
	v_cndmask_b32_e32 v242, v242, v243, vcc
	v_cmp_class_f32_e32 vcc, v247, v90
	s_nop 1
	v_cndmask_b32_e32 v247, v242, v247, vcc
	v_div_scale_f32 v248, s[52:53], v247, v247, 1.0
	v_rcp_f32_e32 v249, v248
	v_div_scale_f32 v228, vcc, 1.0, v247, 1.0
	s_nop 0
	v_fma_f32 v229, -v248, v249, 1.0
	v_fmac_f32_e32 v249, v229, v249
	v_mul_f32_e32 v230, v228, v249
	v_fma_f32 v229, -v248, v230, v228
	v_fmac_f32_e32 v230, v229, v249
	v_fma_f32 v248, -v248, v230, v228
	v_div_fmas_f32 v248, v248, v249, v230
	v_div_fixup_f32 v234, v248, v247, 1.0
	v_fmamk_f32 v240, v226, 0x3a800000, v89
	v_mul_f32_e32 v241, 0x4f800000, v240
	v_cmp_gt_f32_e32 vcc, s54, v240
	s_nop 1
	v_cndmask_b32_e32 v247, v240, v241, vcc
	v_sqrt_f32_e32 v242, v247
	s_nop 1
	v_add_u32_e32 v243, -1, v242
	v_add_u32_e32 v244, 1, v242
	v_fma_f32 v245, -v243, v242, v247
	v_fma_f32 v246, -v244, v242, v247
	v_cmp_ge_f32_e64 s[52:53], 0, v245
	s_nop 1
	v_cndmask_b32_e64 v242, v242, v243, s[52:53]
	v_cmp_lt_f32_e64 s[52:53], 0, v246
	s_nop 1
	v_cndmask_b32_e64 v242, v242, v244, s[52:53]
	v_mul_f32_e32 v243, 0x37800000, v242
	v_cndmask_b32_e32 v242, v242, v243, vcc
	v_cmp_class_f32_e32 vcc, v247, v90
	s_nop 1
	v_cndmask_b32_e32 v247, v242, v247, vcc
	v_div_scale_f32 v248, s[52:53], v247, v247, 1.0
	v_rcp_f32_e32 v249, v248
	v_div_scale_f32 v228, vcc, 1.0, v247, 1.0
	s_nop 0
	v_fma_f32 v229, -v248, v249, 1.0
	v_fmac_f32_e32 v249, v229, v249
	v_mul_f32_e32 v230, v228, v249
	v_fma_f32 v229, -v248, v230, v228
	v_fmac_f32_e32 v230, v229, v249
	v_fma_f32 v248, -v248, v230, v228
	v_div_fmas_f32 v248, v248, v249, v230
	v_div_fixup_f32 v236, v248, v247, 1.0
	v_fmamk_f32 v240, v227, 0x3a800000, v89
	v_mul_f32_e32 v241, 0x4f800000, v240
	v_cmp_gt_f32_e32 vcc, s54, v240
	s_nop 1
	v_cndmask_b32_e32 v247, v240, v241, vcc
	v_sqrt_f32_e32 v242, v247
	s_nop 1
	v_add_u32_e32 v243, -1, v242
	v_add_u32_e32 v244, 1, v242
	v_fma_f32 v245, -v243, v242, v247
	v_fma_f32 v246, -v244, v242, v247
	v_cmp_ge_f32_e64 s[52:53], 0, v245
	s_nop 1
	v_cndmask_b32_e64 v242, v242, v243, s[52:53]
	v_cmp_lt_f32_e64 s[52:53], 0, v246
	s_nop 1
	v_cndmask_b32_e64 v242, v242, v244, s[52:53]
	v_mul_f32_e32 v243, 0x37800000, v242
	v_cndmask_b32_e32 v242, v242, v243, vcc
	v_cmp_class_f32_e32 vcc, v247, v90
	s_nop 1
	v_cndmask_b32_e32 v247, v242, v247, vcc
	v_div_scale_f32 v248, s[52:53], v247, v247, 1.0
	v_rcp_f32_e32 v249, v248
	v_div_scale_f32 v228, vcc, 1.0, v247, 1.0
	s_nop 0
	v_fma_f32 v229, -v248, v249, 1.0
	v_fmac_f32_e32 v249, v229, v249
	v_mul_f32_e32 v230, v228, v249
	v_fma_f32 v229, -v248, v230, v228
	v_fmac_f32_e32 v230, v229, v249
	v_fma_f32 v248, -v248, v230, v228
	v_div_fmas_f32 v248, v248, v249, v230
	v_div_fixup_f32 v238, v248, v247, 1.0
	s_waitcnt vmcnt(0)
; __device__ __forceinline__ unsigned pk2(float lo, float hi) { return pg8::cvt_pk_bf16(lo, hi); }
; template <bool BF> __device__ __forceinline__ void prep_rows(const float* xp, const float* xs, const bf16* hb, const float* g, const float* MOD, int shoff, int scoff, bf16* U, int gw, int NGW, int lane) {
;     ...
;             const float* mr = MOD + (size_t)(m < MP ? (m >> 13) : 8 + ((m - MP) >> 12)) * 6144;
; #pragma unroll
;             for (int j = 0; j < 4; ++j) { const int c = 4 * lane + 256 * j;
;                 const f32x4 gg = *(const f32x4*)(g + c), sc = *(const f32x4*)(mr + scoff + c), sh = *(const f32x4*)(mr + shoff + c);
;                 const f32x4 o = v[r][j] * rstd * gg * (sc + 1.0f) + sh; v2u w; w.x = pk2(o.x, o.y); w.y = pk2(o.z, o.w); *(v2u*)(U + (size_t)m * DM + c) = w; } } }
	v_pk_add_f32 v[160:161], v[160:161], 1.0 op_sel_hi:[1,0]
	v_pk_add_f32 v[162:163], v[162:163], 1.0 op_sel_hi:[1,0]
	v_pk_add_f32 v[164:165], v[164:165], 1.0 op_sel_hi:[1,0]
	v_pk_add_f32 v[166:167], v[166:167], 1.0 op_sel_hi:[1,0]
	v_pk_add_f32 v[168:169], v[168:169], 1.0 op_sel_hi:[1,0]
	v_pk_add_f32 v[170:171], v[170:171], 1.0 op_sel_hi:[1,0]
	v_pk_add_f32 v[172:173], v[172:173], 1.0 op_sel_hi:[1,0]
	v_pk_add_f32 v[174:175], v[174:175], 1.0 op_sel_hi:[1,0]
	v_pk_add_f32 v[192:193], v[192:193], 1.0 op_sel_hi:[1,0]
	v_pk_add_f32 v[194:195], v[194:195], 1.0 op_sel_hi:[1,0]
	v_pk_add_f32 v[196:197], v[196:197], 1.0 op_sel_hi:[1,0]
	v_pk_add_f32 v[198:199], v[198:199], 1.0 op_sel_hi:[1,0]
	v_pk_add_f32 v[200:201], v[200:201], 1.0 op_sel_hi:[1,0]
	v_pk_add_f32 v[202:203], v[202:203], 1.0 op_sel_hi:[1,0]
	v_pk_add_f32 v[204:205], v[204:205], 1.0 op_sel_hi:[1,0]
	v_pk_add_f32 v[206:207], v[206:207], 1.0 op_sel_hi:[1,0]
	s_add_u32 s38, s20, 0xb000000
	s_addc_u32 s39, s21, 0
	s_add_u32 s40, s20, 0xb400000
	s_addc_u32 s41, s21, 0
	s_add_u32 s46, s20, 0xb800000
	s_addc_u32 s47, s21, 0
	s_add_u32 s48, s20, 0xbc00000
	s_addc_u32 s49, s21, 0
	v_pk_mul_f32 v[0:1], v[0:1], v[232:233] op_sel_hi:[1,0]
	v_pk_mul_f32 v[2:3], v[2:3], v[232:233] op_sel_hi:[1,0]
	v_pk_mul_f32 v[0:1], v[64:65], v[0:1]
	v_pk_mul_f32 v[2:3], v[66:67], v[2:3]
	v_pk_fma_f32 v[0:1], v[160:161], v[0:1], v[176:177]
	v_pk_fma_f32 v[2:3], v[162:163], v[2:3], v[178:179]
	v_cvt_pk_bf16_f32 v244, v0, v1
	v_cvt_pk_bf16_f32 v245, v2, v3
	v_pk_mul_f32 v[4:5], v[4:5], v[232:233] op_sel_hi:[1,0]
	v_pk_mul_f32 v[6:7], v[6:7], v[232:233] op_sel_hi:[1,0]
	v_pk_mul_f32 v[4:5], v[68:69], v[4:5]
	v_pk_mul_f32 v[6:7], v[70:71], v[6:7]
	v_pk_fma_f32 v[4:5], v[164:165], v[4:5], v[180:181]
	v_pk_fma_f32 v[6:7], v[166:167], v[6:7], v[182:183]
	v_cvt_pk_bf16_f32 v246, v4, v5
	v_cvt_pk_bf16_f32 v247, v6, v7
	global_store_dwordx4 v82, v[244:247], s[38:39] offset:0
	v_pk_mul_f32 v[8:9], v[8:9], v[232:233] op_sel_hi:[1,0]
	v_pk_mul_f32 v[10:11], v[10:11], v[232:233] op_sel_hi:[1,0]
	v_pk_mul_f32 v[8:9], v[72:73], v[8:9]
	v_pk_mul_f32 v[10:11], v[74:75], v[10:11]
	v_pk_fma_f32 v[8:9], v[168:169], v[8:9], v[184:185]
	v_pk_fma_f32 v[10:11], v[170:171], v[10:11], v[186:187]
	v_cvt_pk_bf16_f32 v240, v8, v9
	v_cvt_pk_bf16_f32 v241, v10, v11
	v_pk_mul_f32 v[12:13], v[12:13], v[232:233] op_sel_hi:[1,0]
	v_pk_mul_f32 v[14:15], v[14:15], v[232:233] op_sel_hi:[1,0]
	v_pk_mul_f32 v[12:13], v[76:77], v[12:13]
	v_pk_mul_f32 v[14:15], v[78:79], v[14:15]
	v_pk_fma_f32 v[12:13], v[172:173], v[12:13], v[188:189]
	v_pk_fma_f32 v[14:15], v[174:175], v[14:15], v[190:191]
	v_cvt_pk_bf16_f32 v242, v12, v13
	v_cvt_pk_bf16_f32 v243, v14, v15
	global_store_dwordx4 v82, v[240:243], s[38:39] offset:1024
	v_pk_mul_f32 v[16:17], v[16:17], v[234:235] op_sel_hi:[1,0]
	v_pk_mul_f32 v[18:19], v[18:19], v[234:235] op_sel_hi:[1,0]
	v_pk_mul_f32 v[16:17], v[64:65], v[16:17]
	v_pk_mul_f32 v[18:19], v[66:67], v[18:19]
	v_pk_fma_f32 v[16:17], v[160:161], v[16:17], v[176:177]
	v_pk_fma_f32 v[18:19], v[162:163], v[18:19], v[178:179]
	v_cvt_pk_bf16_f32 v244, v16, v17
	v_cvt_pk_bf16_f32 v245, v18, v19
	v_pk_mul_f32 v[20:21], v[20:21], v[234:235] op_sel_hi:[1,0]
	v_pk_mul_f32 v[22:23], v[22:23], v[234:235] op_sel_hi:[1,0]
	v_pk_mul_f32 v[20:21], v[68:69], v[20:21]
	v_pk_mul_f32 v[22:23], v[70:71], v[22:23]
	v_pk_fma_f32 v[20:21], v[164:165], v[20:21], v[180:181]
	v_pk_fma_f32 v[22:23], v[166:167], v[22:23], v[182:183]
	v_cvt_pk_bf16_f32 v246, v20, v21
	v_cvt_pk_bf16_f32 v247, v22, v23
	global_store_dwordx4 v82, v[244:247], s[40:41] offset:0
	v_pk_mul_f32 v[24:25], v[24:25], v[234:235] op_sel_hi:[1,0]
	v_pk_mul_f32 v[26:27], v[26:27], v[234:235] op_sel_hi:[1,0]
	v_pk_mul_f32 v[24:25], v[72:73], v[24:25]
	v_pk_mul_f32 v[26:27], v[74:75], v[26:27]
	v_pk_fma_f32 v[24:25], v[168:169], v[24:25], v[184:185]
	v_pk_fma_f32 v[26:27], v[170:171], v[26:27], v[186:187]
; __device__ __forceinline__ unsigned pk2(float lo, float hi) { return pg8::cvt_pk_bf16(lo, hi); }
; template <bool BF> __device__ __forceinline__ void prep_rows(const float* xp, const float* xs, const bf16* hb, const float* g, const float* MOD, int shoff, int scoff, bf16* U, int gw, int NGW, int lane) {
;     ...
;             for (int j = 0; j < 4; ++j) { const int c = 4 * lane + 256 * j;
;                 const f32x4 gg = *(const f32x4*)(g + c), sc = *(const f32x4*)(mr + scoff + c), sh = *(const f32x4*)(mr + shoff + c);
;                 const f32x4 o = v[r][j] * rstd * gg * (sc + 1.0f) + sh; v2u w; w.x = pk2(o.x, o.y); w.y = pk2(o.z, o.w); *(v2u*)(U + (size_t)m * DM + c) = w; } } }
	v_cvt_pk_bf16_f32 v240, v24, v25
	v_cvt_pk_bf16_f32 v241, v26, v27
	v_pk_mul_f32 v[28:29], v[28:29], v[234:235] op_sel_hi:[1,0]
	v_pk_mul_f32 v[30:31], v[30:31], v[234:235] op_sel_hi:[1,0]
	v_pk_mul_f32 v[28:29], v[76:77], v[28:29]
	v_pk_mul_f32 v[30:31], v[78:79], v[30:31]
	v_pk_fma_f32 v[28:29], v[172:173], v[28:29], v[188:189]
	v_pk_fma_f32 v[30:31], v[174:175], v[30:31], v[190:191]
	v_cvt_pk_bf16_f32 v242, v28, v29
	v_cvt_pk_bf16_f32 v243, v30, v31
	global_store_dwordx4 v82, v[240:243], s[40:41] offset:1024
	v_pk_mul_f32 v[32:33], v[32:33], v[236:237] op_sel_hi:[1,0]
	v_pk_mul_f32 v[34:35], v[34:35], v[236:237] op_sel_hi:[1,0]
	v_pk_mul_f32 v[32:33], v[64:65], v[32:33]
	v_pk_mul_f32 v[34:35], v[66:67], v[34:35]
	v_pk_fma_f32 v[32:33], v[192:193], v[32:33], v[208:209]
	v_pk_fma_f32 v[34:35], v[194:195], v[34:35], v[210:211]
	v_cvt_pk_bf16_f32 v244, v32, v33
	v_cvt_pk_bf16_f32 v245, v34, v35
	v_pk_mul_f32 v[36:37], v[36:37], v[236:237] op_sel_hi:[1,0]
	v_pk_mul_f32 v[38:39], v[38:39], v[236:237] op_sel_hi:[1,0]
	v_pk_mul_f32 v[36:37], v[68:69], v[36:37]
	v_pk_mul_f32 v[38:39], v[70:71], v[38:39]
	v_pk_fma_f32 v[36:37], v[196:197], v[36:37], v[212:213]
	v_pk_fma_f32 v[38:39], v[198:199], v[38:39], v[214:215]
	v_cvt_pk_bf16_f32 v246, v36, v37
	v_cvt_pk_bf16_f32 v247, v38, v39
	global_store_dwordx4 v82, v[244:247], s[46:47] offset:0
	v_pk_mul_f32 v[40:41], v[40:41], v[236:237] op_sel_hi:[1,0]
	v_pk_mul_f32 v[42:43], v[42:43], v[236:237] op_sel_hi:[1,0]
	v_pk_mul_f32 v[40:41], v[72:73], v[40:41]
	v_pk_mul_f32 v[42:43], v[74:75], v[42:43]
	v_pk_fma_f32 v[40:41], v[200:201], v[40:41], v[216:217]
	v_pk_fma_f32 v[42:43], v[202:203], v[42:43], v[218:219]
	v_cvt_pk_bf16_f32 v240, v40, v41
	v_cvt_pk_bf16_f32 v241, v42, v43
	v_pk_mul_f32 v[44:45], v[44:45], v[236:237] op_sel_hi:[1,0]
	v_pk_mul_f32 v[46:47], v[46:47], v[236:237] op_sel_hi:[1,0]
	v_pk_mul_f32 v[44:45], v[76:77], v[44:45]
	v_pk_mul_f32 v[46:47], v[78:79], v[46:47]
	v_pk_fma_f32 v[44:45], v[204:205], v[44:45], v[220:221]
	v_pk_fma_f32 v[46:47], v[206:207], v[46:47], v[222:223]
	v_cvt_pk_bf16_f32 v242, v44, v45
	v_cvt_pk_bf16_f32 v243, v46, v47
	global_store_dwordx4 v82, v[240:243], s[46:47] offset:1024
	v_pk_mul_f32 v[48:49], v[48:49], v[238:239] op_sel_hi:[1,0]
	v_pk_mul_f32 v[50:51], v[50:51], v[238:239] op_sel_hi:[1,0]
	v_pk_mul_f32 v[48:49], v[64:65], v[48:49]
	v_pk_mul_f32 v[50:51], v[66:67], v[50:51]
	v_pk_fma_f32 v[48:49], v[192:193], v[48:49], v[208:209]
	v_pk_fma_f32 v[50:51], v[194:195], v[50:51], v[210:211]
	v_cvt_pk_bf16_f32 v244, v48, v49
	v_cvt_pk_bf16_f32 v245, v50, v51
	v_pk_mul_f32 v[52:53], v[52:53], v[238:239] op_sel_hi:[1,0]
	v_pk_mul_f32 v[54:55], v[54:55], v[238:239] op_sel_hi:[1,0]
	v_pk_mul_f32 v[52:53], v[68:69], v[52:53]
	v_pk_mul_f32 v[54:55], v[70:71], v[54:55]
	v_pk_fma_f32 v[52:53], v[196:197], v[52:53], v[212:213]
	v_pk_fma_f32 v[54:55], v[198:199], v[54:55], v[214:215]
	v_cvt_pk_bf16_f32 v246, v52, v53
	v_cvt_pk_bf16_f32 v247, v54, v55
	global_store_dwordx4 v82, v[244:247], s[48:49] offset:0
	v_pk_mul_f32 v[56:57], v[56:57], v[238:239] op_sel_hi:[1,0]
	v_pk_mul_f32 v[58:59], v[58:59], v[238:239] op_sel_hi:[1,0]
	v_pk_mul_f32 v[56:57], v[72:73], v[56:57]
	v_pk_mul_f32 v[58:59], v[74:75], v[58:59]
	v_pk_fma_f32 v[56:57], v[200:201], v[56:57], v[216:217]
	v_pk_fma_f32 v[58:59], v[202:203], v[58:59], v[218:219]
	v_cvt_pk_bf16_f32 v240, v56, v57
	v_cvt_pk_bf16_f32 v241, v58, v59
	v_pk_mul_f32 v[60:61], v[60:61], v[238:239] op_sel_hi:[1,0]
	v_pk_mul_f32 v[62:63], v[62:63], v[238:239] op_sel_hi:[1,0]
	v_pk_mul_f32 v[60:61], v[76:77], v[60:61]
	v_pk_mul_f32 v[62:63], v[78:79], v[62:63]
	v_pk_fma_f32 v[60:61], v[204:205], v[60:61], v[220:221]
	v_pk_fma_f32 v[62:63], v[206:207], v[62:63], v[222:223]
	v_cvt_pk_bf16_f32 v242, v60, v61
	v_cvt_pk_bf16_f32 v243, v62, v63
	global_store_dwordx4 v82, v[240:243], s[48:49] offset:1024
	s_branch .LBB0_1178
